# GEMM MMA segments: a priority flip (s_setprio 0/1) after every 8 MFMAs instead of every 16
# speedup vs baseline: 1.0052x; 1.0052x over previous
; #define G_STAGE(bufoff, gbase, voff) do { _Pragma("unroll") for (int _i = 0; _i < 2; ++_i) \
;         __builtin_amdgcn_global_load_lds((const unsigned*)((const char*)(gbase) + voff[_i]), (LAS unsigned*)(lds + (bufoff) + ldsw + _i * 8192), 16, 0, 0); } while (0)
; #define G_LDA(dst, b, h) do { _Pragma("unroll") for (int m = 0; m < 4; ++m) _Pragma("unroll") for (int k = 0; k < 2; ++k) dst[m][k] = *(const LAS bf16x8*)(lds + G_SA(b, h) + aoff + m * 2048 + k * 1024); } while (0)
; #define G_LDB(dst, b, h) do { _Pragma("unroll") for (int n = 0; n < 2; ++n) _Pragma("unroll") for (int k = 0; k < 2; ++k) dst[n][k] = *(const LAS bf16x8*)(lds + G_SB(b, h) + boff + n * 2048 + k * 1024); } while (0)
; #define G_MMA(ai, bj, At_, Bt_) do { __builtin_amdgcn_s_setprio(1); _Pragma("unroll") for (int m = 0; m < 4; ++m) _Pragma("unroll") for (int n = 0; n < 2; ++n) _Pragma("unroll") for (int k = 0; k < 2; ++k) \
;         acc[ai][bj][m][n] = __builtin_amdgcn_mfma_f32_16x16x32_bf16(Bt_[n][k], At_[m][k], acc[ai][bj][m][n], 0, 0, 0); __builtin_amdgcn_s_setprio(0); } while (0)
; #define WAIT_V(n) asm volatile("s_waitcnt vmcnt(" #n ")" ::: "memory")
; #define WAIT_L(n) asm volatile("s_waitcnt lgkmcnt(" #n ")" ::: "memory")
; #define BAR __builtin_amdgcn_s_barrier()
; #define SCHED __builtin_amdgcn_sched_barrier(0)
; template <class Get, class Epi>
; DI void gemm_loop(int ntiles, int ld, char* shm, const Get& get, const Epi& epi) {
;     ...
;         for (int t = 0; t < nt; t += 2) {
;             const bool last = (t == nt - 2);
;             const char* a1 = cA + (size_t)(t + 1) * kstep;
;             const char* a2 = last ? nA : cA + (size_t)(t + 2) * kstep; const char* b2 = last ? nB : cB + (size_t)(t + 2) * kstep;
;             const char* a3 = a2 + kstep; const char* b3 = b2 + kstep;
;             G_LDB(B0, 0, 0); G_LDB(B1, 0, 1); SCHED; G_LDA(At, 0, 0); G_STAGE(G_SA(1, 1), a1 + hstep, voffA);
;             WAIT_V(8); WAIT_L(0); BAR; G_MMA(0, 0, At, B0); G_MMA(0, 1, At, B1); BAR; SCHED;
;             G_LDA(At, 0, 1); G_STAGE(G_SB(0, 0), b2, voffB); G_STAGE(G_SB(0, 1), b2 + hstep, voffB); G_STAGE(G_SA(0, 0), a2, voffA);
;             WAIT_V(8); WAIT_L(0); BAR; G_MMA(1, 0, At, B0); G_MMA(1, 1, At, B1); BAR; SCHED;
.LBB0_332:
	ds_read_b128 v[0:3], v142
	ds_read_b128 v[4:7], v142 offset:1024
	ds_read_b128 v[8:11], v142 offset:2048
	ds_read_b128 v[12:15], v142 offset:3072
	ds_read_b128 v[16:19], v143
	ds_read_b128 v[20:23], v143 offset:1024
	ds_read_b128 v[24:27], v143 offset:2048
	ds_read_b128 v[28:31], v143 offset:3072
	s_ashr_i32 s37, s36, 31
	s_lshl_b64 s[42:43], s[36:37], 11
	s_add_u32 s42, s73, s42
	s_addc_u32 s43, s74, s43
	s_and_b64 s[44:45], s[38:39], exec
	s_cselect_b32 s55, s43, s15
	s_cselect_b32 s54, s42, s14
	s_ashr_i32 s41, s40, 31
	s_lshl_b64 s[44:45], s[40:41], 11
	s_add_u32 s44, s59, s44
	s_addc_u32 s45, s72, s45
	s_and_b64 s[46:47], s[38:39], exec
	s_cselect_b32 s47, s45, s51
	s_cselect_b32 s46, s44, s50
	s_add_u32 s94, s14, 0x40080
	s_addc_u32 s95, s15, 0
	s_mov_b32 m0, s81
	v_lshl_add_u64 v[64:65], s[94:95], 0, v[134:135]
	ds_read_b128 v[32:35], v144
	ds_read_b128 v[36:39], v144 offset:1024
	ds_read_b128 v[40:43], v144 offset:2048
	ds_read_b128 v[44:47], v144 offset:3072
	ds_read_b128 v[48:51], v144 offset:4096
	ds_read_b128 v[52:55], v144 offset:5120
	ds_read_b128 v[56:59], v144 offset:6144
	ds_read_b128 v[60:63], v144 offset:7168
	global_load_lds_dwordx4 v[64:65], off
	v_lshl_add_u64 v[64:65], s[94:95], 0, v[130:131]
	s_mov_b32 m0, s82
	s_nop 0
	global_load_lds_dwordx4 v[64:65], off
	s_waitcnt vmcnt(8)
	s_waitcnt lgkmcnt(0)
	s_barrier
	s_setprio 1
	s_waitcnt lgkmcnt(0)
	v_mfma_f32_16x16x32_bf16 v[64:67], v[0:3], v[32:35], 0
	v_mfma_f32_16x16x32_bf16 v[68:71], v[8:11], v[32:35], 0
	v_mfma_f32_16x16x32_bf16 v[72:75], v[0:3], v[40:43], 0
	v_mfma_f32_16x16x32_bf16 v[76:79], v[8:11], v[40:43], 0
	v_mfma_f32_16x16x32_bf16 v[80:83], v[0:3], v[48:51], 0
	v_mfma_f32_16x16x32_bf16 v[84:87], v[8:11], v[48:51], 0
	v_mfma_f32_16x16x32_bf16 v[88:91], v[0:3], v[56:59], 0
	v_mfma_f32_16x16x32_bf16 v[92:95], v[8:11], v[56:59], 0
	s_setprio 0
	s_setprio 1
	v_mfma_f32_16x16x32_bf16 v[64:67], v[4:7], v[36:39], v[64:67]
	v_mfma_f32_16x16x32_bf16 v[68:71], v[12:15], v[36:39], v[68:71]
	v_mfma_f32_16x16x32_bf16 v[72:75], v[4:7], v[44:47], v[72:75]
	v_mfma_f32_16x16x32_bf16 v[76:79], v[12:15], v[44:47], v[76:79]
	v_mfma_f32_16x16x32_bf16 v[80:83], v[4:7], v[52:55], v[80:83]
	v_mfma_f32_16x16x32_bf16 v[84:87], v[12:15], v[52:55], v[84:87]
	v_mfma_f32_16x16x32_bf16 v[88:91], v[4:7], v[60:63], v[88:91]
	v_mfma_f32_16x16x32_bf16 v[92:95], v[12:15], v[60:63], v[92:95]
	s_setprio 0
	s_setprio 1
	v_mfma_f32_16x16x32_bf16 v[96:99], v[16:19], v[32:35], 0
	v_mfma_f32_16x16x32_bf16 v[32:35], v[24:27], v[32:35], 0
	v_mfma_f32_16x16x32_bf16 v[96:99], v[20:23], v[36:39], v[96:99]
	v_mfma_f32_16x16x32_bf16 v[32:35], v[28:31], v[36:39], v[32:35]
	v_mfma_f32_16x16x32_bf16 v[36:39], v[16:19], v[40:43], 0
	v_mfma_f32_16x16x32_bf16 v[40:43], v[24:27], v[40:43], 0
	v_mfma_f32_16x16x32_bf16 v[36:39], v[20:23], v[44:47], v[36:39]
	v_mfma_f32_16x16x32_bf16 v[40:43], v[28:31], v[44:47], v[40:43]
	s_setprio 0
	s_setprio 1
	v_mfma_f32_16x16x32_bf16 v[44:47], v[16:19], v[48:51], 0
	v_mfma_f32_16x16x32_bf16 v[48:51], v[24:27], v[48:51], 0
	v_mfma_f32_16x16x32_bf16 v[44:47], v[20:23], v[52:55], v[44:47]
	v_mfma_f32_16x16x32_bf16 v[48:51], v[28:31], v[52:55], v[48:51]
	v_mfma_f32_16x16x32_bf16 v[52:55], v[16:19], v[56:59], 0
	v_mfma_f32_16x16x32_bf16 v[56:59], v[24:27], v[56:59], 0
	v_mfma_f32_16x16x32_bf16 v[52:55], v[20:23], v[60:63], v[52:55]
	v_mfma_f32_16x16x32_bf16 v[56:59], v[28:31], v[60:63], v[56:59]
	s_setprio 0
	s_barrier
	v_lshl_add_u64 v[140:141], s[50:51], 0, v[132:133]
	s_mov_b32 m0, s83
	v_lshl_add_u64 v[136:137], v[140:141], 0, s[28:29]
	v_lshl_add_u64 v[184:185], s[50:51], 0, v[128:129]
	s_add_u32 s94, s50, 0x40100
	ds_read_b128 v[60:63], v144 offset:16384
	ds_read_b128 v[100:103], v144 offset:17408
	ds_read_b128 v[104:107], v144 offset:18432
	ds_read_b128 v[108:111], v144 offset:19456
	ds_read_b128 v[112:115], v144 offset:20480
	ds_read_b128 v[116:119], v144 offset:21504
	ds_read_b128 v[120:123], v144 offset:22528
	ds_read_b128 v[124:127], v144 offset:23552
	global_load_lds_dwordx4 v[136:137], off
	v_lshl_add_u64 v[136:137], v[184:185], 0, s[28:29]
	s_mov_b32 m0, s84
	s_addc_u32 s95, s51, 0
	global_load_lds_dwordx4 v[136:137], off
	v_lshl_add_u64 v[136:137], s[94:95], 0, v[132:133]
	s_mov_b32 m0, s85
	v_lshl_add_u64 v[186:187], s[14:15], 0, v[134:135]
	global_load_lds_dwordx4 v[136:137], off
	v_lshl_add_u64 v[136:137], s[94:95], 0, v[128:129]
	s_mov_b32 m0, s86
	v_lshl_add_u64 v[212:213], s[14:15], 0, v[130:131]
	global_load_lds_dwordx4 v[136:137], off
	v_lshl_add_u64 v[136:137], v[186:187], 0, s[28:29]
	s_mov_b32 m0, s58
	s_nop 0
	global_load_lds_dwordx4 v[136:137], off
	v_lshl_add_u64 v[136:137], v[212:213], 0, s[28:29]
	s_mov_b32 m0, s75
	s_nop 0
	global_load_lds_dwordx4 v[136:137], off
	s_waitcnt vmcnt(8)
	s_waitcnt lgkmcnt(0)
	s_barrier
; #define G_STAGE(bufoff, gbase, voff) do { _Pragma("unroll") for (int _i = 0; _i < 2; ++_i) \
;         __builtin_amdgcn_global_load_lds((const unsigned*)((const char*)(gbase) + voff[_i]), (LAS unsigned*)(lds + (bufoff) + ldsw + _i * 8192), 16, 0, 0); } while (0)
; #define G_LDA(dst, b, h) do { _Pragma("unroll") for (int m = 0; m < 4; ++m) _Pragma("unroll") for (int k = 0; k < 2; ++k) dst[m][k] = *(const LAS bf16x8*)(lds + G_SA(b, h) + aoff + m * 2048 + k * 1024); } while (0)
; #define G_LDB(dst, b, h) do { _Pragma("unroll") for (int n = 0; n < 2; ++n) _Pragma("unroll") for (int k = 0; k < 2; ++k) dst[n][k] = *(const LAS bf16x8*)(lds + G_SB(b, h) + boff + n * 2048 + k * 1024); } while (0)
; #define G_MMA(ai, bj, At_, Bt_) do { __builtin_amdgcn_s_setprio(1); _Pragma("unroll") for (int m = 0; m < 4; ++m) _Pragma("unroll") for (int n = 0; n < 2; ++n) _Pragma("unroll") for (int k = 0; k < 2; ++k) \
;         acc[ai][bj][m][n] = __builtin_amdgcn_mfma_f32_16x16x32_bf16(Bt_[n][k], At_[m][k], acc[ai][bj][m][n], 0, 0, 0); __builtin_amdgcn_s_setprio(0); } while (0)
; #define WAIT_V(n) asm volatile("s_waitcnt vmcnt(" #n ")" ::: "memory")
; #define WAIT_L(n) asm volatile("s_waitcnt lgkmcnt(" #n ")" ::: "memory")
; #define BAR __builtin_amdgcn_s_barrier()
; #define SCHED __builtin_amdgcn_sched_barrier(0)
; template <class Get, class Epi>
; DI void gemm_loop(int ntiles, int ld, char* shm, const Get& get, const Epi& epi) {
;     ...
;             G_LDA(At, 0, 1); G_STAGE(G_SB(0, 0), b2, voffB); G_STAGE(G_SB(0, 1), b2 + hstep, voffB); G_STAGE(G_SA(0, 0), a2, voffA);
;             WAIT_V(8); WAIT_L(0); BAR; G_MMA(1, 0, At, B0); G_MMA(1, 1, At, B1); BAR; SCHED;
;             G_LDB(B0, 1, 0); G_LDB(B1, 1, 1); SCHED; G_LDA(At, 1, 0); G_STAGE(G_SA(0, 1), a2 + hstep, voffA);
;             WAIT_V(8); WAIT_L(0); BAR; G_MMA(0, 0, At, B0); G_MMA(0, 1, At, B1); BAR; SCHED;
	s_setprio 1
	s_waitcnt lgkmcnt(0)
	v_mfma_f32_16x16x32_bf16 v[136:139], v[0:3], v[60:63], 0
	v_mfma_f32_16x16x32_bf16 v[152:155], v[0:3], v[104:107], 0
	v_mfma_f32_16x16x32_bf16 v[160:163], v[0:3], v[112:115], 0
	v_mfma_f32_16x16x32_bf16 v[0:3], v[0:3], v[120:123], 0
	v_mfma_f32_16x16x32_bf16 v[136:139], v[4:7], v[100:103], v[136:139]
	v_mfma_f32_16x16x32_bf16 v[152:155], v[4:7], v[108:111], v[152:155]
	v_mfma_f32_16x16x32_bf16 v[160:163], v[4:7], v[116:119], v[160:163]
	v_mfma_f32_16x16x32_bf16 v[0:3], v[4:7], v[124:127], v[0:3]
	s_setprio 0
	s_setprio 1
	v_mfma_f32_16x16x32_bf16 v[4:7], v[8:11], v[120:123], 0
	v_mfma_f32_16x16x32_bf16 v[148:151], v[8:11], v[60:63], 0
	v_mfma_f32_16x16x32_bf16 v[156:159], v[8:11], v[104:107], 0
	v_mfma_f32_16x16x32_bf16 v[164:167], v[8:11], v[112:115], 0
	v_mfma_f32_16x16x32_bf16 v[4:7], v[12:15], v[124:127], v[4:7]
	v_mfma_f32_16x16x32_bf16 v[148:151], v[12:15], v[100:103], v[148:151]
	v_mfma_f32_16x16x32_bf16 v[156:159], v[12:15], v[108:111], v[156:159]
	v_mfma_f32_16x16x32_bf16 v[164:167], v[12:15], v[116:119], v[164:167]
	s_setprio 0
	s_setprio 1
	v_mfma_f32_16x16x32_bf16 v[8:11], v[16:19], v[60:63], 0
	v_mfma_f32_16x16x32_bf16 v[12:15], v[24:27], v[60:63], 0
	v_mfma_f32_16x16x32_bf16 v[8:11], v[20:23], v[100:103], v[8:11]
	v_mfma_f32_16x16x32_bf16 v[12:15], v[28:31], v[100:103], v[12:15]
	v_mfma_f32_16x16x32_bf16 v[60:63], v[16:19], v[104:107], 0
	v_mfma_f32_16x16x32_bf16 v[100:103], v[24:27], v[104:107], 0
	v_mfma_f32_16x16x32_bf16 v[104:107], v[16:19], v[112:115], 0
	v_mfma_f32_16x16x32_bf16 v[16:19], v[16:19], v[120:123], 0
	s_setprio 0
	s_setprio 1
	v_mfma_f32_16x16x32_bf16 v[60:63], v[20:23], v[108:111], v[60:63]
	v_mfma_f32_16x16x32_bf16 v[100:103], v[28:31], v[108:111], v[100:103]
	v_mfma_f32_16x16x32_bf16 v[104:107], v[20:23], v[116:119], v[104:107]
	v_mfma_f32_16x16x32_bf16 v[108:111], v[24:27], v[112:115], 0
	v_mfma_f32_16x16x32_bf16 v[16:19], v[20:23], v[124:127], v[16:19]
	v_mfma_f32_16x16x32_bf16 v[20:23], v[24:27], v[120:123], 0
	v_mfma_f32_16x16x32_bf16 v[108:111], v[28:31], v[116:119], v[108:111]
	v_mfma_f32_16x16x32_bf16 v[20:23], v[28:31], v[124:127], v[20:23]
	s_setprio 0
	s_barrier
	ds_read_b128 v[24:27], v145
	ds_read_b128 v[28:31], v145 offset:1024
	ds_read_b128 v[112:115], v145 offset:2048
	ds_read_b128 v[116:119], v145 offset:3072
	ds_read_b128 v[120:123], v146
	ds_read_b128 v[124:127], v146 offset:1024
	ds_read_b128 v[168:171], v146 offset:2048
	ds_read_b128 v[172:175], v146 offset:3072
	s_add_u32 s94, s14, 0x40100
	s_addc_u32 s95, s15, 0
	s_mov_b32 m0, s76
	v_lshl_add_u64 v[214:215], s[94:95], 0, v[134:135]
	ds_read_b128 v[176:179], v144 offset:32768
	ds_read_b128 v[180:183], v144 offset:33792
	ds_read_b128 v[188:191], v144 offset:34816
	ds_read_b128 v[192:195], v144 offset:35840
	ds_read_b128 v[196:199], v144 offset:36864
	ds_read_b128 v[200:203], v144 offset:37888
	ds_read_b128 v[204:207], v144 offset:38912
	ds_read_b128 v[208:211], v144 offset:39936
	global_load_lds_dwordx4 v[214:215], off
	v_lshl_add_u64 v[214:215], s[94:95], 0, v[130:131]
	s_mov_b32 m0, s78
	s_nop 0
	global_load_lds_dwordx4 v[214:215], off
	s_waitcnt vmcnt(8)
	s_waitcnt lgkmcnt(0)
	s_barrier
	s_setprio 1
	s_waitcnt lgkmcnt(0)
	v_mfma_f32_16x16x32_bf16 v[64:67], v[24:27], v[176:179], v[64:67]
	v_mfma_f32_16x16x32_bf16 v[68:71], v[112:115], v[176:179], v[68:71]
	v_mfma_f32_16x16x32_bf16 v[72:75], v[24:27], v[188:191], v[72:75]
	v_mfma_f32_16x16x32_bf16 v[76:79], v[112:115], v[188:191], v[76:79]
	v_mfma_f32_16x16x32_bf16 v[80:83], v[24:27], v[196:199], v[80:83]
	v_mfma_f32_16x16x32_bf16 v[84:87], v[112:115], v[196:199], v[84:87]
	v_mfma_f32_16x16x32_bf16 v[88:91], v[24:27], v[204:207], v[88:91]
	v_mfma_f32_16x16x32_bf16 v[92:95], v[112:115], v[204:207], v[92:95]
	s_setprio 0
	s_setprio 1
	v_mfma_f32_16x16x32_bf16 v[64:67], v[28:31], v[180:183], v[64:67]
	v_mfma_f32_16x16x32_bf16 v[68:71], v[116:119], v[180:183], v[68:71]
	v_mfma_f32_16x16x32_bf16 v[72:75], v[28:31], v[192:195], v[72:75]
	v_mfma_f32_16x16x32_bf16 v[76:79], v[116:119], v[192:195], v[76:79]
	v_mfma_f32_16x16x32_bf16 v[80:83], v[28:31], v[200:203], v[80:83]
	v_mfma_f32_16x16x32_bf16 v[84:87], v[116:119], v[200:203], v[84:87]
	v_mfma_f32_16x16x32_bf16 v[88:91], v[28:31], v[208:211], v[88:91]
	v_mfma_f32_16x16x32_bf16 v[92:95], v[116:119], v[208:211], v[92:95]
	s_setprio 0
	s_setprio 1
	v_mfma_f32_16x16x32_bf16 v[96:99], v[120:123], v[176:179], v[96:99]
	v_mfma_f32_16x16x32_bf16 v[32:35], v[168:171], v[176:179], v[32:35]
	v_mfma_f32_16x16x32_bf16 v[36:39], v[120:123], v[188:191], v[36:39]
	v_mfma_f32_16x16x32_bf16 v[40:43], v[168:171], v[188:191], v[40:43]
	v_mfma_f32_16x16x32_bf16 v[44:47], v[120:123], v[196:199], v[44:47]
	v_mfma_f32_16x16x32_bf16 v[48:51], v[168:171], v[196:199], v[48:51]
	v_mfma_f32_16x16x32_bf16 v[52:55], v[120:123], v[204:207], v[52:55]
	v_mfma_f32_16x16x32_bf16 v[56:59], v[168:171], v[204:207], v[56:59]
	s_setprio 0
	s_setprio 1
	v_mfma_f32_16x16x32_bf16 v[96:99], v[124:127], v[180:183], v[96:99]
	v_mfma_f32_16x16x32_bf16 v[32:35], v[172:175], v[180:183], v[32:35]
	v_mfma_f32_16x16x32_bf16 v[36:39], v[124:127], v[192:195], v[36:39]
	v_mfma_f32_16x16x32_bf16 v[40:43], v[172:175], v[192:195], v[40:43]
	v_mfma_f32_16x16x32_bf16 v[44:47], v[124:127], v[200:203], v[44:47]
	v_mfma_f32_16x16x32_bf16 v[48:51], v[172:175], v[200:203], v[48:51]
	v_mfma_f32_16x16x32_bf16 v[52:55], v[124:127], v[208:211], v[52:55]
	v_mfma_f32_16x16x32_bf16 v[56:59], v[172:175], v[208:211], v[56:59]
	s_setprio 0
	s_barrier
; #define G_STAGE(bufoff, gbase, voff) do { _Pragma("unroll") for (int _i = 0; _i < 2; ++_i) \
;         __builtin_amdgcn_global_load_lds((const unsigned*)((const char*)(gbase) + voff[_i]), (LAS unsigned*)(lds + (bufoff) + ldsw + _i * 8192), 16, 0, 0); } while (0)
; #define G_LDA(dst, b, h) do { _Pragma("unroll") for (int m = 0; m < 4; ++m) _Pragma("unroll") for (int k = 0; k < 2; ++k) dst[m][k] = *(const LAS bf16x8*)(lds + G_SA(b, h) + aoff + m * 2048 + k * 1024); } while (0)
; #define G_LDB(dst, b, h) do { _Pragma("unroll") for (int n = 0; n < 2; ++n) _Pragma("unroll") for (int k = 0; k < 2; ++k) dst[n][k] = *(const LAS bf16x8*)(lds + G_SB(b, h) + boff + n * 2048 + k * 1024); } while (0)
; #define G_MMA(ai, bj, At_, Bt_) do { __builtin_amdgcn_s_setprio(1); _Pragma("unroll") for (int m = 0; m < 4; ++m) _Pragma("unroll") for (int n = 0; n < 2; ++n) _Pragma("unroll") for (int k = 0; k < 2; ++k) \
;         acc[ai][bj][m][n] = __builtin_amdgcn_mfma_f32_16x16x32_bf16(Bt_[n][k], At_[m][k], acc[ai][bj][m][n], 0, 0, 0); __builtin_amdgcn_s_setprio(0); } while (0)
; #define WAIT_V(n) asm volatile("s_waitcnt vmcnt(" #n ")" ::: "memory")
; #define WAIT_L(n) asm volatile("s_waitcnt lgkmcnt(" #n ")" ::: "memory")
; #define BAR __builtin_amdgcn_s_barrier()
; #define SCHED __builtin_amdgcn_sched_barrier(0)
; template <class Get, class Epi>
; DI void gemm_loop(int ntiles, int ld, char* shm, const Get& get, const Epi& epi) {
;     ...
;             G_LDB(B0, 0, 0); G_LDB(B1, 0, 1); SCHED; G_LDA(At, 0, 0); G_STAGE(G_SA(1, 1), a1 + hstep, voffA);
;             WAIT_V(8); WAIT_L(0); BAR; G_MMA(0, 0, At, B0); G_MMA(0, 1, At, B1); BAR; SCHED;
;     ...
;             G_LDA(At, 1, 1); G_STAGE(G_SB(1, 0), b3, voffB); G_STAGE(G_SB(1, 1), b3 + hstep, voffB); G_STAGE(G_SA(1, 0), a3, voffA);
;             WAIT_V(8); WAIT_L(0); BAR; G_MMA(1, 0, At, B0); G_MMA(1, 1, At, B1); BAR; SCHED;
	s_mov_b32 m0, s87
	v_lshl_add_u64 v[140:141], v[140:141], 0, s[30:31]
	s_add_u32 s50, s50, 0x40180
	ds_read_b128 v[176:179], v144 offset:49152
	ds_read_b128 v[180:183], v144 offset:50176
	ds_read_b128 v[188:191], v144 offset:51200
	ds_read_b128 v[192:195], v144 offset:52224
	ds_read_b128 v[196:199], v144 offset:53248
	ds_read_b128 v[200:203], v144 offset:54272
	ds_read_b128 v[204:207], v144 offset:55296
	ds_read_b128 v[208:211], v144 offset:56320
	global_load_lds_dwordx4 v[140:141], off
	v_lshl_add_u64 v[140:141], v[184:185], 0, s[30:31]
	s_mov_b32 m0, s88
	s_addc_u32 s51, s51, 0
	global_load_lds_dwordx4 v[140:141], off
	v_lshl_add_u64 v[140:141], s[50:51], 0, v[132:133]
	s_mov_b32 m0, s89
	s_nop 0
	global_load_lds_dwordx4 v[140:141], off
	v_lshl_add_u64 v[140:141], s[50:51], 0, v[128:129]
	s_mov_b32 m0, s90
	s_nop 0
	global_load_lds_dwordx4 v[140:141], off
	v_lshl_add_u64 v[140:141], v[186:187], 0, s[30:31]
	s_mov_b32 m0, s79
	s_nop 0
	global_load_lds_dwordx4 v[140:141], off
	v_lshl_add_u64 v[140:141], v[212:213], 0, s[30:31]
	s_mov_b32 m0, s80
	s_nop 0
	global_load_lds_dwordx4 v[140:141], off
	s_waitcnt vmcnt(8)
	s_waitcnt lgkmcnt(0)
	s_barrier
	s_setprio 1
	s_waitcnt lgkmcnt(0)
	v_mfma_f32_16x16x32_bf16 v[0:3], v[24:27], v[204:207], v[0:3]
	v_mfma_f32_16x16x32_bf16 v[4:7], v[112:115], v[204:207], v[4:7]
	v_mfma_f32_16x16x32_bf16 v[136:139], v[24:27], v[176:179], v[136:139]
	v_mfma_f32_16x16x32_bf16 v[148:151], v[112:115], v[176:179], v[148:151]
	v_mfma_f32_16x16x32_bf16 v[152:155], v[24:27], v[188:191], v[152:155]
	v_mfma_f32_16x16x32_bf16 v[156:159], v[112:115], v[188:191], v[156:159]
	v_mfma_f32_16x16x32_bf16 v[160:163], v[24:27], v[196:199], v[160:163]
	v_mfma_f32_16x16x32_bf16 v[164:167], v[112:115], v[196:199], v[164:167]
	s_setprio 0
	s_setprio 1
	v_mfma_f32_16x16x32_bf16 v[0:3], v[28:31], v[208:211], v[0:3]
	v_mfma_f32_16x16x32_bf16 v[4:7], v[116:119], v[208:211], v[4:7]
	v_mfma_f32_16x16x32_bf16 v[136:139], v[28:31], v[180:183], v[136:139]
	v_mfma_f32_16x16x32_bf16 v[148:151], v[116:119], v[180:183], v[148:151]
	v_mfma_f32_16x16x32_bf16 v[152:155], v[28:31], v[192:195], v[152:155]
	v_mfma_f32_16x16x32_bf16 v[156:159], v[116:119], v[192:195], v[156:159]
	v_mfma_f32_16x16x32_bf16 v[160:163], v[28:31], v[200:203], v[160:163]
	v_mfma_f32_16x16x32_bf16 v[164:167], v[116:119], v[200:203], v[164:167]
	s_setprio 0
	s_setprio 1
	v_mfma_f32_16x16x32_bf16 v[8:11], v[120:123], v[176:179], v[8:11]
	v_mfma_f32_16x16x32_bf16 v[12:15], v[168:171], v[176:179], v[12:15]
	v_mfma_f32_16x16x32_bf16 v[24:27], v[120:123], v[188:191], v[60:63]
	v_mfma_f32_16x16x32_bf16 v[28:31], v[168:171], v[188:191], v[100:103]
	v_mfma_f32_16x16x32_bf16 v[60:63], v[120:123], v[196:199], v[104:107]
	v_mfma_f32_16x16x32_bf16 v[100:103], v[168:171], v[196:199], v[108:111]
	v_mfma_f32_16x16x32_bf16 v[16:19], v[120:123], v[204:207], v[16:19]
	v_mfma_f32_16x16x32_bf16 v[20:23], v[168:171], v[204:207], v[20:23]
	s_setprio 0
	s_setprio 1
	v_mfma_f32_16x16x32_bf16 v[8:11], v[124:127], v[180:183], v[8:11]
	v_mfma_f32_16x16x32_bf16 v[12:15], v[172:175], v[180:183], v[12:15]
	v_mfma_f32_16x16x32_bf16 v[24:27], v[124:127], v[192:195], v[24:27]
	v_mfma_f32_16x16x32_bf16 v[28:31], v[172:175], v[192:195], v[28:31]
	v_mfma_f32_16x16x32_bf16 v[60:63], v[124:127], v[200:203], v[60:63]
	v_mfma_f32_16x16x32_bf16 v[100:103], v[172:175], v[200:203], v[100:103]
	v_mfma_f32_16x16x32_bf16 v[16:19], v[124:127], v[208:211], v[16:19]
	v_mfma_f32_16x16x32_bf16 v[20:23], v[172:175], v[208:211], v[20:23]
	s_setprio 0
	s_barrier
	ds_read_b128 v[104:107], v142
	ds_read_b128 v[108:111], v142 offset:1024
	ds_read_b128 v[112:115], v142 offset:2048
	ds_read_b128 v[116:119], v142 offset:3072
	ds_read_b128 v[120:123], v143
	ds_read_b128 v[124:127], v143 offset:1024
	ds_read_b128 v[168:171], v143 offset:2048
	ds_read_b128 v[172:175], v143 offset:3072
	s_add_u32 s14, s14, 0x40180
	s_addc_u32 s15, s15, 0
	s_mov_b32 m0, s81
	v_lshl_add_u64 v[140:141], s[14:15], 0, v[134:135]
	ds_read_b128 v[176:179], v144
	ds_read_b128 v[180:183], v144 offset:1024
	ds_read_b128 v[188:191], v144 offset:2048
	ds_read_b128 v[192:195], v144 offset:3072
	ds_read_b128 v[196:199], v144 offset:4096
	ds_read_b128 v[200:203], v144 offset:5120
	ds_read_b128 v[204:207], v144 offset:6144
	ds_read_b128 v[208:211], v144 offset:7168
	global_load_lds_dwordx4 v[140:141], off
	v_lshl_add_u64 v[140:141], s[14:15], 0, v[130:131]
	s_mov_b32 m0, s82
	s_nop 0
	global_load_lds_dwordx4 v[140:141], off
	s_waitcnt vmcnt(8)
	s_waitcnt lgkmcnt(0)
	s_barrier
; #define G_STAGE(bufoff, gbase, voff) do { _Pragma("unroll") for (int _i = 0; _i < 2; ++_i) \
;         __builtin_amdgcn_global_load_lds((const unsigned*)((const char*)(gbase) + voff[_i]), (LAS unsigned*)(lds + (bufoff) + ldsw + _i * 8192), 16, 0, 0); } while (0)
; #define G_LDA(dst, b, h) do { _Pragma("unroll") for (int m = 0; m < 4; ++m) _Pragma("unroll") for (int k = 0; k < 2; ++k) dst[m][k] = *(const LAS bf16x8*)(lds + G_SA(b, h) + aoff + m * 2048 + k * 1024); } while (0)
; #define G_LDB(dst, b, h) do { _Pragma("unroll") for (int n = 0; n < 2; ++n) _Pragma("unroll") for (int k = 0; k < 2; ++k) dst[n][k] = *(const LAS bf16x8*)(lds + G_SB(b, h) + boff + n * 2048 + k * 1024); } while (0)
; #define G_MMA(ai, bj, At_, Bt_) do { __builtin_amdgcn_s_setprio(1); _Pragma("unroll") for (int m = 0; m < 4; ++m) _Pragma("unroll") for (int n = 0; n < 2; ++n) _Pragma("unroll") for (int k = 0; k < 2; ++k) \
;         acc[ai][bj][m][n] = __builtin_amdgcn_mfma_f32_16x16x32_bf16(Bt_[n][k], At_[m][k], acc[ai][bj][m][n], 0, 0, 0); __builtin_amdgcn_s_setprio(0); } while (0)
; #define WAIT_V(n) asm volatile("s_waitcnt vmcnt(" #n ")" ::: "memory")
; #define WAIT_L(n) asm volatile("s_waitcnt lgkmcnt(" #n ")" ::: "memory")
; #define BAR __builtin_amdgcn_s_barrier()
; #define SCHED __builtin_amdgcn_sched_barrier(0)
; template <class Get, class Epi>
; DI void gemm_loop(int ntiles, int ld, char* shm, const Get& get, const Epi& epi) {
;     ...
;             G_LDB(B0, 0, 0); G_LDB(B1, 0, 1); SCHED; G_LDA(At, 0, 0); G_STAGE(G_SA(1, 1), a1 + hstep, voffA);
;             WAIT_V(8); WAIT_L(0); BAR; G_MMA(0, 0, At, B0); G_MMA(0, 1, At, B1); BAR; SCHED;
;             G_LDA(At, 0, 1); G_STAGE(G_SB(0, 0), b2, voffB); G_STAGE(G_SB(0, 1), b2 + hstep, voffB); G_STAGE(G_SA(0, 0), a2, voffA);
;             WAIT_V(8); WAIT_L(0); BAR; G_MMA(1, 0, At, B0); G_MMA(1, 1, At, B1); BAR; SCHED;
	s_setprio 1
	s_waitcnt lgkmcnt(0)
	v_mfma_f32_16x16x32_bf16 v[64:67], v[104:107], v[176:179], v[64:67]
	v_mfma_f32_16x16x32_bf16 v[68:71], v[112:115], v[176:179], v[68:71]
	v_mfma_f32_16x16x32_bf16 v[72:75], v[104:107], v[188:191], v[72:75]
	v_mfma_f32_16x16x32_bf16 v[76:79], v[112:115], v[188:191], v[76:79]
	v_mfma_f32_16x16x32_bf16 v[80:83], v[104:107], v[196:199], v[80:83]
	v_mfma_f32_16x16x32_bf16 v[84:87], v[112:115], v[196:199], v[84:87]
	v_mfma_f32_16x16x32_bf16 v[88:91], v[104:107], v[204:207], v[88:91]
	v_mfma_f32_16x16x32_bf16 v[92:95], v[112:115], v[204:207], v[92:95]
	s_setprio 0
	s_setprio 1
	v_mfma_f32_16x16x32_bf16 v[64:67], v[108:111], v[180:183], v[64:67]
	v_mfma_f32_16x16x32_bf16 v[68:71], v[116:119], v[180:183], v[68:71]
	v_mfma_f32_16x16x32_bf16 v[72:75], v[108:111], v[192:195], v[72:75]
	v_mfma_f32_16x16x32_bf16 v[76:79], v[116:119], v[192:195], v[76:79]
	v_mfma_f32_16x16x32_bf16 v[80:83], v[108:111], v[200:203], v[80:83]
	v_mfma_f32_16x16x32_bf16 v[84:87], v[116:119], v[200:203], v[84:87]
	v_mfma_f32_16x16x32_bf16 v[88:91], v[108:111], v[208:211], v[88:91]
	v_mfma_f32_16x16x32_bf16 v[92:95], v[116:119], v[208:211], v[92:95]
	s_setprio 0
	s_setprio 1
	v_mfma_f32_16x16x32_bf16 v[48:51], v[168:171], v[196:199], v[48:51]
	v_mfma_f32_16x16x32_bf16 v[96:99], v[120:123], v[176:179], v[96:99]
	v_mfma_f32_16x16x32_bf16 v[32:35], v[168:171], v[176:179], v[32:35]
	v_mfma_f32_16x16x32_bf16 v[176:179], v[172:175], v[200:203], v[48:51]
	v_mfma_f32_16x16x32_bf16 v[48:51], v[120:123], v[204:207], v[52:55]
	v_mfma_f32_16x16x32_bf16 v[212:215], v[124:127], v[180:183], v[96:99]
	v_mfma_f32_16x16x32_bf16 v[32:35], v[172:175], v[180:183], v[32:35]
	v_mfma_f32_16x16x32_bf16 v[36:39], v[120:123], v[188:191], v[36:39]
	s_setprio 0
	s_setprio 1
	v_mfma_f32_16x16x32_bf16 v[40:43], v[168:171], v[188:191], v[40:43]
	v_mfma_f32_16x16x32_bf16 v[44:47], v[120:123], v[196:199], v[44:47]
	v_mfma_f32_16x16x32_bf16 v[180:183], v[124:127], v[208:211], v[48:51]
	v_mfma_f32_16x16x32_bf16 v[48:51], v[168:171], v[204:207], v[56:59]
	v_mfma_f32_16x16x32_bf16 v[36:39], v[124:127], v[192:195], v[36:39]
	v_mfma_f32_16x16x32_bf16 v[40:43], v[172:175], v[192:195], v[40:43]
	v_mfma_f32_16x16x32_bf16 v[44:47], v[124:127], v[200:203], v[44:47]
	v_mfma_f32_16x16x32_bf16 v[56:59], v[172:175], v[208:211], v[48:51]
	s_setprio 0
	s_barrier
	s_mov_b32 m0, s83
	v_lshl_add_u64 v[140:141], s[46:47], 0, v[132:133]
	s_add_u32 s14, s46, 0x40000
	ds_read_b128 v[48:51], v144 offset:16384
	ds_read_b128 v[52:55], v144 offset:17408
	ds_read_b128 v[96:99], v144 offset:18432
	ds_read_b128 v[188:191], v144 offset:19456
	ds_read_b128 v[192:195], v144 offset:20480
	ds_read_b128 v[196:199], v144 offset:21504
	ds_read_b128 v[200:203], v144 offset:22528
	ds_read_b128 v[204:207], v144 offset:23552
	global_load_lds_dwordx4 v[140:141], off
	v_lshl_add_u64 v[184:185], s[46:47], 0, v[128:129]
	s_mov_b32 m0, s84
	s_addc_u32 s15, s47, 0
	global_load_lds_dwordx4 v[184:185], off
	v_lshl_add_u64 v[186:187], s[14:15], 0, v[132:133]
	s_mov_b32 m0, s85
	v_lshl_add_u64 v[248:249], s[54:55], 0, v[130:131]
	global_load_lds_dwordx4 v[186:187], off
	v_lshl_add_u64 v[186:187], s[14:15], 0, v[128:129]
	s_mov_b32 m0, s86
	s_nop 0
	global_load_lds_dwordx4 v[186:187], off
	v_lshl_add_u64 v[186:187], s[54:55], 0, v[134:135]
	s_mov_b32 m0, s58
	s_nop 0
	global_load_lds_dwordx4 v[186:187], off
	s_mov_b32 m0, s75
	s_nop 0
	global_load_lds_dwordx4 v[248:249], off
	s_waitcnt vmcnt(8)
	s_waitcnt lgkmcnt(0)
	s_barrier
	s_setprio 1
	s_waitcnt lgkmcnt(0)
	v_mfma_f32_16x16x32_bf16 v[0:3], v[104:107], v[200:203], v[0:3]
	v_mfma_f32_16x16x32_bf16 v[4:7], v[112:115], v[200:203], v[4:7]
	v_mfma_f32_16x16x32_bf16 v[136:139], v[104:107], v[48:51], v[136:139]
	v_mfma_f32_16x16x32_bf16 v[148:151], v[112:115], v[48:51], v[148:151]
	v_mfma_f32_16x16x32_bf16 v[152:155], v[104:107], v[96:99], v[152:155]
	v_mfma_f32_16x16x32_bf16 v[156:159], v[112:115], v[96:99], v[156:159]
	v_mfma_f32_16x16x32_bf16 v[160:163], v[104:107], v[192:195], v[160:163]
	v_mfma_f32_16x16x32_bf16 v[164:167], v[112:115], v[192:195], v[164:167]
	s_setprio 0
	s_setprio 1
	v_mfma_f32_16x16x32_bf16 v[0:3], v[108:111], v[204:207], v[0:3]
	v_mfma_f32_16x16x32_bf16 v[4:7], v[116:119], v[204:207], v[4:7]
	v_mfma_f32_16x16x32_bf16 v[136:139], v[108:111], v[52:55], v[136:139]
	v_mfma_f32_16x16x32_bf16 v[148:151], v[116:119], v[52:55], v[148:151]
	v_mfma_f32_16x16x32_bf16 v[152:155], v[108:111], v[188:191], v[152:155]
	v_mfma_f32_16x16x32_bf16 v[156:159], v[116:119], v[188:191], v[156:159]
	v_mfma_f32_16x16x32_bf16 v[160:163], v[108:111], v[196:199], v[160:163]
	v_mfma_f32_16x16x32_bf16 v[164:167], v[116:119], v[196:199], v[164:167]
	s_setprio 0
	s_setprio 1
	v_mfma_f32_16x16x32_bf16 v[8:11], v[120:123], v[48:51], v[8:11]
	v_mfma_f32_16x16x32_bf16 v[12:15], v[168:171], v[48:51], v[12:15]
	v_mfma_f32_16x16x32_bf16 v[24:27], v[120:123], v[96:99], v[24:27]
	v_mfma_f32_16x16x32_bf16 v[28:31], v[168:171], v[96:99], v[28:31]
	v_mfma_f32_16x16x32_bf16 v[48:51], v[120:123], v[192:195], v[60:63]
	v_mfma_f32_16x16x32_bf16 v[24:27], v[124:127], v[188:191], v[24:27]
	v_mfma_f32_16x16x32_bf16 v[28:31], v[172:175], v[188:191], v[28:31]
	v_mfma_f32_16x16x32_bf16 v[188:191], v[124:127], v[196:199], v[48:51]
	s_setprio 0
	s_setprio 1
	v_mfma_f32_16x16x32_bf16 v[48:51], v[168:171], v[192:195], v[100:103]
	v_mfma_f32_16x16x32_bf16 v[16:19], v[120:123], v[200:203], v[16:19]
	v_mfma_f32_16x16x32_bf16 v[8:11], v[124:127], v[52:55], v[8:11]
	v_mfma_f32_16x16x32_bf16 v[12:15], v[172:175], v[52:55], v[12:15]
	v_mfma_f32_16x16x32_bf16 v[192:195], v[172:175], v[196:199], v[48:51]
	v_mfma_f32_16x16x32_bf16 v[196:199], v[124:127], v[204:207], v[16:19]
	v_mfma_f32_16x16x32_bf16 v[16:19], v[168:171], v[200:203], v[20:23]
	v_mfma_f32_16x16x32_bf16 v[168:171], v[172:175], v[204:207], v[16:19]
	s_setprio 0
	s_barrier
; #define G_STAGE(bufoff, gbase, voff) do { _Pragma("unroll") for (int _i = 0; _i < 2; ++_i) \
;         __builtin_amdgcn_global_load_lds((const unsigned*)((const char*)(gbase) + voff[_i]), (LAS unsigned*)(lds + (bufoff) + ldsw + _i * 8192), 16, 0, 0); } while (0)
; #define G_LDA(dst, b, h) do { _Pragma("unroll") for (int m = 0; m < 4; ++m) _Pragma("unroll") for (int k = 0; k < 2; ++k) dst[m][k] = *(const LAS bf16x8*)(lds + G_SA(b, h) + aoff + m * 2048 + k * 1024); } while (0)
; #define G_LDB(dst, b, h) do { _Pragma("unroll") for (int n = 0; n < 2; ++n) _Pragma("unroll") for (int k = 0; k < 2; ++k) dst[n][k] = *(const LAS bf16x8*)(lds + G_SB(b, h) + boff + n * 2048 + k * 1024); } while (0)
; #define G_MMA(ai, bj, At_, Bt_) do { __builtin_amdgcn_s_setprio(1); _Pragma("unroll") for (int m = 0; m < 4; ++m) _Pragma("unroll") for (int n = 0; n < 2; ++n) _Pragma("unroll") for (int k = 0; k < 2; ++k) \
;         acc[ai][bj][m][n] = __builtin_amdgcn_mfma_f32_16x16x32_bf16(Bt_[n][k], At_[m][k], acc[ai][bj][m][n], 0, 0, 0); __builtin_amdgcn_s_setprio(0); } while (0)
; #define WAIT_V(n) asm volatile("s_waitcnt vmcnt(" #n ")" ::: "memory")
; #define WAIT_L(n) asm volatile("s_waitcnt lgkmcnt(" #n ")" ::: "memory")
; #define BAR __builtin_amdgcn_s_barrier()
; #define SCHED __builtin_amdgcn_sched_barrier(0)
; template <class Get, class Epi>
; DI void gemm_loop(int ntiles, int ld, char* shm, const Get& get, const Epi& epi) {
;     ...
;             G_LDB(B0, 1, 0); G_LDB(B1, 1, 1); SCHED; G_LDA(At, 1, 0); G_STAGE(G_SA(0, 1), a2 + hstep, voffA);
;             WAIT_V(8); WAIT_L(0); BAR; G_MMA(0, 0, At, B0); G_MMA(0, 1, At, B1); BAR; SCHED;
;             G_LDA(At, 1, 1); G_STAGE(G_SB(1, 0), b3, voffB); G_STAGE(G_SB(1, 1), b3 + hstep, voffB); G_STAGE(G_SA(1, 0), a3, voffA);
;             WAIT_V(8); WAIT_L(0); BAR; G_MMA(1, 0, At, B0); G_MMA(1, 1, At, B1); BAR; SCHED;
;         }
;         if (wr == 0) BAR;
	ds_read_b128 v[172:175], v145
	ds_read_b128 v[200:203], v145 offset:1024
	ds_read_b128 v[204:207], v145 offset:2048
	ds_read_b128 v[208:211], v145 offset:3072
	ds_read_b128 v[216:219], v146
	ds_read_b128 v[220:223], v146 offset:1024
	ds_read_b128 v[224:227], v146 offset:2048
	ds_read_b128 v[228:231], v146 offset:3072
	s_add_u32 s14, s54, 0x40000
	s_addc_u32 s15, s55, 0
	s_mov_b32 m0, s76
	v_lshl_add_u64 v[48:49], s[14:15], 0, v[134:135]
	ds_read_b128 v[16:19], v144 offset:32768
	ds_read_b128 v[20:23], v144 offset:33792
	ds_read_b128 v[60:63], v144 offset:34816
	ds_read_b128 v[108:111], v144 offset:35840
	ds_read_b128 v[232:235], v144 offset:36864
	ds_read_b128 v[236:239], v144 offset:37888
	ds_read_b128 v[240:243], v144 offset:38912
	ds_read_b128 v[244:247], v144 offset:39936
	global_load_lds_dwordx4 v[48:49], off
	v_lshl_add_u64 v[48:49], s[14:15], 0, v[130:131]
	s_mov_b32 m0, s78
	s_nop 0
	global_load_lds_dwordx4 v[48:49], off
	s_waitcnt vmcnt(8)
	s_waitcnt lgkmcnt(0)
	s_barrier
	s_setprio 1
	s_waitcnt lgkmcnt(0)
	v_mfma_f32_16x16x32_bf16 v[48:51], v[172:175], v[16:19], v[64:67]
	v_mfma_f32_16x16x32_bf16 v[112:115], v[200:203], v[20:23], v[48:51]
	v_mfma_f32_16x16x32_bf16 v[48:51], v[204:207], v[16:19], v[68:71]
	v_mfma_f32_16x16x32_bf16 v[116:119], v[208:211], v[20:23], v[48:51]
	v_mfma_f32_16x16x32_bf16 v[48:51], v[172:175], v[60:63], v[72:75]
	v_mfma_f32_16x16x32_bf16 v[96:99], v[200:203], v[108:111], v[48:51]
	v_mfma_f32_16x16x32_bf16 v[48:51], v[204:207], v[60:63], v[76:79]
	v_mfma_f32_16x16x32_bf16 v[100:103], v[208:211], v[108:111], v[48:51]
	s_setprio 0
	s_setprio 1
	v_mfma_f32_16x16x32_bf16 v[48:51], v[172:175], v[232:235], v[80:83]
	v_mfma_f32_16x16x32_bf16 v[80:83], v[200:203], v[236:239], v[48:51]
	v_mfma_f32_16x16x32_bf16 v[48:51], v[204:207], v[232:235], v[84:87]
	v_mfma_f32_16x16x32_bf16 v[84:87], v[208:211], v[236:239], v[48:51]
	v_mfma_f32_16x16x32_bf16 v[48:51], v[172:175], v[240:243], v[88:91]
	v_mfma_f32_16x16x32_bf16 v[52:55], v[204:207], v[240:243], v[92:95]
	v_mfma_f32_16x16x32_bf16 v[48:51], v[200:203], v[244:247], v[48:51]
	v_mfma_f32_16x16x32_bf16 v[52:55], v[208:211], v[244:247], v[52:55]
	s_setprio 0
	s_setprio 1
	v_mfma_f32_16x16x32_bf16 v[64:67], v[216:219], v[16:19], v[212:215]
	v_mfma_f32_16x16x32_bf16 v[16:19], v[224:227], v[16:19], v[32:35]
	v_mfma_f32_16x16x32_bf16 v[124:127], v[228:231], v[20:23], v[16:19]
	v_mfma_f32_16x16x32_bf16 v[16:19], v[216:219], v[60:63], v[36:39]
	v_mfma_f32_16x16x32_bf16 v[104:107], v[220:223], v[108:111], v[16:19]
	v_mfma_f32_16x16x32_bf16 v[16:19], v[224:227], v[60:63], v[40:43]
	v_mfma_f32_16x16x32_bf16 v[108:111], v[228:231], v[108:111], v[16:19]
	v_mfma_f32_16x16x32_bf16 v[16:19], v[216:219], v[232:235], v[44:47]
	s_setprio 0
	s_setprio 1
	v_mfma_f32_16x16x32_bf16 v[88:91], v[220:223], v[236:239], v[16:19]
	v_mfma_f32_16x16x32_bf16 v[16:19], v[224:227], v[232:235], v[176:179]
	v_mfma_f32_16x16x32_bf16 v[92:95], v[228:231], v[236:239], v[16:19]
	v_mfma_f32_16x16x32_bf16 v[16:19], v[216:219], v[240:243], v[180:183]
	v_mfma_f32_16x16x32_bf16 v[120:123], v[220:223], v[20:23], v[64:67]
	v_mfma_f32_16x16x32_bf16 v[64:67], v[220:223], v[244:247], v[16:19]
	v_mfma_f32_16x16x32_bf16 v[16:19], v[224:227], v[240:243], v[56:59]
	v_mfma_f32_16x16x32_bf16 v[68:71], v[228:231], v[244:247], v[16:19]
	s_setprio 0
	s_barrier
	s_mov_b32 m0, s87
	s_nop 3
	v_lshl_add_u64 v[16:17], v[140:141], 0, s[12:13]
	s_add_u32 s14, s46, 0x40080
	ds_read_b128 v[40:43], v144 offset:49152
	ds_read_b128 v[44:47], v144 offset:50176
	ds_read_b128 v[176:179], v144 offset:51200
	ds_read_b128 v[180:183], v144 offset:52224
	ds_read_b128 v[212:215], v144 offset:53248
	ds_read_b128 v[232:235], v144 offset:54272
	ds_read_b128 v[236:239], v144 offset:55296
	ds_read_b128 v[240:243], v144 offset:56320
	global_load_lds_dwordx4 v[16:17], off
	v_lshl_add_u64 v[16:17], v[184:185], 0, s[12:13]
	s_mov_b32 m0, s88
	s_addc_u32 s15, s47, 0
	global_load_lds_dwordx4 v[16:17], off
	v_lshl_add_u64 v[16:17], s[14:15], 0, v[132:133]
	s_mov_b32 m0, s89
	s_nop 0
	global_load_lds_dwordx4 v[16:17], off
	v_lshl_add_u64 v[16:17], s[14:15], 0, v[128:129]
	s_mov_b32 m0, s90
	s_nop 0
	global_load_lds_dwordx4 v[16:17], off
	v_lshl_add_u64 v[16:17], v[186:187], 0, s[12:13]
	s_mov_b32 m0, s79
	s_nop 0
	global_load_lds_dwordx4 v[16:17], off
	v_lshl_add_u64 v[16:17], v[248:249], 0, s[12:13]
	s_mov_b32 m0, s80
	s_nop 0
	global_load_lds_dwordx4 v[16:17], off
	s_waitcnt vmcnt(8)
	s_waitcnt lgkmcnt(0)
	s_barrier
	s_setprio 1
	s_waitcnt lgkmcnt(0)
	v_mfma_f32_16x16x32_bf16 v[16:19], v[172:175], v[40:43], v[136:139]
	v_mfma_f32_16x16x32_bf16 v[56:59], v[200:203], v[44:47], v[16:19]
	v_mfma_f32_16x16x32_bf16 v[16:19], v[204:207], v[40:43], v[148:151]
	v_mfma_f32_16x16x32_bf16 v[60:63], v[208:211], v[44:47], v[16:19]
	v_mfma_f32_16x16x32_bf16 v[16:19], v[172:175], v[176:179], v[152:155]
	v_mfma_f32_16x16x32_bf16 v[32:35], v[200:203], v[180:183], v[16:19]
	v_mfma_f32_16x16x32_bf16 v[16:19], v[204:207], v[176:179], v[156:159]
	v_mfma_f32_16x16x32_bf16 v[36:39], v[208:211], v[180:183], v[16:19]
	s_setprio 0
	s_setprio 1
	v_mfma_f32_16x16x32_bf16 v[16:19], v[172:175], v[212:215], v[160:163]
	v_mfma_f32_16x16x32_bf16 v[20:23], v[204:207], v[212:215], v[164:167]
	v_mfma_f32_16x16x32_bf16 v[0:3], v[172:175], v[236:239], v[0:3]
	v_mfma_f32_16x16x32_bf16 v[4:7], v[204:207], v[236:239], v[4:7]
	v_mfma_f32_16x16x32_bf16 v[16:19], v[200:203], v[232:235], v[16:19]
	v_mfma_f32_16x16x32_bf16 v[20:23], v[208:211], v[232:235], v[20:23]
	v_mfma_f32_16x16x32_bf16 v[0:3], v[200:203], v[240:243], v[0:3]
	v_mfma_f32_16x16x32_bf16 v[4:7], v[208:211], v[240:243], v[4:7]
	s_setprio 0
	s_setprio 1
	v_mfma_f32_16x16x32_bf16 v[8:11], v[216:219], v[40:43], v[8:11]
	v_mfma_f32_16x16x32_bf16 v[72:75], v[220:223], v[44:47], v[8:11]
	v_mfma_f32_16x16x32_bf16 v[8:11], v[224:227], v[40:43], v[12:15]
	v_mfma_f32_16x16x32_bf16 v[76:79], v[228:231], v[44:47], v[8:11]
	v_mfma_f32_16x16x32_bf16 v[8:11], v[216:219], v[176:179], v[24:27]
	v_mfma_f32_16x16x32_bf16 v[40:43], v[220:223], v[180:183], v[8:11]
	v_mfma_f32_16x16x32_bf16 v[8:11], v[224:227], v[176:179], v[28:31]
	v_mfma_f32_16x16x32_bf16 v[44:47], v[228:231], v[180:183], v[8:11]
	s_setprio 0
	s_setprio 1
	v_mfma_f32_16x16x32_bf16 v[8:11], v[216:219], v[212:215], v[188:191]
	v_mfma_f32_16x16x32_bf16 v[24:27], v[220:223], v[232:235], v[8:11]
	v_mfma_f32_16x16x32_bf16 v[8:11], v[224:227], v[212:215], v[192:195]
	v_mfma_f32_16x16x32_bf16 v[28:31], v[228:231], v[232:235], v[8:11]
	v_mfma_f32_16x16x32_bf16 v[8:11], v[216:219], v[236:239], v[196:199]
	v_mfma_f32_16x16x32_bf16 v[12:15], v[224:227], v[236:239], v[168:171]
	v_mfma_f32_16x16x32_bf16 v[8:11], v[220:223], v[240:243], v[8:11]
	v_mfma_f32_16x16x32_bf16 v[12:15], v[228:231], v[240:243], v[12:15]
	s_setprio 0
	s_barrier
	s_and_b64 vcc, exec, s[2:3]
	s_cbranch_vccnz .LBB0_334
	s_barrier

; #define G_STAGE(bufoff, gbase, voff) do { _Pragma("unroll") for (int _i = 0; _i < 2; ++_i) \
;         __builtin_amdgcn_global_load_lds((const unsigned*)((const char*)(gbase) + voff[_i]), (LAS unsigned*)(lds + (bufoff) + ldsw + _i * 8192), 16, 0, 0); } while (0)
; #define G_LDA(dst, b, h) do { _Pragma("unroll") for (int m = 0; m < 4; ++m) _Pragma("unroll") for (int k = 0; k < 2; ++k) dst[m][k] = *(const LAS bf16x8*)(lds + G_SA(b, h) + aoff + m * 2048 + k * 1024); } while (0)
; #define G_LDB(dst, b, h) do { _Pragma("unroll") for (int n = 0; n < 2; ++n) _Pragma("unroll") for (int k = 0; k < 2; ++k) dst[n][k] = *(const LAS bf16x8*)(lds + G_SB(b, h) + boff + n * 2048 + k * 1024); } while (0)
; #define G_MMA(ai, bj, At_, Bt_) do { __builtin_amdgcn_s_setprio(1); _Pragma("unroll") for (int m = 0; m < 4; ++m) _Pragma("unroll") for (int n = 0; n < 2; ++n) _Pragma("unroll") for (int k = 0; k < 2; ++k) \
;         acc[ai][bj][m][n] = __builtin_amdgcn_mfma_f32_16x16x32_bf16(Bt_[n][k], At_[m][k], acc[ai][bj][m][n], 0, 0, 0); __builtin_amdgcn_s_setprio(0); } while (0)
; #define WAIT_V(n) asm volatile("s_waitcnt vmcnt(" #n ")" ::: "memory")
; #define WAIT_L(n) asm volatile("s_waitcnt lgkmcnt(" #n ")" ::: "memory")
; #define BAR __builtin_amdgcn_s_barrier()
; #define SCHED __builtin_amdgcn_sched_barrier(0)
; template <class Get, class Epi>
; DI void gemm_loop(int ntiles, int ld, char* shm, const Get& get, const Epi& epi) {
;     ...
;             G_LDB(B0, 0, 0); G_LDB(B1, 0, 1); SCHED; G_LDA(At, 0, 0); G_STAGE(G_SA(1, 1), a1 + hstep, voffA);
;             WAIT_V(8); WAIT_L(0); BAR; G_MMA(0, 0, At, B0); G_MMA(0, 1, At, B1); BAR; SCHED;
;             G_LDA(At, 0, 1); G_STAGE(G_SB(0, 0), b2, voffB); G_STAGE(G_SB(0, 1), b2 + hstep, voffB); G_STAGE(G_SA(0, 0), a2, voffA);
;             WAIT_V(8); WAIT_L(0); BAR; G_MMA(1, 0, At, B0); G_MMA(1, 1, At, B1); BAR; SCHED;
.Lrj_431_0:
	s_waitcnt lgkmcnt(0)
	s_barrier
	s_setprio 1
	s_waitcnt lgkmcnt(0)
	v_mfma_f32_16x16x32_bf16 v[124:127], v[146:149], v[178:181], 0
	v_mfma_f32_16x16x32_bf16 v[120:123], v[154:157], v[178:181], 0
	v_mfma_f32_16x16x32_bf16 v[116:119], v[146:149], v[192:195], 0
	v_mfma_f32_16x16x32_bf16 v[112:115], v[154:157], v[192:195], 0
	v_mfma_f32_16x16x32_bf16 v[100:103], v[146:149], v[200:203], 0
	v_mfma_f32_16x16x32_bf16 v[96:99], v[154:157], v[200:203], 0
	v_mfma_f32_16x16x32_bf16 v[84:87], v[146:149], v[208:211], 0
	v_mfma_f32_16x16x32_bf16 v[80:83], v[154:157], v[208:211], 0
	s_setprio 0
	s_setprio 1
	v_mfma_f32_16x16x32_bf16 v[124:127], v[150:153], v[188:191], v[124:127]
	v_mfma_f32_16x16x32_bf16 v[120:123], v[158:161], v[188:191], v[120:123]
	v_mfma_f32_16x16x32_bf16 v[116:119], v[150:153], v[196:199], v[116:119]
	v_mfma_f32_16x16x32_bf16 v[112:115], v[158:161], v[196:199], v[112:115]
	v_mfma_f32_16x16x32_bf16 v[100:103], v[150:153], v[204:207], v[100:103]
	v_mfma_f32_16x16x32_bf16 v[96:99], v[158:161], v[204:207], v[96:99]
	v_mfma_f32_16x16x32_bf16 v[84:87], v[150:153], v[212:215], v[84:87]
	v_mfma_f32_16x16x32_bf16 v[80:83], v[158:161], v[212:215], v[80:83]
	s_setprio 0
	s_setprio 1
	v_mfma_f32_16x16x32_bf16 v[108:111], v[162:165], v[178:181], 0
	v_mfma_f32_16x16x32_bf16 v[104:107], v[170:173], v[178:181], 0
	v_mfma_f32_16x16x32_bf16 v[92:95], v[162:165], v[192:195], 0
	v_mfma_f32_16x16x32_bf16 v[88:91], v[170:173], v[192:195], 0
	v_mfma_f32_16x16x32_bf16 v[76:79], v[162:165], v[200:203], 0
	v_mfma_f32_16x16x32_bf16 v[72:75], v[170:173], v[200:203], 0
	v_mfma_f32_16x16x32_bf16 v[68:71], v[162:165], v[208:211], 0
	v_mfma_f32_16x16x32_bf16 v[64:67], v[170:173], v[208:211], 0
	s_setprio 0
	s_setprio 1
	v_mfma_f32_16x16x32_bf16 v[108:111], v[166:169], v[188:191], v[108:111]
	v_mfma_f32_16x16x32_bf16 v[104:107], v[174:177], v[188:191], v[104:107]
	v_mfma_f32_16x16x32_bf16 v[92:95], v[166:169], v[196:199], v[92:95]
	v_mfma_f32_16x16x32_bf16 v[88:91], v[174:177], v[196:199], v[88:91]
	v_mfma_f32_16x16x32_bf16 v[76:79], v[166:169], v[204:207], v[76:79]
	v_mfma_f32_16x16x32_bf16 v[72:75], v[174:177], v[204:207], v[72:75]
	v_mfma_f32_16x16x32_bf16 v[68:71], v[166:169], v[212:215], v[68:71]
	v_mfma_f32_16x16x32_bf16 v[64:67], v[174:177], v[212:215], v[64:67]
	s_setprio 0
	s_barrier
	s_add_i32 s82, s54, s38
	v_lshl_add_u64 v[182:183], s[14:15], 0, v[132:133]
	s_mov_b32 m0, s82
	ds_read_b128 v[178:181], v143 offset:16384
	ds_read_b128 v[188:191], v143 offset:17408
	ds_read_b128 v[192:195], v143 offset:18432
	ds_read_b128 v[196:199], v143 offset:19456
	ds_read_b128 v[200:203], v143 offset:20480
	ds_read_b128 v[204:207], v143 offset:21504
	ds_read_b128 v[208:211], v143 offset:22528
	ds_read_b128 v[212:215], v143 offset:23552
	global_load_lds_dwordx4 v[182:183], off
	s_add_i32 m0, s82, 0x2000
	s_add_u32 s82, s14, 0x100000
	v_lshl_add_u64 v[184:185], s[14:15], 0, v[128:129]
	s_addc_u32 s83, s15, 0
	s_add_i32 s84, s55, s38
	global_load_lds_dwordx4 v[184:185], off
	v_lshl_add_u64 v[186:187], s[82:83], 0, v[132:133]
	s_mov_b32 m0, s84
	v_lshl_add_u64 v[216:217], s[36:37], 0, v[130:131]
	global_load_lds_dwordx4 v[186:187], off
	v_lshl_add_u64 v[186:187], s[82:83], 0, v[128:129]
	s_add_i32 m0, s84, 0x2000
	s_nop 0
	global_load_lds_dwordx4 v[186:187], off
	v_lshl_add_u64 v[186:187], s[36:37], 0, v[134:135]
	s_mov_b32 m0, s43
	s_nop 0
	global_load_lds_dwordx4 v[186:187], off
	s_mov_b32 m0, s44
	s_nop 0
	global_load_lds_dwordx4 v[216:217], off
	s_cmp_lg_u32 s100, 0
	s_cbranch_scc0 .Lrf_431_1
	s_waitcnt vmcnt(16)
	s_branch .Lrj_431_1

; #define G_STAGE(bufoff, gbase, voff) do { _Pragma("unroll") for (int _i = 0; _i < 2; ++_i) \
;         __builtin_amdgcn_global_load_lds((const unsigned*)((const char*)(gbase) + voff[_i]), (LAS unsigned*)(lds + (bufoff) + ldsw + _i * 8192), 16, 0, 0); } while (0)
; #define G_LDA(dst, b, h) do { _Pragma("unroll") for (int m = 0; m < 4; ++m) _Pragma("unroll") for (int k = 0; k < 2; ++k) dst[m][k] = *(const LAS bf16x8*)(lds + G_SA(b, h) + aoff + m * 2048 + k * 1024); } while (0)
; #define G_LDB(dst, b, h) do { _Pragma("unroll") for (int n = 0; n < 2; ++n) _Pragma("unroll") for (int k = 0; k < 2; ++k) dst[n][k] = *(const LAS bf16x8*)(lds + G_SB(b, h) + boff + n * 2048 + k * 1024); } while (0)
; #define G_MMA(ai, bj, At_, Bt_) do { __builtin_amdgcn_s_setprio(1); _Pragma("unroll") for (int m = 0; m < 4; ++m) _Pragma("unroll") for (int n = 0; n < 2; ++n) _Pragma("unroll") for (int k = 0; k < 2; ++k) \
;         acc[ai][bj][m][n] = __builtin_amdgcn_mfma_f32_16x16x32_bf16(Bt_[n][k], At_[m][k], acc[ai][bj][m][n], 0, 0, 0); __builtin_amdgcn_s_setprio(0); } while (0)
; #define WAIT_V(n) asm volatile("s_waitcnt vmcnt(" #n ")" ::: "memory")
; #define WAIT_L(n) asm volatile("s_waitcnt lgkmcnt(" #n ")" ::: "memory")
; #define BAR __builtin_amdgcn_s_barrier()
; #define SCHED __builtin_amdgcn_sched_barrier(0)
; template <class Get, class Epi>
; DI void gemm_loop(int ntiles, int ld, char* shm, const Get& get, const Epi& epi) {
;     ...
;             WAIT_V(8); WAIT_L(0); BAR; G_MMA(1, 0, At, B0); G_MMA(1, 1, At, B1); BAR; SCHED;
;             G_LDB(B0, 1, 0); G_LDB(B1, 1, 1); SCHED; G_LDA(At, 1, 0); G_STAGE(G_SA(0, 1), a2 + hstep, voffA);
;             WAIT_V(8); WAIT_L(0); BAR; G_MMA(0, 0, At, B0); G_MMA(0, 1, At, B1); BAR; SCHED;
.Lrj_431_1:
	s_waitcnt lgkmcnt(0)
	s_barrier
	s_setprio 1
	s_waitcnt lgkmcnt(0)
	v_mfma_f32_16x16x32_bf16 v[60:63], v[146:149], v[178:181], 0
	v_mfma_f32_16x16x32_bf16 v[56:59], v[154:157], v[178:181], 0
	v_mfma_f32_16x16x32_bf16 v[52:55], v[146:149], v[192:195], 0
	v_mfma_f32_16x16x32_bf16 v[48:51], v[154:157], v[192:195], 0
	v_mfma_f32_16x16x32_bf16 v[36:39], v[146:149], v[200:203], 0
	v_mfma_f32_16x16x32_bf16 v[32:35], v[154:157], v[200:203], 0
	v_mfma_f32_16x16x32_bf16 v[20:23], v[146:149], v[208:211], 0
	v_mfma_f32_16x16x32_bf16 v[16:19], v[154:157], v[208:211], 0
	s_setprio 0
	s_setprio 1
	v_mfma_f32_16x16x32_bf16 v[60:63], v[150:153], v[188:191], v[60:63]
	v_mfma_f32_16x16x32_bf16 v[56:59], v[158:161], v[188:191], v[56:59]
	v_mfma_f32_16x16x32_bf16 v[52:55], v[150:153], v[196:199], v[52:55]
	v_mfma_f32_16x16x32_bf16 v[48:51], v[158:161], v[196:199], v[48:51]
	v_mfma_f32_16x16x32_bf16 v[36:39], v[150:153], v[204:207], v[36:39]
	v_mfma_f32_16x16x32_bf16 v[32:35], v[158:161], v[204:207], v[32:35]
	v_mfma_f32_16x16x32_bf16 v[20:23], v[150:153], v[212:215], v[20:23]
	v_mfma_f32_16x16x32_bf16 v[16:19], v[158:161], v[212:215], v[16:19]
	s_setprio 0
	s_setprio 1
	v_mfma_f32_16x16x32_bf16 v[44:47], v[162:165], v[178:181], 0
	v_mfma_f32_16x16x32_bf16 v[40:43], v[170:173], v[178:181], 0
	v_mfma_f32_16x16x32_bf16 v[28:31], v[162:165], v[192:195], 0
	v_mfma_f32_16x16x32_bf16 v[24:27], v[170:173], v[192:195], 0
	v_mfma_f32_16x16x32_bf16 v[12:15], v[162:165], v[200:203], 0
	v_mfma_f32_16x16x32_bf16 v[8:11], v[170:173], v[200:203], 0
	v_mfma_f32_16x16x32_bf16 v[4:7], v[162:165], v[208:211], 0
	v_mfma_f32_16x16x32_bf16 v[0:3], v[170:173], v[208:211], 0
	s_setprio 0
	s_setprio 1
	v_mfma_f32_16x16x32_bf16 v[44:47], v[166:169], v[188:191], v[44:47]
	v_mfma_f32_16x16x32_bf16 v[40:43], v[174:177], v[188:191], v[40:43]
	v_mfma_f32_16x16x32_bf16 v[28:31], v[166:169], v[196:199], v[28:31]
	v_mfma_f32_16x16x32_bf16 v[24:27], v[174:177], v[196:199], v[24:27]
	v_mfma_f32_16x16x32_bf16 v[12:15], v[166:169], v[204:207], v[12:15]
	v_mfma_f32_16x16x32_bf16 v[8:11], v[174:177], v[204:207], v[8:11]
	v_mfma_f32_16x16x32_bf16 v[4:7], v[166:169], v[212:215], v[4:7]
	v_mfma_f32_16x16x32_bf16 v[0:3], v[174:177], v[212:215], v[0:3]
	s_setprio 0
	s_barrier
	s_add_i32 s82, 0, 0x18000
	v_add_u32_e32 v145, s82, v140
	s_add_i32 s83, 0, 0x1c000
	ds_read_b128 v[146:149], v145
	ds_read_b128 v[150:153], v145 offset:1024
	ds_read_b128 v[154:157], v145 offset:2048
	ds_read_b128 v[158:161], v145 offset:3072
	v_add_u32_e32 v145, s83, v140
	ds_read_b128 v[162:165], v145
	ds_read_b128 v[166:169], v145 offset:1024
	ds_read_b128 v[170:173], v145 offset:2048
	ds_read_b128 v[174:177], v145 offset:3072
	s_add_u32 s36, s36, 0x100000
	s_addc_u32 s37, s37, 0
	s_mov_b32 m0, s45
	v_lshl_add_u64 v[218:219], s[36:37], 0, v[134:135]
	ds_read_b128 v[178:181], v143 offset:32768
	ds_read_b128 v[188:191], v143 offset:33792
	ds_read_b128 v[192:195], v143 offset:34816
	ds_read_b128 v[196:199], v143 offset:35840
	ds_read_b128 v[200:203], v143 offset:36864
	ds_read_b128 v[204:207], v143 offset:37888
	ds_read_b128 v[208:211], v143 offset:38912
	ds_read_b128 v[212:215], v143 offset:39936
	global_load_lds_dwordx4 v[218:219], off
	v_lshl_add_u64 v[218:219], s[36:37], 0, v[130:131]
	s_mov_b32 m0, s46
	s_nop 0
	global_load_lds_dwordx4 v[218:219], off
	s_waitcnt vmcnt(8)
	s_waitcnt lgkmcnt(0)
	s_barrier
	s_setprio 1
	s_waitcnt lgkmcnt(0)
	v_mfma_f32_16x16x32_bf16 v[124:127], v[146:149], v[178:181], v[124:127]
	v_mfma_f32_16x16x32_bf16 v[120:123], v[154:157], v[178:181], v[120:123]
	v_mfma_f32_16x16x32_bf16 v[116:119], v[146:149], v[192:195], v[116:119]
	v_mfma_f32_16x16x32_bf16 v[112:115], v[154:157], v[192:195], v[112:115]
	v_mfma_f32_16x16x32_bf16 v[100:103], v[146:149], v[200:203], v[100:103]
	v_mfma_f32_16x16x32_bf16 v[96:99], v[154:157], v[200:203], v[96:99]
	v_mfma_f32_16x16x32_bf16 v[84:87], v[146:149], v[208:211], v[84:87]
	v_mfma_f32_16x16x32_bf16 v[80:83], v[154:157], v[208:211], v[80:83]
	s_setprio 0
	s_setprio 1
	v_mfma_f32_16x16x32_bf16 v[124:127], v[150:153], v[188:191], v[124:127]
	v_mfma_f32_16x16x32_bf16 v[120:123], v[158:161], v[188:191], v[120:123]
	v_mfma_f32_16x16x32_bf16 v[116:119], v[150:153], v[196:199], v[116:119]
	v_mfma_f32_16x16x32_bf16 v[112:115], v[158:161], v[196:199], v[112:115]
	v_mfma_f32_16x16x32_bf16 v[100:103], v[150:153], v[204:207], v[100:103]
	v_mfma_f32_16x16x32_bf16 v[96:99], v[158:161], v[204:207], v[96:99]
	v_mfma_f32_16x16x32_bf16 v[84:87], v[150:153], v[212:215], v[84:87]
	v_mfma_f32_16x16x32_bf16 v[80:83], v[158:161], v[212:215], v[80:83]
	s_setprio 0
	s_setprio 1
	v_mfma_f32_16x16x32_bf16 v[108:111], v[162:165], v[178:181], v[108:111]
	v_mfma_f32_16x16x32_bf16 v[104:107], v[170:173], v[178:181], v[104:107]
	v_mfma_f32_16x16x32_bf16 v[92:95], v[162:165], v[192:195], v[92:95]
	v_mfma_f32_16x16x32_bf16 v[88:91], v[170:173], v[192:195], v[88:91]
	v_mfma_f32_16x16x32_bf16 v[76:79], v[162:165], v[200:203], v[76:79]
	v_mfma_f32_16x16x32_bf16 v[72:75], v[170:173], v[200:203], v[72:75]
	v_mfma_f32_16x16x32_bf16 v[68:71], v[162:165], v[208:211], v[68:71]
	v_mfma_f32_16x16x32_bf16 v[64:67], v[170:173], v[208:211], v[64:67]
	s_setprio 0
	s_setprio 1
	v_mfma_f32_16x16x32_bf16 v[108:111], v[166:169], v[188:191], v[108:111]
	v_mfma_f32_16x16x32_bf16 v[104:107], v[174:177], v[188:191], v[104:107]
	v_mfma_f32_16x16x32_bf16 v[92:95], v[166:169], v[196:199], v[92:95]
	v_mfma_f32_16x16x32_bf16 v[88:91], v[174:177], v[196:199], v[88:91]
	v_mfma_f32_16x16x32_bf16 v[76:79], v[166:169], v[204:207], v[76:79]
	v_mfma_f32_16x16x32_bf16 v[72:75], v[174:177], v[204:207], v[72:75]
	v_mfma_f32_16x16x32_bf16 v[68:71], v[166:169], v[212:215], v[68:71]
	v_mfma_f32_16x16x32_bf16 v[64:67], v[174:177], v[212:215], v[64:67]
	s_setprio 0
	s_barrier
; #define G_STAGE(bufoff, gbase, voff) do { _Pragma("unroll") for (int _i = 0; _i < 2; ++_i) \
;         __builtin_amdgcn_global_load_lds((const unsigned*)((const char*)(gbase) + voff[_i]), (LAS unsigned*)(lds + (bufoff) + ldsw + _i * 8192), 16, 0, 0); } while (0)
; #define G_LDA(dst, b, h) do { _Pragma("unroll") for (int m = 0; m < 4; ++m) _Pragma("unroll") for (int k = 0; k < 2; ++k) dst[m][k] = *(const LAS bf16x8*)(lds + G_SA(b, h) + aoff + m * 2048 + k * 1024); } while (0)
; #define G_LDB(dst, b, h) do { _Pragma("unroll") for (int n = 0; n < 2; ++n) _Pragma("unroll") for (int k = 0; k < 2; ++k) dst[n][k] = *(const LAS bf16x8*)(lds + G_SB(b, h) + boff + n * 2048 + k * 1024); } while (0)
; #define G_MMA(ai, bj, At_, Bt_) do { __builtin_amdgcn_s_setprio(1); _Pragma("unroll") for (int m = 0; m < 4; ++m) _Pragma("unroll") for (int n = 0; n < 2; ++n) _Pragma("unroll") for (int k = 0; k < 2; ++k) \
;         acc[ai][bj][m][n] = __builtin_amdgcn_mfma_f32_16x16x32_bf16(Bt_[n][k], At_[m][k], acc[ai][bj][m][n], 0, 0, 0); __builtin_amdgcn_s_setprio(0); } while (0)
; #define WAIT_V(n) asm volatile("s_waitcnt vmcnt(" #n ")" ::: "memory")
; #define WAIT_L(n) asm volatile("s_waitcnt lgkmcnt(" #n ")" ::: "memory")
; #define BAR __builtin_amdgcn_s_barrier()
; #define SCHED __builtin_amdgcn_sched_barrier(0)
; template <class Get, class Epi>
; DI void gemm_loop(int ntiles, int ld, char* shm, const Get& get, const Epi& epi) {
;     ...
;         for (int t = 0; t < nt; t += 2) {
;             const bool last = (t == nt - 2);
;             const char* a1 = cA + (size_t)(t + 1) * kstep;
;             const char* a2 = last ? nA : cA + (size_t)(t + 2) * kstep; const char* b2 = last ? nB : cB + (size_t)(t + 2) * kstep;
;             const char* a3 = a2 + kstep; const char* b3 = b2 + kstep;
;             G_LDB(B0, 0, 0); G_LDB(B1, 0, 1); SCHED; G_LDA(At, 0, 0); G_STAGE(G_SA(1, 1), a1 + hstep, voffA);
;     ...
;             G_LDA(At, 1, 1); G_STAGE(G_SB(1, 0), b3, voffB); G_STAGE(G_SB(1, 1), b3 + hstep, voffB); G_STAGE(G_SA(1, 0), a3, voffA);
;             WAIT_V(8); WAIT_L(0); BAR; G_MMA(1, 0, At, B0); G_MMA(1, 1, At, B1); BAR; SCHED;
;         }
	s_add_i32 s36, s82, s38
	v_lshl_add_u64 v[182:183], v[182:183], 0, s[8:9]
	s_mov_b32 m0, s36
	ds_read_b128 v[178:181], v143 offset:49152
	ds_read_b128 v[188:191], v143 offset:50176
	ds_read_b128 v[192:195], v143 offset:51200
	ds_read_b128 v[196:199], v143 offset:52224
	ds_read_b128 v[200:203], v143 offset:53248
	ds_read_b128 v[204:207], v143 offset:54272
	ds_read_b128 v[208:211], v143 offset:55296
	ds_read_b128 v[212:215], v143 offset:56320
	global_load_lds_dwordx4 v[182:183], off
	s_add_i32 m0, s36, 0x2000
	s_add_u32 s14, s14, 0x100080
	v_lshl_add_u64 v[182:183], v[184:185], 0, s[8:9]
	s_addc_u32 s15, s15, 0
	s_add_i32 s36, s83, s38
	global_load_lds_dwordx4 v[182:183], off
	v_lshl_add_u64 v[182:183], s[14:15], 0, v[132:133]
	s_mov_b32 m0, s36
	s_nop 0
	global_load_lds_dwordx4 v[182:183], off
	v_lshl_add_u64 v[182:183], s[14:15], 0, v[128:129]
	s_add_i32 m0, s36, 0x2000
	s_nop 0
	global_load_lds_dwordx4 v[182:183], off
	v_lshl_add_u64 v[182:183], v[186:187], 0, s[8:9]
	s_mov_b32 m0, s47
	s_nop 0
	global_load_lds_dwordx4 v[182:183], off
	v_lshl_add_u64 v[182:183], v[216:217], 0, s[8:9]
	s_mov_b32 m0, s50
	s_nop 0
	global_load_lds_dwordx4 v[182:183], off
	s_waitcnt vmcnt(8)
	s_waitcnt lgkmcnt(0)
	s_barrier
	s_setprio 1
	s_waitcnt lgkmcnt(0)
	v_mfma_f32_16x16x32_bf16 v[60:63], v[146:149], v[178:181], v[60:63]
	v_mfma_f32_16x16x32_bf16 v[56:59], v[154:157], v[178:181], v[56:59]
	v_mfma_f32_16x16x32_bf16 v[52:55], v[146:149], v[192:195], v[52:55]
	v_mfma_f32_16x16x32_bf16 v[48:51], v[154:157], v[192:195], v[48:51]
	v_mfma_f32_16x16x32_bf16 v[36:39], v[146:149], v[200:203], v[36:39]
	v_mfma_f32_16x16x32_bf16 v[32:35], v[154:157], v[200:203], v[32:35]
	v_mfma_f32_16x16x32_bf16 v[20:23], v[146:149], v[208:211], v[20:23]
	v_mfma_f32_16x16x32_bf16 v[16:19], v[154:157], v[208:211], v[16:19]
	s_setprio 0
	s_setprio 1
	v_mfma_f32_16x16x32_bf16 v[60:63], v[150:153], v[188:191], v[60:63]
	v_mfma_f32_16x16x32_bf16 v[56:59], v[158:161], v[188:191], v[56:59]
	v_mfma_f32_16x16x32_bf16 v[52:55], v[150:153], v[196:199], v[52:55]
	v_mfma_f32_16x16x32_bf16 v[48:51], v[158:161], v[196:199], v[48:51]
	v_mfma_f32_16x16x32_bf16 v[36:39], v[150:153], v[204:207], v[36:39]
	v_mfma_f32_16x16x32_bf16 v[32:35], v[158:161], v[204:207], v[32:35]
	v_mfma_f32_16x16x32_bf16 v[20:23], v[150:153], v[212:215], v[20:23]
	v_mfma_f32_16x16x32_bf16 v[16:19], v[158:161], v[212:215], v[16:19]
	s_setprio 0
	s_setprio 1
	v_mfma_f32_16x16x32_bf16 v[44:47], v[162:165], v[178:181], v[44:47]
	v_mfma_f32_16x16x32_bf16 v[40:43], v[170:173], v[178:181], v[40:43]
	v_mfma_f32_16x16x32_bf16 v[28:31], v[162:165], v[192:195], v[28:31]
	v_mfma_f32_16x16x32_bf16 v[24:27], v[170:173], v[192:195], v[24:27]
	v_mfma_f32_16x16x32_bf16 v[12:15], v[162:165], v[200:203], v[12:15]
	v_mfma_f32_16x16x32_bf16 v[8:11], v[170:173], v[200:203], v[8:11]
	v_mfma_f32_16x16x32_bf16 v[4:7], v[162:165], v[208:211], v[4:7]
	v_mfma_f32_16x16x32_bf16 v[0:3], v[170:173], v[208:211], v[0:3]
	s_setprio 0
	s_setprio 1
	v_mfma_f32_16x16x32_bf16 v[44:47], v[166:169], v[188:191], v[44:47]
	v_mfma_f32_16x16x32_bf16 v[40:43], v[174:177], v[188:191], v[40:43]
	v_mfma_f32_16x16x32_bf16 v[28:31], v[166:169], v[196:199], v[28:31]
	v_mfma_f32_16x16x32_bf16 v[24:27], v[174:177], v[196:199], v[24:27]
	v_mfma_f32_16x16x32_bf16 v[12:15], v[166:169], v[204:207], v[12:15]
	v_mfma_f32_16x16x32_bf16 v[8:11], v[174:177], v[204:207], v[8:11]
	v_mfma_f32_16x16x32_bf16 v[4:7], v[166:169], v[212:215], v[4:7]
	v_mfma_f32_16x16x32_bf16 v[0:3], v[174:177], v[212:215], v[0:3]
	s_setprio 0
	s_barrier
	s_add_i32 s81, s81, 2
	s_add_u32 s34, s34, 0x100
	s_addc_u32 s35, s35, 0
	s_add_u32 s79, s79, 0x100
	s_addc_u32 s80, s80, 0
	s_cmp_gt_u32 s81, 61
	s_cbranch_scc0 .LBB0_431
	s_branch .Lpost_431
.LBB0_431:
	ds_read_b128 v[146:149], v141
	ds_read_b128 v[150:153], v141 offset:1024
	ds_read_b128 v[154:157], v141 offset:2048
	ds_read_b128 v[158:161], v141 offset:3072
	ds_read_b128 v[162:165], v142
	ds_read_b128 v[166:169], v142 offset:1024
	ds_read_b128 v[170:173], v142 offset:2048
	ds_read_b128 v[174:177], v142 offset:3072
	s_add_u32 s14, s34, 0xfff00080
	s_addc_u32 s15, s35, -1
	s_cmp_eq_u32 s81, 60
	s_cselect_b32 s37, s74, s15
	s_cselect_b32 s36, s75, s14
	s_cselect_b32 s15, s76, s80
	s_cselect_b32 s14, s78, s79
	s_mov_b32 m0, s56
	v_lshl_add_u64 v[182:183], s[34:35], 0, v[136:137]
	ds_read_b128 v[178:181], v143
	ds_read_b128 v[188:191], v143 offset:1024
	ds_read_b128 v[192:195], v143 offset:2048
	ds_read_b128 v[196:199], v143 offset:3072
	ds_read_b128 v[200:203], v143 offset:4096
	ds_read_b128 v[204:207], v143 offset:5120
	ds_read_b128 v[208:211], v143 offset:6144
	ds_read_b128 v[212:215], v143 offset:7168
	global_load_lds_dwordx4 v[182:183], off
	v_lshl_add_u64 v[182:183], s[34:35], 0, v[138:139]
	s_add_i32 m0, s43, 0xe000
	s_nop 0
	global_load_lds_dwordx4 v[182:183], off
	s_waitcnt vmcnt(8)
	s_waitcnt lgkmcnt(0)
	s_barrier
; #define G_STAGE(bufoff, gbase, voff) do { _Pragma("unroll") for (int _i = 0; _i < 2; ++_i) \
;         __builtin_amdgcn_global_load_lds((const unsigned*)((const char*)(gbase) + voff[_i]), (LAS unsigned*)(lds + (bufoff) + ldsw + _i * 8192), 16, 0, 0); } while (0)
; #define G_LDA(dst, b, h) do { _Pragma("unroll") for (int m = 0; m < 4; ++m) _Pragma("unroll") for (int k = 0; k < 2; ++k) dst[m][k] = *(const LAS bf16x8*)(lds + G_SA(b, h) + aoff + m * 2048 + k * 1024); } while (0)
; #define G_LDB(dst, b, h) do { _Pragma("unroll") for (int n = 0; n < 2; ++n) _Pragma("unroll") for (int k = 0; k < 2; ++k) dst[n][k] = *(const LAS bf16x8*)(lds + G_SB(b, h) + boff + n * 2048 + k * 1024); } while (0)
; #define G_MMA(ai, bj, At_, Bt_) do { __builtin_amdgcn_s_setprio(1); _Pragma("unroll") for (int m = 0; m < 4; ++m) _Pragma("unroll") for (int n = 0; n < 2; ++n) _Pragma("unroll") for (int k = 0; k < 2; ++k) \
;         acc[ai][bj][m][n] = __builtin_amdgcn_mfma_f32_16x16x32_bf16(Bt_[n][k], At_[m][k], acc[ai][bj][m][n], 0, 0, 0); __builtin_amdgcn_s_setprio(0); } while (0)
; #define WAIT_V(n) asm volatile("s_waitcnt vmcnt(" #n ")" ::: "memory")
; #define WAIT_L(n) asm volatile("s_waitcnt lgkmcnt(" #n ")" ::: "memory")
; #define BAR __builtin_amdgcn_s_barrier()
; #define SCHED __builtin_amdgcn_sched_barrier(0)
; template <class Get, class Epi>
; DI void gemm_loop(int ntiles, int ld, char* shm, const Get& get, const Epi& epi) {
;     ...
;             WAIT_V(8); WAIT_L(0); BAR; G_MMA(0, 0, At, B0); G_MMA(0, 1, At, B1); BAR; SCHED;
;             G_LDA(At, 0, 1); G_STAGE(G_SB(0, 0), b2, voffB); G_STAGE(G_SB(0, 1), b2 + hstep, voffB); G_STAGE(G_SA(0, 0), a2, voffA);
;             WAIT_V(8); WAIT_L(0); BAR; G_MMA(1, 0, At, B0); G_MMA(1, 1, At, B1); BAR; SCHED;
;             G_LDB(B0, 1, 0); G_LDB(B1, 1, 1); SCHED; G_LDA(At, 1, 0); G_STAGE(G_SA(0, 1), a2 + hstep, voffA);
;             WAIT_V(8); WAIT_L(0); BAR; G_MMA(0, 0, At, B0); G_MMA(0, 1, At, B1); BAR; SCHED;
	s_setprio 1
	s_waitcnt lgkmcnt(0)
	v_mfma_f32_16x16x32_bf16 v[124:127], v[146:149], v[178:181], v[124:127]
	v_mfma_f32_16x16x32_bf16 v[120:123], v[154:157], v[178:181], v[120:123]
	v_mfma_f32_16x16x32_bf16 v[116:119], v[146:149], v[192:195], v[116:119]
	v_mfma_f32_16x16x32_bf16 v[112:115], v[154:157], v[192:195], v[112:115]
	v_mfma_f32_16x16x32_bf16 v[100:103], v[146:149], v[200:203], v[100:103]
	v_mfma_f32_16x16x32_bf16 v[96:99], v[154:157], v[200:203], v[96:99]
	v_mfma_f32_16x16x32_bf16 v[84:87], v[146:149], v[208:211], v[84:87]
	v_mfma_f32_16x16x32_bf16 v[80:83], v[154:157], v[208:211], v[80:83]
	s_setprio 0
	s_setprio 1
	v_mfma_f32_16x16x32_bf16 v[124:127], v[150:153], v[188:191], v[124:127]
	v_mfma_f32_16x16x32_bf16 v[120:123], v[158:161], v[188:191], v[120:123]
	v_mfma_f32_16x16x32_bf16 v[116:119], v[150:153], v[196:199], v[116:119]
	v_mfma_f32_16x16x32_bf16 v[112:115], v[158:161], v[196:199], v[112:115]
	v_mfma_f32_16x16x32_bf16 v[100:103], v[150:153], v[204:207], v[100:103]
	v_mfma_f32_16x16x32_bf16 v[96:99], v[158:161], v[204:207], v[96:99]
	v_mfma_f32_16x16x32_bf16 v[84:87], v[150:153], v[212:215], v[84:87]
	v_mfma_f32_16x16x32_bf16 v[80:83], v[158:161], v[212:215], v[80:83]
	s_setprio 0
	s_setprio 1
	v_mfma_f32_16x16x32_bf16 v[108:111], v[162:165], v[178:181], v[108:111]
	v_mfma_f32_16x16x32_bf16 v[104:107], v[170:173], v[178:181], v[104:107]
	v_mfma_f32_16x16x32_bf16 v[92:95], v[162:165], v[192:195], v[92:95]
	v_mfma_f32_16x16x32_bf16 v[88:91], v[170:173], v[192:195], v[88:91]
	v_mfma_f32_16x16x32_bf16 v[76:79], v[162:165], v[200:203], v[76:79]
	v_mfma_f32_16x16x32_bf16 v[72:75], v[170:173], v[200:203], v[72:75]
	v_mfma_f32_16x16x32_bf16 v[68:71], v[162:165], v[208:211], v[68:71]
	v_mfma_f32_16x16x32_bf16 v[64:67], v[170:173], v[208:211], v[64:67]
	s_setprio 0
	s_setprio 1
	v_mfma_f32_16x16x32_bf16 v[108:111], v[166:169], v[188:191], v[108:111]
	v_mfma_f32_16x16x32_bf16 v[104:107], v[174:177], v[188:191], v[104:107]
	v_mfma_f32_16x16x32_bf16 v[92:95], v[166:169], v[196:199], v[92:95]
	v_mfma_f32_16x16x32_bf16 v[88:91], v[174:177], v[196:199], v[88:91]
	v_mfma_f32_16x16x32_bf16 v[76:79], v[166:169], v[204:207], v[76:79]
	v_mfma_f32_16x16x32_bf16 v[72:75], v[174:177], v[204:207], v[72:75]
	v_mfma_f32_16x16x32_bf16 v[68:71], v[166:169], v[212:215], v[68:71]
	v_mfma_f32_16x16x32_bf16 v[64:67], v[174:177], v[212:215], v[64:67]
	s_setprio 0
	s_barrier
	s_add_i32 s82, s54, s38
	v_lshl_add_u64 v[182:183], s[14:15], 0, v[132:133]
	s_mov_b32 m0, s82
	ds_read_b128 v[178:181], v143 offset:16384
	ds_read_b128 v[188:191], v143 offset:17408
	ds_read_b128 v[192:195], v143 offset:18432
	ds_read_b128 v[196:199], v143 offset:19456
	ds_read_b128 v[200:203], v143 offset:20480
	ds_read_b128 v[204:207], v143 offset:21504
	ds_read_b128 v[208:211], v143 offset:22528
	ds_read_b128 v[212:215], v143 offset:23552
	global_load_lds_dwordx4 v[182:183], off
	s_add_i32 m0, s82, 0x2000
	s_add_u32 s82, s14, 0x100000
	v_lshl_add_u64 v[184:185], s[14:15], 0, v[128:129]
	s_addc_u32 s83, s15, 0
	s_add_i32 s84, s55, s38
	global_load_lds_dwordx4 v[184:185], off
	v_lshl_add_u64 v[186:187], s[82:83], 0, v[132:133]
	s_mov_b32 m0, s84
	v_lshl_add_u64 v[216:217], s[36:37], 0, v[130:131]
	global_load_lds_dwordx4 v[186:187], off
	v_lshl_add_u64 v[186:187], s[82:83], 0, v[128:129]
	s_add_i32 m0, s84, 0x2000
	s_nop 0
	global_load_lds_dwordx4 v[186:187], off
	v_lshl_add_u64 v[186:187], s[36:37], 0, v[134:135]
	s_mov_b32 m0, s43
	s_nop 0
	global_load_lds_dwordx4 v[186:187], off
	s_mov_b32 m0, s44
	s_nop 0
	global_load_lds_dwordx4 v[216:217], off
	s_waitcnt vmcnt(8)
	s_waitcnt lgkmcnt(0)
	s_barrier
	s_setprio 1
	s_waitcnt lgkmcnt(0)
	v_mfma_f32_16x16x32_bf16 v[60:63], v[146:149], v[178:181], v[60:63]
	v_mfma_f32_16x16x32_bf16 v[56:59], v[154:157], v[178:181], v[56:59]
	v_mfma_f32_16x16x32_bf16 v[52:55], v[146:149], v[192:195], v[52:55]
	v_mfma_f32_16x16x32_bf16 v[48:51], v[154:157], v[192:195], v[48:51]
	v_mfma_f32_16x16x32_bf16 v[36:39], v[146:149], v[200:203], v[36:39]
	v_mfma_f32_16x16x32_bf16 v[32:35], v[154:157], v[200:203], v[32:35]
	v_mfma_f32_16x16x32_bf16 v[20:23], v[146:149], v[208:211], v[20:23]
	v_mfma_f32_16x16x32_bf16 v[16:19], v[154:157], v[208:211], v[16:19]
	s_setprio 0
	s_setprio 1
	v_mfma_f32_16x16x32_bf16 v[60:63], v[150:153], v[188:191], v[60:63]
	v_mfma_f32_16x16x32_bf16 v[56:59], v[158:161], v[188:191], v[56:59]
	v_mfma_f32_16x16x32_bf16 v[52:55], v[150:153], v[196:199], v[52:55]
	v_mfma_f32_16x16x32_bf16 v[48:51], v[158:161], v[196:199], v[48:51]
	v_mfma_f32_16x16x32_bf16 v[36:39], v[150:153], v[204:207], v[36:39]
	v_mfma_f32_16x16x32_bf16 v[32:35], v[158:161], v[204:207], v[32:35]
	v_mfma_f32_16x16x32_bf16 v[20:23], v[150:153], v[212:215], v[20:23]
	v_mfma_f32_16x16x32_bf16 v[16:19], v[158:161], v[212:215], v[16:19]
	s_setprio 0
	s_setprio 1
	v_mfma_f32_16x16x32_bf16 v[44:47], v[162:165], v[178:181], v[44:47]
	v_mfma_f32_16x16x32_bf16 v[40:43], v[170:173], v[178:181], v[40:43]
	v_mfma_f32_16x16x32_bf16 v[28:31], v[162:165], v[192:195], v[28:31]
	v_mfma_f32_16x16x32_bf16 v[24:27], v[170:173], v[192:195], v[24:27]
	v_mfma_f32_16x16x32_bf16 v[12:15], v[162:165], v[200:203], v[12:15]
	v_mfma_f32_16x16x32_bf16 v[8:11], v[170:173], v[200:203], v[8:11]
	v_mfma_f32_16x16x32_bf16 v[4:7], v[162:165], v[208:211], v[4:7]
	v_mfma_f32_16x16x32_bf16 v[0:3], v[170:173], v[208:211], v[0:3]
	s_setprio 0
	s_setprio 1
	v_mfma_f32_16x16x32_bf16 v[44:47], v[166:169], v[188:191], v[44:47]
	v_mfma_f32_16x16x32_bf16 v[40:43], v[174:177], v[188:191], v[40:43]
	v_mfma_f32_16x16x32_bf16 v[28:31], v[166:169], v[196:199], v[28:31]
	v_mfma_f32_16x16x32_bf16 v[24:27], v[174:177], v[196:199], v[24:27]
	v_mfma_f32_16x16x32_bf16 v[12:15], v[166:169], v[204:207], v[12:15]
	v_mfma_f32_16x16x32_bf16 v[8:11], v[174:177], v[204:207], v[8:11]
	v_mfma_f32_16x16x32_bf16 v[4:7], v[166:169], v[212:215], v[4:7]
	v_mfma_f32_16x16x32_bf16 v[0:3], v[174:177], v[212:215], v[0:3]
	s_setprio 0
	s_barrier
; #define G_STAGE(bufoff, gbase, voff) do { _Pragma("unroll") for (int _i = 0; _i < 2; ++_i) \
;         __builtin_amdgcn_global_load_lds((const unsigned*)((const char*)(gbase) + voff[_i]), (LAS unsigned*)(lds + (bufoff) + ldsw + _i * 8192), 16, 0, 0); } while (0)
; #define G_LDA(dst, b, h) do { _Pragma("unroll") for (int m = 0; m < 4; ++m) _Pragma("unroll") for (int k = 0; k < 2; ++k) dst[m][k] = *(const LAS bf16x8*)(lds + G_SA(b, h) + aoff + m * 2048 + k * 1024); } while (0)
; #define G_LDB(dst, b, h) do { _Pragma("unroll") for (int n = 0; n < 2; ++n) _Pragma("unroll") for (int k = 0; k < 2; ++k) dst[n][k] = *(const LAS bf16x8*)(lds + G_SB(b, h) + boff + n * 2048 + k * 1024); } while (0)
; #define G_MMA(ai, bj, At_, Bt_) do { __builtin_amdgcn_s_setprio(1); _Pragma("unroll") for (int m = 0; m < 4; ++m) _Pragma("unroll") for (int n = 0; n < 2; ++n) _Pragma("unroll") for (int k = 0; k < 2; ++k) \
;         acc[ai][bj][m][n] = __builtin_amdgcn_mfma_f32_16x16x32_bf16(Bt_[n][k], At_[m][k], acc[ai][bj][m][n], 0, 0, 0); __builtin_amdgcn_s_setprio(0); } while (0)
; #define WAIT_V(n) asm volatile("s_waitcnt vmcnt(" #n ")" ::: "memory")
; #define WAIT_L(n) asm volatile("s_waitcnt lgkmcnt(" #n ")" ::: "memory")
; #define BAR __builtin_amdgcn_s_barrier()
; #define SCHED __builtin_amdgcn_sched_barrier(0)
; template <class Get, class Epi>
; DI void gemm_loop(int ntiles, int ld, char* shm, const Get& get, const Epi& epi) {
;     ...
;             G_LDB(B0, 1, 0); G_LDB(B1, 1, 1); SCHED; G_LDA(At, 1, 0); G_STAGE(G_SA(0, 1), a2 + hstep, voffA);
;             WAIT_V(8); WAIT_L(0); BAR; G_MMA(0, 0, At, B0); G_MMA(0, 1, At, B1); BAR; SCHED;
	s_add_i32 s82, 0, 0x18000
	v_add_u32_e32 v145, s82, v140
	s_add_i32 s83, 0, 0x1c000
	ds_read_b128 v[146:149], v145
	ds_read_b128 v[150:153], v145 offset:1024
	ds_read_b128 v[154:157], v145 offset:2048
	ds_read_b128 v[158:161], v145 offset:3072
	v_add_u32_e32 v145, s83, v140
	ds_read_b128 v[162:165], v145
	ds_read_b128 v[166:169], v145 offset:1024
	ds_read_b128 v[170:173], v145 offset:2048
	ds_read_b128 v[174:177], v145 offset:3072
	s_add_u32 s36, s36, 0x100000
	s_addc_u32 s37, s37, 0
	s_mov_b32 m0, s45
	v_lshl_add_u64 v[218:219], s[36:37], 0, v[134:135]
	ds_read_b128 v[178:181], v143 offset:32768
	ds_read_b128 v[188:191], v143 offset:33792
	ds_read_b128 v[192:195], v143 offset:34816
	ds_read_b128 v[196:199], v143 offset:35840
	ds_read_b128 v[200:203], v143 offset:36864
	ds_read_b128 v[204:207], v143 offset:37888
	ds_read_b128 v[208:211], v143 offset:38912
	ds_read_b128 v[212:215], v143 offset:39936
	global_load_lds_dwordx4 v[218:219], off
	v_lshl_add_u64 v[218:219], s[36:37], 0, v[130:131]
	s_mov_b32 m0, s46
	s_nop 0
	global_load_lds_dwordx4 v[218:219], off
	s_waitcnt vmcnt(8)
	s_waitcnt lgkmcnt(0)
	s_barrier
	s_setprio 1
	s_waitcnt lgkmcnt(0)
	v_mfma_f32_16x16x32_bf16 v[124:127], v[146:149], v[178:181], v[124:127]
	v_mfma_f32_16x16x32_bf16 v[120:123], v[154:157], v[178:181], v[120:123]
	v_mfma_f32_16x16x32_bf16 v[116:119], v[146:149], v[192:195], v[116:119]
	v_mfma_f32_16x16x32_bf16 v[112:115], v[154:157], v[192:195], v[112:115]
	v_mfma_f32_16x16x32_bf16 v[100:103], v[146:149], v[200:203], v[100:103]
	v_mfma_f32_16x16x32_bf16 v[96:99], v[154:157], v[200:203], v[96:99]
	v_mfma_f32_16x16x32_bf16 v[84:87], v[146:149], v[208:211], v[84:87]
	v_mfma_f32_16x16x32_bf16 v[80:83], v[154:157], v[208:211], v[80:83]
	s_setprio 0
	s_setprio 1
	v_mfma_f32_16x16x32_bf16 v[124:127], v[150:153], v[188:191], v[124:127]
	v_mfma_f32_16x16x32_bf16 v[120:123], v[158:161], v[188:191], v[120:123]
	v_mfma_f32_16x16x32_bf16 v[116:119], v[150:153], v[196:199], v[116:119]
	v_mfma_f32_16x16x32_bf16 v[112:115], v[158:161], v[196:199], v[112:115]
	v_mfma_f32_16x16x32_bf16 v[100:103], v[150:153], v[204:207], v[100:103]
	v_mfma_f32_16x16x32_bf16 v[96:99], v[158:161], v[204:207], v[96:99]
	v_mfma_f32_16x16x32_bf16 v[84:87], v[150:153], v[212:215], v[84:87]
	v_mfma_f32_16x16x32_bf16 v[80:83], v[158:161], v[212:215], v[80:83]
	s_setprio 0
	s_setprio 1
	v_mfma_f32_16x16x32_bf16 v[108:111], v[162:165], v[178:181], v[108:111]
	v_mfma_f32_16x16x32_bf16 v[104:107], v[170:173], v[178:181], v[104:107]
	v_mfma_f32_16x16x32_bf16 v[92:95], v[162:165], v[192:195], v[92:95]
	v_mfma_f32_16x16x32_bf16 v[88:91], v[170:173], v[192:195], v[88:91]
	v_mfma_f32_16x16x32_bf16 v[76:79], v[162:165], v[200:203], v[76:79]
	v_mfma_f32_16x16x32_bf16 v[72:75], v[170:173], v[200:203], v[72:75]
	v_mfma_f32_16x16x32_bf16 v[68:71], v[162:165], v[208:211], v[68:71]
	v_mfma_f32_16x16x32_bf16 v[64:67], v[170:173], v[208:211], v[64:67]
	s_setprio 0
	s_setprio 1
	v_mfma_f32_16x16x32_bf16 v[108:111], v[166:169], v[188:191], v[108:111]
	v_mfma_f32_16x16x32_bf16 v[104:107], v[174:177], v[188:191], v[104:107]
	v_mfma_f32_16x16x32_bf16 v[92:95], v[166:169], v[196:199], v[92:95]
	v_mfma_f32_16x16x32_bf16 v[88:91], v[174:177], v[196:199], v[88:91]
	v_mfma_f32_16x16x32_bf16 v[76:79], v[166:169], v[204:207], v[76:79]
	v_mfma_f32_16x16x32_bf16 v[72:75], v[174:177], v[204:207], v[72:75]
	v_mfma_f32_16x16x32_bf16 v[68:71], v[166:169], v[212:215], v[68:71]
	v_mfma_f32_16x16x32_bf16 v[64:67], v[174:177], v[212:215], v[64:67]
	s_setprio 0
	s_barrier
; #define G_STAGE(bufoff, gbase, voff) do { _Pragma("unroll") for (int _i = 0; _i < 2; ++_i) \
;         __builtin_amdgcn_global_load_lds((const unsigned*)((const char*)(gbase) + voff[_i]), (LAS unsigned*)(lds + (bufoff) + ldsw + _i * 8192), 16, 0, 0); } while (0)
; #define G_LDA(dst, b, h) do { _Pragma("unroll") for (int m = 0; m < 4; ++m) _Pragma("unroll") for (int k = 0; k < 2; ++k) dst[m][k] = *(const LAS bf16x8*)(lds + G_SA(b, h) + aoff + m * 2048 + k * 1024); } while (0)
; #define G_MMA(ai, bj, At_, Bt_) do { __builtin_amdgcn_s_setprio(1); _Pragma("unroll") for (int m = 0; m < 4; ++m) _Pragma("unroll") for (int n = 0; n < 2; ++n) _Pragma("unroll") for (int k = 0; k < 2; ++k) \
;         acc[ai][bj][m][n] = __builtin_amdgcn_mfma_f32_16x16x32_bf16(Bt_[n][k], At_[m][k], acc[ai][bj][m][n], 0, 0, 0); __builtin_amdgcn_s_setprio(0); } while (0)
; #define WAIT_V(n) asm volatile("s_waitcnt vmcnt(" #n ")" ::: "memory")
; #define WAIT_L(n) asm volatile("s_waitcnt lgkmcnt(" #n ")" ::: "memory")
; #define BAR __builtin_amdgcn_s_barrier()
; #define SCHED __builtin_amdgcn_sched_barrier(0)
; template <class Get, class Epi>
; DI void gemm_loop(int ntiles, int ld, char* shm, const Get& get, const Epi& epi) {
;     ...
;             G_LDA(At, 1, 1); G_STAGE(G_SB(1, 0), b3, voffB); G_STAGE(G_SB(1, 1), b3 + hstep, voffB); G_STAGE(G_SA(1, 0), a3, voffA);
;             WAIT_V(8); WAIT_L(0); BAR; G_MMA(1, 0, At, B0); G_MMA(1, 1, At, B1); BAR; SCHED;
;         }
	s_add_i32 s36, s82, s38
	v_lshl_add_u64 v[182:183], v[182:183], 0, s[8:9]
	s_mov_b32 m0, s36
	ds_read_b128 v[178:181], v143 offset:49152
	ds_read_b128 v[188:191], v143 offset:50176
	ds_read_b128 v[192:195], v143 offset:51200
	ds_read_b128 v[196:199], v143 offset:52224
	ds_read_b128 v[200:203], v143 offset:53248
	ds_read_b128 v[204:207], v143 offset:54272
	ds_read_b128 v[208:211], v143 offset:55296
	ds_read_b128 v[212:215], v143 offset:56320
	global_load_lds_dwordx4 v[182:183], off
	s_add_i32 m0, s36, 0x2000
	s_add_u32 s14, s14, 0x100080
	v_lshl_add_u64 v[182:183], v[184:185], 0, s[8:9]
	s_addc_u32 s15, s15, 0
	s_add_i32 s36, s83, s38
	global_load_lds_dwordx4 v[182:183], off
	v_lshl_add_u64 v[182:183], s[14:15], 0, v[132:133]
	s_mov_b32 m0, s36
	s_nop 0
	global_load_lds_dwordx4 v[182:183], off
	v_lshl_add_u64 v[182:183], s[14:15], 0, v[128:129]
	s_add_i32 m0, s36, 0x2000
	s_nop 0
	global_load_lds_dwordx4 v[182:183], off
	v_lshl_add_u64 v[182:183], v[186:187], 0, s[8:9]
	s_mov_b32 m0, s47
	s_nop 0
	global_load_lds_dwordx4 v[182:183], off
	v_lshl_add_u64 v[182:183], v[216:217], 0, s[8:9]
	s_mov_b32 m0, s50
	s_nop 0
	global_load_lds_dwordx4 v[182:183], off
	s_waitcnt vmcnt(8)
	s_waitcnt lgkmcnt(0)
	s_barrier
	s_setprio 1
	s_waitcnt lgkmcnt(0)
	v_mfma_f32_16x16x32_bf16 v[60:63], v[146:149], v[178:181], v[60:63]
	v_mfma_f32_16x16x32_bf16 v[56:59], v[154:157], v[178:181], v[56:59]
	v_mfma_f32_16x16x32_bf16 v[52:55], v[146:149], v[192:195], v[52:55]
	v_mfma_f32_16x16x32_bf16 v[48:51], v[154:157], v[192:195], v[48:51]
	v_mfma_f32_16x16x32_bf16 v[36:39], v[146:149], v[200:203], v[36:39]
	v_mfma_f32_16x16x32_bf16 v[32:35], v[154:157], v[200:203], v[32:35]
	v_mfma_f32_16x16x32_bf16 v[20:23], v[146:149], v[208:211], v[20:23]
	v_mfma_f32_16x16x32_bf16 v[16:19], v[154:157], v[208:211], v[16:19]
	s_setprio 0
	s_setprio 1
	v_mfma_f32_16x16x32_bf16 v[60:63], v[150:153], v[188:191], v[60:63]
	v_mfma_f32_16x16x32_bf16 v[56:59], v[158:161], v[188:191], v[56:59]
	v_mfma_f32_16x16x32_bf16 v[52:55], v[150:153], v[196:199], v[52:55]
	v_mfma_f32_16x16x32_bf16 v[48:51], v[158:161], v[196:199], v[48:51]
	v_mfma_f32_16x16x32_bf16 v[36:39], v[150:153], v[204:207], v[36:39]
	v_mfma_f32_16x16x32_bf16 v[32:35], v[158:161], v[204:207], v[32:35]
	v_mfma_f32_16x16x32_bf16 v[20:23], v[150:153], v[212:215], v[20:23]
	v_mfma_f32_16x16x32_bf16 v[16:19], v[158:161], v[212:215], v[16:19]
	s_setprio 0
	s_setprio 1
	v_mfma_f32_16x16x32_bf16 v[44:47], v[162:165], v[178:181], v[44:47]
	v_mfma_f32_16x16x32_bf16 v[40:43], v[170:173], v[178:181], v[40:43]
	v_mfma_f32_16x16x32_bf16 v[28:31], v[162:165], v[192:195], v[28:31]
	v_mfma_f32_16x16x32_bf16 v[24:27], v[170:173], v[192:195], v[24:27]
	v_mfma_f32_16x16x32_bf16 v[12:15], v[162:165], v[200:203], v[12:15]
	v_mfma_f32_16x16x32_bf16 v[8:11], v[170:173], v[200:203], v[8:11]
	v_mfma_f32_16x16x32_bf16 v[4:7], v[162:165], v[208:211], v[4:7]
	v_mfma_f32_16x16x32_bf16 v[0:3], v[170:173], v[208:211], v[0:3]
	s_setprio 0
	s_setprio 1
	v_mfma_f32_16x16x32_bf16 v[44:47], v[166:169], v[188:191], v[44:47]
	v_mfma_f32_16x16x32_bf16 v[40:43], v[174:177], v[188:191], v[40:43]
	v_mfma_f32_16x16x32_bf16 v[28:31], v[166:169], v[196:199], v[28:31]
	v_mfma_f32_16x16x32_bf16 v[24:27], v[174:177], v[196:199], v[24:27]
	v_mfma_f32_16x16x32_bf16 v[12:15], v[166:169], v[204:207], v[12:15]
	v_mfma_f32_16x16x32_bf16 v[8:11], v[174:177], v[204:207], v[8:11]
	v_mfma_f32_16x16x32_bf16 v[4:7], v[166:169], v[212:215], v[4:7]
	v_mfma_f32_16x16x32_bf16 v[0:3], v[174:177], v[212:215], v[0:3]
	s_setprio 0
	s_barrier
	s_add_i32 s81, s81, 2
	s_add_u32 s34, s34, 0x100
	s_addc_u32 s35, s35, 0
	s_add_u32 s79, s79, 0x100
	s_addc_u32 s80, s80, 0
	s_cmp_gt_u32 s81, 61
	s_cbranch_scc0 .LBB0_431

; #define G_STAGE(bufoff, gbase, voff) do { _Pragma("unroll") for (int _i = 0; _i < 2; ++_i) \
;         __builtin_amdgcn_global_load_lds((const unsigned*)((const char*)(gbase) + voff[_i]), (LAS unsigned*)(lds + (bufoff) + ldsw + _i * 8192), 16, 0, 0); } while (0)
; #define G_LDA(dst, b, h) do { _Pragma("unroll") for (int m = 0; m < 4; ++m) _Pragma("unroll") for (int k = 0; k < 2; ++k) dst[m][k] = *(const LAS bf16x8*)(lds + G_SA(b, h) + aoff + m * 2048 + k * 1024); } while (0)
; #define G_LDB(dst, b, h) do { _Pragma("unroll") for (int n = 0; n < 2; ++n) _Pragma("unroll") for (int k = 0; k < 2; ++k) dst[n][k] = *(const LAS bf16x8*)(lds + G_SB(b, h) + boff + n * 2048 + k * 1024); } while (0)
; #define G_MMA(ai, bj, At_, Bt_) do { __builtin_amdgcn_s_setprio(1); _Pragma("unroll") for (int m = 0; m < 4; ++m) _Pragma("unroll") for (int n = 0; n < 2; ++n) _Pragma("unroll") for (int k = 0; k < 2; ++k) \
;         acc[ai][bj][m][n] = __builtin_amdgcn_mfma_f32_16x16x32_bf16(Bt_[n][k], At_[m][k], acc[ai][bj][m][n], 0, 0, 0); __builtin_amdgcn_s_setprio(0); } while (0)
; #define WAIT_V(n) asm volatile("s_waitcnt vmcnt(" #n ")" ::: "memory")
; #define WAIT_L(n) asm volatile("s_waitcnt lgkmcnt(" #n ")" ::: "memory")
; #define BAR __builtin_amdgcn_s_barrier()
; #define SCHED __builtin_amdgcn_sched_barrier(0)
; template <class Get, class Epi>
; DI void gemm_loop(int ntiles, int ld, char* shm, const Get& get, const Epi& epi) {
;     ...
;             G_LDB(B0, 0, 0); G_LDB(B1, 0, 1); SCHED; G_LDA(At, 0, 0); G_STAGE(G_SA(1, 1), a1 + hstep, voffA);
;             WAIT_V(8); WAIT_L(0); BAR; G_MMA(0, 0, At, B0); G_MMA(0, 1, At, B1); BAR; SCHED;
;             G_LDA(At, 0, 1); G_STAGE(G_SB(0, 0), b2, voffB); G_STAGE(G_SB(0, 1), b2 + hstep, voffB); G_STAGE(G_SA(0, 0), a2, voffA);
;             WAIT_V(8); WAIT_L(0); BAR; G_MMA(1, 0, At, B0); G_MMA(1, 1, At, B1); BAR; SCHED;
.Lrj_445_0:
	s_waitcnt lgkmcnt(0)
	s_barrier
	s_setprio 1
	s_waitcnt lgkmcnt(0)
	v_mfma_f32_16x16x32_bf16 v[124:127], v[146:149], v[178:181], 0
	v_mfma_f32_16x16x32_bf16 v[120:123], v[154:157], v[178:181], 0
	v_mfma_f32_16x16x32_bf16 v[116:119], v[146:149], v[192:195], 0
	v_mfma_f32_16x16x32_bf16 v[112:115], v[154:157], v[192:195], 0
	v_mfma_f32_16x16x32_bf16 v[100:103], v[146:149], v[200:203], 0
	v_mfma_f32_16x16x32_bf16 v[96:99], v[154:157], v[200:203], 0
	v_mfma_f32_16x16x32_bf16 v[84:87], v[146:149], v[208:211], 0
	v_mfma_f32_16x16x32_bf16 v[80:83], v[154:157], v[208:211], 0
	s_setprio 0
	s_setprio 1
	v_mfma_f32_16x16x32_bf16 v[124:127], v[150:153], v[188:191], v[124:127]
	v_mfma_f32_16x16x32_bf16 v[120:123], v[158:161], v[188:191], v[120:123]
	v_mfma_f32_16x16x32_bf16 v[116:119], v[150:153], v[196:199], v[116:119]
	v_mfma_f32_16x16x32_bf16 v[112:115], v[158:161], v[196:199], v[112:115]
	v_mfma_f32_16x16x32_bf16 v[100:103], v[150:153], v[204:207], v[100:103]
	v_mfma_f32_16x16x32_bf16 v[96:99], v[158:161], v[204:207], v[96:99]
	v_mfma_f32_16x16x32_bf16 v[84:87], v[150:153], v[212:215], v[84:87]
	v_mfma_f32_16x16x32_bf16 v[80:83], v[158:161], v[212:215], v[80:83]
	s_setprio 0
	s_setprio 1
	v_mfma_f32_16x16x32_bf16 v[108:111], v[162:165], v[178:181], 0
	v_mfma_f32_16x16x32_bf16 v[104:107], v[170:173], v[178:181], 0
	v_mfma_f32_16x16x32_bf16 v[92:95], v[162:165], v[192:195], 0
	v_mfma_f32_16x16x32_bf16 v[88:91], v[170:173], v[192:195], 0
	v_mfma_f32_16x16x32_bf16 v[76:79], v[162:165], v[200:203], 0
	v_mfma_f32_16x16x32_bf16 v[72:75], v[170:173], v[200:203], 0
	v_mfma_f32_16x16x32_bf16 v[68:71], v[162:165], v[208:211], 0
	v_mfma_f32_16x16x32_bf16 v[64:67], v[170:173], v[208:211], 0
	s_setprio 0
	s_setprio 1
	v_mfma_f32_16x16x32_bf16 v[108:111], v[166:169], v[188:191], v[108:111]
	v_mfma_f32_16x16x32_bf16 v[104:107], v[174:177], v[188:191], v[104:107]
	v_mfma_f32_16x16x32_bf16 v[92:95], v[166:169], v[196:199], v[92:95]
	v_mfma_f32_16x16x32_bf16 v[88:91], v[174:177], v[196:199], v[88:91]
	v_mfma_f32_16x16x32_bf16 v[76:79], v[166:169], v[204:207], v[76:79]
	v_mfma_f32_16x16x32_bf16 v[72:75], v[174:177], v[204:207], v[72:75]
	v_mfma_f32_16x16x32_bf16 v[68:71], v[166:169], v[212:215], v[68:71]
	v_mfma_f32_16x16x32_bf16 v[64:67], v[174:177], v[212:215], v[64:67]
	s_setprio 0
	s_barrier
	s_mov_b32 m0, s54
	v_lshl_add_u64 v[182:183], s[14:15], 0, v[132:133]
	s_add_u32 s82, s14, 0x20000
	ds_read_b128 v[178:181], v142 offset:16384
	ds_read_b128 v[188:191], v142 offset:17408
	ds_read_b128 v[192:195], v142 offset:18432
	ds_read_b128 v[196:199], v142 offset:19456
	ds_read_b128 v[200:203], v142 offset:20480
	ds_read_b128 v[204:207], v142 offset:21504
	ds_read_b128 v[208:211], v142 offset:22528
	ds_read_b128 v[212:215], v142 offset:23552
	global_load_lds_dwordx4 v[182:183], off
	v_lshl_add_u64 v[184:185], s[14:15], 0, v[128:129]
	s_mov_b32 m0, s55
	s_addc_u32 s83, s15, 0
	global_load_lds_dwordx4 v[184:185], off
	v_lshl_add_u64 v[186:187], s[82:83], 0, v[132:133]
	s_mov_b32 m0, s56
	v_lshl_add_u64 v[216:217], s[38:39], 0, v[130:131]
	global_load_lds_dwordx4 v[186:187], off
	v_lshl_add_u64 v[186:187], s[82:83], 0, v[128:129]
	s_mov_b32 m0, s57
	s_nop 0
	global_load_lds_dwordx4 v[186:187], off
	v_lshl_add_u64 v[186:187], s[38:39], 0, v[134:135]
	s_mov_b32 m0, s41
	s_nop 0
	global_load_lds_dwordx4 v[186:187], off
	s_mov_b32 m0, s43
	s_nop 0
	global_load_lds_dwordx4 v[216:217], off
	s_cmp_lg_u32 s100, 0
	s_cbranch_scc0 .Lrf_445_1
	s_waitcnt vmcnt(16)
	s_branch .Lrj_445_1

; #define G_STAGE(bufoff, gbase, voff) do { _Pragma("unroll") for (int _i = 0; _i < 2; ++_i) \
;         __builtin_amdgcn_global_load_lds((const unsigned*)((const char*)(gbase) + voff[_i]), (LAS unsigned*)(lds + (bufoff) + ldsw + _i * 8192), 16, 0, 0); } while (0)
; #define G_LDA(dst, b, h) do { _Pragma("unroll") for (int m = 0; m < 4; ++m) _Pragma("unroll") for (int k = 0; k < 2; ++k) dst[m][k] = *(const LAS bf16x8*)(lds + G_SA(b, h) + aoff + m * 2048 + k * 1024); } while (0)
; #define G_LDB(dst, b, h) do { _Pragma("unroll") for (int n = 0; n < 2; ++n) _Pragma("unroll") for (int k = 0; k < 2; ++k) dst[n][k] = *(const LAS bf16x8*)(lds + G_SB(b, h) + boff + n * 2048 + k * 1024); } while (0)
; #define G_MMA(ai, bj, At_, Bt_) do { __builtin_amdgcn_s_setprio(1); _Pragma("unroll") for (int m = 0; m < 4; ++m) _Pragma("unroll") for (int n = 0; n < 2; ++n) _Pragma("unroll") for (int k = 0; k < 2; ++k) \
;         acc[ai][bj][m][n] = __builtin_amdgcn_mfma_f32_16x16x32_bf16(Bt_[n][k], At_[m][k], acc[ai][bj][m][n], 0, 0, 0); __builtin_amdgcn_s_setprio(0); } while (0)
; #define WAIT_V(n) asm volatile("s_waitcnt vmcnt(" #n ")" ::: "memory")
; #define WAIT_L(n) asm volatile("s_waitcnt lgkmcnt(" #n ")" ::: "memory")
; #define BAR __builtin_amdgcn_s_barrier()
; #define SCHED __builtin_amdgcn_sched_barrier(0)
; template <class Get, class Epi>
; DI void gemm_loop(int ntiles, int ld, char* shm, const Get& get, const Epi& epi) {
;     ...
;             WAIT_V(8); WAIT_L(0); BAR; G_MMA(1, 0, At, B0); G_MMA(1, 1, At, B1); BAR; SCHED;
;             G_LDB(B0, 1, 0); G_LDB(B1, 1, 1); SCHED; G_LDA(At, 1, 0); G_STAGE(G_SA(0, 1), a2 + hstep, voffA);
;             WAIT_V(8); WAIT_L(0); BAR; G_MMA(0, 0, At, B0); G_MMA(0, 1, At, B1); BAR; SCHED;
.Lrj_445_1:
	s_waitcnt lgkmcnt(0)
	s_barrier
	s_setprio 1
	s_waitcnt lgkmcnt(0)
	v_mfma_f32_16x16x32_bf16 v[60:63], v[146:149], v[178:181], 0
	v_mfma_f32_16x16x32_bf16 v[56:59], v[154:157], v[178:181], 0
	v_mfma_f32_16x16x32_bf16 v[52:55], v[146:149], v[192:195], 0
	v_mfma_f32_16x16x32_bf16 v[48:51], v[154:157], v[192:195], 0
	v_mfma_f32_16x16x32_bf16 v[36:39], v[146:149], v[200:203], 0
	v_mfma_f32_16x16x32_bf16 v[32:35], v[154:157], v[200:203], 0
	v_mfma_f32_16x16x32_bf16 v[20:23], v[146:149], v[208:211], 0
	v_mfma_f32_16x16x32_bf16 v[16:19], v[154:157], v[208:211], 0
	s_setprio 0
	s_setprio 1
	v_mfma_f32_16x16x32_bf16 v[60:63], v[150:153], v[188:191], v[60:63]
	v_mfma_f32_16x16x32_bf16 v[56:59], v[158:161], v[188:191], v[56:59]
	v_mfma_f32_16x16x32_bf16 v[52:55], v[150:153], v[196:199], v[52:55]
	v_mfma_f32_16x16x32_bf16 v[48:51], v[158:161], v[196:199], v[48:51]
	v_mfma_f32_16x16x32_bf16 v[36:39], v[150:153], v[204:207], v[36:39]
	v_mfma_f32_16x16x32_bf16 v[32:35], v[158:161], v[204:207], v[32:35]
	v_mfma_f32_16x16x32_bf16 v[20:23], v[150:153], v[212:215], v[20:23]
	v_mfma_f32_16x16x32_bf16 v[16:19], v[158:161], v[212:215], v[16:19]
	s_setprio 0
	s_setprio 1
	v_mfma_f32_16x16x32_bf16 v[44:47], v[162:165], v[178:181], 0
	v_mfma_f32_16x16x32_bf16 v[40:43], v[170:173], v[178:181], 0
	v_mfma_f32_16x16x32_bf16 v[28:31], v[162:165], v[192:195], 0
	v_mfma_f32_16x16x32_bf16 v[24:27], v[170:173], v[192:195], 0
	v_mfma_f32_16x16x32_bf16 v[12:15], v[162:165], v[200:203], 0
	v_mfma_f32_16x16x32_bf16 v[8:11], v[170:173], v[200:203], 0
	v_mfma_f32_16x16x32_bf16 v[4:7], v[162:165], v[208:211], 0
	v_mfma_f32_16x16x32_bf16 v[0:3], v[170:173], v[208:211], 0
	s_setprio 0
	s_setprio 1
	v_mfma_f32_16x16x32_bf16 v[44:47], v[166:169], v[188:191], v[44:47]
	v_mfma_f32_16x16x32_bf16 v[40:43], v[174:177], v[188:191], v[40:43]
	v_mfma_f32_16x16x32_bf16 v[28:31], v[166:169], v[196:199], v[28:31]
	v_mfma_f32_16x16x32_bf16 v[24:27], v[174:177], v[196:199], v[24:27]
	v_mfma_f32_16x16x32_bf16 v[12:15], v[166:169], v[204:207], v[12:15]
	v_mfma_f32_16x16x32_bf16 v[8:11], v[174:177], v[204:207], v[8:11]
	v_mfma_f32_16x16x32_bf16 v[4:7], v[166:169], v[212:215], v[4:7]
	v_mfma_f32_16x16x32_bf16 v[0:3], v[174:177], v[212:215], v[0:3]
	s_setprio 0
	s_barrier
	ds_read_b128 v[146:149], v143
	ds_read_b128 v[150:153], v143 offset:1024
	ds_read_b128 v[154:157], v143 offset:2048
	ds_read_b128 v[158:161], v143 offset:3072
	ds_read_b128 v[162:165], v144
	ds_read_b128 v[166:169], v144 offset:1024
	ds_read_b128 v[170:173], v144 offset:2048
	ds_read_b128 v[174:177], v144 offset:3072
	s_add_u32 s38, s38, 0x20000
	s_addc_u32 s39, s39, 0
	s_mov_b32 m0, s44
	v_lshl_add_u64 v[218:219], s[38:39], 0, v[134:135]
	ds_read_b128 v[178:181], v142 offset:32768
	ds_read_b128 v[188:191], v142 offset:33792
	ds_read_b128 v[192:195], v142 offset:34816
	ds_read_b128 v[196:199], v142 offset:35840
	ds_read_b128 v[200:203], v142 offset:36864
	ds_read_b128 v[204:207], v142 offset:37888
	ds_read_b128 v[208:211], v142 offset:38912
	ds_read_b128 v[212:215], v142 offset:39936
	global_load_lds_dwordx4 v[218:219], off
	v_lshl_add_u64 v[218:219], s[38:39], 0, v[130:131]
	s_mov_b32 m0, s45
	s_nop 0
	global_load_lds_dwordx4 v[218:219], off
	s_waitcnt vmcnt(8)
	s_waitcnt lgkmcnt(0)
	s_barrier
	s_setprio 1
	s_waitcnt lgkmcnt(0)
	v_mfma_f32_16x16x32_bf16 v[124:127], v[146:149], v[178:181], v[124:127]
	v_mfma_f32_16x16x32_bf16 v[120:123], v[154:157], v[178:181], v[120:123]
	v_mfma_f32_16x16x32_bf16 v[116:119], v[146:149], v[192:195], v[116:119]
	v_mfma_f32_16x16x32_bf16 v[112:115], v[154:157], v[192:195], v[112:115]
	v_mfma_f32_16x16x32_bf16 v[100:103], v[146:149], v[200:203], v[100:103]
	v_mfma_f32_16x16x32_bf16 v[96:99], v[154:157], v[200:203], v[96:99]
	v_mfma_f32_16x16x32_bf16 v[84:87], v[146:149], v[208:211], v[84:87]
	v_mfma_f32_16x16x32_bf16 v[80:83], v[154:157], v[208:211], v[80:83]
	s_setprio 0
	s_setprio 1
	v_mfma_f32_16x16x32_bf16 v[124:127], v[150:153], v[188:191], v[124:127]
	v_mfma_f32_16x16x32_bf16 v[120:123], v[158:161], v[188:191], v[120:123]
	v_mfma_f32_16x16x32_bf16 v[116:119], v[150:153], v[196:199], v[116:119]
	v_mfma_f32_16x16x32_bf16 v[112:115], v[158:161], v[196:199], v[112:115]
	v_mfma_f32_16x16x32_bf16 v[100:103], v[150:153], v[204:207], v[100:103]
	v_mfma_f32_16x16x32_bf16 v[96:99], v[158:161], v[204:207], v[96:99]
	v_mfma_f32_16x16x32_bf16 v[84:87], v[150:153], v[212:215], v[84:87]
	v_mfma_f32_16x16x32_bf16 v[80:83], v[158:161], v[212:215], v[80:83]
	s_setprio 0
	s_setprio 1
	v_mfma_f32_16x16x32_bf16 v[108:111], v[162:165], v[178:181], v[108:111]
	v_mfma_f32_16x16x32_bf16 v[104:107], v[170:173], v[178:181], v[104:107]
	v_mfma_f32_16x16x32_bf16 v[92:95], v[162:165], v[192:195], v[92:95]
	v_mfma_f32_16x16x32_bf16 v[88:91], v[170:173], v[192:195], v[88:91]
	v_mfma_f32_16x16x32_bf16 v[76:79], v[162:165], v[200:203], v[76:79]
	v_mfma_f32_16x16x32_bf16 v[72:75], v[170:173], v[200:203], v[72:75]
	v_mfma_f32_16x16x32_bf16 v[68:71], v[162:165], v[208:211], v[68:71]
	v_mfma_f32_16x16x32_bf16 v[64:67], v[170:173], v[208:211], v[64:67]
	s_setprio 0
	s_setprio 1
	v_mfma_f32_16x16x32_bf16 v[108:111], v[166:169], v[188:191], v[108:111]
	v_mfma_f32_16x16x32_bf16 v[104:107], v[174:177], v[188:191], v[104:107]
	v_mfma_f32_16x16x32_bf16 v[92:95], v[166:169], v[196:199], v[92:95]
	v_mfma_f32_16x16x32_bf16 v[88:91], v[174:177], v[196:199], v[88:91]
	v_mfma_f32_16x16x32_bf16 v[76:79], v[166:169], v[204:207], v[76:79]
	v_mfma_f32_16x16x32_bf16 v[72:75], v[174:177], v[204:207], v[72:75]
	v_mfma_f32_16x16x32_bf16 v[68:71], v[166:169], v[212:215], v[68:71]
	v_mfma_f32_16x16x32_bf16 v[64:67], v[174:177], v[212:215], v[64:67]
	s_setprio 0
	s_barrier
; #define G_STAGE(bufoff, gbase, voff) do { _Pragma("unroll") for (int _i = 0; _i < 2; ++_i) \
;         __builtin_amdgcn_global_load_lds((const unsigned*)((const char*)(gbase) + voff[_i]), (LAS unsigned*)(lds + (bufoff) + ldsw + _i * 8192), 16, 0, 0); } while (0)
; #define G_LDA(dst, b, h) do { _Pragma("unroll") for (int m = 0; m < 4; ++m) _Pragma("unroll") for (int k = 0; k < 2; ++k) dst[m][k] = *(const LAS bf16x8*)(lds + G_SA(b, h) + aoff + m * 2048 + k * 1024); } while (0)
; #define G_LDB(dst, b, h) do { _Pragma("unroll") for (int n = 0; n < 2; ++n) _Pragma("unroll") for (int k = 0; k < 2; ++k) dst[n][k] = *(const LAS bf16x8*)(lds + G_SB(b, h) + boff + n * 2048 + k * 1024); } while (0)
; #define G_MMA(ai, bj, At_, Bt_) do { __builtin_amdgcn_s_setprio(1); _Pragma("unroll") for (int m = 0; m < 4; ++m) _Pragma("unroll") for (int n = 0; n < 2; ++n) _Pragma("unroll") for (int k = 0; k < 2; ++k) \
;         acc[ai][bj][m][n] = __builtin_amdgcn_mfma_f32_16x16x32_bf16(Bt_[n][k], At_[m][k], acc[ai][bj][m][n], 0, 0, 0); __builtin_amdgcn_s_setprio(0); } while (0)
; #define WAIT_V(n) asm volatile("s_waitcnt vmcnt(" #n ")" ::: "memory")
; #define WAIT_L(n) asm volatile("s_waitcnt lgkmcnt(" #n ")" ::: "memory")
; #define BAR __builtin_amdgcn_s_barrier()
; #define SCHED __builtin_amdgcn_sched_barrier(0)
; template <class Get, class Epi>
; DI void gemm_loop(int ntiles, int ld, char* shm, const Get& get, const Epi& epi) {
;     ...
;         for (int t = 0; t < nt; t += 2) {
;             const bool last = (t == nt - 2);
;             const char* a1 = cA + (size_t)(t + 1) * kstep;
;             const char* a2 = last ? nA : cA + (size_t)(t + 2) * kstep; const char* b2 = last ? nB : cB + (size_t)(t + 2) * kstep;
;             const char* a3 = a2 + kstep; const char* b3 = b2 + kstep;
;             G_LDB(B0, 0, 0); G_LDB(B1, 0, 1); SCHED; G_LDA(At, 0, 0); G_STAGE(G_SA(1, 1), a1 + hstep, voffA);
;     ...
;             G_LDA(At, 1, 1); G_STAGE(G_SB(1, 0), b3, voffB); G_STAGE(G_SB(1, 1), b3 + hstep, voffB); G_STAGE(G_SA(1, 0), a3, voffA);
;             WAIT_V(8); WAIT_L(0); BAR; G_MMA(1, 0, At, B0); G_MMA(1, 1, At, B1); BAR; SCHED;
;         }
	s_mov_b32 m0, s58
	v_lshl_add_u64 v[182:183], v[182:183], 0, s[12:13]
	s_add_u32 s14, s14, 0x20080
	ds_read_b128 v[178:181], v142 offset:49152
	ds_read_b128 v[188:191], v142 offset:50176
	ds_read_b128 v[192:195], v142 offset:51200
	ds_read_b128 v[196:199], v142 offset:52224
	ds_read_b128 v[200:203], v142 offset:53248
	ds_read_b128 v[204:207], v142 offset:54272
	ds_read_b128 v[208:211], v142 offset:55296
	ds_read_b128 v[212:215], v142 offset:56320
	global_load_lds_dwordx4 v[182:183], off
	v_lshl_add_u64 v[182:183], v[184:185], 0, s[12:13]
	s_mov_b32 m0, s59
	s_addc_u32 s15, s15, 0
	global_load_lds_dwordx4 v[182:183], off
	v_lshl_add_u64 v[182:183], s[14:15], 0, v[132:133]
	s_mov_b32 m0, s72
	s_nop 0
	global_load_lds_dwordx4 v[182:183], off
	v_lshl_add_u64 v[182:183], s[14:15], 0, v[128:129]
	s_mov_b32 m0, s73
	s_nop 0
	global_load_lds_dwordx4 v[182:183], off
	v_lshl_add_u64 v[182:183], v[186:187], 0, s[12:13]
	s_mov_b32 m0, s46
	s_nop 0
	global_load_lds_dwordx4 v[182:183], off
	v_lshl_add_u64 v[182:183], v[216:217], 0, s[12:13]
	s_mov_b32 m0, s47
	s_nop 0
	global_load_lds_dwordx4 v[182:183], off
	s_waitcnt vmcnt(8)
	s_waitcnt lgkmcnt(0)
	s_barrier
	s_setprio 1
	s_waitcnt lgkmcnt(0)
	v_mfma_f32_16x16x32_bf16 v[60:63], v[146:149], v[178:181], v[60:63]
	v_mfma_f32_16x16x32_bf16 v[56:59], v[154:157], v[178:181], v[56:59]
	v_mfma_f32_16x16x32_bf16 v[52:55], v[146:149], v[192:195], v[52:55]
	v_mfma_f32_16x16x32_bf16 v[48:51], v[154:157], v[192:195], v[48:51]
	v_mfma_f32_16x16x32_bf16 v[36:39], v[146:149], v[200:203], v[36:39]
	v_mfma_f32_16x16x32_bf16 v[32:35], v[154:157], v[200:203], v[32:35]
	v_mfma_f32_16x16x32_bf16 v[20:23], v[146:149], v[208:211], v[20:23]
	v_mfma_f32_16x16x32_bf16 v[16:19], v[154:157], v[208:211], v[16:19]
	s_setprio 0
	s_setprio 1
	v_mfma_f32_16x16x32_bf16 v[60:63], v[150:153], v[188:191], v[60:63]
	v_mfma_f32_16x16x32_bf16 v[56:59], v[158:161], v[188:191], v[56:59]
	v_mfma_f32_16x16x32_bf16 v[52:55], v[150:153], v[196:199], v[52:55]
	v_mfma_f32_16x16x32_bf16 v[48:51], v[158:161], v[196:199], v[48:51]
	v_mfma_f32_16x16x32_bf16 v[36:39], v[150:153], v[204:207], v[36:39]
	v_mfma_f32_16x16x32_bf16 v[32:35], v[158:161], v[204:207], v[32:35]
	v_mfma_f32_16x16x32_bf16 v[20:23], v[150:153], v[212:215], v[20:23]
	v_mfma_f32_16x16x32_bf16 v[16:19], v[158:161], v[212:215], v[16:19]
	s_setprio 0
	s_setprio 1
	v_mfma_f32_16x16x32_bf16 v[44:47], v[162:165], v[178:181], v[44:47]
	v_mfma_f32_16x16x32_bf16 v[40:43], v[170:173], v[178:181], v[40:43]
	v_mfma_f32_16x16x32_bf16 v[28:31], v[162:165], v[192:195], v[28:31]
	v_mfma_f32_16x16x32_bf16 v[24:27], v[170:173], v[192:195], v[24:27]
	v_mfma_f32_16x16x32_bf16 v[12:15], v[162:165], v[200:203], v[12:15]
	v_mfma_f32_16x16x32_bf16 v[8:11], v[170:173], v[200:203], v[8:11]
	v_mfma_f32_16x16x32_bf16 v[4:7], v[162:165], v[208:211], v[4:7]
	v_mfma_f32_16x16x32_bf16 v[0:3], v[170:173], v[208:211], v[0:3]
	s_setprio 0
	s_setprio 1
	v_mfma_f32_16x16x32_bf16 v[44:47], v[166:169], v[188:191], v[44:47]
	v_mfma_f32_16x16x32_bf16 v[40:43], v[174:177], v[188:191], v[40:43]
	v_mfma_f32_16x16x32_bf16 v[28:31], v[166:169], v[196:199], v[28:31]
	v_mfma_f32_16x16x32_bf16 v[24:27], v[174:177], v[196:199], v[24:27]
	v_mfma_f32_16x16x32_bf16 v[12:15], v[166:169], v[204:207], v[12:15]
	v_mfma_f32_16x16x32_bf16 v[8:11], v[174:177], v[204:207], v[8:11]
	v_mfma_f32_16x16x32_bf16 v[4:7], v[166:169], v[212:215], v[4:7]
	v_mfma_f32_16x16x32_bf16 v[0:3], v[174:177], v[212:215], v[0:3]
	s_setprio 0
	s_barrier
	s_add_i32 s81, s81, 2
	s_add_u32 s36, s36, 0x100
	s_addc_u32 s37, s37, 0
	s_add_u32 s79, s79, 0x100
	s_addc_u32 s80, s80, 0
	s_cmp_gt_u32 s81, 5
	s_cbranch_scc0 .LBB0_445
	s_branch .Lpost_445
.LBB0_445:
	ds_read_b128 v[146:149], v140
	ds_read_b128 v[150:153], v140 offset:1024
	ds_read_b128 v[154:157], v140 offset:2048
	ds_read_b128 v[158:161], v140 offset:3072
	ds_read_b128 v[162:165], v141
	ds_read_b128 v[166:169], v141 offset:1024
	ds_read_b128 v[170:173], v141 offset:2048
	ds_read_b128 v[174:177], v141 offset:3072
	s_add_u32 s14, s36, 0xfffe0080
	s_addc_u32 s15, s37, -1
	s_cmp_eq_u32 s81, 4
	s_cselect_b32 s39, s3, s15
	s_cselect_b32 s38, s2, s14
	s_cselect_b32 s15, s76, s80
	s_cselect_b32 s14, s78, s79
	s_mov_b32 m0, s50
	v_lshl_add_u64 v[182:183], s[36:37], 0, v[136:137]
	ds_read_b128 v[178:181], v142
	ds_read_b128 v[188:191], v142 offset:1024
	ds_read_b128 v[192:195], v142 offset:2048
	ds_read_b128 v[196:199], v142 offset:3072
	ds_read_b128 v[200:203], v142 offset:4096
	ds_read_b128 v[204:207], v142 offset:5120
	ds_read_b128 v[208:211], v142 offset:6144
	ds_read_b128 v[212:215], v142 offset:7168
	global_load_lds_dwordx4 v[182:183], off
	v_lshl_add_u64 v[182:183], s[36:37], 0, v[138:139]
	s_mov_b32 m0, s51
	s_nop 0
	global_load_lds_dwordx4 v[182:183], off
	s_waitcnt vmcnt(8)
	s_waitcnt lgkmcnt(0)
	s_barrier
; #define G_STAGE(bufoff, gbase, voff) do { _Pragma("unroll") for (int _i = 0; _i < 2; ++_i) \
;         __builtin_amdgcn_global_load_lds((const unsigned*)((const char*)(gbase) + voff[_i]), (LAS unsigned*)(lds + (bufoff) + ldsw + _i * 8192), 16, 0, 0); } while (0)
; #define G_LDA(dst, b, h) do { _Pragma("unroll") for (int m = 0; m < 4; ++m) _Pragma("unroll") for (int k = 0; k < 2; ++k) dst[m][k] = *(const LAS bf16x8*)(lds + G_SA(b, h) + aoff + m * 2048 + k * 1024); } while (0)
; #define G_LDB(dst, b, h) do { _Pragma("unroll") for (int n = 0; n < 2; ++n) _Pragma("unroll") for (int k = 0; k < 2; ++k) dst[n][k] = *(const LAS bf16x8*)(lds + G_SB(b, h) + boff + n * 2048 + k * 1024); } while (0)
; #define G_MMA(ai, bj, At_, Bt_) do { __builtin_amdgcn_s_setprio(1); _Pragma("unroll") for (int m = 0; m < 4; ++m) _Pragma("unroll") for (int n = 0; n < 2; ++n) _Pragma("unroll") for (int k = 0; k < 2; ++k) \
;         acc[ai][bj][m][n] = __builtin_amdgcn_mfma_f32_16x16x32_bf16(Bt_[n][k], At_[m][k], acc[ai][bj][m][n], 0, 0, 0); __builtin_amdgcn_s_setprio(0); } while (0)
; #define WAIT_V(n) asm volatile("s_waitcnt vmcnt(" #n ")" ::: "memory")
; #define WAIT_L(n) asm volatile("s_waitcnt lgkmcnt(" #n ")" ::: "memory")
; #define BAR __builtin_amdgcn_s_barrier()
; #define SCHED __builtin_amdgcn_sched_barrier(0)
; template <class Get, class Epi>
; DI void gemm_loop(int ntiles, int ld, char* shm, const Get& get, const Epi& epi) {
;     ...
;             WAIT_V(8); WAIT_L(0); BAR; G_MMA(0, 0, At, B0); G_MMA(0, 1, At, B1); BAR; SCHED;
;             G_LDA(At, 0, 1); G_STAGE(G_SB(0, 0), b2, voffB); G_STAGE(G_SB(0, 1), b2 + hstep, voffB); G_STAGE(G_SA(0, 0), a2, voffA);
;             WAIT_V(8); WAIT_L(0); BAR; G_MMA(1, 0, At, B0); G_MMA(1, 1, At, B1); BAR; SCHED;
;             G_LDB(B0, 1, 0); G_LDB(B1, 1, 1); SCHED; G_LDA(At, 1, 0); G_STAGE(G_SA(0, 1), a2 + hstep, voffA);
;             WAIT_V(8); WAIT_L(0); BAR; G_MMA(0, 0, At, B0); G_MMA(0, 1, At, B1); BAR; SCHED;
	s_setprio 1
	s_waitcnt lgkmcnt(0)
	v_mfma_f32_16x16x32_bf16 v[124:127], v[146:149], v[178:181], v[124:127]
	v_mfma_f32_16x16x32_bf16 v[120:123], v[154:157], v[178:181], v[120:123]
	v_mfma_f32_16x16x32_bf16 v[116:119], v[146:149], v[192:195], v[116:119]
	v_mfma_f32_16x16x32_bf16 v[112:115], v[154:157], v[192:195], v[112:115]
	v_mfma_f32_16x16x32_bf16 v[100:103], v[146:149], v[200:203], v[100:103]
	v_mfma_f32_16x16x32_bf16 v[96:99], v[154:157], v[200:203], v[96:99]
	v_mfma_f32_16x16x32_bf16 v[84:87], v[146:149], v[208:211], v[84:87]
	v_mfma_f32_16x16x32_bf16 v[80:83], v[154:157], v[208:211], v[80:83]
	s_setprio 0
	s_setprio 1
	v_mfma_f32_16x16x32_bf16 v[124:127], v[150:153], v[188:191], v[124:127]
	v_mfma_f32_16x16x32_bf16 v[120:123], v[158:161], v[188:191], v[120:123]
	v_mfma_f32_16x16x32_bf16 v[116:119], v[150:153], v[196:199], v[116:119]
	v_mfma_f32_16x16x32_bf16 v[112:115], v[158:161], v[196:199], v[112:115]
	v_mfma_f32_16x16x32_bf16 v[100:103], v[150:153], v[204:207], v[100:103]
	v_mfma_f32_16x16x32_bf16 v[96:99], v[158:161], v[204:207], v[96:99]
	v_mfma_f32_16x16x32_bf16 v[84:87], v[150:153], v[212:215], v[84:87]
	v_mfma_f32_16x16x32_bf16 v[80:83], v[158:161], v[212:215], v[80:83]
	s_setprio 0
	s_setprio 1
	v_mfma_f32_16x16x32_bf16 v[108:111], v[162:165], v[178:181], v[108:111]
	v_mfma_f32_16x16x32_bf16 v[104:107], v[170:173], v[178:181], v[104:107]
	v_mfma_f32_16x16x32_bf16 v[92:95], v[162:165], v[192:195], v[92:95]
	v_mfma_f32_16x16x32_bf16 v[88:91], v[170:173], v[192:195], v[88:91]
	v_mfma_f32_16x16x32_bf16 v[76:79], v[162:165], v[200:203], v[76:79]
	v_mfma_f32_16x16x32_bf16 v[72:75], v[170:173], v[200:203], v[72:75]
	v_mfma_f32_16x16x32_bf16 v[68:71], v[162:165], v[208:211], v[68:71]
	v_mfma_f32_16x16x32_bf16 v[64:67], v[170:173], v[208:211], v[64:67]
	s_setprio 0
	s_setprio 1
	v_mfma_f32_16x16x32_bf16 v[108:111], v[166:169], v[188:191], v[108:111]
	v_mfma_f32_16x16x32_bf16 v[104:107], v[174:177], v[188:191], v[104:107]
	v_mfma_f32_16x16x32_bf16 v[92:95], v[166:169], v[196:199], v[92:95]
	v_mfma_f32_16x16x32_bf16 v[88:91], v[174:177], v[196:199], v[88:91]
	v_mfma_f32_16x16x32_bf16 v[76:79], v[166:169], v[204:207], v[76:79]
	v_mfma_f32_16x16x32_bf16 v[72:75], v[174:177], v[204:207], v[72:75]
	v_mfma_f32_16x16x32_bf16 v[68:71], v[166:169], v[212:215], v[68:71]
	v_mfma_f32_16x16x32_bf16 v[64:67], v[174:177], v[212:215], v[64:67]
	s_setprio 0
	s_barrier
	s_mov_b32 m0, s54
	v_lshl_add_u64 v[182:183], s[14:15], 0, v[132:133]
	s_add_u32 s82, s14, 0x20000
	ds_read_b128 v[178:181], v142 offset:16384
	ds_read_b128 v[188:191], v142 offset:17408
	ds_read_b128 v[192:195], v142 offset:18432
	ds_read_b128 v[196:199], v142 offset:19456
	ds_read_b128 v[200:203], v142 offset:20480
	ds_read_b128 v[204:207], v142 offset:21504
	ds_read_b128 v[208:211], v142 offset:22528
	ds_read_b128 v[212:215], v142 offset:23552
	global_load_lds_dwordx4 v[182:183], off
	v_lshl_add_u64 v[184:185], s[14:15], 0, v[128:129]
	s_mov_b32 m0, s55
	s_addc_u32 s83, s15, 0
	global_load_lds_dwordx4 v[184:185], off
	v_lshl_add_u64 v[186:187], s[82:83], 0, v[132:133]
	s_mov_b32 m0, s56
	v_lshl_add_u64 v[216:217], s[38:39], 0, v[130:131]
	global_load_lds_dwordx4 v[186:187], off
	v_lshl_add_u64 v[186:187], s[82:83], 0, v[128:129]
	s_mov_b32 m0, s57
	s_nop 0
	global_load_lds_dwordx4 v[186:187], off
	v_lshl_add_u64 v[186:187], s[38:39], 0, v[134:135]
	s_mov_b32 m0, s41
	s_nop 0
	global_load_lds_dwordx4 v[186:187], off
	s_mov_b32 m0, s43
	s_nop 0
	global_load_lds_dwordx4 v[216:217], off
	s_waitcnt vmcnt(8)
	s_waitcnt lgkmcnt(0)
	s_barrier
	s_setprio 1
	s_waitcnt lgkmcnt(0)
	v_mfma_f32_16x16x32_bf16 v[60:63], v[146:149], v[178:181], v[60:63]
	v_mfma_f32_16x16x32_bf16 v[56:59], v[154:157], v[178:181], v[56:59]
	v_mfma_f32_16x16x32_bf16 v[52:55], v[146:149], v[192:195], v[52:55]
	v_mfma_f32_16x16x32_bf16 v[48:51], v[154:157], v[192:195], v[48:51]
	v_mfma_f32_16x16x32_bf16 v[36:39], v[146:149], v[200:203], v[36:39]
	v_mfma_f32_16x16x32_bf16 v[32:35], v[154:157], v[200:203], v[32:35]
	v_mfma_f32_16x16x32_bf16 v[20:23], v[146:149], v[208:211], v[20:23]
	v_mfma_f32_16x16x32_bf16 v[16:19], v[154:157], v[208:211], v[16:19]
	s_setprio 0
	s_setprio 1
	v_mfma_f32_16x16x32_bf16 v[60:63], v[150:153], v[188:191], v[60:63]
	v_mfma_f32_16x16x32_bf16 v[56:59], v[158:161], v[188:191], v[56:59]
	v_mfma_f32_16x16x32_bf16 v[52:55], v[150:153], v[196:199], v[52:55]
	v_mfma_f32_16x16x32_bf16 v[48:51], v[158:161], v[196:199], v[48:51]
	v_mfma_f32_16x16x32_bf16 v[36:39], v[150:153], v[204:207], v[36:39]
	v_mfma_f32_16x16x32_bf16 v[32:35], v[158:161], v[204:207], v[32:35]
	v_mfma_f32_16x16x32_bf16 v[20:23], v[150:153], v[212:215], v[20:23]
	v_mfma_f32_16x16x32_bf16 v[16:19], v[158:161], v[212:215], v[16:19]
	s_setprio 0
	s_setprio 1
	v_mfma_f32_16x16x32_bf16 v[44:47], v[162:165], v[178:181], v[44:47]
	v_mfma_f32_16x16x32_bf16 v[40:43], v[170:173], v[178:181], v[40:43]
	v_mfma_f32_16x16x32_bf16 v[28:31], v[162:165], v[192:195], v[28:31]
	v_mfma_f32_16x16x32_bf16 v[24:27], v[170:173], v[192:195], v[24:27]
	v_mfma_f32_16x16x32_bf16 v[12:15], v[162:165], v[200:203], v[12:15]
	v_mfma_f32_16x16x32_bf16 v[8:11], v[170:173], v[200:203], v[8:11]
	v_mfma_f32_16x16x32_bf16 v[4:7], v[162:165], v[208:211], v[4:7]
	v_mfma_f32_16x16x32_bf16 v[0:3], v[170:173], v[208:211], v[0:3]
	s_setprio 0
	s_setprio 1
	v_mfma_f32_16x16x32_bf16 v[44:47], v[166:169], v[188:191], v[44:47]
	v_mfma_f32_16x16x32_bf16 v[40:43], v[174:177], v[188:191], v[40:43]
	v_mfma_f32_16x16x32_bf16 v[28:31], v[166:169], v[196:199], v[28:31]
	v_mfma_f32_16x16x32_bf16 v[24:27], v[174:177], v[196:199], v[24:27]
	v_mfma_f32_16x16x32_bf16 v[12:15], v[166:169], v[204:207], v[12:15]
	v_mfma_f32_16x16x32_bf16 v[8:11], v[174:177], v[204:207], v[8:11]
	v_mfma_f32_16x16x32_bf16 v[4:7], v[166:169], v[212:215], v[4:7]
	v_mfma_f32_16x16x32_bf16 v[0:3], v[174:177], v[212:215], v[0:3]
	s_setprio 0
	s_barrier
; #define G_STAGE(bufoff, gbase, voff) do { _Pragma("unroll") for (int _i = 0; _i < 2; ++_i) \
;         __builtin_amdgcn_global_load_lds((const unsigned*)((const char*)(gbase) + voff[_i]), (LAS unsigned*)(lds + (bufoff) + ldsw + _i * 8192), 16, 0, 0); } while (0)
; #define G_LDA(dst, b, h) do { _Pragma("unroll") for (int m = 0; m < 4; ++m) _Pragma("unroll") for (int k = 0; k < 2; ++k) dst[m][k] = *(const LAS bf16x8*)(lds + G_SA(b, h) + aoff + m * 2048 + k * 1024); } while (0)
; #define G_LDB(dst, b, h) do { _Pragma("unroll") for (int n = 0; n < 2; ++n) _Pragma("unroll") for (int k = 0; k < 2; ++k) dst[n][k] = *(const LAS bf16x8*)(lds + G_SB(b, h) + boff + n * 2048 + k * 1024); } while (0)
; #define G_MMA(ai, bj, At_, Bt_) do { __builtin_amdgcn_s_setprio(1); _Pragma("unroll") for (int m = 0; m < 4; ++m) _Pragma("unroll") for (int n = 0; n < 2; ++n) _Pragma("unroll") for (int k = 0; k < 2; ++k) \
;         acc[ai][bj][m][n] = __builtin_amdgcn_mfma_f32_16x16x32_bf16(Bt_[n][k], At_[m][k], acc[ai][bj][m][n], 0, 0, 0); __builtin_amdgcn_s_setprio(0); } while (0)
; #define WAIT_V(n) asm volatile("s_waitcnt vmcnt(" #n ")" ::: "memory")
; #define WAIT_L(n) asm volatile("s_waitcnt lgkmcnt(" #n ")" ::: "memory")
; #define BAR __builtin_amdgcn_s_barrier()
; #define SCHED __builtin_amdgcn_sched_barrier(0)
; template <class Get, class Epi>
; DI void gemm_loop(int ntiles, int ld, char* shm, const Get& get, const Epi& epi) {
;     ...
;             G_LDB(B0, 1, 0); G_LDB(B1, 1, 1); SCHED; G_LDA(At, 1, 0); G_STAGE(G_SA(0, 1), a2 + hstep, voffA);
;             WAIT_V(8); WAIT_L(0); BAR; G_MMA(0, 0, At, B0); G_MMA(0, 1, At, B1); BAR; SCHED;
	ds_read_b128 v[146:149], v143
	ds_read_b128 v[150:153], v143 offset:1024
	ds_read_b128 v[154:157], v143 offset:2048
	ds_read_b128 v[158:161], v143 offset:3072
	ds_read_b128 v[162:165], v144
	ds_read_b128 v[166:169], v144 offset:1024
	ds_read_b128 v[170:173], v144 offset:2048
	ds_read_b128 v[174:177], v144 offset:3072
	s_add_u32 s38, s38, 0x20000
	s_addc_u32 s39, s39, 0
	s_mov_b32 m0, s44
	v_lshl_add_u64 v[218:219], s[38:39], 0, v[134:135]
	ds_read_b128 v[178:181], v142 offset:32768
	ds_read_b128 v[188:191], v142 offset:33792
	ds_read_b128 v[192:195], v142 offset:34816
	ds_read_b128 v[196:199], v142 offset:35840
	ds_read_b128 v[200:203], v142 offset:36864
	ds_read_b128 v[204:207], v142 offset:37888
	ds_read_b128 v[208:211], v142 offset:38912
	ds_read_b128 v[212:215], v142 offset:39936
	global_load_lds_dwordx4 v[218:219], off
	v_lshl_add_u64 v[218:219], s[38:39], 0, v[130:131]
	s_mov_b32 m0, s45
	s_nop 0
	global_load_lds_dwordx4 v[218:219], off
	s_waitcnt vmcnt(8)
	s_waitcnt lgkmcnt(0)
	s_barrier
	s_setprio 1
	s_waitcnt lgkmcnt(0)
	v_mfma_f32_16x16x32_bf16 v[124:127], v[146:149], v[178:181], v[124:127]
	v_mfma_f32_16x16x32_bf16 v[120:123], v[154:157], v[178:181], v[120:123]
	v_mfma_f32_16x16x32_bf16 v[116:119], v[146:149], v[192:195], v[116:119]
	v_mfma_f32_16x16x32_bf16 v[112:115], v[154:157], v[192:195], v[112:115]
	v_mfma_f32_16x16x32_bf16 v[100:103], v[146:149], v[200:203], v[100:103]
	v_mfma_f32_16x16x32_bf16 v[96:99], v[154:157], v[200:203], v[96:99]
	v_mfma_f32_16x16x32_bf16 v[84:87], v[146:149], v[208:211], v[84:87]
	v_mfma_f32_16x16x32_bf16 v[80:83], v[154:157], v[208:211], v[80:83]
	s_setprio 0
	s_setprio 1
	v_mfma_f32_16x16x32_bf16 v[124:127], v[150:153], v[188:191], v[124:127]
	v_mfma_f32_16x16x32_bf16 v[120:123], v[158:161], v[188:191], v[120:123]
	v_mfma_f32_16x16x32_bf16 v[116:119], v[150:153], v[196:199], v[116:119]
	v_mfma_f32_16x16x32_bf16 v[112:115], v[158:161], v[196:199], v[112:115]
	v_mfma_f32_16x16x32_bf16 v[100:103], v[150:153], v[204:207], v[100:103]
	v_mfma_f32_16x16x32_bf16 v[96:99], v[158:161], v[204:207], v[96:99]
	v_mfma_f32_16x16x32_bf16 v[84:87], v[150:153], v[212:215], v[84:87]
	v_mfma_f32_16x16x32_bf16 v[80:83], v[158:161], v[212:215], v[80:83]
	s_setprio 0
	s_setprio 1
	v_mfma_f32_16x16x32_bf16 v[108:111], v[162:165], v[178:181], v[108:111]
	v_mfma_f32_16x16x32_bf16 v[104:107], v[170:173], v[178:181], v[104:107]
	v_mfma_f32_16x16x32_bf16 v[92:95], v[162:165], v[192:195], v[92:95]
	v_mfma_f32_16x16x32_bf16 v[88:91], v[170:173], v[192:195], v[88:91]
	v_mfma_f32_16x16x32_bf16 v[76:79], v[162:165], v[200:203], v[76:79]
	v_mfma_f32_16x16x32_bf16 v[72:75], v[170:173], v[200:203], v[72:75]
	v_mfma_f32_16x16x32_bf16 v[68:71], v[162:165], v[208:211], v[68:71]
	v_mfma_f32_16x16x32_bf16 v[64:67], v[170:173], v[208:211], v[64:67]
	s_setprio 0
	s_setprio 1
	v_mfma_f32_16x16x32_bf16 v[108:111], v[166:169], v[188:191], v[108:111]
	v_mfma_f32_16x16x32_bf16 v[104:107], v[174:177], v[188:191], v[104:107]
	v_mfma_f32_16x16x32_bf16 v[92:95], v[166:169], v[196:199], v[92:95]
	v_mfma_f32_16x16x32_bf16 v[88:91], v[174:177], v[196:199], v[88:91]
	v_mfma_f32_16x16x32_bf16 v[76:79], v[166:169], v[204:207], v[76:79]
	v_mfma_f32_16x16x32_bf16 v[72:75], v[174:177], v[204:207], v[72:75]
	v_mfma_f32_16x16x32_bf16 v[68:71], v[166:169], v[212:215], v[68:71]
	v_mfma_f32_16x16x32_bf16 v[64:67], v[174:177], v[212:215], v[64:67]
	s_setprio 0
	s_barrier
; #define G_STAGE(bufoff, gbase, voff) do { _Pragma("unroll") for (int _i = 0; _i < 2; ++_i) \
;         __builtin_amdgcn_global_load_lds((const unsigned*)((const char*)(gbase) + voff[_i]), (LAS unsigned*)(lds + (bufoff) + ldsw + _i * 8192), 16, 0, 0); } while (0)
; #define G_LDA(dst, b, h) do { _Pragma("unroll") for (int m = 0; m < 4; ++m) _Pragma("unroll") for (int k = 0; k < 2; ++k) dst[m][k] = *(const LAS bf16x8*)(lds + G_SA(b, h) + aoff + m * 2048 + k * 1024); } while (0)
; #define G_MMA(ai, bj, At_, Bt_) do { __builtin_amdgcn_s_setprio(1); _Pragma("unroll") for (int m = 0; m < 4; ++m) _Pragma("unroll") for (int n = 0; n < 2; ++n) _Pragma("unroll") for (int k = 0; k < 2; ++k) \
;         acc[ai][bj][m][n] = __builtin_amdgcn_mfma_f32_16x16x32_bf16(Bt_[n][k], At_[m][k], acc[ai][bj][m][n], 0, 0, 0); __builtin_amdgcn_s_setprio(0); } while (0)
; #define WAIT_V(n) asm volatile("s_waitcnt vmcnt(" #n ")" ::: "memory")
; #define WAIT_L(n) asm volatile("s_waitcnt lgkmcnt(" #n ")" ::: "memory")
; #define BAR __builtin_amdgcn_s_barrier()
; #define SCHED __builtin_amdgcn_sched_barrier(0)
; template <class Get, class Epi>
; DI void gemm_loop(int ntiles, int ld, char* shm, const Get& get, const Epi& epi) {
;     ...
;             G_LDA(At, 1, 1); G_STAGE(G_SB(1, 0), b3, voffB); G_STAGE(G_SB(1, 1), b3 + hstep, voffB); G_STAGE(G_SA(1, 0), a3, voffA);
;             WAIT_V(8); WAIT_L(0); BAR; G_MMA(1, 0, At, B0); G_MMA(1, 1, At, B1); BAR; SCHED;
;         }
	s_mov_b32 m0, s58
	v_lshl_add_u64 v[182:183], v[182:183], 0, s[12:13]
	s_add_u32 s14, s14, 0x20080
	ds_read_b128 v[178:181], v142 offset:49152
	ds_read_b128 v[188:191], v142 offset:50176
	ds_read_b128 v[192:195], v142 offset:51200
	ds_read_b128 v[196:199], v142 offset:52224
	ds_read_b128 v[200:203], v142 offset:53248
	ds_read_b128 v[204:207], v142 offset:54272
	ds_read_b128 v[208:211], v142 offset:55296
	ds_read_b128 v[212:215], v142 offset:56320
	global_load_lds_dwordx4 v[182:183], off
	v_lshl_add_u64 v[182:183], v[184:185], 0, s[12:13]
	s_mov_b32 m0, s59
	s_addc_u32 s15, s15, 0
	global_load_lds_dwordx4 v[182:183], off
	v_lshl_add_u64 v[182:183], s[14:15], 0, v[132:133]
	s_mov_b32 m0, s72
	s_nop 0
	global_load_lds_dwordx4 v[182:183], off
	v_lshl_add_u64 v[182:183], s[14:15], 0, v[128:129]
	s_mov_b32 m0, s73
	s_nop 0
	global_load_lds_dwordx4 v[182:183], off
	v_lshl_add_u64 v[182:183], v[186:187], 0, s[12:13]
	s_mov_b32 m0, s46
	s_nop 0
	global_load_lds_dwordx4 v[182:183], off
	v_lshl_add_u64 v[182:183], v[216:217], 0, s[12:13]
	s_mov_b32 m0, s47
	s_nop 0
	global_load_lds_dwordx4 v[182:183], off
	s_waitcnt vmcnt(8)
	s_waitcnt lgkmcnt(0)
	s_barrier
	s_setprio 1
	s_waitcnt lgkmcnt(0)
	v_mfma_f32_16x16x32_bf16 v[60:63], v[146:149], v[178:181], v[60:63]
	v_mfma_f32_16x16x32_bf16 v[56:59], v[154:157], v[178:181], v[56:59]
	v_mfma_f32_16x16x32_bf16 v[52:55], v[146:149], v[192:195], v[52:55]
	v_mfma_f32_16x16x32_bf16 v[48:51], v[154:157], v[192:195], v[48:51]
	v_mfma_f32_16x16x32_bf16 v[36:39], v[146:149], v[200:203], v[36:39]
	v_mfma_f32_16x16x32_bf16 v[32:35], v[154:157], v[200:203], v[32:35]
	v_mfma_f32_16x16x32_bf16 v[20:23], v[146:149], v[208:211], v[20:23]
	v_mfma_f32_16x16x32_bf16 v[16:19], v[154:157], v[208:211], v[16:19]
	s_setprio 0
	s_setprio 1
	v_mfma_f32_16x16x32_bf16 v[60:63], v[150:153], v[188:191], v[60:63]
	v_mfma_f32_16x16x32_bf16 v[56:59], v[158:161], v[188:191], v[56:59]
	v_mfma_f32_16x16x32_bf16 v[52:55], v[150:153], v[196:199], v[52:55]
	v_mfma_f32_16x16x32_bf16 v[48:51], v[158:161], v[196:199], v[48:51]
	v_mfma_f32_16x16x32_bf16 v[36:39], v[150:153], v[204:207], v[36:39]
	v_mfma_f32_16x16x32_bf16 v[32:35], v[158:161], v[204:207], v[32:35]
	v_mfma_f32_16x16x32_bf16 v[20:23], v[150:153], v[212:215], v[20:23]
	v_mfma_f32_16x16x32_bf16 v[16:19], v[158:161], v[212:215], v[16:19]
	s_setprio 0
	s_setprio 1
	v_mfma_f32_16x16x32_bf16 v[44:47], v[162:165], v[178:181], v[44:47]
	v_mfma_f32_16x16x32_bf16 v[40:43], v[170:173], v[178:181], v[40:43]
	v_mfma_f32_16x16x32_bf16 v[28:31], v[162:165], v[192:195], v[28:31]
	v_mfma_f32_16x16x32_bf16 v[24:27], v[170:173], v[192:195], v[24:27]
	v_mfma_f32_16x16x32_bf16 v[12:15], v[162:165], v[200:203], v[12:15]
	v_mfma_f32_16x16x32_bf16 v[8:11], v[170:173], v[200:203], v[8:11]
	v_mfma_f32_16x16x32_bf16 v[4:7], v[162:165], v[208:211], v[4:7]
	v_mfma_f32_16x16x32_bf16 v[0:3], v[170:173], v[208:211], v[0:3]
	s_setprio 0
	s_setprio 1
	v_mfma_f32_16x16x32_bf16 v[44:47], v[166:169], v[188:191], v[44:47]
	v_mfma_f32_16x16x32_bf16 v[40:43], v[174:177], v[188:191], v[40:43]
	v_mfma_f32_16x16x32_bf16 v[28:31], v[166:169], v[196:199], v[28:31]
	v_mfma_f32_16x16x32_bf16 v[24:27], v[174:177], v[196:199], v[24:27]
	v_mfma_f32_16x16x32_bf16 v[12:15], v[166:169], v[204:207], v[12:15]
	v_mfma_f32_16x16x32_bf16 v[8:11], v[174:177], v[204:207], v[8:11]
	v_mfma_f32_16x16x32_bf16 v[4:7], v[166:169], v[212:215], v[4:7]
	v_mfma_f32_16x16x32_bf16 v[0:3], v[174:177], v[212:215], v[0:3]
	s_setprio 0
	s_barrier
	s_add_i32 s81, s81, 2
	s_add_u32 s36, s36, 0x100
	s_addc_u32 s37, s37, 0
	s_add_u32 s79, s79, 0x100
	s_addc_u32 s80, s80, 0
	s_cmp_gt_u32 s81, 5
	s_cbranch_scc0 .LBB0_445

; #define G_STAGE(bufoff, gbase, voff) do { _Pragma("unroll") for (int _i = 0; _i < 2; ++_i) \
;         __builtin_amdgcn_global_load_lds((const unsigned*)((const char*)(gbase) + voff[_i]), (LAS unsigned*)(lds + (bufoff) + ldsw + _i * 8192), 16, 0, 0); } while (0)
; #define G_LDA(dst, b, h) do { _Pragma("unroll") for (int m = 0; m < 4; ++m) _Pragma("unroll") for (int k = 0; k < 2; ++k) dst[m][k] = *(const LAS bf16x8*)(lds + G_SA(b, h) + aoff + m * 2048 + k * 1024); } while (0)
; #define G_LDB(dst, b, h) do { _Pragma("unroll") for (int n = 0; n < 2; ++n) _Pragma("unroll") for (int k = 0; k < 2; ++k) dst[n][k] = *(const LAS bf16x8*)(lds + G_SB(b, h) + boff + n * 2048 + k * 1024); } while (0)
; #define G_MMA(ai, bj, At_, Bt_) do { __builtin_amdgcn_s_setprio(1); _Pragma("unroll") for (int m = 0; m < 4; ++m) _Pragma("unroll") for (int n = 0; n < 2; ++n) _Pragma("unroll") for (int k = 0; k < 2; ++k) \
;         acc[ai][bj][m][n] = __builtin_amdgcn_mfma_f32_16x16x32_bf16(Bt_[n][k], At_[m][k], acc[ai][bj][m][n], 0, 0, 0); __builtin_amdgcn_s_setprio(0); } while (0)
; #define WAIT_V(n) asm volatile("s_waitcnt vmcnt(" #n ")" ::: "memory")
; #define WAIT_L(n) asm volatile("s_waitcnt lgkmcnt(" #n ")" ::: "memory")
; #define BAR __builtin_amdgcn_s_barrier()
; #define SCHED __builtin_amdgcn_sched_barrier(0)
; template <class Get, class Epi>
; DI void gemm_loop(int ntiles, int ld, char* shm, const Get& get, const Epi& epi) {
;     ...
;             G_LDB(B0, 0, 0); G_LDB(B1, 0, 1); SCHED; G_LDA(At, 0, 0); G_STAGE(G_SA(1, 1), a1 + hstep, voffA);
;             WAIT_V(8); WAIT_L(0); BAR; G_MMA(0, 0, At, B0); G_MMA(0, 1, At, B1); BAR; SCHED;
;             G_LDA(At, 0, 1); G_STAGE(G_SB(0, 0), b2, voffB); G_STAGE(G_SB(0, 1), b2 + hstep, voffB); G_STAGE(G_SA(0, 0), a2, voffA);
;             WAIT_V(8); WAIT_L(0); BAR; G_MMA(1, 0, At, B0); G_MMA(1, 1, At, B1); BAR; SCHED;
.Lrj_528_0:
	s_waitcnt lgkmcnt(0)
	s_barrier
	s_setprio 1
	s_waitcnt lgkmcnt(0)
	v_mfma_f32_16x16x32_bf16 v[124:127], v[128:131], v[172:175], 0
	v_mfma_f32_16x16x32_bf16 v[120:123], v[136:139], v[172:175], 0
	v_mfma_f32_16x16x32_bf16 v[116:119], v[128:131], v[188:191], 0
	v_mfma_f32_16x16x32_bf16 v[112:115], v[136:139], v[188:191], 0
	v_mfma_f32_16x16x32_bf16 v[108:111], v[128:131], v[196:199], 0
	v_mfma_f32_16x16x32_bf16 v[104:107], v[136:139], v[196:199], 0
	v_mfma_f32_16x16x32_bf16 v[100:103], v[128:131], v[204:207], 0
	v_mfma_f32_16x16x32_bf16 v[96:99], v[136:139], v[204:207], 0
	s_setprio 0
	s_setprio 1
	v_mfma_f32_16x16x32_bf16 v[124:127], v[132:135], v[180:183], v[124:127]
	v_mfma_f32_16x16x32_bf16 v[120:123], v[140:143], v[180:183], v[120:123]
	v_mfma_f32_16x16x32_bf16 v[116:119], v[132:135], v[192:195], v[116:119]
	v_mfma_f32_16x16x32_bf16 v[112:115], v[140:143], v[192:195], v[112:115]
	v_mfma_f32_16x16x32_bf16 v[108:111], v[132:135], v[200:203], v[108:111]
	v_mfma_f32_16x16x32_bf16 v[104:107], v[140:143], v[200:203], v[104:107]
	v_mfma_f32_16x16x32_bf16 v[100:103], v[132:135], v[208:211], v[100:103]
	v_mfma_f32_16x16x32_bf16 v[96:99], v[140:143], v[208:211], v[96:99]
	s_setprio 0
	s_setprio 1
	v_mfma_f32_16x16x32_bf16 v[60:63], v[144:147], v[172:175], 0
	v_mfma_f32_16x16x32_bf16 v[56:59], v[164:167], v[172:175], 0
	v_mfma_f32_16x16x32_bf16 v[52:55], v[144:147], v[188:191], 0
	v_mfma_f32_16x16x32_bf16 v[48:51], v[164:167], v[188:191], 0
	v_mfma_f32_16x16x32_bf16 v[44:47], v[144:147], v[196:199], 0
	v_mfma_f32_16x16x32_bf16 v[40:43], v[164:167], v[196:199], 0
	v_mfma_f32_16x16x32_bf16 v[36:39], v[144:147], v[204:207], 0
	v_mfma_f32_16x16x32_bf16 v[32:35], v[164:167], v[204:207], 0
	s_setprio 0
	s_setprio 1
	v_mfma_f32_16x16x32_bf16 v[60:63], v[148:151], v[180:183], v[60:63]
	v_mfma_f32_16x16x32_bf16 v[56:59], v[168:171], v[180:183], v[56:59]
	v_mfma_f32_16x16x32_bf16 v[52:55], v[148:151], v[192:195], v[52:55]
	v_mfma_f32_16x16x32_bf16 v[48:51], v[168:171], v[192:195], v[48:51]
	v_mfma_f32_16x16x32_bf16 v[44:47], v[148:151], v[200:203], v[44:47]
	v_mfma_f32_16x16x32_bf16 v[40:43], v[168:171], v[200:203], v[40:43]
	v_mfma_f32_16x16x32_bf16 v[36:39], v[148:151], v[208:211], v[36:39]
	v_mfma_f32_16x16x32_bf16 v[32:35], v[168:171], v[208:211], v[32:35]
	s_setprio 0
	s_barrier
	s_add_i32 s84, s78, s56
	v_lshl_add_u64 v[184:185], s[14:15], 0, v[154:155]
	s_mov_b32 m0, s84
	ds_read_b128 v[172:175], v179 offset:16384
	ds_read_b128 v[180:183], v179 offset:17408
	ds_read_b128 v[188:191], v179 offset:18432
	ds_read_b128 v[192:195], v179 offset:19456
	ds_read_b128 v[196:199], v179 offset:20480
	ds_read_b128 v[200:203], v179 offset:21504
	ds_read_b128 v[204:207], v179 offset:22528
	ds_read_b128 v[208:211], v179 offset:23552
	global_load_lds_dwordx4 v[184:185], off
	s_add_i32 m0, s84, 0x2000
	s_add_u32 s84, s14, 0x40000
	v_lshl_add_u64 v[186:187], s[14:15], 0, v[158:159]
	s_addc_u32 s85, s15, 0
	s_add_i32 s86, s79, s56
	global_load_lds_dwordx4 v[186:187], off
	v_lshl_add_u64 v[212:213], s[84:85], 0, v[154:155]
	s_mov_b32 m0, s86
	v_lshl_add_u64 v[214:215], s[46:47], 0, v[156:157]
	global_load_lds_dwordx4 v[212:213], off
	v_lshl_add_u64 v[212:213], s[84:85], 0, v[158:159]
	s_add_i32 m0, s86, 0x2000
	s_nop 0
	global_load_lds_dwordx4 v[212:213], off
	v_lshl_add_u64 v[212:213], s[46:47], 0, v[152:153]
	s_mov_b32 m0, s57
	s_nop 0
	global_load_lds_dwordx4 v[212:213], off
	s_mov_b32 m0, s58
	s_nop 0
	global_load_lds_dwordx4 v[214:215], off
	s_cmp_lg_u32 s100, 0
	s_cbranch_scc0 .Lrf_528_1
	s_waitcnt vmcnt(16)
	s_branch .Lrj_528_1

; #define G_STAGE(bufoff, gbase, voff) do { _Pragma("unroll") for (int _i = 0; _i < 2; ++_i) \
;         __builtin_amdgcn_global_load_lds((const unsigned*)((const char*)(gbase) + voff[_i]), (LAS unsigned*)(lds + (bufoff) + ldsw + _i * 8192), 16, 0, 0); } while (0)
; #define G_LDA(dst, b, h) do { _Pragma("unroll") for (int m = 0; m < 4; ++m) _Pragma("unroll") for (int k = 0; k < 2; ++k) dst[m][k] = *(const LAS bf16x8*)(lds + G_SA(b, h) + aoff + m * 2048 + k * 1024); } while (0)
; #define G_LDB(dst, b, h) do { _Pragma("unroll") for (int n = 0; n < 2; ++n) _Pragma("unroll") for (int k = 0; k < 2; ++k) dst[n][k] = *(const LAS bf16x8*)(lds + G_SB(b, h) + boff + n * 2048 + k * 1024); } while (0)
; #define G_MMA(ai, bj, At_, Bt_) do { __builtin_amdgcn_s_setprio(1); _Pragma("unroll") for (int m = 0; m < 4; ++m) _Pragma("unroll") for (int n = 0; n < 2; ++n) _Pragma("unroll") for (int k = 0; k < 2; ++k) \
;         acc[ai][bj][m][n] = __builtin_amdgcn_mfma_f32_16x16x32_bf16(Bt_[n][k], At_[m][k], acc[ai][bj][m][n], 0, 0, 0); __builtin_amdgcn_s_setprio(0); } while (0)
; #define WAIT_V(n) asm volatile("s_waitcnt vmcnt(" #n ")" ::: "memory")
; #define WAIT_L(n) asm volatile("s_waitcnt lgkmcnt(" #n ")" ::: "memory")
; #define BAR __builtin_amdgcn_s_barrier()
; #define SCHED __builtin_amdgcn_sched_barrier(0)
; template <class Get, class Epi>
; DI void gemm_loop(int ntiles, int ld, char* shm, const Get& get, const Epi& epi) {
;     ...
;             WAIT_V(8); WAIT_L(0); BAR; G_MMA(1, 0, At, B0); G_MMA(1, 1, At, B1); BAR; SCHED;
;             G_LDB(B0, 1, 0); G_LDB(B1, 1, 1); SCHED; G_LDA(At, 1, 0); G_STAGE(G_SA(0, 1), a2 + hstep, voffA);
;             WAIT_V(8); WAIT_L(0); BAR; G_MMA(0, 0, At, B0); G_MMA(0, 1, At, B1); BAR; SCHED;
.Lrj_528_1:
	s_waitcnt lgkmcnt(0)
	s_barrier
	s_setprio 1
	s_waitcnt lgkmcnt(0)
	v_mfma_f32_16x16x32_bf16 v[92:95], v[128:131], v[172:175], 0
	v_mfma_f32_16x16x32_bf16 v[88:91], v[136:139], v[172:175], 0
	v_mfma_f32_16x16x32_bf16 v[84:87], v[128:131], v[188:191], 0
	v_mfma_f32_16x16x32_bf16 v[80:83], v[136:139], v[188:191], 0
	v_mfma_f32_16x16x32_bf16 v[76:79], v[128:131], v[196:199], 0
	v_mfma_f32_16x16x32_bf16 v[72:75], v[136:139], v[196:199], 0
	v_mfma_f32_16x16x32_bf16 v[68:71], v[128:131], v[204:207], 0
	v_mfma_f32_16x16x32_bf16 v[64:67], v[136:139], v[204:207], 0
	s_setprio 0
	s_setprio 1
	v_mfma_f32_16x16x32_bf16 v[92:95], v[132:135], v[180:183], v[92:95]
	v_mfma_f32_16x16x32_bf16 v[88:91], v[140:143], v[180:183], v[88:91]
	v_mfma_f32_16x16x32_bf16 v[84:87], v[132:135], v[192:195], v[84:87]
	v_mfma_f32_16x16x32_bf16 v[80:83], v[140:143], v[192:195], v[80:83]
	v_mfma_f32_16x16x32_bf16 v[76:79], v[132:135], v[200:203], v[76:79]
	v_mfma_f32_16x16x32_bf16 v[72:75], v[140:143], v[200:203], v[72:75]
	v_mfma_f32_16x16x32_bf16 v[68:71], v[132:135], v[208:211], v[68:71]
	v_mfma_f32_16x16x32_bf16 v[64:67], v[140:143], v[208:211], v[64:67]
	s_setprio 0
	s_setprio 1
	v_mfma_f32_16x16x32_bf16 v[28:31], v[144:147], v[172:175], 0
	v_mfma_f32_16x16x32_bf16 v[24:27], v[164:167], v[172:175], 0
	v_mfma_f32_16x16x32_bf16 v[20:23], v[144:147], v[188:191], 0
	v_mfma_f32_16x16x32_bf16 v[16:19], v[164:167], v[188:191], 0
	v_mfma_f32_16x16x32_bf16 v[12:15], v[144:147], v[196:199], 0
	v_mfma_f32_16x16x32_bf16 v[8:11], v[164:167], v[196:199], 0
	v_mfma_f32_16x16x32_bf16 v[4:7], v[144:147], v[204:207], 0
	v_mfma_f32_16x16x32_bf16 v[0:3], v[164:167], v[204:207], 0
	s_setprio 0
	s_setprio 1
	v_mfma_f32_16x16x32_bf16 v[28:31], v[148:151], v[180:183], v[28:31]
	v_mfma_f32_16x16x32_bf16 v[24:27], v[168:171], v[180:183], v[24:27]
	v_mfma_f32_16x16x32_bf16 v[20:23], v[148:151], v[192:195], v[20:23]
	v_mfma_f32_16x16x32_bf16 v[16:19], v[168:171], v[192:195], v[16:19]
	v_mfma_f32_16x16x32_bf16 v[12:15], v[148:151], v[200:203], v[12:15]
	v_mfma_f32_16x16x32_bf16 v[8:11], v[168:171], v[200:203], v[8:11]
	v_mfma_f32_16x16x32_bf16 v[4:7], v[148:151], v[208:211], v[4:7]
	v_mfma_f32_16x16x32_bf16 v[0:3], v[168:171], v[208:211], v[0:3]
	s_setprio 0
	s_barrier
	s_add_i32 s84, 0, 0x18000
	s_add_i32 s85, 0, 0x1c000
	v_add_u32_e32 v140, s84, v176
	v_add_u32_e32 v168, s85, v176
	ds_read_b128 v[128:131], v140
	ds_read_b128 v[132:135], v140 offset:1024
	ds_read_b128 v[136:139], v140 offset:2048
	ds_read_b128 v[140:143], v140 offset:3072
	ds_read_b128 v[144:147], v168
	ds_read_b128 v[148:151], v168 offset:1024
	ds_read_b128 v[164:167], v168 offset:2048
	ds_read_b128 v[168:171], v168 offset:3072
	s_add_u32 s46, s46, 0x40000
	s_addc_u32 s47, s47, 0
	s_mov_b32 m0, s59
	v_lshl_add_u64 v[216:217], s[46:47], 0, v[152:153]
	ds_read_b128 v[172:175], v179 offset:32768
	ds_read_b128 v[180:183], v179 offset:33792
	ds_read_b128 v[188:191], v179 offset:34816
	ds_read_b128 v[192:195], v179 offset:35840
	ds_read_b128 v[196:199], v179 offset:36864
	ds_read_b128 v[200:203], v179 offset:37888
	ds_read_b128 v[204:207], v179 offset:38912
	ds_read_b128 v[208:211], v179 offset:39936
	global_load_lds_dwordx4 v[216:217], off
	v_lshl_add_u64 v[216:217], s[46:47], 0, v[156:157]
	s_mov_b32 m0, s72
	s_nop 0
	global_load_lds_dwordx4 v[216:217], off
	s_waitcnt vmcnt(8)
	s_waitcnt lgkmcnt(0)
	s_barrier
	s_setprio 1
	s_waitcnt lgkmcnt(0)
	v_mfma_f32_16x16x32_bf16 v[124:127], v[128:131], v[172:175], v[124:127]
	v_mfma_f32_16x16x32_bf16 v[120:123], v[136:139], v[172:175], v[120:123]
	v_mfma_f32_16x16x32_bf16 v[116:119], v[128:131], v[188:191], v[116:119]
	v_mfma_f32_16x16x32_bf16 v[112:115], v[136:139], v[188:191], v[112:115]
	v_mfma_f32_16x16x32_bf16 v[108:111], v[128:131], v[196:199], v[108:111]
	v_mfma_f32_16x16x32_bf16 v[104:107], v[136:139], v[196:199], v[104:107]
	v_mfma_f32_16x16x32_bf16 v[100:103], v[128:131], v[204:207], v[100:103]
	v_mfma_f32_16x16x32_bf16 v[96:99], v[136:139], v[204:207], v[96:99]
	s_setprio 0
	s_setprio 1
	v_mfma_f32_16x16x32_bf16 v[124:127], v[132:135], v[180:183], v[124:127]
	v_mfma_f32_16x16x32_bf16 v[120:123], v[140:143], v[180:183], v[120:123]
	v_mfma_f32_16x16x32_bf16 v[116:119], v[132:135], v[192:195], v[116:119]
	v_mfma_f32_16x16x32_bf16 v[112:115], v[140:143], v[192:195], v[112:115]
	v_mfma_f32_16x16x32_bf16 v[108:111], v[132:135], v[200:203], v[108:111]
	v_mfma_f32_16x16x32_bf16 v[104:107], v[140:143], v[200:203], v[104:107]
	v_mfma_f32_16x16x32_bf16 v[100:103], v[132:135], v[208:211], v[100:103]
	v_mfma_f32_16x16x32_bf16 v[96:99], v[140:143], v[208:211], v[96:99]
	s_setprio 0
	s_setprio 1
	v_mfma_f32_16x16x32_bf16 v[60:63], v[144:147], v[172:175], v[60:63]
	v_mfma_f32_16x16x32_bf16 v[56:59], v[164:167], v[172:175], v[56:59]
	v_mfma_f32_16x16x32_bf16 v[52:55], v[144:147], v[188:191], v[52:55]
	v_mfma_f32_16x16x32_bf16 v[48:51], v[164:167], v[188:191], v[48:51]
	v_mfma_f32_16x16x32_bf16 v[44:47], v[144:147], v[196:199], v[44:47]
	v_mfma_f32_16x16x32_bf16 v[40:43], v[164:167], v[196:199], v[40:43]
	v_mfma_f32_16x16x32_bf16 v[36:39], v[144:147], v[204:207], v[36:39]
	v_mfma_f32_16x16x32_bf16 v[32:35], v[164:167], v[204:207], v[32:35]
	s_setprio 0
	s_setprio 1
	v_mfma_f32_16x16x32_bf16 v[60:63], v[148:151], v[180:183], v[60:63]
	v_mfma_f32_16x16x32_bf16 v[56:59], v[168:171], v[180:183], v[56:59]
	v_mfma_f32_16x16x32_bf16 v[52:55], v[148:151], v[192:195], v[52:55]
	v_mfma_f32_16x16x32_bf16 v[48:51], v[168:171], v[192:195], v[48:51]
	v_mfma_f32_16x16x32_bf16 v[44:47], v[148:151], v[200:203], v[44:47]
	v_mfma_f32_16x16x32_bf16 v[40:43], v[168:171], v[200:203], v[40:43]
	v_mfma_f32_16x16x32_bf16 v[36:39], v[148:151], v[208:211], v[36:39]
	v_mfma_f32_16x16x32_bf16 v[32:35], v[168:171], v[208:211], v[32:35]
	s_setprio 0
	s_barrier
; #define G_STAGE(bufoff, gbase, voff) do { _Pragma("unroll") for (int _i = 0; _i < 2; ++_i) \
;         __builtin_amdgcn_global_load_lds((const unsigned*)((const char*)(gbase) + voff[_i]), (LAS unsigned*)(lds + (bufoff) + ldsw + _i * 8192), 16, 0, 0); } while (0)
; #define G_LDA(dst, b, h) do { _Pragma("unroll") for (int m = 0; m < 4; ++m) _Pragma("unroll") for (int k = 0; k < 2; ++k) dst[m][k] = *(const LAS bf16x8*)(lds + G_SA(b, h) + aoff + m * 2048 + k * 1024); } while (0)
; #define G_LDB(dst, b, h) do { _Pragma("unroll") for (int n = 0; n < 2; ++n) _Pragma("unroll") for (int k = 0; k < 2; ++k) dst[n][k] = *(const LAS bf16x8*)(lds + G_SB(b, h) + boff + n * 2048 + k * 1024); } while (0)
; #define G_MMA(ai, bj, At_, Bt_) do { __builtin_amdgcn_s_setprio(1); _Pragma("unroll") for (int m = 0; m < 4; ++m) _Pragma("unroll") for (int n = 0; n < 2; ++n) _Pragma("unroll") for (int k = 0; k < 2; ++k) \
;         acc[ai][bj][m][n] = __builtin_amdgcn_mfma_f32_16x16x32_bf16(Bt_[n][k], At_[m][k], acc[ai][bj][m][n], 0, 0, 0); __builtin_amdgcn_s_setprio(0); } while (0)
; #define WAIT_V(n) asm volatile("s_waitcnt vmcnt(" #n ")" ::: "memory")
; #define WAIT_L(n) asm volatile("s_waitcnt lgkmcnt(" #n ")" ::: "memory")
; #define BAR __builtin_amdgcn_s_barrier()
; #define SCHED __builtin_amdgcn_sched_barrier(0)
; template <class Get, class Epi>
; DI void gemm_loop(int ntiles, int ld, char* shm, const Get& get, const Epi& epi) {
;     ...
;         for (int t = 0; t < nt; t += 2) {
;             const bool last = (t == nt - 2);
;             const char* a1 = cA + (size_t)(t + 1) * kstep;
;             const char* a2 = last ? nA : cA + (size_t)(t + 2) * kstep; const char* b2 = last ? nB : cB + (size_t)(t + 2) * kstep;
;             const char* a3 = a2 + kstep; const char* b3 = b2 + kstep;
;             G_LDB(B0, 0, 0); G_LDB(B1, 0, 1); SCHED; G_LDA(At, 0, 0); G_STAGE(G_SA(1, 1), a1 + hstep, voffA);
;     ...
;             G_LDA(At, 1, 1); G_STAGE(G_SB(1, 0), b3, voffB); G_STAGE(G_SB(1, 1), b3 + hstep, voffB); G_STAGE(G_SA(1, 0), a3, voffA);
;             WAIT_V(8); WAIT_L(0); BAR; G_MMA(1, 0, At, B0); G_MMA(1, 1, At, B1); BAR; SCHED;
;         }
	s_add_i32 s46, s84, s56
	v_lshl_add_u64 v[184:185], v[184:185], 0, s[10:11]
	s_mov_b32 m0, s46
	ds_read_b128 v[172:175], v179 offset:49152
	ds_read_b128 v[180:183], v179 offset:50176
	ds_read_b128 v[188:191], v179 offset:51200
	ds_read_b128 v[192:195], v179 offset:52224
	ds_read_b128 v[196:199], v179 offset:53248
	ds_read_b128 v[200:203], v179 offset:54272
	ds_read_b128 v[204:207], v179 offset:55296
	ds_read_b128 v[208:211], v179 offset:56320
	global_load_lds_dwordx4 v[184:185], off
	s_add_i32 m0, s46, 0x2000
	s_add_u32 s14, s14, 0x40080
	v_lshl_add_u64 v[184:185], v[186:187], 0, s[10:11]
	s_addc_u32 s15, s15, 0
	s_add_i32 s46, s85, s56
	global_load_lds_dwordx4 v[184:185], off
	v_lshl_add_u64 v[184:185], s[14:15], 0, v[154:155]
	s_mov_b32 m0, s46
	s_nop 0
	global_load_lds_dwordx4 v[184:185], off
	v_lshl_add_u64 v[184:185], s[14:15], 0, v[158:159]
	s_add_i32 m0, s46, 0x2000
	s_nop 0
	global_load_lds_dwordx4 v[184:185], off
	v_lshl_add_u64 v[184:185], v[212:213], 0, s[10:11]
	s_mov_b32 m0, s75
	s_nop 0
	global_load_lds_dwordx4 v[184:185], off
	v_lshl_add_u64 v[184:185], v[214:215], 0, s[10:11]
	s_mov_b32 m0, s76
	s_nop 0
	global_load_lds_dwordx4 v[184:185], off
	s_waitcnt vmcnt(8)
	s_waitcnt lgkmcnt(0)
	s_barrier
	s_setprio 1
	s_waitcnt lgkmcnt(0)
	v_mfma_f32_16x16x32_bf16 v[92:95], v[128:131], v[172:175], v[92:95]
	v_mfma_f32_16x16x32_bf16 v[88:91], v[136:139], v[172:175], v[88:91]
	v_mfma_f32_16x16x32_bf16 v[84:87], v[128:131], v[188:191], v[84:87]
	v_mfma_f32_16x16x32_bf16 v[80:83], v[136:139], v[188:191], v[80:83]
	v_mfma_f32_16x16x32_bf16 v[76:79], v[128:131], v[196:199], v[76:79]
	v_mfma_f32_16x16x32_bf16 v[72:75], v[136:139], v[196:199], v[72:75]
	v_mfma_f32_16x16x32_bf16 v[68:71], v[128:131], v[204:207], v[68:71]
	v_mfma_f32_16x16x32_bf16 v[64:67], v[136:139], v[204:207], v[64:67]
	s_setprio 0
	s_setprio 1
	v_mfma_f32_16x16x32_bf16 v[92:95], v[132:135], v[180:183], v[92:95]
	v_mfma_f32_16x16x32_bf16 v[88:91], v[140:143], v[180:183], v[88:91]
	v_mfma_f32_16x16x32_bf16 v[84:87], v[132:135], v[192:195], v[84:87]
	v_mfma_f32_16x16x32_bf16 v[80:83], v[140:143], v[192:195], v[80:83]
	v_mfma_f32_16x16x32_bf16 v[76:79], v[132:135], v[200:203], v[76:79]
	v_mfma_f32_16x16x32_bf16 v[72:75], v[140:143], v[200:203], v[72:75]
	v_mfma_f32_16x16x32_bf16 v[68:71], v[132:135], v[208:211], v[68:71]
	v_mfma_f32_16x16x32_bf16 v[64:67], v[140:143], v[208:211], v[64:67]
	s_setprio 0
	s_setprio 1
	v_mfma_f32_16x16x32_bf16 v[28:31], v[144:147], v[172:175], v[28:31]
	v_mfma_f32_16x16x32_bf16 v[24:27], v[164:167], v[172:175], v[24:27]
	v_mfma_f32_16x16x32_bf16 v[20:23], v[144:147], v[188:191], v[20:23]
	v_mfma_f32_16x16x32_bf16 v[16:19], v[164:167], v[188:191], v[16:19]
	v_mfma_f32_16x16x32_bf16 v[12:15], v[144:147], v[196:199], v[12:15]
	v_mfma_f32_16x16x32_bf16 v[8:11], v[164:167], v[196:199], v[8:11]
	v_mfma_f32_16x16x32_bf16 v[4:7], v[144:147], v[204:207], v[4:7]
	v_mfma_f32_16x16x32_bf16 v[0:3], v[164:167], v[204:207], v[0:3]
	s_setprio 0
	s_setprio 1
	v_mfma_f32_16x16x32_bf16 v[28:31], v[148:151], v[180:183], v[28:31]
	v_mfma_f32_16x16x32_bf16 v[24:27], v[168:171], v[180:183], v[24:27]
	v_mfma_f32_16x16x32_bf16 v[20:23], v[148:151], v[192:195], v[20:23]
	v_mfma_f32_16x16x32_bf16 v[16:19], v[168:171], v[192:195], v[16:19]
	v_mfma_f32_16x16x32_bf16 v[12:15], v[148:151], v[200:203], v[12:15]
	v_mfma_f32_16x16x32_bf16 v[8:11], v[168:171], v[200:203], v[8:11]
	v_mfma_f32_16x16x32_bf16 v[4:7], v[148:151], v[208:211], v[4:7]
	v_mfma_f32_16x16x32_bf16 v[0:3], v[168:171], v[208:211], v[0:3]
	s_setprio 0
	s_barrier
	s_add_u32 s44, s44, 0x100
	s_addc_u32 s45, s45, 0
	s_add_u32 s55, s55, 0x100
	s_addc_u32 s82, s82, 0
	s_cmp_ge_u32 s83, s51
	s_mov_b32 s14, s83
	s_cbranch_scc0 .LBB0_528
	s_branch .Lpost_528
.LBB0_528:
	ds_read_b128 v[128:131], v177
	ds_read_b128 v[132:135], v177 offset:1024
	ds_read_b128 v[136:139], v177 offset:2048
	ds_read_b128 v[140:143], v177 offset:3072
	ds_read_b128 v[144:147], v178
	ds_read_b128 v[148:151], v178 offset:1024
	ds_read_b128 v[164:167], v178 offset:2048
	ds_read_b128 v[168:171], v178 offset:3072
	s_add_i32 s83, s14, 2
	s_add_u32 s15, s44, 0xfffc0080
	s_addc_u32 s46, s45, -1
	s_cmp_eq_u32 s54, s14
	s_cselect_b32 s14, s43, s55
	s_cselect_b32 s47, s3, s46
	s_cselect_b32 s46, s35, s15
	s_cselect_b32 s15, s37, s82
	v_lshl_add_u64 v[184:185], s[44:45], 0, v[160:161]
	s_add_i32 m0, s57, 0xc000
	ds_read_b128 v[172:175], v179
	ds_read_b128 v[180:183], v179 offset:1024
	ds_read_b128 v[188:191], v179 offset:2048
	ds_read_b128 v[192:195], v179 offset:3072
	ds_read_b128 v[196:199], v179 offset:4096
	ds_read_b128 v[200:203], v179 offset:5120
	ds_read_b128 v[204:207], v179 offset:6144
	ds_read_b128 v[208:211], v179 offset:7168
	global_load_lds_dwordx4 v[184:185], off
	v_lshl_add_u64 v[184:185], s[44:45], 0, v[162:163]
	s_add_i32 m0, s57, 0xe000
	s_nop 0
	global_load_lds_dwordx4 v[184:185], off
	s_waitcnt vmcnt(8)
	s_waitcnt lgkmcnt(0)
	s_barrier
; #define G_STAGE(bufoff, gbase, voff) do { _Pragma("unroll") for (int _i = 0; _i < 2; ++_i) \
;         __builtin_amdgcn_global_load_lds((const unsigned*)((const char*)(gbase) + voff[_i]), (LAS unsigned*)(lds + (bufoff) + ldsw + _i * 8192), 16, 0, 0); } while (0)
; #define G_LDA(dst, b, h) do { _Pragma("unroll") for (int m = 0; m < 4; ++m) _Pragma("unroll") for (int k = 0; k < 2; ++k) dst[m][k] = *(const LAS bf16x8*)(lds + G_SA(b, h) + aoff + m * 2048 + k * 1024); } while (0)
; #define G_LDB(dst, b, h) do { _Pragma("unroll") for (int n = 0; n < 2; ++n) _Pragma("unroll") for (int k = 0; k < 2; ++k) dst[n][k] = *(const LAS bf16x8*)(lds + G_SB(b, h) + boff + n * 2048 + k * 1024); } while (0)
; #define G_MMA(ai, bj, At_, Bt_) do { __builtin_amdgcn_s_setprio(1); _Pragma("unroll") for (int m = 0; m < 4; ++m) _Pragma("unroll") for (int n = 0; n < 2; ++n) _Pragma("unroll") for (int k = 0; k < 2; ++k) \
;         acc[ai][bj][m][n] = __builtin_amdgcn_mfma_f32_16x16x32_bf16(Bt_[n][k], At_[m][k], acc[ai][bj][m][n], 0, 0, 0); __builtin_amdgcn_s_setprio(0); } while (0)
; #define WAIT_V(n) asm volatile("s_waitcnt vmcnt(" #n ")" ::: "memory")
; #define WAIT_L(n) asm volatile("s_waitcnt lgkmcnt(" #n ")" ::: "memory")
; #define BAR __builtin_amdgcn_s_barrier()
; #define SCHED __builtin_amdgcn_sched_barrier(0)
; template <class Get, class Epi>
; DI void gemm_loop(int ntiles, int ld, char* shm, const Get& get, const Epi& epi) {
;     ...
;             WAIT_V(8); WAIT_L(0); BAR; G_MMA(0, 0, At, B0); G_MMA(0, 1, At, B1); BAR; SCHED;
;             G_LDA(At, 0, 1); G_STAGE(G_SB(0, 0), b2, voffB); G_STAGE(G_SB(0, 1), b2 + hstep, voffB); G_STAGE(G_SA(0, 0), a2, voffA);
;             WAIT_V(8); WAIT_L(0); BAR; G_MMA(1, 0, At, B0); G_MMA(1, 1, At, B1); BAR; SCHED;
;             G_LDB(B0, 1, 0); G_LDB(B1, 1, 1); SCHED; G_LDA(At, 1, 0); G_STAGE(G_SA(0, 1), a2 + hstep, voffA);
;             WAIT_V(8); WAIT_L(0); BAR; G_MMA(0, 0, At, B0); G_MMA(0, 1, At, B1); BAR; SCHED;
	s_setprio 1
	s_waitcnt lgkmcnt(0)
	v_mfma_f32_16x16x32_bf16 v[124:127], v[128:131], v[172:175], v[124:127]
	v_mfma_f32_16x16x32_bf16 v[120:123], v[136:139], v[172:175], v[120:123]
	v_mfma_f32_16x16x32_bf16 v[116:119], v[128:131], v[188:191], v[116:119]
	v_mfma_f32_16x16x32_bf16 v[112:115], v[136:139], v[188:191], v[112:115]
	v_mfma_f32_16x16x32_bf16 v[108:111], v[128:131], v[196:199], v[108:111]
	v_mfma_f32_16x16x32_bf16 v[104:107], v[136:139], v[196:199], v[104:107]
	v_mfma_f32_16x16x32_bf16 v[100:103], v[128:131], v[204:207], v[100:103]
	v_mfma_f32_16x16x32_bf16 v[96:99], v[136:139], v[204:207], v[96:99]
	s_setprio 0
	s_setprio 1
	v_mfma_f32_16x16x32_bf16 v[124:127], v[132:135], v[180:183], v[124:127]
	v_mfma_f32_16x16x32_bf16 v[120:123], v[140:143], v[180:183], v[120:123]
	v_mfma_f32_16x16x32_bf16 v[116:119], v[132:135], v[192:195], v[116:119]
	v_mfma_f32_16x16x32_bf16 v[112:115], v[140:143], v[192:195], v[112:115]
	v_mfma_f32_16x16x32_bf16 v[108:111], v[132:135], v[200:203], v[108:111]
	v_mfma_f32_16x16x32_bf16 v[104:107], v[140:143], v[200:203], v[104:107]
	v_mfma_f32_16x16x32_bf16 v[100:103], v[132:135], v[208:211], v[100:103]
	v_mfma_f32_16x16x32_bf16 v[96:99], v[140:143], v[208:211], v[96:99]
	s_setprio 0
	s_setprio 1
	v_mfma_f32_16x16x32_bf16 v[60:63], v[144:147], v[172:175], v[60:63]
	v_mfma_f32_16x16x32_bf16 v[56:59], v[164:167], v[172:175], v[56:59]
	v_mfma_f32_16x16x32_bf16 v[52:55], v[144:147], v[188:191], v[52:55]
	v_mfma_f32_16x16x32_bf16 v[48:51], v[164:167], v[188:191], v[48:51]
	v_mfma_f32_16x16x32_bf16 v[44:47], v[144:147], v[196:199], v[44:47]
	v_mfma_f32_16x16x32_bf16 v[40:43], v[164:167], v[196:199], v[40:43]
	v_mfma_f32_16x16x32_bf16 v[36:39], v[144:147], v[204:207], v[36:39]
	v_mfma_f32_16x16x32_bf16 v[32:35], v[164:167], v[204:207], v[32:35]
	s_setprio 0
	s_setprio 1
	v_mfma_f32_16x16x32_bf16 v[60:63], v[148:151], v[180:183], v[60:63]
	v_mfma_f32_16x16x32_bf16 v[56:59], v[168:171], v[180:183], v[56:59]
	v_mfma_f32_16x16x32_bf16 v[52:55], v[148:151], v[192:195], v[52:55]
	v_mfma_f32_16x16x32_bf16 v[48:51], v[168:171], v[192:195], v[48:51]
	v_mfma_f32_16x16x32_bf16 v[44:47], v[148:151], v[200:203], v[44:47]
	v_mfma_f32_16x16x32_bf16 v[40:43], v[168:171], v[200:203], v[40:43]
	v_mfma_f32_16x16x32_bf16 v[36:39], v[148:151], v[208:211], v[36:39]
	v_mfma_f32_16x16x32_bf16 v[32:35], v[168:171], v[208:211], v[32:35]
	s_setprio 0
	s_barrier
	s_add_i32 s84, s78, s56
	v_lshl_add_u64 v[184:185], s[14:15], 0, v[154:155]
	s_mov_b32 m0, s84
	ds_read_b128 v[172:175], v179 offset:16384
	ds_read_b128 v[180:183], v179 offset:17408
	ds_read_b128 v[188:191], v179 offset:18432
	ds_read_b128 v[192:195], v179 offset:19456
	ds_read_b128 v[196:199], v179 offset:20480
	ds_read_b128 v[200:203], v179 offset:21504
	ds_read_b128 v[204:207], v179 offset:22528
	ds_read_b128 v[208:211], v179 offset:23552
	global_load_lds_dwordx4 v[184:185], off
	s_add_i32 m0, s84, 0x2000
	s_add_u32 s84, s14, 0x40000
	v_lshl_add_u64 v[186:187], s[14:15], 0, v[158:159]
	s_addc_u32 s85, s15, 0
	s_add_i32 s86, s79, s56
	global_load_lds_dwordx4 v[186:187], off
	v_lshl_add_u64 v[212:213], s[84:85], 0, v[154:155]
	s_mov_b32 m0, s86
	v_lshl_add_u64 v[214:215], s[46:47], 0, v[156:157]
	global_load_lds_dwordx4 v[212:213], off
	v_lshl_add_u64 v[212:213], s[84:85], 0, v[158:159]
	s_add_i32 m0, s86, 0x2000
	s_nop 0
	global_load_lds_dwordx4 v[212:213], off
	v_lshl_add_u64 v[212:213], s[46:47], 0, v[152:153]
	s_mov_b32 m0, s57
	s_nop 0
	global_load_lds_dwordx4 v[212:213], off
	s_mov_b32 m0, s58
	s_nop 0
	global_load_lds_dwordx4 v[214:215], off
	s_waitcnt vmcnt(8)
	s_waitcnt lgkmcnt(0)
	s_barrier
	s_setprio 1
	s_waitcnt lgkmcnt(0)
	v_mfma_f32_16x16x32_bf16 v[92:95], v[128:131], v[172:175], v[92:95]
	v_mfma_f32_16x16x32_bf16 v[88:91], v[136:139], v[172:175], v[88:91]
	v_mfma_f32_16x16x32_bf16 v[84:87], v[128:131], v[188:191], v[84:87]
	v_mfma_f32_16x16x32_bf16 v[80:83], v[136:139], v[188:191], v[80:83]
	v_mfma_f32_16x16x32_bf16 v[76:79], v[128:131], v[196:199], v[76:79]
	v_mfma_f32_16x16x32_bf16 v[72:75], v[136:139], v[196:199], v[72:75]
	v_mfma_f32_16x16x32_bf16 v[68:71], v[128:131], v[204:207], v[68:71]
	v_mfma_f32_16x16x32_bf16 v[64:67], v[136:139], v[204:207], v[64:67]
	s_setprio 0
	s_setprio 1
	v_mfma_f32_16x16x32_bf16 v[92:95], v[132:135], v[180:183], v[92:95]
	v_mfma_f32_16x16x32_bf16 v[88:91], v[140:143], v[180:183], v[88:91]
	v_mfma_f32_16x16x32_bf16 v[84:87], v[132:135], v[192:195], v[84:87]
	v_mfma_f32_16x16x32_bf16 v[80:83], v[140:143], v[192:195], v[80:83]
	v_mfma_f32_16x16x32_bf16 v[76:79], v[132:135], v[200:203], v[76:79]
	v_mfma_f32_16x16x32_bf16 v[72:75], v[140:143], v[200:203], v[72:75]
	v_mfma_f32_16x16x32_bf16 v[68:71], v[132:135], v[208:211], v[68:71]
	v_mfma_f32_16x16x32_bf16 v[64:67], v[140:143], v[208:211], v[64:67]
	s_setprio 0
	s_setprio 1
	v_mfma_f32_16x16x32_bf16 v[28:31], v[144:147], v[172:175], v[28:31]
	v_mfma_f32_16x16x32_bf16 v[24:27], v[164:167], v[172:175], v[24:27]
	v_mfma_f32_16x16x32_bf16 v[20:23], v[144:147], v[188:191], v[20:23]
	v_mfma_f32_16x16x32_bf16 v[16:19], v[164:167], v[188:191], v[16:19]
	v_mfma_f32_16x16x32_bf16 v[12:15], v[144:147], v[196:199], v[12:15]
	v_mfma_f32_16x16x32_bf16 v[8:11], v[164:167], v[196:199], v[8:11]
	v_mfma_f32_16x16x32_bf16 v[4:7], v[144:147], v[204:207], v[4:7]
	v_mfma_f32_16x16x32_bf16 v[0:3], v[164:167], v[204:207], v[0:3]
	s_setprio 0
	s_setprio 1
	v_mfma_f32_16x16x32_bf16 v[28:31], v[148:151], v[180:183], v[28:31]
	v_mfma_f32_16x16x32_bf16 v[24:27], v[168:171], v[180:183], v[24:27]
	v_mfma_f32_16x16x32_bf16 v[20:23], v[148:151], v[192:195], v[20:23]
	v_mfma_f32_16x16x32_bf16 v[16:19], v[168:171], v[192:195], v[16:19]
	v_mfma_f32_16x16x32_bf16 v[12:15], v[148:151], v[200:203], v[12:15]
	v_mfma_f32_16x16x32_bf16 v[8:11], v[168:171], v[200:203], v[8:11]
	v_mfma_f32_16x16x32_bf16 v[4:7], v[148:151], v[208:211], v[4:7]
	v_mfma_f32_16x16x32_bf16 v[0:3], v[168:171], v[208:211], v[0:3]
	s_setprio 0
	s_barrier
; #define G_STAGE(bufoff, gbase, voff) do { _Pragma("unroll") for (int _i = 0; _i < 2; ++_i) \
;         __builtin_amdgcn_global_load_lds((const unsigned*)((const char*)(gbase) + voff[_i]), (LAS unsigned*)(lds + (bufoff) + ldsw + _i * 8192), 16, 0, 0); } while (0)
; #define G_LDA(dst, b, h) do { _Pragma("unroll") for (int m = 0; m < 4; ++m) _Pragma("unroll") for (int k = 0; k < 2; ++k) dst[m][k] = *(const LAS bf16x8*)(lds + G_SA(b, h) + aoff + m * 2048 + k * 1024); } while (0)
; #define G_LDB(dst, b, h) do { _Pragma("unroll") for (int n = 0; n < 2; ++n) _Pragma("unroll") for (int k = 0; k < 2; ++k) dst[n][k] = *(const LAS bf16x8*)(lds + G_SB(b, h) + boff + n * 2048 + k * 1024); } while (0)
; #define G_MMA(ai, bj, At_, Bt_) do { __builtin_amdgcn_s_setprio(1); _Pragma("unroll") for (int m = 0; m < 4; ++m) _Pragma("unroll") for (int n = 0; n < 2; ++n) _Pragma("unroll") for (int k = 0; k < 2; ++k) \
;         acc[ai][bj][m][n] = __builtin_amdgcn_mfma_f32_16x16x32_bf16(Bt_[n][k], At_[m][k], acc[ai][bj][m][n], 0, 0, 0); __builtin_amdgcn_s_setprio(0); } while (0)
; #define WAIT_V(n) asm volatile("s_waitcnt vmcnt(" #n ")" ::: "memory")
; #define WAIT_L(n) asm volatile("s_waitcnt lgkmcnt(" #n ")" ::: "memory")
; #define BAR __builtin_amdgcn_s_barrier()
; #define SCHED __builtin_amdgcn_sched_barrier(0)
; template <class Get, class Epi>
; DI void gemm_loop(int ntiles, int ld, char* shm, const Get& get, const Epi& epi) {
;     ...
;             G_LDB(B0, 1, 0); G_LDB(B1, 1, 1); SCHED; G_LDA(At, 1, 0); G_STAGE(G_SA(0, 1), a2 + hstep, voffA);
;             WAIT_V(8); WAIT_L(0); BAR; G_MMA(0, 0, At, B0); G_MMA(0, 1, At, B1); BAR; SCHED;
	s_add_i32 s84, 0, 0x18000
	s_add_i32 s85, 0, 0x1c000
	v_add_u32_e32 v140, s84, v176
	v_add_u32_e32 v168, s85, v176
	ds_read_b128 v[128:131], v140
	ds_read_b128 v[132:135], v140 offset:1024
	ds_read_b128 v[136:139], v140 offset:2048
	ds_read_b128 v[140:143], v140 offset:3072
	ds_read_b128 v[144:147], v168
	ds_read_b128 v[148:151], v168 offset:1024
	ds_read_b128 v[164:167], v168 offset:2048
	ds_read_b128 v[168:171], v168 offset:3072
	s_add_u32 s46, s46, 0x40000
	s_addc_u32 s47, s47, 0
	s_mov_b32 m0, s59
	v_lshl_add_u64 v[216:217], s[46:47], 0, v[152:153]
	ds_read_b128 v[172:175], v179 offset:32768
	ds_read_b128 v[180:183], v179 offset:33792
	ds_read_b128 v[188:191], v179 offset:34816
	ds_read_b128 v[192:195], v179 offset:35840
	ds_read_b128 v[196:199], v179 offset:36864
	ds_read_b128 v[200:203], v179 offset:37888
	ds_read_b128 v[204:207], v179 offset:38912
	ds_read_b128 v[208:211], v179 offset:39936
	global_load_lds_dwordx4 v[216:217], off
	v_lshl_add_u64 v[216:217], s[46:47], 0, v[156:157]
	s_mov_b32 m0, s72
	s_nop 0
	global_load_lds_dwordx4 v[216:217], off
	s_waitcnt vmcnt(8)
	s_waitcnt lgkmcnt(0)
	s_barrier
	s_setprio 1
	s_waitcnt lgkmcnt(0)
	v_mfma_f32_16x16x32_bf16 v[124:127], v[128:131], v[172:175], v[124:127]
	v_mfma_f32_16x16x32_bf16 v[120:123], v[136:139], v[172:175], v[120:123]
	v_mfma_f32_16x16x32_bf16 v[116:119], v[128:131], v[188:191], v[116:119]
	v_mfma_f32_16x16x32_bf16 v[112:115], v[136:139], v[188:191], v[112:115]
	v_mfma_f32_16x16x32_bf16 v[108:111], v[128:131], v[196:199], v[108:111]
	v_mfma_f32_16x16x32_bf16 v[104:107], v[136:139], v[196:199], v[104:107]
	v_mfma_f32_16x16x32_bf16 v[100:103], v[128:131], v[204:207], v[100:103]
	v_mfma_f32_16x16x32_bf16 v[96:99], v[136:139], v[204:207], v[96:99]
	s_setprio 0
	s_setprio 1
	v_mfma_f32_16x16x32_bf16 v[124:127], v[132:135], v[180:183], v[124:127]
	v_mfma_f32_16x16x32_bf16 v[120:123], v[140:143], v[180:183], v[120:123]
	v_mfma_f32_16x16x32_bf16 v[116:119], v[132:135], v[192:195], v[116:119]
	v_mfma_f32_16x16x32_bf16 v[112:115], v[140:143], v[192:195], v[112:115]
	v_mfma_f32_16x16x32_bf16 v[108:111], v[132:135], v[200:203], v[108:111]
	v_mfma_f32_16x16x32_bf16 v[104:107], v[140:143], v[200:203], v[104:107]
	v_mfma_f32_16x16x32_bf16 v[100:103], v[132:135], v[208:211], v[100:103]
	v_mfma_f32_16x16x32_bf16 v[96:99], v[140:143], v[208:211], v[96:99]
	s_setprio 0
	s_setprio 1
	v_mfma_f32_16x16x32_bf16 v[60:63], v[144:147], v[172:175], v[60:63]
	v_mfma_f32_16x16x32_bf16 v[56:59], v[164:167], v[172:175], v[56:59]
	v_mfma_f32_16x16x32_bf16 v[52:55], v[144:147], v[188:191], v[52:55]
	v_mfma_f32_16x16x32_bf16 v[48:51], v[164:167], v[188:191], v[48:51]
	v_mfma_f32_16x16x32_bf16 v[44:47], v[144:147], v[196:199], v[44:47]
	v_mfma_f32_16x16x32_bf16 v[40:43], v[164:167], v[196:199], v[40:43]
	v_mfma_f32_16x16x32_bf16 v[36:39], v[144:147], v[204:207], v[36:39]
	v_mfma_f32_16x16x32_bf16 v[32:35], v[164:167], v[204:207], v[32:35]
	s_setprio 0
	s_setprio 1
	v_mfma_f32_16x16x32_bf16 v[60:63], v[148:151], v[180:183], v[60:63]
	v_mfma_f32_16x16x32_bf16 v[56:59], v[168:171], v[180:183], v[56:59]
	v_mfma_f32_16x16x32_bf16 v[52:55], v[148:151], v[192:195], v[52:55]
	v_mfma_f32_16x16x32_bf16 v[48:51], v[168:171], v[192:195], v[48:51]
	v_mfma_f32_16x16x32_bf16 v[44:47], v[148:151], v[200:203], v[44:47]
	v_mfma_f32_16x16x32_bf16 v[40:43], v[168:171], v[200:203], v[40:43]
	v_mfma_f32_16x16x32_bf16 v[36:39], v[148:151], v[208:211], v[36:39]
	v_mfma_f32_16x16x32_bf16 v[32:35], v[168:171], v[208:211], v[32:35]
	s_setprio 0
	s_barrier
; #define G_STAGE(bufoff, gbase, voff) do { _Pragma("unroll") for (int _i = 0; _i < 2; ++_i) \
;         __builtin_amdgcn_global_load_lds((const unsigned*)((const char*)(gbase) + voff[_i]), (LAS unsigned*)(lds + (bufoff) + ldsw + _i * 8192), 16, 0, 0); } while (0)
; #define G_LDA(dst, b, h) do { _Pragma("unroll") for (int m = 0; m < 4; ++m) _Pragma("unroll") for (int k = 0; k < 2; ++k) dst[m][k] = *(const LAS bf16x8*)(lds + G_SA(b, h) + aoff + m * 2048 + k * 1024); } while (0)
; #define G_MMA(ai, bj, At_, Bt_) do { __builtin_amdgcn_s_setprio(1); _Pragma("unroll") for (int m = 0; m < 4; ++m) _Pragma("unroll") for (int n = 0; n < 2; ++n) _Pragma("unroll") for (int k = 0; k < 2; ++k) \
;         acc[ai][bj][m][n] = __builtin_amdgcn_mfma_f32_16x16x32_bf16(Bt_[n][k], At_[m][k], acc[ai][bj][m][n], 0, 0, 0); __builtin_amdgcn_s_setprio(0); } while (0)
; #define WAIT_V(n) asm volatile("s_waitcnt vmcnt(" #n ")" ::: "memory")
; #define WAIT_L(n) asm volatile("s_waitcnt lgkmcnt(" #n ")" ::: "memory")
; #define BAR __builtin_amdgcn_s_barrier()
; #define SCHED __builtin_amdgcn_sched_barrier(0)
; template <class Get, class Epi>
; DI void gemm_loop(int ntiles, int ld, char* shm, const Get& get, const Epi& epi) {
;     ...
;             G_LDA(At, 1, 1); G_STAGE(G_SB(1, 0), b3, voffB); G_STAGE(G_SB(1, 1), b3 + hstep, voffB); G_STAGE(G_SA(1, 0), a3, voffA);
;             WAIT_V(8); WAIT_L(0); BAR; G_MMA(1, 0, At, B0); G_MMA(1, 1, At, B1); BAR; SCHED;
;         }
	s_add_i32 s46, s84, s56
	v_lshl_add_u64 v[184:185], v[184:185], 0, s[10:11]
	s_mov_b32 m0, s46
	ds_read_b128 v[172:175], v179 offset:49152
	ds_read_b128 v[180:183], v179 offset:50176
	ds_read_b128 v[188:191], v179 offset:51200
	ds_read_b128 v[192:195], v179 offset:52224
	ds_read_b128 v[196:199], v179 offset:53248
	ds_read_b128 v[200:203], v179 offset:54272
	ds_read_b128 v[204:207], v179 offset:55296
	ds_read_b128 v[208:211], v179 offset:56320
	global_load_lds_dwordx4 v[184:185], off
	s_add_i32 m0, s46, 0x2000
	s_add_u32 s14, s14, 0x40080
	v_lshl_add_u64 v[184:185], v[186:187], 0, s[10:11]
	s_addc_u32 s15, s15, 0
	s_add_i32 s46, s85, s56
	global_load_lds_dwordx4 v[184:185], off
	v_lshl_add_u64 v[184:185], s[14:15], 0, v[154:155]
	s_mov_b32 m0, s46
	s_nop 0
	global_load_lds_dwordx4 v[184:185], off
	v_lshl_add_u64 v[184:185], s[14:15], 0, v[158:159]
	s_add_i32 m0, s46, 0x2000
	s_nop 0
	global_load_lds_dwordx4 v[184:185], off
	v_lshl_add_u64 v[184:185], v[212:213], 0, s[10:11]
	s_mov_b32 m0, s75
	s_nop 0
	global_load_lds_dwordx4 v[184:185], off
	v_lshl_add_u64 v[184:185], v[214:215], 0, s[10:11]
	s_mov_b32 m0, s76
	s_nop 0
	global_load_lds_dwordx4 v[184:185], off
	s_waitcnt vmcnt(8)
	s_waitcnt lgkmcnt(0)
	s_barrier
	s_setprio 1
	s_waitcnt lgkmcnt(0)
	v_mfma_f32_16x16x32_bf16 v[92:95], v[128:131], v[172:175], v[92:95]
	v_mfma_f32_16x16x32_bf16 v[88:91], v[136:139], v[172:175], v[88:91]
	v_mfma_f32_16x16x32_bf16 v[84:87], v[128:131], v[188:191], v[84:87]
	v_mfma_f32_16x16x32_bf16 v[80:83], v[136:139], v[188:191], v[80:83]
	v_mfma_f32_16x16x32_bf16 v[76:79], v[128:131], v[196:199], v[76:79]
	v_mfma_f32_16x16x32_bf16 v[72:75], v[136:139], v[196:199], v[72:75]
	v_mfma_f32_16x16x32_bf16 v[68:71], v[128:131], v[204:207], v[68:71]
	v_mfma_f32_16x16x32_bf16 v[64:67], v[136:139], v[204:207], v[64:67]
	s_setprio 0
	s_setprio 1
	v_mfma_f32_16x16x32_bf16 v[92:95], v[132:135], v[180:183], v[92:95]
	v_mfma_f32_16x16x32_bf16 v[88:91], v[140:143], v[180:183], v[88:91]
	v_mfma_f32_16x16x32_bf16 v[84:87], v[132:135], v[192:195], v[84:87]
	v_mfma_f32_16x16x32_bf16 v[80:83], v[140:143], v[192:195], v[80:83]
	v_mfma_f32_16x16x32_bf16 v[76:79], v[132:135], v[200:203], v[76:79]
	v_mfma_f32_16x16x32_bf16 v[72:75], v[140:143], v[200:203], v[72:75]
	v_mfma_f32_16x16x32_bf16 v[68:71], v[132:135], v[208:211], v[68:71]
	v_mfma_f32_16x16x32_bf16 v[64:67], v[140:143], v[208:211], v[64:67]
	s_setprio 0
	s_setprio 1
	v_mfma_f32_16x16x32_bf16 v[28:31], v[144:147], v[172:175], v[28:31]
	v_mfma_f32_16x16x32_bf16 v[24:27], v[164:167], v[172:175], v[24:27]
	v_mfma_f32_16x16x32_bf16 v[20:23], v[144:147], v[188:191], v[20:23]
	v_mfma_f32_16x16x32_bf16 v[16:19], v[164:167], v[188:191], v[16:19]
	v_mfma_f32_16x16x32_bf16 v[12:15], v[144:147], v[196:199], v[12:15]
	v_mfma_f32_16x16x32_bf16 v[8:11], v[164:167], v[196:199], v[8:11]
	v_mfma_f32_16x16x32_bf16 v[4:7], v[144:147], v[204:207], v[4:7]
	v_mfma_f32_16x16x32_bf16 v[0:3], v[164:167], v[204:207], v[0:3]
	s_setprio 0
	s_setprio 1
	v_mfma_f32_16x16x32_bf16 v[28:31], v[148:151], v[180:183], v[28:31]
	v_mfma_f32_16x16x32_bf16 v[24:27], v[168:171], v[180:183], v[24:27]
	v_mfma_f32_16x16x32_bf16 v[20:23], v[148:151], v[192:195], v[20:23]
	v_mfma_f32_16x16x32_bf16 v[16:19], v[168:171], v[192:195], v[16:19]
	v_mfma_f32_16x16x32_bf16 v[12:15], v[148:151], v[200:203], v[12:15]
	v_mfma_f32_16x16x32_bf16 v[8:11], v[168:171], v[200:203], v[8:11]
	v_mfma_f32_16x16x32_bf16 v[4:7], v[148:151], v[208:211], v[4:7]
	v_mfma_f32_16x16x32_bf16 v[0:3], v[168:171], v[208:211], v[0:3]
	s_setprio 0
	s_barrier
	s_add_u32 s44, s44, 0x100
	s_addc_u32 s45, s45, 0
	s_add_u32 s55, s55, 0x100
	s_addc_u32 s82, s82, 0
	s_cmp_ge_u32 s83, s51
	s_mov_b32 s14, s83
	s_cbranch_scc0 .LBB0_528

; #define G_STAGE(bufoff, gbase, voff) do { _Pragma("unroll") for (int _i = 0; _i < 2; ++_i) \
;         __builtin_amdgcn_global_load_lds((const unsigned*)((const char*)(gbase) + voff[_i]), (LAS unsigned*)(lds + (bufoff) + ldsw + _i * 8192), 16, 0, 0); } while (0)
; #define G_LDA(dst, b, h) do { _Pragma("unroll") for (int m = 0; m < 4; ++m) _Pragma("unroll") for (int k = 0; k < 2; ++k) dst[m][k] = *(const LAS bf16x8*)(lds + G_SA(b, h) + aoff + m * 2048 + k * 1024); } while (0)
; #define G_MMA(ai, bj, At_, Bt_) do { __builtin_amdgcn_s_setprio(1); _Pragma("unroll") for (int m = 0; m < 4; ++m) _Pragma("unroll") for (int n = 0; n < 2; ++n) _Pragma("unroll") for (int k = 0; k < 2; ++k) \
;         acc[ai][bj][m][n] = __builtin_amdgcn_mfma_f32_16x16x32_bf16(Bt_[n][k], At_[m][k], acc[ai][bj][m][n], 0, 0, 0); __builtin_amdgcn_s_setprio(0); } while (0)
; #define WAIT_V(n) asm volatile("s_waitcnt vmcnt(" #n ")" ::: "memory")
; #define WAIT_L(n) asm volatile("s_waitcnt lgkmcnt(" #n ")" ::: "memory")
; #define BAR __builtin_amdgcn_s_barrier()
; #define SCHED __builtin_amdgcn_sched_barrier(0)
; template <class Get, class Epi>
; DI void gemm_loop(int ntiles, int ld, char* shm, const Get& get, const Epi& epi) {
;     ...
;             WAIT_V(8); WAIT_L(0); BAR; G_MMA(0, 0, At, B0); G_MMA(0, 1, At, B1); BAR; SCHED;
;             G_LDA(At, 0, 1); G_STAGE(G_SB(0, 0), b2, voffB); G_STAGE(G_SB(0, 1), b2 + hstep, voffB); G_STAGE(G_SA(0, 0), a2, voffA);
;             WAIT_V(8); WAIT_L(0); BAR; G_MMA(1, 0, At, B0); G_MMA(1, 1, At, B1); BAR; SCHED;
.Lrj_763_0:
	s_waitcnt lgkmcnt(0)
	s_barrier
	s_setprio 1
	s_waitcnt lgkmcnt(0)
	v_mfma_f32_16x16x32_bf16 v[124:127], v[144:147], v[176:179], 0
	v_mfma_f32_16x16x32_bf16 v[120:123], v[152:155], v[176:179], 0
	v_mfma_f32_16x16x32_bf16 v[108:111], v[144:147], v[188:191], 0
	v_mfma_f32_16x16x32_bf16 v[104:107], v[152:155], v[188:191], 0
	v_mfma_f32_16x16x32_bf16 v[92:95], v[144:147], v[196:199], 0
	v_mfma_f32_16x16x32_bf16 v[88:91], v[152:155], v[196:199], 0
	v_mfma_f32_16x16x32_bf16 v[76:79], v[144:147], v[204:207], 0
	v_mfma_f32_16x16x32_bf16 v[72:75], v[152:155], v[204:207], 0
	s_setprio 0
	s_setprio 1
	v_mfma_f32_16x16x32_bf16 v[124:127], v[148:151], v[180:183], v[124:127]
	v_mfma_f32_16x16x32_bf16 v[120:123], v[156:159], v[180:183], v[120:123]
	v_mfma_f32_16x16x32_bf16 v[108:111], v[148:151], v[192:195], v[108:111]
	v_mfma_f32_16x16x32_bf16 v[104:107], v[156:159], v[192:195], v[104:107]
	v_mfma_f32_16x16x32_bf16 v[92:95], v[148:151], v[200:203], v[92:95]
	v_mfma_f32_16x16x32_bf16 v[88:91], v[156:159], v[200:203], v[88:91]
	v_mfma_f32_16x16x32_bf16 v[76:79], v[148:151], v[208:211], v[76:79]
	v_mfma_f32_16x16x32_bf16 v[72:75], v[156:159], v[208:211], v[72:75]
	s_setprio 0
	s_setprio 1
	v_mfma_f32_16x16x32_bf16 v[116:119], v[160:163], v[176:179], 0
	v_mfma_f32_16x16x32_bf16 v[112:115], v[168:171], v[176:179], 0
	v_mfma_f32_16x16x32_bf16 v[100:103], v[160:163], v[188:191], 0
	v_mfma_f32_16x16x32_bf16 v[96:99], v[168:171], v[188:191], 0
	v_mfma_f32_16x16x32_bf16 v[84:87], v[160:163], v[196:199], 0
	v_mfma_f32_16x16x32_bf16 v[80:83], v[168:171], v[196:199], 0
	v_mfma_f32_16x16x32_bf16 v[68:71], v[160:163], v[204:207], 0
	v_mfma_f32_16x16x32_bf16 v[64:67], v[168:171], v[204:207], 0
	s_setprio 0
	s_setprio 1
	v_mfma_f32_16x16x32_bf16 v[116:119], v[164:167], v[180:183], v[116:119]
	v_mfma_f32_16x16x32_bf16 v[112:115], v[172:175], v[180:183], v[112:115]
	v_mfma_f32_16x16x32_bf16 v[100:103], v[164:167], v[192:195], v[100:103]
	v_mfma_f32_16x16x32_bf16 v[96:99], v[172:175], v[192:195], v[96:99]
	v_mfma_f32_16x16x32_bf16 v[84:87], v[164:167], v[200:203], v[84:87]
	v_mfma_f32_16x16x32_bf16 v[80:83], v[172:175], v[200:203], v[80:83]
	v_mfma_f32_16x16x32_bf16 v[68:71], v[164:167], v[208:211], v[68:71]
	v_mfma_f32_16x16x32_bf16 v[64:67], v[172:175], v[208:211], v[64:67]
	s_setprio 0
	s_barrier
	s_add_i32 s55, s45, s26
	v_lshl_add_u64 v[184:185], s[14:15], 0, v[132:133]
	s_mov_b32 m0, s55
	ds_read_b128 v[176:179], v143 offset:16384
	ds_read_b128 v[180:183], v143 offset:17408
	ds_read_b128 v[188:191], v143 offset:18432
	ds_read_b128 v[192:195], v143 offset:19456
	ds_read_b128 v[196:199], v143 offset:20480
	ds_read_b128 v[200:203], v143 offset:21504
	ds_read_b128 v[204:207], v143 offset:22528
	ds_read_b128 v[208:211], v143 offset:23552
	global_load_lds_dwordx4 v[184:185], off
	s_add_i32 m0, s55, 0x2000
	s_add_u32 s56, s14, 0x40000
	v_lshl_add_u64 v[186:187], s[14:15], 0, v[128:129]
	s_addc_u32 s57, s15, 0
	s_add_i32 s55, s46, s26
	global_load_lds_dwordx4 v[186:187], off
	v_lshl_add_u64 v[212:213], s[56:57], 0, v[132:133]
	s_mov_b32 m0, s55
	v_lshl_add_u64 v[214:215], s[38:39], 0, v[130:131]
	global_load_lds_dwordx4 v[212:213], off
	v_lshl_add_u64 v[212:213], s[56:57], 0, v[128:129]
	s_add_i32 m0, s55, 0x2000
	s_nop 0
	global_load_lds_dwordx4 v[212:213], off
	v_lshl_add_u64 v[212:213], s[38:39], 0, v[134:135]
	s_mov_b32 m0, s31
	s_nop 0
	global_load_lds_dwordx4 v[212:213], off
	s_mov_b32 m0, s35
	s_nop 0
	global_load_lds_dwordx4 v[214:215], off
	s_cmp_lg_u32 s100, 0
	s_cbranch_scc0 .Lrf_763_1
	s_waitcnt vmcnt(16)
	s_branch .Lrj_763_1

; #define G_STAGE(bufoff, gbase, voff) do { _Pragma("unroll") for (int _i = 0; _i < 2; ++_i) \
;         __builtin_amdgcn_global_load_lds((const unsigned*)((const char*)(gbase) + voff[_i]), (LAS unsigned*)(lds + (bufoff) + ldsw + _i * 8192), 16, 0, 0); } while (0)
; #define G_LDA(dst, b, h) do { _Pragma("unroll") for (int m = 0; m < 4; ++m) _Pragma("unroll") for (int k = 0; k < 2; ++k) dst[m][k] = *(const LAS bf16x8*)(lds + G_SA(b, h) + aoff + m * 2048 + k * 1024); } while (0)
; #define G_LDB(dst, b, h) do { _Pragma("unroll") for (int n = 0; n < 2; ++n) _Pragma("unroll") for (int k = 0; k < 2; ++k) dst[n][k] = *(const LAS bf16x8*)(lds + G_SB(b, h) + boff + n * 2048 + k * 1024); } while (0)
; #define G_MMA(ai, bj, At_, Bt_) do { __builtin_amdgcn_s_setprio(1); _Pragma("unroll") for (int m = 0; m < 4; ++m) _Pragma("unroll") for (int n = 0; n < 2; ++n) _Pragma("unroll") for (int k = 0; k < 2; ++k) \
;         acc[ai][bj][m][n] = __builtin_amdgcn_mfma_f32_16x16x32_bf16(Bt_[n][k], At_[m][k], acc[ai][bj][m][n], 0, 0, 0); __builtin_amdgcn_s_setprio(0); } while (0)
; #define WAIT_V(n) asm volatile("s_waitcnt vmcnt(" #n ")" ::: "memory")
; #define WAIT_L(n) asm volatile("s_waitcnt lgkmcnt(" #n ")" ::: "memory")
; #define BAR __builtin_amdgcn_s_barrier()
; #define SCHED __builtin_amdgcn_sched_barrier(0)
; template <class Get, class Epi>
; DI void gemm_loop(int ntiles, int ld, char* shm, const Get& get, const Epi& epi) {
;     ...
;             WAIT_V(8); WAIT_L(0); BAR; G_MMA(1, 0, At, B0); G_MMA(1, 1, At, B1); BAR; SCHED;
;             G_LDB(B0, 1, 0); G_LDB(B1, 1, 1); SCHED; G_LDA(At, 1, 0); G_STAGE(G_SA(0, 1), a2 + hstep, voffA);
;             WAIT_V(8); WAIT_L(0); BAR; G_MMA(0, 0, At, B0); G_MMA(0, 1, At, B1); BAR; SCHED;
.Lrj_763_1:
	s_waitcnt lgkmcnt(0)
	s_barrier
	s_setprio 1
	s_waitcnt lgkmcnt(0)
	v_mfma_f32_16x16x32_bf16 v[60:63], v[144:147], v[176:179], 0
	v_mfma_f32_16x16x32_bf16 v[56:59], v[152:155], v[176:179], 0
	v_mfma_f32_16x16x32_bf16 v[44:47], v[144:147], v[188:191], 0
	v_mfma_f32_16x16x32_bf16 v[40:43], v[152:155], v[188:191], 0
	v_mfma_f32_16x16x32_bf16 v[28:31], v[144:147], v[196:199], 0
	v_mfma_f32_16x16x32_bf16 v[24:27], v[152:155], v[196:199], 0
	v_mfma_f32_16x16x32_bf16 v[12:15], v[144:147], v[204:207], 0
	v_mfma_f32_16x16x32_bf16 v[8:11], v[152:155], v[204:207], 0
	s_setprio 0
	s_setprio 1
	v_mfma_f32_16x16x32_bf16 v[60:63], v[148:151], v[180:183], v[60:63]
	v_mfma_f32_16x16x32_bf16 v[56:59], v[156:159], v[180:183], v[56:59]
	v_mfma_f32_16x16x32_bf16 v[44:47], v[148:151], v[192:195], v[44:47]
	v_mfma_f32_16x16x32_bf16 v[40:43], v[156:159], v[192:195], v[40:43]
	v_mfma_f32_16x16x32_bf16 v[28:31], v[148:151], v[200:203], v[28:31]
	v_mfma_f32_16x16x32_bf16 v[24:27], v[156:159], v[200:203], v[24:27]
	v_mfma_f32_16x16x32_bf16 v[12:15], v[148:151], v[208:211], v[12:15]
	v_mfma_f32_16x16x32_bf16 v[8:11], v[156:159], v[208:211], v[8:11]
	s_setprio 0
	s_setprio 1
	v_mfma_f32_16x16x32_bf16 v[52:55], v[160:163], v[176:179], 0
	v_mfma_f32_16x16x32_bf16 v[48:51], v[168:171], v[176:179], 0
	v_mfma_f32_16x16x32_bf16 v[36:39], v[160:163], v[188:191], 0
	v_mfma_f32_16x16x32_bf16 v[32:35], v[168:171], v[188:191], 0
	v_mfma_f32_16x16x32_bf16 v[20:23], v[160:163], v[196:199], 0
	v_mfma_f32_16x16x32_bf16 v[16:19], v[168:171], v[196:199], 0
	v_mfma_f32_16x16x32_bf16 v[4:7], v[160:163], v[204:207], 0
	v_mfma_f32_16x16x32_bf16 v[0:3], v[168:171], v[204:207], 0
	s_setprio 0
	s_setprio 1
	v_mfma_f32_16x16x32_bf16 v[52:55], v[164:167], v[180:183], v[52:55]
	v_mfma_f32_16x16x32_bf16 v[48:51], v[172:175], v[180:183], v[48:51]
	v_mfma_f32_16x16x32_bf16 v[36:39], v[164:167], v[192:195], v[36:39]
	v_mfma_f32_16x16x32_bf16 v[32:35], v[172:175], v[192:195], v[32:35]
	v_mfma_f32_16x16x32_bf16 v[20:23], v[164:167], v[200:203], v[20:23]
	v_mfma_f32_16x16x32_bf16 v[16:19], v[172:175], v[200:203], v[16:19]
	v_mfma_f32_16x16x32_bf16 v[4:7], v[164:167], v[208:211], v[4:7]
	v_mfma_f32_16x16x32_bf16 v[0:3], v[172:175], v[208:211], v[0:3]
	s_setprio 0
	s_barrier
	s_add_i32 s55, 0, 0x18000
	s_add_i32 s56, 0, 0x1c000
	v_add_u32_e32 v156, s55, v140
	v_add_u32_e32 v172, s56, v140
	ds_read_b128 v[144:147], v156
	ds_read_b128 v[148:151], v156 offset:1024
	ds_read_b128 v[152:155], v156 offset:2048
	ds_read_b128 v[156:159], v156 offset:3072
	ds_read_b128 v[160:163], v172
	ds_read_b128 v[164:167], v172 offset:1024
	ds_read_b128 v[168:171], v172 offset:2048
	ds_read_b128 v[172:175], v172 offset:3072
	s_add_u32 s38, s38, 0x40000
	s_addc_u32 s39, s39, 0
	s_mov_b32 m0, s41
	v_lshl_add_u64 v[216:217], s[38:39], 0, v[134:135]
	ds_read_b128 v[176:179], v143 offset:32768
	ds_read_b128 v[180:183], v143 offset:33792
	ds_read_b128 v[188:191], v143 offset:34816
	ds_read_b128 v[192:195], v143 offset:35840
	ds_read_b128 v[196:199], v143 offset:36864
	ds_read_b128 v[200:203], v143 offset:37888
	ds_read_b128 v[204:207], v143 offset:38912
	ds_read_b128 v[208:211], v143 offset:39936
	global_load_lds_dwordx4 v[216:217], off
	v_lshl_add_u64 v[216:217], s[38:39], 0, v[130:131]
	s_mov_b32 m0, s42
	s_nop 0
	global_load_lds_dwordx4 v[216:217], off
	s_waitcnt vmcnt(8)
	s_waitcnt lgkmcnt(0)
	s_barrier
	s_setprio 1
	s_waitcnt lgkmcnt(0)
	v_mfma_f32_16x16x32_bf16 v[124:127], v[144:147], v[176:179], v[124:127]
	v_mfma_f32_16x16x32_bf16 v[120:123], v[152:155], v[176:179], v[120:123]
	v_mfma_f32_16x16x32_bf16 v[108:111], v[144:147], v[188:191], v[108:111]
	v_mfma_f32_16x16x32_bf16 v[104:107], v[152:155], v[188:191], v[104:107]
	v_mfma_f32_16x16x32_bf16 v[92:95], v[144:147], v[196:199], v[92:95]
	v_mfma_f32_16x16x32_bf16 v[88:91], v[152:155], v[196:199], v[88:91]
	v_mfma_f32_16x16x32_bf16 v[76:79], v[144:147], v[204:207], v[76:79]
	v_mfma_f32_16x16x32_bf16 v[72:75], v[152:155], v[204:207], v[72:75]
	s_setprio 0
	s_setprio 1
	v_mfma_f32_16x16x32_bf16 v[124:127], v[148:151], v[180:183], v[124:127]
	v_mfma_f32_16x16x32_bf16 v[120:123], v[156:159], v[180:183], v[120:123]
	v_mfma_f32_16x16x32_bf16 v[108:111], v[148:151], v[192:195], v[108:111]
	v_mfma_f32_16x16x32_bf16 v[104:107], v[156:159], v[192:195], v[104:107]
	v_mfma_f32_16x16x32_bf16 v[92:95], v[148:151], v[200:203], v[92:95]
	v_mfma_f32_16x16x32_bf16 v[88:91], v[156:159], v[200:203], v[88:91]
	v_mfma_f32_16x16x32_bf16 v[76:79], v[148:151], v[208:211], v[76:79]
	v_mfma_f32_16x16x32_bf16 v[72:75], v[156:159], v[208:211], v[72:75]
	s_setprio 0
	s_setprio 1
	v_mfma_f32_16x16x32_bf16 v[116:119], v[160:163], v[176:179], v[116:119]
	v_mfma_f32_16x16x32_bf16 v[112:115], v[168:171], v[176:179], v[112:115]
	v_mfma_f32_16x16x32_bf16 v[100:103], v[160:163], v[188:191], v[100:103]
	v_mfma_f32_16x16x32_bf16 v[96:99], v[168:171], v[188:191], v[96:99]
	v_mfma_f32_16x16x32_bf16 v[84:87], v[160:163], v[196:199], v[84:87]
	v_mfma_f32_16x16x32_bf16 v[80:83], v[168:171], v[196:199], v[80:83]
	v_mfma_f32_16x16x32_bf16 v[68:71], v[160:163], v[204:207], v[68:71]
	v_mfma_f32_16x16x32_bf16 v[64:67], v[168:171], v[204:207], v[64:67]
	s_setprio 0
	s_setprio 1
	v_mfma_f32_16x16x32_bf16 v[116:119], v[164:167], v[180:183], v[116:119]
	v_mfma_f32_16x16x32_bf16 v[112:115], v[172:175], v[180:183], v[112:115]
	v_mfma_f32_16x16x32_bf16 v[100:103], v[164:167], v[192:195], v[100:103]
	v_mfma_f32_16x16x32_bf16 v[96:99], v[172:175], v[192:195], v[96:99]
	v_mfma_f32_16x16x32_bf16 v[84:87], v[164:167], v[200:203], v[84:87]
	v_mfma_f32_16x16x32_bf16 v[80:83], v[172:175], v[200:203], v[80:83]
	v_mfma_f32_16x16x32_bf16 v[68:71], v[164:167], v[208:211], v[68:71]
	v_mfma_f32_16x16x32_bf16 v[64:67], v[172:175], v[208:211], v[64:67]
	s_setprio 0
	s_barrier
; #define G_STAGE(bufoff, gbase, voff) do { _Pragma("unroll") for (int _i = 0; _i < 2; ++_i) \
;         __builtin_amdgcn_global_load_lds((const unsigned*)((const char*)(gbase) + voff[_i]), (LAS unsigned*)(lds + (bufoff) + ldsw + _i * 8192), 16, 0, 0); } while (0)
; #define G_LDA(dst, b, h) do { _Pragma("unroll") for (int m = 0; m < 4; ++m) _Pragma("unroll") for (int k = 0; k < 2; ++k) dst[m][k] = *(const LAS bf16x8*)(lds + G_SA(b, h) + aoff + m * 2048 + k * 1024); } while (0)
; #define G_LDB(dst, b, h) do { _Pragma("unroll") for (int n = 0; n < 2; ++n) _Pragma("unroll") for (int k = 0; k < 2; ++k) dst[n][k] = *(const LAS bf16x8*)(lds + G_SB(b, h) + boff + n * 2048 + k * 1024); } while (0)
; #define WAIT_V(n) asm volatile("s_waitcnt vmcnt(" #n ")" ::: "memory")
; #define WAIT_L(n) asm volatile("s_waitcnt lgkmcnt(" #n ")" ::: "memory")
; #define BAR __builtin_amdgcn_s_barrier()
; #define SCHED __builtin_amdgcn_sched_barrier(0)
; template <class Get, class Epi>
; DI void gemm_loop(int ntiles, int ld, char* shm, const Get& get, const Epi& epi) {
;     ...
;         for (int t = 0; t < nt; t += 2) {
;             const bool last = (t == nt - 2);
;             const char* a1 = cA + (size_t)(t + 1) * kstep;
;             const char* a2 = last ? nA : cA + (size_t)(t + 2) * kstep; const char* b2 = last ? nB : cB + (size_t)(t + 2) * kstep;
;             const char* a3 = a2 + kstep; const char* b3 = b2 + kstep;
;             G_LDB(B0, 0, 0); G_LDB(B1, 0, 1); SCHED; G_LDA(At, 0, 0); G_STAGE(G_SA(1, 1), a1 + hstep, voffA);
;             WAIT_V(8); WAIT_L(0); BAR; G_MMA(0, 0, At, B0); G_MMA(0, 1, At, B1); BAR; SCHED;
;             G_LDA(At, 0, 1); G_STAGE(G_SB(0, 0), b2, voffB); G_STAGE(G_SB(0, 1), b2 + hstep, voffB); G_STAGE(G_SA(0, 0), a2, voffA);
;             WAIT_V(8); WAIT_L(0); BAR; G_MMA(1, 0, At, B0); G_MMA(1, 1, At, B1); BAR; SCHED;
;             G_LDB(B0, 1, 0); G_LDB(B1, 1, 1); SCHED; G_LDA(At, 1, 0); G_STAGE(G_SA(0, 1), a2 + hstep, voffA);
;             WAIT_V(8); WAIT_L(0); BAR; G_MMA(0, 0, At, B0); G_MMA(0, 1, At, B1); BAR; SCHED;
;             G_LDA(At, 1, 1); G_STAGE(G_SB(1, 0), b3, voffB); G_STAGE(G_SB(1, 1), b3 + hstep, voffB); G_STAGE(G_SA(1, 0), a3, voffA);
;             WAIT_V(8); WAIT_L(0); BAR; G_MMA(1, 0, At, B0); G_MMA(1, 1, At, B1); BAR; SCHED;
	s_add_i32 s38, s55, s26
	v_lshl_add_u64 v[184:185], v[184:185], 0, s[2:3]
	s_mov_b32 m0, s38
	ds_read_b128 v[176:179], v143 offset:49152
	ds_read_b128 v[180:183], v143 offset:50176
	ds_read_b128 v[188:191], v143 offset:51200
	ds_read_b128 v[192:195], v143 offset:52224
	ds_read_b128 v[196:199], v143 offset:53248
	ds_read_b128 v[200:203], v143 offset:54272
	ds_read_b128 v[204:207], v143 offset:55296
	ds_read_b128 v[208:211], v143 offset:56320
	global_load_lds_dwordx4 v[184:185], off
	s_add_i32 m0, s38, 0x2000
	s_add_u32 s14, s14, 0x40080
	v_lshl_add_u64 v[184:185], v[186:187], 0, s[2:3]
	s_addc_u32 s15, s15, 0
	s_add_i32 s38, s56, s26
	global_load_lds_dwordx4 v[184:185], off
	v_lshl_add_u64 v[184:185], s[14:15], 0, v[132:133]
	s_mov_b32 m0, s38
	s_nop 0
	global_load_lds_dwordx4 v[184:185], off
	v_lshl_add_u64 v[184:185], s[14:15], 0, v[128:129]
	s_add_i32 m0, s38, 0x2000
	s_nop 0
	global_load_lds_dwordx4 v[184:185], off
	v_lshl_add_u64 v[184:185], v[212:213], 0, s[2:3]
	s_mov_b32 m0, s43
	s_nop 0
	global_load_lds_dwordx4 v[184:185], off
	v_lshl_add_u64 v[184:185], v[214:215], 0, s[2:3]
	s_mov_b32 m0, s44
	s_nop 0
	global_load_lds_dwordx4 v[184:185], off
	s_waitcnt vmcnt(8)
	s_waitcnt lgkmcnt(0)
	s_barrier
	s_setprio 1
	s_waitcnt lgkmcnt(0)
	v_mfma_f32_16x16x32_bf16 v[60:63], v[144:147], v[176:179], v[60:63]
	v_mfma_f32_16x16x32_bf16 v[56:59], v[152:155], v[176:179], v[56:59]
	v_mfma_f32_16x16x32_bf16 v[44:47], v[144:147], v[188:191], v[44:47]
	v_mfma_f32_16x16x32_bf16 v[40:43], v[152:155], v[188:191], v[40:43]
	v_mfma_f32_16x16x32_bf16 v[28:31], v[144:147], v[196:199], v[28:31]
	v_mfma_f32_16x16x32_bf16 v[24:27], v[152:155], v[196:199], v[24:27]
	v_mfma_f32_16x16x32_bf16 v[12:15], v[144:147], v[204:207], v[12:15]
	v_mfma_f32_16x16x32_bf16 v[8:11], v[152:155], v[204:207], v[8:11]
	s_setprio 0
	s_setprio 1
	v_mfma_f32_16x16x32_bf16 v[60:63], v[148:151], v[180:183], v[60:63]
	v_mfma_f32_16x16x32_bf16 v[56:59], v[156:159], v[180:183], v[56:59]
	v_mfma_f32_16x16x32_bf16 v[44:47], v[148:151], v[192:195], v[44:47]
	v_mfma_f32_16x16x32_bf16 v[40:43], v[156:159], v[192:195], v[40:43]
	v_mfma_f32_16x16x32_bf16 v[28:31], v[148:151], v[200:203], v[28:31]
	v_mfma_f32_16x16x32_bf16 v[24:27], v[156:159], v[200:203], v[24:27]
	v_mfma_f32_16x16x32_bf16 v[12:15], v[148:151], v[208:211], v[12:15]
	v_mfma_f32_16x16x32_bf16 v[8:11], v[156:159], v[208:211], v[8:11]
	s_setprio 0
	s_setprio 1
	v_mfma_f32_16x16x32_bf16 v[52:55], v[160:163], v[176:179], v[52:55]
	v_mfma_f32_16x16x32_bf16 v[48:51], v[168:171], v[176:179], v[48:51]
	v_mfma_f32_16x16x32_bf16 v[36:39], v[160:163], v[188:191], v[36:39]
	v_mfma_f32_16x16x32_bf16 v[32:35], v[168:171], v[188:191], v[32:35]
	v_mfma_f32_16x16x32_bf16 v[20:23], v[160:163], v[196:199], v[20:23]
	v_mfma_f32_16x16x32_bf16 v[16:19], v[168:171], v[196:199], v[16:19]
	v_mfma_f32_16x16x32_bf16 v[4:7], v[160:163], v[204:207], v[4:7]
	v_mfma_f32_16x16x32_bf16 v[0:3], v[168:171], v[204:207], v[0:3]
	s_setprio 0
	s_setprio 1
	v_mfma_f32_16x16x32_bf16 v[52:55], v[164:167], v[180:183], v[52:55]
	v_mfma_f32_16x16x32_bf16 v[48:51], v[172:175], v[180:183], v[48:51]
	v_mfma_f32_16x16x32_bf16 v[36:39], v[164:167], v[192:195], v[36:39]
	v_mfma_f32_16x16x32_bf16 v[32:35], v[172:175], v[192:195], v[32:35]
	v_mfma_f32_16x16x32_bf16 v[20:23], v[164:167], v[200:203], v[20:23]
	v_mfma_f32_16x16x32_bf16 v[16:19], v[172:175], v[200:203], v[16:19]
	v_mfma_f32_16x16x32_bf16 v[4:7], v[164:167], v[208:211], v[4:7]
	v_mfma_f32_16x16x32_bf16 v[0:3], v[172:175], v[208:211], v[0:3]
	s_setprio 0
	s_barrier
	s_add_i32 s54, s54, 2
	s_add_u32 s36, s36, 0x100
	s_addc_u32 s37, s37, 0
	s_add_u32 s52, s52, 0x100
	s_addc_u32 s53, s53, 0
	s_cmp_gt_u32 s54, 13
	s_cbranch_scc0 .LBB0_763
	s_branch .Lpost_763
.LBB0_763:
	ds_read_b128 v[144:147], v141
	ds_read_b128 v[148:151], v141 offset:1024
	ds_read_b128 v[152:155], v141 offset:2048
	ds_read_b128 v[156:159], v141 offset:3072
	ds_read_b128 v[160:163], v142
	ds_read_b128 v[164:167], v142 offset:1024
	ds_read_b128 v[168:171], v142 offset:2048
	ds_read_b128 v[172:175], v142 offset:3072
	s_add_u32 s14, s36, 0xfffc0080
	s_addc_u32 s15, s37, -1
	s_cmp_eq_u32 s54, 12
	s_cselect_b32 s39, s9, s15
	s_cselect_b32 s38, s50, s14
	s_cselect_b32 s15, s11, s53
	s_cselect_b32 s14, s51, s52
	v_lshl_add_u64 v[184:185], s[36:37], 0, v[136:137]
	s_add_i32 m0, s31, 0xc000
	ds_read_b128 v[176:179], v143
	ds_read_b128 v[180:183], v143 offset:1024
	ds_read_b128 v[188:191], v143 offset:2048
	ds_read_b128 v[192:195], v143 offset:3072
	ds_read_b128 v[196:199], v143 offset:4096
	ds_read_b128 v[200:203], v143 offset:5120
	ds_read_b128 v[204:207], v143 offset:6144
	ds_read_b128 v[208:211], v143 offset:7168
	global_load_lds_dwordx4 v[184:185], off
	v_lshl_add_u64 v[184:185], s[36:37], 0, v[138:139]
	s_add_i32 m0, s31, 0xe000
	s_nop 0
	global_load_lds_dwordx4 v[184:185], off
	s_waitcnt vmcnt(8)
	s_waitcnt lgkmcnt(0)
	s_barrier
; #define G_STAGE(bufoff, gbase, voff) do { _Pragma("unroll") for (int _i = 0; _i < 2; ++_i) \
;         __builtin_amdgcn_global_load_lds((const unsigned*)((const char*)(gbase) + voff[_i]), (LAS unsigned*)(lds + (bufoff) + ldsw + _i * 8192), 16, 0, 0); } while (0)
; #define G_LDA(dst, b, h) do { _Pragma("unroll") for (int m = 0; m < 4; ++m) _Pragma("unroll") for (int k = 0; k < 2; ++k) dst[m][k] = *(const LAS bf16x8*)(lds + G_SA(b, h) + aoff + m * 2048 + k * 1024); } while (0)
; #define G_MMA(ai, bj, At_, Bt_) do { __builtin_amdgcn_s_setprio(1); _Pragma("unroll") for (int m = 0; m < 4; ++m) _Pragma("unroll") for (int n = 0; n < 2; ++n) _Pragma("unroll") for (int k = 0; k < 2; ++k) \
;         acc[ai][bj][m][n] = __builtin_amdgcn_mfma_f32_16x16x32_bf16(Bt_[n][k], At_[m][k], acc[ai][bj][m][n], 0, 0, 0); __builtin_amdgcn_s_setprio(0); } while (0)
; #define WAIT_V(n) asm volatile("s_waitcnt vmcnt(" #n ")" ::: "memory")
; #define WAIT_L(n) asm volatile("s_waitcnt lgkmcnt(" #n ")" ::: "memory")
; #define BAR __builtin_amdgcn_s_barrier()
; #define SCHED __builtin_amdgcn_sched_barrier(0)
; template <class Get, class Epi>
; DI void gemm_loop(int ntiles, int ld, char* shm, const Get& get, const Epi& epi) {
;     ...
;             WAIT_V(8); WAIT_L(0); BAR; G_MMA(0, 0, At, B0); G_MMA(0, 1, At, B1); BAR; SCHED;
;             G_LDA(At, 0, 1); G_STAGE(G_SB(0, 0), b2, voffB); G_STAGE(G_SB(0, 1), b2 + hstep, voffB); G_STAGE(G_SA(0, 0), a2, voffA);
;             WAIT_V(8); WAIT_L(0); BAR; G_MMA(1, 0, At, B0); G_MMA(1, 1, At, B1); BAR; SCHED;
	s_setprio 1
	s_waitcnt lgkmcnt(0)
	v_mfma_f32_16x16x32_bf16 v[124:127], v[144:147], v[176:179], v[124:127]
	v_mfma_f32_16x16x32_bf16 v[120:123], v[152:155], v[176:179], v[120:123]
	v_mfma_f32_16x16x32_bf16 v[108:111], v[144:147], v[188:191], v[108:111]
	v_mfma_f32_16x16x32_bf16 v[104:107], v[152:155], v[188:191], v[104:107]
	v_mfma_f32_16x16x32_bf16 v[92:95], v[144:147], v[196:199], v[92:95]
	v_mfma_f32_16x16x32_bf16 v[88:91], v[152:155], v[196:199], v[88:91]
	v_mfma_f32_16x16x32_bf16 v[76:79], v[144:147], v[204:207], v[76:79]
	v_mfma_f32_16x16x32_bf16 v[72:75], v[152:155], v[204:207], v[72:75]
	s_setprio 0
	s_setprio 1
	v_mfma_f32_16x16x32_bf16 v[124:127], v[148:151], v[180:183], v[124:127]
	v_mfma_f32_16x16x32_bf16 v[120:123], v[156:159], v[180:183], v[120:123]
	v_mfma_f32_16x16x32_bf16 v[108:111], v[148:151], v[192:195], v[108:111]
	v_mfma_f32_16x16x32_bf16 v[104:107], v[156:159], v[192:195], v[104:107]
	v_mfma_f32_16x16x32_bf16 v[92:95], v[148:151], v[200:203], v[92:95]
	v_mfma_f32_16x16x32_bf16 v[88:91], v[156:159], v[200:203], v[88:91]
	v_mfma_f32_16x16x32_bf16 v[76:79], v[148:151], v[208:211], v[76:79]
	v_mfma_f32_16x16x32_bf16 v[72:75], v[156:159], v[208:211], v[72:75]
	s_setprio 0
	s_setprio 1
	v_mfma_f32_16x16x32_bf16 v[116:119], v[160:163], v[176:179], v[116:119]
	v_mfma_f32_16x16x32_bf16 v[112:115], v[168:171], v[176:179], v[112:115]
	v_mfma_f32_16x16x32_bf16 v[100:103], v[160:163], v[188:191], v[100:103]
	v_mfma_f32_16x16x32_bf16 v[96:99], v[168:171], v[188:191], v[96:99]
	v_mfma_f32_16x16x32_bf16 v[84:87], v[160:163], v[196:199], v[84:87]
	v_mfma_f32_16x16x32_bf16 v[80:83], v[168:171], v[196:199], v[80:83]
	v_mfma_f32_16x16x32_bf16 v[68:71], v[160:163], v[204:207], v[68:71]
	v_mfma_f32_16x16x32_bf16 v[64:67], v[168:171], v[204:207], v[64:67]
	s_setprio 0
	s_setprio 1
	v_mfma_f32_16x16x32_bf16 v[116:119], v[164:167], v[180:183], v[116:119]
	v_mfma_f32_16x16x32_bf16 v[112:115], v[172:175], v[180:183], v[112:115]
	v_mfma_f32_16x16x32_bf16 v[100:103], v[164:167], v[192:195], v[100:103]
	v_mfma_f32_16x16x32_bf16 v[96:99], v[172:175], v[192:195], v[96:99]
	v_mfma_f32_16x16x32_bf16 v[84:87], v[164:167], v[200:203], v[84:87]
	v_mfma_f32_16x16x32_bf16 v[80:83], v[172:175], v[200:203], v[80:83]
	v_mfma_f32_16x16x32_bf16 v[68:71], v[164:167], v[208:211], v[68:71]
	v_mfma_f32_16x16x32_bf16 v[64:67], v[172:175], v[208:211], v[64:67]
	s_setprio 0
	s_barrier
	s_add_i32 s55, s45, s26
	v_lshl_add_u64 v[184:185], s[14:15], 0, v[132:133]
	s_mov_b32 m0, s55
	ds_read_b128 v[176:179], v143 offset:16384
	ds_read_b128 v[180:183], v143 offset:17408
	ds_read_b128 v[188:191], v143 offset:18432
	ds_read_b128 v[192:195], v143 offset:19456
	ds_read_b128 v[196:199], v143 offset:20480
	ds_read_b128 v[200:203], v143 offset:21504
	ds_read_b128 v[204:207], v143 offset:22528
	ds_read_b128 v[208:211], v143 offset:23552
	global_load_lds_dwordx4 v[184:185], off
	s_add_i32 m0, s55, 0x2000
	s_add_u32 s56, s14, 0x40000
	v_lshl_add_u64 v[186:187], s[14:15], 0, v[128:129]
	s_addc_u32 s57, s15, 0
	s_add_i32 s55, s46, s26
	global_load_lds_dwordx4 v[186:187], off
	v_lshl_add_u64 v[212:213], s[56:57], 0, v[132:133]
	s_mov_b32 m0, s55
	v_lshl_add_u64 v[214:215], s[38:39], 0, v[130:131]
	global_load_lds_dwordx4 v[212:213], off
	v_lshl_add_u64 v[212:213], s[56:57], 0, v[128:129]
	s_add_i32 m0, s55, 0x2000
	s_nop 0
	global_load_lds_dwordx4 v[212:213], off
	v_lshl_add_u64 v[212:213], s[38:39], 0, v[134:135]
	s_mov_b32 m0, s31
	s_nop 0
	global_load_lds_dwordx4 v[212:213], off
	s_mov_b32 m0, s35
	s_nop 0
	global_load_lds_dwordx4 v[214:215], off
	s_waitcnt vmcnt(8)
	s_waitcnt lgkmcnt(0)
	s_barrier
	s_setprio 1
	s_waitcnt lgkmcnt(0)
	v_mfma_f32_16x16x32_bf16 v[60:63], v[144:147], v[176:179], v[60:63]
	v_mfma_f32_16x16x32_bf16 v[56:59], v[152:155], v[176:179], v[56:59]
	v_mfma_f32_16x16x32_bf16 v[44:47], v[144:147], v[188:191], v[44:47]
	v_mfma_f32_16x16x32_bf16 v[40:43], v[152:155], v[188:191], v[40:43]
	v_mfma_f32_16x16x32_bf16 v[28:31], v[144:147], v[196:199], v[28:31]
	v_mfma_f32_16x16x32_bf16 v[24:27], v[152:155], v[196:199], v[24:27]
	v_mfma_f32_16x16x32_bf16 v[12:15], v[144:147], v[204:207], v[12:15]
	v_mfma_f32_16x16x32_bf16 v[8:11], v[152:155], v[204:207], v[8:11]
	s_setprio 0
	s_setprio 1
	v_mfma_f32_16x16x32_bf16 v[60:63], v[148:151], v[180:183], v[60:63]
	v_mfma_f32_16x16x32_bf16 v[56:59], v[156:159], v[180:183], v[56:59]
	v_mfma_f32_16x16x32_bf16 v[44:47], v[148:151], v[192:195], v[44:47]
	v_mfma_f32_16x16x32_bf16 v[40:43], v[156:159], v[192:195], v[40:43]
	v_mfma_f32_16x16x32_bf16 v[28:31], v[148:151], v[200:203], v[28:31]
	v_mfma_f32_16x16x32_bf16 v[24:27], v[156:159], v[200:203], v[24:27]
	v_mfma_f32_16x16x32_bf16 v[12:15], v[148:151], v[208:211], v[12:15]
	v_mfma_f32_16x16x32_bf16 v[8:11], v[156:159], v[208:211], v[8:11]
	s_setprio 0
	s_setprio 1
	v_mfma_f32_16x16x32_bf16 v[52:55], v[160:163], v[176:179], v[52:55]
	v_mfma_f32_16x16x32_bf16 v[48:51], v[168:171], v[176:179], v[48:51]
	v_mfma_f32_16x16x32_bf16 v[36:39], v[160:163], v[188:191], v[36:39]
	v_mfma_f32_16x16x32_bf16 v[32:35], v[168:171], v[188:191], v[32:35]
	v_mfma_f32_16x16x32_bf16 v[20:23], v[160:163], v[196:199], v[20:23]
	v_mfma_f32_16x16x32_bf16 v[16:19], v[168:171], v[196:199], v[16:19]
	v_mfma_f32_16x16x32_bf16 v[4:7], v[160:163], v[204:207], v[4:7]
	v_mfma_f32_16x16x32_bf16 v[0:3], v[168:171], v[204:207], v[0:3]
	s_setprio 0
	s_setprio 1
	v_mfma_f32_16x16x32_bf16 v[52:55], v[164:167], v[180:183], v[52:55]
	v_mfma_f32_16x16x32_bf16 v[48:51], v[172:175], v[180:183], v[48:51]
	v_mfma_f32_16x16x32_bf16 v[36:39], v[164:167], v[192:195], v[36:39]
	v_mfma_f32_16x16x32_bf16 v[32:35], v[172:175], v[192:195], v[32:35]
	v_mfma_f32_16x16x32_bf16 v[20:23], v[164:167], v[200:203], v[20:23]
	v_mfma_f32_16x16x32_bf16 v[16:19], v[172:175], v[200:203], v[16:19]
	v_mfma_f32_16x16x32_bf16 v[4:7], v[164:167], v[208:211], v[4:7]
	v_mfma_f32_16x16x32_bf16 v[0:3], v[172:175], v[208:211], v[0:3]
	s_setprio 0
	s_barrier
; #define G_STAGE(bufoff, gbase, voff) do { _Pragma("unroll") for (int _i = 0; _i < 2; ++_i) \
;         __builtin_amdgcn_global_load_lds((const unsigned*)((const char*)(gbase) + voff[_i]), (LAS unsigned*)(lds + (bufoff) + ldsw + _i * 8192), 16, 0, 0); } while (0)
; #define G_LDA(dst, b, h) do { _Pragma("unroll") for (int m = 0; m < 4; ++m) _Pragma("unroll") for (int k = 0; k < 2; ++k) dst[m][k] = *(const LAS bf16x8*)(lds + G_SA(b, h) + aoff + m * 2048 + k * 1024); } while (0)
; #define G_LDB(dst, b, h) do { _Pragma("unroll") for (int n = 0; n < 2; ++n) _Pragma("unroll") for (int k = 0; k < 2; ++k) dst[n][k] = *(const LAS bf16x8*)(lds + G_SB(b, h) + boff + n * 2048 + k * 1024); } while (0)
; #define G_MMA(ai, bj, At_, Bt_) do { __builtin_amdgcn_s_setprio(1); _Pragma("unroll") for (int m = 0; m < 4; ++m) _Pragma("unroll") for (int n = 0; n < 2; ++n) _Pragma("unroll") for (int k = 0; k < 2; ++k) \
;         acc[ai][bj][m][n] = __builtin_amdgcn_mfma_f32_16x16x32_bf16(Bt_[n][k], At_[m][k], acc[ai][bj][m][n], 0, 0, 0); __builtin_amdgcn_s_setprio(0); } while (0)
; #define WAIT_V(n) asm volatile("s_waitcnt vmcnt(" #n ")" ::: "memory")
; #define WAIT_L(n) asm volatile("s_waitcnt lgkmcnt(" #n ")" ::: "memory")
; #define BAR __builtin_amdgcn_s_barrier()
; #define SCHED __builtin_amdgcn_sched_barrier(0)
; template <class Get, class Epi>
; DI void gemm_loop(int ntiles, int ld, char* shm, const Get& get, const Epi& epi) {
;     ...
;             G_LDB(B0, 1, 0); G_LDB(B1, 1, 1); SCHED; G_LDA(At, 1, 0); G_STAGE(G_SA(0, 1), a2 + hstep, voffA);
;             WAIT_V(8); WAIT_L(0); BAR; G_MMA(0, 0, At, B0); G_MMA(0, 1, At, B1); BAR; SCHED;
	s_add_i32 s55, 0, 0x18000
	s_add_i32 s56, 0, 0x1c000
	v_add_u32_e32 v156, s55, v140
	v_add_u32_e32 v172, s56, v140
	ds_read_b128 v[144:147], v156
	ds_read_b128 v[148:151], v156 offset:1024
	ds_read_b128 v[152:155], v156 offset:2048
	ds_read_b128 v[156:159], v156 offset:3072
	ds_read_b128 v[160:163], v172
	ds_read_b128 v[164:167], v172 offset:1024
	ds_read_b128 v[168:171], v172 offset:2048
	ds_read_b128 v[172:175], v172 offset:3072
	s_add_u32 s38, s38, 0x40000
	s_addc_u32 s39, s39, 0
	s_mov_b32 m0, s41
	v_lshl_add_u64 v[216:217], s[38:39], 0, v[134:135]
	ds_read_b128 v[176:179], v143 offset:32768
	ds_read_b128 v[180:183], v143 offset:33792
	ds_read_b128 v[188:191], v143 offset:34816
	ds_read_b128 v[192:195], v143 offset:35840
	ds_read_b128 v[196:199], v143 offset:36864
	ds_read_b128 v[200:203], v143 offset:37888
	ds_read_b128 v[204:207], v143 offset:38912
	ds_read_b128 v[208:211], v143 offset:39936
	global_load_lds_dwordx4 v[216:217], off
	v_lshl_add_u64 v[216:217], s[38:39], 0, v[130:131]
	s_mov_b32 m0, s42
	s_nop 0
	global_load_lds_dwordx4 v[216:217], off
	s_waitcnt vmcnt(8)
	s_waitcnt lgkmcnt(0)
	s_barrier
	s_setprio 1
	s_waitcnt lgkmcnt(0)
	v_mfma_f32_16x16x32_bf16 v[124:127], v[144:147], v[176:179], v[124:127]
	v_mfma_f32_16x16x32_bf16 v[120:123], v[152:155], v[176:179], v[120:123]
	v_mfma_f32_16x16x32_bf16 v[108:111], v[144:147], v[188:191], v[108:111]
	v_mfma_f32_16x16x32_bf16 v[104:107], v[152:155], v[188:191], v[104:107]
	v_mfma_f32_16x16x32_bf16 v[92:95], v[144:147], v[196:199], v[92:95]
	v_mfma_f32_16x16x32_bf16 v[88:91], v[152:155], v[196:199], v[88:91]
	v_mfma_f32_16x16x32_bf16 v[76:79], v[144:147], v[204:207], v[76:79]
	v_mfma_f32_16x16x32_bf16 v[72:75], v[152:155], v[204:207], v[72:75]
	s_setprio 0
	s_setprio 1
	v_mfma_f32_16x16x32_bf16 v[124:127], v[148:151], v[180:183], v[124:127]
	v_mfma_f32_16x16x32_bf16 v[120:123], v[156:159], v[180:183], v[120:123]
	v_mfma_f32_16x16x32_bf16 v[108:111], v[148:151], v[192:195], v[108:111]
	v_mfma_f32_16x16x32_bf16 v[104:107], v[156:159], v[192:195], v[104:107]
	v_mfma_f32_16x16x32_bf16 v[92:95], v[148:151], v[200:203], v[92:95]
	v_mfma_f32_16x16x32_bf16 v[88:91], v[156:159], v[200:203], v[88:91]
	v_mfma_f32_16x16x32_bf16 v[76:79], v[148:151], v[208:211], v[76:79]
	v_mfma_f32_16x16x32_bf16 v[72:75], v[156:159], v[208:211], v[72:75]
	s_setprio 0
	s_setprio 1
	v_mfma_f32_16x16x32_bf16 v[116:119], v[160:163], v[176:179], v[116:119]
	v_mfma_f32_16x16x32_bf16 v[112:115], v[168:171], v[176:179], v[112:115]
	v_mfma_f32_16x16x32_bf16 v[100:103], v[160:163], v[188:191], v[100:103]
	v_mfma_f32_16x16x32_bf16 v[96:99], v[168:171], v[188:191], v[96:99]
	v_mfma_f32_16x16x32_bf16 v[84:87], v[160:163], v[196:199], v[84:87]
	v_mfma_f32_16x16x32_bf16 v[80:83], v[168:171], v[196:199], v[80:83]
	v_mfma_f32_16x16x32_bf16 v[68:71], v[160:163], v[204:207], v[68:71]
	v_mfma_f32_16x16x32_bf16 v[64:67], v[168:171], v[204:207], v[64:67]
	s_setprio 0
	s_setprio 1
	v_mfma_f32_16x16x32_bf16 v[116:119], v[164:167], v[180:183], v[116:119]
	v_mfma_f32_16x16x32_bf16 v[112:115], v[172:175], v[180:183], v[112:115]
	v_mfma_f32_16x16x32_bf16 v[100:103], v[164:167], v[192:195], v[100:103]
	v_mfma_f32_16x16x32_bf16 v[96:99], v[172:175], v[192:195], v[96:99]
	v_mfma_f32_16x16x32_bf16 v[84:87], v[164:167], v[200:203], v[84:87]
	v_mfma_f32_16x16x32_bf16 v[80:83], v[172:175], v[200:203], v[80:83]
	v_mfma_f32_16x16x32_bf16 v[68:71], v[164:167], v[208:211], v[68:71]
	v_mfma_f32_16x16x32_bf16 v[64:67], v[172:175], v[208:211], v[64:67]
	s_setprio 0
	s_barrier
; #define G_STAGE(bufoff, gbase, voff) do { _Pragma("unroll") for (int _i = 0; _i < 2; ++_i) \
;         __builtin_amdgcn_global_load_lds((const unsigned*)((const char*)(gbase) + voff[_i]), (LAS unsigned*)(lds + (bufoff) + ldsw + _i * 8192), 16, 0, 0); } while (0)
; #define G_LDA(dst, b, h) do { _Pragma("unroll") for (int m = 0; m < 4; ++m) _Pragma("unroll") for (int k = 0; k < 2; ++k) dst[m][k] = *(const LAS bf16x8*)(lds + G_SA(b, h) + aoff + m * 2048 + k * 1024); } while (0)
; #define G_MMA(ai, bj, At_, Bt_) do { __builtin_amdgcn_s_setprio(1); _Pragma("unroll") for (int m = 0; m < 4; ++m) _Pragma("unroll") for (int n = 0; n < 2; ++n) _Pragma("unroll") for (int k = 0; k < 2; ++k) \
;         acc[ai][bj][m][n] = __builtin_amdgcn_mfma_f32_16x16x32_bf16(Bt_[n][k], At_[m][k], acc[ai][bj][m][n], 0, 0, 0); __builtin_amdgcn_s_setprio(0); } while (0)
; #define WAIT_V(n) asm volatile("s_waitcnt vmcnt(" #n ")" ::: "memory")
; #define WAIT_L(n) asm volatile("s_waitcnt lgkmcnt(" #n ")" ::: "memory")
; #define BAR __builtin_amdgcn_s_barrier()
; #define SCHED __builtin_amdgcn_sched_barrier(0)
; template <class Get, class Epi>
; DI void gemm_loop(int ntiles, int ld, char* shm, const Get& get, const Epi& epi) {
;     ...
;             G_LDA(At, 1, 1); G_STAGE(G_SB(1, 0), b3, voffB); G_STAGE(G_SB(1, 1), b3 + hstep, voffB); G_STAGE(G_SA(1, 0), a3, voffA);
;             WAIT_V(8); WAIT_L(0); BAR; G_MMA(1, 0, At, B0); G_MMA(1, 1, At, B1); BAR; SCHED;
;         }
	s_add_i32 s38, s55, s26
	v_lshl_add_u64 v[184:185], v[184:185], 0, s[2:3]
	s_mov_b32 m0, s38
	ds_read_b128 v[176:179], v143 offset:49152
	ds_read_b128 v[180:183], v143 offset:50176
	ds_read_b128 v[188:191], v143 offset:51200
	ds_read_b128 v[192:195], v143 offset:52224
	ds_read_b128 v[196:199], v143 offset:53248
	ds_read_b128 v[200:203], v143 offset:54272
	ds_read_b128 v[204:207], v143 offset:55296
	ds_read_b128 v[208:211], v143 offset:56320
	global_load_lds_dwordx4 v[184:185], off
	s_add_i32 m0, s38, 0x2000
	s_add_u32 s14, s14, 0x40080
	v_lshl_add_u64 v[184:185], v[186:187], 0, s[2:3]
	s_addc_u32 s15, s15, 0
	s_add_i32 s38, s56, s26
	global_load_lds_dwordx4 v[184:185], off
	v_lshl_add_u64 v[184:185], s[14:15], 0, v[132:133]
	s_mov_b32 m0, s38
	s_nop 0
	global_load_lds_dwordx4 v[184:185], off
	v_lshl_add_u64 v[184:185], s[14:15], 0, v[128:129]
	s_add_i32 m0, s38, 0x2000
	s_nop 0
	global_load_lds_dwordx4 v[184:185], off
	v_lshl_add_u64 v[184:185], v[212:213], 0, s[2:3]
	s_mov_b32 m0, s43
	s_nop 0
	global_load_lds_dwordx4 v[184:185], off
	v_lshl_add_u64 v[184:185], v[214:215], 0, s[2:3]
	s_mov_b32 m0, s44
	s_nop 0
	global_load_lds_dwordx4 v[184:185], off
	s_waitcnt vmcnt(8)
	s_waitcnt lgkmcnt(0)
	s_barrier
	s_setprio 1
	s_waitcnt lgkmcnt(0)
	v_mfma_f32_16x16x32_bf16 v[60:63], v[144:147], v[176:179], v[60:63]
	v_mfma_f32_16x16x32_bf16 v[56:59], v[152:155], v[176:179], v[56:59]
	v_mfma_f32_16x16x32_bf16 v[44:47], v[144:147], v[188:191], v[44:47]
	v_mfma_f32_16x16x32_bf16 v[40:43], v[152:155], v[188:191], v[40:43]
	v_mfma_f32_16x16x32_bf16 v[28:31], v[144:147], v[196:199], v[28:31]
	v_mfma_f32_16x16x32_bf16 v[24:27], v[152:155], v[196:199], v[24:27]
	v_mfma_f32_16x16x32_bf16 v[12:15], v[144:147], v[204:207], v[12:15]
	v_mfma_f32_16x16x32_bf16 v[8:11], v[152:155], v[204:207], v[8:11]
	s_setprio 0
	s_setprio 1
	v_mfma_f32_16x16x32_bf16 v[60:63], v[148:151], v[180:183], v[60:63]
	v_mfma_f32_16x16x32_bf16 v[56:59], v[156:159], v[180:183], v[56:59]
	v_mfma_f32_16x16x32_bf16 v[44:47], v[148:151], v[192:195], v[44:47]
	v_mfma_f32_16x16x32_bf16 v[40:43], v[156:159], v[192:195], v[40:43]
	v_mfma_f32_16x16x32_bf16 v[28:31], v[148:151], v[200:203], v[28:31]
	v_mfma_f32_16x16x32_bf16 v[24:27], v[156:159], v[200:203], v[24:27]
	v_mfma_f32_16x16x32_bf16 v[12:15], v[148:151], v[208:211], v[12:15]
	v_mfma_f32_16x16x32_bf16 v[8:11], v[156:159], v[208:211], v[8:11]
	s_setprio 0
	s_setprio 1
	v_mfma_f32_16x16x32_bf16 v[52:55], v[160:163], v[176:179], v[52:55]
	v_mfma_f32_16x16x32_bf16 v[48:51], v[168:171], v[176:179], v[48:51]
	v_mfma_f32_16x16x32_bf16 v[36:39], v[160:163], v[188:191], v[36:39]
	v_mfma_f32_16x16x32_bf16 v[32:35], v[168:171], v[188:191], v[32:35]
	v_mfma_f32_16x16x32_bf16 v[20:23], v[160:163], v[196:199], v[20:23]
	v_mfma_f32_16x16x32_bf16 v[16:19], v[168:171], v[196:199], v[16:19]
	v_mfma_f32_16x16x32_bf16 v[4:7], v[160:163], v[204:207], v[4:7]
	v_mfma_f32_16x16x32_bf16 v[0:3], v[168:171], v[204:207], v[0:3]
	s_setprio 0
	s_setprio 1
	v_mfma_f32_16x16x32_bf16 v[52:55], v[164:167], v[180:183], v[52:55]
	v_mfma_f32_16x16x32_bf16 v[48:51], v[172:175], v[180:183], v[48:51]
	v_mfma_f32_16x16x32_bf16 v[36:39], v[164:167], v[192:195], v[36:39]
	v_mfma_f32_16x16x32_bf16 v[32:35], v[172:175], v[192:195], v[32:35]
	v_mfma_f32_16x16x32_bf16 v[20:23], v[164:167], v[200:203], v[20:23]
	v_mfma_f32_16x16x32_bf16 v[16:19], v[172:175], v[200:203], v[16:19]
	v_mfma_f32_16x16x32_bf16 v[4:7], v[164:167], v[208:211], v[4:7]
	v_mfma_f32_16x16x32_bf16 v[0:3], v[172:175], v[208:211], v[0:3]
	s_setprio 0
	s_barrier
	s_add_i32 s54, s54, 2
	s_add_u32 s36, s36, 0x100
	s_addc_u32 s37, s37, 0
	s_add_u32 s52, s52, 0x100
	s_addc_u32 s53, s53, 0
	s_cmp_gt_u32 s54, 13
	s_cbranch_scc0 .LBB0_763

; #define G_STAGE(bufoff, gbase, voff) do { _Pragma("unroll") for (int _i = 0; _i < 2; ++_i) \
;         __builtin_amdgcn_global_load_lds((const unsigned*)((const char*)(gbase) + voff[_i]), (LAS unsigned*)(lds + (bufoff) + ldsw + _i * 8192), 16, 0, 0); } while (0)
; #define G_LDA(dst, b, h) do { _Pragma("unroll") for (int m = 0; m < 4; ++m) _Pragma("unroll") for (int k = 0; k < 2; ++k) dst[m][k] = *(const LAS bf16x8*)(lds + G_SA(b, h) + aoff + m * 2048 + k * 1024); } while (0)
; #define G_MMA(ai, bj, At_, Bt_) do { __builtin_amdgcn_s_setprio(1); _Pragma("unroll") for (int m = 0; m < 4; ++m) _Pragma("unroll") for (int n = 0; n < 2; ++n) _Pragma("unroll") for (int k = 0; k < 2; ++k) \
;         acc[ai][bj][m][n] = __builtin_amdgcn_mfma_f32_16x16x32_bf16(Bt_[n][k], At_[m][k], acc[ai][bj][m][n], 0, 0, 0); __builtin_amdgcn_s_setprio(0); } while (0)
; #define WAIT_V(n) asm volatile("s_waitcnt vmcnt(" #n ")" ::: "memory")
; #define WAIT_L(n) asm volatile("s_waitcnt lgkmcnt(" #n ")" ::: "memory")
; #define BAR __builtin_amdgcn_s_barrier()
; #define SCHED __builtin_amdgcn_sched_barrier(0)
; template <class Get, class Epi>
; DI void gemm_loop(int ntiles, int ld, char* shm, const Get& get, const Epi& epi) {
;     ...
;             WAIT_V(8); WAIT_L(0); BAR; G_MMA(0, 0, At, B0); G_MMA(0, 1, At, B1); BAR; SCHED;
;             G_LDA(At, 0, 1); G_STAGE(G_SB(0, 0), b2, voffB); G_STAGE(G_SB(0, 1), b2 + hstep, voffB); G_STAGE(G_SA(0, 0), a2, voffA);
;             WAIT_V(8); WAIT_L(0); BAR; G_MMA(1, 0, At, B0); G_MMA(1, 1, At, B1); BAR; SCHED;
.Lrj_850_0:
	s_waitcnt lgkmcnt(0)
	s_barrier
	s_setprio 1
	s_waitcnt lgkmcnt(0)
	v_mfma_f32_16x16x32_bf16 v[124:127], v[128:131], v[180:183], 0
	v_mfma_f32_16x16x32_bf16 v[120:123], v[136:139], v[180:183], 0
	v_mfma_f32_16x16x32_bf16 v[116:119], v[128:131], v[192:195], 0
	v_mfma_f32_16x16x32_bf16 v[112:115], v[136:139], v[192:195], 0
	v_mfma_f32_16x16x32_bf16 v[108:111], v[128:131], v[200:203], 0
	v_mfma_f32_16x16x32_bf16 v[104:107], v[136:139], v[200:203], 0
	v_mfma_f32_16x16x32_bf16 v[100:103], v[128:131], v[208:211], 0
	v_mfma_f32_16x16x32_bf16 v[96:99], v[136:139], v[208:211], 0
	s_setprio 0
	s_setprio 1
	v_mfma_f32_16x16x32_bf16 v[124:127], v[132:135], v[188:191], v[124:127]
	v_mfma_f32_16x16x32_bf16 v[120:123], v[140:143], v[188:191], v[120:123]
	v_mfma_f32_16x16x32_bf16 v[116:119], v[132:135], v[196:199], v[116:119]
	v_mfma_f32_16x16x32_bf16 v[112:115], v[140:143], v[196:199], v[112:115]
	v_mfma_f32_16x16x32_bf16 v[108:111], v[132:135], v[204:207], v[108:111]
	v_mfma_f32_16x16x32_bf16 v[104:107], v[140:143], v[204:207], v[104:107]
	v_mfma_f32_16x16x32_bf16 v[100:103], v[132:135], v[212:215], v[100:103]
	v_mfma_f32_16x16x32_bf16 v[96:99], v[140:143], v[212:215], v[96:99]
	s_setprio 0
	s_setprio 1
	v_mfma_f32_16x16x32_bf16 v[60:63], v[158:161], v[180:183], 0
	v_mfma_f32_16x16x32_bf16 v[56:59], v[172:175], v[180:183], 0
	v_mfma_f32_16x16x32_bf16 v[52:55], v[158:161], v[192:195], 0
	v_mfma_f32_16x16x32_bf16 v[48:51], v[172:175], v[192:195], 0
	v_mfma_f32_16x16x32_bf16 v[44:47], v[158:161], v[200:203], 0
	v_mfma_f32_16x16x32_bf16 v[40:43], v[172:175], v[200:203], 0
	v_mfma_f32_16x16x32_bf16 v[36:39], v[158:161], v[208:211], 0
	v_mfma_f32_16x16x32_bf16 v[32:35], v[172:175], v[208:211], 0
	s_setprio 0
	s_setprio 1
	v_mfma_f32_16x16x32_bf16 v[60:63], v[162:165], v[188:191], v[60:63]
	v_mfma_f32_16x16x32_bf16 v[56:59], v[176:179], v[188:191], v[56:59]
	v_mfma_f32_16x16x32_bf16 v[52:55], v[162:165], v[196:199], v[52:55]
	v_mfma_f32_16x16x32_bf16 v[48:51], v[176:179], v[196:199], v[48:51]
	v_mfma_f32_16x16x32_bf16 v[44:47], v[162:165], v[204:207], v[44:47]
	v_mfma_f32_16x16x32_bf16 v[40:43], v[176:179], v[204:207], v[40:43]
	v_mfma_f32_16x16x32_bf16 v[36:39], v[162:165], v[212:215], v[36:39]
	v_mfma_f32_16x16x32_bf16 v[32:35], v[176:179], v[212:215], v[32:35]
	s_setprio 0
	s_barrier
	s_add_i32 s4, s50, s26
	v_lshl_add_u64 v[144:145], s[38:39], 0, v[148:149]
	s_mov_b32 m0, s4
	ds_read_b128 v[180:183], v171 offset:16384
	ds_read_b128 v[188:191], v171 offset:17408
	ds_read_b128 v[192:195], v171 offset:18432
	ds_read_b128 v[196:199], v171 offset:19456
	ds_read_b128 v[200:203], v171 offset:20480
	ds_read_b128 v[204:207], v171 offset:21504
	ds_read_b128 v[208:211], v171 offset:22528
	ds_read_b128 v[212:215], v171 offset:23552
	global_load_lds_dwordx4 v[144:145], off
	s_add_i32 m0, s4, 0x2000
	s_add_u32 s4, s38, 0xb0000
	v_lshl_add_u64 v[166:167], s[38:39], 0, v[152:153]
	s_addc_u32 s5, s39, 0
	s_add_i32 s76, s51, s26
	global_load_lds_dwordx4 v[166:167], off
	v_lshl_add_u64 v[184:185], s[4:5], 0, v[148:149]
	s_mov_b32 m0, s76
	v_lshl_add_u64 v[186:187], s[40:41], 0, v[150:151]
	global_load_lds_dwordx4 v[184:185], off
	v_lshl_add_u64 v[184:185], s[4:5], 0, v[152:153]
	s_add_i32 m0, s76, 0x2000
	s_nop 0
	global_load_lds_dwordx4 v[184:185], off
	v_lshl_add_u64 v[184:185], s[40:41], 0, v[146:147]
	s_mov_b32 m0, s42
	s_nop 0
	global_load_lds_dwordx4 v[184:185], off
	s_mov_b32 m0, s43
	s_nop 0
	global_load_lds_dwordx4 v[186:187], off
	s_cmp_lg_u32 s100, 0
	s_cbranch_scc0 .Lrf_850_1
	s_waitcnt vmcnt(16)
	s_branch .Lrj_850_1

; #define G_STAGE(bufoff, gbase, voff) do { _Pragma("unroll") for (int _i = 0; _i < 2; ++_i) \
;         __builtin_amdgcn_global_load_lds((const unsigned*)((const char*)(gbase) + voff[_i]), (LAS unsigned*)(lds + (bufoff) + ldsw + _i * 8192), 16, 0, 0); } while (0)
; #define G_LDA(dst, b, h) do { _Pragma("unroll") for (int m = 0; m < 4; ++m) _Pragma("unroll") for (int k = 0; k < 2; ++k) dst[m][k] = *(const LAS bf16x8*)(lds + G_SA(b, h) + aoff + m * 2048 + k * 1024); } while (0)
; #define G_LDB(dst, b, h) do { _Pragma("unroll") for (int n = 0; n < 2; ++n) _Pragma("unroll") for (int k = 0; k < 2; ++k) dst[n][k] = *(const LAS bf16x8*)(lds + G_SB(b, h) + boff + n * 2048 + k * 1024); } while (0)
; #define G_MMA(ai, bj, At_, Bt_) do { __builtin_amdgcn_s_setprio(1); _Pragma("unroll") for (int m = 0; m < 4; ++m) _Pragma("unroll") for (int n = 0; n < 2; ++n) _Pragma("unroll") for (int k = 0; k < 2; ++k) \
;         acc[ai][bj][m][n] = __builtin_amdgcn_mfma_f32_16x16x32_bf16(Bt_[n][k], At_[m][k], acc[ai][bj][m][n], 0, 0, 0); __builtin_amdgcn_s_setprio(0); } while (0)
; #define WAIT_V(n) asm volatile("s_waitcnt vmcnt(" #n ")" ::: "memory")
; #define WAIT_L(n) asm volatile("s_waitcnt lgkmcnt(" #n ")" ::: "memory")
; #define BAR __builtin_amdgcn_s_barrier()
; #define SCHED __builtin_amdgcn_sched_barrier(0)
; template <class Get, class Epi>
; DI void gemm_loop(int ntiles, int ld, char* shm, const Get& get, const Epi& epi) {
;     ...
;             WAIT_V(8); WAIT_L(0); BAR; G_MMA(1, 0, At, B0); G_MMA(1, 1, At, B1); BAR; SCHED;
;             G_LDB(B0, 1, 0); G_LDB(B1, 1, 1); SCHED; G_LDA(At, 1, 0); G_STAGE(G_SA(0, 1), a2 + hstep, voffA);
;             WAIT_V(8); WAIT_L(0); BAR; G_MMA(0, 0, At, B0); G_MMA(0, 1, At, B1); BAR; SCHED;
.Lrj_850_1:
	s_waitcnt lgkmcnt(0)
	s_barrier
	s_setprio 1
	s_waitcnt lgkmcnt(0)
	v_mfma_f32_16x16x32_bf16 v[92:95], v[128:131], v[180:183], 0
	v_mfma_f32_16x16x32_bf16 v[88:91], v[136:139], v[180:183], 0
	v_mfma_f32_16x16x32_bf16 v[84:87], v[128:131], v[192:195], 0
	v_mfma_f32_16x16x32_bf16 v[80:83], v[136:139], v[192:195], 0
	v_mfma_f32_16x16x32_bf16 v[76:79], v[128:131], v[200:203], 0
	v_mfma_f32_16x16x32_bf16 v[72:75], v[136:139], v[200:203], 0
	v_mfma_f32_16x16x32_bf16 v[68:71], v[128:131], v[208:211], 0
	v_mfma_f32_16x16x32_bf16 v[64:67], v[136:139], v[208:211], 0
	s_setprio 0
	s_setprio 1
	v_mfma_f32_16x16x32_bf16 v[92:95], v[132:135], v[188:191], v[92:95]
	v_mfma_f32_16x16x32_bf16 v[88:91], v[140:143], v[188:191], v[88:91]
	v_mfma_f32_16x16x32_bf16 v[84:87], v[132:135], v[196:199], v[84:87]
	v_mfma_f32_16x16x32_bf16 v[80:83], v[140:143], v[196:199], v[80:83]
	v_mfma_f32_16x16x32_bf16 v[76:79], v[132:135], v[204:207], v[76:79]
	v_mfma_f32_16x16x32_bf16 v[72:75], v[140:143], v[204:207], v[72:75]
	v_mfma_f32_16x16x32_bf16 v[68:71], v[132:135], v[212:215], v[68:71]
	v_mfma_f32_16x16x32_bf16 v[64:67], v[140:143], v[212:215], v[64:67]
	s_setprio 0
	s_setprio 1
	v_mfma_f32_16x16x32_bf16 v[28:31], v[158:161], v[180:183], 0
	v_mfma_f32_16x16x32_bf16 v[24:27], v[172:175], v[180:183], 0
	v_mfma_f32_16x16x32_bf16 v[20:23], v[158:161], v[192:195], 0
	v_mfma_f32_16x16x32_bf16 v[16:19], v[172:175], v[192:195], 0
	v_mfma_f32_16x16x32_bf16 v[12:15], v[158:161], v[200:203], 0
	v_mfma_f32_16x16x32_bf16 v[8:11], v[172:175], v[200:203], 0
	v_mfma_f32_16x16x32_bf16 v[4:7], v[158:161], v[208:211], 0
	v_mfma_f32_16x16x32_bf16 v[0:3], v[172:175], v[208:211], 0
	s_setprio 0
	s_setprio 1
	v_mfma_f32_16x16x32_bf16 v[28:31], v[162:165], v[188:191], v[28:31]
	v_mfma_f32_16x16x32_bf16 v[24:27], v[176:179], v[188:191], v[24:27]
	v_mfma_f32_16x16x32_bf16 v[20:23], v[162:165], v[196:199], v[20:23]
	v_mfma_f32_16x16x32_bf16 v[16:19], v[176:179], v[196:199], v[16:19]
	v_mfma_f32_16x16x32_bf16 v[12:15], v[162:165], v[204:207], v[12:15]
	v_mfma_f32_16x16x32_bf16 v[8:11], v[176:179], v[204:207], v[8:11]
	v_mfma_f32_16x16x32_bf16 v[4:7], v[162:165], v[212:215], v[4:7]
	v_mfma_f32_16x16x32_bf16 v[0:3], v[176:179], v[212:215], v[0:3]
	s_setprio 0
	s_barrier
	s_add_i32 s76, 0, 0x18000
	s_add_i32 s78, 0, 0x1c000
	v_add_u32_e32 v140, s76, v168
	v_add_u32_e32 v176, s78, v168
	ds_read_b128 v[128:131], v140
	ds_read_b128 v[132:135], v140 offset:1024
	ds_read_b128 v[136:139], v140 offset:2048
	ds_read_b128 v[140:143], v140 offset:3072
	ds_read_b128 v[158:161], v176
	ds_read_b128 v[162:165], v176 offset:1024
	ds_read_b128 v[172:175], v176 offset:2048
	ds_read_b128 v[176:179], v176 offset:3072
	s_add_u32 s4, s40, 0xb0000
	s_addc_u32 s5, s41, 0
	s_mov_b32 m0, s44
	v_lshl_add_u64 v[216:217], s[4:5], 0, v[146:147]
	ds_read_b128 v[180:183], v171 offset:32768
	ds_read_b128 v[188:191], v171 offset:33792
	ds_read_b128 v[192:195], v171 offset:34816
	ds_read_b128 v[196:199], v171 offset:35840
	ds_read_b128 v[200:203], v171 offset:36864
	ds_read_b128 v[204:207], v171 offset:37888
	ds_read_b128 v[208:211], v171 offset:38912
	ds_read_b128 v[212:215], v171 offset:39936
	global_load_lds_dwordx4 v[216:217], off
	v_lshl_add_u64 v[216:217], s[4:5], 0, v[150:151]
	s_mov_b32 m0, s45
	s_nop 0
	global_load_lds_dwordx4 v[216:217], off
	s_waitcnt vmcnt(8)
	s_waitcnt lgkmcnt(0)
	s_barrier
	s_setprio 1
	s_waitcnt lgkmcnt(0)
	v_mfma_f32_16x16x32_bf16 v[124:127], v[128:131], v[180:183], v[124:127]
	v_mfma_f32_16x16x32_bf16 v[120:123], v[136:139], v[180:183], v[120:123]
	v_mfma_f32_16x16x32_bf16 v[116:119], v[128:131], v[192:195], v[116:119]
	v_mfma_f32_16x16x32_bf16 v[112:115], v[136:139], v[192:195], v[112:115]
	v_mfma_f32_16x16x32_bf16 v[108:111], v[128:131], v[200:203], v[108:111]
	v_mfma_f32_16x16x32_bf16 v[104:107], v[136:139], v[200:203], v[104:107]
	v_mfma_f32_16x16x32_bf16 v[100:103], v[128:131], v[208:211], v[100:103]
	v_mfma_f32_16x16x32_bf16 v[96:99], v[136:139], v[208:211], v[96:99]
	s_setprio 0
	s_setprio 1
	v_mfma_f32_16x16x32_bf16 v[124:127], v[132:135], v[188:191], v[124:127]
	v_mfma_f32_16x16x32_bf16 v[120:123], v[140:143], v[188:191], v[120:123]
	v_mfma_f32_16x16x32_bf16 v[116:119], v[132:135], v[196:199], v[116:119]
	v_mfma_f32_16x16x32_bf16 v[112:115], v[140:143], v[196:199], v[112:115]
	v_mfma_f32_16x16x32_bf16 v[108:111], v[132:135], v[204:207], v[108:111]
	v_mfma_f32_16x16x32_bf16 v[104:107], v[140:143], v[204:207], v[104:107]
	v_mfma_f32_16x16x32_bf16 v[100:103], v[132:135], v[212:215], v[100:103]
	v_mfma_f32_16x16x32_bf16 v[96:99], v[140:143], v[212:215], v[96:99]
	s_setprio 0
	s_setprio 1
	v_mfma_f32_16x16x32_bf16 v[60:63], v[158:161], v[180:183], v[60:63]
	v_mfma_f32_16x16x32_bf16 v[56:59], v[172:175], v[180:183], v[56:59]
	v_mfma_f32_16x16x32_bf16 v[52:55], v[158:161], v[192:195], v[52:55]
	v_mfma_f32_16x16x32_bf16 v[48:51], v[172:175], v[192:195], v[48:51]
	v_mfma_f32_16x16x32_bf16 v[44:47], v[158:161], v[200:203], v[44:47]
	v_mfma_f32_16x16x32_bf16 v[40:43], v[172:175], v[200:203], v[40:43]
	v_mfma_f32_16x16x32_bf16 v[36:39], v[158:161], v[208:211], v[36:39]
	v_mfma_f32_16x16x32_bf16 v[32:35], v[172:175], v[208:211], v[32:35]
	s_setprio 0
	s_setprio 1
	v_mfma_f32_16x16x32_bf16 v[60:63], v[162:165], v[188:191], v[60:63]
	v_mfma_f32_16x16x32_bf16 v[56:59], v[176:179], v[188:191], v[56:59]
	v_mfma_f32_16x16x32_bf16 v[52:55], v[162:165], v[196:199], v[52:55]
	v_mfma_f32_16x16x32_bf16 v[48:51], v[176:179], v[196:199], v[48:51]
	v_mfma_f32_16x16x32_bf16 v[44:47], v[162:165], v[204:207], v[44:47]
	v_mfma_f32_16x16x32_bf16 v[40:43], v[176:179], v[204:207], v[40:43]
	v_mfma_f32_16x16x32_bf16 v[36:39], v[162:165], v[212:215], v[36:39]
	v_mfma_f32_16x16x32_bf16 v[32:35], v[176:179], v[212:215], v[32:35]
	s_setprio 0
	s_barrier
; #define G_STAGE(bufoff, gbase, voff) do { _Pragma("unroll") for (int _i = 0; _i < 2; ++_i) \
;         __builtin_amdgcn_global_load_lds((const unsigned*)((const char*)(gbase) + voff[_i]), (LAS unsigned*)(lds + (bufoff) + ldsw + _i * 8192), 16, 0, 0); } while (0)
; #define G_LDA(dst, b, h) do { _Pragma("unroll") for (int m = 0; m < 4; ++m) _Pragma("unroll") for (int k = 0; k < 2; ++k) dst[m][k] = *(const LAS bf16x8*)(lds + G_SA(b, h) + aoff + m * 2048 + k * 1024); } while (0)
; #define G_LDB(dst, b, h) do { _Pragma("unroll") for (int n = 0; n < 2; ++n) _Pragma("unroll") for (int k = 0; k < 2; ++k) dst[n][k] = *(const LAS bf16x8*)(lds + G_SB(b, h) + boff + n * 2048 + k * 1024); } while (0)
; #define WAIT_V(n) asm volatile("s_waitcnt vmcnt(" #n ")" ::: "memory")
; #define WAIT_L(n) asm volatile("s_waitcnt lgkmcnt(" #n ")" ::: "memory")
; #define BAR __builtin_amdgcn_s_barrier()
; #define SCHED __builtin_amdgcn_sched_barrier(0)
; template <class Get, class Epi>
; DI void gemm_loop(int ntiles, int ld, char* shm, const Get& get, const Epi& epi) {
;     ...
;         for (int t = 0; t < nt; t += 2) {
;             const bool last = (t == nt - 2);
;             const char* a1 = cA + (size_t)(t + 1) * kstep;
;             const char* a2 = last ? nA : cA + (size_t)(t + 2) * kstep; const char* b2 = last ? nB : cB + (size_t)(t + 2) * kstep;
;             const char* a3 = a2 + kstep; const char* b3 = b2 + kstep;
;             G_LDB(B0, 0, 0); G_LDB(B1, 0, 1); SCHED; G_LDA(At, 0, 0); G_STAGE(G_SA(1, 1), a1 + hstep, voffA);
;             WAIT_V(8); WAIT_L(0); BAR; G_MMA(0, 0, At, B0); G_MMA(0, 1, At, B1); BAR; SCHED;
;             G_LDA(At, 0, 1); G_STAGE(G_SB(0, 0), b2, voffB); G_STAGE(G_SB(0, 1), b2 + hstep, voffB); G_STAGE(G_SA(0, 0), a2, voffA);
;             WAIT_V(8); WAIT_L(0); BAR; G_MMA(1, 0, At, B0); G_MMA(1, 1, At, B1); BAR; SCHED;
;             G_LDB(B0, 1, 0); G_LDB(B1, 1, 1); SCHED; G_LDA(At, 1, 0); G_STAGE(G_SA(0, 1), a2 + hstep, voffA);
;             WAIT_V(8); WAIT_L(0); BAR; G_MMA(0, 0, At, B0); G_MMA(0, 1, At, B1); BAR; SCHED;
;             G_LDA(At, 1, 1); G_STAGE(G_SB(1, 0), b3, voffB); G_STAGE(G_SB(1, 1), b3 + hstep, voffB); G_STAGE(G_SA(1, 0), a3, voffA);
;             WAIT_V(8); WAIT_L(0); BAR; G_MMA(1, 0, At, B0); G_MMA(1, 1, At, B1); BAR; SCHED;
	s_add_i32 s4, s76, s26
	v_lshl_add_u64 v[144:145], v[144:145], 0, s[10:11]
	s_mov_b32 m0, s4
	ds_read_b128 v[180:183], v171 offset:49152
	ds_read_b128 v[188:191], v171 offset:50176
	ds_read_b128 v[192:195], v171 offset:51200
	ds_read_b128 v[196:199], v171 offset:52224
	ds_read_b128 v[200:203], v171 offset:53248
	ds_read_b128 v[204:207], v171 offset:54272
	ds_read_b128 v[208:211], v171 offset:55296
	ds_read_b128 v[212:215], v171 offset:56320
	global_load_lds_dwordx4 v[144:145], off
	s_add_i32 m0, s4, 0x2000
	s_add_u32 s4, s38, 0xb0080
	v_lshl_add_u64 v[144:145], v[166:167], 0, s[10:11]
	s_addc_u32 s5, s39, 0
	s_add_i32 s38, s78, s26
	global_load_lds_dwordx4 v[144:145], off
	v_lshl_add_u64 v[144:145], s[4:5], 0, v[148:149]
	s_mov_b32 m0, s38
	s_nop 0
	global_load_lds_dwordx4 v[144:145], off
	v_lshl_add_u64 v[144:145], s[4:5], 0, v[152:153]
	s_add_i32 m0, s38, 0x2000
	s_nop 0
	global_load_lds_dwordx4 v[144:145], off
	v_lshl_add_u64 v[144:145], v[184:185], 0, s[10:11]
	s_mov_b32 m0, s48
	s_nop 0
	global_load_lds_dwordx4 v[144:145], off
	v_lshl_add_u64 v[144:145], v[186:187], 0, s[10:11]
	s_mov_b32 m0, s49
	s_nop 0
	global_load_lds_dwordx4 v[144:145], off
	s_waitcnt vmcnt(8)
	s_waitcnt lgkmcnt(0)
	s_barrier
	s_setprio 1
	s_waitcnt lgkmcnt(0)
	v_mfma_f32_16x16x32_bf16 v[92:95], v[128:131], v[180:183], v[92:95]
	v_mfma_f32_16x16x32_bf16 v[88:91], v[136:139], v[180:183], v[88:91]
	v_mfma_f32_16x16x32_bf16 v[84:87], v[128:131], v[192:195], v[84:87]
	v_mfma_f32_16x16x32_bf16 v[80:83], v[136:139], v[192:195], v[80:83]
	v_mfma_f32_16x16x32_bf16 v[76:79], v[128:131], v[200:203], v[76:79]
	v_mfma_f32_16x16x32_bf16 v[72:75], v[136:139], v[200:203], v[72:75]
	v_mfma_f32_16x16x32_bf16 v[68:71], v[128:131], v[208:211], v[68:71]
	v_mfma_f32_16x16x32_bf16 v[64:67], v[136:139], v[208:211], v[64:67]
	s_setprio 0
	s_setprio 1
	v_mfma_f32_16x16x32_bf16 v[92:95], v[132:135], v[188:191], v[92:95]
	v_mfma_f32_16x16x32_bf16 v[88:91], v[140:143], v[188:191], v[88:91]
	v_mfma_f32_16x16x32_bf16 v[84:87], v[132:135], v[196:199], v[84:87]
	v_mfma_f32_16x16x32_bf16 v[80:83], v[140:143], v[196:199], v[80:83]
	v_mfma_f32_16x16x32_bf16 v[76:79], v[132:135], v[204:207], v[76:79]
	v_mfma_f32_16x16x32_bf16 v[72:75], v[140:143], v[204:207], v[72:75]
	v_mfma_f32_16x16x32_bf16 v[68:71], v[132:135], v[212:215], v[68:71]
	v_mfma_f32_16x16x32_bf16 v[64:67], v[140:143], v[212:215], v[64:67]
	s_setprio 0
	s_setprio 1
	v_mfma_f32_16x16x32_bf16 v[28:31], v[158:161], v[180:183], v[28:31]
	v_mfma_f32_16x16x32_bf16 v[24:27], v[172:175], v[180:183], v[24:27]
	v_mfma_f32_16x16x32_bf16 v[20:23], v[158:161], v[192:195], v[20:23]
	v_mfma_f32_16x16x32_bf16 v[16:19], v[172:175], v[192:195], v[16:19]
	v_mfma_f32_16x16x32_bf16 v[12:15], v[158:161], v[200:203], v[12:15]
	v_mfma_f32_16x16x32_bf16 v[8:11], v[172:175], v[200:203], v[8:11]
	v_mfma_f32_16x16x32_bf16 v[4:7], v[158:161], v[208:211], v[4:7]
	v_mfma_f32_16x16x32_bf16 v[0:3], v[172:175], v[208:211], v[0:3]
	s_setprio 0
	s_setprio 1
	v_mfma_f32_16x16x32_bf16 v[28:31], v[162:165], v[188:191], v[28:31]
	v_mfma_f32_16x16x32_bf16 v[24:27], v[176:179], v[188:191], v[24:27]
	v_mfma_f32_16x16x32_bf16 v[20:23], v[162:165], v[196:199], v[20:23]
	v_mfma_f32_16x16x32_bf16 v[16:19], v[176:179], v[196:199], v[16:19]
	v_mfma_f32_16x16x32_bf16 v[12:15], v[162:165], v[204:207], v[12:15]
	v_mfma_f32_16x16x32_bf16 v[8:11], v[176:179], v[204:207], v[8:11]
	v_mfma_f32_16x16x32_bf16 v[4:7], v[162:165], v[212:215], v[4:7]
	v_mfma_f32_16x16x32_bf16 v[0:3], v[176:179], v[212:215], v[0:3]
	s_setprio 0
	s_barrier
	s_add_u32 s73, s73, 0x100
	s_addc_u32 s74, s74, 0
	s_cmp_ge_u32 s75, s59
	s_mov_b64 s[4:5], s[14:15]
	s_mov_b32 s38, s75
	s_cbranch_scc0 .LBB0_850
	s_branch .Lpost_850
.LBB0_850:
	ds_read_b128 v[128:131], v169
	ds_read_b128 v[132:135], v169 offset:1024
	ds_read_b128 v[136:139], v169 offset:2048
	ds_read_b128 v[140:143], v169 offset:3072
	ds_read_b128 v[158:161], v170
	ds_read_b128 v[162:165], v170 offset:1024
	ds_read_b128 v[172:175], v170 offset:2048
	ds_read_b128 v[176:179], v170 offset:3072
	s_add_i32 s75, s38, 2
	s_add_u32 s14, s4, 0x100
	s_addc_u32 s15, s5, 0
	s_cmp_eq_u32 s72, s38
	s_cselect_b32 s38, s36, s73
	s_cselect_b32 s41, s35, s15
	s_cselect_b32 s40, s34, s14
	s_cselect_b32 s39, s37, s74
	v_lshl_add_u64 v[144:145], s[4:5], 0, v[154:155]
	s_add_i32 m0, s42, 0xc000
	ds_read_b128 v[180:183], v171
	ds_read_b128 v[188:191], v171 offset:1024
	ds_read_b128 v[192:195], v171 offset:2048
	ds_read_b128 v[196:199], v171 offset:3072
	ds_read_b128 v[200:203], v171 offset:4096
	ds_read_b128 v[204:207], v171 offset:5120
	ds_read_b128 v[208:211], v171 offset:6144
	ds_read_b128 v[212:215], v171 offset:7168
	global_load_lds_dwordx4 v[144:145], off
	v_lshl_add_u64 v[144:145], s[4:5], 0, v[156:157]
	s_add_i32 m0, s42, 0xe000
	s_nop 0
	global_load_lds_dwordx4 v[144:145], off
	s_waitcnt vmcnt(8)
	s_waitcnt lgkmcnt(0)
	s_barrier
; #define G_STAGE(bufoff, gbase, voff) do { _Pragma("unroll") for (int _i = 0; _i < 2; ++_i) \
;         __builtin_amdgcn_global_load_lds((const unsigned*)((const char*)(gbase) + voff[_i]), (LAS unsigned*)(lds + (bufoff) + ldsw + _i * 8192), 16, 0, 0); } while (0)
; #define G_LDA(dst, b, h) do { _Pragma("unroll") for (int m = 0; m < 4; ++m) _Pragma("unroll") for (int k = 0; k < 2; ++k) dst[m][k] = *(const LAS bf16x8*)(lds + G_SA(b, h) + aoff + m * 2048 + k * 1024); } while (0)
; #define G_MMA(ai, bj, At_, Bt_) do { __builtin_amdgcn_s_setprio(1); _Pragma("unroll") for (int m = 0; m < 4; ++m) _Pragma("unroll") for (int n = 0; n < 2; ++n) _Pragma("unroll") for (int k = 0; k < 2; ++k) \
;         acc[ai][bj][m][n] = __builtin_amdgcn_mfma_f32_16x16x32_bf16(Bt_[n][k], At_[m][k], acc[ai][bj][m][n], 0, 0, 0); __builtin_amdgcn_s_setprio(0); } while (0)
; #define WAIT_V(n) asm volatile("s_waitcnt vmcnt(" #n ")" ::: "memory")
; #define WAIT_L(n) asm volatile("s_waitcnt lgkmcnt(" #n ")" ::: "memory")
; #define BAR __builtin_amdgcn_s_barrier()
; #define SCHED __builtin_amdgcn_sched_barrier(0)
; template <class Get, class Epi>
; DI void gemm_loop(int ntiles, int ld, char* shm, const Get& get, const Epi& epi) {
;     ...
;             WAIT_V(8); WAIT_L(0); BAR; G_MMA(0, 0, At, B0); G_MMA(0, 1, At, B1); BAR; SCHED;
;             G_LDA(At, 0, 1); G_STAGE(G_SB(0, 0), b2, voffB); G_STAGE(G_SB(0, 1), b2 + hstep, voffB); G_STAGE(G_SA(0, 0), a2, voffA);
;             WAIT_V(8); WAIT_L(0); BAR; G_MMA(1, 0, At, B0); G_MMA(1, 1, At, B1); BAR; SCHED;
	s_setprio 1
	s_waitcnt lgkmcnt(0)
	v_mfma_f32_16x16x32_bf16 v[124:127], v[128:131], v[180:183], v[124:127]
	v_mfma_f32_16x16x32_bf16 v[120:123], v[136:139], v[180:183], v[120:123]
	v_mfma_f32_16x16x32_bf16 v[116:119], v[128:131], v[192:195], v[116:119]
	v_mfma_f32_16x16x32_bf16 v[112:115], v[136:139], v[192:195], v[112:115]
	v_mfma_f32_16x16x32_bf16 v[108:111], v[128:131], v[200:203], v[108:111]
	v_mfma_f32_16x16x32_bf16 v[104:107], v[136:139], v[200:203], v[104:107]
	v_mfma_f32_16x16x32_bf16 v[100:103], v[128:131], v[208:211], v[100:103]
	v_mfma_f32_16x16x32_bf16 v[96:99], v[136:139], v[208:211], v[96:99]
	s_setprio 0
	s_setprio 1
	v_mfma_f32_16x16x32_bf16 v[124:127], v[132:135], v[188:191], v[124:127]
	v_mfma_f32_16x16x32_bf16 v[120:123], v[140:143], v[188:191], v[120:123]
	v_mfma_f32_16x16x32_bf16 v[116:119], v[132:135], v[196:199], v[116:119]
	v_mfma_f32_16x16x32_bf16 v[112:115], v[140:143], v[196:199], v[112:115]
	v_mfma_f32_16x16x32_bf16 v[108:111], v[132:135], v[204:207], v[108:111]
	v_mfma_f32_16x16x32_bf16 v[104:107], v[140:143], v[204:207], v[104:107]
	v_mfma_f32_16x16x32_bf16 v[100:103], v[132:135], v[212:215], v[100:103]
	v_mfma_f32_16x16x32_bf16 v[96:99], v[140:143], v[212:215], v[96:99]
	s_setprio 0
	s_setprio 1
	v_mfma_f32_16x16x32_bf16 v[60:63], v[158:161], v[180:183], v[60:63]
	v_mfma_f32_16x16x32_bf16 v[56:59], v[172:175], v[180:183], v[56:59]
	v_mfma_f32_16x16x32_bf16 v[52:55], v[158:161], v[192:195], v[52:55]
	v_mfma_f32_16x16x32_bf16 v[48:51], v[172:175], v[192:195], v[48:51]
	v_mfma_f32_16x16x32_bf16 v[44:47], v[158:161], v[200:203], v[44:47]
	v_mfma_f32_16x16x32_bf16 v[40:43], v[172:175], v[200:203], v[40:43]
	v_mfma_f32_16x16x32_bf16 v[36:39], v[158:161], v[208:211], v[36:39]
	v_mfma_f32_16x16x32_bf16 v[32:35], v[172:175], v[208:211], v[32:35]
	s_setprio 0
	s_setprio 1
	v_mfma_f32_16x16x32_bf16 v[60:63], v[162:165], v[188:191], v[60:63]
	v_mfma_f32_16x16x32_bf16 v[56:59], v[176:179], v[188:191], v[56:59]
	v_mfma_f32_16x16x32_bf16 v[52:55], v[162:165], v[196:199], v[52:55]
	v_mfma_f32_16x16x32_bf16 v[48:51], v[176:179], v[196:199], v[48:51]
	v_mfma_f32_16x16x32_bf16 v[44:47], v[162:165], v[204:207], v[44:47]
	v_mfma_f32_16x16x32_bf16 v[40:43], v[176:179], v[204:207], v[40:43]
	v_mfma_f32_16x16x32_bf16 v[36:39], v[162:165], v[212:215], v[36:39]
	v_mfma_f32_16x16x32_bf16 v[32:35], v[176:179], v[212:215], v[32:35]
	s_setprio 0
	s_barrier
	s_add_i32 s4, s50, s26
	v_lshl_add_u64 v[144:145], s[38:39], 0, v[148:149]
	s_mov_b32 m0, s4
	ds_read_b128 v[180:183], v171 offset:16384
	ds_read_b128 v[188:191], v171 offset:17408
	ds_read_b128 v[192:195], v171 offset:18432
	ds_read_b128 v[196:199], v171 offset:19456
	ds_read_b128 v[200:203], v171 offset:20480
	ds_read_b128 v[204:207], v171 offset:21504
	ds_read_b128 v[208:211], v171 offset:22528
	ds_read_b128 v[212:215], v171 offset:23552
	global_load_lds_dwordx4 v[144:145], off
	s_add_i32 m0, s4, 0x2000
	s_add_u32 s4, s38, 0xb0000
	v_lshl_add_u64 v[166:167], s[38:39], 0, v[152:153]
	s_addc_u32 s5, s39, 0
	s_add_i32 s76, s51, s26
	global_load_lds_dwordx4 v[166:167], off
	v_lshl_add_u64 v[184:185], s[4:5], 0, v[148:149]
	s_mov_b32 m0, s76
	v_lshl_add_u64 v[186:187], s[40:41], 0, v[150:151]
	global_load_lds_dwordx4 v[184:185], off
	v_lshl_add_u64 v[184:185], s[4:5], 0, v[152:153]
	s_add_i32 m0, s76, 0x2000
	s_nop 0
	global_load_lds_dwordx4 v[184:185], off
	v_lshl_add_u64 v[184:185], s[40:41], 0, v[146:147]
	s_mov_b32 m0, s42
	s_nop 0
	global_load_lds_dwordx4 v[184:185], off
	s_mov_b32 m0, s43
	s_nop 0
	global_load_lds_dwordx4 v[186:187], off
	s_waitcnt vmcnt(8)
	s_waitcnt lgkmcnt(0)
	s_barrier
	s_setprio 1
	s_waitcnt lgkmcnt(0)
	v_mfma_f32_16x16x32_bf16 v[92:95], v[128:131], v[180:183], v[92:95]
	v_mfma_f32_16x16x32_bf16 v[88:91], v[136:139], v[180:183], v[88:91]
	v_mfma_f32_16x16x32_bf16 v[84:87], v[128:131], v[192:195], v[84:87]
	v_mfma_f32_16x16x32_bf16 v[80:83], v[136:139], v[192:195], v[80:83]
	v_mfma_f32_16x16x32_bf16 v[76:79], v[128:131], v[200:203], v[76:79]
	v_mfma_f32_16x16x32_bf16 v[72:75], v[136:139], v[200:203], v[72:75]
	v_mfma_f32_16x16x32_bf16 v[68:71], v[128:131], v[208:211], v[68:71]
	v_mfma_f32_16x16x32_bf16 v[64:67], v[136:139], v[208:211], v[64:67]
	s_setprio 0
	s_setprio 1
	v_mfma_f32_16x16x32_bf16 v[92:95], v[132:135], v[188:191], v[92:95]
	v_mfma_f32_16x16x32_bf16 v[88:91], v[140:143], v[188:191], v[88:91]
	v_mfma_f32_16x16x32_bf16 v[84:87], v[132:135], v[196:199], v[84:87]
	v_mfma_f32_16x16x32_bf16 v[80:83], v[140:143], v[196:199], v[80:83]
	v_mfma_f32_16x16x32_bf16 v[76:79], v[132:135], v[204:207], v[76:79]
	v_mfma_f32_16x16x32_bf16 v[72:75], v[140:143], v[204:207], v[72:75]
	v_mfma_f32_16x16x32_bf16 v[68:71], v[132:135], v[212:215], v[68:71]
	v_mfma_f32_16x16x32_bf16 v[64:67], v[140:143], v[212:215], v[64:67]
	s_setprio 0
	s_setprio 1
	v_mfma_f32_16x16x32_bf16 v[28:31], v[158:161], v[180:183], v[28:31]
	v_mfma_f32_16x16x32_bf16 v[24:27], v[172:175], v[180:183], v[24:27]
	v_mfma_f32_16x16x32_bf16 v[20:23], v[158:161], v[192:195], v[20:23]
	v_mfma_f32_16x16x32_bf16 v[16:19], v[172:175], v[192:195], v[16:19]
	v_mfma_f32_16x16x32_bf16 v[12:15], v[158:161], v[200:203], v[12:15]
	v_mfma_f32_16x16x32_bf16 v[8:11], v[172:175], v[200:203], v[8:11]
	v_mfma_f32_16x16x32_bf16 v[4:7], v[158:161], v[208:211], v[4:7]
	v_mfma_f32_16x16x32_bf16 v[0:3], v[172:175], v[208:211], v[0:3]
	s_setprio 0
	s_setprio 1
	v_mfma_f32_16x16x32_bf16 v[28:31], v[162:165], v[188:191], v[28:31]
	v_mfma_f32_16x16x32_bf16 v[24:27], v[176:179], v[188:191], v[24:27]
	v_mfma_f32_16x16x32_bf16 v[20:23], v[162:165], v[196:199], v[20:23]
	v_mfma_f32_16x16x32_bf16 v[16:19], v[176:179], v[196:199], v[16:19]
	v_mfma_f32_16x16x32_bf16 v[12:15], v[162:165], v[204:207], v[12:15]
	v_mfma_f32_16x16x32_bf16 v[8:11], v[176:179], v[204:207], v[8:11]
	v_mfma_f32_16x16x32_bf16 v[4:7], v[162:165], v[212:215], v[4:7]
	v_mfma_f32_16x16x32_bf16 v[0:3], v[176:179], v[212:215], v[0:3]
	s_setprio 0
	s_barrier
; #define G_STAGE(bufoff, gbase, voff) do { _Pragma("unroll") for (int _i = 0; _i < 2; ++_i) \
;         __builtin_amdgcn_global_load_lds((const unsigned*)((const char*)(gbase) + voff[_i]), (LAS unsigned*)(lds + (bufoff) + ldsw + _i * 8192), 16, 0, 0); } while (0)
; #define G_LDA(dst, b, h) do { _Pragma("unroll") for (int m = 0; m < 4; ++m) _Pragma("unroll") for (int k = 0; k < 2; ++k) dst[m][k] = *(const LAS bf16x8*)(lds + G_SA(b, h) + aoff + m * 2048 + k * 1024); } while (0)
; #define G_LDB(dst, b, h) do { _Pragma("unroll") for (int n = 0; n < 2; ++n) _Pragma("unroll") for (int k = 0; k < 2; ++k) dst[n][k] = *(const LAS bf16x8*)(lds + G_SB(b, h) + boff + n * 2048 + k * 1024); } while (0)
; #define G_MMA(ai, bj, At_, Bt_) do { __builtin_amdgcn_s_setprio(1); _Pragma("unroll") for (int m = 0; m < 4; ++m) _Pragma("unroll") for (int n = 0; n < 2; ++n) _Pragma("unroll") for (int k = 0; k < 2; ++k) \
;         acc[ai][bj][m][n] = __builtin_amdgcn_mfma_f32_16x16x32_bf16(Bt_[n][k], At_[m][k], acc[ai][bj][m][n], 0, 0, 0); __builtin_amdgcn_s_setprio(0); } while (0)
; #define WAIT_V(n) asm volatile("s_waitcnt vmcnt(" #n ")" ::: "memory")
; #define WAIT_L(n) asm volatile("s_waitcnt lgkmcnt(" #n ")" ::: "memory")
; #define BAR __builtin_amdgcn_s_barrier()
; #define SCHED __builtin_amdgcn_sched_barrier(0)
; template <class Get, class Epi>
; DI void gemm_loop(int ntiles, int ld, char* shm, const Get& get, const Epi& epi) {
;     ...
;             G_LDB(B0, 1, 0); G_LDB(B1, 1, 1); SCHED; G_LDA(At, 1, 0); G_STAGE(G_SA(0, 1), a2 + hstep, voffA);
;             WAIT_V(8); WAIT_L(0); BAR; G_MMA(0, 0, At, B0); G_MMA(0, 1, At, B1); BAR; SCHED;
	s_add_i32 s76, 0, 0x18000
	s_add_i32 s78, 0, 0x1c000
	v_add_u32_e32 v140, s76, v168
	v_add_u32_e32 v176, s78, v168
	ds_read_b128 v[128:131], v140
	ds_read_b128 v[132:135], v140 offset:1024
	ds_read_b128 v[136:139], v140 offset:2048
	ds_read_b128 v[140:143], v140 offset:3072
	ds_read_b128 v[158:161], v176
	ds_read_b128 v[162:165], v176 offset:1024
	ds_read_b128 v[172:175], v176 offset:2048
	ds_read_b128 v[176:179], v176 offset:3072
	s_add_u32 s4, s40, 0xb0000
	s_addc_u32 s5, s41, 0
	s_mov_b32 m0, s44
	v_lshl_add_u64 v[216:217], s[4:5], 0, v[146:147]
	ds_read_b128 v[180:183], v171 offset:32768
	ds_read_b128 v[188:191], v171 offset:33792
	ds_read_b128 v[192:195], v171 offset:34816
	ds_read_b128 v[196:199], v171 offset:35840
	ds_read_b128 v[200:203], v171 offset:36864
	ds_read_b128 v[204:207], v171 offset:37888
	ds_read_b128 v[208:211], v171 offset:38912
	ds_read_b128 v[212:215], v171 offset:39936
	global_load_lds_dwordx4 v[216:217], off
	v_lshl_add_u64 v[216:217], s[4:5], 0, v[150:151]
	s_mov_b32 m0, s45
	s_nop 0
	global_load_lds_dwordx4 v[216:217], off
	s_waitcnt vmcnt(8)
	s_waitcnt lgkmcnt(0)
	s_barrier
	s_setprio 1
	s_waitcnt lgkmcnt(0)
	v_mfma_f32_16x16x32_bf16 v[124:127], v[128:131], v[180:183], v[124:127]
	v_mfma_f32_16x16x32_bf16 v[120:123], v[136:139], v[180:183], v[120:123]
	v_mfma_f32_16x16x32_bf16 v[116:119], v[128:131], v[192:195], v[116:119]
	v_mfma_f32_16x16x32_bf16 v[112:115], v[136:139], v[192:195], v[112:115]
	v_mfma_f32_16x16x32_bf16 v[108:111], v[128:131], v[200:203], v[108:111]
	v_mfma_f32_16x16x32_bf16 v[104:107], v[136:139], v[200:203], v[104:107]
	v_mfma_f32_16x16x32_bf16 v[100:103], v[128:131], v[208:211], v[100:103]
	v_mfma_f32_16x16x32_bf16 v[96:99], v[136:139], v[208:211], v[96:99]
	s_setprio 0
	s_setprio 1
	v_mfma_f32_16x16x32_bf16 v[124:127], v[132:135], v[188:191], v[124:127]
	v_mfma_f32_16x16x32_bf16 v[120:123], v[140:143], v[188:191], v[120:123]
	v_mfma_f32_16x16x32_bf16 v[116:119], v[132:135], v[196:199], v[116:119]
	v_mfma_f32_16x16x32_bf16 v[112:115], v[140:143], v[196:199], v[112:115]
	v_mfma_f32_16x16x32_bf16 v[108:111], v[132:135], v[204:207], v[108:111]
	v_mfma_f32_16x16x32_bf16 v[104:107], v[140:143], v[204:207], v[104:107]
	v_mfma_f32_16x16x32_bf16 v[100:103], v[132:135], v[212:215], v[100:103]
	v_mfma_f32_16x16x32_bf16 v[96:99], v[140:143], v[212:215], v[96:99]
	s_setprio 0
	s_setprio 1
	v_mfma_f32_16x16x32_bf16 v[60:63], v[158:161], v[180:183], v[60:63]
	v_mfma_f32_16x16x32_bf16 v[56:59], v[172:175], v[180:183], v[56:59]
	v_mfma_f32_16x16x32_bf16 v[52:55], v[158:161], v[192:195], v[52:55]
	v_mfma_f32_16x16x32_bf16 v[48:51], v[172:175], v[192:195], v[48:51]
	v_mfma_f32_16x16x32_bf16 v[44:47], v[158:161], v[200:203], v[44:47]
	v_mfma_f32_16x16x32_bf16 v[40:43], v[172:175], v[200:203], v[40:43]
	v_mfma_f32_16x16x32_bf16 v[36:39], v[158:161], v[208:211], v[36:39]
	v_mfma_f32_16x16x32_bf16 v[32:35], v[172:175], v[208:211], v[32:35]
	s_setprio 0
	s_setprio 1
	v_mfma_f32_16x16x32_bf16 v[60:63], v[162:165], v[188:191], v[60:63]
	v_mfma_f32_16x16x32_bf16 v[56:59], v[176:179], v[188:191], v[56:59]
	v_mfma_f32_16x16x32_bf16 v[52:55], v[162:165], v[196:199], v[52:55]
	v_mfma_f32_16x16x32_bf16 v[48:51], v[176:179], v[196:199], v[48:51]
	v_mfma_f32_16x16x32_bf16 v[44:47], v[162:165], v[204:207], v[44:47]
	v_mfma_f32_16x16x32_bf16 v[40:43], v[176:179], v[204:207], v[40:43]
	v_mfma_f32_16x16x32_bf16 v[36:39], v[162:165], v[212:215], v[36:39]
	v_mfma_f32_16x16x32_bf16 v[32:35], v[176:179], v[212:215], v[32:35]
	s_setprio 0
	s_barrier
; #define G_STAGE(bufoff, gbase, voff) do { _Pragma("unroll") for (int _i = 0; _i < 2; ++_i) \
;         __builtin_amdgcn_global_load_lds((const unsigned*)((const char*)(gbase) + voff[_i]), (LAS unsigned*)(lds + (bufoff) + ldsw + _i * 8192), 16, 0, 0); } while (0)
; #define G_LDA(dst, b, h) do { _Pragma("unroll") for (int m = 0; m < 4; ++m) _Pragma("unroll") for (int k = 0; k < 2; ++k) dst[m][k] = *(const LAS bf16x8*)(lds + G_SA(b, h) + aoff + m * 2048 + k * 1024); } while (0)
; #define G_MMA(ai, bj, At_, Bt_) do { __builtin_amdgcn_s_setprio(1); _Pragma("unroll") for (int m = 0; m < 4; ++m) _Pragma("unroll") for (int n = 0; n < 2; ++n) _Pragma("unroll") for (int k = 0; k < 2; ++k) \
;         acc[ai][bj][m][n] = __builtin_amdgcn_mfma_f32_16x16x32_bf16(Bt_[n][k], At_[m][k], acc[ai][bj][m][n], 0, 0, 0); __builtin_amdgcn_s_setprio(0); } while (0)
; #define WAIT_V(n) asm volatile("s_waitcnt vmcnt(" #n ")" ::: "memory")
; #define WAIT_L(n) asm volatile("s_waitcnt lgkmcnt(" #n ")" ::: "memory")
; #define BAR __builtin_amdgcn_s_barrier()
; #define SCHED __builtin_amdgcn_sched_barrier(0)
; template <class Get, class Epi>
; DI void gemm_loop(int ntiles, int ld, char* shm, const Get& get, const Epi& epi) {
;     ...
;             G_LDA(At, 1, 1); G_STAGE(G_SB(1, 0), b3, voffB); G_STAGE(G_SB(1, 1), b3 + hstep, voffB); G_STAGE(G_SA(1, 0), a3, voffA);
;             WAIT_V(8); WAIT_L(0); BAR; G_MMA(1, 0, At, B0); G_MMA(1, 1, At, B1); BAR; SCHED;
;         }
	s_add_i32 s4, s76, s26
	v_lshl_add_u64 v[144:145], v[144:145], 0, s[10:11]
	s_mov_b32 m0, s4
	ds_read_b128 v[180:183], v171 offset:49152
	ds_read_b128 v[188:191], v171 offset:50176
	ds_read_b128 v[192:195], v171 offset:51200
	ds_read_b128 v[196:199], v171 offset:52224
	ds_read_b128 v[200:203], v171 offset:53248
	ds_read_b128 v[204:207], v171 offset:54272
	ds_read_b128 v[208:211], v171 offset:55296
	ds_read_b128 v[212:215], v171 offset:56320
	global_load_lds_dwordx4 v[144:145], off
	s_add_i32 m0, s4, 0x2000
	s_add_u32 s4, s38, 0xb0080
	v_lshl_add_u64 v[144:145], v[166:167], 0, s[10:11]
	s_addc_u32 s5, s39, 0
	s_add_i32 s38, s78, s26
	global_load_lds_dwordx4 v[144:145], off
	v_lshl_add_u64 v[144:145], s[4:5], 0, v[148:149]
	s_mov_b32 m0, s38
	s_nop 0
	global_load_lds_dwordx4 v[144:145], off
	v_lshl_add_u64 v[144:145], s[4:5], 0, v[152:153]
	s_add_i32 m0, s38, 0x2000
	s_nop 0
	global_load_lds_dwordx4 v[144:145], off
	v_lshl_add_u64 v[144:145], v[184:185], 0, s[10:11]
	s_mov_b32 m0, s48
	s_nop 0
	global_load_lds_dwordx4 v[144:145], off
	v_lshl_add_u64 v[144:145], v[186:187], 0, s[10:11]
	s_mov_b32 m0, s49
	s_nop 0
	global_load_lds_dwordx4 v[144:145], off
	s_waitcnt vmcnt(8)
	s_waitcnt lgkmcnt(0)
	s_barrier
	s_setprio 1
	s_waitcnt lgkmcnt(0)
	v_mfma_f32_16x16x32_bf16 v[92:95], v[128:131], v[180:183], v[92:95]
	v_mfma_f32_16x16x32_bf16 v[88:91], v[136:139], v[180:183], v[88:91]
	v_mfma_f32_16x16x32_bf16 v[84:87], v[128:131], v[192:195], v[84:87]
	v_mfma_f32_16x16x32_bf16 v[80:83], v[136:139], v[192:195], v[80:83]
	v_mfma_f32_16x16x32_bf16 v[76:79], v[128:131], v[200:203], v[76:79]
	v_mfma_f32_16x16x32_bf16 v[72:75], v[136:139], v[200:203], v[72:75]
	v_mfma_f32_16x16x32_bf16 v[68:71], v[128:131], v[208:211], v[68:71]
	v_mfma_f32_16x16x32_bf16 v[64:67], v[136:139], v[208:211], v[64:67]
	s_setprio 0
	s_setprio 1
	v_mfma_f32_16x16x32_bf16 v[92:95], v[132:135], v[188:191], v[92:95]
	v_mfma_f32_16x16x32_bf16 v[88:91], v[140:143], v[188:191], v[88:91]
	v_mfma_f32_16x16x32_bf16 v[84:87], v[132:135], v[196:199], v[84:87]
	v_mfma_f32_16x16x32_bf16 v[80:83], v[140:143], v[196:199], v[80:83]
	v_mfma_f32_16x16x32_bf16 v[76:79], v[132:135], v[204:207], v[76:79]
	v_mfma_f32_16x16x32_bf16 v[72:75], v[140:143], v[204:207], v[72:75]
	v_mfma_f32_16x16x32_bf16 v[68:71], v[132:135], v[212:215], v[68:71]
	v_mfma_f32_16x16x32_bf16 v[64:67], v[140:143], v[212:215], v[64:67]
	s_setprio 0
	s_setprio 1
	v_mfma_f32_16x16x32_bf16 v[28:31], v[158:161], v[180:183], v[28:31]
	v_mfma_f32_16x16x32_bf16 v[24:27], v[172:175], v[180:183], v[24:27]
	v_mfma_f32_16x16x32_bf16 v[20:23], v[158:161], v[192:195], v[20:23]
	v_mfma_f32_16x16x32_bf16 v[16:19], v[172:175], v[192:195], v[16:19]
	v_mfma_f32_16x16x32_bf16 v[12:15], v[158:161], v[200:203], v[12:15]
	v_mfma_f32_16x16x32_bf16 v[8:11], v[172:175], v[200:203], v[8:11]
	v_mfma_f32_16x16x32_bf16 v[4:7], v[158:161], v[208:211], v[4:7]
	v_mfma_f32_16x16x32_bf16 v[0:3], v[172:175], v[208:211], v[0:3]
	s_setprio 0
	s_setprio 1
	v_mfma_f32_16x16x32_bf16 v[28:31], v[162:165], v[188:191], v[28:31]
	v_mfma_f32_16x16x32_bf16 v[24:27], v[176:179], v[188:191], v[24:27]
	v_mfma_f32_16x16x32_bf16 v[20:23], v[162:165], v[196:199], v[20:23]
	v_mfma_f32_16x16x32_bf16 v[16:19], v[176:179], v[196:199], v[16:19]
	v_mfma_f32_16x16x32_bf16 v[12:15], v[162:165], v[204:207], v[12:15]
	v_mfma_f32_16x16x32_bf16 v[8:11], v[176:179], v[204:207], v[8:11]
	v_mfma_f32_16x16x32_bf16 v[4:7], v[162:165], v[212:215], v[4:7]
	v_mfma_f32_16x16x32_bf16 v[0:3], v[176:179], v[212:215], v[0:3]
	s_setprio 0
	s_barrier
	s_add_u32 s73, s73, 0x100
	s_addc_u32 s74, s74, 0
	s_cmp_ge_u32 s75, s59
	s_mov_b64 s[4:5], s[14:15]
	s_mov_b32 s38, s75
	s_cbranch_scc0 .LBB0_850

; #define G_STAGE(bufoff, gbase, voff) do { _Pragma("unroll") for (int _i = 0; _i < 2; ++_i) \
;         __builtin_amdgcn_global_load_lds((const unsigned*)((const char*)(gbase) + voff[_i]), (LAS unsigned*)(lds + (bufoff) + ldsw + _i * 8192), 16, 0, 0); } while (0)
; #define G_LDA(dst, b, h) do { _Pragma("unroll") for (int m = 0; m < 4; ++m) _Pragma("unroll") for (int k = 0; k < 2; ++k) dst[m][k] = *(const LAS bf16x8*)(lds + G_SA(b, h) + aoff + m * 2048 + k * 1024); } while (0)
; #define G_MMA(ai, bj, At_, Bt_) do { __builtin_amdgcn_s_setprio(1); _Pragma("unroll") for (int m = 0; m < 4; ++m) _Pragma("unroll") for (int n = 0; n < 2; ++n) _Pragma("unroll") for (int k = 0; k < 2; ++k) \
;         acc[ai][bj][m][n] = __builtin_amdgcn_mfma_f32_16x16x32_bf16(Bt_[n][k], At_[m][k], acc[ai][bj][m][n], 0, 0, 0); __builtin_amdgcn_s_setprio(0); } while (0)
; #define WAIT_V(n) asm volatile("s_waitcnt vmcnt(" #n ")" ::: "memory")
; #define WAIT_L(n) asm volatile("s_waitcnt lgkmcnt(" #n ")" ::: "memory")
; #define BAR __builtin_amdgcn_s_barrier()
; #define SCHED __builtin_amdgcn_sched_barrier(0)
; template <class Get, class Epi>
; DI void gemm_loop(int ntiles, int ld, char* shm, const Get& get, const Epi& epi) {
;     ...
;             WAIT_V(8); WAIT_L(0); BAR; G_MMA(0, 0, At, B0); G_MMA(0, 1, At, B1); BAR; SCHED;
;             G_LDA(At, 0, 1); G_STAGE(G_SB(0, 0), b2, voffB); G_STAGE(G_SB(0, 1), b2 + hstep, voffB); G_STAGE(G_SA(0, 0), a2, voffA);
;             WAIT_V(8); WAIT_L(0); BAR; G_MMA(1, 0, At, B0); G_MMA(1, 1, At, B1); BAR; SCHED;
.Lrj_1099_0:
	s_waitcnt lgkmcnt(0)
	s_barrier
	s_setprio 1
	s_waitcnt lgkmcnt(0)
	v_mfma_f32_16x16x32_bf16 v[124:127], v[140:143], v[176:179], 0
	v_mfma_f32_16x16x32_bf16 v[120:123], v[152:155], v[176:179], 0
	v_mfma_f32_16x16x32_bf16 v[116:119], v[140:143], v[184:187], 0
	v_mfma_f32_16x16x32_bf16 v[112:115], v[152:155], v[184:187], 0
	v_mfma_f32_16x16x32_bf16 v[108:111], v[140:143], v[192:195], 0
	v_mfma_f32_16x16x32_bf16 v[100:103], v[152:155], v[192:195], 0
	v_mfma_f32_16x16x32_bf16 v[92:95], v[140:143], v[200:203], 0
	v_mfma_f32_16x16x32_bf16 v[84:87], v[152:155], v[200:203], 0
	s_setprio 0
	s_setprio 1
	v_mfma_f32_16x16x32_bf16 v[124:127], v[148:151], v[180:183], v[124:127]
	v_mfma_f32_16x16x32_bf16 v[120:123], v[156:159], v[180:183], v[120:123]
	v_mfma_f32_16x16x32_bf16 v[116:119], v[148:151], v[188:191], v[116:119]
	v_mfma_f32_16x16x32_bf16 v[112:115], v[156:159], v[188:191], v[112:115]
	v_mfma_f32_16x16x32_bf16 v[108:111], v[148:151], v[196:199], v[108:111]
	v_mfma_f32_16x16x32_bf16 v[100:103], v[156:159], v[196:199], v[100:103]
	v_mfma_f32_16x16x32_bf16 v[92:95], v[148:151], v[204:207], v[92:95]
	v_mfma_f32_16x16x32_bf16 v[84:87], v[156:159], v[204:207], v[84:87]
	s_setprio 0
	s_setprio 1
	v_mfma_f32_16x16x32_bf16 v[104:107], v[160:163], v[176:179], 0
	v_mfma_f32_16x16x32_bf16 v[96:99], v[168:171], v[176:179], 0
	v_mfma_f32_16x16x32_bf16 v[88:91], v[160:163], v[184:187], 0
	v_mfma_f32_16x16x32_bf16 v[80:83], v[168:171], v[184:187], 0
	v_mfma_f32_16x16x32_bf16 v[76:79], v[160:163], v[192:195], 0
	v_mfma_f32_16x16x32_bf16 v[72:75], v[168:171], v[192:195], 0
	v_mfma_f32_16x16x32_bf16 v[68:71], v[160:163], v[200:203], 0
	v_mfma_f32_16x16x32_bf16 v[64:67], v[168:171], v[200:203], 0
	s_setprio 0
	s_setprio 1
	v_mfma_f32_16x16x32_bf16 v[104:107], v[164:167], v[180:183], v[104:107]
	v_mfma_f32_16x16x32_bf16 v[96:99], v[172:175], v[180:183], v[96:99]
	v_mfma_f32_16x16x32_bf16 v[88:91], v[164:167], v[188:191], v[88:91]
	v_mfma_f32_16x16x32_bf16 v[80:83], v[172:175], v[188:191], v[80:83]
	v_mfma_f32_16x16x32_bf16 v[76:79], v[164:167], v[196:199], v[76:79]
	v_mfma_f32_16x16x32_bf16 v[72:75], v[172:175], v[196:199], v[72:75]
	v_mfma_f32_16x16x32_bf16 v[68:71], v[164:167], v[204:207], v[68:71]
	v_mfma_f32_16x16x32_bf16 v[64:67], v[172:175], v[204:207], v[64:67]
	s_setprio 0
	s_barrier
	s_add_i32 s77, s57, s7
	v_lshl_add_u64 v[208:209], s[14:15], 0, v[130:131]
	s_mov_b32 m0, s77
	ds_read_b128 v[176:179], v147 offset:16384
	ds_read_b128 v[180:183], v147 offset:17408
	ds_read_b128 v[184:187], v147 offset:18432
	ds_read_b128 v[188:191], v147 offset:19456
	ds_read_b128 v[192:195], v147 offset:20480
	ds_read_b128 v[196:199], v147 offset:21504
	ds_read_b128 v[200:203], v147 offset:22528
	ds_read_b128 v[204:207], v147 offset:23552
	global_load_lds_dwordx4 v[208:209], off
	s_add_i32 m0, s77, 0x2000
	s_add_u32 s78, s14, 0x40000
	v_lshl_add_u64 v[210:211], s[14:15], 0, v[134:135]
	s_addc_u32 s79, s15, 0
	s_add_i32 s77, s58, s7
	global_load_lds_dwordx4 v[210:211], off
	v_lshl_add_u64 v[212:213], s[78:79], 0, v[130:131]
	s_mov_b32 m0, s77
	v_lshl_add_u64 v[214:215], s[46:47], 0, v[132:133]
	global_load_lds_dwordx4 v[212:213], off
	v_lshl_add_u64 v[212:213], s[78:79], 0, v[134:135]
	s_add_i32 m0, s77, 0x2000
	s_nop 0
	global_load_lds_dwordx4 v[212:213], off
	v_lshl_add_u64 v[212:213], s[46:47], 0, v[128:129]
	s_mov_b32 m0, s45
	s_nop 0
	global_load_lds_dwordx4 v[212:213], off
	s_mov_b32 m0, s49
	s_nop 0
	global_load_lds_dwordx4 v[214:215], off
	s_cmp_lg_u32 s100, 0
	s_cbranch_scc0 .Lrf_1099_1
	s_waitcnt vmcnt(16)
	s_branch .Lrj_1099_1

; #define G_STAGE(bufoff, gbase, voff) do { _Pragma("unroll") for (int _i = 0; _i < 2; ++_i) \
;         __builtin_amdgcn_global_load_lds((const unsigned*)((const char*)(gbase) + voff[_i]), (LAS unsigned*)(lds + (bufoff) + ldsw + _i * 8192), 16, 0, 0); } while (0)
; #define G_LDA(dst, b, h) do { _Pragma("unroll") for (int m = 0; m < 4; ++m) _Pragma("unroll") for (int k = 0; k < 2; ++k) dst[m][k] = *(const LAS bf16x8*)(lds + G_SA(b, h) + aoff + m * 2048 + k * 1024); } while (0)
; #define G_LDB(dst, b, h) do { _Pragma("unroll") for (int n = 0; n < 2; ++n) _Pragma("unroll") for (int k = 0; k < 2; ++k) dst[n][k] = *(const LAS bf16x8*)(lds + G_SB(b, h) + boff + n * 2048 + k * 1024); } while (0)
; #define G_MMA(ai, bj, At_, Bt_) do { __builtin_amdgcn_s_setprio(1); _Pragma("unroll") for (int m = 0; m < 4; ++m) _Pragma("unroll") for (int n = 0; n < 2; ++n) _Pragma("unroll") for (int k = 0; k < 2; ++k) \
;         acc[ai][bj][m][n] = __builtin_amdgcn_mfma_f32_16x16x32_bf16(Bt_[n][k], At_[m][k], acc[ai][bj][m][n], 0, 0, 0); __builtin_amdgcn_s_setprio(0); } while (0)
; #define WAIT_V(n) asm volatile("s_waitcnt vmcnt(" #n ")" ::: "memory")
; #define WAIT_L(n) asm volatile("s_waitcnt lgkmcnt(" #n ")" ::: "memory")
; #define BAR __builtin_amdgcn_s_barrier()
; #define SCHED __builtin_amdgcn_sched_barrier(0)
; template <class Get, class Epi>
; DI void gemm_loop(int ntiles, int ld, char* shm, const Get& get, const Epi& epi) {
;     ...
;             WAIT_V(8); WAIT_L(0); BAR; G_MMA(1, 0, At, B0); G_MMA(1, 1, At, B1); BAR; SCHED;
;             G_LDB(B0, 1, 0); G_LDB(B1, 1, 1); SCHED; G_LDA(At, 1, 0); G_STAGE(G_SA(0, 1), a2 + hstep, voffA);
;             WAIT_V(8); WAIT_L(0); BAR; G_MMA(0, 0, At, B0); G_MMA(0, 1, At, B1); BAR; SCHED;
.Lrj_1099_1:
	s_waitcnt lgkmcnt(0)
	s_barrier
	s_setprio 1
	s_waitcnt lgkmcnt(0)
	v_mfma_f32_16x16x32_bf16 v[60:63], v[140:143], v[176:179], 0
	v_mfma_f32_16x16x32_bf16 v[56:59], v[152:155], v[176:179], 0
	v_mfma_f32_16x16x32_bf16 v[52:55], v[140:143], v[184:187], 0
	v_mfma_f32_16x16x32_bf16 v[48:51], v[152:155], v[184:187], 0
	v_mfma_f32_16x16x32_bf16 v[44:47], v[140:143], v[192:195], 0
	v_mfma_f32_16x16x32_bf16 v[36:39], v[152:155], v[192:195], 0
	v_mfma_f32_16x16x32_bf16 v[28:31], v[140:143], v[200:203], 0
	v_mfma_f32_16x16x32_bf16 v[20:23], v[152:155], v[200:203], 0
	s_setprio 0
	s_setprio 1
	v_mfma_f32_16x16x32_bf16 v[60:63], v[148:151], v[180:183], v[60:63]
	v_mfma_f32_16x16x32_bf16 v[56:59], v[156:159], v[180:183], v[56:59]
	v_mfma_f32_16x16x32_bf16 v[52:55], v[148:151], v[188:191], v[52:55]
	v_mfma_f32_16x16x32_bf16 v[48:51], v[156:159], v[188:191], v[48:51]
	v_mfma_f32_16x16x32_bf16 v[44:47], v[148:151], v[196:199], v[44:47]
	v_mfma_f32_16x16x32_bf16 v[36:39], v[156:159], v[196:199], v[36:39]
	v_mfma_f32_16x16x32_bf16 v[28:31], v[148:151], v[204:207], v[28:31]
	v_mfma_f32_16x16x32_bf16 v[20:23], v[156:159], v[204:207], v[20:23]
	s_setprio 0
	s_setprio 1
	v_mfma_f32_16x16x32_bf16 v[40:43], v[160:163], v[176:179], 0
	v_mfma_f32_16x16x32_bf16 v[32:35], v[168:171], v[176:179], 0
	v_mfma_f32_16x16x32_bf16 v[24:27], v[160:163], v[184:187], 0
	v_mfma_f32_16x16x32_bf16 v[16:19], v[168:171], v[184:187], 0
	v_mfma_f32_16x16x32_bf16 v[12:15], v[160:163], v[192:195], 0
	v_mfma_f32_16x16x32_bf16 v[8:11], v[168:171], v[192:195], 0
	v_mfma_f32_16x16x32_bf16 v[4:7], v[160:163], v[200:203], 0
	v_mfma_f32_16x16x32_bf16 v[0:3], v[168:171], v[200:203], 0
	s_setprio 0
	s_setprio 1
	v_mfma_f32_16x16x32_bf16 v[40:43], v[164:167], v[180:183], v[40:43]
	v_mfma_f32_16x16x32_bf16 v[32:35], v[172:175], v[180:183], v[32:35]
	v_mfma_f32_16x16x32_bf16 v[24:27], v[164:167], v[188:191], v[24:27]
	v_mfma_f32_16x16x32_bf16 v[16:19], v[172:175], v[188:191], v[16:19]
	v_mfma_f32_16x16x32_bf16 v[12:15], v[164:167], v[196:199], v[12:15]
	v_mfma_f32_16x16x32_bf16 v[8:11], v[172:175], v[196:199], v[8:11]
	v_mfma_f32_16x16x32_bf16 v[4:7], v[164:167], v[204:207], v[4:7]
	v_mfma_f32_16x16x32_bf16 v[0:3], v[172:175], v[204:207], v[0:3]
	s_setprio 0
	s_barrier
	s_add_i32 s77, 0, 0x18000
	s_add_i32 s78, 0, 0x1c000
	v_add_u32_e32 v156, s77, v144
	v_add_u32_e32 v172, s78, v144
	ds_read_b128 v[140:143], v156
	ds_read_b128 v[148:151], v156 offset:1024
	ds_read_b128 v[152:155], v156 offset:2048
	ds_read_b128 v[156:159], v156 offset:3072
	ds_read_b128 v[160:163], v172
	ds_read_b128 v[164:167], v172 offset:1024
	ds_read_b128 v[168:171], v172 offset:2048
	ds_read_b128 v[172:175], v172 offset:3072
	s_add_u32 s46, s46, 0x40000
	s_addc_u32 s47, s47, 0
	s_mov_b32 m0, s50
	v_lshl_add_u64 v[216:217], s[46:47], 0, v[128:129]
	ds_read_b128 v[176:179], v147 offset:32768
	ds_read_b128 v[180:183], v147 offset:33792
	ds_read_b128 v[184:187], v147 offset:34816
	ds_read_b128 v[188:191], v147 offset:35840
	ds_read_b128 v[192:195], v147 offset:36864
	ds_read_b128 v[196:199], v147 offset:37888
	ds_read_b128 v[200:203], v147 offset:38912
	ds_read_b128 v[204:207], v147 offset:39936
	global_load_lds_dwordx4 v[216:217], off
	v_lshl_add_u64 v[216:217], s[46:47], 0, v[132:133]
	s_mov_b32 m0, s51
	s_nop 0
	global_load_lds_dwordx4 v[216:217], off
	s_waitcnt vmcnt(8)
	s_waitcnt lgkmcnt(0)
	s_barrier
	s_setprio 1
	s_waitcnt lgkmcnt(0)
	v_mfma_f32_16x16x32_bf16 v[124:127], v[140:143], v[176:179], v[124:127]
	v_mfma_f32_16x16x32_bf16 v[120:123], v[152:155], v[176:179], v[120:123]
	v_mfma_f32_16x16x32_bf16 v[116:119], v[140:143], v[184:187], v[116:119]
	v_mfma_f32_16x16x32_bf16 v[112:115], v[152:155], v[184:187], v[112:115]
	v_mfma_f32_16x16x32_bf16 v[108:111], v[140:143], v[192:195], v[108:111]
	v_mfma_f32_16x16x32_bf16 v[100:103], v[152:155], v[192:195], v[100:103]
	v_mfma_f32_16x16x32_bf16 v[92:95], v[140:143], v[200:203], v[92:95]
	v_mfma_f32_16x16x32_bf16 v[84:87], v[152:155], v[200:203], v[84:87]
	s_setprio 0
	s_setprio 1
	v_mfma_f32_16x16x32_bf16 v[124:127], v[148:151], v[180:183], v[124:127]
	v_mfma_f32_16x16x32_bf16 v[120:123], v[156:159], v[180:183], v[120:123]
	v_mfma_f32_16x16x32_bf16 v[116:119], v[148:151], v[188:191], v[116:119]
	v_mfma_f32_16x16x32_bf16 v[112:115], v[156:159], v[188:191], v[112:115]
	v_mfma_f32_16x16x32_bf16 v[108:111], v[148:151], v[196:199], v[108:111]
	v_mfma_f32_16x16x32_bf16 v[100:103], v[156:159], v[196:199], v[100:103]
	v_mfma_f32_16x16x32_bf16 v[92:95], v[148:151], v[204:207], v[92:95]
	v_mfma_f32_16x16x32_bf16 v[84:87], v[156:159], v[204:207], v[84:87]
	s_setprio 0
	s_setprio 1
	v_mfma_f32_16x16x32_bf16 v[104:107], v[160:163], v[176:179], v[104:107]
	v_mfma_f32_16x16x32_bf16 v[96:99], v[168:171], v[176:179], v[96:99]
	v_mfma_f32_16x16x32_bf16 v[88:91], v[160:163], v[184:187], v[88:91]
	v_mfma_f32_16x16x32_bf16 v[80:83], v[168:171], v[184:187], v[80:83]
	v_mfma_f32_16x16x32_bf16 v[76:79], v[160:163], v[192:195], v[76:79]
	v_mfma_f32_16x16x32_bf16 v[72:75], v[168:171], v[192:195], v[72:75]
	v_mfma_f32_16x16x32_bf16 v[68:71], v[160:163], v[200:203], v[68:71]
	v_mfma_f32_16x16x32_bf16 v[64:67], v[168:171], v[200:203], v[64:67]
	s_setprio 0
	s_setprio 1
	v_mfma_f32_16x16x32_bf16 v[104:107], v[164:167], v[180:183], v[104:107]
	v_mfma_f32_16x16x32_bf16 v[96:99], v[172:175], v[180:183], v[96:99]
	v_mfma_f32_16x16x32_bf16 v[88:91], v[164:167], v[188:191], v[88:91]
	v_mfma_f32_16x16x32_bf16 v[80:83], v[172:175], v[188:191], v[80:83]
	v_mfma_f32_16x16x32_bf16 v[76:79], v[164:167], v[196:199], v[76:79]
	v_mfma_f32_16x16x32_bf16 v[72:75], v[172:175], v[196:199], v[72:75]
	v_mfma_f32_16x16x32_bf16 v[68:71], v[164:167], v[204:207], v[68:71]
	v_mfma_f32_16x16x32_bf16 v[64:67], v[172:175], v[204:207], v[64:67]
	s_setprio 0
	s_barrier
; #define G_STAGE(bufoff, gbase, voff) do { _Pragma("unroll") for (int _i = 0; _i < 2; ++_i) \
;         __builtin_amdgcn_global_load_lds((const unsigned*)((const char*)(gbase) + voff[_i]), (LAS unsigned*)(lds + (bufoff) + ldsw + _i * 8192), 16, 0, 0); } while (0)
; #define G_LDA(dst, b, h) do { _Pragma("unroll") for (int m = 0; m < 4; ++m) _Pragma("unroll") for (int k = 0; k < 2; ++k) dst[m][k] = *(const LAS bf16x8*)(lds + G_SA(b, h) + aoff + m * 2048 + k * 1024); } while (0)
; #define G_LDB(dst, b, h) do { _Pragma("unroll") for (int n = 0; n < 2; ++n) _Pragma("unroll") for (int k = 0; k < 2; ++k) dst[n][k] = *(const LAS bf16x8*)(lds + G_SB(b, h) + boff + n * 2048 + k * 1024); } while (0)
; #define WAIT_V(n) asm volatile("s_waitcnt vmcnt(" #n ")" ::: "memory")
; #define WAIT_L(n) asm volatile("s_waitcnt lgkmcnt(" #n ")" ::: "memory")
; #define BAR __builtin_amdgcn_s_barrier()
; #define SCHED __builtin_amdgcn_sched_barrier(0)
; template <class Get, class Epi>
; DI void gemm_loop(int ntiles, int ld, char* shm, const Get& get, const Epi& epi) {
;     ...
;         for (int t = 0; t < nt; t += 2) {
;             const bool last = (t == nt - 2);
;             const char* a1 = cA + (size_t)(t + 1) * kstep;
;             const char* a2 = last ? nA : cA + (size_t)(t + 2) * kstep; const char* b2 = last ? nB : cB + (size_t)(t + 2) * kstep;
;             const char* a3 = a2 + kstep; const char* b3 = b2 + kstep;
;             G_LDB(B0, 0, 0); G_LDB(B1, 0, 1); SCHED; G_LDA(At, 0, 0); G_STAGE(G_SA(1, 1), a1 + hstep, voffA);
;             WAIT_V(8); WAIT_L(0); BAR; G_MMA(0, 0, At, B0); G_MMA(0, 1, At, B1); BAR; SCHED;
;             G_LDA(At, 0, 1); G_STAGE(G_SB(0, 0), b2, voffB); G_STAGE(G_SB(0, 1), b2 + hstep, voffB); G_STAGE(G_SA(0, 0), a2, voffA);
;             WAIT_V(8); WAIT_L(0); BAR; G_MMA(1, 0, At, B0); G_MMA(1, 1, At, B1); BAR; SCHED;
;             G_LDB(B0, 1, 0); G_LDB(B1, 1, 1); SCHED; G_LDA(At, 1, 0); G_STAGE(G_SA(0, 1), a2 + hstep, voffA);
;             WAIT_V(8); WAIT_L(0); BAR; G_MMA(0, 0, At, B0); G_MMA(0, 1, At, B1); BAR; SCHED;
;             G_LDA(At, 1, 1); G_STAGE(G_SB(1, 0), b3, voffB); G_STAGE(G_SB(1, 1), b3 + hstep, voffB); G_STAGE(G_SA(1, 0), a3, voffA);
;             WAIT_V(8); WAIT_L(0); BAR; G_MMA(1, 0, At, B0); G_MMA(1, 1, At, B1); BAR; SCHED;
	s_add_i32 s46, s77, s7
	v_lshl_add_u64 v[208:209], v[208:209], 0, s[10:11]
	s_mov_b32 m0, s46
	ds_read_b128 v[176:179], v147 offset:49152
	ds_read_b128 v[180:183], v147 offset:50176
	ds_read_b128 v[184:187], v147 offset:51200
	ds_read_b128 v[188:191], v147 offset:52224
	ds_read_b128 v[192:195], v147 offset:53248
	ds_read_b128 v[196:199], v147 offset:54272
	ds_read_b128 v[200:203], v147 offset:55296
	ds_read_b128 v[204:207], v147 offset:56320
	global_load_lds_dwordx4 v[208:209], off
	s_add_i32 m0, s46, 0x2000
	s_add_u32 s14, s14, 0x40080
	v_lshl_add_u64 v[208:209], v[210:211], 0, s[10:11]
	s_addc_u32 s15, s15, 0
	s_add_i32 s46, s78, s7
	global_load_lds_dwordx4 v[208:209], off
	v_lshl_add_u64 v[208:209], s[14:15], 0, v[130:131]
	s_mov_b32 m0, s46
	s_nop 0
	global_load_lds_dwordx4 v[208:209], off
	v_lshl_add_u64 v[208:209], s[14:15], 0, v[134:135]
	s_add_i32 m0, s46, 0x2000
	s_nop 0
	global_load_lds_dwordx4 v[208:209], off
	v_lshl_add_u64 v[208:209], v[212:213], 0, s[10:11]
	s_mov_b32 m0, s54
	s_nop 0
	global_load_lds_dwordx4 v[208:209], off
	v_lshl_add_u64 v[208:209], v[214:215], 0, s[10:11]
	s_mov_b32 m0, s55
	s_nop 0
	global_load_lds_dwordx4 v[208:209], off
	s_waitcnt vmcnt(8)
	s_waitcnt lgkmcnt(0)
	s_barrier
	s_setprio 1
	s_waitcnt lgkmcnt(0)
	v_mfma_f32_16x16x32_bf16 v[60:63], v[140:143], v[176:179], v[60:63]
	v_mfma_f32_16x16x32_bf16 v[56:59], v[152:155], v[176:179], v[56:59]
	v_mfma_f32_16x16x32_bf16 v[52:55], v[140:143], v[184:187], v[52:55]
	v_mfma_f32_16x16x32_bf16 v[48:51], v[152:155], v[184:187], v[48:51]
	v_mfma_f32_16x16x32_bf16 v[44:47], v[140:143], v[192:195], v[44:47]
	v_mfma_f32_16x16x32_bf16 v[36:39], v[152:155], v[192:195], v[36:39]
	v_mfma_f32_16x16x32_bf16 v[28:31], v[140:143], v[200:203], v[28:31]
	v_mfma_f32_16x16x32_bf16 v[20:23], v[152:155], v[200:203], v[20:23]
	s_setprio 0
	s_setprio 1
	v_mfma_f32_16x16x32_bf16 v[60:63], v[148:151], v[180:183], v[60:63]
	v_mfma_f32_16x16x32_bf16 v[56:59], v[156:159], v[180:183], v[56:59]
	v_mfma_f32_16x16x32_bf16 v[52:55], v[148:151], v[188:191], v[52:55]
	v_mfma_f32_16x16x32_bf16 v[48:51], v[156:159], v[188:191], v[48:51]
	v_mfma_f32_16x16x32_bf16 v[44:47], v[148:151], v[196:199], v[44:47]
	v_mfma_f32_16x16x32_bf16 v[36:39], v[156:159], v[196:199], v[36:39]
	v_mfma_f32_16x16x32_bf16 v[28:31], v[148:151], v[204:207], v[28:31]
	v_mfma_f32_16x16x32_bf16 v[20:23], v[156:159], v[204:207], v[20:23]
	s_setprio 0
	s_setprio 1
	v_mfma_f32_16x16x32_bf16 v[40:43], v[160:163], v[176:179], v[40:43]
	v_mfma_f32_16x16x32_bf16 v[32:35], v[168:171], v[176:179], v[32:35]
	v_mfma_f32_16x16x32_bf16 v[24:27], v[160:163], v[184:187], v[24:27]
	v_mfma_f32_16x16x32_bf16 v[16:19], v[168:171], v[184:187], v[16:19]
	v_mfma_f32_16x16x32_bf16 v[12:15], v[160:163], v[192:195], v[12:15]
	v_mfma_f32_16x16x32_bf16 v[8:11], v[168:171], v[192:195], v[8:11]
	v_mfma_f32_16x16x32_bf16 v[4:7], v[160:163], v[200:203], v[4:7]
	v_mfma_f32_16x16x32_bf16 v[0:3], v[168:171], v[200:203], v[0:3]
	s_setprio 0
	s_setprio 1
	v_mfma_f32_16x16x32_bf16 v[40:43], v[164:167], v[180:183], v[40:43]
	v_mfma_f32_16x16x32_bf16 v[32:35], v[172:175], v[180:183], v[32:35]
	v_mfma_f32_16x16x32_bf16 v[24:27], v[164:167], v[188:191], v[24:27]
	v_mfma_f32_16x16x32_bf16 v[16:19], v[172:175], v[188:191], v[16:19]
	v_mfma_f32_16x16x32_bf16 v[12:15], v[164:167], v[196:199], v[12:15]
	v_mfma_f32_16x16x32_bf16 v[8:11], v[172:175], v[196:199], v[8:11]
	v_mfma_f32_16x16x32_bf16 v[4:7], v[164:167], v[204:207], v[4:7]
	v_mfma_f32_16x16x32_bf16 v[0:3], v[172:175], v[204:207], v[0:3]
	s_setprio 0
	s_barrier
	s_add_i32 s76, s76, 2
	s_add_u32 s52, s52, 0x100
	s_addc_u32 s53, s53, 0
	s_add_u32 s74, s74, 0x100
	s_addc_u32 s75, s75, 0
	s_cmp_gt_u32 s76, 13
	s_cbranch_scc0 .LBB0_1099
	s_branch .Lpost_1099
.LBB0_1099:
	ds_read_b128 v[140:143], v145
	ds_read_b128 v[148:151], v145 offset:1024
	ds_read_b128 v[152:155], v145 offset:2048
	ds_read_b128 v[156:159], v145 offset:3072
	ds_read_b128 v[160:163], v146
	ds_read_b128 v[164:167], v146 offset:1024
	ds_read_b128 v[168:171], v146 offset:2048
	ds_read_b128 v[172:175], v146 offset:3072
	s_add_u32 s14, s52, 0xfffc0080
	s_addc_u32 s15, s53, -1
	s_cmp_eq_u32 s76, 12
	s_cselect_b32 s47, s39, s15
	s_cselect_b32 s46, s72, s14
	s_cselect_b32 s15, s37, s75
	s_cselect_b32 s14, s73, s74
	v_lshl_add_u64 v[208:209], s[52:53], 0, v[136:137]
	s_add_i32 m0, s45, 0xc000
	ds_read_b128 v[176:179], v147
	ds_read_b128 v[180:183], v147 offset:1024
	ds_read_b128 v[184:187], v147 offset:2048
	ds_read_b128 v[188:191], v147 offset:3072
	ds_read_b128 v[192:195], v147 offset:4096
	ds_read_b128 v[196:199], v147 offset:5120
	ds_read_b128 v[200:203], v147 offset:6144
	ds_read_b128 v[204:207], v147 offset:7168
	global_load_lds_dwordx4 v[208:209], off
	v_lshl_add_u64 v[208:209], s[52:53], 0, v[138:139]
	s_add_i32 m0, s45, 0xe000
	s_nop 0
	global_load_lds_dwordx4 v[208:209], off
	s_waitcnt vmcnt(8)
	s_waitcnt lgkmcnt(0)
	s_barrier
; #define G_STAGE(bufoff, gbase, voff) do { _Pragma("unroll") for (int _i = 0; _i < 2; ++_i) \
;         __builtin_amdgcn_global_load_lds((const unsigned*)((const char*)(gbase) + voff[_i]), (LAS unsigned*)(lds + (bufoff) + ldsw + _i * 8192), 16, 0, 0); } while (0)
; #define G_LDA(dst, b, h) do { _Pragma("unroll") for (int m = 0; m < 4; ++m) _Pragma("unroll") for (int k = 0; k < 2; ++k) dst[m][k] = *(const LAS bf16x8*)(lds + G_SA(b, h) + aoff + m * 2048 + k * 1024); } while (0)
; #define G_MMA(ai, bj, At_, Bt_) do { __builtin_amdgcn_s_setprio(1); _Pragma("unroll") for (int m = 0; m < 4; ++m) _Pragma("unroll") for (int n = 0; n < 2; ++n) _Pragma("unroll") for (int k = 0; k < 2; ++k) \
;         acc[ai][bj][m][n] = __builtin_amdgcn_mfma_f32_16x16x32_bf16(Bt_[n][k], At_[m][k], acc[ai][bj][m][n], 0, 0, 0); __builtin_amdgcn_s_setprio(0); } while (0)
; #define WAIT_V(n) asm volatile("s_waitcnt vmcnt(" #n ")" ::: "memory")
; #define WAIT_L(n) asm volatile("s_waitcnt lgkmcnt(" #n ")" ::: "memory")
; #define BAR __builtin_amdgcn_s_barrier()
; #define SCHED __builtin_amdgcn_sched_barrier(0)
; template <class Get, class Epi>
; DI void gemm_loop(int ntiles, int ld, char* shm, const Get& get, const Epi& epi) {
;     ...
;             WAIT_V(8); WAIT_L(0); BAR; G_MMA(0, 0, At, B0); G_MMA(0, 1, At, B1); BAR; SCHED;
;             G_LDA(At, 0, 1); G_STAGE(G_SB(0, 0), b2, voffB); G_STAGE(G_SB(0, 1), b2 + hstep, voffB); G_STAGE(G_SA(0, 0), a2, voffA);
;             WAIT_V(8); WAIT_L(0); BAR; G_MMA(1, 0, At, B0); G_MMA(1, 1, At, B1); BAR; SCHED;
	s_setprio 1
	s_waitcnt lgkmcnt(0)
	v_mfma_f32_16x16x32_bf16 v[124:127], v[140:143], v[176:179], v[124:127]
	v_mfma_f32_16x16x32_bf16 v[120:123], v[152:155], v[176:179], v[120:123]
	v_mfma_f32_16x16x32_bf16 v[116:119], v[140:143], v[184:187], v[116:119]
	v_mfma_f32_16x16x32_bf16 v[112:115], v[152:155], v[184:187], v[112:115]
	v_mfma_f32_16x16x32_bf16 v[108:111], v[140:143], v[192:195], v[108:111]
	v_mfma_f32_16x16x32_bf16 v[100:103], v[152:155], v[192:195], v[100:103]
	v_mfma_f32_16x16x32_bf16 v[92:95], v[140:143], v[200:203], v[92:95]
	v_mfma_f32_16x16x32_bf16 v[84:87], v[152:155], v[200:203], v[84:87]
	s_setprio 0
	s_setprio 1
	v_mfma_f32_16x16x32_bf16 v[124:127], v[148:151], v[180:183], v[124:127]
	v_mfma_f32_16x16x32_bf16 v[120:123], v[156:159], v[180:183], v[120:123]
	v_mfma_f32_16x16x32_bf16 v[116:119], v[148:151], v[188:191], v[116:119]
	v_mfma_f32_16x16x32_bf16 v[112:115], v[156:159], v[188:191], v[112:115]
	v_mfma_f32_16x16x32_bf16 v[108:111], v[148:151], v[196:199], v[108:111]
	v_mfma_f32_16x16x32_bf16 v[100:103], v[156:159], v[196:199], v[100:103]
	v_mfma_f32_16x16x32_bf16 v[92:95], v[148:151], v[204:207], v[92:95]
	v_mfma_f32_16x16x32_bf16 v[84:87], v[156:159], v[204:207], v[84:87]
	s_setprio 0
	s_setprio 1
	v_mfma_f32_16x16x32_bf16 v[104:107], v[160:163], v[176:179], v[104:107]
	v_mfma_f32_16x16x32_bf16 v[96:99], v[168:171], v[176:179], v[96:99]
	v_mfma_f32_16x16x32_bf16 v[88:91], v[160:163], v[184:187], v[88:91]
	v_mfma_f32_16x16x32_bf16 v[80:83], v[168:171], v[184:187], v[80:83]
	v_mfma_f32_16x16x32_bf16 v[76:79], v[160:163], v[192:195], v[76:79]
	v_mfma_f32_16x16x32_bf16 v[72:75], v[168:171], v[192:195], v[72:75]
	v_mfma_f32_16x16x32_bf16 v[68:71], v[160:163], v[200:203], v[68:71]
	v_mfma_f32_16x16x32_bf16 v[64:67], v[168:171], v[200:203], v[64:67]
	s_setprio 0
	s_setprio 1
	v_mfma_f32_16x16x32_bf16 v[104:107], v[164:167], v[180:183], v[104:107]
	v_mfma_f32_16x16x32_bf16 v[96:99], v[172:175], v[180:183], v[96:99]
	v_mfma_f32_16x16x32_bf16 v[88:91], v[164:167], v[188:191], v[88:91]
	v_mfma_f32_16x16x32_bf16 v[80:83], v[172:175], v[188:191], v[80:83]
	v_mfma_f32_16x16x32_bf16 v[76:79], v[164:167], v[196:199], v[76:79]
	v_mfma_f32_16x16x32_bf16 v[72:75], v[172:175], v[196:199], v[72:75]
	v_mfma_f32_16x16x32_bf16 v[68:71], v[164:167], v[204:207], v[68:71]
	v_mfma_f32_16x16x32_bf16 v[64:67], v[172:175], v[204:207], v[64:67]
	s_setprio 0
	s_barrier
	s_add_i32 s77, s57, s7
	v_lshl_add_u64 v[208:209], s[14:15], 0, v[130:131]
	s_mov_b32 m0, s77
	ds_read_b128 v[176:179], v147 offset:16384
	ds_read_b128 v[180:183], v147 offset:17408
	ds_read_b128 v[184:187], v147 offset:18432
	ds_read_b128 v[188:191], v147 offset:19456
	ds_read_b128 v[192:195], v147 offset:20480
	ds_read_b128 v[196:199], v147 offset:21504
	ds_read_b128 v[200:203], v147 offset:22528
	ds_read_b128 v[204:207], v147 offset:23552
	global_load_lds_dwordx4 v[208:209], off
	s_add_i32 m0, s77, 0x2000
	s_add_u32 s78, s14, 0x40000
	v_lshl_add_u64 v[210:211], s[14:15], 0, v[134:135]
	s_addc_u32 s79, s15, 0
	s_add_i32 s77, s58, s7
	global_load_lds_dwordx4 v[210:211], off
	v_lshl_add_u64 v[212:213], s[78:79], 0, v[130:131]
	s_mov_b32 m0, s77
	v_lshl_add_u64 v[214:215], s[46:47], 0, v[132:133]
	global_load_lds_dwordx4 v[212:213], off
	v_lshl_add_u64 v[212:213], s[78:79], 0, v[134:135]
	s_add_i32 m0, s77, 0x2000
	s_nop 0
	global_load_lds_dwordx4 v[212:213], off
	v_lshl_add_u64 v[212:213], s[46:47], 0, v[128:129]
	s_mov_b32 m0, s45
	s_nop 0
	global_load_lds_dwordx4 v[212:213], off
	s_mov_b32 m0, s49
	s_nop 0
	global_load_lds_dwordx4 v[214:215], off
	s_waitcnt vmcnt(8)
	s_waitcnt lgkmcnt(0)
	s_barrier
	s_setprio 1
	s_waitcnt lgkmcnt(0)
	v_mfma_f32_16x16x32_bf16 v[60:63], v[140:143], v[176:179], v[60:63]
	v_mfma_f32_16x16x32_bf16 v[56:59], v[152:155], v[176:179], v[56:59]
	v_mfma_f32_16x16x32_bf16 v[52:55], v[140:143], v[184:187], v[52:55]
	v_mfma_f32_16x16x32_bf16 v[48:51], v[152:155], v[184:187], v[48:51]
	v_mfma_f32_16x16x32_bf16 v[44:47], v[140:143], v[192:195], v[44:47]
	v_mfma_f32_16x16x32_bf16 v[36:39], v[152:155], v[192:195], v[36:39]
	v_mfma_f32_16x16x32_bf16 v[28:31], v[140:143], v[200:203], v[28:31]
	v_mfma_f32_16x16x32_bf16 v[20:23], v[152:155], v[200:203], v[20:23]
	s_setprio 0
	s_setprio 1
	v_mfma_f32_16x16x32_bf16 v[60:63], v[148:151], v[180:183], v[60:63]
	v_mfma_f32_16x16x32_bf16 v[56:59], v[156:159], v[180:183], v[56:59]
	v_mfma_f32_16x16x32_bf16 v[52:55], v[148:151], v[188:191], v[52:55]
	v_mfma_f32_16x16x32_bf16 v[48:51], v[156:159], v[188:191], v[48:51]
	v_mfma_f32_16x16x32_bf16 v[44:47], v[148:151], v[196:199], v[44:47]
	v_mfma_f32_16x16x32_bf16 v[36:39], v[156:159], v[196:199], v[36:39]
	v_mfma_f32_16x16x32_bf16 v[28:31], v[148:151], v[204:207], v[28:31]
	v_mfma_f32_16x16x32_bf16 v[20:23], v[156:159], v[204:207], v[20:23]
	s_setprio 0
	s_setprio 1
	v_mfma_f32_16x16x32_bf16 v[40:43], v[160:163], v[176:179], v[40:43]
	v_mfma_f32_16x16x32_bf16 v[32:35], v[168:171], v[176:179], v[32:35]
	v_mfma_f32_16x16x32_bf16 v[24:27], v[160:163], v[184:187], v[24:27]
	v_mfma_f32_16x16x32_bf16 v[16:19], v[168:171], v[184:187], v[16:19]
	v_mfma_f32_16x16x32_bf16 v[12:15], v[160:163], v[192:195], v[12:15]
	v_mfma_f32_16x16x32_bf16 v[8:11], v[168:171], v[192:195], v[8:11]
	v_mfma_f32_16x16x32_bf16 v[4:7], v[160:163], v[200:203], v[4:7]
	v_mfma_f32_16x16x32_bf16 v[0:3], v[168:171], v[200:203], v[0:3]
	s_setprio 0
	s_setprio 1
	v_mfma_f32_16x16x32_bf16 v[40:43], v[164:167], v[180:183], v[40:43]
	v_mfma_f32_16x16x32_bf16 v[32:35], v[172:175], v[180:183], v[32:35]
	v_mfma_f32_16x16x32_bf16 v[24:27], v[164:167], v[188:191], v[24:27]
	v_mfma_f32_16x16x32_bf16 v[16:19], v[172:175], v[188:191], v[16:19]
	v_mfma_f32_16x16x32_bf16 v[12:15], v[164:167], v[196:199], v[12:15]
	v_mfma_f32_16x16x32_bf16 v[8:11], v[172:175], v[196:199], v[8:11]
	v_mfma_f32_16x16x32_bf16 v[4:7], v[164:167], v[204:207], v[4:7]
	v_mfma_f32_16x16x32_bf16 v[0:3], v[172:175], v[204:207], v[0:3]
	s_setprio 0
	s_barrier
; #define G_STAGE(bufoff, gbase, voff) do { _Pragma("unroll") for (int _i = 0; _i < 2; ++_i) \
;         __builtin_amdgcn_global_load_lds((const unsigned*)((const char*)(gbase) + voff[_i]), (LAS unsigned*)(lds + (bufoff) + ldsw + _i * 8192), 16, 0, 0); } while (0)
; #define G_LDA(dst, b, h) do { _Pragma("unroll") for (int m = 0; m < 4; ++m) _Pragma("unroll") for (int k = 0; k < 2; ++k) dst[m][k] = *(const LAS bf16x8*)(lds + G_SA(b, h) + aoff + m * 2048 + k * 1024); } while (0)
; #define G_LDB(dst, b, h) do { _Pragma("unroll") for (int n = 0; n < 2; ++n) _Pragma("unroll") for (int k = 0; k < 2; ++k) dst[n][k] = *(const LAS bf16x8*)(lds + G_SB(b, h) + boff + n * 2048 + k * 1024); } while (0)
; #define G_MMA(ai, bj, At_, Bt_) do { __builtin_amdgcn_s_setprio(1); _Pragma("unroll") for (int m = 0; m < 4; ++m) _Pragma("unroll") for (int n = 0; n < 2; ++n) _Pragma("unroll") for (int k = 0; k < 2; ++k) \
;         acc[ai][bj][m][n] = __builtin_amdgcn_mfma_f32_16x16x32_bf16(Bt_[n][k], At_[m][k], acc[ai][bj][m][n], 0, 0, 0); __builtin_amdgcn_s_setprio(0); } while (0)
; #define WAIT_V(n) asm volatile("s_waitcnt vmcnt(" #n ")" ::: "memory")
; #define WAIT_L(n) asm volatile("s_waitcnt lgkmcnt(" #n ")" ::: "memory")
; #define BAR __builtin_amdgcn_s_barrier()
; #define SCHED __builtin_amdgcn_sched_barrier(0)
; template <class Get, class Epi>
; DI void gemm_loop(int ntiles, int ld, char* shm, const Get& get, const Epi& epi) {
;     ...
;             G_LDB(B0, 1, 0); G_LDB(B1, 1, 1); SCHED; G_LDA(At, 1, 0); G_STAGE(G_SA(0, 1), a2 + hstep, voffA);
;             WAIT_V(8); WAIT_L(0); BAR; G_MMA(0, 0, At, B0); G_MMA(0, 1, At, B1); BAR; SCHED;
	s_add_i32 s77, 0, 0x18000
	s_add_i32 s78, 0, 0x1c000
	v_add_u32_e32 v156, s77, v144
	v_add_u32_e32 v172, s78, v144
	ds_read_b128 v[140:143], v156
	ds_read_b128 v[148:151], v156 offset:1024
	ds_read_b128 v[152:155], v156 offset:2048
	ds_read_b128 v[156:159], v156 offset:3072
	ds_read_b128 v[160:163], v172
	ds_read_b128 v[164:167], v172 offset:1024
	ds_read_b128 v[168:171], v172 offset:2048
	ds_read_b128 v[172:175], v172 offset:3072
	s_add_u32 s46, s46, 0x40000
	s_addc_u32 s47, s47, 0
	s_mov_b32 m0, s50
	v_lshl_add_u64 v[216:217], s[46:47], 0, v[128:129]
	ds_read_b128 v[176:179], v147 offset:32768
	ds_read_b128 v[180:183], v147 offset:33792
	ds_read_b128 v[184:187], v147 offset:34816
	ds_read_b128 v[188:191], v147 offset:35840
	ds_read_b128 v[192:195], v147 offset:36864
	ds_read_b128 v[196:199], v147 offset:37888
	ds_read_b128 v[200:203], v147 offset:38912
	ds_read_b128 v[204:207], v147 offset:39936
	global_load_lds_dwordx4 v[216:217], off
	v_lshl_add_u64 v[216:217], s[46:47], 0, v[132:133]
	s_mov_b32 m0, s51
	s_nop 0
	global_load_lds_dwordx4 v[216:217], off
	s_waitcnt vmcnt(8)
	s_waitcnt lgkmcnt(0)
	s_barrier
	s_setprio 1
	s_waitcnt lgkmcnt(0)
	v_mfma_f32_16x16x32_bf16 v[124:127], v[140:143], v[176:179], v[124:127]
	v_mfma_f32_16x16x32_bf16 v[120:123], v[152:155], v[176:179], v[120:123]
	v_mfma_f32_16x16x32_bf16 v[116:119], v[140:143], v[184:187], v[116:119]
	v_mfma_f32_16x16x32_bf16 v[112:115], v[152:155], v[184:187], v[112:115]
	v_mfma_f32_16x16x32_bf16 v[108:111], v[140:143], v[192:195], v[108:111]
	v_mfma_f32_16x16x32_bf16 v[100:103], v[152:155], v[192:195], v[100:103]
	v_mfma_f32_16x16x32_bf16 v[92:95], v[140:143], v[200:203], v[92:95]
	v_mfma_f32_16x16x32_bf16 v[84:87], v[152:155], v[200:203], v[84:87]
	s_setprio 0
	s_setprio 1
	v_mfma_f32_16x16x32_bf16 v[124:127], v[148:151], v[180:183], v[124:127]
	v_mfma_f32_16x16x32_bf16 v[120:123], v[156:159], v[180:183], v[120:123]
	v_mfma_f32_16x16x32_bf16 v[116:119], v[148:151], v[188:191], v[116:119]
	v_mfma_f32_16x16x32_bf16 v[112:115], v[156:159], v[188:191], v[112:115]
	v_mfma_f32_16x16x32_bf16 v[108:111], v[148:151], v[196:199], v[108:111]
	v_mfma_f32_16x16x32_bf16 v[100:103], v[156:159], v[196:199], v[100:103]
	v_mfma_f32_16x16x32_bf16 v[92:95], v[148:151], v[204:207], v[92:95]
	v_mfma_f32_16x16x32_bf16 v[84:87], v[156:159], v[204:207], v[84:87]
	s_setprio 0
	s_setprio 1
	v_mfma_f32_16x16x32_bf16 v[104:107], v[160:163], v[176:179], v[104:107]
	v_mfma_f32_16x16x32_bf16 v[96:99], v[168:171], v[176:179], v[96:99]
	v_mfma_f32_16x16x32_bf16 v[88:91], v[160:163], v[184:187], v[88:91]
	v_mfma_f32_16x16x32_bf16 v[80:83], v[168:171], v[184:187], v[80:83]
	v_mfma_f32_16x16x32_bf16 v[76:79], v[160:163], v[192:195], v[76:79]
	v_mfma_f32_16x16x32_bf16 v[72:75], v[168:171], v[192:195], v[72:75]
	v_mfma_f32_16x16x32_bf16 v[68:71], v[160:163], v[200:203], v[68:71]
	v_mfma_f32_16x16x32_bf16 v[64:67], v[168:171], v[200:203], v[64:67]
	s_setprio 0
	s_setprio 1
	v_mfma_f32_16x16x32_bf16 v[104:107], v[164:167], v[180:183], v[104:107]
	v_mfma_f32_16x16x32_bf16 v[96:99], v[172:175], v[180:183], v[96:99]
	v_mfma_f32_16x16x32_bf16 v[88:91], v[164:167], v[188:191], v[88:91]
	v_mfma_f32_16x16x32_bf16 v[80:83], v[172:175], v[188:191], v[80:83]
	v_mfma_f32_16x16x32_bf16 v[76:79], v[164:167], v[196:199], v[76:79]
	v_mfma_f32_16x16x32_bf16 v[72:75], v[172:175], v[196:199], v[72:75]
	v_mfma_f32_16x16x32_bf16 v[68:71], v[164:167], v[204:207], v[68:71]
	v_mfma_f32_16x16x32_bf16 v[64:67], v[172:175], v[204:207], v[64:67]
	s_setprio 0
	s_barrier
; #define G_STAGE(bufoff, gbase, voff) do { _Pragma("unroll") for (int _i = 0; _i < 2; ++_i) \
;         __builtin_amdgcn_global_load_lds((const unsigned*)((const char*)(gbase) + voff[_i]), (LAS unsigned*)(lds + (bufoff) + ldsw + _i * 8192), 16, 0, 0); } while (0)
; #define G_LDA(dst, b, h) do { _Pragma("unroll") for (int m = 0; m < 4; ++m) _Pragma("unroll") for (int k = 0; k < 2; ++k) dst[m][k] = *(const LAS bf16x8*)(lds + G_SA(b, h) + aoff + m * 2048 + k * 1024); } while (0)
; #define G_MMA(ai, bj, At_, Bt_) do { __builtin_amdgcn_s_setprio(1); _Pragma("unroll") for (int m = 0; m < 4; ++m) _Pragma("unroll") for (int n = 0; n < 2; ++n) _Pragma("unroll") for (int k = 0; k < 2; ++k) \
;         acc[ai][bj][m][n] = __builtin_amdgcn_mfma_f32_16x16x32_bf16(Bt_[n][k], At_[m][k], acc[ai][bj][m][n], 0, 0, 0); __builtin_amdgcn_s_setprio(0); } while (0)
; #define WAIT_V(n) asm volatile("s_waitcnt vmcnt(" #n ")" ::: "memory")
; #define WAIT_L(n) asm volatile("s_waitcnt lgkmcnt(" #n ")" ::: "memory")
; #define BAR __builtin_amdgcn_s_barrier()
; #define SCHED __builtin_amdgcn_sched_barrier(0)
; template <class Get, class Epi>
; DI void gemm_loop(int ntiles, int ld, char* shm, const Get& get, const Epi& epi) {
;     ...
;             G_LDA(At, 1, 1); G_STAGE(G_SB(1, 0), b3, voffB); G_STAGE(G_SB(1, 1), b3 + hstep, voffB); G_STAGE(G_SA(1, 0), a3, voffA);
;             WAIT_V(8); WAIT_L(0); BAR; G_MMA(1, 0, At, B0); G_MMA(1, 1, At, B1); BAR; SCHED;
;         }
	s_add_i32 s46, s77, s7
	v_lshl_add_u64 v[208:209], v[208:209], 0, s[10:11]
	s_mov_b32 m0, s46
	ds_read_b128 v[176:179], v147 offset:49152
	ds_read_b128 v[180:183], v147 offset:50176
	ds_read_b128 v[184:187], v147 offset:51200
	ds_read_b128 v[188:191], v147 offset:52224
	ds_read_b128 v[192:195], v147 offset:53248
	ds_read_b128 v[196:199], v147 offset:54272
	ds_read_b128 v[200:203], v147 offset:55296
	ds_read_b128 v[204:207], v147 offset:56320
	global_load_lds_dwordx4 v[208:209], off
	s_add_i32 m0, s46, 0x2000
	s_add_u32 s14, s14, 0x40080
	v_lshl_add_u64 v[208:209], v[210:211], 0, s[10:11]
	s_addc_u32 s15, s15, 0
	s_add_i32 s46, s78, s7
	global_load_lds_dwordx4 v[208:209], off
	v_lshl_add_u64 v[208:209], s[14:15], 0, v[130:131]
	s_mov_b32 m0, s46
	s_nop 0
	global_load_lds_dwordx4 v[208:209], off
	v_lshl_add_u64 v[208:209], s[14:15], 0, v[134:135]
	s_add_i32 m0, s46, 0x2000
	s_nop 0
	global_load_lds_dwordx4 v[208:209], off
	v_lshl_add_u64 v[208:209], v[212:213], 0, s[10:11]
	s_mov_b32 m0, s54
	s_nop 0
	global_load_lds_dwordx4 v[208:209], off
	v_lshl_add_u64 v[208:209], v[214:215], 0, s[10:11]
	s_mov_b32 m0, s55
	s_nop 0
	global_load_lds_dwordx4 v[208:209], off
	s_waitcnt vmcnt(8)
	s_waitcnt lgkmcnt(0)
	s_barrier
	s_setprio 1
	s_waitcnt lgkmcnt(0)
	v_mfma_f32_16x16x32_bf16 v[60:63], v[140:143], v[176:179], v[60:63]
	v_mfma_f32_16x16x32_bf16 v[56:59], v[152:155], v[176:179], v[56:59]
	v_mfma_f32_16x16x32_bf16 v[52:55], v[140:143], v[184:187], v[52:55]
	v_mfma_f32_16x16x32_bf16 v[48:51], v[152:155], v[184:187], v[48:51]
	v_mfma_f32_16x16x32_bf16 v[44:47], v[140:143], v[192:195], v[44:47]
	v_mfma_f32_16x16x32_bf16 v[36:39], v[152:155], v[192:195], v[36:39]
	v_mfma_f32_16x16x32_bf16 v[28:31], v[140:143], v[200:203], v[28:31]
	v_mfma_f32_16x16x32_bf16 v[20:23], v[152:155], v[200:203], v[20:23]
	s_setprio 0
	s_setprio 1
	v_mfma_f32_16x16x32_bf16 v[60:63], v[148:151], v[180:183], v[60:63]
	v_mfma_f32_16x16x32_bf16 v[56:59], v[156:159], v[180:183], v[56:59]
	v_mfma_f32_16x16x32_bf16 v[52:55], v[148:151], v[188:191], v[52:55]
	v_mfma_f32_16x16x32_bf16 v[48:51], v[156:159], v[188:191], v[48:51]
	v_mfma_f32_16x16x32_bf16 v[44:47], v[148:151], v[196:199], v[44:47]
	v_mfma_f32_16x16x32_bf16 v[36:39], v[156:159], v[196:199], v[36:39]
	v_mfma_f32_16x16x32_bf16 v[28:31], v[148:151], v[204:207], v[28:31]
	v_mfma_f32_16x16x32_bf16 v[20:23], v[156:159], v[204:207], v[20:23]
	s_setprio 0
	s_setprio 1
	v_mfma_f32_16x16x32_bf16 v[40:43], v[160:163], v[176:179], v[40:43]
	v_mfma_f32_16x16x32_bf16 v[32:35], v[168:171], v[176:179], v[32:35]
	v_mfma_f32_16x16x32_bf16 v[24:27], v[160:163], v[184:187], v[24:27]
	v_mfma_f32_16x16x32_bf16 v[16:19], v[168:171], v[184:187], v[16:19]
	v_mfma_f32_16x16x32_bf16 v[12:15], v[160:163], v[192:195], v[12:15]
	v_mfma_f32_16x16x32_bf16 v[8:11], v[168:171], v[192:195], v[8:11]
	v_mfma_f32_16x16x32_bf16 v[4:7], v[160:163], v[200:203], v[4:7]
	v_mfma_f32_16x16x32_bf16 v[0:3], v[168:171], v[200:203], v[0:3]
	s_setprio 0
	s_setprio 1
	v_mfma_f32_16x16x32_bf16 v[40:43], v[164:167], v[180:183], v[40:43]
	v_mfma_f32_16x16x32_bf16 v[32:35], v[172:175], v[180:183], v[32:35]
	v_mfma_f32_16x16x32_bf16 v[24:27], v[164:167], v[188:191], v[24:27]
	v_mfma_f32_16x16x32_bf16 v[16:19], v[172:175], v[188:191], v[16:19]
	v_mfma_f32_16x16x32_bf16 v[12:15], v[164:167], v[196:199], v[12:15]
	v_mfma_f32_16x16x32_bf16 v[8:11], v[172:175], v[196:199], v[8:11]
	v_mfma_f32_16x16x32_bf16 v[4:7], v[164:167], v[204:207], v[4:7]
	v_mfma_f32_16x16x32_bf16 v[0:3], v[172:175], v[204:207], v[0:3]
	s_setprio 0
	s_barrier
	s_add_i32 s76, s76, 2
	s_add_u32 s52, s52, 0x100
	s_addc_u32 s53, s53, 0
	s_add_u32 s74, s74, 0x100
	s_addc_u32 s75, s75, 0
	s_cmp_gt_u32 s76, 13
	s_cbranch_scc0 .LBB0_1099

; #define G_STAGE(bufoff, gbase, voff) do { _Pragma("unroll") for (int _i = 0; _i < 2; ++_i) \
;         __builtin_amdgcn_global_load_lds((const unsigned*)((const char*)(gbase) + voff[_i]), (LAS unsigned*)(lds + (bufoff) + ldsw + _i * 8192), 16, 0, 0); } while (0)
; #define G_LDA(dst, b, h) do { _Pragma("unroll") for (int m = 0; m < 4; ++m) _Pragma("unroll") for (int k = 0; k < 2; ++k) dst[m][k] = *(const LAS bf16x8*)(lds + G_SA(b, h) + aoff + m * 2048 + k * 1024); } while (0)
; #define G_MMA(ai, bj, At_, Bt_) do { __builtin_amdgcn_s_setprio(1); _Pragma("unroll") for (int m = 0; m < 4; ++m) _Pragma("unroll") for (int n = 0; n < 2; ++n) _Pragma("unroll") for (int k = 0; k < 2; ++k) \
;         acc[ai][bj][m][n] = __builtin_amdgcn_mfma_f32_16x16x32_bf16(Bt_[n][k], At_[m][k], acc[ai][bj][m][n], 0, 0, 0); __builtin_amdgcn_s_setprio(0); } while (0)
; #define WAIT_V(n) asm volatile("s_waitcnt vmcnt(" #n ")" ::: "memory")
; #define WAIT_L(n) asm volatile("s_waitcnt lgkmcnt(" #n ")" ::: "memory")
; #define BAR __builtin_amdgcn_s_barrier()
; #define SCHED __builtin_amdgcn_sched_barrier(0)
; template <class Get, class Epi>
; DI void gemm_loop(int ntiles, int ld, char* shm, const Get& get, const Epi& epi) {
;     ...
;             WAIT_V(8); WAIT_L(0); BAR; G_MMA(0, 0, At, B0); G_MMA(0, 1, At, B1); BAR; SCHED;
;             G_LDA(At, 0, 1); G_STAGE(G_SB(0, 0), b2, voffB); G_STAGE(G_SB(0, 1), b2 + hstep, voffB); G_STAGE(G_SA(0, 0), a2, voffA);
;             WAIT_V(8); WAIT_L(0); BAR; G_MMA(1, 0, At, B0); G_MMA(1, 1, At, B1); BAR; SCHED;
.Lrj_1463_0:
	s_waitcnt lgkmcnt(0)
	s_barrier
	s_setprio 1
	s_waitcnt lgkmcnt(0)
	v_mfma_f32_16x16x32_bf16 v[124:127], v[128:131], v[180:183], 0
	v_mfma_f32_16x16x32_bf16 v[120:123], v[136:139], v[180:183], 0
	v_mfma_f32_16x16x32_bf16 v[116:119], v[128:131], v[188:191], 0
	v_mfma_f32_16x16x32_bf16 v[112:115], v[136:139], v[188:191], 0
	v_mfma_f32_16x16x32_bf16 v[108:111], v[128:131], v[196:199], 0
	v_mfma_f32_16x16x32_bf16 v[104:107], v[136:139], v[196:199], 0
	v_mfma_f32_16x16x32_bf16 v[100:103], v[128:131], v[204:207], 0
	v_mfma_f32_16x16x32_bf16 v[96:99], v[136:139], v[204:207], 0
	s_setprio 0
	s_setprio 1
	v_mfma_f32_16x16x32_bf16 v[124:127], v[132:135], v[184:187], v[124:127]
	v_mfma_f32_16x16x32_bf16 v[120:123], v[140:143], v[184:187], v[120:123]
	v_mfma_f32_16x16x32_bf16 v[116:119], v[132:135], v[192:195], v[116:119]
	v_mfma_f32_16x16x32_bf16 v[112:115], v[140:143], v[192:195], v[112:115]
	v_mfma_f32_16x16x32_bf16 v[108:111], v[132:135], v[200:203], v[108:111]
	v_mfma_f32_16x16x32_bf16 v[104:107], v[140:143], v[200:203], v[104:107]
	v_mfma_f32_16x16x32_bf16 v[100:103], v[132:135], v[208:211], v[100:103]
	v_mfma_f32_16x16x32_bf16 v[96:99], v[140:143], v[208:211], v[96:99]
	s_setprio 0
	s_setprio 1
	v_mfma_f32_16x16x32_bf16 v[60:63], v[158:161], v[180:183], 0
	v_mfma_f32_16x16x32_bf16 v[56:59], v[172:175], v[180:183], 0
	v_mfma_f32_16x16x32_bf16 v[52:55], v[158:161], v[188:191], 0
	v_mfma_f32_16x16x32_bf16 v[48:51], v[172:175], v[188:191], 0
	v_mfma_f32_16x16x32_bf16 v[44:47], v[158:161], v[196:199], 0
	v_mfma_f32_16x16x32_bf16 v[40:43], v[172:175], v[196:199], 0
	v_mfma_f32_16x16x32_bf16 v[36:39], v[158:161], v[204:207], 0
	v_mfma_f32_16x16x32_bf16 v[32:35], v[172:175], v[204:207], 0
	s_setprio 0
	s_setprio 1
	v_mfma_f32_16x16x32_bf16 v[60:63], v[162:165], v[184:187], v[60:63]
	v_mfma_f32_16x16x32_bf16 v[56:59], v[176:179], v[184:187], v[56:59]
	v_mfma_f32_16x16x32_bf16 v[52:55], v[162:165], v[192:195], v[52:55]
	v_mfma_f32_16x16x32_bf16 v[48:51], v[176:179], v[192:195], v[48:51]
	v_mfma_f32_16x16x32_bf16 v[44:47], v[162:165], v[200:203], v[44:47]
	v_mfma_f32_16x16x32_bf16 v[40:43], v[176:179], v[200:203], v[40:43]
	v_mfma_f32_16x16x32_bf16 v[36:39], v[162:165], v[208:211], v[36:39]
	v_mfma_f32_16x16x32_bf16 v[32:35], v[176:179], v[208:211], v[32:35]
	s_setprio 0
	s_barrier
	s_add_i32 s79, s57, s7
	v_lshl_add_u64 v[144:145], s[14:15], 0, v[148:149]
	s_mov_b32 m0, s79
	ds_read_b128 v[180:183], v171 offset:16384
	ds_read_b128 v[184:187], v171 offset:17408
	ds_read_b128 v[188:191], v171 offset:18432
	ds_read_b128 v[192:195], v171 offset:19456
	ds_read_b128 v[196:199], v171 offset:20480
	ds_read_b128 v[200:203], v171 offset:21504
	ds_read_b128 v[204:207], v171 offset:22528
	ds_read_b128 v[208:211], v171 offset:23552
	global_load_lds_dwordx4 v[144:145], off
	s_add_i32 m0, s79, 0x2000
	s_add_u32 s80, s14, 0x40000
	v_lshl_add_u64 v[166:167], s[14:15], 0, v[152:153]
	s_addc_u32 s81, s15, 0
	s_add_i32 s79, s58, s7
	global_load_lds_dwordx4 v[166:167], off
	v_lshl_add_u64 v[212:213], s[80:81], 0, v[148:149]
	s_mov_b32 m0, s79
	v_lshl_add_u64 v[214:215], s[46:47], 0, v[150:151]
	global_load_lds_dwordx4 v[212:213], off
	v_lshl_add_u64 v[212:213], s[80:81], 0, v[152:153]
	s_add_i32 m0, s79, 0x2000
	s_nop 0
	global_load_lds_dwordx4 v[212:213], off
	v_lshl_add_u64 v[212:213], s[46:47], 0, v[146:147]
	s_mov_b32 m0, s45
	s_nop 0
	global_load_lds_dwordx4 v[212:213], off
	s_mov_b32 m0, s50
	s_nop 0
	global_load_lds_dwordx4 v[214:215], off
	s_cmp_lg_u32 s100, 0
	s_cbranch_scc0 .Lrf_1463_1
	s_waitcnt vmcnt(16)
	s_branch .Lrj_1463_1

; #define G_STAGE(bufoff, gbase, voff) do { _Pragma("unroll") for (int _i = 0; _i < 2; ++_i) \
;         __builtin_amdgcn_global_load_lds((const unsigned*)((const char*)(gbase) + voff[_i]), (LAS unsigned*)(lds + (bufoff) + ldsw + _i * 8192), 16, 0, 0); } while (0)
; #define G_LDA(dst, b, h) do { _Pragma("unroll") for (int m = 0; m < 4; ++m) _Pragma("unroll") for (int k = 0; k < 2; ++k) dst[m][k] = *(const LAS bf16x8*)(lds + G_SA(b, h) + aoff + m * 2048 + k * 1024); } while (0)
; #define G_LDB(dst, b, h) do { _Pragma("unroll") for (int n = 0; n < 2; ++n) _Pragma("unroll") for (int k = 0; k < 2; ++k) dst[n][k] = *(const LAS bf16x8*)(lds + G_SB(b, h) + boff + n * 2048 + k * 1024); } while (0)
; #define G_MMA(ai, bj, At_, Bt_) do { __builtin_amdgcn_s_setprio(1); _Pragma("unroll") for (int m = 0; m < 4; ++m) _Pragma("unroll") for (int n = 0; n < 2; ++n) _Pragma("unroll") for (int k = 0; k < 2; ++k) \
;         acc[ai][bj][m][n] = __builtin_amdgcn_mfma_f32_16x16x32_bf16(Bt_[n][k], At_[m][k], acc[ai][bj][m][n], 0, 0, 0); __builtin_amdgcn_s_setprio(0); } while (0)
; #define WAIT_V(n) asm volatile("s_waitcnt vmcnt(" #n ")" ::: "memory")
; #define WAIT_L(n) asm volatile("s_waitcnt lgkmcnt(" #n ")" ::: "memory")
; #define BAR __builtin_amdgcn_s_barrier()
; #define SCHED __builtin_amdgcn_sched_barrier(0)
; template <class Get, class Epi>
; DI void gemm_loop(int ntiles, int ld, char* shm, const Get& get, const Epi& epi) {
;     ...
;             WAIT_V(8); WAIT_L(0); BAR; G_MMA(1, 0, At, B0); G_MMA(1, 1, At, B1); BAR; SCHED;
;             G_LDB(B0, 1, 0); G_LDB(B1, 1, 1); SCHED; G_LDA(At, 1, 0); G_STAGE(G_SA(0, 1), a2 + hstep, voffA);
;             WAIT_V(8); WAIT_L(0); BAR; G_MMA(0, 0, At, B0); G_MMA(0, 1, At, B1); BAR; SCHED;
.Lrj_1463_1:
	s_waitcnt lgkmcnt(0)
	s_barrier
	s_setprio 1
	s_waitcnt lgkmcnt(0)
	v_mfma_f32_16x16x32_bf16 v[92:95], v[128:131], v[180:183], 0
	v_mfma_f32_16x16x32_bf16 v[88:91], v[136:139], v[180:183], 0
	v_mfma_f32_16x16x32_bf16 v[84:87], v[128:131], v[188:191], 0
	v_mfma_f32_16x16x32_bf16 v[80:83], v[136:139], v[188:191], 0
	v_mfma_f32_16x16x32_bf16 v[76:79], v[128:131], v[196:199], 0
	v_mfma_f32_16x16x32_bf16 v[72:75], v[136:139], v[196:199], 0
	v_mfma_f32_16x16x32_bf16 v[68:71], v[128:131], v[204:207], 0
	v_mfma_f32_16x16x32_bf16 v[64:67], v[136:139], v[204:207], 0
	s_setprio 0
	s_setprio 1
	v_mfma_f32_16x16x32_bf16 v[92:95], v[132:135], v[184:187], v[92:95]
	v_mfma_f32_16x16x32_bf16 v[88:91], v[140:143], v[184:187], v[88:91]
	v_mfma_f32_16x16x32_bf16 v[84:87], v[132:135], v[192:195], v[84:87]
	v_mfma_f32_16x16x32_bf16 v[80:83], v[140:143], v[192:195], v[80:83]
	v_mfma_f32_16x16x32_bf16 v[76:79], v[132:135], v[200:203], v[76:79]
	v_mfma_f32_16x16x32_bf16 v[72:75], v[140:143], v[200:203], v[72:75]
	v_mfma_f32_16x16x32_bf16 v[68:71], v[132:135], v[208:211], v[68:71]
	v_mfma_f32_16x16x32_bf16 v[64:67], v[140:143], v[208:211], v[64:67]
	s_setprio 0
	s_setprio 1
	v_mfma_f32_16x16x32_bf16 v[28:31], v[158:161], v[180:183], 0
	v_mfma_f32_16x16x32_bf16 v[24:27], v[172:175], v[180:183], 0
	v_mfma_f32_16x16x32_bf16 v[20:23], v[158:161], v[188:191], 0
	v_mfma_f32_16x16x32_bf16 v[16:19], v[172:175], v[188:191], 0
	v_mfma_f32_16x16x32_bf16 v[12:15], v[158:161], v[196:199], 0
	v_mfma_f32_16x16x32_bf16 v[8:11], v[172:175], v[196:199], 0
	v_mfma_f32_16x16x32_bf16 v[4:7], v[158:161], v[204:207], 0
	v_mfma_f32_16x16x32_bf16 v[0:3], v[172:175], v[204:207], 0
	s_setprio 0
	s_setprio 1
	v_mfma_f32_16x16x32_bf16 v[28:31], v[162:165], v[184:187], v[28:31]
	v_mfma_f32_16x16x32_bf16 v[24:27], v[176:179], v[184:187], v[24:27]
	v_mfma_f32_16x16x32_bf16 v[20:23], v[162:165], v[192:195], v[20:23]
	v_mfma_f32_16x16x32_bf16 v[16:19], v[176:179], v[192:195], v[16:19]
	v_mfma_f32_16x16x32_bf16 v[12:15], v[162:165], v[200:203], v[12:15]
	v_mfma_f32_16x16x32_bf16 v[8:11], v[176:179], v[200:203], v[8:11]
	v_mfma_f32_16x16x32_bf16 v[4:7], v[162:165], v[208:211], v[4:7]
	v_mfma_f32_16x16x32_bf16 v[0:3], v[176:179], v[208:211], v[0:3]
	s_setprio 0
	s_barrier
	s_add_i32 s79, 0, 0x18000
	s_add_i32 s80, 0, 0x1c000
	v_add_u32_e32 v140, s79, v168
	v_add_u32_e32 v176, s80, v168
	ds_read_b128 v[128:131], v140
	ds_read_b128 v[132:135], v140 offset:1024
	ds_read_b128 v[136:139], v140 offset:2048
	ds_read_b128 v[140:143], v140 offset:3072
	ds_read_b128 v[158:161], v176
	ds_read_b128 v[162:165], v176 offset:1024
	ds_read_b128 v[172:175], v176 offset:2048
	ds_read_b128 v[176:179], v176 offset:3072
	s_add_u32 s46, s46, 0x40000
	s_addc_u32 s47, s47, 0
	s_mov_b32 m0, s51
	v_lshl_add_u64 v[216:217], s[46:47], 0, v[146:147]
	ds_read_b128 v[180:183], v171 offset:32768
	ds_read_b128 v[184:187], v171 offset:33792
	ds_read_b128 v[188:191], v171 offset:34816
	ds_read_b128 v[192:195], v171 offset:35840
	ds_read_b128 v[196:199], v171 offset:36864
	ds_read_b128 v[200:203], v171 offset:37888
	ds_read_b128 v[204:207], v171 offset:38912
	ds_read_b128 v[208:211], v171 offset:39936
	global_load_lds_dwordx4 v[216:217], off
	v_lshl_add_u64 v[216:217], s[46:47], 0, v[150:151]
	s_mov_b32 m0, s52
	s_nop 0
	global_load_lds_dwordx4 v[216:217], off
	s_waitcnt vmcnt(8)
	s_waitcnt lgkmcnt(0)
	s_barrier
	s_setprio 1
	s_waitcnt lgkmcnt(0)
	v_mfma_f32_16x16x32_bf16 v[124:127], v[128:131], v[180:183], v[124:127]
	v_mfma_f32_16x16x32_bf16 v[120:123], v[136:139], v[180:183], v[120:123]
	v_mfma_f32_16x16x32_bf16 v[116:119], v[128:131], v[188:191], v[116:119]
	v_mfma_f32_16x16x32_bf16 v[112:115], v[136:139], v[188:191], v[112:115]
	v_mfma_f32_16x16x32_bf16 v[108:111], v[128:131], v[196:199], v[108:111]
	v_mfma_f32_16x16x32_bf16 v[104:107], v[136:139], v[196:199], v[104:107]
	v_mfma_f32_16x16x32_bf16 v[100:103], v[128:131], v[204:207], v[100:103]
	v_mfma_f32_16x16x32_bf16 v[96:99], v[136:139], v[204:207], v[96:99]
	s_setprio 0
	s_setprio 1
	v_mfma_f32_16x16x32_bf16 v[124:127], v[132:135], v[184:187], v[124:127]
	v_mfma_f32_16x16x32_bf16 v[120:123], v[140:143], v[184:187], v[120:123]
	v_mfma_f32_16x16x32_bf16 v[116:119], v[132:135], v[192:195], v[116:119]
	v_mfma_f32_16x16x32_bf16 v[112:115], v[140:143], v[192:195], v[112:115]
	v_mfma_f32_16x16x32_bf16 v[108:111], v[132:135], v[200:203], v[108:111]
	v_mfma_f32_16x16x32_bf16 v[104:107], v[140:143], v[200:203], v[104:107]
	v_mfma_f32_16x16x32_bf16 v[100:103], v[132:135], v[208:211], v[100:103]
	v_mfma_f32_16x16x32_bf16 v[96:99], v[140:143], v[208:211], v[96:99]
	s_setprio 0
	s_setprio 1
	v_mfma_f32_16x16x32_bf16 v[60:63], v[158:161], v[180:183], v[60:63]
	v_mfma_f32_16x16x32_bf16 v[56:59], v[172:175], v[180:183], v[56:59]
	v_mfma_f32_16x16x32_bf16 v[52:55], v[158:161], v[188:191], v[52:55]
	v_mfma_f32_16x16x32_bf16 v[48:51], v[172:175], v[188:191], v[48:51]
	v_mfma_f32_16x16x32_bf16 v[44:47], v[158:161], v[196:199], v[44:47]
	v_mfma_f32_16x16x32_bf16 v[40:43], v[172:175], v[196:199], v[40:43]
	v_mfma_f32_16x16x32_bf16 v[36:39], v[158:161], v[204:207], v[36:39]
	v_mfma_f32_16x16x32_bf16 v[32:35], v[172:175], v[204:207], v[32:35]
	s_setprio 0
	s_setprio 1
	v_mfma_f32_16x16x32_bf16 v[60:63], v[162:165], v[184:187], v[60:63]
	v_mfma_f32_16x16x32_bf16 v[56:59], v[176:179], v[184:187], v[56:59]
	v_mfma_f32_16x16x32_bf16 v[52:55], v[162:165], v[192:195], v[52:55]
	v_mfma_f32_16x16x32_bf16 v[48:51], v[176:179], v[192:195], v[48:51]
	v_mfma_f32_16x16x32_bf16 v[44:47], v[162:165], v[200:203], v[44:47]
	v_mfma_f32_16x16x32_bf16 v[40:43], v[176:179], v[200:203], v[40:43]
	v_mfma_f32_16x16x32_bf16 v[36:39], v[162:165], v[208:211], v[36:39]
	v_mfma_f32_16x16x32_bf16 v[32:35], v[176:179], v[208:211], v[32:35]
	s_setprio 0
	s_barrier
; #define G_STAGE(bufoff, gbase, voff) do { _Pragma("unroll") for (int _i = 0; _i < 2; ++_i) \
;         __builtin_amdgcn_global_load_lds((const unsigned*)((const char*)(gbase) + voff[_i]), (LAS unsigned*)(lds + (bufoff) + ldsw + _i * 8192), 16, 0, 0); } while (0)
; #define G_LDA(dst, b, h) do { _Pragma("unroll") for (int m = 0; m < 4; ++m) _Pragma("unroll") for (int k = 0; k < 2; ++k) dst[m][k] = *(const LAS bf16x8*)(lds + G_SA(b, h) + aoff + m * 2048 + k * 1024); } while (0)
; #define G_LDB(dst, b, h) do { _Pragma("unroll") for (int n = 0; n < 2; ++n) _Pragma("unroll") for (int k = 0; k < 2; ++k) dst[n][k] = *(const LAS bf16x8*)(lds + G_SB(b, h) + boff + n * 2048 + k * 1024); } while (0)
; #define WAIT_V(n) asm volatile("s_waitcnt vmcnt(" #n ")" ::: "memory")
; #define WAIT_L(n) asm volatile("s_waitcnt lgkmcnt(" #n ")" ::: "memory")
; #define BAR __builtin_amdgcn_s_barrier()
; #define SCHED __builtin_amdgcn_sched_barrier(0)
; template <class Get, class Epi>
; DI void gemm_loop(int ntiles, int ld, char* shm, const Get& get, const Epi& epi) {
;     ...
;         for (int t = 0; t < nt; t += 2) {
;             const bool last = (t == nt - 2);
;             const char* a1 = cA + (size_t)(t + 1) * kstep;
;             const char* a2 = last ? nA : cA + (size_t)(t + 2) * kstep; const char* b2 = last ? nB : cB + (size_t)(t + 2) * kstep;
;             const char* a3 = a2 + kstep; const char* b3 = b2 + kstep;
;             G_LDB(B0, 0, 0); G_LDB(B1, 0, 1); SCHED; G_LDA(At, 0, 0); G_STAGE(G_SA(1, 1), a1 + hstep, voffA);
;             WAIT_V(8); WAIT_L(0); BAR; G_MMA(0, 0, At, B0); G_MMA(0, 1, At, B1); BAR; SCHED;
;             G_LDA(At, 0, 1); G_STAGE(G_SB(0, 0), b2, voffB); G_STAGE(G_SB(0, 1), b2 + hstep, voffB); G_STAGE(G_SA(0, 0), a2, voffA);
;             WAIT_V(8); WAIT_L(0); BAR; G_MMA(1, 0, At, B0); G_MMA(1, 1, At, B1); BAR; SCHED;
;             G_LDB(B0, 1, 0); G_LDB(B1, 1, 1); SCHED; G_LDA(At, 1, 0); G_STAGE(G_SA(0, 1), a2 + hstep, voffA);
;             WAIT_V(8); WAIT_L(0); BAR; G_MMA(0, 0, At, B0); G_MMA(0, 1, At, B1); BAR; SCHED;
;             G_LDA(At, 1, 1); G_STAGE(G_SB(1, 0), b3, voffB); G_STAGE(G_SB(1, 1), b3 + hstep, voffB); G_STAGE(G_SA(1, 0), a3, voffA);
;             WAIT_V(8); WAIT_L(0); BAR; G_MMA(1, 0, At, B0); G_MMA(1, 1, At, B1); BAR; SCHED;
	s_add_i32 s46, s79, s7
	v_lshl_add_u64 v[144:145], v[144:145], 0, s[10:11]
	s_mov_b32 m0, s46
	ds_read_b128 v[180:183], v171 offset:49152
	ds_read_b128 v[184:187], v171 offset:50176
	ds_read_b128 v[188:191], v171 offset:51200
	ds_read_b128 v[192:195], v171 offset:52224
	ds_read_b128 v[196:199], v171 offset:53248
	ds_read_b128 v[200:203], v171 offset:54272
	ds_read_b128 v[204:207], v171 offset:55296
	ds_read_b128 v[208:211], v171 offset:56320
	global_load_lds_dwordx4 v[144:145], off
	s_add_i32 m0, s46, 0x2000
	s_add_u32 s14, s14, 0x40080
	v_lshl_add_u64 v[144:145], v[166:167], 0, s[10:11]
	s_addc_u32 s15, s15, 0
	s_add_i32 s46, s80, s7
	global_load_lds_dwordx4 v[144:145], off
	v_lshl_add_u64 v[144:145], s[14:15], 0, v[148:149]
	s_mov_b32 m0, s46
	s_nop 0
	global_load_lds_dwordx4 v[144:145], off
	v_lshl_add_u64 v[144:145], s[14:15], 0, v[152:153]
	s_add_i32 m0, s46, 0x2000
	s_nop 0
	global_load_lds_dwordx4 v[144:145], off
	v_lshl_add_u64 v[144:145], v[212:213], 0, s[10:11]
	s_mov_b32 m0, s55
	s_nop 0
	global_load_lds_dwordx4 v[144:145], off
	v_lshl_add_u64 v[144:145], v[214:215], 0, s[10:11]
	s_mov_b32 m0, s56
	s_nop 0
	global_load_lds_dwordx4 v[144:145], off
	s_waitcnt vmcnt(8)
	s_waitcnt lgkmcnt(0)
	s_barrier
	s_setprio 1
	s_waitcnt lgkmcnt(0)
	v_mfma_f32_16x16x32_bf16 v[92:95], v[128:131], v[180:183], v[92:95]
	v_mfma_f32_16x16x32_bf16 v[88:91], v[136:139], v[180:183], v[88:91]
	v_mfma_f32_16x16x32_bf16 v[84:87], v[128:131], v[188:191], v[84:87]
	v_mfma_f32_16x16x32_bf16 v[80:83], v[136:139], v[188:191], v[80:83]
	v_mfma_f32_16x16x32_bf16 v[76:79], v[128:131], v[196:199], v[76:79]
	v_mfma_f32_16x16x32_bf16 v[72:75], v[136:139], v[196:199], v[72:75]
	v_mfma_f32_16x16x32_bf16 v[68:71], v[128:131], v[204:207], v[68:71]
	v_mfma_f32_16x16x32_bf16 v[64:67], v[136:139], v[204:207], v[64:67]
	s_setprio 0
	s_setprio 1
	v_mfma_f32_16x16x32_bf16 v[92:95], v[132:135], v[184:187], v[92:95]
	v_mfma_f32_16x16x32_bf16 v[88:91], v[140:143], v[184:187], v[88:91]
	v_mfma_f32_16x16x32_bf16 v[84:87], v[132:135], v[192:195], v[84:87]
	v_mfma_f32_16x16x32_bf16 v[80:83], v[140:143], v[192:195], v[80:83]
	v_mfma_f32_16x16x32_bf16 v[76:79], v[132:135], v[200:203], v[76:79]
	v_mfma_f32_16x16x32_bf16 v[72:75], v[140:143], v[200:203], v[72:75]
	v_mfma_f32_16x16x32_bf16 v[68:71], v[132:135], v[208:211], v[68:71]
	v_mfma_f32_16x16x32_bf16 v[64:67], v[140:143], v[208:211], v[64:67]
	s_setprio 0
	s_setprio 1
	v_mfma_f32_16x16x32_bf16 v[28:31], v[158:161], v[180:183], v[28:31]
	v_mfma_f32_16x16x32_bf16 v[24:27], v[172:175], v[180:183], v[24:27]
	v_mfma_f32_16x16x32_bf16 v[20:23], v[158:161], v[188:191], v[20:23]
	v_mfma_f32_16x16x32_bf16 v[16:19], v[172:175], v[188:191], v[16:19]
	v_mfma_f32_16x16x32_bf16 v[12:15], v[158:161], v[196:199], v[12:15]
	v_mfma_f32_16x16x32_bf16 v[8:11], v[172:175], v[196:199], v[8:11]
	v_mfma_f32_16x16x32_bf16 v[4:7], v[158:161], v[204:207], v[4:7]
	v_mfma_f32_16x16x32_bf16 v[0:3], v[172:175], v[204:207], v[0:3]
	s_setprio 0
	s_setprio 1
	v_mfma_f32_16x16x32_bf16 v[28:31], v[162:165], v[184:187], v[28:31]
	v_mfma_f32_16x16x32_bf16 v[24:27], v[176:179], v[184:187], v[24:27]
	v_mfma_f32_16x16x32_bf16 v[20:23], v[162:165], v[192:195], v[20:23]
	v_mfma_f32_16x16x32_bf16 v[16:19], v[176:179], v[192:195], v[16:19]
	v_mfma_f32_16x16x32_bf16 v[12:15], v[162:165], v[200:203], v[12:15]
	v_mfma_f32_16x16x32_bf16 v[8:11], v[176:179], v[200:203], v[8:11]
	v_mfma_f32_16x16x32_bf16 v[4:7], v[162:165], v[208:211], v[4:7]
	v_mfma_f32_16x16x32_bf16 v[0:3], v[176:179], v[208:211], v[0:3]
	s_setprio 0
	s_barrier
	s_add_u32 s48, s48, 0x100
	s_addc_u32 s49, s49, 0
	s_add_u32 s76, s76, 0x100
	s_addc_u32 s77, s77, 0
	s_cmp_ge_u32 s78, s74
	s_mov_b32 s14, s78
	s_cbranch_scc0 .LBB0_1463
	s_branch .Lpost_1463
.LBB0_1463:
	ds_read_b128 v[128:131], v169
	ds_read_b128 v[132:135], v169 offset:1024
	ds_read_b128 v[136:139], v169 offset:2048
	ds_read_b128 v[140:143], v169 offset:3072
	ds_read_b128 v[158:161], v170
	ds_read_b128 v[162:165], v170 offset:1024
	ds_read_b128 v[172:175], v170 offset:2048
	ds_read_b128 v[176:179], v170 offset:3072
	s_add_i32 s78, s14, 2
	s_add_u32 s15, s48, 0xfffc0080
	s_addc_u32 s46, s49, -1
	s_cmp_eq_u32 s75, s14
	s_cselect_b32 s14, s73, s76
	s_cselect_b32 s47, s3, s46
	s_cselect_b32 s46, s37, s15
	s_cselect_b32 s15, s39, s77
	v_lshl_add_u64 v[144:145], s[48:49], 0, v[154:155]
	s_add_i32 m0, s45, 0xc000
	ds_read_b128 v[180:183], v171
	ds_read_b128 v[184:187], v171 offset:1024
	ds_read_b128 v[188:191], v171 offset:2048
	ds_read_b128 v[192:195], v171 offset:3072
	ds_read_b128 v[196:199], v171 offset:4096
	ds_read_b128 v[200:203], v171 offset:5120
	ds_read_b128 v[204:207], v171 offset:6144
	ds_read_b128 v[208:211], v171 offset:7168
	global_load_lds_dwordx4 v[144:145], off
	v_lshl_add_u64 v[144:145], s[48:49], 0, v[156:157]
	s_add_i32 m0, s45, 0xe000
	s_nop 0
	global_load_lds_dwordx4 v[144:145], off
	s_waitcnt vmcnt(8)
	s_waitcnt lgkmcnt(0)
	s_barrier
; #define G_STAGE(bufoff, gbase, voff) do { _Pragma("unroll") for (int _i = 0; _i < 2; ++_i) \
;         __builtin_amdgcn_global_load_lds((const unsigned*)((const char*)(gbase) + voff[_i]), (LAS unsigned*)(lds + (bufoff) + ldsw + _i * 8192), 16, 0, 0); } while (0)
; #define G_LDA(dst, b, h) do { _Pragma("unroll") for (int m = 0; m < 4; ++m) _Pragma("unroll") for (int k = 0; k < 2; ++k) dst[m][k] = *(const LAS bf16x8*)(lds + G_SA(b, h) + aoff + m * 2048 + k * 1024); } while (0)
; #define G_MMA(ai, bj, At_, Bt_) do { __builtin_amdgcn_s_setprio(1); _Pragma("unroll") for (int m = 0; m < 4; ++m) _Pragma("unroll") for (int n = 0; n < 2; ++n) _Pragma("unroll") for (int k = 0; k < 2; ++k) \
;         acc[ai][bj][m][n] = __builtin_amdgcn_mfma_f32_16x16x32_bf16(Bt_[n][k], At_[m][k], acc[ai][bj][m][n], 0, 0, 0); __builtin_amdgcn_s_setprio(0); } while (0)
; #define WAIT_V(n) asm volatile("s_waitcnt vmcnt(" #n ")" ::: "memory")
; #define WAIT_L(n) asm volatile("s_waitcnt lgkmcnt(" #n ")" ::: "memory")
; #define BAR __builtin_amdgcn_s_barrier()
; #define SCHED __builtin_amdgcn_sched_barrier(0)
; template <class Get, class Epi>
; DI void gemm_loop(int ntiles, int ld, char* shm, const Get& get, const Epi& epi) {
;     ...
;             WAIT_V(8); WAIT_L(0); BAR; G_MMA(0, 0, At, B0); G_MMA(0, 1, At, B1); BAR; SCHED;
;             G_LDA(At, 0, 1); G_STAGE(G_SB(0, 0), b2, voffB); G_STAGE(G_SB(0, 1), b2 + hstep, voffB); G_STAGE(G_SA(0, 0), a2, voffA);
;             WAIT_V(8); WAIT_L(0); BAR; G_MMA(1, 0, At, B0); G_MMA(1, 1, At, B1); BAR; SCHED;
	s_setprio 1
	s_waitcnt lgkmcnt(0)
	v_mfma_f32_16x16x32_bf16 v[124:127], v[128:131], v[180:183], v[124:127]
	v_mfma_f32_16x16x32_bf16 v[120:123], v[136:139], v[180:183], v[120:123]
	v_mfma_f32_16x16x32_bf16 v[116:119], v[128:131], v[188:191], v[116:119]
	v_mfma_f32_16x16x32_bf16 v[112:115], v[136:139], v[188:191], v[112:115]
	v_mfma_f32_16x16x32_bf16 v[108:111], v[128:131], v[196:199], v[108:111]
	v_mfma_f32_16x16x32_bf16 v[104:107], v[136:139], v[196:199], v[104:107]
	v_mfma_f32_16x16x32_bf16 v[100:103], v[128:131], v[204:207], v[100:103]
	v_mfma_f32_16x16x32_bf16 v[96:99], v[136:139], v[204:207], v[96:99]
	s_setprio 0
	s_setprio 1
	v_mfma_f32_16x16x32_bf16 v[124:127], v[132:135], v[184:187], v[124:127]
	v_mfma_f32_16x16x32_bf16 v[120:123], v[140:143], v[184:187], v[120:123]
	v_mfma_f32_16x16x32_bf16 v[116:119], v[132:135], v[192:195], v[116:119]
	v_mfma_f32_16x16x32_bf16 v[112:115], v[140:143], v[192:195], v[112:115]
	v_mfma_f32_16x16x32_bf16 v[108:111], v[132:135], v[200:203], v[108:111]
	v_mfma_f32_16x16x32_bf16 v[104:107], v[140:143], v[200:203], v[104:107]
	v_mfma_f32_16x16x32_bf16 v[100:103], v[132:135], v[208:211], v[100:103]
	v_mfma_f32_16x16x32_bf16 v[96:99], v[140:143], v[208:211], v[96:99]
	s_setprio 0
	s_setprio 1
	v_mfma_f32_16x16x32_bf16 v[60:63], v[158:161], v[180:183], v[60:63]
	v_mfma_f32_16x16x32_bf16 v[56:59], v[172:175], v[180:183], v[56:59]
	v_mfma_f32_16x16x32_bf16 v[52:55], v[158:161], v[188:191], v[52:55]
	v_mfma_f32_16x16x32_bf16 v[48:51], v[172:175], v[188:191], v[48:51]
	v_mfma_f32_16x16x32_bf16 v[44:47], v[158:161], v[196:199], v[44:47]
	v_mfma_f32_16x16x32_bf16 v[40:43], v[172:175], v[196:199], v[40:43]
	v_mfma_f32_16x16x32_bf16 v[36:39], v[158:161], v[204:207], v[36:39]
	v_mfma_f32_16x16x32_bf16 v[32:35], v[172:175], v[204:207], v[32:35]
	s_setprio 0
	s_setprio 1
	v_mfma_f32_16x16x32_bf16 v[60:63], v[162:165], v[184:187], v[60:63]
	v_mfma_f32_16x16x32_bf16 v[56:59], v[176:179], v[184:187], v[56:59]
	v_mfma_f32_16x16x32_bf16 v[52:55], v[162:165], v[192:195], v[52:55]
	v_mfma_f32_16x16x32_bf16 v[48:51], v[176:179], v[192:195], v[48:51]
	v_mfma_f32_16x16x32_bf16 v[44:47], v[162:165], v[200:203], v[44:47]
	v_mfma_f32_16x16x32_bf16 v[40:43], v[176:179], v[200:203], v[40:43]
	v_mfma_f32_16x16x32_bf16 v[36:39], v[162:165], v[208:211], v[36:39]
	v_mfma_f32_16x16x32_bf16 v[32:35], v[176:179], v[208:211], v[32:35]
	s_setprio 0
	s_barrier
	s_add_i32 s79, s57, s7
	v_lshl_add_u64 v[144:145], s[14:15], 0, v[148:149]
	s_mov_b32 m0, s79
	ds_read_b128 v[180:183], v171 offset:16384
	ds_read_b128 v[184:187], v171 offset:17408
	ds_read_b128 v[188:191], v171 offset:18432
	ds_read_b128 v[192:195], v171 offset:19456
	ds_read_b128 v[196:199], v171 offset:20480
	ds_read_b128 v[200:203], v171 offset:21504
	ds_read_b128 v[204:207], v171 offset:22528
	ds_read_b128 v[208:211], v171 offset:23552
	global_load_lds_dwordx4 v[144:145], off
	s_add_i32 m0, s79, 0x2000
	s_add_u32 s80, s14, 0x40000
	v_lshl_add_u64 v[166:167], s[14:15], 0, v[152:153]
	s_addc_u32 s81, s15, 0
	s_add_i32 s79, s58, s7
	global_load_lds_dwordx4 v[166:167], off
	v_lshl_add_u64 v[212:213], s[80:81], 0, v[148:149]
	s_mov_b32 m0, s79
	v_lshl_add_u64 v[214:215], s[46:47], 0, v[150:151]
	global_load_lds_dwordx4 v[212:213], off
	v_lshl_add_u64 v[212:213], s[80:81], 0, v[152:153]
	s_add_i32 m0, s79, 0x2000
	s_nop 0
	global_load_lds_dwordx4 v[212:213], off
	v_lshl_add_u64 v[212:213], s[46:47], 0, v[146:147]
	s_mov_b32 m0, s45
	s_nop 0
	global_load_lds_dwordx4 v[212:213], off
	s_mov_b32 m0, s50
	s_nop 0
	global_load_lds_dwordx4 v[214:215], off
	s_waitcnt vmcnt(8)
	s_waitcnt lgkmcnt(0)
	s_barrier
	s_setprio 1
	s_waitcnt lgkmcnt(0)
	v_mfma_f32_16x16x32_bf16 v[92:95], v[128:131], v[180:183], v[92:95]
	v_mfma_f32_16x16x32_bf16 v[88:91], v[136:139], v[180:183], v[88:91]
	v_mfma_f32_16x16x32_bf16 v[84:87], v[128:131], v[188:191], v[84:87]
	v_mfma_f32_16x16x32_bf16 v[80:83], v[136:139], v[188:191], v[80:83]
	v_mfma_f32_16x16x32_bf16 v[76:79], v[128:131], v[196:199], v[76:79]
	v_mfma_f32_16x16x32_bf16 v[72:75], v[136:139], v[196:199], v[72:75]
	v_mfma_f32_16x16x32_bf16 v[68:71], v[128:131], v[204:207], v[68:71]
	v_mfma_f32_16x16x32_bf16 v[64:67], v[136:139], v[204:207], v[64:67]
	s_setprio 0
	s_setprio 1
	v_mfma_f32_16x16x32_bf16 v[92:95], v[132:135], v[184:187], v[92:95]
	v_mfma_f32_16x16x32_bf16 v[88:91], v[140:143], v[184:187], v[88:91]
	v_mfma_f32_16x16x32_bf16 v[84:87], v[132:135], v[192:195], v[84:87]
	v_mfma_f32_16x16x32_bf16 v[80:83], v[140:143], v[192:195], v[80:83]
	v_mfma_f32_16x16x32_bf16 v[76:79], v[132:135], v[200:203], v[76:79]
	v_mfma_f32_16x16x32_bf16 v[72:75], v[140:143], v[200:203], v[72:75]
	v_mfma_f32_16x16x32_bf16 v[68:71], v[132:135], v[208:211], v[68:71]
	v_mfma_f32_16x16x32_bf16 v[64:67], v[140:143], v[208:211], v[64:67]
	s_setprio 0
	s_setprio 1
	v_mfma_f32_16x16x32_bf16 v[28:31], v[158:161], v[180:183], v[28:31]
	v_mfma_f32_16x16x32_bf16 v[24:27], v[172:175], v[180:183], v[24:27]
	v_mfma_f32_16x16x32_bf16 v[20:23], v[158:161], v[188:191], v[20:23]
	v_mfma_f32_16x16x32_bf16 v[16:19], v[172:175], v[188:191], v[16:19]
	v_mfma_f32_16x16x32_bf16 v[12:15], v[158:161], v[196:199], v[12:15]
	v_mfma_f32_16x16x32_bf16 v[8:11], v[172:175], v[196:199], v[8:11]
	v_mfma_f32_16x16x32_bf16 v[4:7], v[158:161], v[204:207], v[4:7]
	v_mfma_f32_16x16x32_bf16 v[0:3], v[172:175], v[204:207], v[0:3]
	s_setprio 0
	s_setprio 1
	v_mfma_f32_16x16x32_bf16 v[28:31], v[162:165], v[184:187], v[28:31]
	v_mfma_f32_16x16x32_bf16 v[24:27], v[176:179], v[184:187], v[24:27]
	v_mfma_f32_16x16x32_bf16 v[20:23], v[162:165], v[192:195], v[20:23]
	v_mfma_f32_16x16x32_bf16 v[16:19], v[176:179], v[192:195], v[16:19]
	v_mfma_f32_16x16x32_bf16 v[12:15], v[162:165], v[200:203], v[12:15]
	v_mfma_f32_16x16x32_bf16 v[8:11], v[176:179], v[200:203], v[8:11]
	v_mfma_f32_16x16x32_bf16 v[4:7], v[162:165], v[208:211], v[4:7]
	v_mfma_f32_16x16x32_bf16 v[0:3], v[176:179], v[208:211], v[0:3]
	s_setprio 0
	s_barrier
; #define G_STAGE(bufoff, gbase, voff) do { _Pragma("unroll") for (int _i = 0; _i < 2; ++_i) \
;         __builtin_amdgcn_global_load_lds((const unsigned*)((const char*)(gbase) + voff[_i]), (LAS unsigned*)(lds + (bufoff) + ldsw + _i * 8192), 16, 0, 0); } while (0)
; #define G_LDA(dst, b, h) do { _Pragma("unroll") for (int m = 0; m < 4; ++m) _Pragma("unroll") for (int k = 0; k < 2; ++k) dst[m][k] = *(const LAS bf16x8*)(lds + G_SA(b, h) + aoff + m * 2048 + k * 1024); } while (0)
; #define G_LDB(dst, b, h) do { _Pragma("unroll") for (int n = 0; n < 2; ++n) _Pragma("unroll") for (int k = 0; k < 2; ++k) dst[n][k] = *(const LAS bf16x8*)(lds + G_SB(b, h) + boff + n * 2048 + k * 1024); } while (0)
; #define G_MMA(ai, bj, At_, Bt_) do { __builtin_amdgcn_s_setprio(1); _Pragma("unroll") for (int m = 0; m < 4; ++m) _Pragma("unroll") for (int n = 0; n < 2; ++n) _Pragma("unroll") for (int k = 0; k < 2; ++k) \
;         acc[ai][bj][m][n] = __builtin_amdgcn_mfma_f32_16x16x32_bf16(Bt_[n][k], At_[m][k], acc[ai][bj][m][n], 0, 0, 0); __builtin_amdgcn_s_setprio(0); } while (0)
; #define WAIT_V(n) asm volatile("s_waitcnt vmcnt(" #n ")" ::: "memory")
; #define WAIT_L(n) asm volatile("s_waitcnt lgkmcnt(" #n ")" ::: "memory")
; #define BAR __builtin_amdgcn_s_barrier()
; #define SCHED __builtin_amdgcn_sched_barrier(0)
; template <class Get, class Epi>
; DI void gemm_loop(int ntiles, int ld, char* shm, const Get& get, const Epi& epi) {
;     ...
;             G_LDB(B0, 1, 0); G_LDB(B1, 1, 1); SCHED; G_LDA(At, 1, 0); G_STAGE(G_SA(0, 1), a2 + hstep, voffA);
;             WAIT_V(8); WAIT_L(0); BAR; G_MMA(0, 0, At, B0); G_MMA(0, 1, At, B1); BAR; SCHED;
	s_add_i32 s79, 0, 0x18000
	s_add_i32 s80, 0, 0x1c000
	v_add_u32_e32 v140, s79, v168
	v_add_u32_e32 v176, s80, v168
	ds_read_b128 v[128:131], v140
	ds_read_b128 v[132:135], v140 offset:1024
	ds_read_b128 v[136:139], v140 offset:2048
	ds_read_b128 v[140:143], v140 offset:3072
	ds_read_b128 v[158:161], v176
	ds_read_b128 v[162:165], v176 offset:1024
	ds_read_b128 v[172:175], v176 offset:2048
	ds_read_b128 v[176:179], v176 offset:3072
	s_add_u32 s46, s46, 0x40000
	s_addc_u32 s47, s47, 0
	s_mov_b32 m0, s51
	v_lshl_add_u64 v[216:217], s[46:47], 0, v[146:147]
	ds_read_b128 v[180:183], v171 offset:32768
	ds_read_b128 v[184:187], v171 offset:33792
	ds_read_b128 v[188:191], v171 offset:34816
	ds_read_b128 v[192:195], v171 offset:35840
	ds_read_b128 v[196:199], v171 offset:36864
	ds_read_b128 v[200:203], v171 offset:37888
	ds_read_b128 v[204:207], v171 offset:38912
	ds_read_b128 v[208:211], v171 offset:39936
	global_load_lds_dwordx4 v[216:217], off
	v_lshl_add_u64 v[216:217], s[46:47], 0, v[150:151]
	s_mov_b32 m0, s52
	s_nop 0
	global_load_lds_dwordx4 v[216:217], off
	s_waitcnt vmcnt(8)
	s_waitcnt lgkmcnt(0)
	s_barrier
	s_setprio 1
	s_waitcnt lgkmcnt(0)
	v_mfma_f32_16x16x32_bf16 v[124:127], v[128:131], v[180:183], v[124:127]
	v_mfma_f32_16x16x32_bf16 v[120:123], v[136:139], v[180:183], v[120:123]
	v_mfma_f32_16x16x32_bf16 v[116:119], v[128:131], v[188:191], v[116:119]
	v_mfma_f32_16x16x32_bf16 v[112:115], v[136:139], v[188:191], v[112:115]
	v_mfma_f32_16x16x32_bf16 v[108:111], v[128:131], v[196:199], v[108:111]
	v_mfma_f32_16x16x32_bf16 v[104:107], v[136:139], v[196:199], v[104:107]
	v_mfma_f32_16x16x32_bf16 v[100:103], v[128:131], v[204:207], v[100:103]
	v_mfma_f32_16x16x32_bf16 v[96:99], v[136:139], v[204:207], v[96:99]
	s_setprio 0
	s_setprio 1
	v_mfma_f32_16x16x32_bf16 v[124:127], v[132:135], v[184:187], v[124:127]
	v_mfma_f32_16x16x32_bf16 v[120:123], v[140:143], v[184:187], v[120:123]
	v_mfma_f32_16x16x32_bf16 v[116:119], v[132:135], v[192:195], v[116:119]
	v_mfma_f32_16x16x32_bf16 v[112:115], v[140:143], v[192:195], v[112:115]
	v_mfma_f32_16x16x32_bf16 v[108:111], v[132:135], v[200:203], v[108:111]
	v_mfma_f32_16x16x32_bf16 v[104:107], v[140:143], v[200:203], v[104:107]
	v_mfma_f32_16x16x32_bf16 v[100:103], v[132:135], v[208:211], v[100:103]
	v_mfma_f32_16x16x32_bf16 v[96:99], v[140:143], v[208:211], v[96:99]
	s_setprio 0
	s_setprio 1
	v_mfma_f32_16x16x32_bf16 v[60:63], v[158:161], v[180:183], v[60:63]
	v_mfma_f32_16x16x32_bf16 v[56:59], v[172:175], v[180:183], v[56:59]
	v_mfma_f32_16x16x32_bf16 v[52:55], v[158:161], v[188:191], v[52:55]
	v_mfma_f32_16x16x32_bf16 v[48:51], v[172:175], v[188:191], v[48:51]
	v_mfma_f32_16x16x32_bf16 v[44:47], v[158:161], v[196:199], v[44:47]
	v_mfma_f32_16x16x32_bf16 v[40:43], v[172:175], v[196:199], v[40:43]
	v_mfma_f32_16x16x32_bf16 v[36:39], v[158:161], v[204:207], v[36:39]
	v_mfma_f32_16x16x32_bf16 v[32:35], v[172:175], v[204:207], v[32:35]
	s_setprio 0
	s_setprio 1
	v_mfma_f32_16x16x32_bf16 v[60:63], v[162:165], v[184:187], v[60:63]
	v_mfma_f32_16x16x32_bf16 v[56:59], v[176:179], v[184:187], v[56:59]
	v_mfma_f32_16x16x32_bf16 v[52:55], v[162:165], v[192:195], v[52:55]
	v_mfma_f32_16x16x32_bf16 v[48:51], v[176:179], v[192:195], v[48:51]
	v_mfma_f32_16x16x32_bf16 v[44:47], v[162:165], v[200:203], v[44:47]
	v_mfma_f32_16x16x32_bf16 v[40:43], v[176:179], v[200:203], v[40:43]
	v_mfma_f32_16x16x32_bf16 v[36:39], v[162:165], v[208:211], v[36:39]
	v_mfma_f32_16x16x32_bf16 v[32:35], v[176:179], v[208:211], v[32:35]
	s_setprio 0
	s_barrier
; #define G_STAGE(bufoff, gbase, voff) do { _Pragma("unroll") for (int _i = 0; _i < 2; ++_i) \
;         __builtin_amdgcn_global_load_lds((const unsigned*)((const char*)(gbase) + voff[_i]), (LAS unsigned*)(lds + (bufoff) + ldsw + _i * 8192), 16, 0, 0); } while (0)
; #define G_LDA(dst, b, h) do { _Pragma("unroll") for (int m = 0; m < 4; ++m) _Pragma("unroll") for (int k = 0; k < 2; ++k) dst[m][k] = *(const LAS bf16x8*)(lds + G_SA(b, h) + aoff + m * 2048 + k * 1024); } while (0)
; #define G_MMA(ai, bj, At_, Bt_) do { __builtin_amdgcn_s_setprio(1); _Pragma("unroll") for (int m = 0; m < 4; ++m) _Pragma("unroll") for (int n = 0; n < 2; ++n) _Pragma("unroll") for (int k = 0; k < 2; ++k) \
;         acc[ai][bj][m][n] = __builtin_amdgcn_mfma_f32_16x16x32_bf16(Bt_[n][k], At_[m][k], acc[ai][bj][m][n], 0, 0, 0); __builtin_amdgcn_s_setprio(0); } while (0)
; #define WAIT_V(n) asm volatile("s_waitcnt vmcnt(" #n ")" ::: "memory")
; #define WAIT_L(n) asm volatile("s_waitcnt lgkmcnt(" #n ")" ::: "memory")
; #define BAR __builtin_amdgcn_s_barrier()
; #define SCHED __builtin_amdgcn_sched_barrier(0)
; template <class Get, class Epi>
; DI void gemm_loop(int ntiles, int ld, char* shm, const Get& get, const Epi& epi) {
;     ...
;             G_LDA(At, 1, 1); G_STAGE(G_SB(1, 0), b3, voffB); G_STAGE(G_SB(1, 1), b3 + hstep, voffB); G_STAGE(G_SA(1, 0), a3, voffA);
;             WAIT_V(8); WAIT_L(0); BAR; G_MMA(1, 0, At, B0); G_MMA(1, 1, At, B1); BAR; SCHED;
;         }
	s_add_i32 s46, s79, s7
	v_lshl_add_u64 v[144:145], v[144:145], 0, s[10:11]
	s_mov_b32 m0, s46
	ds_read_b128 v[180:183], v171 offset:49152
	ds_read_b128 v[184:187], v171 offset:50176
	ds_read_b128 v[188:191], v171 offset:51200
	ds_read_b128 v[192:195], v171 offset:52224
	ds_read_b128 v[196:199], v171 offset:53248
	ds_read_b128 v[200:203], v171 offset:54272
	ds_read_b128 v[204:207], v171 offset:55296
	ds_read_b128 v[208:211], v171 offset:56320
	global_load_lds_dwordx4 v[144:145], off
	s_add_i32 m0, s46, 0x2000
	s_add_u32 s14, s14, 0x40080
	v_lshl_add_u64 v[144:145], v[166:167], 0, s[10:11]
	s_addc_u32 s15, s15, 0
	s_add_i32 s46, s80, s7
	global_load_lds_dwordx4 v[144:145], off
	v_lshl_add_u64 v[144:145], s[14:15], 0, v[148:149]
	s_mov_b32 m0, s46
	s_nop 0
	global_load_lds_dwordx4 v[144:145], off
	v_lshl_add_u64 v[144:145], s[14:15], 0, v[152:153]
	s_add_i32 m0, s46, 0x2000
	s_nop 0
	global_load_lds_dwordx4 v[144:145], off
	v_lshl_add_u64 v[144:145], v[212:213], 0, s[10:11]
	s_mov_b32 m0, s55
	s_nop 0
	global_load_lds_dwordx4 v[144:145], off
	v_lshl_add_u64 v[144:145], v[214:215], 0, s[10:11]
	s_mov_b32 m0, s56
	s_nop 0
	global_load_lds_dwordx4 v[144:145], off
	s_waitcnt vmcnt(8)
	s_waitcnt lgkmcnt(0)
	s_barrier
	s_setprio 1
	s_waitcnt lgkmcnt(0)
	v_mfma_f32_16x16x32_bf16 v[92:95], v[128:131], v[180:183], v[92:95]
	v_mfma_f32_16x16x32_bf16 v[88:91], v[136:139], v[180:183], v[88:91]
	v_mfma_f32_16x16x32_bf16 v[84:87], v[128:131], v[188:191], v[84:87]
	v_mfma_f32_16x16x32_bf16 v[80:83], v[136:139], v[188:191], v[80:83]
	v_mfma_f32_16x16x32_bf16 v[76:79], v[128:131], v[196:199], v[76:79]
	v_mfma_f32_16x16x32_bf16 v[72:75], v[136:139], v[196:199], v[72:75]
	v_mfma_f32_16x16x32_bf16 v[68:71], v[128:131], v[204:207], v[68:71]
	v_mfma_f32_16x16x32_bf16 v[64:67], v[136:139], v[204:207], v[64:67]
	s_setprio 0
	s_setprio 1
	v_mfma_f32_16x16x32_bf16 v[92:95], v[132:135], v[184:187], v[92:95]
	v_mfma_f32_16x16x32_bf16 v[88:91], v[140:143], v[184:187], v[88:91]
	v_mfma_f32_16x16x32_bf16 v[84:87], v[132:135], v[192:195], v[84:87]
	v_mfma_f32_16x16x32_bf16 v[80:83], v[140:143], v[192:195], v[80:83]
	v_mfma_f32_16x16x32_bf16 v[76:79], v[132:135], v[200:203], v[76:79]
	v_mfma_f32_16x16x32_bf16 v[72:75], v[140:143], v[200:203], v[72:75]
	v_mfma_f32_16x16x32_bf16 v[68:71], v[132:135], v[208:211], v[68:71]
	v_mfma_f32_16x16x32_bf16 v[64:67], v[140:143], v[208:211], v[64:67]
	s_setprio 0
	s_setprio 1
	v_mfma_f32_16x16x32_bf16 v[28:31], v[158:161], v[180:183], v[28:31]
	v_mfma_f32_16x16x32_bf16 v[24:27], v[172:175], v[180:183], v[24:27]
	v_mfma_f32_16x16x32_bf16 v[20:23], v[158:161], v[188:191], v[20:23]
	v_mfma_f32_16x16x32_bf16 v[16:19], v[172:175], v[188:191], v[16:19]
	v_mfma_f32_16x16x32_bf16 v[12:15], v[158:161], v[196:199], v[12:15]
	v_mfma_f32_16x16x32_bf16 v[8:11], v[172:175], v[196:199], v[8:11]
	v_mfma_f32_16x16x32_bf16 v[4:7], v[158:161], v[204:207], v[4:7]
	v_mfma_f32_16x16x32_bf16 v[0:3], v[172:175], v[204:207], v[0:3]
	s_setprio 0
	s_setprio 1
	v_mfma_f32_16x16x32_bf16 v[28:31], v[162:165], v[184:187], v[28:31]
	v_mfma_f32_16x16x32_bf16 v[24:27], v[176:179], v[184:187], v[24:27]
	v_mfma_f32_16x16x32_bf16 v[20:23], v[162:165], v[192:195], v[20:23]
	v_mfma_f32_16x16x32_bf16 v[16:19], v[176:179], v[192:195], v[16:19]
	v_mfma_f32_16x16x32_bf16 v[12:15], v[162:165], v[200:203], v[12:15]
	v_mfma_f32_16x16x32_bf16 v[8:11], v[176:179], v[200:203], v[8:11]
	v_mfma_f32_16x16x32_bf16 v[4:7], v[162:165], v[208:211], v[4:7]
	v_mfma_f32_16x16x32_bf16 v[0:3], v[176:179], v[208:211], v[0:3]
	s_setprio 0
	s_barrier
	s_add_u32 s48, s48, 0x100
	s_addc_u32 s49, s49, 0
	s_add_u32 s76, s76, 0x100
	s_addc_u32 s77, s77, 0
	s_cmp_ge_u32 s78, s74
	s_mov_b32 s14, s78
	s_cbranch_scc0 .LBB0_1463

; #define G_STAGE(bufoff, gbase, voff) do { _Pragma("unroll") for (int _i = 0; _i < 2; ++_i) \
;         __builtin_amdgcn_global_load_lds((const unsigned*)((const char*)(gbase) + voff[_i]), (LAS unsigned*)(lds + (bufoff) + ldsw + _i * 8192), 16, 0, 0); } while (0)
; #define G_LDA(dst, b, h) do { _Pragma("unroll") for (int m = 0; m < 4; ++m) _Pragma("unroll") for (int k = 0; k < 2; ++k) dst[m][k] = *(const LAS bf16x8*)(lds + G_SA(b, h) + aoff + m * 2048 + k * 1024); } while (0)
; #define G_MMA(ai, bj, At_, Bt_) do { __builtin_amdgcn_s_setprio(1); _Pragma("unroll") for (int m = 0; m < 4; ++m) _Pragma("unroll") for (int n = 0; n < 2; ++n) _Pragma("unroll") for (int k = 0; k < 2; ++k) \
;         acc[ai][bj][m][n] = __builtin_amdgcn_mfma_f32_16x16x32_bf16(Bt_[n][k], At_[m][k], acc[ai][bj][m][n], 0, 0, 0); __builtin_amdgcn_s_setprio(0); } while (0)
; #define WAIT_V(n) asm volatile("s_waitcnt vmcnt(" #n ")" ::: "memory")
; #define WAIT_L(n) asm volatile("s_waitcnt lgkmcnt(" #n ")" ::: "memory")
; #define BAR __builtin_amdgcn_s_barrier()
; #define SCHED __builtin_amdgcn_sched_barrier(0)
; template <class Get, class Epi>
; DI void gemm_loop(int ntiles, int ld, char* shm, const Get& get, const Epi& epi) {
;     ...
;             WAIT_V(8); WAIT_L(0); BAR; G_MMA(0, 0, At, B0); G_MMA(0, 1, At, B1); BAR; SCHED;
;             G_LDA(At, 0, 1); G_STAGE(G_SB(0, 0), b2, voffB); G_STAGE(G_SB(0, 1), b2 + hstep, voffB); G_STAGE(G_SA(0, 0), a2, voffA);
;             WAIT_V(8); WAIT_L(0); BAR; G_MMA(1, 0, At, B0); G_MMA(1, 1, At, B1); BAR; SCHED;
.Lrj_1694_0:
	s_waitcnt lgkmcnt(0)
	s_barrier
	s_setprio 1
	s_waitcnt lgkmcnt(0)
	v_mfma_f32_16x16x32_bf16 v[124:127], v[144:147], v[176:179], 0
	v_mfma_f32_16x16x32_bf16 v[120:123], v[152:155], v[176:179], 0
	v_mfma_f32_16x16x32_bf16 v[108:111], v[144:147], v[184:187], 0
	v_mfma_f32_16x16x32_bf16 v[104:107], v[152:155], v[184:187], 0
	v_mfma_f32_16x16x32_bf16 v[92:95], v[144:147], v[192:195], 0
	v_mfma_f32_16x16x32_bf16 v[88:91], v[152:155], v[192:195], 0
	v_mfma_f32_16x16x32_bf16 v[76:79], v[144:147], v[200:203], 0
	v_mfma_f32_16x16x32_bf16 v[72:75], v[152:155], v[200:203], 0
	s_setprio 0
	s_setprio 1
	v_mfma_f32_16x16x32_bf16 v[124:127], v[148:151], v[180:183], v[124:127]
	v_mfma_f32_16x16x32_bf16 v[120:123], v[156:159], v[180:183], v[120:123]
	v_mfma_f32_16x16x32_bf16 v[108:111], v[148:151], v[188:191], v[108:111]
	v_mfma_f32_16x16x32_bf16 v[104:107], v[156:159], v[188:191], v[104:107]
	v_mfma_f32_16x16x32_bf16 v[92:95], v[148:151], v[196:199], v[92:95]
	v_mfma_f32_16x16x32_bf16 v[88:91], v[156:159], v[196:199], v[88:91]
	v_mfma_f32_16x16x32_bf16 v[76:79], v[148:151], v[204:207], v[76:79]
	v_mfma_f32_16x16x32_bf16 v[72:75], v[156:159], v[204:207], v[72:75]
	s_setprio 0
	s_setprio 1
	v_mfma_f32_16x16x32_bf16 v[116:119], v[160:163], v[176:179], 0
	v_mfma_f32_16x16x32_bf16 v[112:115], v[168:171], v[176:179], 0
	v_mfma_f32_16x16x32_bf16 v[100:103], v[160:163], v[184:187], 0
	v_mfma_f32_16x16x32_bf16 v[96:99], v[168:171], v[184:187], 0
	v_mfma_f32_16x16x32_bf16 v[84:87], v[160:163], v[192:195], 0
	v_mfma_f32_16x16x32_bf16 v[80:83], v[168:171], v[192:195], 0
	v_mfma_f32_16x16x32_bf16 v[68:71], v[160:163], v[200:203], 0
	v_mfma_f32_16x16x32_bf16 v[64:67], v[168:171], v[200:203], 0
	s_setprio 0
	s_setprio 1
	v_mfma_f32_16x16x32_bf16 v[116:119], v[164:167], v[180:183], v[116:119]
	v_mfma_f32_16x16x32_bf16 v[112:115], v[172:175], v[180:183], v[112:115]
	v_mfma_f32_16x16x32_bf16 v[100:103], v[164:167], v[188:191], v[100:103]
	v_mfma_f32_16x16x32_bf16 v[96:99], v[172:175], v[188:191], v[96:99]
	v_mfma_f32_16x16x32_bf16 v[84:87], v[164:167], v[196:199], v[84:87]
	v_mfma_f32_16x16x32_bf16 v[80:83], v[172:175], v[196:199], v[80:83]
	v_mfma_f32_16x16x32_bf16 v[68:71], v[164:167], v[204:207], v[68:71]
	v_mfma_f32_16x16x32_bf16 v[64:67], v[172:175], v[204:207], v[64:67]
	s_setprio 0
	s_barrier
	s_add_i32 s58, s48, s42
	v_lshl_add_u64 v[208:209], s[14:15], 0, v[132:133]
	s_mov_b32 m0, s58
	ds_read_b128 v[176:179], v143 offset:16384
	ds_read_b128 v[180:183], v143 offset:17408
	ds_read_b128 v[184:187], v143 offset:18432
	ds_read_b128 v[188:191], v143 offset:19456
	ds_read_b128 v[192:195], v143 offset:20480
	ds_read_b128 v[196:199], v143 offset:21504
	ds_read_b128 v[200:203], v143 offset:22528
	ds_read_b128 v[204:207], v143 offset:23552
	global_load_lds_dwordx4 v[208:209], off
	s_add_i32 m0, s58, 0x2000
	s_add_u32 s58, s14, 0x40000
	v_lshl_add_u64 v[210:211], s[14:15], 0, v[128:129]
	s_addc_u32 s59, s15, 0
	s_add_i32 s71, s49, s42
	global_load_lds_dwordx4 v[210:211], off
	v_lshl_add_u64 v[212:213], s[58:59], 0, v[132:133]
	s_mov_b32 m0, s71
	v_lshl_add_u64 v[214:215], s[40:41], 0, v[130:131]
	global_load_lds_dwordx4 v[212:213], off
	v_lshl_add_u64 v[212:213], s[58:59], 0, v[128:129]
	s_add_i32 m0, s71, 0x2000
	s_nop 0
	global_load_lds_dwordx4 v[212:213], off
	v_lshl_add_u64 v[212:213], s[40:41], 0, v[134:135]
	s_mov_b32 m0, s35
	s_nop 0
	global_load_lds_dwordx4 v[212:213], off
	s_mov_b32 m0, s37
	s_nop 0
	global_load_lds_dwordx4 v[214:215], off
	s_cmp_lg_u32 s100, 0
	s_cbranch_scc0 .Lrf_1694_1
	s_waitcnt vmcnt(16)
	s_branch .Lrj_1694_1

; #define G_STAGE(bufoff, gbase, voff) do { _Pragma("unroll") for (int _i = 0; _i < 2; ++_i) \
;         __builtin_amdgcn_global_load_lds((const unsigned*)((const char*)(gbase) + voff[_i]), (LAS unsigned*)(lds + (bufoff) + ldsw + _i * 8192), 16, 0, 0); } while (0)
; #define G_LDA(dst, b, h) do { _Pragma("unroll") for (int m = 0; m < 4; ++m) _Pragma("unroll") for (int k = 0; k < 2; ++k) dst[m][k] = *(const LAS bf16x8*)(lds + G_SA(b, h) + aoff + m * 2048 + k * 1024); } while (0)
; #define G_LDB(dst, b, h) do { _Pragma("unroll") for (int n = 0; n < 2; ++n) _Pragma("unroll") for (int k = 0; k < 2; ++k) dst[n][k] = *(const LAS bf16x8*)(lds + G_SB(b, h) + boff + n * 2048 + k * 1024); } while (0)
; #define G_MMA(ai, bj, At_, Bt_) do { __builtin_amdgcn_s_setprio(1); _Pragma("unroll") for (int m = 0; m < 4; ++m) _Pragma("unroll") for (int n = 0; n < 2; ++n) _Pragma("unroll") for (int k = 0; k < 2; ++k) \
;         acc[ai][bj][m][n] = __builtin_amdgcn_mfma_f32_16x16x32_bf16(Bt_[n][k], At_[m][k], acc[ai][bj][m][n], 0, 0, 0); __builtin_amdgcn_s_setprio(0); } while (0)
; #define WAIT_V(n) asm volatile("s_waitcnt vmcnt(" #n ")" ::: "memory")
; #define WAIT_L(n) asm volatile("s_waitcnt lgkmcnt(" #n ")" ::: "memory")
; #define BAR __builtin_amdgcn_s_barrier()
; #define SCHED __builtin_amdgcn_sched_barrier(0)
; template <class Get, class Epi>
; DI void gemm_loop(int ntiles, int ld, char* shm, const Get& get, const Epi& epi) {
;     ...
;             WAIT_V(8); WAIT_L(0); BAR; G_MMA(1, 0, At, B0); G_MMA(1, 1, At, B1); BAR; SCHED;
;             G_LDB(B0, 1, 0); G_LDB(B1, 1, 1); SCHED; G_LDA(At, 1, 0); G_STAGE(G_SA(0, 1), a2 + hstep, voffA);
;             WAIT_V(8); WAIT_L(0); BAR; G_MMA(0, 0, At, B0); G_MMA(0, 1, At, B1); BAR; SCHED;
.Lrj_1694_1:
	s_waitcnt lgkmcnt(0)
	s_barrier
	s_setprio 1
	s_waitcnt lgkmcnt(0)
	v_mfma_f32_16x16x32_bf16 v[60:63], v[144:147], v[176:179], 0
	v_mfma_f32_16x16x32_bf16 v[56:59], v[152:155], v[176:179], 0
	v_mfma_f32_16x16x32_bf16 v[44:47], v[144:147], v[184:187], 0
	v_mfma_f32_16x16x32_bf16 v[40:43], v[152:155], v[184:187], 0
	v_mfma_f32_16x16x32_bf16 v[28:31], v[144:147], v[192:195], 0
	v_mfma_f32_16x16x32_bf16 v[24:27], v[152:155], v[192:195], 0
	v_mfma_f32_16x16x32_bf16 v[12:15], v[144:147], v[200:203], 0
	v_mfma_f32_16x16x32_bf16 v[8:11], v[152:155], v[200:203], 0
	s_setprio 0
	s_setprio 1
	v_mfma_f32_16x16x32_bf16 v[60:63], v[148:151], v[180:183], v[60:63]
	v_mfma_f32_16x16x32_bf16 v[56:59], v[156:159], v[180:183], v[56:59]
	v_mfma_f32_16x16x32_bf16 v[44:47], v[148:151], v[188:191], v[44:47]
	v_mfma_f32_16x16x32_bf16 v[40:43], v[156:159], v[188:191], v[40:43]
	v_mfma_f32_16x16x32_bf16 v[28:31], v[148:151], v[196:199], v[28:31]
	v_mfma_f32_16x16x32_bf16 v[24:27], v[156:159], v[196:199], v[24:27]
	v_mfma_f32_16x16x32_bf16 v[12:15], v[148:151], v[204:207], v[12:15]
	v_mfma_f32_16x16x32_bf16 v[8:11], v[156:159], v[204:207], v[8:11]
	s_setprio 0
	s_setprio 1
	v_mfma_f32_16x16x32_bf16 v[52:55], v[160:163], v[176:179], 0
	v_mfma_f32_16x16x32_bf16 v[48:51], v[168:171], v[176:179], 0
	v_mfma_f32_16x16x32_bf16 v[36:39], v[160:163], v[184:187], 0
	v_mfma_f32_16x16x32_bf16 v[32:35], v[168:171], v[184:187], 0
	v_mfma_f32_16x16x32_bf16 v[20:23], v[160:163], v[192:195], 0
	v_mfma_f32_16x16x32_bf16 v[16:19], v[168:171], v[192:195], 0
	v_mfma_f32_16x16x32_bf16 v[4:7], v[160:163], v[200:203], 0
	v_mfma_f32_16x16x32_bf16 v[0:3], v[168:171], v[200:203], 0
	s_setprio 0
	s_setprio 1
	v_mfma_f32_16x16x32_bf16 v[52:55], v[164:167], v[180:183], v[52:55]
	v_mfma_f32_16x16x32_bf16 v[48:51], v[172:175], v[180:183], v[48:51]
	v_mfma_f32_16x16x32_bf16 v[36:39], v[164:167], v[188:191], v[36:39]
	v_mfma_f32_16x16x32_bf16 v[32:35], v[172:175], v[188:191], v[32:35]
	v_mfma_f32_16x16x32_bf16 v[20:23], v[164:167], v[196:199], v[20:23]
	v_mfma_f32_16x16x32_bf16 v[16:19], v[172:175], v[196:199], v[16:19]
	v_mfma_f32_16x16x32_bf16 v[4:7], v[164:167], v[204:207], v[4:7]
	v_mfma_f32_16x16x32_bf16 v[0:3], v[172:175], v[204:207], v[0:3]
	s_setprio 0
	s_barrier
	s_add_i32 s58, 0, 0x18000
	s_add_i32 s59, 0, 0x1c000
	v_add_u32_e32 v156, s58, v140
	v_add_u32_e32 v172, s59, v140
	ds_read_b128 v[144:147], v156
	ds_read_b128 v[148:151], v156 offset:1024
	ds_read_b128 v[152:155], v156 offset:2048
	ds_read_b128 v[156:159], v156 offset:3072
	ds_read_b128 v[160:163], v172
	ds_read_b128 v[164:167], v172 offset:1024
	ds_read_b128 v[168:171], v172 offset:2048
	ds_read_b128 v[172:175], v172 offset:3072
	s_add_u32 s40, s40, 0x40000
	s_addc_u32 s41, s41, 0
	s_mov_b32 m0, s44
	v_lshl_add_u64 v[216:217], s[40:41], 0, v[134:135]
	ds_read_b128 v[176:179], v143 offset:32768
	ds_read_b128 v[180:183], v143 offset:33792
	ds_read_b128 v[184:187], v143 offset:34816
	ds_read_b128 v[188:191], v143 offset:35840
	ds_read_b128 v[192:195], v143 offset:36864
	ds_read_b128 v[196:199], v143 offset:37888
	ds_read_b128 v[200:203], v143 offset:38912
	ds_read_b128 v[204:207], v143 offset:39936
	global_load_lds_dwordx4 v[216:217], off
	v_lshl_add_u64 v[216:217], s[40:41], 0, v[130:131]
	s_mov_b32 m0, s45
	s_nop 0
	global_load_lds_dwordx4 v[216:217], off
	s_waitcnt vmcnt(8)
	s_waitcnt lgkmcnt(0)
	s_barrier
	s_setprio 1
	s_waitcnt lgkmcnt(0)
	v_mfma_f32_16x16x32_bf16 v[124:127], v[144:147], v[176:179], v[124:127]
	v_mfma_f32_16x16x32_bf16 v[120:123], v[152:155], v[176:179], v[120:123]
	v_mfma_f32_16x16x32_bf16 v[108:111], v[144:147], v[184:187], v[108:111]
	v_mfma_f32_16x16x32_bf16 v[104:107], v[152:155], v[184:187], v[104:107]
	v_mfma_f32_16x16x32_bf16 v[92:95], v[144:147], v[192:195], v[92:95]
	v_mfma_f32_16x16x32_bf16 v[88:91], v[152:155], v[192:195], v[88:91]
	v_mfma_f32_16x16x32_bf16 v[76:79], v[144:147], v[200:203], v[76:79]
	v_mfma_f32_16x16x32_bf16 v[72:75], v[152:155], v[200:203], v[72:75]
	s_setprio 0
	s_setprio 1
	v_mfma_f32_16x16x32_bf16 v[124:127], v[148:151], v[180:183], v[124:127]
	v_mfma_f32_16x16x32_bf16 v[120:123], v[156:159], v[180:183], v[120:123]
	v_mfma_f32_16x16x32_bf16 v[108:111], v[148:151], v[188:191], v[108:111]
	v_mfma_f32_16x16x32_bf16 v[104:107], v[156:159], v[188:191], v[104:107]
	v_mfma_f32_16x16x32_bf16 v[92:95], v[148:151], v[196:199], v[92:95]
	v_mfma_f32_16x16x32_bf16 v[88:91], v[156:159], v[196:199], v[88:91]
	v_mfma_f32_16x16x32_bf16 v[76:79], v[148:151], v[204:207], v[76:79]
	v_mfma_f32_16x16x32_bf16 v[72:75], v[156:159], v[204:207], v[72:75]
	s_setprio 0
	s_setprio 1
	v_mfma_f32_16x16x32_bf16 v[116:119], v[160:163], v[176:179], v[116:119]
	v_mfma_f32_16x16x32_bf16 v[112:115], v[168:171], v[176:179], v[112:115]
	v_mfma_f32_16x16x32_bf16 v[100:103], v[160:163], v[184:187], v[100:103]
	v_mfma_f32_16x16x32_bf16 v[96:99], v[168:171], v[184:187], v[96:99]
	v_mfma_f32_16x16x32_bf16 v[84:87], v[160:163], v[192:195], v[84:87]
	v_mfma_f32_16x16x32_bf16 v[80:83], v[168:171], v[192:195], v[80:83]
	v_mfma_f32_16x16x32_bf16 v[68:71], v[160:163], v[200:203], v[68:71]
	v_mfma_f32_16x16x32_bf16 v[64:67], v[168:171], v[200:203], v[64:67]
	s_setprio 0
	s_setprio 1
	v_mfma_f32_16x16x32_bf16 v[116:119], v[164:167], v[180:183], v[116:119]
	v_mfma_f32_16x16x32_bf16 v[112:115], v[172:175], v[180:183], v[112:115]
	v_mfma_f32_16x16x32_bf16 v[100:103], v[164:167], v[188:191], v[100:103]
	v_mfma_f32_16x16x32_bf16 v[96:99], v[172:175], v[188:191], v[96:99]
	v_mfma_f32_16x16x32_bf16 v[84:87], v[164:167], v[196:199], v[84:87]
	v_mfma_f32_16x16x32_bf16 v[80:83], v[172:175], v[196:199], v[80:83]
	v_mfma_f32_16x16x32_bf16 v[68:71], v[164:167], v[204:207], v[68:71]
	v_mfma_f32_16x16x32_bf16 v[64:67], v[172:175], v[204:207], v[64:67]
	s_setprio 0
	s_barrier
; #define G_STAGE(bufoff, gbase, voff) do { _Pragma("unroll") for (int _i = 0; _i < 2; ++_i) \
;         __builtin_amdgcn_global_load_lds((const unsigned*)((const char*)(gbase) + voff[_i]), (LAS unsigned*)(lds + (bufoff) + ldsw + _i * 8192), 16, 0, 0); } while (0)
; #define G_LDA(dst, b, h) do { _Pragma("unroll") for (int m = 0; m < 4; ++m) _Pragma("unroll") for (int k = 0; k < 2; ++k) dst[m][k] = *(const LAS bf16x8*)(lds + G_SA(b, h) + aoff + m * 2048 + k * 1024); } while (0)
; #define G_LDB(dst, b, h) do { _Pragma("unroll") for (int n = 0; n < 2; ++n) _Pragma("unroll") for (int k = 0; k < 2; ++k) dst[n][k] = *(const LAS bf16x8*)(lds + G_SB(b, h) + boff + n * 2048 + k * 1024); } while (0)
; #define G_MMA(ai, bj, At_, Bt_) do { __builtin_amdgcn_s_setprio(1); _Pragma("unroll") for (int m = 0; m < 4; ++m) _Pragma("unroll") for (int n = 0; n < 2; ++n) _Pragma("unroll") for (int k = 0; k < 2; ++k) \
;         acc[ai][bj][m][n] = __builtin_amdgcn_mfma_f32_16x16x32_bf16(Bt_[n][k], At_[m][k], acc[ai][bj][m][n], 0, 0, 0); __builtin_amdgcn_s_setprio(0); } while (0)
; #define WAIT_V(n) asm volatile("s_waitcnt vmcnt(" #n ")" ::: "memory")
; #define WAIT_L(n) asm volatile("s_waitcnt lgkmcnt(" #n ")" ::: "memory")
; #define BAR __builtin_amdgcn_s_barrier()
; #define SCHED __builtin_amdgcn_sched_barrier(0)
; template <class Get, class Epi>
; DI void gemm_loop(int ntiles, int ld, char* shm, const Get& get, const Epi& epi) {
;     ...
;             G_LDB(B0, 0, 0); G_LDB(B1, 0, 1); SCHED; G_LDA(At, 0, 0); G_STAGE(G_SA(1, 1), a1 + hstep, voffA);
;             WAIT_V(8); WAIT_L(0); BAR; G_MMA(0, 0, At, B0); G_MMA(0, 1, At, B1); BAR; SCHED;
;     ...
;             G_LDA(At, 1, 1); G_STAGE(G_SB(1, 0), b3, voffB); G_STAGE(G_SB(1, 1), b3 + hstep, voffB); G_STAGE(G_SA(1, 0), a3, voffA);
;             WAIT_V(8); WAIT_L(0); BAR; G_MMA(1, 0, At, B0); G_MMA(1, 1, At, B1); BAR; SCHED;
	s_add_i32 s40, s58, s42
	v_lshl_add_u64 v[208:209], v[208:209], 0, s[2:3]
	s_mov_b32 m0, s40
	ds_read_b128 v[176:179], v143 offset:49152
	ds_read_b128 v[180:183], v143 offset:50176
	ds_read_b128 v[184:187], v143 offset:51200
	ds_read_b128 v[188:191], v143 offset:52224
	ds_read_b128 v[192:195], v143 offset:53248
	ds_read_b128 v[196:199], v143 offset:54272
	ds_read_b128 v[200:203], v143 offset:55296
	ds_read_b128 v[204:207], v143 offset:56320
	global_load_lds_dwordx4 v[208:209], off
	s_add_i32 m0, s40, 0x2000
	s_add_u32 s14, s14, 0x40080
	v_lshl_add_u64 v[208:209], v[210:211], 0, s[2:3]
	s_addc_u32 s15, s15, 0
	s_add_i32 s40, s59, s42
	global_load_lds_dwordx4 v[208:209], off
	v_lshl_add_u64 v[208:209], s[14:15], 0, v[132:133]
	s_mov_b32 m0, s40
	s_nop 0
	global_load_lds_dwordx4 v[208:209], off
	v_lshl_add_u64 v[208:209], s[14:15], 0, v[128:129]
	s_add_i32 m0, s40, 0x2000
	s_nop 0
	global_load_lds_dwordx4 v[208:209], off
	v_lshl_add_u64 v[208:209], v[212:213], 0, s[2:3]
	s_mov_b32 m0, s46
	s_nop 0
	global_load_lds_dwordx4 v[208:209], off
	v_lshl_add_u64 v[208:209], v[214:215], 0, s[2:3]
	s_mov_b32 m0, s47
	s_nop 0
	global_load_lds_dwordx4 v[208:209], off
	s_waitcnt vmcnt(8)
	s_waitcnt lgkmcnt(0)
	s_barrier
	s_setprio 1
	s_waitcnt lgkmcnt(0)
	v_mfma_f32_16x16x32_bf16 v[60:63], v[144:147], v[176:179], v[60:63]
	v_mfma_f32_16x16x32_bf16 v[56:59], v[152:155], v[176:179], v[56:59]
	v_mfma_f32_16x16x32_bf16 v[44:47], v[144:147], v[184:187], v[44:47]
	v_mfma_f32_16x16x32_bf16 v[40:43], v[152:155], v[184:187], v[40:43]
	v_mfma_f32_16x16x32_bf16 v[28:31], v[144:147], v[192:195], v[28:31]
	v_mfma_f32_16x16x32_bf16 v[24:27], v[152:155], v[192:195], v[24:27]
	v_mfma_f32_16x16x32_bf16 v[12:15], v[144:147], v[200:203], v[12:15]
	v_mfma_f32_16x16x32_bf16 v[8:11], v[152:155], v[200:203], v[8:11]
	s_setprio 0
	s_setprio 1
	v_mfma_f32_16x16x32_bf16 v[60:63], v[148:151], v[180:183], v[60:63]
	v_mfma_f32_16x16x32_bf16 v[56:59], v[156:159], v[180:183], v[56:59]
	v_mfma_f32_16x16x32_bf16 v[44:47], v[148:151], v[188:191], v[44:47]
	v_mfma_f32_16x16x32_bf16 v[40:43], v[156:159], v[188:191], v[40:43]
	v_mfma_f32_16x16x32_bf16 v[28:31], v[148:151], v[196:199], v[28:31]
	v_mfma_f32_16x16x32_bf16 v[24:27], v[156:159], v[196:199], v[24:27]
	v_mfma_f32_16x16x32_bf16 v[12:15], v[148:151], v[204:207], v[12:15]
	v_mfma_f32_16x16x32_bf16 v[8:11], v[156:159], v[204:207], v[8:11]
	s_setprio 0
	s_setprio 1
	v_mfma_f32_16x16x32_bf16 v[52:55], v[160:163], v[176:179], v[52:55]
	v_mfma_f32_16x16x32_bf16 v[48:51], v[168:171], v[176:179], v[48:51]
	v_mfma_f32_16x16x32_bf16 v[36:39], v[160:163], v[184:187], v[36:39]
	v_mfma_f32_16x16x32_bf16 v[32:35], v[168:171], v[184:187], v[32:35]
	v_mfma_f32_16x16x32_bf16 v[20:23], v[160:163], v[192:195], v[20:23]
	v_mfma_f32_16x16x32_bf16 v[16:19], v[168:171], v[192:195], v[16:19]
	v_mfma_f32_16x16x32_bf16 v[4:7], v[160:163], v[200:203], v[4:7]
	v_mfma_f32_16x16x32_bf16 v[0:3], v[168:171], v[200:203], v[0:3]
	s_setprio 0
	s_setprio 1
	v_mfma_f32_16x16x32_bf16 v[52:55], v[164:167], v[180:183], v[52:55]
	v_mfma_f32_16x16x32_bf16 v[48:51], v[172:175], v[180:183], v[48:51]
	v_mfma_f32_16x16x32_bf16 v[36:39], v[164:167], v[188:191], v[36:39]
	v_mfma_f32_16x16x32_bf16 v[32:35], v[172:175], v[188:191], v[32:35]
	v_mfma_f32_16x16x32_bf16 v[20:23], v[164:167], v[196:199], v[20:23]
	v_mfma_f32_16x16x32_bf16 v[16:19], v[172:175], v[196:199], v[16:19]
	v_mfma_f32_16x16x32_bf16 v[4:7], v[164:167], v[204:207], v[4:7]
	v_mfma_f32_16x16x32_bf16 v[0:3], v[172:175], v[204:207], v[0:3]
	s_setprio 0
	s_barrier
	s_add_i32 s57, s57, 2
	s_add_u32 s38, s38, 0x100
	s_addc_u32 s39, s39, 0
	s_add_u32 s55, s55, 0x100
	s_addc_u32 s56, s56, 0
	s_cmp_gt_u32 s57, 13
	s_cbranch_scc0 .LBB0_1694
	s_branch .Lpost_1694
.LBB0_1694:
	ds_read_b128 v[144:147], v141
	ds_read_b128 v[148:151], v141 offset:1024
	ds_read_b128 v[152:155], v141 offset:2048
	ds_read_b128 v[156:159], v141 offset:3072
	ds_read_b128 v[160:163], v142
	ds_read_b128 v[164:167], v142 offset:1024
	ds_read_b128 v[168:171], v142 offset:2048
	ds_read_b128 v[172:175], v142 offset:3072
	s_add_u32 s14, s38, 0xfffc0080
	s_addc_u32 s15, s39, -1
	s_cmp_eq_u32 s57, 12
	s_cselect_b32 s41, s9, s15
	s_cselect_b32 s40, s53, s14
	s_cselect_b32 s15, s11, s56
	s_cselect_b32 s14, s54, s55
	v_lshl_add_u64 v[208:209], s[38:39], 0, v[136:137]
	s_add_i32 m0, s35, 0xc000
	ds_read_b128 v[176:179], v143
	ds_read_b128 v[180:183], v143 offset:1024
	ds_read_b128 v[184:187], v143 offset:2048
	ds_read_b128 v[188:191], v143 offset:3072
	ds_read_b128 v[192:195], v143 offset:4096
	ds_read_b128 v[196:199], v143 offset:5120
	ds_read_b128 v[200:203], v143 offset:6144
	ds_read_b128 v[204:207], v143 offset:7168
	global_load_lds_dwordx4 v[208:209], off
	v_lshl_add_u64 v[208:209], s[38:39], 0, v[138:139]
	s_add_i32 m0, s35, 0xe000
	s_nop 0
	global_load_lds_dwordx4 v[208:209], off
	s_waitcnt vmcnt(8)
	s_waitcnt lgkmcnt(0)
	s_barrier
; #define G_STAGE(bufoff, gbase, voff) do { _Pragma("unroll") for (int _i = 0; _i < 2; ++_i) \
;         __builtin_amdgcn_global_load_lds((const unsigned*)((const char*)(gbase) + voff[_i]), (LAS unsigned*)(lds + (bufoff) + ldsw + _i * 8192), 16, 0, 0); } while (0)
; #define G_LDA(dst, b, h) do { _Pragma("unroll") for (int m = 0; m < 4; ++m) _Pragma("unroll") for (int k = 0; k < 2; ++k) dst[m][k] = *(const LAS bf16x8*)(lds + G_SA(b, h) + aoff + m * 2048 + k * 1024); } while (0)
; #define G_MMA(ai, bj, At_, Bt_) do { __builtin_amdgcn_s_setprio(1); _Pragma("unroll") for (int m = 0; m < 4; ++m) _Pragma("unroll") for (int n = 0; n < 2; ++n) _Pragma("unroll") for (int k = 0; k < 2; ++k) \
;         acc[ai][bj][m][n] = __builtin_amdgcn_mfma_f32_16x16x32_bf16(Bt_[n][k], At_[m][k], acc[ai][bj][m][n], 0, 0, 0); __builtin_amdgcn_s_setprio(0); } while (0)
; #define WAIT_V(n) asm volatile("s_waitcnt vmcnt(" #n ")" ::: "memory")
; #define WAIT_L(n) asm volatile("s_waitcnt lgkmcnt(" #n ")" ::: "memory")
; #define BAR __builtin_amdgcn_s_barrier()
; #define SCHED __builtin_amdgcn_sched_barrier(0)
; template <class Get, class Epi>
; DI void gemm_loop(int ntiles, int ld, char* shm, const Get& get, const Epi& epi) {
;     ...
;             WAIT_V(8); WAIT_L(0); BAR; G_MMA(0, 0, At, B0); G_MMA(0, 1, At, B1); BAR; SCHED;
;             G_LDA(At, 0, 1); G_STAGE(G_SB(0, 0), b2, voffB); G_STAGE(G_SB(0, 1), b2 + hstep, voffB); G_STAGE(G_SA(0, 0), a2, voffA);
;             WAIT_V(8); WAIT_L(0); BAR; G_MMA(1, 0, At, B0); G_MMA(1, 1, At, B1); BAR; SCHED;
	s_setprio 1
	s_waitcnt lgkmcnt(0)
	v_mfma_f32_16x16x32_bf16 v[124:127], v[144:147], v[176:179], v[124:127]
	v_mfma_f32_16x16x32_bf16 v[120:123], v[152:155], v[176:179], v[120:123]
	v_mfma_f32_16x16x32_bf16 v[108:111], v[144:147], v[184:187], v[108:111]
	v_mfma_f32_16x16x32_bf16 v[104:107], v[152:155], v[184:187], v[104:107]
	v_mfma_f32_16x16x32_bf16 v[92:95], v[144:147], v[192:195], v[92:95]
	v_mfma_f32_16x16x32_bf16 v[88:91], v[152:155], v[192:195], v[88:91]
	v_mfma_f32_16x16x32_bf16 v[76:79], v[144:147], v[200:203], v[76:79]
	v_mfma_f32_16x16x32_bf16 v[72:75], v[152:155], v[200:203], v[72:75]
	s_setprio 0
	s_setprio 1
	v_mfma_f32_16x16x32_bf16 v[124:127], v[148:151], v[180:183], v[124:127]
	v_mfma_f32_16x16x32_bf16 v[120:123], v[156:159], v[180:183], v[120:123]
	v_mfma_f32_16x16x32_bf16 v[108:111], v[148:151], v[188:191], v[108:111]
	v_mfma_f32_16x16x32_bf16 v[104:107], v[156:159], v[188:191], v[104:107]
	v_mfma_f32_16x16x32_bf16 v[92:95], v[148:151], v[196:199], v[92:95]
	v_mfma_f32_16x16x32_bf16 v[88:91], v[156:159], v[196:199], v[88:91]
	v_mfma_f32_16x16x32_bf16 v[76:79], v[148:151], v[204:207], v[76:79]
	v_mfma_f32_16x16x32_bf16 v[72:75], v[156:159], v[204:207], v[72:75]
	s_setprio 0
	s_setprio 1
	v_mfma_f32_16x16x32_bf16 v[116:119], v[160:163], v[176:179], v[116:119]
	v_mfma_f32_16x16x32_bf16 v[112:115], v[168:171], v[176:179], v[112:115]
	v_mfma_f32_16x16x32_bf16 v[100:103], v[160:163], v[184:187], v[100:103]
	v_mfma_f32_16x16x32_bf16 v[96:99], v[168:171], v[184:187], v[96:99]
	v_mfma_f32_16x16x32_bf16 v[84:87], v[160:163], v[192:195], v[84:87]
	v_mfma_f32_16x16x32_bf16 v[80:83], v[168:171], v[192:195], v[80:83]
	v_mfma_f32_16x16x32_bf16 v[68:71], v[160:163], v[200:203], v[68:71]
	v_mfma_f32_16x16x32_bf16 v[64:67], v[168:171], v[200:203], v[64:67]
	s_setprio 0
	s_setprio 1
	v_mfma_f32_16x16x32_bf16 v[116:119], v[164:167], v[180:183], v[116:119]
	v_mfma_f32_16x16x32_bf16 v[112:115], v[172:175], v[180:183], v[112:115]
	v_mfma_f32_16x16x32_bf16 v[100:103], v[164:167], v[188:191], v[100:103]
	v_mfma_f32_16x16x32_bf16 v[96:99], v[172:175], v[188:191], v[96:99]
	v_mfma_f32_16x16x32_bf16 v[84:87], v[164:167], v[196:199], v[84:87]
	v_mfma_f32_16x16x32_bf16 v[80:83], v[172:175], v[196:199], v[80:83]
	v_mfma_f32_16x16x32_bf16 v[68:71], v[164:167], v[204:207], v[68:71]
	v_mfma_f32_16x16x32_bf16 v[64:67], v[172:175], v[204:207], v[64:67]
	s_setprio 0
	s_barrier
	s_add_i32 s58, s48, s42
	v_lshl_add_u64 v[208:209], s[14:15], 0, v[132:133]
	s_mov_b32 m0, s58
	ds_read_b128 v[176:179], v143 offset:16384
	ds_read_b128 v[180:183], v143 offset:17408
	ds_read_b128 v[184:187], v143 offset:18432
	ds_read_b128 v[188:191], v143 offset:19456
	ds_read_b128 v[192:195], v143 offset:20480
	ds_read_b128 v[196:199], v143 offset:21504
	ds_read_b128 v[200:203], v143 offset:22528
	ds_read_b128 v[204:207], v143 offset:23552
	global_load_lds_dwordx4 v[208:209], off
	s_add_i32 m0, s58, 0x2000
	s_add_u32 s58, s14, 0x40000
	v_lshl_add_u64 v[210:211], s[14:15], 0, v[128:129]
	s_addc_u32 s59, s15, 0
	s_add_i32 s71, s49, s42
	global_load_lds_dwordx4 v[210:211], off
	v_lshl_add_u64 v[212:213], s[58:59], 0, v[132:133]
	s_mov_b32 m0, s71
	v_lshl_add_u64 v[214:215], s[40:41], 0, v[130:131]
	global_load_lds_dwordx4 v[212:213], off
	v_lshl_add_u64 v[212:213], s[58:59], 0, v[128:129]
	s_add_i32 m0, s71, 0x2000
	s_nop 0
	global_load_lds_dwordx4 v[212:213], off
	v_lshl_add_u64 v[212:213], s[40:41], 0, v[134:135]
	s_mov_b32 m0, s35
	s_nop 0
	global_load_lds_dwordx4 v[212:213], off
	s_mov_b32 m0, s37
	s_nop 0
	global_load_lds_dwordx4 v[214:215], off
	s_waitcnt vmcnt(8)
	s_waitcnt lgkmcnt(0)
	s_barrier
	s_setprio 1
	s_waitcnt lgkmcnt(0)
	v_mfma_f32_16x16x32_bf16 v[60:63], v[144:147], v[176:179], v[60:63]
	v_mfma_f32_16x16x32_bf16 v[56:59], v[152:155], v[176:179], v[56:59]
	v_mfma_f32_16x16x32_bf16 v[44:47], v[144:147], v[184:187], v[44:47]
	v_mfma_f32_16x16x32_bf16 v[40:43], v[152:155], v[184:187], v[40:43]
	v_mfma_f32_16x16x32_bf16 v[28:31], v[144:147], v[192:195], v[28:31]
	v_mfma_f32_16x16x32_bf16 v[24:27], v[152:155], v[192:195], v[24:27]
	v_mfma_f32_16x16x32_bf16 v[12:15], v[144:147], v[200:203], v[12:15]
	v_mfma_f32_16x16x32_bf16 v[8:11], v[152:155], v[200:203], v[8:11]
	s_setprio 0
	s_setprio 1
	v_mfma_f32_16x16x32_bf16 v[60:63], v[148:151], v[180:183], v[60:63]
	v_mfma_f32_16x16x32_bf16 v[56:59], v[156:159], v[180:183], v[56:59]
	v_mfma_f32_16x16x32_bf16 v[44:47], v[148:151], v[188:191], v[44:47]
	v_mfma_f32_16x16x32_bf16 v[40:43], v[156:159], v[188:191], v[40:43]
	v_mfma_f32_16x16x32_bf16 v[28:31], v[148:151], v[196:199], v[28:31]
	v_mfma_f32_16x16x32_bf16 v[24:27], v[156:159], v[196:199], v[24:27]
	v_mfma_f32_16x16x32_bf16 v[12:15], v[148:151], v[204:207], v[12:15]
	v_mfma_f32_16x16x32_bf16 v[8:11], v[156:159], v[204:207], v[8:11]
	s_setprio 0
	s_setprio 1
	v_mfma_f32_16x16x32_bf16 v[52:55], v[160:163], v[176:179], v[52:55]
	v_mfma_f32_16x16x32_bf16 v[48:51], v[168:171], v[176:179], v[48:51]
	v_mfma_f32_16x16x32_bf16 v[36:39], v[160:163], v[184:187], v[36:39]
	v_mfma_f32_16x16x32_bf16 v[32:35], v[168:171], v[184:187], v[32:35]
	v_mfma_f32_16x16x32_bf16 v[20:23], v[160:163], v[192:195], v[20:23]
	v_mfma_f32_16x16x32_bf16 v[16:19], v[168:171], v[192:195], v[16:19]
	v_mfma_f32_16x16x32_bf16 v[4:7], v[160:163], v[200:203], v[4:7]
	v_mfma_f32_16x16x32_bf16 v[0:3], v[168:171], v[200:203], v[0:3]
	s_setprio 0
	s_setprio 1
	v_mfma_f32_16x16x32_bf16 v[52:55], v[164:167], v[180:183], v[52:55]
	v_mfma_f32_16x16x32_bf16 v[48:51], v[172:175], v[180:183], v[48:51]
	v_mfma_f32_16x16x32_bf16 v[36:39], v[164:167], v[188:191], v[36:39]
	v_mfma_f32_16x16x32_bf16 v[32:35], v[172:175], v[188:191], v[32:35]
	v_mfma_f32_16x16x32_bf16 v[20:23], v[164:167], v[196:199], v[20:23]
	v_mfma_f32_16x16x32_bf16 v[16:19], v[172:175], v[196:199], v[16:19]
	v_mfma_f32_16x16x32_bf16 v[4:7], v[164:167], v[204:207], v[4:7]
	v_mfma_f32_16x16x32_bf16 v[0:3], v[172:175], v[204:207], v[0:3]
	s_setprio 0
	s_barrier
; #define G_STAGE(bufoff, gbase, voff) do { _Pragma("unroll") for (int _i = 0; _i < 2; ++_i) \
;         __builtin_amdgcn_global_load_lds((const unsigned*)((const char*)(gbase) + voff[_i]), (LAS unsigned*)(lds + (bufoff) + ldsw + _i * 8192), 16, 0, 0); } while (0)
; #define G_LDA(dst, b, h) do { _Pragma("unroll") for (int m = 0; m < 4; ++m) _Pragma("unroll") for (int k = 0; k < 2; ++k) dst[m][k] = *(const LAS bf16x8*)(lds + G_SA(b, h) + aoff + m * 2048 + k * 1024); } while (0)
; #define G_LDB(dst, b, h) do { _Pragma("unroll") for (int n = 0; n < 2; ++n) _Pragma("unroll") for (int k = 0; k < 2; ++k) dst[n][k] = *(const LAS bf16x8*)(lds + G_SB(b, h) + boff + n * 2048 + k * 1024); } while (0)
; #define G_MMA(ai, bj, At_, Bt_) do { __builtin_amdgcn_s_setprio(1); _Pragma("unroll") for (int m = 0; m < 4; ++m) _Pragma("unroll") for (int n = 0; n < 2; ++n) _Pragma("unroll") for (int k = 0; k < 2; ++k) \
;         acc[ai][bj][m][n] = __builtin_amdgcn_mfma_f32_16x16x32_bf16(Bt_[n][k], At_[m][k], acc[ai][bj][m][n], 0, 0, 0); __builtin_amdgcn_s_setprio(0); } while (0)
; #define WAIT_V(n) asm volatile("s_waitcnt vmcnt(" #n ")" ::: "memory")
; #define WAIT_L(n) asm volatile("s_waitcnt lgkmcnt(" #n ")" ::: "memory")
; #define BAR __builtin_amdgcn_s_barrier()
; #define SCHED __builtin_amdgcn_sched_barrier(0)
; template <class Get, class Epi>
; DI void gemm_loop(int ntiles, int ld, char* shm, const Get& get, const Epi& epi) {
;     ...
;             G_LDB(B0, 1, 0); G_LDB(B1, 1, 1); SCHED; G_LDA(At, 1, 0); G_STAGE(G_SA(0, 1), a2 + hstep, voffA);
;             WAIT_V(8); WAIT_L(0); BAR; G_MMA(0, 0, At, B0); G_MMA(0, 1, At, B1); BAR; SCHED;
	s_add_i32 s58, 0, 0x18000
	s_add_i32 s59, 0, 0x1c000
	v_add_u32_e32 v156, s58, v140
	v_add_u32_e32 v172, s59, v140
	ds_read_b128 v[144:147], v156
	ds_read_b128 v[148:151], v156 offset:1024
	ds_read_b128 v[152:155], v156 offset:2048
	ds_read_b128 v[156:159], v156 offset:3072
	ds_read_b128 v[160:163], v172
	ds_read_b128 v[164:167], v172 offset:1024
	ds_read_b128 v[168:171], v172 offset:2048
	ds_read_b128 v[172:175], v172 offset:3072
	s_add_u32 s40, s40, 0x40000
	s_addc_u32 s41, s41, 0
	s_mov_b32 m0, s44
	v_lshl_add_u64 v[216:217], s[40:41], 0, v[134:135]
	ds_read_b128 v[176:179], v143 offset:32768
	ds_read_b128 v[180:183], v143 offset:33792
	ds_read_b128 v[184:187], v143 offset:34816
	ds_read_b128 v[188:191], v143 offset:35840
	ds_read_b128 v[192:195], v143 offset:36864
	ds_read_b128 v[196:199], v143 offset:37888
	ds_read_b128 v[200:203], v143 offset:38912
	ds_read_b128 v[204:207], v143 offset:39936
	global_load_lds_dwordx4 v[216:217], off
	v_lshl_add_u64 v[216:217], s[40:41], 0, v[130:131]
	s_mov_b32 m0, s45
	s_nop 0
	global_load_lds_dwordx4 v[216:217], off
	s_waitcnt vmcnt(8)
	s_waitcnt lgkmcnt(0)
	s_barrier
	s_setprio 1
	s_waitcnt lgkmcnt(0)
	v_mfma_f32_16x16x32_bf16 v[124:127], v[144:147], v[176:179], v[124:127]
	v_mfma_f32_16x16x32_bf16 v[120:123], v[152:155], v[176:179], v[120:123]
	v_mfma_f32_16x16x32_bf16 v[108:111], v[144:147], v[184:187], v[108:111]
	v_mfma_f32_16x16x32_bf16 v[104:107], v[152:155], v[184:187], v[104:107]
	v_mfma_f32_16x16x32_bf16 v[92:95], v[144:147], v[192:195], v[92:95]
	v_mfma_f32_16x16x32_bf16 v[88:91], v[152:155], v[192:195], v[88:91]
	v_mfma_f32_16x16x32_bf16 v[76:79], v[144:147], v[200:203], v[76:79]
	v_mfma_f32_16x16x32_bf16 v[72:75], v[152:155], v[200:203], v[72:75]
	s_setprio 0
	s_setprio 1
	v_mfma_f32_16x16x32_bf16 v[124:127], v[148:151], v[180:183], v[124:127]
	v_mfma_f32_16x16x32_bf16 v[120:123], v[156:159], v[180:183], v[120:123]
	v_mfma_f32_16x16x32_bf16 v[108:111], v[148:151], v[188:191], v[108:111]
	v_mfma_f32_16x16x32_bf16 v[104:107], v[156:159], v[188:191], v[104:107]
	v_mfma_f32_16x16x32_bf16 v[92:95], v[148:151], v[196:199], v[92:95]
	v_mfma_f32_16x16x32_bf16 v[88:91], v[156:159], v[196:199], v[88:91]
	v_mfma_f32_16x16x32_bf16 v[76:79], v[148:151], v[204:207], v[76:79]
	v_mfma_f32_16x16x32_bf16 v[72:75], v[156:159], v[204:207], v[72:75]
	s_setprio 0
	s_setprio 1
	v_mfma_f32_16x16x32_bf16 v[116:119], v[160:163], v[176:179], v[116:119]
	v_mfma_f32_16x16x32_bf16 v[112:115], v[168:171], v[176:179], v[112:115]
	v_mfma_f32_16x16x32_bf16 v[100:103], v[160:163], v[184:187], v[100:103]
	v_mfma_f32_16x16x32_bf16 v[96:99], v[168:171], v[184:187], v[96:99]
	v_mfma_f32_16x16x32_bf16 v[84:87], v[160:163], v[192:195], v[84:87]
	v_mfma_f32_16x16x32_bf16 v[80:83], v[168:171], v[192:195], v[80:83]
	v_mfma_f32_16x16x32_bf16 v[68:71], v[160:163], v[200:203], v[68:71]
	v_mfma_f32_16x16x32_bf16 v[64:67], v[168:171], v[200:203], v[64:67]
	s_setprio 0
	s_setprio 1
	v_mfma_f32_16x16x32_bf16 v[116:119], v[164:167], v[180:183], v[116:119]
	v_mfma_f32_16x16x32_bf16 v[112:115], v[172:175], v[180:183], v[112:115]
	v_mfma_f32_16x16x32_bf16 v[100:103], v[164:167], v[188:191], v[100:103]
	v_mfma_f32_16x16x32_bf16 v[96:99], v[172:175], v[188:191], v[96:99]
	v_mfma_f32_16x16x32_bf16 v[84:87], v[164:167], v[196:199], v[84:87]
	v_mfma_f32_16x16x32_bf16 v[80:83], v[172:175], v[196:199], v[80:83]
	v_mfma_f32_16x16x32_bf16 v[68:71], v[164:167], v[204:207], v[68:71]
	v_mfma_f32_16x16x32_bf16 v[64:67], v[172:175], v[204:207], v[64:67]
	s_setprio 0
	s_barrier
; #define G_STAGE(bufoff, gbase, voff) do { _Pragma("unroll") for (int _i = 0; _i < 2; ++_i) \
;         __builtin_amdgcn_global_load_lds((const unsigned*)((const char*)(gbase) + voff[_i]), (LAS unsigned*)(lds + (bufoff) + ldsw + _i * 8192), 16, 0, 0); } while (0)
; #define G_LDA(dst, b, h) do { _Pragma("unroll") for (int m = 0; m < 4; ++m) _Pragma("unroll") for (int k = 0; k < 2; ++k) dst[m][k] = *(const LAS bf16x8*)(lds + G_SA(b, h) + aoff + m * 2048 + k * 1024); } while (0)
; #define G_MMA(ai, bj, At_, Bt_) do { __builtin_amdgcn_s_setprio(1); _Pragma("unroll") for (int m = 0; m < 4; ++m) _Pragma("unroll") for (int n = 0; n < 2; ++n) _Pragma("unroll") for (int k = 0; k < 2; ++k) \
;         acc[ai][bj][m][n] = __builtin_amdgcn_mfma_f32_16x16x32_bf16(Bt_[n][k], At_[m][k], acc[ai][bj][m][n], 0, 0, 0); __builtin_amdgcn_s_setprio(0); } while (0)
; #define WAIT_V(n) asm volatile("s_waitcnt vmcnt(" #n ")" ::: "memory")
; #define WAIT_L(n) asm volatile("s_waitcnt lgkmcnt(" #n ")" ::: "memory")
; #define BAR __builtin_amdgcn_s_barrier()
; #define SCHED __builtin_amdgcn_sched_barrier(0)
; template <class Get, class Epi>
; DI void gemm_loop(int ntiles, int ld, char* shm, const Get& get, const Epi& epi) {
;     ...
;             G_LDA(At, 1, 1); G_STAGE(G_SB(1, 0), b3, voffB); G_STAGE(G_SB(1, 1), b3 + hstep, voffB); G_STAGE(G_SA(1, 0), a3, voffA);
;             WAIT_V(8); WAIT_L(0); BAR; G_MMA(1, 0, At, B0); G_MMA(1, 1, At, B1); BAR; SCHED;
	s_add_i32 s40, s58, s42
	v_lshl_add_u64 v[208:209], v[208:209], 0, s[2:3]
	s_mov_b32 m0, s40
	ds_read_b128 v[176:179], v143 offset:49152
	ds_read_b128 v[180:183], v143 offset:50176
	ds_read_b128 v[184:187], v143 offset:51200
	ds_read_b128 v[188:191], v143 offset:52224
	ds_read_b128 v[192:195], v143 offset:53248
	ds_read_b128 v[196:199], v143 offset:54272
	ds_read_b128 v[200:203], v143 offset:55296
	ds_read_b128 v[204:207], v143 offset:56320
	global_load_lds_dwordx4 v[208:209], off
	s_add_i32 m0, s40, 0x2000
	s_add_u32 s14, s14, 0x40080
	v_lshl_add_u64 v[208:209], v[210:211], 0, s[2:3]
	s_addc_u32 s15, s15, 0
	s_add_i32 s40, s59, s42
	global_load_lds_dwordx4 v[208:209], off
	v_lshl_add_u64 v[208:209], s[14:15], 0, v[132:133]
	s_mov_b32 m0, s40
	s_nop 0
	global_load_lds_dwordx4 v[208:209], off
	v_lshl_add_u64 v[208:209], s[14:15], 0, v[128:129]
	s_add_i32 m0, s40, 0x2000
	s_nop 0
	global_load_lds_dwordx4 v[208:209], off
	v_lshl_add_u64 v[208:209], v[212:213], 0, s[2:3]
	s_mov_b32 m0, s46
	s_nop 0
	global_load_lds_dwordx4 v[208:209], off
	v_lshl_add_u64 v[208:209], v[214:215], 0, s[2:3]
	s_mov_b32 m0, s47
	s_nop 0
	global_load_lds_dwordx4 v[208:209], off
	s_waitcnt vmcnt(8)
	s_waitcnt lgkmcnt(0)
	s_barrier
	s_setprio 1
	s_waitcnt lgkmcnt(0)
	v_mfma_f32_16x16x32_bf16 v[60:63], v[144:147], v[176:179], v[60:63]
	v_mfma_f32_16x16x32_bf16 v[56:59], v[152:155], v[176:179], v[56:59]
	v_mfma_f32_16x16x32_bf16 v[44:47], v[144:147], v[184:187], v[44:47]
	v_mfma_f32_16x16x32_bf16 v[40:43], v[152:155], v[184:187], v[40:43]
	v_mfma_f32_16x16x32_bf16 v[28:31], v[144:147], v[192:195], v[28:31]
	v_mfma_f32_16x16x32_bf16 v[24:27], v[152:155], v[192:195], v[24:27]
	v_mfma_f32_16x16x32_bf16 v[12:15], v[144:147], v[200:203], v[12:15]
	v_mfma_f32_16x16x32_bf16 v[8:11], v[152:155], v[200:203], v[8:11]
	s_setprio 0
	s_setprio 1
	v_mfma_f32_16x16x32_bf16 v[60:63], v[148:151], v[180:183], v[60:63]
	v_mfma_f32_16x16x32_bf16 v[56:59], v[156:159], v[180:183], v[56:59]
	v_mfma_f32_16x16x32_bf16 v[44:47], v[148:151], v[188:191], v[44:47]
	v_mfma_f32_16x16x32_bf16 v[40:43], v[156:159], v[188:191], v[40:43]
	v_mfma_f32_16x16x32_bf16 v[28:31], v[148:151], v[196:199], v[28:31]
	v_mfma_f32_16x16x32_bf16 v[24:27], v[156:159], v[196:199], v[24:27]
	v_mfma_f32_16x16x32_bf16 v[12:15], v[148:151], v[204:207], v[12:15]
	v_mfma_f32_16x16x32_bf16 v[8:11], v[156:159], v[204:207], v[8:11]
	s_setprio 0
	s_setprio 1
	v_mfma_f32_16x16x32_bf16 v[52:55], v[160:163], v[176:179], v[52:55]
	v_mfma_f32_16x16x32_bf16 v[48:51], v[168:171], v[176:179], v[48:51]
	v_mfma_f32_16x16x32_bf16 v[36:39], v[160:163], v[184:187], v[36:39]
	v_mfma_f32_16x16x32_bf16 v[32:35], v[168:171], v[184:187], v[32:35]
	v_mfma_f32_16x16x32_bf16 v[20:23], v[160:163], v[192:195], v[20:23]
	v_mfma_f32_16x16x32_bf16 v[16:19], v[168:171], v[192:195], v[16:19]
	v_mfma_f32_16x16x32_bf16 v[4:7], v[160:163], v[200:203], v[4:7]
	v_mfma_f32_16x16x32_bf16 v[0:3], v[168:171], v[200:203], v[0:3]
	s_setprio 0
	s_setprio 1
	v_mfma_f32_16x16x32_bf16 v[52:55], v[164:167], v[180:183], v[52:55]
	v_mfma_f32_16x16x32_bf16 v[48:51], v[172:175], v[180:183], v[48:51]
	v_mfma_f32_16x16x32_bf16 v[36:39], v[164:167], v[188:191], v[36:39]
	v_mfma_f32_16x16x32_bf16 v[32:35], v[172:175], v[188:191], v[32:35]
	v_mfma_f32_16x16x32_bf16 v[20:23], v[164:167], v[196:199], v[20:23]
	v_mfma_f32_16x16x32_bf16 v[16:19], v[172:175], v[196:199], v[16:19]
	v_mfma_f32_16x16x32_bf16 v[4:7], v[164:167], v[204:207], v[4:7]
	v_mfma_f32_16x16x32_bf16 v[0:3], v[172:175], v[204:207], v[0:3]
	s_setprio 0
	s_barrier
	s_add_i32 s57, s57, 2
	s_add_u32 s38, s38, 0x100
	s_addc_u32 s39, s39, 0
	s_add_u32 s55, s55, 0x100
	s_addc_u32 s56, s56, 0
	s_cmp_gt_u32 s57, 13
	s_cbranch_scc0 .LBB0_1694

; #define G_STAGE(bufoff, gbase, voff) do { _Pragma("unroll") for (int _i = 0; _i < 2; ++_i) \
;         __builtin_amdgcn_global_load_lds((const unsigned*)((const char*)(gbase) + voff[_i]), (LAS unsigned*)(lds + (bufoff) + ldsw + _i * 8192), 16, 0, 0); } while (0)
; #define G_LDA(dst, b, h) do { _Pragma("unroll") for (int m = 0; m < 4; ++m) _Pragma("unroll") for (int k = 0; k < 2; ++k) dst[m][k] = *(const LAS bf16x8*)(lds + G_SA(b, h) + aoff + m * 2048 + k * 1024); } while (0)
; #define G_MMA(ai, bj, At_, Bt_) do { __builtin_amdgcn_s_setprio(1); _Pragma("unroll") for (int m = 0; m < 4; ++m) _Pragma("unroll") for (int n = 0; n < 2; ++n) _Pragma("unroll") for (int k = 0; k < 2; ++k) \
;         acc[ai][bj][m][n] = __builtin_amdgcn_mfma_f32_16x16x32_bf16(Bt_[n][k], At_[m][k], acc[ai][bj][m][n], 0, 0, 0); __builtin_amdgcn_s_setprio(0); } while (0)
; #define WAIT_V(n) asm volatile("s_waitcnt vmcnt(" #n ")" ::: "memory")
; #define WAIT_L(n) asm volatile("s_waitcnt lgkmcnt(" #n ")" ::: "memory")
; #define BAR __builtin_amdgcn_s_barrier()
; #define SCHED __builtin_amdgcn_sched_barrier(0)
; template <class Get, class Epi>
; DI void gemm_loop(int ntiles, int ld, char* shm, const Get& get, const Epi& epi) {
;     ...
;             WAIT_V(8); WAIT_L(0); BAR; G_MMA(0, 0, At, B0); G_MMA(0, 1, At, B1); BAR; SCHED;
;             G_LDA(At, 0, 1); G_STAGE(G_SB(0, 0), b2, voffB); G_STAGE(G_SB(0, 1), b2 + hstep, voffB); G_STAGE(G_SA(0, 0), a2, voffA);
.Lrj_1781_0:
	s_waitcnt lgkmcnt(0)
	s_barrier
	s_setprio 1
	s_waitcnt lgkmcnt(0)
	v_mfma_f32_16x16x32_bf16 v[124:127], v[128:131], v[180:183], 0
	v_mfma_f32_16x16x32_bf16 v[120:123], v[136:139], v[180:183], 0
	v_mfma_f32_16x16x32_bf16 v[116:119], v[128:131], v[188:191], 0
	v_mfma_f32_16x16x32_bf16 v[112:115], v[136:139], v[188:191], 0
	v_mfma_f32_16x16x32_bf16 v[108:111], v[128:131], v[196:199], 0
	v_mfma_f32_16x16x32_bf16 v[104:107], v[136:139], v[196:199], 0
	v_mfma_f32_16x16x32_bf16 v[100:103], v[128:131], v[204:207], 0
	v_mfma_f32_16x16x32_bf16 v[96:99], v[136:139], v[204:207], 0
	s_setprio 0
	s_setprio 1
	v_mfma_f32_16x16x32_bf16 v[124:127], v[132:135], v[184:187], v[124:127]
	v_mfma_f32_16x16x32_bf16 v[120:123], v[140:143], v[184:187], v[120:123]
	v_mfma_f32_16x16x32_bf16 v[116:119], v[132:135], v[192:195], v[116:119]
	v_mfma_f32_16x16x32_bf16 v[112:115], v[140:143], v[192:195], v[112:115]
	v_mfma_f32_16x16x32_bf16 v[108:111], v[132:135], v[200:203], v[108:111]
	v_mfma_f32_16x16x32_bf16 v[104:107], v[140:143], v[200:203], v[104:107]
	v_mfma_f32_16x16x32_bf16 v[100:103], v[132:135], v[208:211], v[100:103]
	v_mfma_f32_16x16x32_bf16 v[96:99], v[140:143], v[208:211], v[96:99]
	s_setprio 0
	s_setprio 1
	v_mfma_f32_16x16x32_bf16 v[60:63], v[158:161], v[180:183], 0
	v_mfma_f32_16x16x32_bf16 v[56:59], v[172:175], v[180:183], 0
	v_mfma_f32_16x16x32_bf16 v[52:55], v[158:161], v[188:191], 0
	v_mfma_f32_16x16x32_bf16 v[48:51], v[172:175], v[188:191], 0
	v_mfma_f32_16x16x32_bf16 v[44:47], v[158:161], v[196:199], 0
	v_mfma_f32_16x16x32_bf16 v[40:43], v[172:175], v[196:199], 0
	v_mfma_f32_16x16x32_bf16 v[36:39], v[158:161], v[204:207], 0
	v_mfma_f32_16x16x32_bf16 v[32:35], v[172:175], v[204:207], 0
	s_setprio 0
	s_setprio 1
	v_mfma_f32_16x16x32_bf16 v[60:63], v[162:165], v[184:187], v[60:63]
	v_mfma_f32_16x16x32_bf16 v[56:59], v[176:179], v[184:187], v[56:59]
	v_mfma_f32_16x16x32_bf16 v[52:55], v[162:165], v[192:195], v[52:55]
	v_mfma_f32_16x16x32_bf16 v[48:51], v[176:179], v[192:195], v[48:51]
	v_mfma_f32_16x16x32_bf16 v[44:47], v[162:165], v[200:203], v[44:47]
	v_mfma_f32_16x16x32_bf16 v[40:43], v[176:179], v[200:203], v[40:43]
	v_mfma_f32_16x16x32_bf16 v[36:39], v[162:165], v[208:211], v[36:39]
	v_mfma_f32_16x16x32_bf16 v[32:35], v[176:179], v[208:211], v[32:35]
	s_setprio 0
	s_barrier
	s_add_i32 s4, s53, s44
	v_lshl_add_u64 v[144:145], s[40:41], 0, v[148:149]
	s_mov_b32 m0, s4
	ds_read_b128 v[180:183], v171 offset:16384
	ds_read_b128 v[184:187], v171 offset:17408
	ds_read_b128 v[188:191], v171 offset:18432
	ds_read_b128 v[192:195], v171 offset:19456
	ds_read_b128 v[196:199], v171 offset:20480
	ds_read_b128 v[200:203], v171 offset:21504
	ds_read_b128 v[204:207], v171 offset:22528
	ds_read_b128 v[208:211], v171 offset:23552
	global_load_lds_dwordx4 v[144:145], off
	s_add_i32 m0, s4, 0x2000
	s_add_u32 s4, s40, 0xb0000
	v_lshl_add_u64 v[166:167], s[40:41], 0, v[152:153]
	s_addc_u32 s5, s41, 0
	s_add_i32 s78, s54, s44
	global_load_lds_dwordx4 v[166:167], off
	v_lshl_add_u64 v[212:213], s[4:5], 0, v[148:149]
	s_mov_b32 m0, s78
	v_lshl_add_u64 v[214:215], s[42:43], 0, v[150:151]
	global_load_lds_dwordx4 v[212:213], off
	v_lshl_add_u64 v[212:213], s[4:5], 0, v[152:153]
	s_add_i32 m0, s78, 0x2000
	s_nop 0
	global_load_lds_dwordx4 v[212:213], off
	v_lshl_add_u64 v[212:213], s[42:43], 0, v[146:147]
	s_mov_b32 m0, s45
	s_nop 0
	global_load_lds_dwordx4 v[212:213], off
	s_mov_b32 m0, s46
	s_nop 0
	global_load_lds_dwordx4 v[214:215], off
	s_cmp_lg_u32 s100, 0
	s_cbranch_scc0 .Lrf_1781_1
	s_waitcnt vmcnt(16)
	s_branch .Lrj_1781_1

; #define G_STAGE(bufoff, gbase, voff) do { _Pragma("unroll") for (int _i = 0; _i < 2; ++_i) \
;         __builtin_amdgcn_global_load_lds((const unsigned*)((const char*)(gbase) + voff[_i]), (LAS unsigned*)(lds + (bufoff) + ldsw + _i * 8192), 16, 0, 0); } while (0)
; #define G_LDA(dst, b, h) do { _Pragma("unroll") for (int m = 0; m < 4; ++m) _Pragma("unroll") for (int k = 0; k < 2; ++k) dst[m][k] = *(const LAS bf16x8*)(lds + G_SA(b, h) + aoff + m * 2048 + k * 1024); } while (0)
; #define G_LDB(dst, b, h) do { _Pragma("unroll") for (int n = 0; n < 2; ++n) _Pragma("unroll") for (int k = 0; k < 2; ++k) dst[n][k] = *(const LAS bf16x8*)(lds + G_SB(b, h) + boff + n * 2048 + k * 1024); } while (0)
; #define G_MMA(ai, bj, At_, Bt_) do { __builtin_amdgcn_s_setprio(1); _Pragma("unroll") for (int m = 0; m < 4; ++m) _Pragma("unroll") for (int n = 0; n < 2; ++n) _Pragma("unroll") for (int k = 0; k < 2; ++k) \
;         acc[ai][bj][m][n] = __builtin_amdgcn_mfma_f32_16x16x32_bf16(Bt_[n][k], At_[m][k], acc[ai][bj][m][n], 0, 0, 0); __builtin_amdgcn_s_setprio(0); } while (0)
; #define WAIT_V(n) asm volatile("s_waitcnt vmcnt(" #n ")" ::: "memory")
; #define WAIT_L(n) asm volatile("s_waitcnt lgkmcnt(" #n ")" ::: "memory")
; #define BAR __builtin_amdgcn_s_barrier()
; #define SCHED __builtin_amdgcn_sched_barrier(0)
; template <class Get, class Epi>
; DI void gemm_loop(int ntiles, int ld, char* shm, const Get& get, const Epi& epi) {
;     ...
;             WAIT_V(8); WAIT_L(0); BAR; G_MMA(1, 0, At, B0); G_MMA(1, 1, At, B1); BAR; SCHED;
;             G_LDB(B0, 1, 0); G_LDB(B1, 1, 1); SCHED; G_LDA(At, 1, 0); G_STAGE(G_SA(0, 1), a2 + hstep, voffA);
;             WAIT_V(8); WAIT_L(0); BAR; G_MMA(0, 0, At, B0); G_MMA(0, 1, At, B1); BAR; SCHED;
.Lrj_1781_1:
	s_waitcnt lgkmcnt(0)
	s_barrier
	s_setprio 1
	s_waitcnt lgkmcnt(0)
	v_mfma_f32_16x16x32_bf16 v[92:95], v[128:131], v[180:183], 0
	v_mfma_f32_16x16x32_bf16 v[88:91], v[136:139], v[180:183], 0
	v_mfma_f32_16x16x32_bf16 v[84:87], v[128:131], v[188:191], 0
	v_mfma_f32_16x16x32_bf16 v[80:83], v[136:139], v[188:191], 0
	v_mfma_f32_16x16x32_bf16 v[76:79], v[128:131], v[196:199], 0
	v_mfma_f32_16x16x32_bf16 v[72:75], v[136:139], v[196:199], 0
	v_mfma_f32_16x16x32_bf16 v[68:71], v[128:131], v[204:207], 0
	v_mfma_f32_16x16x32_bf16 v[64:67], v[136:139], v[204:207], 0
	s_setprio 0
	s_setprio 1
	v_mfma_f32_16x16x32_bf16 v[92:95], v[132:135], v[184:187], v[92:95]
	v_mfma_f32_16x16x32_bf16 v[88:91], v[140:143], v[184:187], v[88:91]
	v_mfma_f32_16x16x32_bf16 v[84:87], v[132:135], v[192:195], v[84:87]
	v_mfma_f32_16x16x32_bf16 v[80:83], v[140:143], v[192:195], v[80:83]
	v_mfma_f32_16x16x32_bf16 v[76:79], v[132:135], v[200:203], v[76:79]
	v_mfma_f32_16x16x32_bf16 v[72:75], v[140:143], v[200:203], v[72:75]
	v_mfma_f32_16x16x32_bf16 v[68:71], v[132:135], v[208:211], v[68:71]
	v_mfma_f32_16x16x32_bf16 v[64:67], v[140:143], v[208:211], v[64:67]
	s_setprio 0
	s_setprio 1
	v_mfma_f32_16x16x32_bf16 v[28:31], v[158:161], v[180:183], 0
	v_mfma_f32_16x16x32_bf16 v[24:27], v[172:175], v[180:183], 0
	v_mfma_f32_16x16x32_bf16 v[20:23], v[158:161], v[188:191], 0
	v_mfma_f32_16x16x32_bf16 v[16:19], v[172:175], v[188:191], 0
	v_mfma_f32_16x16x32_bf16 v[12:15], v[158:161], v[196:199], 0
	v_mfma_f32_16x16x32_bf16 v[8:11], v[172:175], v[196:199], 0
	v_mfma_f32_16x16x32_bf16 v[4:7], v[158:161], v[204:207], 0
	v_mfma_f32_16x16x32_bf16 v[0:3], v[172:175], v[204:207], 0
	s_setprio 0
	s_setprio 1
	v_mfma_f32_16x16x32_bf16 v[28:31], v[162:165], v[184:187], v[28:31]
	v_mfma_f32_16x16x32_bf16 v[24:27], v[176:179], v[184:187], v[24:27]
	v_mfma_f32_16x16x32_bf16 v[20:23], v[162:165], v[192:195], v[20:23]
	v_mfma_f32_16x16x32_bf16 v[16:19], v[176:179], v[192:195], v[16:19]
	v_mfma_f32_16x16x32_bf16 v[12:15], v[162:165], v[200:203], v[12:15]
	v_mfma_f32_16x16x32_bf16 v[8:11], v[176:179], v[200:203], v[8:11]
	v_mfma_f32_16x16x32_bf16 v[4:7], v[162:165], v[208:211], v[4:7]
	v_mfma_f32_16x16x32_bf16 v[0:3], v[176:179], v[208:211], v[0:3]
	s_setprio 0
	s_barrier
	s_add_i32 s78, 0, 0x18000
	s_add_i32 s79, 0, 0x1c000
	v_add_u32_e32 v140, s78, v168
	v_add_u32_e32 v176, s79, v168
	ds_read_b128 v[128:131], v140
	ds_read_b128 v[132:135], v140 offset:1024
	ds_read_b128 v[136:139], v140 offset:2048
	ds_read_b128 v[140:143], v140 offset:3072
	ds_read_b128 v[158:161], v176
	ds_read_b128 v[162:165], v176 offset:1024
	ds_read_b128 v[172:175], v176 offset:2048
	ds_read_b128 v[176:179], v176 offset:3072
	s_add_u32 s4, s42, 0xb0000
	s_addc_u32 s5, s43, 0
	s_mov_b32 m0, s47
	v_lshl_add_u64 v[216:217], s[4:5], 0, v[146:147]
	ds_read_b128 v[180:183], v171 offset:32768
	ds_read_b128 v[184:187], v171 offset:33792
	ds_read_b128 v[188:191], v171 offset:34816
	ds_read_b128 v[192:195], v171 offset:35840
	ds_read_b128 v[196:199], v171 offset:36864
	ds_read_b128 v[200:203], v171 offset:37888
	ds_read_b128 v[204:207], v171 offset:38912
	ds_read_b128 v[208:211], v171 offset:39936
	global_load_lds_dwordx4 v[216:217], off
	v_lshl_add_u64 v[216:217], s[4:5], 0, v[150:151]
	s_mov_b32 m0, s48
	s_nop 0
	global_load_lds_dwordx4 v[216:217], off
	s_waitcnt vmcnt(8)
	s_waitcnt lgkmcnt(0)
	s_barrier
	s_setprio 1
	s_waitcnt lgkmcnt(0)
	v_mfma_f32_16x16x32_bf16 v[124:127], v[128:131], v[180:183], v[124:127]
	v_mfma_f32_16x16x32_bf16 v[120:123], v[136:139], v[180:183], v[120:123]
	v_mfma_f32_16x16x32_bf16 v[116:119], v[128:131], v[188:191], v[116:119]
	v_mfma_f32_16x16x32_bf16 v[112:115], v[136:139], v[188:191], v[112:115]
	v_mfma_f32_16x16x32_bf16 v[108:111], v[128:131], v[196:199], v[108:111]
	v_mfma_f32_16x16x32_bf16 v[104:107], v[136:139], v[196:199], v[104:107]
	v_mfma_f32_16x16x32_bf16 v[100:103], v[128:131], v[204:207], v[100:103]
	v_mfma_f32_16x16x32_bf16 v[96:99], v[136:139], v[204:207], v[96:99]
	s_setprio 0
	s_setprio 1
	v_mfma_f32_16x16x32_bf16 v[124:127], v[132:135], v[184:187], v[124:127]
	v_mfma_f32_16x16x32_bf16 v[120:123], v[140:143], v[184:187], v[120:123]
	v_mfma_f32_16x16x32_bf16 v[116:119], v[132:135], v[192:195], v[116:119]
	v_mfma_f32_16x16x32_bf16 v[112:115], v[140:143], v[192:195], v[112:115]
	v_mfma_f32_16x16x32_bf16 v[108:111], v[132:135], v[200:203], v[108:111]
	v_mfma_f32_16x16x32_bf16 v[104:107], v[140:143], v[200:203], v[104:107]
	v_mfma_f32_16x16x32_bf16 v[100:103], v[132:135], v[208:211], v[100:103]
	v_mfma_f32_16x16x32_bf16 v[96:99], v[140:143], v[208:211], v[96:99]
	s_setprio 0
	s_setprio 1
	v_mfma_f32_16x16x32_bf16 v[60:63], v[158:161], v[180:183], v[60:63]
	v_mfma_f32_16x16x32_bf16 v[56:59], v[172:175], v[180:183], v[56:59]
	v_mfma_f32_16x16x32_bf16 v[52:55], v[158:161], v[188:191], v[52:55]
	v_mfma_f32_16x16x32_bf16 v[48:51], v[172:175], v[188:191], v[48:51]
	v_mfma_f32_16x16x32_bf16 v[44:47], v[158:161], v[196:199], v[44:47]
	v_mfma_f32_16x16x32_bf16 v[40:43], v[172:175], v[196:199], v[40:43]
	v_mfma_f32_16x16x32_bf16 v[36:39], v[158:161], v[204:207], v[36:39]
	v_mfma_f32_16x16x32_bf16 v[32:35], v[172:175], v[204:207], v[32:35]
	s_setprio 0
	s_setprio 1
	v_mfma_f32_16x16x32_bf16 v[60:63], v[162:165], v[184:187], v[60:63]
	v_mfma_f32_16x16x32_bf16 v[56:59], v[176:179], v[184:187], v[56:59]
	v_mfma_f32_16x16x32_bf16 v[52:55], v[162:165], v[192:195], v[52:55]
	v_mfma_f32_16x16x32_bf16 v[48:51], v[176:179], v[192:195], v[48:51]
	v_mfma_f32_16x16x32_bf16 v[44:47], v[162:165], v[200:203], v[44:47]
	v_mfma_f32_16x16x32_bf16 v[40:43], v[176:179], v[200:203], v[40:43]
	v_mfma_f32_16x16x32_bf16 v[36:39], v[162:165], v[208:211], v[36:39]
	v_mfma_f32_16x16x32_bf16 v[32:35], v[176:179], v[208:211], v[32:35]
	s_setprio 0
	s_barrier
; #define G_STAGE(bufoff, gbase, voff) do { _Pragma("unroll") for (int _i = 0; _i < 2; ++_i) \
;         __builtin_amdgcn_global_load_lds((const unsigned*)((const char*)(gbase) + voff[_i]), (LAS unsigned*)(lds + (bufoff) + ldsw + _i * 8192), 16, 0, 0); } while (0)
; #define G_LDA(dst, b, h) do { _Pragma("unroll") for (int m = 0; m < 4; ++m) _Pragma("unroll") for (int k = 0; k < 2; ++k) dst[m][k] = *(const LAS bf16x8*)(lds + G_SA(b, h) + aoff + m * 2048 + k * 1024); } while (0)
; #define G_LDB(dst, b, h) do { _Pragma("unroll") for (int n = 0; n < 2; ++n) _Pragma("unroll") for (int k = 0; k < 2; ++k) dst[n][k] = *(const LAS bf16x8*)(lds + G_SB(b, h) + boff + n * 2048 + k * 1024); } while (0)
; #define G_MMA(ai, bj, At_, Bt_) do { __builtin_amdgcn_s_setprio(1); _Pragma("unroll") for (int m = 0; m < 4; ++m) _Pragma("unroll") for (int n = 0; n < 2; ++n) _Pragma("unroll") for (int k = 0; k < 2; ++k) \
;         acc[ai][bj][m][n] = __builtin_amdgcn_mfma_f32_16x16x32_bf16(Bt_[n][k], At_[m][k], acc[ai][bj][m][n], 0, 0, 0); __builtin_amdgcn_s_setprio(0); } while (0)
; #define WAIT_V(n) asm volatile("s_waitcnt vmcnt(" #n ")" ::: "memory")
; #define WAIT_L(n) asm volatile("s_waitcnt lgkmcnt(" #n ")" ::: "memory")
; #define BAR __builtin_amdgcn_s_barrier()
; #define SCHED __builtin_amdgcn_sched_barrier(0)
; template <class Get, class Epi>
; DI void gemm_loop(int ntiles, int ld, char* shm, const Get& get, const Epi& epi) {
;     ...
;             G_LDB(B0, 0, 0); G_LDB(B1, 0, 1); SCHED; G_LDA(At, 0, 0); G_STAGE(G_SA(1, 1), a1 + hstep, voffA);
;             WAIT_V(8); WAIT_L(0); BAR; G_MMA(0, 0, At, B0); G_MMA(0, 1, At, B1); BAR; SCHED;
;     ...
;             G_LDA(At, 1, 1); G_STAGE(G_SB(1, 0), b3, voffB); G_STAGE(G_SB(1, 1), b3 + hstep, voffB); G_STAGE(G_SA(1, 0), a3, voffA);
;             WAIT_V(8); WAIT_L(0); BAR; G_MMA(1, 0, At, B0); G_MMA(1, 1, At, B1); BAR; SCHED;
	s_add_i32 s4, s78, s44
	v_lshl_add_u64 v[144:145], v[144:145], 0, s[10:11]
	s_mov_b32 m0, s4
	ds_read_b128 v[180:183], v171 offset:49152
	ds_read_b128 v[184:187], v171 offset:50176
	ds_read_b128 v[188:191], v171 offset:51200
	ds_read_b128 v[192:195], v171 offset:52224
	ds_read_b128 v[196:199], v171 offset:53248
	ds_read_b128 v[200:203], v171 offset:54272
	ds_read_b128 v[204:207], v171 offset:55296
	ds_read_b128 v[208:211], v171 offset:56320
	global_load_lds_dwordx4 v[144:145], off
	s_add_i32 m0, s4, 0x2000
	s_add_u32 s4, s40, 0xb0080
	v_lshl_add_u64 v[144:145], v[166:167], 0, s[10:11]
	s_addc_u32 s5, s41, 0
	s_add_i32 s40, s79, s44
	global_load_lds_dwordx4 v[144:145], off
	v_lshl_add_u64 v[144:145], s[4:5], 0, v[148:149]
	s_mov_b32 m0, s40
	s_nop 0
	global_load_lds_dwordx4 v[144:145], off
	v_lshl_add_u64 v[144:145], s[4:5], 0, v[152:153]
	s_add_i32 m0, s40, 0x2000
	s_nop 0
	global_load_lds_dwordx4 v[144:145], off
	v_lshl_add_u64 v[144:145], v[212:213], 0, s[10:11]
	s_mov_b32 m0, s51
	s_nop 0
	global_load_lds_dwordx4 v[144:145], off
	v_lshl_add_u64 v[144:145], v[214:215], 0, s[10:11]
	s_mov_b32 m0, s52
	s_nop 0
	global_load_lds_dwordx4 v[144:145], off
	s_waitcnt vmcnt(8)
	s_waitcnt lgkmcnt(0)
	s_barrier
	s_setprio 1
	s_waitcnt lgkmcnt(0)
	v_mfma_f32_16x16x32_bf16 v[92:95], v[128:131], v[180:183], v[92:95]
	v_mfma_f32_16x16x32_bf16 v[88:91], v[136:139], v[180:183], v[88:91]
	v_mfma_f32_16x16x32_bf16 v[84:87], v[128:131], v[188:191], v[84:87]
	v_mfma_f32_16x16x32_bf16 v[80:83], v[136:139], v[188:191], v[80:83]
	v_mfma_f32_16x16x32_bf16 v[76:79], v[128:131], v[196:199], v[76:79]
	v_mfma_f32_16x16x32_bf16 v[72:75], v[136:139], v[196:199], v[72:75]
	v_mfma_f32_16x16x32_bf16 v[68:71], v[128:131], v[204:207], v[68:71]
	v_mfma_f32_16x16x32_bf16 v[64:67], v[136:139], v[204:207], v[64:67]
	s_setprio 0
	s_setprio 1
	v_mfma_f32_16x16x32_bf16 v[92:95], v[132:135], v[184:187], v[92:95]
	v_mfma_f32_16x16x32_bf16 v[88:91], v[140:143], v[184:187], v[88:91]
	v_mfma_f32_16x16x32_bf16 v[84:87], v[132:135], v[192:195], v[84:87]
	v_mfma_f32_16x16x32_bf16 v[80:83], v[140:143], v[192:195], v[80:83]
	v_mfma_f32_16x16x32_bf16 v[76:79], v[132:135], v[200:203], v[76:79]
	v_mfma_f32_16x16x32_bf16 v[72:75], v[140:143], v[200:203], v[72:75]
	v_mfma_f32_16x16x32_bf16 v[68:71], v[132:135], v[208:211], v[68:71]
	v_mfma_f32_16x16x32_bf16 v[64:67], v[140:143], v[208:211], v[64:67]
	s_setprio 0
	s_setprio 1
	v_mfma_f32_16x16x32_bf16 v[28:31], v[158:161], v[180:183], v[28:31]
	v_mfma_f32_16x16x32_bf16 v[24:27], v[172:175], v[180:183], v[24:27]
	v_mfma_f32_16x16x32_bf16 v[20:23], v[158:161], v[188:191], v[20:23]
	v_mfma_f32_16x16x32_bf16 v[16:19], v[172:175], v[188:191], v[16:19]
	v_mfma_f32_16x16x32_bf16 v[12:15], v[158:161], v[196:199], v[12:15]
	v_mfma_f32_16x16x32_bf16 v[8:11], v[172:175], v[196:199], v[8:11]
	v_mfma_f32_16x16x32_bf16 v[4:7], v[158:161], v[204:207], v[4:7]
	v_mfma_f32_16x16x32_bf16 v[0:3], v[172:175], v[204:207], v[0:3]
	s_setprio 0
	s_setprio 1
	v_mfma_f32_16x16x32_bf16 v[28:31], v[162:165], v[184:187], v[28:31]
	v_mfma_f32_16x16x32_bf16 v[24:27], v[176:179], v[184:187], v[24:27]
	v_mfma_f32_16x16x32_bf16 v[20:23], v[162:165], v[192:195], v[20:23]
	v_mfma_f32_16x16x32_bf16 v[16:19], v[176:179], v[192:195], v[16:19]
	v_mfma_f32_16x16x32_bf16 v[12:15], v[162:165], v[200:203], v[12:15]
	v_mfma_f32_16x16x32_bf16 v[8:11], v[176:179], v[200:203], v[8:11]
	v_mfma_f32_16x16x32_bf16 v[4:7], v[162:165], v[208:211], v[4:7]
	v_mfma_f32_16x16x32_bf16 v[0:3], v[176:179], v[208:211], v[0:3]
	s_setprio 0
	s_barrier
	s_add_u32 s75, s75, 0x100
	s_addc_u32 s76, s76, 0
	s_cmp_ge_u32 s77, s73
	s_mov_b64 s[4:5], s[14:15]
	s_mov_b32 s40, s77
	s_cbranch_scc0 .LBB0_1781
	s_branch .Lpost_1781
.LBB0_1781:
	ds_read_b128 v[128:131], v169
	ds_read_b128 v[132:135], v169 offset:1024
	ds_read_b128 v[136:139], v169 offset:2048
	ds_read_b128 v[140:143], v169 offset:3072
	ds_read_b128 v[158:161], v170
	ds_read_b128 v[162:165], v170 offset:1024
	ds_read_b128 v[172:175], v170 offset:2048
	ds_read_b128 v[176:179], v170 offset:3072
	s_add_i32 s77, s40, 2
	s_add_u32 s14, s4, 0x100
	s_addc_u32 s15, s5, 0
	s_cmp_eq_u32 s74, s40
	s_cselect_b32 s40, s38, s75
	s_cselect_b32 s43, s37, s15
	s_cselect_b32 s42, s36, s14
	s_cselect_b32 s41, s39, s76
	v_lshl_add_u64 v[144:145], s[4:5], 0, v[154:155]
	s_add_i32 m0, s45, 0xc000
	ds_read_b128 v[180:183], v171
	ds_read_b128 v[184:187], v171 offset:1024
	ds_read_b128 v[188:191], v171 offset:2048
	ds_read_b128 v[192:195], v171 offset:3072
	ds_read_b128 v[196:199], v171 offset:4096
	ds_read_b128 v[200:203], v171 offset:5120
	ds_read_b128 v[204:207], v171 offset:6144
	ds_read_b128 v[208:211], v171 offset:7168
	global_load_lds_dwordx4 v[144:145], off
	v_lshl_add_u64 v[144:145], s[4:5], 0, v[156:157]
	s_add_i32 m0, s45, 0xe000
	s_nop 0
	global_load_lds_dwordx4 v[144:145], off
	s_waitcnt vmcnt(8)
	s_waitcnt lgkmcnt(0)
	s_barrier
; #define G_STAGE(bufoff, gbase, voff) do { _Pragma("unroll") for (int _i = 0; _i < 2; ++_i) \
;         __builtin_amdgcn_global_load_lds((const unsigned*)((const char*)(gbase) + voff[_i]), (LAS unsigned*)(lds + (bufoff) + ldsw + _i * 8192), 16, 0, 0); } while (0)
; #define G_LDA(dst, b, h) do { _Pragma("unroll") for (int m = 0; m < 4; ++m) _Pragma("unroll") for (int k = 0; k < 2; ++k) dst[m][k] = *(const LAS bf16x8*)(lds + G_SA(b, h) + aoff + m * 2048 + k * 1024); } while (0)
; #define G_MMA(ai, bj, At_, Bt_) do { __builtin_amdgcn_s_setprio(1); _Pragma("unroll") for (int m = 0; m < 4; ++m) _Pragma("unroll") for (int n = 0; n < 2; ++n) _Pragma("unroll") for (int k = 0; k < 2; ++k) \
;         acc[ai][bj][m][n] = __builtin_amdgcn_mfma_f32_16x16x32_bf16(Bt_[n][k], At_[m][k], acc[ai][bj][m][n], 0, 0, 0); __builtin_amdgcn_s_setprio(0); } while (0)
; #define WAIT_V(n) asm volatile("s_waitcnt vmcnt(" #n ")" ::: "memory")
; #define WAIT_L(n) asm volatile("s_waitcnt lgkmcnt(" #n ")" ::: "memory")
; #define BAR __builtin_amdgcn_s_barrier()
; #define SCHED __builtin_amdgcn_sched_barrier(0)
; template <class Get, class Epi>
; DI void gemm_loop(int ntiles, int ld, char* shm, const Get& get, const Epi& epi) {
;     ...
;             WAIT_V(8); WAIT_L(0); BAR; G_MMA(0, 0, At, B0); G_MMA(0, 1, At, B1); BAR; SCHED;
;             G_LDA(At, 0, 1); G_STAGE(G_SB(0, 0), b2, voffB); G_STAGE(G_SB(0, 1), b2 + hstep, voffB); G_STAGE(G_SA(0, 0), a2, voffA);
;             WAIT_V(8); WAIT_L(0); BAR; G_MMA(1, 0, At, B0); G_MMA(1, 1, At, B1); BAR; SCHED;
	s_setprio 1
	s_waitcnt lgkmcnt(0)
	v_mfma_f32_16x16x32_bf16 v[124:127], v[128:131], v[180:183], v[124:127]
	v_mfma_f32_16x16x32_bf16 v[120:123], v[136:139], v[180:183], v[120:123]
	v_mfma_f32_16x16x32_bf16 v[116:119], v[128:131], v[188:191], v[116:119]
	v_mfma_f32_16x16x32_bf16 v[112:115], v[136:139], v[188:191], v[112:115]
	v_mfma_f32_16x16x32_bf16 v[108:111], v[128:131], v[196:199], v[108:111]
	v_mfma_f32_16x16x32_bf16 v[104:107], v[136:139], v[196:199], v[104:107]
	v_mfma_f32_16x16x32_bf16 v[100:103], v[128:131], v[204:207], v[100:103]
	v_mfma_f32_16x16x32_bf16 v[96:99], v[136:139], v[204:207], v[96:99]
	s_setprio 0
	s_setprio 1
	v_mfma_f32_16x16x32_bf16 v[124:127], v[132:135], v[184:187], v[124:127]
	v_mfma_f32_16x16x32_bf16 v[120:123], v[140:143], v[184:187], v[120:123]
	v_mfma_f32_16x16x32_bf16 v[116:119], v[132:135], v[192:195], v[116:119]
	v_mfma_f32_16x16x32_bf16 v[112:115], v[140:143], v[192:195], v[112:115]
	v_mfma_f32_16x16x32_bf16 v[108:111], v[132:135], v[200:203], v[108:111]
	v_mfma_f32_16x16x32_bf16 v[104:107], v[140:143], v[200:203], v[104:107]
	v_mfma_f32_16x16x32_bf16 v[100:103], v[132:135], v[208:211], v[100:103]
	v_mfma_f32_16x16x32_bf16 v[96:99], v[140:143], v[208:211], v[96:99]
	s_setprio 0
	s_setprio 1
	v_mfma_f32_16x16x32_bf16 v[60:63], v[158:161], v[180:183], v[60:63]
	v_mfma_f32_16x16x32_bf16 v[56:59], v[172:175], v[180:183], v[56:59]
	v_mfma_f32_16x16x32_bf16 v[52:55], v[158:161], v[188:191], v[52:55]
	v_mfma_f32_16x16x32_bf16 v[48:51], v[172:175], v[188:191], v[48:51]
	v_mfma_f32_16x16x32_bf16 v[44:47], v[158:161], v[196:199], v[44:47]
	v_mfma_f32_16x16x32_bf16 v[40:43], v[172:175], v[196:199], v[40:43]
	v_mfma_f32_16x16x32_bf16 v[36:39], v[158:161], v[204:207], v[36:39]
	v_mfma_f32_16x16x32_bf16 v[32:35], v[172:175], v[204:207], v[32:35]
	s_setprio 0
	s_setprio 1
	v_mfma_f32_16x16x32_bf16 v[60:63], v[162:165], v[184:187], v[60:63]
	v_mfma_f32_16x16x32_bf16 v[56:59], v[176:179], v[184:187], v[56:59]
	v_mfma_f32_16x16x32_bf16 v[52:55], v[162:165], v[192:195], v[52:55]
	v_mfma_f32_16x16x32_bf16 v[48:51], v[176:179], v[192:195], v[48:51]
	v_mfma_f32_16x16x32_bf16 v[44:47], v[162:165], v[200:203], v[44:47]
	v_mfma_f32_16x16x32_bf16 v[40:43], v[176:179], v[200:203], v[40:43]
	v_mfma_f32_16x16x32_bf16 v[36:39], v[162:165], v[208:211], v[36:39]
	v_mfma_f32_16x16x32_bf16 v[32:35], v[176:179], v[208:211], v[32:35]
	s_setprio 0
	s_barrier
	s_add_i32 s4, s53, s44
	v_lshl_add_u64 v[144:145], s[40:41], 0, v[148:149]
	s_mov_b32 m0, s4
	ds_read_b128 v[180:183], v171 offset:16384
	ds_read_b128 v[184:187], v171 offset:17408
	ds_read_b128 v[188:191], v171 offset:18432
	ds_read_b128 v[192:195], v171 offset:19456
	ds_read_b128 v[196:199], v171 offset:20480
	ds_read_b128 v[200:203], v171 offset:21504
	ds_read_b128 v[204:207], v171 offset:22528
	ds_read_b128 v[208:211], v171 offset:23552
	global_load_lds_dwordx4 v[144:145], off
	s_add_i32 m0, s4, 0x2000
	s_add_u32 s4, s40, 0xb0000
	v_lshl_add_u64 v[166:167], s[40:41], 0, v[152:153]
	s_addc_u32 s5, s41, 0
	s_add_i32 s78, s54, s44
	global_load_lds_dwordx4 v[166:167], off
	v_lshl_add_u64 v[212:213], s[4:5], 0, v[148:149]
	s_mov_b32 m0, s78
	v_lshl_add_u64 v[214:215], s[42:43], 0, v[150:151]
	global_load_lds_dwordx4 v[212:213], off
	v_lshl_add_u64 v[212:213], s[4:5], 0, v[152:153]
	s_add_i32 m0, s78, 0x2000
	s_nop 0
	global_load_lds_dwordx4 v[212:213], off
	v_lshl_add_u64 v[212:213], s[42:43], 0, v[146:147]
	s_mov_b32 m0, s45
	s_nop 0
	global_load_lds_dwordx4 v[212:213], off
	s_mov_b32 m0, s46
	s_nop 0
	global_load_lds_dwordx4 v[214:215], off
	s_waitcnt vmcnt(8)
	s_waitcnt lgkmcnt(0)
	s_barrier
	s_setprio 1
	s_waitcnt lgkmcnt(0)
	v_mfma_f32_16x16x32_bf16 v[92:95], v[128:131], v[180:183], v[92:95]
	v_mfma_f32_16x16x32_bf16 v[88:91], v[136:139], v[180:183], v[88:91]
	v_mfma_f32_16x16x32_bf16 v[84:87], v[128:131], v[188:191], v[84:87]
	v_mfma_f32_16x16x32_bf16 v[80:83], v[136:139], v[188:191], v[80:83]
	v_mfma_f32_16x16x32_bf16 v[76:79], v[128:131], v[196:199], v[76:79]
	v_mfma_f32_16x16x32_bf16 v[72:75], v[136:139], v[196:199], v[72:75]
	v_mfma_f32_16x16x32_bf16 v[68:71], v[128:131], v[204:207], v[68:71]
	v_mfma_f32_16x16x32_bf16 v[64:67], v[136:139], v[204:207], v[64:67]
	s_setprio 0
	s_setprio 1
	v_mfma_f32_16x16x32_bf16 v[92:95], v[132:135], v[184:187], v[92:95]
	v_mfma_f32_16x16x32_bf16 v[88:91], v[140:143], v[184:187], v[88:91]
	v_mfma_f32_16x16x32_bf16 v[84:87], v[132:135], v[192:195], v[84:87]
	v_mfma_f32_16x16x32_bf16 v[80:83], v[140:143], v[192:195], v[80:83]
	v_mfma_f32_16x16x32_bf16 v[76:79], v[132:135], v[200:203], v[76:79]
	v_mfma_f32_16x16x32_bf16 v[72:75], v[140:143], v[200:203], v[72:75]
	v_mfma_f32_16x16x32_bf16 v[68:71], v[132:135], v[208:211], v[68:71]
	v_mfma_f32_16x16x32_bf16 v[64:67], v[140:143], v[208:211], v[64:67]
	s_setprio 0
	s_setprio 1
	v_mfma_f32_16x16x32_bf16 v[28:31], v[158:161], v[180:183], v[28:31]
	v_mfma_f32_16x16x32_bf16 v[24:27], v[172:175], v[180:183], v[24:27]
	v_mfma_f32_16x16x32_bf16 v[20:23], v[158:161], v[188:191], v[20:23]
	v_mfma_f32_16x16x32_bf16 v[16:19], v[172:175], v[188:191], v[16:19]
	v_mfma_f32_16x16x32_bf16 v[12:15], v[158:161], v[196:199], v[12:15]
	v_mfma_f32_16x16x32_bf16 v[8:11], v[172:175], v[196:199], v[8:11]
	v_mfma_f32_16x16x32_bf16 v[4:7], v[158:161], v[204:207], v[4:7]
	v_mfma_f32_16x16x32_bf16 v[0:3], v[172:175], v[204:207], v[0:3]
	s_setprio 0
	s_setprio 1
	v_mfma_f32_16x16x32_bf16 v[28:31], v[162:165], v[184:187], v[28:31]
	v_mfma_f32_16x16x32_bf16 v[24:27], v[176:179], v[184:187], v[24:27]
	v_mfma_f32_16x16x32_bf16 v[20:23], v[162:165], v[192:195], v[20:23]
	v_mfma_f32_16x16x32_bf16 v[16:19], v[176:179], v[192:195], v[16:19]
	v_mfma_f32_16x16x32_bf16 v[12:15], v[162:165], v[200:203], v[12:15]
	v_mfma_f32_16x16x32_bf16 v[8:11], v[176:179], v[200:203], v[8:11]
	v_mfma_f32_16x16x32_bf16 v[4:7], v[162:165], v[208:211], v[4:7]
	v_mfma_f32_16x16x32_bf16 v[0:3], v[176:179], v[208:211], v[0:3]
	s_setprio 0
	s_barrier
; #define G_STAGE(bufoff, gbase, voff) do { _Pragma("unroll") for (int _i = 0; _i < 2; ++_i) \
;         __builtin_amdgcn_global_load_lds((const unsigned*)((const char*)(gbase) + voff[_i]), (LAS unsigned*)(lds + (bufoff) + ldsw + _i * 8192), 16, 0, 0); } while (0)
; #define G_LDA(dst, b, h) do { _Pragma("unroll") for (int m = 0; m < 4; ++m) _Pragma("unroll") for (int k = 0; k < 2; ++k) dst[m][k] = *(const LAS bf16x8*)(lds + G_SA(b, h) + aoff + m * 2048 + k * 1024); } while (0)
; #define G_LDB(dst, b, h) do { _Pragma("unroll") for (int n = 0; n < 2; ++n) _Pragma("unroll") for (int k = 0; k < 2; ++k) dst[n][k] = *(const LAS bf16x8*)(lds + G_SB(b, h) + boff + n * 2048 + k * 1024); } while (0)
; #define G_MMA(ai, bj, At_, Bt_) do { __builtin_amdgcn_s_setprio(1); _Pragma("unroll") for (int m = 0; m < 4; ++m) _Pragma("unroll") for (int n = 0; n < 2; ++n) _Pragma("unroll") for (int k = 0; k < 2; ++k) \
;         acc[ai][bj][m][n] = __builtin_amdgcn_mfma_f32_16x16x32_bf16(Bt_[n][k], At_[m][k], acc[ai][bj][m][n], 0, 0, 0); __builtin_amdgcn_s_setprio(0); } while (0)
; #define WAIT_V(n) asm volatile("s_waitcnt vmcnt(" #n ")" ::: "memory")
; #define WAIT_L(n) asm volatile("s_waitcnt lgkmcnt(" #n ")" ::: "memory")
; #define BAR __builtin_amdgcn_s_barrier()
; #define SCHED __builtin_amdgcn_sched_barrier(0)
; template <class Get, class Epi>
; DI void gemm_loop(int ntiles, int ld, char* shm, const Get& get, const Epi& epi) {
;     ...
;             G_LDB(B0, 1, 0); G_LDB(B1, 1, 1); SCHED; G_LDA(At, 1, 0); G_STAGE(G_SA(0, 1), a2 + hstep, voffA);
;             WAIT_V(8); WAIT_L(0); BAR; G_MMA(0, 0, At, B0); G_MMA(0, 1, At, B1); BAR; SCHED;
	s_add_i32 s78, 0, 0x18000
	s_add_i32 s79, 0, 0x1c000
	v_add_u32_e32 v140, s78, v168
	v_add_u32_e32 v176, s79, v168
	ds_read_b128 v[128:131], v140
	ds_read_b128 v[132:135], v140 offset:1024
	ds_read_b128 v[136:139], v140 offset:2048
	ds_read_b128 v[140:143], v140 offset:3072
	ds_read_b128 v[158:161], v176
	ds_read_b128 v[162:165], v176 offset:1024
	ds_read_b128 v[172:175], v176 offset:2048
	ds_read_b128 v[176:179], v176 offset:3072
	s_add_u32 s4, s42, 0xb0000
	s_addc_u32 s5, s43, 0
	s_mov_b32 m0, s47
	v_lshl_add_u64 v[216:217], s[4:5], 0, v[146:147]
	ds_read_b128 v[180:183], v171 offset:32768
	ds_read_b128 v[184:187], v171 offset:33792
	ds_read_b128 v[188:191], v171 offset:34816
	ds_read_b128 v[192:195], v171 offset:35840
	ds_read_b128 v[196:199], v171 offset:36864
	ds_read_b128 v[200:203], v171 offset:37888
	ds_read_b128 v[204:207], v171 offset:38912
	ds_read_b128 v[208:211], v171 offset:39936
	global_load_lds_dwordx4 v[216:217], off
	v_lshl_add_u64 v[216:217], s[4:5], 0, v[150:151]
	s_mov_b32 m0, s48
	s_nop 0
	global_load_lds_dwordx4 v[216:217], off
	s_waitcnt vmcnt(8)
	s_waitcnt lgkmcnt(0)
	s_barrier
	s_setprio 1
	s_waitcnt lgkmcnt(0)
	v_mfma_f32_16x16x32_bf16 v[124:127], v[128:131], v[180:183], v[124:127]
	v_mfma_f32_16x16x32_bf16 v[120:123], v[136:139], v[180:183], v[120:123]
	v_mfma_f32_16x16x32_bf16 v[116:119], v[128:131], v[188:191], v[116:119]
	v_mfma_f32_16x16x32_bf16 v[112:115], v[136:139], v[188:191], v[112:115]
	v_mfma_f32_16x16x32_bf16 v[108:111], v[128:131], v[196:199], v[108:111]
	v_mfma_f32_16x16x32_bf16 v[104:107], v[136:139], v[196:199], v[104:107]
	v_mfma_f32_16x16x32_bf16 v[100:103], v[128:131], v[204:207], v[100:103]
	v_mfma_f32_16x16x32_bf16 v[96:99], v[136:139], v[204:207], v[96:99]
	s_setprio 0
	s_setprio 1
	v_mfma_f32_16x16x32_bf16 v[124:127], v[132:135], v[184:187], v[124:127]
	v_mfma_f32_16x16x32_bf16 v[120:123], v[140:143], v[184:187], v[120:123]
	v_mfma_f32_16x16x32_bf16 v[116:119], v[132:135], v[192:195], v[116:119]
	v_mfma_f32_16x16x32_bf16 v[112:115], v[140:143], v[192:195], v[112:115]
	v_mfma_f32_16x16x32_bf16 v[108:111], v[132:135], v[200:203], v[108:111]
	v_mfma_f32_16x16x32_bf16 v[104:107], v[140:143], v[200:203], v[104:107]
	v_mfma_f32_16x16x32_bf16 v[100:103], v[132:135], v[208:211], v[100:103]
	v_mfma_f32_16x16x32_bf16 v[96:99], v[140:143], v[208:211], v[96:99]
	s_setprio 0
	s_setprio 1
	v_mfma_f32_16x16x32_bf16 v[60:63], v[158:161], v[180:183], v[60:63]
	v_mfma_f32_16x16x32_bf16 v[56:59], v[172:175], v[180:183], v[56:59]
	v_mfma_f32_16x16x32_bf16 v[52:55], v[158:161], v[188:191], v[52:55]
	v_mfma_f32_16x16x32_bf16 v[48:51], v[172:175], v[188:191], v[48:51]
	v_mfma_f32_16x16x32_bf16 v[44:47], v[158:161], v[196:199], v[44:47]
	v_mfma_f32_16x16x32_bf16 v[40:43], v[172:175], v[196:199], v[40:43]
	v_mfma_f32_16x16x32_bf16 v[36:39], v[158:161], v[204:207], v[36:39]
	v_mfma_f32_16x16x32_bf16 v[32:35], v[172:175], v[204:207], v[32:35]
	s_setprio 0
	s_setprio 1
	v_mfma_f32_16x16x32_bf16 v[60:63], v[162:165], v[184:187], v[60:63]
	v_mfma_f32_16x16x32_bf16 v[56:59], v[176:179], v[184:187], v[56:59]
	v_mfma_f32_16x16x32_bf16 v[52:55], v[162:165], v[192:195], v[52:55]
	v_mfma_f32_16x16x32_bf16 v[48:51], v[176:179], v[192:195], v[48:51]
	v_mfma_f32_16x16x32_bf16 v[44:47], v[162:165], v[200:203], v[44:47]
	v_mfma_f32_16x16x32_bf16 v[40:43], v[176:179], v[200:203], v[40:43]
	v_mfma_f32_16x16x32_bf16 v[36:39], v[162:165], v[208:211], v[36:39]
	v_mfma_f32_16x16x32_bf16 v[32:35], v[176:179], v[208:211], v[32:35]
	s_setprio 0
	s_barrier
; #define G_STAGE(bufoff, gbase, voff) do { _Pragma("unroll") for (int _i = 0; _i < 2; ++_i) \
;         __builtin_amdgcn_global_load_lds((const unsigned*)((const char*)(gbase) + voff[_i]), (LAS unsigned*)(lds + (bufoff) + ldsw + _i * 8192), 16, 0, 0); } while (0)
; #define G_LDA(dst, b, h) do { _Pragma("unroll") for (int m = 0; m < 4; ++m) _Pragma("unroll") for (int k = 0; k < 2; ++k) dst[m][k] = *(const LAS bf16x8*)(lds + G_SA(b, h) + aoff + m * 2048 + k * 1024); } while (0)
; #define G_MMA(ai, bj, At_, Bt_) do { __builtin_amdgcn_s_setprio(1); _Pragma("unroll") for (int m = 0; m < 4; ++m) _Pragma("unroll") for (int n = 0; n < 2; ++n) _Pragma("unroll") for (int k = 0; k < 2; ++k) \
;         acc[ai][bj][m][n] = __builtin_amdgcn_mfma_f32_16x16x32_bf16(Bt_[n][k], At_[m][k], acc[ai][bj][m][n], 0, 0, 0); __builtin_amdgcn_s_setprio(0); } while (0)
; #define WAIT_V(n) asm volatile("s_waitcnt vmcnt(" #n ")" ::: "memory")
; #define WAIT_L(n) asm volatile("s_waitcnt lgkmcnt(" #n ")" ::: "memory")
; #define BAR __builtin_amdgcn_s_barrier()
; #define SCHED __builtin_amdgcn_sched_barrier(0)
; template <class Get, class Epi>
; DI void gemm_loop(int ntiles, int ld, char* shm, const Get& get, const Epi& epi) {
;     ...
;             G_LDA(At, 1, 1); G_STAGE(G_SB(1, 0), b3, voffB); G_STAGE(G_SB(1, 1), b3 + hstep, voffB); G_STAGE(G_SA(1, 0), a3, voffA);
;             WAIT_V(8); WAIT_L(0); BAR; G_MMA(1, 0, At, B0); G_MMA(1, 1, At, B1); BAR; SCHED;
	s_add_i32 s4, s78, s44
	v_lshl_add_u64 v[144:145], v[144:145], 0, s[10:11]
	s_mov_b32 m0, s4
	ds_read_b128 v[180:183], v171 offset:49152
	ds_read_b128 v[184:187], v171 offset:50176
	ds_read_b128 v[188:191], v171 offset:51200
	ds_read_b128 v[192:195], v171 offset:52224
	ds_read_b128 v[196:199], v171 offset:53248
	ds_read_b128 v[200:203], v171 offset:54272
	ds_read_b128 v[204:207], v171 offset:55296
	ds_read_b128 v[208:211], v171 offset:56320
	global_load_lds_dwordx4 v[144:145], off
	s_add_i32 m0, s4, 0x2000
	s_add_u32 s4, s40, 0xb0080
	v_lshl_add_u64 v[144:145], v[166:167], 0, s[10:11]
	s_addc_u32 s5, s41, 0
	s_add_i32 s40, s79, s44
	global_load_lds_dwordx4 v[144:145], off
	v_lshl_add_u64 v[144:145], s[4:5], 0, v[148:149]
	s_mov_b32 m0, s40
	s_nop 0
	global_load_lds_dwordx4 v[144:145], off
	v_lshl_add_u64 v[144:145], s[4:5], 0, v[152:153]
	s_add_i32 m0, s40, 0x2000
	s_nop 0
	global_load_lds_dwordx4 v[144:145], off
	v_lshl_add_u64 v[144:145], v[212:213], 0, s[10:11]
	s_mov_b32 m0, s51
	s_nop 0
	global_load_lds_dwordx4 v[144:145], off
	v_lshl_add_u64 v[144:145], v[214:215], 0, s[10:11]
	s_mov_b32 m0, s52
	s_nop 0
	global_load_lds_dwordx4 v[144:145], off
	s_waitcnt vmcnt(8)
	s_waitcnt lgkmcnt(0)
	s_barrier
	s_setprio 1
	s_waitcnt lgkmcnt(0)
	v_mfma_f32_16x16x32_bf16 v[92:95], v[128:131], v[180:183], v[92:95]
	v_mfma_f32_16x16x32_bf16 v[88:91], v[136:139], v[180:183], v[88:91]
	v_mfma_f32_16x16x32_bf16 v[84:87], v[128:131], v[188:191], v[84:87]
	v_mfma_f32_16x16x32_bf16 v[80:83], v[136:139], v[188:191], v[80:83]
	v_mfma_f32_16x16x32_bf16 v[76:79], v[128:131], v[196:199], v[76:79]
	v_mfma_f32_16x16x32_bf16 v[72:75], v[136:139], v[196:199], v[72:75]
	v_mfma_f32_16x16x32_bf16 v[68:71], v[128:131], v[204:207], v[68:71]
	v_mfma_f32_16x16x32_bf16 v[64:67], v[136:139], v[204:207], v[64:67]
	s_setprio 0
	s_setprio 1
	v_mfma_f32_16x16x32_bf16 v[92:95], v[132:135], v[184:187], v[92:95]
	v_mfma_f32_16x16x32_bf16 v[88:91], v[140:143], v[184:187], v[88:91]
	v_mfma_f32_16x16x32_bf16 v[84:87], v[132:135], v[192:195], v[84:87]
	v_mfma_f32_16x16x32_bf16 v[80:83], v[140:143], v[192:195], v[80:83]
	v_mfma_f32_16x16x32_bf16 v[76:79], v[132:135], v[200:203], v[76:79]
	v_mfma_f32_16x16x32_bf16 v[72:75], v[140:143], v[200:203], v[72:75]
	v_mfma_f32_16x16x32_bf16 v[68:71], v[132:135], v[208:211], v[68:71]
	v_mfma_f32_16x16x32_bf16 v[64:67], v[140:143], v[208:211], v[64:67]
	s_setprio 0
	s_setprio 1
	v_mfma_f32_16x16x32_bf16 v[28:31], v[158:161], v[180:183], v[28:31]
	v_mfma_f32_16x16x32_bf16 v[24:27], v[172:175], v[180:183], v[24:27]
	v_mfma_f32_16x16x32_bf16 v[20:23], v[158:161], v[188:191], v[20:23]
	v_mfma_f32_16x16x32_bf16 v[16:19], v[172:175], v[188:191], v[16:19]
	v_mfma_f32_16x16x32_bf16 v[12:15], v[158:161], v[196:199], v[12:15]
	v_mfma_f32_16x16x32_bf16 v[8:11], v[172:175], v[196:199], v[8:11]
	v_mfma_f32_16x16x32_bf16 v[4:7], v[158:161], v[204:207], v[4:7]
	v_mfma_f32_16x16x32_bf16 v[0:3], v[172:175], v[204:207], v[0:3]
	s_setprio 0
	s_setprio 1
	v_mfma_f32_16x16x32_bf16 v[28:31], v[162:165], v[184:187], v[28:31]
	v_mfma_f32_16x16x32_bf16 v[24:27], v[176:179], v[184:187], v[24:27]
	v_mfma_f32_16x16x32_bf16 v[20:23], v[162:165], v[192:195], v[20:23]
	v_mfma_f32_16x16x32_bf16 v[16:19], v[176:179], v[192:195], v[16:19]
	v_mfma_f32_16x16x32_bf16 v[12:15], v[162:165], v[200:203], v[12:15]
	v_mfma_f32_16x16x32_bf16 v[8:11], v[176:179], v[200:203], v[8:11]
	v_mfma_f32_16x16x32_bf16 v[4:7], v[162:165], v[208:211], v[4:7]
	v_mfma_f32_16x16x32_bf16 v[0:3], v[176:179], v[208:211], v[0:3]
	s_setprio 0
	s_barrier
	s_add_u32 s75, s75, 0x100
	s_addc_u32 s76, s76, 0
	s_cmp_ge_u32 s77, s73
	s_mov_b64 s[4:5], s[14:15]
	s_mov_b32 s40, s77
	s_cbranch_scc0 .LBB0_1781

; #define G_STAGE(bufoff, gbase, voff) do { _Pragma("unroll") for (int _i = 0; _i < 2; ++_i) \
;         __builtin_amdgcn_global_load_lds((const unsigned*)((const char*)(gbase) + voff[_i]), (LAS unsigned*)(lds + (bufoff) + ldsw + _i * 8192), 16, 0, 0); } while (0)
; #define G_LDA(dst, b, h) do { _Pragma("unroll") for (int m = 0; m < 4; ++m) _Pragma("unroll") for (int k = 0; k < 2; ++k) dst[m][k] = *(const LAS bf16x8*)(lds + G_SA(b, h) + aoff + m * 2048 + k * 1024); } while (0)
; #define G_MMA(ai, bj, At_, Bt_) do { __builtin_amdgcn_s_setprio(1); _Pragma("unroll") for (int m = 0; m < 4; ++m) _Pragma("unroll") for (int n = 0; n < 2; ++n) _Pragma("unroll") for (int k = 0; k < 2; ++k) \
;         acc[ai][bj][m][n] = __builtin_amdgcn_mfma_f32_16x16x32_bf16(Bt_[n][k], At_[m][k], acc[ai][bj][m][n], 0, 0, 0); __builtin_amdgcn_s_setprio(0); } while (0)
; #define WAIT_V(n) asm volatile("s_waitcnt vmcnt(" #n ")" ::: "memory")
; #define WAIT_L(n) asm volatile("s_waitcnt lgkmcnt(" #n ")" ::: "memory")
; #define BAR __builtin_amdgcn_s_barrier()
; #define SCHED __builtin_amdgcn_sched_barrier(0)
; template <class Get, class Epi>
; DI void gemm_loop(int ntiles, int ld, char* shm, const Get& get, const Epi& epi) {
;     ...
;             WAIT_V(8); WAIT_L(0); BAR; G_MMA(0, 0, At, B0); G_MMA(0, 1, At, B1); BAR; SCHED;
;             G_LDA(At, 0, 1); G_STAGE(G_SB(0, 0), b2, voffB); G_STAGE(G_SB(0, 1), b2 + hstep, voffB); G_STAGE(G_SA(0, 0), a2, voffA);
.Lrj_2022_0:
	s_waitcnt lgkmcnt(0)
	s_barrier
	s_setprio 1
	s_waitcnt lgkmcnt(0)
	v_mfma_f32_16x16x32_bf16 v[132:135], v[96:99], v[184:187], 0
	v_mfma_f32_16x16x32_bf16 v[124:127], v[150:153], v[184:187], 0
	v_mfma_f32_16x16x32_bf16 v[128:131], v[96:99], v[192:195], 0
	v_mfma_f32_16x16x32_bf16 v[120:123], v[150:153], v[192:195], 0
	v_mfma_f32_16x16x32_bf16 v[116:119], v[96:99], v[200:203], 0
	v_mfma_f32_16x16x32_bf16 v[104:107], v[150:153], v[200:203], 0
	v_mfma_f32_16x16x32_bf16 v[112:115], v[96:99], v[208:211], 0
	v_mfma_f32_16x16x32_bf16 v[100:103], v[150:153], v[208:211], 0
	s_setprio 0
	s_setprio 1
	v_mfma_f32_16x16x32_bf16 v[132:135], v[108:111], v[188:191], v[132:135]
	v_mfma_f32_16x16x32_bf16 v[124:127], v[154:157], v[188:191], v[124:127]
	v_mfma_f32_16x16x32_bf16 v[128:131], v[108:111], v[196:199], v[128:131]
	v_mfma_f32_16x16x32_bf16 v[120:123], v[154:157], v[196:199], v[120:123]
	v_mfma_f32_16x16x32_bf16 v[116:119], v[108:111], v[204:207], v[116:119]
	v_mfma_f32_16x16x32_bf16 v[104:107], v[154:157], v[204:207], v[104:107]
	v_mfma_f32_16x16x32_bf16 v[112:115], v[108:111], v[212:215], v[112:115]
	v_mfma_f32_16x16x32_bf16 v[100:103], v[154:157], v[212:215], v[100:103]
	s_setprio 0
	s_setprio 1
	v_mfma_f32_16x16x32_bf16 v[60:63], v[158:161], v[184:187], 0
	v_mfma_f32_16x16x32_bf16 v[52:55], v[166:169], v[184:187], 0
	v_mfma_f32_16x16x32_bf16 v[56:59], v[158:161], v[192:195], 0
	v_mfma_f32_16x16x32_bf16 v[48:51], v[166:169], v[192:195], 0
	v_mfma_f32_16x16x32_bf16 v[44:47], v[158:161], v[200:203], 0
	v_mfma_f32_16x16x32_bf16 v[36:39], v[166:169], v[200:203], 0
	v_mfma_f32_16x16x32_bf16 v[40:43], v[158:161], v[208:211], 0
	v_mfma_f32_16x16x32_bf16 v[32:35], v[166:169], v[208:211], 0
	s_setprio 0
	s_setprio 1
	v_mfma_f32_16x16x32_bf16 v[60:63], v[162:165], v[188:191], v[60:63]
	v_mfma_f32_16x16x32_bf16 v[52:55], v[180:183], v[188:191], v[52:55]
	v_mfma_f32_16x16x32_bf16 v[56:59], v[162:165], v[196:199], v[56:59]
	v_mfma_f32_16x16x32_bf16 v[48:51], v[180:183], v[196:199], v[48:51]
	v_mfma_f32_16x16x32_bf16 v[44:47], v[162:165], v[204:207], v[44:47]
	v_mfma_f32_16x16x32_bf16 v[36:39], v[180:183], v[204:207], v[36:39]
	v_mfma_f32_16x16x32_bf16 v[40:43], v[162:165], v[212:215], v[40:43]
	v_mfma_f32_16x16x32_bf16 v[32:35], v[180:183], v[212:215], v[32:35]
	s_setprio 0
	s_barrier
	s_add_i32 s57, s75, s46
	v_lshl_add_u64 v[170:171], s[6:7], 0, v[140:141]
	s_mov_b32 m0, s57
	ds_read_b128 v[184:187], v175 offset:16384
	ds_read_b128 v[188:191], v175 offset:17408
	ds_read_b128 v[192:195], v175 offset:18432
	ds_read_b128 v[196:199], v175 offset:19456
	ds_read_b128 v[200:203], v175 offset:20480
	ds_read_b128 v[204:207], v175 offset:21504
	ds_read_b128 v[208:211], v175 offset:22528
	ds_read_b128 v[212:215], v175 offset:23552
	global_load_lds_dwordx4 v[170:171], off
	s_add_i32 m0, s57, 0x2000
	s_add_u32 s58, s6, 0x40000
	v_lshl_add_u64 v[216:217], s[6:7], 0, v[136:137]
	s_addc_u32 s59, s7, 0
	s_add_i32 s57, s76, s46
	global_load_lds_dwordx4 v[216:217], off
	v_lshl_add_u64 v[218:219], s[58:59], 0, v[140:141]
	s_mov_b32 m0, s57
	v_lshl_add_u64 v[220:221], s[14:15], 0, v[138:139]
	global_load_lds_dwordx4 v[218:219], off
	v_lshl_add_u64 v[218:219], s[58:59], 0, v[136:137]
	s_add_i32 m0, s57, 0x2000
	s_nop 0
	global_load_lds_dwordx4 v[218:219], off
	v_lshl_add_u64 v[218:219], s[14:15], 0, v[142:143]
	s_mov_b32 m0, s50
	s_nop 0
	global_load_lds_dwordx4 v[218:219], off
	s_mov_b32 m0, s51
	s_nop 0
	global_load_lds_dwordx4 v[220:221], off
	s_cmp_lg_u32 s100, 0
	s_cbranch_scc0 .Lrf_2022_1
	s_waitcnt vmcnt(16)
	s_branch .Lrj_2022_1

; #define G_STAGE(bufoff, gbase, voff) do { _Pragma("unroll") for (int _i = 0; _i < 2; ++_i) \
;         __builtin_amdgcn_global_load_lds((const unsigned*)((const char*)(gbase) + voff[_i]), (LAS unsigned*)(lds + (bufoff) + ldsw + _i * 8192), 16, 0, 0); } while (0)
; #define G_LDA(dst, b, h) do { _Pragma("unroll") for (int m = 0; m < 4; ++m) _Pragma("unroll") for (int k = 0; k < 2; ++k) dst[m][k] = *(const LAS bf16x8*)(lds + G_SA(b, h) + aoff + m * 2048 + k * 1024); } while (0)
; #define G_LDB(dst, b, h) do { _Pragma("unroll") for (int n = 0; n < 2; ++n) _Pragma("unroll") for (int k = 0; k < 2; ++k) dst[n][k] = *(const LAS bf16x8*)(lds + G_SB(b, h) + boff + n * 2048 + k * 1024); } while (0)
; #define G_MMA(ai, bj, At_, Bt_) do { __builtin_amdgcn_s_setprio(1); _Pragma("unroll") for (int m = 0; m < 4; ++m) _Pragma("unroll") for (int n = 0; n < 2; ++n) _Pragma("unroll") for (int k = 0; k < 2; ++k) \
;         acc[ai][bj][m][n] = __builtin_amdgcn_mfma_f32_16x16x32_bf16(Bt_[n][k], At_[m][k], acc[ai][bj][m][n], 0, 0, 0); __builtin_amdgcn_s_setprio(0); } while (0)
; #define WAIT_V(n) asm volatile("s_waitcnt vmcnt(" #n ")" ::: "memory")
; #define WAIT_L(n) asm volatile("s_waitcnt lgkmcnt(" #n ")" ::: "memory")
; #define BAR __builtin_amdgcn_s_barrier()
; #define SCHED __builtin_amdgcn_sched_barrier(0)
; template <class Get, class Epi>
; DI void gemm_loop(int ntiles, int ld, char* shm, const Get& get, const Epi& epi) {
;     ...
;             WAIT_V(8); WAIT_L(0); BAR; G_MMA(1, 0, At, B0); G_MMA(1, 1, At, B1); BAR; SCHED;
;             G_LDB(B0, 1, 0); G_LDB(B1, 1, 1); SCHED; G_LDA(At, 1, 0); G_STAGE(G_SA(0, 1), a2 + hstep, voffA);
;             WAIT_V(8); WAIT_L(0); BAR; G_MMA(0, 0, At, B0); G_MMA(0, 1, At, B1); BAR; SCHED;
.Lrj_2022_1:
	s_waitcnt lgkmcnt(0)
	s_barrier
	s_setprio 1
	s_waitcnt lgkmcnt(0)
	v_mfma_f32_16x16x32_bf16 v[92:95], v[96:99], v[184:187], 0
	v_mfma_f32_16x16x32_bf16 v[84:87], v[150:153], v[184:187], 0
	v_mfma_f32_16x16x32_bf16 v[88:91], v[96:99], v[192:195], 0
	v_mfma_f32_16x16x32_bf16 v[80:83], v[150:153], v[192:195], 0
	v_mfma_f32_16x16x32_bf16 v[76:79], v[96:99], v[200:203], 0
	v_mfma_f32_16x16x32_bf16 v[68:71], v[150:153], v[200:203], 0
	v_mfma_f32_16x16x32_bf16 v[72:75], v[96:99], v[208:211], 0
	v_mfma_f32_16x16x32_bf16 v[64:67], v[150:153], v[208:211], 0
	s_setprio 0
	s_setprio 1
	v_mfma_f32_16x16x32_bf16 v[92:95], v[108:111], v[188:191], v[92:95]
	v_mfma_f32_16x16x32_bf16 v[84:87], v[154:157], v[188:191], v[84:87]
	v_mfma_f32_16x16x32_bf16 v[88:91], v[108:111], v[196:199], v[88:91]
	v_mfma_f32_16x16x32_bf16 v[80:83], v[154:157], v[196:199], v[80:83]
	v_mfma_f32_16x16x32_bf16 v[76:79], v[108:111], v[204:207], v[76:79]
	v_mfma_f32_16x16x32_bf16 v[68:71], v[154:157], v[204:207], v[68:71]
	v_mfma_f32_16x16x32_bf16 v[72:75], v[108:111], v[212:215], v[72:75]
	v_mfma_f32_16x16x32_bf16 v[64:67], v[154:157], v[212:215], v[64:67]
	s_setprio 0
	s_setprio 1
	v_mfma_f32_16x16x32_bf16 v[28:31], v[158:161], v[184:187], 0
	v_mfma_f32_16x16x32_bf16 v[20:23], v[166:169], v[184:187], 0
	v_mfma_f32_16x16x32_bf16 v[24:27], v[158:161], v[192:195], 0
	v_mfma_f32_16x16x32_bf16 v[16:19], v[166:169], v[192:195], 0
	v_mfma_f32_16x16x32_bf16 v[12:15], v[158:161], v[200:203], 0
	v_mfma_f32_16x16x32_bf16 v[4:7], v[166:169], v[200:203], 0
	v_mfma_f32_16x16x32_bf16 v[8:11], v[158:161], v[208:211], 0
	v_mfma_f32_16x16x32_bf16 v[0:3], v[166:169], v[208:211], 0
	s_setprio 0
	s_setprio 1
	v_mfma_f32_16x16x32_bf16 v[28:31], v[162:165], v[188:191], v[28:31]
	v_mfma_f32_16x16x32_bf16 v[20:23], v[180:183], v[188:191], v[20:23]
	v_mfma_f32_16x16x32_bf16 v[24:27], v[162:165], v[196:199], v[24:27]
	v_mfma_f32_16x16x32_bf16 v[16:19], v[180:183], v[196:199], v[16:19]
	v_mfma_f32_16x16x32_bf16 v[12:15], v[162:165], v[204:207], v[12:15]
	v_mfma_f32_16x16x32_bf16 v[4:7], v[180:183], v[204:207], v[4:7]
	v_mfma_f32_16x16x32_bf16 v[8:11], v[162:165], v[212:215], v[8:11]
	v_mfma_f32_16x16x32_bf16 v[0:3], v[180:183], v[212:215], v[0:3]
	s_setprio 0
	s_barrier
	s_add_i32 s57, 0, 0x18000
	v_add_u32_e32 v144, s57, v172
	s_add_i32 s58, 0, 0x1c000
	ds_read_b128 v[96:99], v144
	ds_read_b128 v[108:111], v144 offset:1024
	ds_read_b128 v[150:153], v144 offset:2048
	ds_read_b128 v[154:157], v144 offset:3072
	v_add_u32_e32 v144, s58, v172
	ds_read_b128 v[158:161], v144
	ds_read_b128 v[162:165], v144 offset:1024
	ds_read_b128 v[166:169], v144 offset:2048
	ds_read_b128 v[180:183], v144 offset:3072
	s_add_u32 s14, s14, 0x40000
	s_addc_u32 s15, s15, 0
	s_mov_b32 m0, s71
	v_lshl_add_u64 v[222:223], s[14:15], 0, v[142:143]
	ds_read_b128 v[184:187], v175 offset:32768
	ds_read_b128 v[188:191], v175 offset:33792
	ds_read_b128 v[192:195], v175 offset:34816
	ds_read_b128 v[196:199], v175 offset:35840
	ds_read_b128 v[200:203], v175 offset:36864
	ds_read_b128 v[204:207], v175 offset:37888
	ds_read_b128 v[208:211], v175 offset:38912
	ds_read_b128 v[212:215], v175 offset:39936
	global_load_lds_dwordx4 v[222:223], off
	v_lshl_add_u64 v[222:223], s[14:15], 0, v[138:139]
	s_mov_b32 m0, s72
	s_nop 0
	global_load_lds_dwordx4 v[222:223], off
	s_waitcnt vmcnt(8)
	s_waitcnt lgkmcnt(0)
	s_barrier
	s_setprio 1
	s_waitcnt lgkmcnt(0)
	v_mfma_f32_16x16x32_bf16 v[132:135], v[96:99], v[184:187], v[132:135]
	v_mfma_f32_16x16x32_bf16 v[124:127], v[150:153], v[184:187], v[124:127]
	v_mfma_f32_16x16x32_bf16 v[128:131], v[96:99], v[192:195], v[128:131]
	v_mfma_f32_16x16x32_bf16 v[120:123], v[150:153], v[192:195], v[120:123]
	v_mfma_f32_16x16x32_bf16 v[116:119], v[96:99], v[200:203], v[116:119]
	v_mfma_f32_16x16x32_bf16 v[104:107], v[150:153], v[200:203], v[104:107]
	v_mfma_f32_16x16x32_bf16 v[112:115], v[96:99], v[208:211], v[112:115]
	v_mfma_f32_16x16x32_bf16 v[100:103], v[150:153], v[208:211], v[100:103]
	s_setprio 0
	s_setprio 1
	v_mfma_f32_16x16x32_bf16 v[132:135], v[108:111], v[188:191], v[132:135]
	v_mfma_f32_16x16x32_bf16 v[124:127], v[154:157], v[188:191], v[124:127]
	v_mfma_f32_16x16x32_bf16 v[128:131], v[108:111], v[196:199], v[128:131]
	v_mfma_f32_16x16x32_bf16 v[120:123], v[154:157], v[196:199], v[120:123]
	v_mfma_f32_16x16x32_bf16 v[116:119], v[108:111], v[204:207], v[116:119]
	v_mfma_f32_16x16x32_bf16 v[104:107], v[154:157], v[204:207], v[104:107]
	v_mfma_f32_16x16x32_bf16 v[112:115], v[108:111], v[212:215], v[112:115]
	v_mfma_f32_16x16x32_bf16 v[100:103], v[154:157], v[212:215], v[100:103]
	s_setprio 0
	s_setprio 1
	v_mfma_f32_16x16x32_bf16 v[60:63], v[158:161], v[184:187], v[60:63]
	v_mfma_f32_16x16x32_bf16 v[52:55], v[166:169], v[184:187], v[52:55]
	v_mfma_f32_16x16x32_bf16 v[56:59], v[158:161], v[192:195], v[56:59]
	v_mfma_f32_16x16x32_bf16 v[48:51], v[166:169], v[192:195], v[48:51]
	v_mfma_f32_16x16x32_bf16 v[44:47], v[158:161], v[200:203], v[44:47]
	v_mfma_f32_16x16x32_bf16 v[36:39], v[166:169], v[200:203], v[36:39]
	v_mfma_f32_16x16x32_bf16 v[40:43], v[158:161], v[208:211], v[40:43]
	v_mfma_f32_16x16x32_bf16 v[32:35], v[166:169], v[208:211], v[32:35]
	s_setprio 0
	s_setprio 1
	v_mfma_f32_16x16x32_bf16 v[60:63], v[162:165], v[188:191], v[60:63]
	v_mfma_f32_16x16x32_bf16 v[52:55], v[180:183], v[188:191], v[52:55]
	v_mfma_f32_16x16x32_bf16 v[56:59], v[162:165], v[196:199], v[56:59]
	v_mfma_f32_16x16x32_bf16 v[48:51], v[180:183], v[196:199], v[48:51]
	v_mfma_f32_16x16x32_bf16 v[44:47], v[162:165], v[204:207], v[44:47]
	v_mfma_f32_16x16x32_bf16 v[36:39], v[180:183], v[204:207], v[36:39]
	v_mfma_f32_16x16x32_bf16 v[40:43], v[162:165], v[212:215], v[40:43]
	v_mfma_f32_16x16x32_bf16 v[32:35], v[180:183], v[212:215], v[32:35]
	s_setprio 0
	s_barrier
; #define G_STAGE(bufoff, gbase, voff) do { _Pragma("unroll") for (int _i = 0; _i < 2; ++_i) \
;         __builtin_amdgcn_global_load_lds((const unsigned*)((const char*)(gbase) + voff[_i]), (LAS unsigned*)(lds + (bufoff) + ldsw + _i * 8192), 16, 0, 0); } while (0)
; #define G_LDA(dst, b, h) do { _Pragma("unroll") for (int m = 0; m < 4; ++m) _Pragma("unroll") for (int k = 0; k < 2; ++k) dst[m][k] = *(const LAS bf16x8*)(lds + G_SA(b, h) + aoff + m * 2048 + k * 1024); } while (0)
; #define G_LDB(dst, b, h) do { _Pragma("unroll") for (int n = 0; n < 2; ++n) _Pragma("unroll") for (int k = 0; k < 2; ++k) dst[n][k] = *(const LAS bf16x8*)(lds + G_SB(b, h) + boff + n * 2048 + k * 1024); } while (0)
; #define G_MMA(ai, bj, At_, Bt_) do { __builtin_amdgcn_s_setprio(1); _Pragma("unroll") for (int m = 0; m < 4; ++m) _Pragma("unroll") for (int n = 0; n < 2; ++n) _Pragma("unroll") for (int k = 0; k < 2; ++k) \
;         acc[ai][bj][m][n] = __builtin_amdgcn_mfma_f32_16x16x32_bf16(Bt_[n][k], At_[m][k], acc[ai][bj][m][n], 0, 0, 0); __builtin_amdgcn_s_setprio(0); } while (0)
; #define WAIT_V(n) asm volatile("s_waitcnt vmcnt(" #n ")" ::: "memory")
; #define WAIT_L(n) asm volatile("s_waitcnt lgkmcnt(" #n ")" ::: "memory")
; #define BAR __builtin_amdgcn_s_barrier()
; #define SCHED __builtin_amdgcn_sched_barrier(0)
; template <class Get, class Epi>
; DI void gemm_loop(int ntiles, int ld, char* shm, const Get& get, const Epi& epi) {
;     ...
;             G_LDB(B0, 0, 0); G_LDB(B1, 0, 1); SCHED; G_LDA(At, 0, 0); G_STAGE(G_SA(1, 1), a1 + hstep, voffA);
;             WAIT_V(8); WAIT_L(0); BAR; G_MMA(0, 0, At, B0); G_MMA(0, 1, At, B1); BAR; SCHED;
;     ...
;             G_LDA(At, 1, 1); G_STAGE(G_SB(1, 0), b3, voffB); G_STAGE(G_SB(1, 1), b3 + hstep, voffB); G_STAGE(G_SA(1, 0), a3, voffA);
;             WAIT_V(8); WAIT_L(0); BAR; G_MMA(1, 0, At, B0); G_MMA(1, 1, At, B1); BAR; SCHED;
	s_add_i32 s14, s57, s46
	v_lshl_add_u64 v[170:171], v[170:171], 0, s[10:11]
	s_mov_b32 m0, s14
	ds_read_b128 v[184:187], v175 offset:49152
	ds_read_b128 v[188:191], v175 offset:50176
	ds_read_b128 v[192:195], v175 offset:51200
	ds_read_b128 v[196:199], v175 offset:52224
	ds_read_b128 v[200:203], v175 offset:53248
	ds_read_b128 v[204:207], v175 offset:54272
	ds_read_b128 v[208:211], v175 offset:55296
	ds_read_b128 v[212:215], v175 offset:56320
	global_load_lds_dwordx4 v[170:171], off
	s_add_i32 m0, s14, 0x2000
	s_add_u32 s6, s6, 0x40080
	v_lshl_add_u64 v[170:171], v[216:217], 0, s[10:11]
	s_addc_u32 s7, s7, 0
	s_add_i32 s14, s58, s46
	global_load_lds_dwordx4 v[170:171], off
	v_lshl_add_u64 v[170:171], s[6:7], 0, v[140:141]
	s_mov_b32 m0, s14
	s_nop 0
	global_load_lds_dwordx4 v[170:171], off
	v_lshl_add_u64 v[170:171], s[6:7], 0, v[136:137]
	s_add_i32 m0, s14, 0x2000
	s_nop 0
	global_load_lds_dwordx4 v[170:171], off
	v_lshl_add_u64 v[170:171], v[218:219], 0, s[10:11]
	s_mov_b32 m0, s73
	s_nop 0
	global_load_lds_dwordx4 v[170:171], off
	v_lshl_add_u64 v[170:171], v[220:221], 0, s[10:11]
	s_mov_b32 m0, s74
	s_nop 0
	global_load_lds_dwordx4 v[170:171], off
	s_waitcnt vmcnt(8)
	s_waitcnt lgkmcnt(0)
	s_barrier
	s_setprio 1
	s_waitcnt lgkmcnt(0)
	v_mfma_f32_16x16x32_bf16 v[92:95], v[96:99], v[184:187], v[92:95]
	v_mfma_f32_16x16x32_bf16 v[84:87], v[150:153], v[184:187], v[84:87]
	v_mfma_f32_16x16x32_bf16 v[88:91], v[96:99], v[192:195], v[88:91]
	v_mfma_f32_16x16x32_bf16 v[80:83], v[150:153], v[192:195], v[80:83]
	v_mfma_f32_16x16x32_bf16 v[76:79], v[96:99], v[200:203], v[76:79]
	v_mfma_f32_16x16x32_bf16 v[68:71], v[150:153], v[200:203], v[68:71]
	v_mfma_f32_16x16x32_bf16 v[72:75], v[96:99], v[208:211], v[72:75]
	v_mfma_f32_16x16x32_bf16 v[64:67], v[150:153], v[208:211], v[64:67]
	s_setprio 0
	s_setprio 1
	v_mfma_f32_16x16x32_bf16 v[92:95], v[108:111], v[188:191], v[92:95]
	v_mfma_f32_16x16x32_bf16 v[84:87], v[154:157], v[188:191], v[84:87]
	v_mfma_f32_16x16x32_bf16 v[88:91], v[108:111], v[196:199], v[88:91]
	v_mfma_f32_16x16x32_bf16 v[80:83], v[154:157], v[196:199], v[80:83]
	v_mfma_f32_16x16x32_bf16 v[76:79], v[108:111], v[204:207], v[76:79]
	v_mfma_f32_16x16x32_bf16 v[68:71], v[154:157], v[204:207], v[68:71]
	v_mfma_f32_16x16x32_bf16 v[72:75], v[108:111], v[212:215], v[72:75]
	v_mfma_f32_16x16x32_bf16 v[64:67], v[154:157], v[212:215], v[64:67]
	s_setprio 0
	s_setprio 1
	v_mfma_f32_16x16x32_bf16 v[28:31], v[158:161], v[184:187], v[28:31]
	v_mfma_f32_16x16x32_bf16 v[20:23], v[166:169], v[184:187], v[20:23]
	v_mfma_f32_16x16x32_bf16 v[24:27], v[158:161], v[192:195], v[24:27]
	v_mfma_f32_16x16x32_bf16 v[16:19], v[166:169], v[192:195], v[16:19]
	v_mfma_f32_16x16x32_bf16 v[12:15], v[158:161], v[200:203], v[12:15]
	v_mfma_f32_16x16x32_bf16 v[4:7], v[166:169], v[200:203], v[4:7]
	v_mfma_f32_16x16x32_bf16 v[8:11], v[158:161], v[208:211], v[8:11]
	v_mfma_f32_16x16x32_bf16 v[0:3], v[166:169], v[208:211], v[0:3]
	s_setprio 0
	s_setprio 1
	v_mfma_f32_16x16x32_bf16 v[28:31], v[162:165], v[188:191], v[28:31]
	v_mfma_f32_16x16x32_bf16 v[20:23], v[180:183], v[188:191], v[20:23]
	v_mfma_f32_16x16x32_bf16 v[24:27], v[162:165], v[196:199], v[24:27]
	v_mfma_f32_16x16x32_bf16 v[16:19], v[180:183], v[196:199], v[16:19]
	v_mfma_f32_16x16x32_bf16 v[12:15], v[162:165], v[204:207], v[12:15]
	v_mfma_f32_16x16x32_bf16 v[4:7], v[180:183], v[204:207], v[4:7]
	v_mfma_f32_16x16x32_bf16 v[8:11], v[162:165], v[212:215], v[8:11]
	v_mfma_f32_16x16x32_bf16 v[0:3], v[180:183], v[212:215], v[0:3]
	s_setprio 0
	s_barrier
	s_add_i32 s56, s56, 2
	s_add_u32 s4, s4, 0x100
	s_addc_u32 s5, s5, 0
	s_add_u32 s54, s54, 0x100
	s_addc_u32 s55, s55, 0
	s_cmp_gt_u32 s56, 13
	s_cbranch_scc0 .LBB0_2022
	s_branch .Lpost_2022
.LBB0_2022:
	ds_read_b128 v[96:99], v173
	ds_read_b128 v[108:111], v173 offset:1024
	ds_read_b128 v[150:153], v173 offset:2048
	ds_read_b128 v[154:157], v173 offset:3072
	ds_read_b128 v[158:161], v174
	ds_read_b128 v[162:165], v174 offset:1024
	ds_read_b128 v[166:169], v174 offset:2048
	ds_read_b128 v[180:183], v174 offset:3072
	s_add_u32 s6, s4, 0xfffc0080
	s_addc_u32 s7, s5, -1
	s_cmp_eq_u32 s56, 12
	s_cselect_b32 s15, s3, s7
	s_cselect_b32 s14, s41, s6
	s_cselect_b32 s7, s43, s55
	s_cselect_b32 s6, s53, s54
	v_lshl_add_u64 v[170:171], s[4:5], 0, v[146:147]
	s_add_i32 m0, s50, 0xc000
	ds_read_b128 v[184:187], v175
	ds_read_b128 v[188:191], v175 offset:1024
	ds_read_b128 v[192:195], v175 offset:2048
	ds_read_b128 v[196:199], v175 offset:3072
	ds_read_b128 v[200:203], v175 offset:4096
	ds_read_b128 v[204:207], v175 offset:5120
	ds_read_b128 v[208:211], v175 offset:6144
	ds_read_b128 v[212:215], v175 offset:7168
	global_load_lds_dwordx4 v[170:171], off
	v_lshl_add_u64 v[170:171], s[4:5], 0, v[148:149]
	s_add_i32 m0, s50, 0xe000
	s_nop 0
	global_load_lds_dwordx4 v[170:171], off
	s_waitcnt vmcnt(8)
	s_waitcnt lgkmcnt(0)
	s_barrier
; #define G_STAGE(bufoff, gbase, voff) do { _Pragma("unroll") for (int _i = 0; _i < 2; ++_i) \
;         __builtin_amdgcn_global_load_lds((const unsigned*)((const char*)(gbase) + voff[_i]), (LAS unsigned*)(lds + (bufoff) + ldsw + _i * 8192), 16, 0, 0); } while (0)
; #define G_LDA(dst, b, h) do { _Pragma("unroll") for (int m = 0; m < 4; ++m) _Pragma("unroll") for (int k = 0; k < 2; ++k) dst[m][k] = *(const LAS bf16x8*)(lds + G_SA(b, h) + aoff + m * 2048 + k * 1024); } while (0)
; #define G_MMA(ai, bj, At_, Bt_) do { __builtin_amdgcn_s_setprio(1); _Pragma("unroll") for (int m = 0; m < 4; ++m) _Pragma("unroll") for (int n = 0; n < 2; ++n) _Pragma("unroll") for (int k = 0; k < 2; ++k) \
;         acc[ai][bj][m][n] = __builtin_amdgcn_mfma_f32_16x16x32_bf16(Bt_[n][k], At_[m][k], acc[ai][bj][m][n], 0, 0, 0); __builtin_amdgcn_s_setprio(0); } while (0)
; #define WAIT_V(n) asm volatile("s_waitcnt vmcnt(" #n ")" ::: "memory")
; #define WAIT_L(n) asm volatile("s_waitcnt lgkmcnt(" #n ")" ::: "memory")
; #define BAR __builtin_amdgcn_s_barrier()
; #define SCHED __builtin_amdgcn_sched_barrier(0)
; template <class Get, class Epi>
; DI void gemm_loop(int ntiles, int ld, char* shm, const Get& get, const Epi& epi) {
;     ...
;             WAIT_V(8); WAIT_L(0); BAR; G_MMA(0, 0, At, B0); G_MMA(0, 1, At, B1); BAR; SCHED;
;             G_LDA(At, 0, 1); G_STAGE(G_SB(0, 0), b2, voffB); G_STAGE(G_SB(0, 1), b2 + hstep, voffB); G_STAGE(G_SA(0, 0), a2, voffA);
;             WAIT_V(8); WAIT_L(0); BAR; G_MMA(1, 0, At, B0); G_MMA(1, 1, At, B1); BAR; SCHED;
	s_setprio 1
	s_waitcnt lgkmcnt(0)
	v_mfma_f32_16x16x32_bf16 v[132:135], v[96:99], v[184:187], v[132:135]
	v_mfma_f32_16x16x32_bf16 v[124:127], v[150:153], v[184:187], v[124:127]
	v_mfma_f32_16x16x32_bf16 v[128:131], v[96:99], v[192:195], v[128:131]
	v_mfma_f32_16x16x32_bf16 v[120:123], v[150:153], v[192:195], v[120:123]
	v_mfma_f32_16x16x32_bf16 v[116:119], v[96:99], v[200:203], v[116:119]
	v_mfma_f32_16x16x32_bf16 v[104:107], v[150:153], v[200:203], v[104:107]
	v_mfma_f32_16x16x32_bf16 v[112:115], v[96:99], v[208:211], v[112:115]
	v_mfma_f32_16x16x32_bf16 v[100:103], v[150:153], v[208:211], v[100:103]
	s_setprio 0
	s_setprio 1
	v_mfma_f32_16x16x32_bf16 v[132:135], v[108:111], v[188:191], v[132:135]
	v_mfma_f32_16x16x32_bf16 v[124:127], v[154:157], v[188:191], v[124:127]
	v_mfma_f32_16x16x32_bf16 v[128:131], v[108:111], v[196:199], v[128:131]
	v_mfma_f32_16x16x32_bf16 v[120:123], v[154:157], v[196:199], v[120:123]
	v_mfma_f32_16x16x32_bf16 v[116:119], v[108:111], v[204:207], v[116:119]
	v_mfma_f32_16x16x32_bf16 v[104:107], v[154:157], v[204:207], v[104:107]
	v_mfma_f32_16x16x32_bf16 v[112:115], v[108:111], v[212:215], v[112:115]
	v_mfma_f32_16x16x32_bf16 v[100:103], v[154:157], v[212:215], v[100:103]
	s_setprio 0
	s_setprio 1
	v_mfma_f32_16x16x32_bf16 v[60:63], v[158:161], v[184:187], v[60:63]
	v_mfma_f32_16x16x32_bf16 v[52:55], v[166:169], v[184:187], v[52:55]
	v_mfma_f32_16x16x32_bf16 v[56:59], v[158:161], v[192:195], v[56:59]
	v_mfma_f32_16x16x32_bf16 v[48:51], v[166:169], v[192:195], v[48:51]
	v_mfma_f32_16x16x32_bf16 v[44:47], v[158:161], v[200:203], v[44:47]
	v_mfma_f32_16x16x32_bf16 v[36:39], v[166:169], v[200:203], v[36:39]
	v_mfma_f32_16x16x32_bf16 v[40:43], v[158:161], v[208:211], v[40:43]
	v_mfma_f32_16x16x32_bf16 v[32:35], v[166:169], v[208:211], v[32:35]
	s_setprio 0
	s_setprio 1
	v_mfma_f32_16x16x32_bf16 v[60:63], v[162:165], v[188:191], v[60:63]
	v_mfma_f32_16x16x32_bf16 v[52:55], v[180:183], v[188:191], v[52:55]
	v_mfma_f32_16x16x32_bf16 v[56:59], v[162:165], v[196:199], v[56:59]
	v_mfma_f32_16x16x32_bf16 v[48:51], v[180:183], v[196:199], v[48:51]
	v_mfma_f32_16x16x32_bf16 v[44:47], v[162:165], v[204:207], v[44:47]
	v_mfma_f32_16x16x32_bf16 v[36:39], v[180:183], v[204:207], v[36:39]
	v_mfma_f32_16x16x32_bf16 v[40:43], v[162:165], v[212:215], v[40:43]
	v_mfma_f32_16x16x32_bf16 v[32:35], v[180:183], v[212:215], v[32:35]
	s_setprio 0
	s_barrier
	s_add_i32 s57, s75, s46
	v_lshl_add_u64 v[170:171], s[6:7], 0, v[140:141]
	s_mov_b32 m0, s57
	ds_read_b128 v[184:187], v175 offset:16384
	ds_read_b128 v[188:191], v175 offset:17408
	ds_read_b128 v[192:195], v175 offset:18432
	ds_read_b128 v[196:199], v175 offset:19456
	ds_read_b128 v[200:203], v175 offset:20480
	ds_read_b128 v[204:207], v175 offset:21504
	ds_read_b128 v[208:211], v175 offset:22528
	ds_read_b128 v[212:215], v175 offset:23552
	global_load_lds_dwordx4 v[170:171], off
	s_add_i32 m0, s57, 0x2000
	s_add_u32 s58, s6, 0x40000
	v_lshl_add_u64 v[216:217], s[6:7], 0, v[136:137]
	s_addc_u32 s59, s7, 0
	s_add_i32 s57, s76, s46
	global_load_lds_dwordx4 v[216:217], off
	v_lshl_add_u64 v[218:219], s[58:59], 0, v[140:141]
	s_mov_b32 m0, s57
	v_lshl_add_u64 v[220:221], s[14:15], 0, v[138:139]
	global_load_lds_dwordx4 v[218:219], off
	v_lshl_add_u64 v[218:219], s[58:59], 0, v[136:137]
	s_add_i32 m0, s57, 0x2000
	s_nop 0
	global_load_lds_dwordx4 v[218:219], off
	v_lshl_add_u64 v[218:219], s[14:15], 0, v[142:143]
	s_mov_b32 m0, s50
	s_nop 0
	global_load_lds_dwordx4 v[218:219], off
	s_mov_b32 m0, s51
	s_nop 0
	global_load_lds_dwordx4 v[220:221], off
	s_waitcnt vmcnt(8)
	s_waitcnt lgkmcnt(0)
	s_barrier
	s_setprio 1
	s_waitcnt lgkmcnt(0)
	v_mfma_f32_16x16x32_bf16 v[92:95], v[96:99], v[184:187], v[92:95]
	v_mfma_f32_16x16x32_bf16 v[84:87], v[150:153], v[184:187], v[84:87]
	v_mfma_f32_16x16x32_bf16 v[88:91], v[96:99], v[192:195], v[88:91]
	v_mfma_f32_16x16x32_bf16 v[80:83], v[150:153], v[192:195], v[80:83]
	v_mfma_f32_16x16x32_bf16 v[76:79], v[96:99], v[200:203], v[76:79]
	v_mfma_f32_16x16x32_bf16 v[68:71], v[150:153], v[200:203], v[68:71]
	v_mfma_f32_16x16x32_bf16 v[72:75], v[96:99], v[208:211], v[72:75]
	v_mfma_f32_16x16x32_bf16 v[64:67], v[150:153], v[208:211], v[64:67]
	s_setprio 0
	s_setprio 1
	v_mfma_f32_16x16x32_bf16 v[92:95], v[108:111], v[188:191], v[92:95]
	v_mfma_f32_16x16x32_bf16 v[84:87], v[154:157], v[188:191], v[84:87]
	v_mfma_f32_16x16x32_bf16 v[88:91], v[108:111], v[196:199], v[88:91]
	v_mfma_f32_16x16x32_bf16 v[80:83], v[154:157], v[196:199], v[80:83]
	v_mfma_f32_16x16x32_bf16 v[76:79], v[108:111], v[204:207], v[76:79]
	v_mfma_f32_16x16x32_bf16 v[68:71], v[154:157], v[204:207], v[68:71]
	v_mfma_f32_16x16x32_bf16 v[72:75], v[108:111], v[212:215], v[72:75]
	v_mfma_f32_16x16x32_bf16 v[64:67], v[154:157], v[212:215], v[64:67]
	s_setprio 0
	s_setprio 1
	v_mfma_f32_16x16x32_bf16 v[28:31], v[158:161], v[184:187], v[28:31]
	v_mfma_f32_16x16x32_bf16 v[20:23], v[166:169], v[184:187], v[20:23]
	v_mfma_f32_16x16x32_bf16 v[24:27], v[158:161], v[192:195], v[24:27]
	v_mfma_f32_16x16x32_bf16 v[16:19], v[166:169], v[192:195], v[16:19]
	v_mfma_f32_16x16x32_bf16 v[12:15], v[158:161], v[200:203], v[12:15]
	v_mfma_f32_16x16x32_bf16 v[4:7], v[166:169], v[200:203], v[4:7]
	v_mfma_f32_16x16x32_bf16 v[8:11], v[158:161], v[208:211], v[8:11]
	v_mfma_f32_16x16x32_bf16 v[0:3], v[166:169], v[208:211], v[0:3]
	s_setprio 0
	s_setprio 1
	v_mfma_f32_16x16x32_bf16 v[28:31], v[162:165], v[188:191], v[28:31]
	v_mfma_f32_16x16x32_bf16 v[20:23], v[180:183], v[188:191], v[20:23]
	v_mfma_f32_16x16x32_bf16 v[24:27], v[162:165], v[196:199], v[24:27]
	v_mfma_f32_16x16x32_bf16 v[16:19], v[180:183], v[196:199], v[16:19]
	v_mfma_f32_16x16x32_bf16 v[12:15], v[162:165], v[204:207], v[12:15]
	v_mfma_f32_16x16x32_bf16 v[4:7], v[180:183], v[204:207], v[4:7]
	v_mfma_f32_16x16x32_bf16 v[8:11], v[162:165], v[212:215], v[8:11]
	v_mfma_f32_16x16x32_bf16 v[0:3], v[180:183], v[212:215], v[0:3]
	s_setprio 0
	s_barrier
; #define G_STAGE(bufoff, gbase, voff) do { _Pragma("unroll") for (int _i = 0; _i < 2; ++_i) \
;         __builtin_amdgcn_global_load_lds((const unsigned*)((const char*)(gbase) + voff[_i]), (LAS unsigned*)(lds + (bufoff) + ldsw + _i * 8192), 16, 0, 0); } while (0)
; #define G_LDA(dst, b, h) do { _Pragma("unroll") for (int m = 0; m < 4; ++m) _Pragma("unroll") for (int k = 0; k < 2; ++k) dst[m][k] = *(const LAS bf16x8*)(lds + G_SA(b, h) + aoff + m * 2048 + k * 1024); } while (0)
; #define G_LDB(dst, b, h) do { _Pragma("unroll") for (int n = 0; n < 2; ++n) _Pragma("unroll") for (int k = 0; k < 2; ++k) dst[n][k] = *(const LAS bf16x8*)(lds + G_SB(b, h) + boff + n * 2048 + k * 1024); } while (0)
; #define G_MMA(ai, bj, At_, Bt_) do { __builtin_amdgcn_s_setprio(1); _Pragma("unroll") for (int m = 0; m < 4; ++m) _Pragma("unroll") for (int n = 0; n < 2; ++n) _Pragma("unroll") for (int k = 0; k < 2; ++k) \
;         acc[ai][bj][m][n] = __builtin_amdgcn_mfma_f32_16x16x32_bf16(Bt_[n][k], At_[m][k], acc[ai][bj][m][n], 0, 0, 0); __builtin_amdgcn_s_setprio(0); } while (0)
; #define WAIT_V(n) asm volatile("s_waitcnt vmcnt(" #n ")" ::: "memory")
; #define WAIT_L(n) asm volatile("s_waitcnt lgkmcnt(" #n ")" ::: "memory")
; #define BAR __builtin_amdgcn_s_barrier()
; #define SCHED __builtin_amdgcn_sched_barrier(0)
; template <class Get, class Epi>
; DI void gemm_loop(int ntiles, int ld, char* shm, const Get& get, const Epi& epi) {
;     ...
;             G_LDB(B0, 1, 0); G_LDB(B1, 1, 1); SCHED; G_LDA(At, 1, 0); G_STAGE(G_SA(0, 1), a2 + hstep, voffA);
;             WAIT_V(8); WAIT_L(0); BAR; G_MMA(0, 0, At, B0); G_MMA(0, 1, At, B1); BAR; SCHED;
	s_add_i32 s57, 0, 0x18000
	v_add_u32_e32 v144, s57, v172
	s_add_i32 s58, 0, 0x1c000
	ds_read_b128 v[96:99], v144
	ds_read_b128 v[108:111], v144 offset:1024
	ds_read_b128 v[150:153], v144 offset:2048
	ds_read_b128 v[154:157], v144 offset:3072
	v_add_u32_e32 v144, s58, v172
	ds_read_b128 v[158:161], v144
	ds_read_b128 v[162:165], v144 offset:1024
	ds_read_b128 v[166:169], v144 offset:2048
	ds_read_b128 v[180:183], v144 offset:3072
	s_add_u32 s14, s14, 0x40000
	s_addc_u32 s15, s15, 0
	s_mov_b32 m0, s71
	v_lshl_add_u64 v[222:223], s[14:15], 0, v[142:143]
	ds_read_b128 v[184:187], v175 offset:32768
	ds_read_b128 v[188:191], v175 offset:33792
	ds_read_b128 v[192:195], v175 offset:34816
	ds_read_b128 v[196:199], v175 offset:35840
	ds_read_b128 v[200:203], v175 offset:36864
	ds_read_b128 v[204:207], v175 offset:37888
	ds_read_b128 v[208:211], v175 offset:38912
	ds_read_b128 v[212:215], v175 offset:39936
	global_load_lds_dwordx4 v[222:223], off
	v_lshl_add_u64 v[222:223], s[14:15], 0, v[138:139]
	s_mov_b32 m0, s72
	s_nop 0
	global_load_lds_dwordx4 v[222:223], off
	s_waitcnt vmcnt(8)
	s_waitcnt lgkmcnt(0)
	s_barrier
	s_setprio 1
	s_waitcnt lgkmcnt(0)
	v_mfma_f32_16x16x32_bf16 v[132:135], v[96:99], v[184:187], v[132:135]
	v_mfma_f32_16x16x32_bf16 v[124:127], v[150:153], v[184:187], v[124:127]
	v_mfma_f32_16x16x32_bf16 v[128:131], v[96:99], v[192:195], v[128:131]
	v_mfma_f32_16x16x32_bf16 v[120:123], v[150:153], v[192:195], v[120:123]
	v_mfma_f32_16x16x32_bf16 v[116:119], v[96:99], v[200:203], v[116:119]
	v_mfma_f32_16x16x32_bf16 v[104:107], v[150:153], v[200:203], v[104:107]
	v_mfma_f32_16x16x32_bf16 v[112:115], v[96:99], v[208:211], v[112:115]
	v_mfma_f32_16x16x32_bf16 v[100:103], v[150:153], v[208:211], v[100:103]
	s_setprio 0
	s_setprio 1
	v_mfma_f32_16x16x32_bf16 v[132:135], v[108:111], v[188:191], v[132:135]
	v_mfma_f32_16x16x32_bf16 v[124:127], v[154:157], v[188:191], v[124:127]
	v_mfma_f32_16x16x32_bf16 v[128:131], v[108:111], v[196:199], v[128:131]
	v_mfma_f32_16x16x32_bf16 v[120:123], v[154:157], v[196:199], v[120:123]
	v_mfma_f32_16x16x32_bf16 v[116:119], v[108:111], v[204:207], v[116:119]
	v_mfma_f32_16x16x32_bf16 v[104:107], v[154:157], v[204:207], v[104:107]
	v_mfma_f32_16x16x32_bf16 v[112:115], v[108:111], v[212:215], v[112:115]
	v_mfma_f32_16x16x32_bf16 v[100:103], v[154:157], v[212:215], v[100:103]
	s_setprio 0
	s_setprio 1
	v_mfma_f32_16x16x32_bf16 v[60:63], v[158:161], v[184:187], v[60:63]
	v_mfma_f32_16x16x32_bf16 v[52:55], v[166:169], v[184:187], v[52:55]
	v_mfma_f32_16x16x32_bf16 v[56:59], v[158:161], v[192:195], v[56:59]
	v_mfma_f32_16x16x32_bf16 v[48:51], v[166:169], v[192:195], v[48:51]
	v_mfma_f32_16x16x32_bf16 v[44:47], v[158:161], v[200:203], v[44:47]
	v_mfma_f32_16x16x32_bf16 v[36:39], v[166:169], v[200:203], v[36:39]
	v_mfma_f32_16x16x32_bf16 v[40:43], v[158:161], v[208:211], v[40:43]
	v_mfma_f32_16x16x32_bf16 v[32:35], v[166:169], v[208:211], v[32:35]
	s_setprio 0
	s_setprio 1
	v_mfma_f32_16x16x32_bf16 v[60:63], v[162:165], v[188:191], v[60:63]
	v_mfma_f32_16x16x32_bf16 v[52:55], v[180:183], v[188:191], v[52:55]
	v_mfma_f32_16x16x32_bf16 v[56:59], v[162:165], v[196:199], v[56:59]
	v_mfma_f32_16x16x32_bf16 v[48:51], v[180:183], v[196:199], v[48:51]
	v_mfma_f32_16x16x32_bf16 v[44:47], v[162:165], v[204:207], v[44:47]
	v_mfma_f32_16x16x32_bf16 v[36:39], v[180:183], v[204:207], v[36:39]
	v_mfma_f32_16x16x32_bf16 v[40:43], v[162:165], v[212:215], v[40:43]
	v_mfma_f32_16x16x32_bf16 v[32:35], v[180:183], v[212:215], v[32:35]
	s_setprio 0
	s_barrier
; #define G_STAGE(bufoff, gbase, voff) do { _Pragma("unroll") for (int _i = 0; _i < 2; ++_i) \
;         __builtin_amdgcn_global_load_lds((const unsigned*)((const char*)(gbase) + voff[_i]), (LAS unsigned*)(lds + (bufoff) + ldsw + _i * 8192), 16, 0, 0); } while (0)
; #define G_LDA(dst, b, h) do { _Pragma("unroll") for (int m = 0; m < 4; ++m) _Pragma("unroll") for (int k = 0; k < 2; ++k) dst[m][k] = *(const LAS bf16x8*)(lds + G_SA(b, h) + aoff + m * 2048 + k * 1024); } while (0)
; #define G_MMA(ai, bj, At_, Bt_) do { __builtin_amdgcn_s_setprio(1); _Pragma("unroll") for (int m = 0; m < 4; ++m) _Pragma("unroll") for (int n = 0; n < 2; ++n) _Pragma("unroll") for (int k = 0; k < 2; ++k) \
;         acc[ai][bj][m][n] = __builtin_amdgcn_mfma_f32_16x16x32_bf16(Bt_[n][k], At_[m][k], acc[ai][bj][m][n], 0, 0, 0); __builtin_amdgcn_s_setprio(0); } while (0)
; #define WAIT_V(n) asm volatile("s_waitcnt vmcnt(" #n ")" ::: "memory")
; #define WAIT_L(n) asm volatile("s_waitcnt lgkmcnt(" #n ")" ::: "memory")
; #define BAR __builtin_amdgcn_s_barrier()
; #define SCHED __builtin_amdgcn_sched_barrier(0)
; template <class Get, class Epi>
; DI void gemm_loop(int ntiles, int ld, char* shm, const Get& get, const Epi& epi) {
;     ...
;             G_LDA(At, 1, 1); G_STAGE(G_SB(1, 0), b3, voffB); G_STAGE(G_SB(1, 1), b3 + hstep, voffB); G_STAGE(G_SA(1, 0), a3, voffA);
;             WAIT_V(8); WAIT_L(0); BAR; G_MMA(1, 0, At, B0); G_MMA(1, 1, At, B1); BAR; SCHED;
	s_add_i32 s14, s57, s46
	v_lshl_add_u64 v[170:171], v[170:171], 0, s[10:11]
	s_mov_b32 m0, s14
	ds_read_b128 v[184:187], v175 offset:49152
	ds_read_b128 v[188:191], v175 offset:50176
	ds_read_b128 v[192:195], v175 offset:51200
	ds_read_b128 v[196:199], v175 offset:52224
	ds_read_b128 v[200:203], v175 offset:53248
	ds_read_b128 v[204:207], v175 offset:54272
	ds_read_b128 v[208:211], v175 offset:55296
	ds_read_b128 v[212:215], v175 offset:56320
	global_load_lds_dwordx4 v[170:171], off
	s_add_i32 m0, s14, 0x2000
	s_add_u32 s6, s6, 0x40080
	v_lshl_add_u64 v[170:171], v[216:217], 0, s[10:11]
	s_addc_u32 s7, s7, 0
	s_add_i32 s14, s58, s46
	global_load_lds_dwordx4 v[170:171], off
	v_lshl_add_u64 v[170:171], s[6:7], 0, v[140:141]
	s_mov_b32 m0, s14
	s_nop 0
	global_load_lds_dwordx4 v[170:171], off
	v_lshl_add_u64 v[170:171], s[6:7], 0, v[136:137]
	s_add_i32 m0, s14, 0x2000
	s_nop 0
	global_load_lds_dwordx4 v[170:171], off
	v_lshl_add_u64 v[170:171], v[218:219], 0, s[10:11]
	s_mov_b32 m0, s73
	s_nop 0
	global_load_lds_dwordx4 v[170:171], off
	v_lshl_add_u64 v[170:171], v[220:221], 0, s[10:11]
	s_mov_b32 m0, s74
	s_nop 0
	global_load_lds_dwordx4 v[170:171], off
	s_waitcnt vmcnt(8)
	s_waitcnt lgkmcnt(0)
	s_barrier
	s_setprio 1
	s_waitcnt lgkmcnt(0)
	v_mfma_f32_16x16x32_bf16 v[92:95], v[96:99], v[184:187], v[92:95]
	v_mfma_f32_16x16x32_bf16 v[84:87], v[150:153], v[184:187], v[84:87]
	v_mfma_f32_16x16x32_bf16 v[88:91], v[96:99], v[192:195], v[88:91]
	v_mfma_f32_16x16x32_bf16 v[80:83], v[150:153], v[192:195], v[80:83]
	v_mfma_f32_16x16x32_bf16 v[76:79], v[96:99], v[200:203], v[76:79]
	v_mfma_f32_16x16x32_bf16 v[68:71], v[150:153], v[200:203], v[68:71]
	v_mfma_f32_16x16x32_bf16 v[72:75], v[96:99], v[208:211], v[72:75]
	v_mfma_f32_16x16x32_bf16 v[64:67], v[150:153], v[208:211], v[64:67]
	s_setprio 0
	s_setprio 1
	v_mfma_f32_16x16x32_bf16 v[92:95], v[108:111], v[188:191], v[92:95]
	v_mfma_f32_16x16x32_bf16 v[84:87], v[154:157], v[188:191], v[84:87]
	v_mfma_f32_16x16x32_bf16 v[88:91], v[108:111], v[196:199], v[88:91]
	v_mfma_f32_16x16x32_bf16 v[80:83], v[154:157], v[196:199], v[80:83]
	v_mfma_f32_16x16x32_bf16 v[76:79], v[108:111], v[204:207], v[76:79]
	v_mfma_f32_16x16x32_bf16 v[68:71], v[154:157], v[204:207], v[68:71]
	v_mfma_f32_16x16x32_bf16 v[72:75], v[108:111], v[212:215], v[72:75]
	v_mfma_f32_16x16x32_bf16 v[64:67], v[154:157], v[212:215], v[64:67]
	s_setprio 0
	s_setprio 1
	v_mfma_f32_16x16x32_bf16 v[28:31], v[158:161], v[184:187], v[28:31]
	v_mfma_f32_16x16x32_bf16 v[20:23], v[166:169], v[184:187], v[20:23]
	v_mfma_f32_16x16x32_bf16 v[24:27], v[158:161], v[192:195], v[24:27]
	v_mfma_f32_16x16x32_bf16 v[16:19], v[166:169], v[192:195], v[16:19]
	v_mfma_f32_16x16x32_bf16 v[12:15], v[158:161], v[200:203], v[12:15]
	v_mfma_f32_16x16x32_bf16 v[4:7], v[166:169], v[200:203], v[4:7]
	v_mfma_f32_16x16x32_bf16 v[8:11], v[158:161], v[208:211], v[8:11]
	v_mfma_f32_16x16x32_bf16 v[0:3], v[166:169], v[208:211], v[0:3]
	s_setprio 0
	s_setprio 1
	v_mfma_f32_16x16x32_bf16 v[28:31], v[162:165], v[188:191], v[28:31]
	v_mfma_f32_16x16x32_bf16 v[20:23], v[180:183], v[188:191], v[20:23]
	v_mfma_f32_16x16x32_bf16 v[24:27], v[162:165], v[196:199], v[24:27]
	v_mfma_f32_16x16x32_bf16 v[16:19], v[180:183], v[196:199], v[16:19]
	v_mfma_f32_16x16x32_bf16 v[12:15], v[162:165], v[204:207], v[12:15]
	v_mfma_f32_16x16x32_bf16 v[4:7], v[180:183], v[204:207], v[4:7]
	v_mfma_f32_16x16x32_bf16 v[8:11], v[162:165], v[212:215], v[8:11]
	v_mfma_f32_16x16x32_bf16 v[0:3], v[180:183], v[212:215], v[0:3]
	s_setprio 0
	s_barrier
	s_add_i32 s56, s56, 2
	s_add_u32 s4, s4, 0x100
	s_addc_u32 s5, s5, 0
	s_add_u32 s54, s54, 0x100
	s_addc_u32 s55, s55, 0
	s_cmp_gt_u32 s56, 13
	s_cbranch_scc0 .LBB0_2022

; #define G_STAGE(bufoff, gbase, voff) do { _Pragma("unroll") for (int _i = 0; _i < 2; ++_i) \
;         __builtin_amdgcn_global_load_lds((const unsigned*)((const char*)(gbase) + voff[_i]), (LAS unsigned*)(lds + (bufoff) + ldsw + _i * 8192), 16, 0, 0); } while (0)
; #define G_LDA(dst, b, h) do { _Pragma("unroll") for (int m = 0; m < 4; ++m) _Pragma("unroll") for (int k = 0; k < 2; ++k) dst[m][k] = *(const LAS bf16x8*)(lds + G_SA(b, h) + aoff + m * 2048 + k * 1024); } while (0)
; #define G_MMA(ai, bj, At_, Bt_) do { __builtin_amdgcn_s_setprio(1); _Pragma("unroll") for (int m = 0; m < 4; ++m) _Pragma("unroll") for (int n = 0; n < 2; ++n) _Pragma("unroll") for (int k = 0; k < 2; ++k) \
;         acc[ai][bj][m][n] = __builtin_amdgcn_mfma_f32_16x16x32_bf16(Bt_[n][k], At_[m][k], acc[ai][bj][m][n], 0, 0, 0); __builtin_amdgcn_s_setprio(0); } while (0)
; #define WAIT_V(n) asm volatile("s_waitcnt vmcnt(" #n ")" ::: "memory")
; #define WAIT_L(n) asm volatile("s_waitcnt lgkmcnt(" #n ")" ::: "memory")
; #define BAR __builtin_amdgcn_s_barrier()
; #define SCHED __builtin_amdgcn_sched_barrier(0)
; template <class Get, class Epi>
; DI void gemm_loop(int ntiles, int ld, char* shm, const Get& get, const Epi& epi) {
;     ...
;             WAIT_V(8); WAIT_L(0); BAR; G_MMA(0, 0, At, B0); G_MMA(0, 1, At, B1); BAR; SCHED;
;             G_LDA(At, 0, 1); G_STAGE(G_SB(0, 0), b2, voffB); G_STAGE(G_SB(0, 1), b2 + hstep, voffB); G_STAGE(G_SA(0, 0), a2, voffA);
.Lrj_2574_0:
	s_waitcnt lgkmcnt(0)
	s_barrier
	s_setprio 1
	s_waitcnt lgkmcnt(0)
	v_mfma_f32_16x16x32_bf16 v[124:127], v[128:131], v[180:183], 0
	v_mfma_f32_16x16x32_bf16 v[120:123], v[136:139], v[180:183], 0
	v_mfma_f32_16x16x32_bf16 v[116:119], v[128:131], v[188:191], 0
	v_mfma_f32_16x16x32_bf16 v[112:115], v[136:139], v[188:191], 0
	v_mfma_f32_16x16x32_bf16 v[108:111], v[128:131], v[196:199], 0
	v_mfma_f32_16x16x32_bf16 v[104:107], v[136:139], v[196:199], 0
	v_mfma_f32_16x16x32_bf16 v[100:103], v[128:131], v[204:207], 0
	v_mfma_f32_16x16x32_bf16 v[96:99], v[136:139], v[204:207], 0
	s_setprio 0
	s_setprio 1
	v_mfma_f32_16x16x32_bf16 v[124:127], v[132:135], v[184:187], v[124:127]
	v_mfma_f32_16x16x32_bf16 v[120:123], v[140:143], v[184:187], v[120:123]
	v_mfma_f32_16x16x32_bf16 v[116:119], v[132:135], v[192:195], v[116:119]
	v_mfma_f32_16x16x32_bf16 v[112:115], v[140:143], v[192:195], v[112:115]
	v_mfma_f32_16x16x32_bf16 v[108:111], v[132:135], v[200:203], v[108:111]
	v_mfma_f32_16x16x32_bf16 v[104:107], v[140:143], v[200:203], v[104:107]
	v_mfma_f32_16x16x32_bf16 v[100:103], v[132:135], v[208:211], v[100:103]
	v_mfma_f32_16x16x32_bf16 v[96:99], v[140:143], v[208:211], v[96:99]
	s_setprio 0
	s_setprio 1
	v_mfma_f32_16x16x32_bf16 v[60:63], v[158:161], v[180:183], 0
	v_mfma_f32_16x16x32_bf16 v[56:59], v[172:175], v[180:183], 0
	v_mfma_f32_16x16x32_bf16 v[52:55], v[158:161], v[188:191], 0
	v_mfma_f32_16x16x32_bf16 v[48:51], v[172:175], v[188:191], 0
	v_mfma_f32_16x16x32_bf16 v[44:47], v[158:161], v[196:199], 0
	v_mfma_f32_16x16x32_bf16 v[40:43], v[172:175], v[196:199], 0
	v_mfma_f32_16x16x32_bf16 v[36:39], v[158:161], v[204:207], 0
	v_mfma_f32_16x16x32_bf16 v[32:35], v[172:175], v[204:207], 0
	s_setprio 0
	s_setprio 1
	v_mfma_f32_16x16x32_bf16 v[60:63], v[162:165], v[184:187], v[60:63]
	v_mfma_f32_16x16x32_bf16 v[56:59], v[176:179], v[184:187], v[56:59]
	v_mfma_f32_16x16x32_bf16 v[52:55], v[162:165], v[192:195], v[52:55]
	v_mfma_f32_16x16x32_bf16 v[48:51], v[176:179], v[192:195], v[48:51]
	v_mfma_f32_16x16x32_bf16 v[44:47], v[162:165], v[200:203], v[44:47]
	v_mfma_f32_16x16x32_bf16 v[40:43], v[176:179], v[200:203], v[40:43]
	v_mfma_f32_16x16x32_bf16 v[36:39], v[162:165], v[208:211], v[36:39]
	v_mfma_f32_16x16x32_bf16 v[32:35], v[176:179], v[208:211], v[32:35]
	s_setprio 0
	s_barrier
	s_add_i32 s83, s72, s31
	v_lshl_add_u64 v[144:145], s[14:15], 0, v[148:149]
	s_mov_b32 m0, s83
	ds_read_b128 v[180:183], v171 offset:16384
	ds_read_b128 v[184:187], v171 offset:17408
	ds_read_b128 v[188:191], v171 offset:18432
	ds_read_b128 v[192:195], v171 offset:19456
	ds_read_b128 v[196:199], v171 offset:20480
	ds_read_b128 v[200:203], v171 offset:21504
	ds_read_b128 v[204:207], v171 offset:22528
	ds_read_b128 v[208:211], v171 offset:23552
	global_load_lds_dwordx4 v[144:145], off
	s_add_i32 m0, s83, 0x2000
	s_add_u32 s84, s14, 0x40000
	v_lshl_add_u64 v[166:167], s[14:15], 0, v[152:153]
	s_addc_u32 s85, s15, 0
	s_add_i32 s83, s73, s31
	global_load_lds_dwordx4 v[166:167], off
	v_lshl_add_u64 v[212:213], s[84:85], 0, v[148:149]
	s_mov_b32 m0, s83
	v_lshl_add_u64 v[214:215], s[46:47], 0, v[150:151]
	global_load_lds_dwordx4 v[212:213], off
	v_lshl_add_u64 v[212:213], s[84:85], 0, v[152:153]
	s_add_i32 m0, s83, 0x2000
	s_nop 0
	global_load_lds_dwordx4 v[212:213], off
	v_lshl_add_u64 v[212:213], s[46:47], 0, v[146:147]
	s_mov_b32 m0, s51
	s_nop 0
	global_load_lds_dwordx4 v[212:213], off
	s_mov_b32 m0, s54
	s_nop 0
	global_load_lds_dwordx4 v[214:215], off
	s_cmp_lg_u32 s100, 0
	s_cbranch_scc0 .Lrf_2574_1
	s_waitcnt vmcnt(16)
	s_branch .Lrj_2574_1

; #define G_STAGE(bufoff, gbase, voff) do { _Pragma("unroll") for (int _i = 0; _i < 2; ++_i) \
;         __builtin_amdgcn_global_load_lds((const unsigned*)((const char*)(gbase) + voff[_i]), (LAS unsigned*)(lds + (bufoff) + ldsw + _i * 8192), 16, 0, 0); } while (0)
; #define G_LDA(dst, b, h) do { _Pragma("unroll") for (int m = 0; m < 4; ++m) _Pragma("unroll") for (int k = 0; k < 2; ++k) dst[m][k] = *(const LAS bf16x8*)(lds + G_SA(b, h) + aoff + m * 2048 + k * 1024); } while (0)
; #define G_LDB(dst, b, h) do { _Pragma("unroll") for (int n = 0; n < 2; ++n) _Pragma("unroll") for (int k = 0; k < 2; ++k) dst[n][k] = *(const LAS bf16x8*)(lds + G_SB(b, h) + boff + n * 2048 + k * 1024); } while (0)
; #define G_MMA(ai, bj, At_, Bt_) do { __builtin_amdgcn_s_setprio(1); _Pragma("unroll") for (int m = 0; m < 4; ++m) _Pragma("unroll") for (int n = 0; n < 2; ++n) _Pragma("unroll") for (int k = 0; k < 2; ++k) \
;         acc[ai][bj][m][n] = __builtin_amdgcn_mfma_f32_16x16x32_bf16(Bt_[n][k], At_[m][k], acc[ai][bj][m][n], 0, 0, 0); __builtin_amdgcn_s_setprio(0); } while (0)
; #define WAIT_V(n) asm volatile("s_waitcnt vmcnt(" #n ")" ::: "memory")
; #define WAIT_L(n) asm volatile("s_waitcnt lgkmcnt(" #n ")" ::: "memory")
; #define BAR __builtin_amdgcn_s_barrier()
; #define SCHED __builtin_amdgcn_sched_barrier(0)
; template <class Get, class Epi>
; DI void gemm_loop(int ntiles, int ld, char* shm, const Get& get, const Epi& epi) {
;     ...
;             WAIT_V(8); WAIT_L(0); BAR; G_MMA(1, 0, At, B0); G_MMA(1, 1, At, B1); BAR; SCHED;
;             G_LDB(B0, 1, 0); G_LDB(B1, 1, 1); SCHED; G_LDA(At, 1, 0); G_STAGE(G_SA(0, 1), a2 + hstep, voffA);
;             WAIT_V(8); WAIT_L(0); BAR; G_MMA(0, 0, At, B0); G_MMA(0, 1, At, B1); BAR; SCHED;
.Lrj_2574_1:
	s_waitcnt lgkmcnt(0)
	s_barrier
	s_setprio 1
	s_waitcnt lgkmcnt(0)
	v_mfma_f32_16x16x32_bf16 v[92:95], v[128:131], v[180:183], 0
	v_mfma_f32_16x16x32_bf16 v[88:91], v[136:139], v[180:183], 0
	v_mfma_f32_16x16x32_bf16 v[84:87], v[128:131], v[188:191], 0
	v_mfma_f32_16x16x32_bf16 v[80:83], v[136:139], v[188:191], 0
	v_mfma_f32_16x16x32_bf16 v[76:79], v[128:131], v[196:199], 0
	v_mfma_f32_16x16x32_bf16 v[72:75], v[136:139], v[196:199], 0
	v_mfma_f32_16x16x32_bf16 v[68:71], v[128:131], v[204:207], 0
	v_mfma_f32_16x16x32_bf16 v[64:67], v[136:139], v[204:207], 0
	s_setprio 0
	s_setprio 1
	v_mfma_f32_16x16x32_bf16 v[92:95], v[132:135], v[184:187], v[92:95]
	v_mfma_f32_16x16x32_bf16 v[88:91], v[140:143], v[184:187], v[88:91]
	v_mfma_f32_16x16x32_bf16 v[84:87], v[132:135], v[192:195], v[84:87]
	v_mfma_f32_16x16x32_bf16 v[80:83], v[140:143], v[192:195], v[80:83]
	v_mfma_f32_16x16x32_bf16 v[76:79], v[132:135], v[200:203], v[76:79]
	v_mfma_f32_16x16x32_bf16 v[72:75], v[140:143], v[200:203], v[72:75]
	v_mfma_f32_16x16x32_bf16 v[68:71], v[132:135], v[208:211], v[68:71]
	v_mfma_f32_16x16x32_bf16 v[64:67], v[140:143], v[208:211], v[64:67]
	s_setprio 0
	s_setprio 1
	v_mfma_f32_16x16x32_bf16 v[28:31], v[158:161], v[180:183], 0
	v_mfma_f32_16x16x32_bf16 v[24:27], v[172:175], v[180:183], 0
	v_mfma_f32_16x16x32_bf16 v[20:23], v[158:161], v[188:191], 0
	v_mfma_f32_16x16x32_bf16 v[16:19], v[172:175], v[188:191], 0
	v_mfma_f32_16x16x32_bf16 v[12:15], v[158:161], v[196:199], 0
	v_mfma_f32_16x16x32_bf16 v[8:11], v[172:175], v[196:199], 0
	v_mfma_f32_16x16x32_bf16 v[4:7], v[158:161], v[204:207], 0
	v_mfma_f32_16x16x32_bf16 v[0:3], v[172:175], v[204:207], 0
	s_setprio 0
	s_setprio 1
	v_mfma_f32_16x16x32_bf16 v[28:31], v[162:165], v[184:187], v[28:31]
	v_mfma_f32_16x16x32_bf16 v[24:27], v[176:179], v[184:187], v[24:27]
	v_mfma_f32_16x16x32_bf16 v[20:23], v[162:165], v[192:195], v[20:23]
	v_mfma_f32_16x16x32_bf16 v[16:19], v[176:179], v[192:195], v[16:19]
	v_mfma_f32_16x16x32_bf16 v[12:15], v[162:165], v[200:203], v[12:15]
	v_mfma_f32_16x16x32_bf16 v[8:11], v[176:179], v[200:203], v[8:11]
	v_mfma_f32_16x16x32_bf16 v[4:7], v[162:165], v[208:211], v[4:7]
	v_mfma_f32_16x16x32_bf16 v[0:3], v[176:179], v[208:211], v[0:3]
	s_setprio 0
	s_barrier
	s_add_i32 s83, 0, 0x18000
	s_add_i32 s84, 0, 0x1c000
	v_add_u32_e32 v140, s83, v168
	v_add_u32_e32 v176, s84, v168
	ds_read_b128 v[128:131], v140
	ds_read_b128 v[132:135], v140 offset:1024
	ds_read_b128 v[136:139], v140 offset:2048
	ds_read_b128 v[140:143], v140 offset:3072
	ds_read_b128 v[158:161], v176
	ds_read_b128 v[162:165], v176 offset:1024
	ds_read_b128 v[172:175], v176 offset:2048
	ds_read_b128 v[176:179], v176 offset:3072
	s_add_u32 s46, s46, 0x40000
	s_addc_u32 s47, s47, 0
	s_mov_b32 m0, s55
	v_lshl_add_u64 v[216:217], s[46:47], 0, v[146:147]
	ds_read_b128 v[180:183], v171 offset:32768
	ds_read_b128 v[184:187], v171 offset:33792
	ds_read_b128 v[188:191], v171 offset:34816
	ds_read_b128 v[192:195], v171 offset:35840
	ds_read_b128 v[196:199], v171 offset:36864
	ds_read_b128 v[200:203], v171 offset:37888
	ds_read_b128 v[204:207], v171 offset:38912
	ds_read_b128 v[208:211], v171 offset:39936
	global_load_lds_dwordx4 v[216:217], off
	v_lshl_add_u64 v[216:217], s[46:47], 0, v[150:151]
	s_mov_b32 m0, s56
	s_nop 0
	global_load_lds_dwordx4 v[216:217], off
	s_waitcnt vmcnt(8)
	s_waitcnt lgkmcnt(0)
	s_barrier
	s_setprio 1
	s_waitcnt lgkmcnt(0)
	v_mfma_f32_16x16x32_bf16 v[124:127], v[128:131], v[180:183], v[124:127]
	v_mfma_f32_16x16x32_bf16 v[120:123], v[136:139], v[180:183], v[120:123]
	v_mfma_f32_16x16x32_bf16 v[116:119], v[128:131], v[188:191], v[116:119]
	v_mfma_f32_16x16x32_bf16 v[112:115], v[136:139], v[188:191], v[112:115]
	v_mfma_f32_16x16x32_bf16 v[108:111], v[128:131], v[196:199], v[108:111]
	v_mfma_f32_16x16x32_bf16 v[104:107], v[136:139], v[196:199], v[104:107]
	v_mfma_f32_16x16x32_bf16 v[100:103], v[128:131], v[204:207], v[100:103]
	v_mfma_f32_16x16x32_bf16 v[96:99], v[136:139], v[204:207], v[96:99]
	s_setprio 0
	s_setprio 1
	v_mfma_f32_16x16x32_bf16 v[124:127], v[132:135], v[184:187], v[124:127]
	v_mfma_f32_16x16x32_bf16 v[120:123], v[140:143], v[184:187], v[120:123]
	v_mfma_f32_16x16x32_bf16 v[116:119], v[132:135], v[192:195], v[116:119]
	v_mfma_f32_16x16x32_bf16 v[112:115], v[140:143], v[192:195], v[112:115]
	v_mfma_f32_16x16x32_bf16 v[108:111], v[132:135], v[200:203], v[108:111]
	v_mfma_f32_16x16x32_bf16 v[104:107], v[140:143], v[200:203], v[104:107]
	v_mfma_f32_16x16x32_bf16 v[100:103], v[132:135], v[208:211], v[100:103]
	v_mfma_f32_16x16x32_bf16 v[96:99], v[140:143], v[208:211], v[96:99]
	s_setprio 0
	s_setprio 1
	v_mfma_f32_16x16x32_bf16 v[60:63], v[158:161], v[180:183], v[60:63]
	v_mfma_f32_16x16x32_bf16 v[56:59], v[172:175], v[180:183], v[56:59]
	v_mfma_f32_16x16x32_bf16 v[52:55], v[158:161], v[188:191], v[52:55]
	v_mfma_f32_16x16x32_bf16 v[48:51], v[172:175], v[188:191], v[48:51]
	v_mfma_f32_16x16x32_bf16 v[44:47], v[158:161], v[196:199], v[44:47]
	v_mfma_f32_16x16x32_bf16 v[40:43], v[172:175], v[196:199], v[40:43]
	v_mfma_f32_16x16x32_bf16 v[36:39], v[158:161], v[204:207], v[36:39]
	v_mfma_f32_16x16x32_bf16 v[32:35], v[172:175], v[204:207], v[32:35]
	s_setprio 0
	s_setprio 1
	v_mfma_f32_16x16x32_bf16 v[60:63], v[162:165], v[184:187], v[60:63]
	v_mfma_f32_16x16x32_bf16 v[56:59], v[176:179], v[184:187], v[56:59]
	v_mfma_f32_16x16x32_bf16 v[52:55], v[162:165], v[192:195], v[52:55]
	v_mfma_f32_16x16x32_bf16 v[48:51], v[176:179], v[192:195], v[48:51]
	v_mfma_f32_16x16x32_bf16 v[44:47], v[162:165], v[200:203], v[44:47]
	v_mfma_f32_16x16x32_bf16 v[40:43], v[176:179], v[200:203], v[40:43]
	v_mfma_f32_16x16x32_bf16 v[36:39], v[162:165], v[208:211], v[36:39]
	v_mfma_f32_16x16x32_bf16 v[32:35], v[176:179], v[208:211], v[32:35]
	s_setprio 0
	s_barrier
; #define G_STAGE(bufoff, gbase, voff) do { _Pragma("unroll") for (int _i = 0; _i < 2; ++_i) \
;         __builtin_amdgcn_global_load_lds((const unsigned*)((const char*)(gbase) + voff[_i]), (LAS unsigned*)(lds + (bufoff) + ldsw + _i * 8192), 16, 0, 0); } while (0)
; #define G_LDA(dst, b, h) do { _Pragma("unroll") for (int m = 0; m < 4; ++m) _Pragma("unroll") for (int k = 0; k < 2; ++k) dst[m][k] = *(const LAS bf16x8*)(lds + G_SA(b, h) + aoff + m * 2048 + k * 1024); } while (0)
; #define G_LDB(dst, b, h) do { _Pragma("unroll") for (int n = 0; n < 2; ++n) _Pragma("unroll") for (int k = 0; k < 2; ++k) dst[n][k] = *(const LAS bf16x8*)(lds + G_SB(b, h) + boff + n * 2048 + k * 1024); } while (0)
; #define G_MMA(ai, bj, At_, Bt_) do { __builtin_amdgcn_s_setprio(1); _Pragma("unroll") for (int m = 0; m < 4; ++m) _Pragma("unroll") for (int n = 0; n < 2; ++n) _Pragma("unroll") for (int k = 0; k < 2; ++k) \
;         acc[ai][bj][m][n] = __builtin_amdgcn_mfma_f32_16x16x32_bf16(Bt_[n][k], At_[m][k], acc[ai][bj][m][n], 0, 0, 0); __builtin_amdgcn_s_setprio(0); } while (0)
; #define WAIT_V(n) asm volatile("s_waitcnt vmcnt(" #n ")" ::: "memory")
; #define WAIT_L(n) asm volatile("s_waitcnt lgkmcnt(" #n ")" ::: "memory")
; #define BAR __builtin_amdgcn_s_barrier()
; #define SCHED __builtin_amdgcn_sched_barrier(0)
; template <class Get, class Epi>
; DI void gemm_loop(int ntiles, int ld, char* shm, const Get& get, const Epi& epi) {
;     ...
;             G_LDB(B0, 0, 0); G_LDB(B1, 0, 1); SCHED; G_LDA(At, 0, 0); G_STAGE(G_SA(1, 1), a1 + hstep, voffA);
;             WAIT_V(8); WAIT_L(0); BAR; G_MMA(0, 0, At, B0); G_MMA(0, 1, At, B1); BAR; SCHED;
;     ...
;             G_LDA(At, 1, 1); G_STAGE(G_SB(1, 0), b3, voffB); G_STAGE(G_SB(1, 1), b3 + hstep, voffB); G_STAGE(G_SA(1, 0), a3, voffA);
;             WAIT_V(8); WAIT_L(0); BAR; G_MMA(1, 0, At, B0); G_MMA(1, 1, At, B1); BAR; SCHED;
	s_add_i32 s46, s83, s31
	v_lshl_add_u64 v[144:145], v[144:145], 0, s[8:9]
	s_mov_b32 m0, s46
	ds_read_b128 v[180:183], v171 offset:49152
	ds_read_b128 v[184:187], v171 offset:50176
	ds_read_b128 v[188:191], v171 offset:51200
	ds_read_b128 v[192:195], v171 offset:52224
	ds_read_b128 v[196:199], v171 offset:53248
	ds_read_b128 v[200:203], v171 offset:54272
	ds_read_b128 v[204:207], v171 offset:55296
	ds_read_b128 v[208:211], v171 offset:56320
	global_load_lds_dwordx4 v[144:145], off
	s_add_i32 m0, s46, 0x2000
	s_add_u32 s14, s14, 0x40080
	v_lshl_add_u64 v[144:145], v[166:167], 0, s[8:9]
	s_addc_u32 s15, s15, 0
	s_add_i32 s46, s84, s31
	global_load_lds_dwordx4 v[144:145], off
	v_lshl_add_u64 v[144:145], s[14:15], 0, v[148:149]
	s_mov_b32 m0, s46
	s_nop 0
	global_load_lds_dwordx4 v[144:145], off
	v_lshl_add_u64 v[144:145], s[14:15], 0, v[152:153]
	s_add_i32 m0, s46, 0x2000
	s_nop 0
	global_load_lds_dwordx4 v[144:145], off
	v_lshl_add_u64 v[144:145], v[212:213], 0, s[8:9]
	s_mov_b32 m0, s59
	s_nop 0
	global_load_lds_dwordx4 v[144:145], off
	v_lshl_add_u64 v[144:145], v[214:215], 0, s[8:9]
	s_mov_b32 m0, s71
	s_nop 0
	global_load_lds_dwordx4 v[144:145], off
	s_waitcnt vmcnt(8)
	s_waitcnt lgkmcnt(0)
	s_barrier
	s_setprio 1
	s_waitcnt lgkmcnt(0)
	v_mfma_f32_16x16x32_bf16 v[92:95], v[128:131], v[180:183], v[92:95]
	v_mfma_f32_16x16x32_bf16 v[88:91], v[136:139], v[180:183], v[88:91]
	v_mfma_f32_16x16x32_bf16 v[84:87], v[128:131], v[188:191], v[84:87]
	v_mfma_f32_16x16x32_bf16 v[80:83], v[136:139], v[188:191], v[80:83]
	v_mfma_f32_16x16x32_bf16 v[76:79], v[128:131], v[196:199], v[76:79]
	v_mfma_f32_16x16x32_bf16 v[72:75], v[136:139], v[196:199], v[72:75]
	v_mfma_f32_16x16x32_bf16 v[68:71], v[128:131], v[204:207], v[68:71]
	v_mfma_f32_16x16x32_bf16 v[64:67], v[136:139], v[204:207], v[64:67]
	s_setprio 0
	s_setprio 1
	v_mfma_f32_16x16x32_bf16 v[92:95], v[132:135], v[184:187], v[92:95]
	v_mfma_f32_16x16x32_bf16 v[88:91], v[140:143], v[184:187], v[88:91]
	v_mfma_f32_16x16x32_bf16 v[84:87], v[132:135], v[192:195], v[84:87]
	v_mfma_f32_16x16x32_bf16 v[80:83], v[140:143], v[192:195], v[80:83]
	v_mfma_f32_16x16x32_bf16 v[76:79], v[132:135], v[200:203], v[76:79]
	v_mfma_f32_16x16x32_bf16 v[72:75], v[140:143], v[200:203], v[72:75]
	v_mfma_f32_16x16x32_bf16 v[68:71], v[132:135], v[208:211], v[68:71]
	v_mfma_f32_16x16x32_bf16 v[64:67], v[140:143], v[208:211], v[64:67]
	s_setprio 0
	s_setprio 1
	v_mfma_f32_16x16x32_bf16 v[28:31], v[158:161], v[180:183], v[28:31]
	v_mfma_f32_16x16x32_bf16 v[24:27], v[172:175], v[180:183], v[24:27]
	v_mfma_f32_16x16x32_bf16 v[20:23], v[158:161], v[188:191], v[20:23]
	v_mfma_f32_16x16x32_bf16 v[16:19], v[172:175], v[188:191], v[16:19]
	v_mfma_f32_16x16x32_bf16 v[12:15], v[158:161], v[196:199], v[12:15]
	v_mfma_f32_16x16x32_bf16 v[8:11], v[172:175], v[196:199], v[8:11]
	v_mfma_f32_16x16x32_bf16 v[4:7], v[158:161], v[204:207], v[4:7]
	v_mfma_f32_16x16x32_bf16 v[0:3], v[172:175], v[204:207], v[0:3]
	s_setprio 0
	s_setprio 1
	v_mfma_f32_16x16x32_bf16 v[28:31], v[162:165], v[184:187], v[28:31]
	v_mfma_f32_16x16x32_bf16 v[24:27], v[176:179], v[184:187], v[24:27]
	v_mfma_f32_16x16x32_bf16 v[20:23], v[162:165], v[192:195], v[20:23]
	v_mfma_f32_16x16x32_bf16 v[16:19], v[176:179], v[192:195], v[16:19]
	v_mfma_f32_16x16x32_bf16 v[12:15], v[162:165], v[200:203], v[12:15]
	v_mfma_f32_16x16x32_bf16 v[8:11], v[176:179], v[200:203], v[8:11]
	v_mfma_f32_16x16x32_bf16 v[4:7], v[162:165], v[208:211], v[4:7]
	v_mfma_f32_16x16x32_bf16 v[0:3], v[176:179], v[208:211], v[0:3]
	s_setprio 0
	s_barrier
	s_add_u32 s52, s52, 0x100
	s_addc_u32 s53, s53, 0
	s_add_u32 s80, s80, 0x100
	s_addc_u32 s81, s81, 0
	s_cmp_ge_u32 s82, s78
	s_mov_b32 s14, s82
	s_cbranch_scc0 .LBB0_2574
	s_branch .Lpost_2574
.LBB0_2574:
	ds_read_b128 v[128:131], v169
	ds_read_b128 v[132:135], v169 offset:1024
	ds_read_b128 v[136:139], v169 offset:2048
	ds_read_b128 v[140:143], v169 offset:3072
	ds_read_b128 v[158:161], v170
	ds_read_b128 v[162:165], v170 offset:1024
	ds_read_b128 v[172:175], v170 offset:2048
	ds_read_b128 v[176:179], v170 offset:3072
	s_add_i32 s82, s14, 2
	s_add_u32 s15, s52, 0xfffc0080
	s_addc_u32 s46, s53, -1
	s_cmp_eq_u32 s79, s14
	s_cselect_b32 s14, s77, s80
	s_cselect_b32 s47, s3, s46
	s_cselect_b32 s46, s41, s15
	s_cselect_b32 s15, s43, s81
	v_lshl_add_u64 v[144:145], s[52:53], 0, v[154:155]
	s_add_i32 m0, s51, 0xc000
	ds_read_b128 v[180:183], v171
	ds_read_b128 v[184:187], v171 offset:1024
	ds_read_b128 v[188:191], v171 offset:2048
	ds_read_b128 v[192:195], v171 offset:3072
	ds_read_b128 v[196:199], v171 offset:4096
	ds_read_b128 v[200:203], v171 offset:5120
	ds_read_b128 v[204:207], v171 offset:6144
	ds_read_b128 v[208:211], v171 offset:7168
	global_load_lds_dwordx4 v[144:145], off
	v_lshl_add_u64 v[144:145], s[52:53], 0, v[156:157]
	s_add_i32 m0, s51, 0xe000
	s_nop 0
	global_load_lds_dwordx4 v[144:145], off
	s_waitcnt vmcnt(8)
	s_waitcnt lgkmcnt(0)
	s_barrier
; #define G_STAGE(bufoff, gbase, voff) do { _Pragma("unroll") for (int _i = 0; _i < 2; ++_i) \
;         __builtin_amdgcn_global_load_lds((const unsigned*)((const char*)(gbase) + voff[_i]), (LAS unsigned*)(lds + (bufoff) + ldsw + _i * 8192), 16, 0, 0); } while (0)
; #define G_LDA(dst, b, h) do { _Pragma("unroll") for (int m = 0; m < 4; ++m) _Pragma("unroll") for (int k = 0; k < 2; ++k) dst[m][k] = *(const LAS bf16x8*)(lds + G_SA(b, h) + aoff + m * 2048 + k * 1024); } while (0)
; #define G_MMA(ai, bj, At_, Bt_) do { __builtin_amdgcn_s_setprio(1); _Pragma("unroll") for (int m = 0; m < 4; ++m) _Pragma("unroll") for (int n = 0; n < 2; ++n) _Pragma("unroll") for (int k = 0; k < 2; ++k) \
;         acc[ai][bj][m][n] = __builtin_amdgcn_mfma_f32_16x16x32_bf16(Bt_[n][k], At_[m][k], acc[ai][bj][m][n], 0, 0, 0); __builtin_amdgcn_s_setprio(0); } while (0)
; #define WAIT_V(n) asm volatile("s_waitcnt vmcnt(" #n ")" ::: "memory")
; #define WAIT_L(n) asm volatile("s_waitcnt lgkmcnt(" #n ")" ::: "memory")
; #define BAR __builtin_amdgcn_s_barrier()
; #define SCHED __builtin_amdgcn_sched_barrier(0)
; template <class Get, class Epi>
; DI void gemm_loop(int ntiles, int ld, char* shm, const Get& get, const Epi& epi) {
;     ...
;             WAIT_V(8); WAIT_L(0); BAR; G_MMA(0, 0, At, B0); G_MMA(0, 1, At, B1); BAR; SCHED;
;             G_LDA(At, 0, 1); G_STAGE(G_SB(0, 0), b2, voffB); G_STAGE(G_SB(0, 1), b2 + hstep, voffB); G_STAGE(G_SA(0, 0), a2, voffA);
;             WAIT_V(8); WAIT_L(0); BAR; G_MMA(1, 0, At, B0); G_MMA(1, 1, At, B1); BAR; SCHED;
	s_setprio 1
	s_waitcnt lgkmcnt(0)
	v_mfma_f32_16x16x32_bf16 v[124:127], v[128:131], v[180:183], v[124:127]
	v_mfma_f32_16x16x32_bf16 v[120:123], v[136:139], v[180:183], v[120:123]
	v_mfma_f32_16x16x32_bf16 v[116:119], v[128:131], v[188:191], v[116:119]
	v_mfma_f32_16x16x32_bf16 v[112:115], v[136:139], v[188:191], v[112:115]
	v_mfma_f32_16x16x32_bf16 v[108:111], v[128:131], v[196:199], v[108:111]
	v_mfma_f32_16x16x32_bf16 v[104:107], v[136:139], v[196:199], v[104:107]
	v_mfma_f32_16x16x32_bf16 v[100:103], v[128:131], v[204:207], v[100:103]
	v_mfma_f32_16x16x32_bf16 v[96:99], v[136:139], v[204:207], v[96:99]
	s_setprio 0
	s_setprio 1
	v_mfma_f32_16x16x32_bf16 v[124:127], v[132:135], v[184:187], v[124:127]
	v_mfma_f32_16x16x32_bf16 v[120:123], v[140:143], v[184:187], v[120:123]
	v_mfma_f32_16x16x32_bf16 v[116:119], v[132:135], v[192:195], v[116:119]
	v_mfma_f32_16x16x32_bf16 v[112:115], v[140:143], v[192:195], v[112:115]
	v_mfma_f32_16x16x32_bf16 v[108:111], v[132:135], v[200:203], v[108:111]
	v_mfma_f32_16x16x32_bf16 v[104:107], v[140:143], v[200:203], v[104:107]
	v_mfma_f32_16x16x32_bf16 v[100:103], v[132:135], v[208:211], v[100:103]
	v_mfma_f32_16x16x32_bf16 v[96:99], v[140:143], v[208:211], v[96:99]
	s_setprio 0
	s_setprio 1
	v_mfma_f32_16x16x32_bf16 v[60:63], v[158:161], v[180:183], v[60:63]
	v_mfma_f32_16x16x32_bf16 v[56:59], v[172:175], v[180:183], v[56:59]
	v_mfma_f32_16x16x32_bf16 v[52:55], v[158:161], v[188:191], v[52:55]
	v_mfma_f32_16x16x32_bf16 v[48:51], v[172:175], v[188:191], v[48:51]
	v_mfma_f32_16x16x32_bf16 v[44:47], v[158:161], v[196:199], v[44:47]
	v_mfma_f32_16x16x32_bf16 v[40:43], v[172:175], v[196:199], v[40:43]
	v_mfma_f32_16x16x32_bf16 v[36:39], v[158:161], v[204:207], v[36:39]
	v_mfma_f32_16x16x32_bf16 v[32:35], v[172:175], v[204:207], v[32:35]
	s_setprio 0
	s_setprio 1
	v_mfma_f32_16x16x32_bf16 v[60:63], v[162:165], v[184:187], v[60:63]
	v_mfma_f32_16x16x32_bf16 v[56:59], v[176:179], v[184:187], v[56:59]
	v_mfma_f32_16x16x32_bf16 v[52:55], v[162:165], v[192:195], v[52:55]
	v_mfma_f32_16x16x32_bf16 v[48:51], v[176:179], v[192:195], v[48:51]
	v_mfma_f32_16x16x32_bf16 v[44:47], v[162:165], v[200:203], v[44:47]
	v_mfma_f32_16x16x32_bf16 v[40:43], v[176:179], v[200:203], v[40:43]
	v_mfma_f32_16x16x32_bf16 v[36:39], v[162:165], v[208:211], v[36:39]
	v_mfma_f32_16x16x32_bf16 v[32:35], v[176:179], v[208:211], v[32:35]
	s_setprio 0
	s_barrier
	s_add_i32 s83, s72, s31
	v_lshl_add_u64 v[144:145], s[14:15], 0, v[148:149]
	s_mov_b32 m0, s83
	ds_read_b128 v[180:183], v171 offset:16384
	ds_read_b128 v[184:187], v171 offset:17408
	ds_read_b128 v[188:191], v171 offset:18432
	ds_read_b128 v[192:195], v171 offset:19456
	ds_read_b128 v[196:199], v171 offset:20480
	ds_read_b128 v[200:203], v171 offset:21504
	ds_read_b128 v[204:207], v171 offset:22528
	ds_read_b128 v[208:211], v171 offset:23552
	global_load_lds_dwordx4 v[144:145], off
	s_add_i32 m0, s83, 0x2000
	s_add_u32 s84, s14, 0x40000
	v_lshl_add_u64 v[166:167], s[14:15], 0, v[152:153]
	s_addc_u32 s85, s15, 0
	s_add_i32 s83, s73, s31
	global_load_lds_dwordx4 v[166:167], off
	v_lshl_add_u64 v[212:213], s[84:85], 0, v[148:149]
	s_mov_b32 m0, s83
	v_lshl_add_u64 v[214:215], s[46:47], 0, v[150:151]
	global_load_lds_dwordx4 v[212:213], off
	v_lshl_add_u64 v[212:213], s[84:85], 0, v[152:153]
	s_add_i32 m0, s83, 0x2000
	s_nop 0
	global_load_lds_dwordx4 v[212:213], off
	v_lshl_add_u64 v[212:213], s[46:47], 0, v[146:147]
	s_mov_b32 m0, s51
	s_nop 0
	global_load_lds_dwordx4 v[212:213], off
	s_mov_b32 m0, s54
	s_nop 0
	global_load_lds_dwordx4 v[214:215], off
	s_waitcnt vmcnt(8)
	s_waitcnt lgkmcnt(0)
	s_barrier
	s_setprio 1
	s_waitcnt lgkmcnt(0)
	v_mfma_f32_16x16x32_bf16 v[92:95], v[128:131], v[180:183], v[92:95]
	v_mfma_f32_16x16x32_bf16 v[88:91], v[136:139], v[180:183], v[88:91]
	v_mfma_f32_16x16x32_bf16 v[84:87], v[128:131], v[188:191], v[84:87]
	v_mfma_f32_16x16x32_bf16 v[80:83], v[136:139], v[188:191], v[80:83]
	v_mfma_f32_16x16x32_bf16 v[76:79], v[128:131], v[196:199], v[76:79]
	v_mfma_f32_16x16x32_bf16 v[72:75], v[136:139], v[196:199], v[72:75]
	v_mfma_f32_16x16x32_bf16 v[68:71], v[128:131], v[204:207], v[68:71]
	v_mfma_f32_16x16x32_bf16 v[64:67], v[136:139], v[204:207], v[64:67]
	s_setprio 0
	s_setprio 1
	v_mfma_f32_16x16x32_bf16 v[92:95], v[132:135], v[184:187], v[92:95]
	v_mfma_f32_16x16x32_bf16 v[88:91], v[140:143], v[184:187], v[88:91]
	v_mfma_f32_16x16x32_bf16 v[84:87], v[132:135], v[192:195], v[84:87]
	v_mfma_f32_16x16x32_bf16 v[80:83], v[140:143], v[192:195], v[80:83]
	v_mfma_f32_16x16x32_bf16 v[76:79], v[132:135], v[200:203], v[76:79]
	v_mfma_f32_16x16x32_bf16 v[72:75], v[140:143], v[200:203], v[72:75]
	v_mfma_f32_16x16x32_bf16 v[68:71], v[132:135], v[208:211], v[68:71]
	v_mfma_f32_16x16x32_bf16 v[64:67], v[140:143], v[208:211], v[64:67]
	s_setprio 0
	s_setprio 1
	v_mfma_f32_16x16x32_bf16 v[28:31], v[158:161], v[180:183], v[28:31]
	v_mfma_f32_16x16x32_bf16 v[24:27], v[172:175], v[180:183], v[24:27]
	v_mfma_f32_16x16x32_bf16 v[20:23], v[158:161], v[188:191], v[20:23]
	v_mfma_f32_16x16x32_bf16 v[16:19], v[172:175], v[188:191], v[16:19]
	v_mfma_f32_16x16x32_bf16 v[12:15], v[158:161], v[196:199], v[12:15]
	v_mfma_f32_16x16x32_bf16 v[8:11], v[172:175], v[196:199], v[8:11]
	v_mfma_f32_16x16x32_bf16 v[4:7], v[158:161], v[204:207], v[4:7]
	v_mfma_f32_16x16x32_bf16 v[0:3], v[172:175], v[204:207], v[0:3]
	s_setprio 0
	s_setprio 1
	v_mfma_f32_16x16x32_bf16 v[28:31], v[162:165], v[184:187], v[28:31]
	v_mfma_f32_16x16x32_bf16 v[24:27], v[176:179], v[184:187], v[24:27]
	v_mfma_f32_16x16x32_bf16 v[20:23], v[162:165], v[192:195], v[20:23]
	v_mfma_f32_16x16x32_bf16 v[16:19], v[176:179], v[192:195], v[16:19]
	v_mfma_f32_16x16x32_bf16 v[12:15], v[162:165], v[200:203], v[12:15]
	v_mfma_f32_16x16x32_bf16 v[8:11], v[176:179], v[200:203], v[8:11]
	v_mfma_f32_16x16x32_bf16 v[4:7], v[162:165], v[208:211], v[4:7]
	v_mfma_f32_16x16x32_bf16 v[0:3], v[176:179], v[208:211], v[0:3]
	s_setprio 0
	s_barrier
; #define G_STAGE(bufoff, gbase, voff) do { _Pragma("unroll") for (int _i = 0; _i < 2; ++_i) \
;         __builtin_amdgcn_global_load_lds((const unsigned*)((const char*)(gbase) + voff[_i]), (LAS unsigned*)(lds + (bufoff) + ldsw + _i * 8192), 16, 0, 0); } while (0)
; #define G_LDA(dst, b, h) do { _Pragma("unroll") for (int m = 0; m < 4; ++m) _Pragma("unroll") for (int k = 0; k < 2; ++k) dst[m][k] = *(const LAS bf16x8*)(lds + G_SA(b, h) + aoff + m * 2048 + k * 1024); } while (0)
; #define G_LDB(dst, b, h) do { _Pragma("unroll") for (int n = 0; n < 2; ++n) _Pragma("unroll") for (int k = 0; k < 2; ++k) dst[n][k] = *(const LAS bf16x8*)(lds + G_SB(b, h) + boff + n * 2048 + k * 1024); } while (0)
; #define G_MMA(ai, bj, At_, Bt_) do { __builtin_amdgcn_s_setprio(1); _Pragma("unroll") for (int m = 0; m < 4; ++m) _Pragma("unroll") for (int n = 0; n < 2; ++n) _Pragma("unroll") for (int k = 0; k < 2; ++k) \
;         acc[ai][bj][m][n] = __builtin_amdgcn_mfma_f32_16x16x32_bf16(Bt_[n][k], At_[m][k], acc[ai][bj][m][n], 0, 0, 0); __builtin_amdgcn_s_setprio(0); } while (0)
; #define WAIT_V(n) asm volatile("s_waitcnt vmcnt(" #n ")" ::: "memory")
; #define WAIT_L(n) asm volatile("s_waitcnt lgkmcnt(" #n ")" ::: "memory")
; #define BAR __builtin_amdgcn_s_barrier()
; #define SCHED __builtin_amdgcn_sched_barrier(0)
; template <class Get, class Epi>
; DI void gemm_loop(int ntiles, int ld, char* shm, const Get& get, const Epi& epi) {
;     ...
;             G_LDB(B0, 1, 0); G_LDB(B1, 1, 1); SCHED; G_LDA(At, 1, 0); G_STAGE(G_SA(0, 1), a2 + hstep, voffA);
;             WAIT_V(8); WAIT_L(0); BAR; G_MMA(0, 0, At, B0); G_MMA(0, 1, At, B1); BAR; SCHED;
	s_add_i32 s83, 0, 0x18000
	s_add_i32 s84, 0, 0x1c000
	v_add_u32_e32 v140, s83, v168
	v_add_u32_e32 v176, s84, v168
	ds_read_b128 v[128:131], v140
	ds_read_b128 v[132:135], v140 offset:1024
	ds_read_b128 v[136:139], v140 offset:2048
	ds_read_b128 v[140:143], v140 offset:3072
	ds_read_b128 v[158:161], v176
	ds_read_b128 v[162:165], v176 offset:1024
	ds_read_b128 v[172:175], v176 offset:2048
	ds_read_b128 v[176:179], v176 offset:3072
	s_add_u32 s46, s46, 0x40000
	s_addc_u32 s47, s47, 0
	s_mov_b32 m0, s55
	v_lshl_add_u64 v[216:217], s[46:47], 0, v[146:147]
	ds_read_b128 v[180:183], v171 offset:32768
	ds_read_b128 v[184:187], v171 offset:33792
	ds_read_b128 v[188:191], v171 offset:34816
	ds_read_b128 v[192:195], v171 offset:35840
	ds_read_b128 v[196:199], v171 offset:36864
	ds_read_b128 v[200:203], v171 offset:37888
	ds_read_b128 v[204:207], v171 offset:38912
	ds_read_b128 v[208:211], v171 offset:39936
	global_load_lds_dwordx4 v[216:217], off
	v_lshl_add_u64 v[216:217], s[46:47], 0, v[150:151]
	s_mov_b32 m0, s56
	s_nop 0
	global_load_lds_dwordx4 v[216:217], off
	s_waitcnt vmcnt(8)
	s_waitcnt lgkmcnt(0)
	s_barrier
	s_setprio 1
	s_waitcnt lgkmcnt(0)
	v_mfma_f32_16x16x32_bf16 v[124:127], v[128:131], v[180:183], v[124:127]
	v_mfma_f32_16x16x32_bf16 v[120:123], v[136:139], v[180:183], v[120:123]
	v_mfma_f32_16x16x32_bf16 v[116:119], v[128:131], v[188:191], v[116:119]
	v_mfma_f32_16x16x32_bf16 v[112:115], v[136:139], v[188:191], v[112:115]
	v_mfma_f32_16x16x32_bf16 v[108:111], v[128:131], v[196:199], v[108:111]
	v_mfma_f32_16x16x32_bf16 v[104:107], v[136:139], v[196:199], v[104:107]
	v_mfma_f32_16x16x32_bf16 v[100:103], v[128:131], v[204:207], v[100:103]
	v_mfma_f32_16x16x32_bf16 v[96:99], v[136:139], v[204:207], v[96:99]
	s_setprio 0
	s_setprio 1
	v_mfma_f32_16x16x32_bf16 v[124:127], v[132:135], v[184:187], v[124:127]
	v_mfma_f32_16x16x32_bf16 v[120:123], v[140:143], v[184:187], v[120:123]
	v_mfma_f32_16x16x32_bf16 v[116:119], v[132:135], v[192:195], v[116:119]
	v_mfma_f32_16x16x32_bf16 v[112:115], v[140:143], v[192:195], v[112:115]
	v_mfma_f32_16x16x32_bf16 v[108:111], v[132:135], v[200:203], v[108:111]
	v_mfma_f32_16x16x32_bf16 v[104:107], v[140:143], v[200:203], v[104:107]
	v_mfma_f32_16x16x32_bf16 v[100:103], v[132:135], v[208:211], v[100:103]
	v_mfma_f32_16x16x32_bf16 v[96:99], v[140:143], v[208:211], v[96:99]
	s_setprio 0
	s_setprio 1
	v_mfma_f32_16x16x32_bf16 v[60:63], v[158:161], v[180:183], v[60:63]
	v_mfma_f32_16x16x32_bf16 v[56:59], v[172:175], v[180:183], v[56:59]
	v_mfma_f32_16x16x32_bf16 v[52:55], v[158:161], v[188:191], v[52:55]
	v_mfma_f32_16x16x32_bf16 v[48:51], v[172:175], v[188:191], v[48:51]
	v_mfma_f32_16x16x32_bf16 v[44:47], v[158:161], v[196:199], v[44:47]
	v_mfma_f32_16x16x32_bf16 v[40:43], v[172:175], v[196:199], v[40:43]
	v_mfma_f32_16x16x32_bf16 v[36:39], v[158:161], v[204:207], v[36:39]
	v_mfma_f32_16x16x32_bf16 v[32:35], v[172:175], v[204:207], v[32:35]
	s_setprio 0
	s_setprio 1
	v_mfma_f32_16x16x32_bf16 v[60:63], v[162:165], v[184:187], v[60:63]
	v_mfma_f32_16x16x32_bf16 v[56:59], v[176:179], v[184:187], v[56:59]
	v_mfma_f32_16x16x32_bf16 v[52:55], v[162:165], v[192:195], v[52:55]
	v_mfma_f32_16x16x32_bf16 v[48:51], v[176:179], v[192:195], v[48:51]
	v_mfma_f32_16x16x32_bf16 v[44:47], v[162:165], v[200:203], v[44:47]
	v_mfma_f32_16x16x32_bf16 v[40:43], v[176:179], v[200:203], v[40:43]
	v_mfma_f32_16x16x32_bf16 v[36:39], v[162:165], v[208:211], v[36:39]
	v_mfma_f32_16x16x32_bf16 v[32:35], v[176:179], v[208:211], v[32:35]
	s_setprio 0
	s_barrier
; #define G_STAGE(bufoff, gbase, voff) do { _Pragma("unroll") for (int _i = 0; _i < 2; ++_i) \
;         __builtin_amdgcn_global_load_lds((const unsigned*)((const char*)(gbase) + voff[_i]), (LAS unsigned*)(lds + (bufoff) + ldsw + _i * 8192), 16, 0, 0); } while (0)
; #define G_LDA(dst, b, h) do { _Pragma("unroll") for (int m = 0; m < 4; ++m) _Pragma("unroll") for (int k = 0; k < 2; ++k) dst[m][k] = *(const LAS bf16x8*)(lds + G_SA(b, h) + aoff + m * 2048 + k * 1024); } while (0)
; #define G_MMA(ai, bj, At_, Bt_) do { __builtin_amdgcn_s_setprio(1); _Pragma("unroll") for (int m = 0; m < 4; ++m) _Pragma("unroll") for (int n = 0; n < 2; ++n) _Pragma("unroll") for (int k = 0; k < 2; ++k) \
;         acc[ai][bj][m][n] = __builtin_amdgcn_mfma_f32_16x16x32_bf16(Bt_[n][k], At_[m][k], acc[ai][bj][m][n], 0, 0, 0); __builtin_amdgcn_s_setprio(0); } while (0)
; #define WAIT_V(n) asm volatile("s_waitcnt vmcnt(" #n ")" ::: "memory")
; #define WAIT_L(n) asm volatile("s_waitcnt lgkmcnt(" #n ")" ::: "memory")
; #define BAR __builtin_amdgcn_s_barrier()
; #define SCHED __builtin_amdgcn_sched_barrier(0)
; template <class Get, class Epi>
; DI void gemm_loop(int ntiles, int ld, char* shm, const Get& get, const Epi& epi) {
;     ...
;             G_LDA(At, 1, 1); G_STAGE(G_SB(1, 0), b3, voffB); G_STAGE(G_SB(1, 1), b3 + hstep, voffB); G_STAGE(G_SA(1, 0), a3, voffA);
;             WAIT_V(8); WAIT_L(0); BAR; G_MMA(1, 0, At, B0); G_MMA(1, 1, At, B1); BAR; SCHED;
	s_add_i32 s46, s83, s31
	v_lshl_add_u64 v[144:145], v[144:145], 0, s[8:9]
	s_mov_b32 m0, s46
	ds_read_b128 v[180:183], v171 offset:49152
	ds_read_b128 v[184:187], v171 offset:50176
	ds_read_b128 v[188:191], v171 offset:51200
	ds_read_b128 v[192:195], v171 offset:52224
	ds_read_b128 v[196:199], v171 offset:53248
	ds_read_b128 v[200:203], v171 offset:54272
	ds_read_b128 v[204:207], v171 offset:55296
	ds_read_b128 v[208:211], v171 offset:56320
	global_load_lds_dwordx4 v[144:145], off
	s_add_i32 m0, s46, 0x2000
	s_add_u32 s14, s14, 0x40080
	v_lshl_add_u64 v[144:145], v[166:167], 0, s[8:9]
	s_addc_u32 s15, s15, 0
	s_add_i32 s46, s84, s31
	global_load_lds_dwordx4 v[144:145], off
	v_lshl_add_u64 v[144:145], s[14:15], 0, v[148:149]
	s_mov_b32 m0, s46
	s_nop 0
	global_load_lds_dwordx4 v[144:145], off
	v_lshl_add_u64 v[144:145], s[14:15], 0, v[152:153]
	s_add_i32 m0, s46, 0x2000
	s_nop 0
	global_load_lds_dwordx4 v[144:145], off
	v_lshl_add_u64 v[144:145], v[212:213], 0, s[8:9]
	s_mov_b32 m0, s59
	s_nop 0
	global_load_lds_dwordx4 v[144:145], off
	v_lshl_add_u64 v[144:145], v[214:215], 0, s[8:9]
	s_mov_b32 m0, s71
	s_nop 0
	global_load_lds_dwordx4 v[144:145], off
	s_waitcnt vmcnt(8)
	s_waitcnt lgkmcnt(0)
	s_barrier
	s_setprio 1
	s_waitcnt lgkmcnt(0)
	v_mfma_f32_16x16x32_bf16 v[92:95], v[128:131], v[180:183], v[92:95]
	v_mfma_f32_16x16x32_bf16 v[88:91], v[136:139], v[180:183], v[88:91]
	v_mfma_f32_16x16x32_bf16 v[84:87], v[128:131], v[188:191], v[84:87]
	v_mfma_f32_16x16x32_bf16 v[80:83], v[136:139], v[188:191], v[80:83]
	v_mfma_f32_16x16x32_bf16 v[76:79], v[128:131], v[196:199], v[76:79]
	v_mfma_f32_16x16x32_bf16 v[72:75], v[136:139], v[196:199], v[72:75]
	v_mfma_f32_16x16x32_bf16 v[68:71], v[128:131], v[204:207], v[68:71]
	v_mfma_f32_16x16x32_bf16 v[64:67], v[136:139], v[204:207], v[64:67]
	s_setprio 0
	s_setprio 1
	v_mfma_f32_16x16x32_bf16 v[92:95], v[132:135], v[184:187], v[92:95]
	v_mfma_f32_16x16x32_bf16 v[88:91], v[140:143], v[184:187], v[88:91]
	v_mfma_f32_16x16x32_bf16 v[84:87], v[132:135], v[192:195], v[84:87]
	v_mfma_f32_16x16x32_bf16 v[80:83], v[140:143], v[192:195], v[80:83]
	v_mfma_f32_16x16x32_bf16 v[76:79], v[132:135], v[200:203], v[76:79]
	v_mfma_f32_16x16x32_bf16 v[72:75], v[140:143], v[200:203], v[72:75]
	v_mfma_f32_16x16x32_bf16 v[68:71], v[132:135], v[208:211], v[68:71]
	v_mfma_f32_16x16x32_bf16 v[64:67], v[140:143], v[208:211], v[64:67]
	s_setprio 0
	s_setprio 1
	v_mfma_f32_16x16x32_bf16 v[28:31], v[158:161], v[180:183], v[28:31]
	v_mfma_f32_16x16x32_bf16 v[24:27], v[172:175], v[180:183], v[24:27]
	v_mfma_f32_16x16x32_bf16 v[20:23], v[158:161], v[188:191], v[20:23]
	v_mfma_f32_16x16x32_bf16 v[16:19], v[172:175], v[188:191], v[16:19]
	v_mfma_f32_16x16x32_bf16 v[12:15], v[158:161], v[196:199], v[12:15]
	v_mfma_f32_16x16x32_bf16 v[8:11], v[172:175], v[196:199], v[8:11]
	v_mfma_f32_16x16x32_bf16 v[4:7], v[158:161], v[204:207], v[4:7]
	v_mfma_f32_16x16x32_bf16 v[0:3], v[172:175], v[204:207], v[0:3]
	s_setprio 0
	s_setprio 1
	v_mfma_f32_16x16x32_bf16 v[28:31], v[162:165], v[184:187], v[28:31]
	v_mfma_f32_16x16x32_bf16 v[24:27], v[176:179], v[184:187], v[24:27]
	v_mfma_f32_16x16x32_bf16 v[20:23], v[162:165], v[192:195], v[20:23]
	v_mfma_f32_16x16x32_bf16 v[16:19], v[176:179], v[192:195], v[16:19]
	v_mfma_f32_16x16x32_bf16 v[12:15], v[162:165], v[200:203], v[12:15]
	v_mfma_f32_16x16x32_bf16 v[8:11], v[176:179], v[200:203], v[8:11]
	v_mfma_f32_16x16x32_bf16 v[4:7], v[162:165], v[208:211], v[4:7]
	v_mfma_f32_16x16x32_bf16 v[0:3], v[176:179], v[208:211], v[0:3]
	s_setprio 0
	s_barrier
	s_add_u32 s52, s52, 0x100
	s_addc_u32 s53, s53, 0
	s_add_u32 s80, s80, 0x100
	s_addc_u32 s81, s81, 0
	s_cmp_ge_u32 s82, s78
	s_mov_b32 s14, s82
	s_cbranch_scc0 .LBB0_2574

; #define G_STAGE(bufoff, gbase, voff) do { _Pragma("unroll") for (int _i = 0; _i < 2; ++_i) \
;         __builtin_amdgcn_global_load_lds((const unsigned*)((const char*)(gbase) + voff[_i]), (LAS unsigned*)(lds + (bufoff) + ldsw + _i * 8192), 16, 0, 0); } while (0)
; #define G_LDA(dst, b, h) do { _Pragma("unroll") for (int m = 0; m < 4; ++m) _Pragma("unroll") for (int k = 0; k < 2; ++k) dst[m][k] = *(const LAS bf16x8*)(lds + G_SA(b, h) + aoff + m * 2048 + k * 1024); } while (0)
; #define G_MMA(ai, bj, At_, Bt_) do { __builtin_amdgcn_s_setprio(1); _Pragma("unroll") for (int m = 0; m < 4; ++m) _Pragma("unroll") for (int n = 0; n < 2; ++n) _Pragma("unroll") for (int k = 0; k < 2; ++k) \
;         acc[ai][bj][m][n] = __builtin_amdgcn_mfma_f32_16x16x32_bf16(Bt_[n][k], At_[m][k], acc[ai][bj][m][n], 0, 0, 0); __builtin_amdgcn_s_setprio(0); } while (0)
; #define WAIT_V(n) asm volatile("s_waitcnt vmcnt(" #n ")" ::: "memory")
; #define WAIT_L(n) asm volatile("s_waitcnt lgkmcnt(" #n ")" ::: "memory")
; #define BAR __builtin_amdgcn_s_barrier()
; #define SCHED __builtin_amdgcn_sched_barrier(0)
; template <class Get, class Epi>
; DI void gemm_loop(int ntiles, int ld, char* shm, const Get& get, const Epi& epi) {
;     ...
;             WAIT_V(8); WAIT_L(0); BAR; G_MMA(0, 0, At, B0); G_MMA(0, 1, At, B1); BAR; SCHED;
;             G_LDA(At, 0, 1); G_STAGE(G_SB(0, 0), b2, voffB); G_STAGE(G_SB(0, 1), b2 + hstep, voffB); G_STAGE(G_SA(0, 0), a2, voffA);
.Lrj_2892_0:
	s_waitcnt lgkmcnt(0)
	s_barrier
	s_setprio 1
	s_waitcnt lgkmcnt(0)
	v_mfma_f32_16x16x32_bf16 v[124:127], v[128:131], v[180:183], 0
	v_mfma_f32_16x16x32_bf16 v[120:123], v[136:139], v[180:183], 0
	v_mfma_f32_16x16x32_bf16 v[116:119], v[128:131], v[188:191], 0
	v_mfma_f32_16x16x32_bf16 v[112:115], v[136:139], v[188:191], 0
	v_mfma_f32_16x16x32_bf16 v[108:111], v[128:131], v[196:199], 0
	v_mfma_f32_16x16x32_bf16 v[104:107], v[136:139], v[196:199], 0
	v_mfma_f32_16x16x32_bf16 v[100:103], v[128:131], v[204:207], 0
	v_mfma_f32_16x16x32_bf16 v[96:99], v[136:139], v[204:207], 0
	s_setprio 0
	s_setprio 1
	v_mfma_f32_16x16x32_bf16 v[124:127], v[132:135], v[184:187], v[124:127]
	v_mfma_f32_16x16x32_bf16 v[120:123], v[140:143], v[184:187], v[120:123]
	v_mfma_f32_16x16x32_bf16 v[116:119], v[132:135], v[192:195], v[116:119]
	v_mfma_f32_16x16x32_bf16 v[112:115], v[140:143], v[192:195], v[112:115]
	v_mfma_f32_16x16x32_bf16 v[108:111], v[132:135], v[200:203], v[108:111]
	v_mfma_f32_16x16x32_bf16 v[104:107], v[140:143], v[200:203], v[104:107]
	v_mfma_f32_16x16x32_bf16 v[100:103], v[132:135], v[208:211], v[100:103]
	v_mfma_f32_16x16x32_bf16 v[96:99], v[140:143], v[208:211], v[96:99]
	s_setprio 0
	s_setprio 1
	v_mfma_f32_16x16x32_bf16 v[60:63], v[158:161], v[180:183], 0
	v_mfma_f32_16x16x32_bf16 v[56:59], v[172:175], v[180:183], 0
	v_mfma_f32_16x16x32_bf16 v[52:55], v[158:161], v[188:191], 0
	v_mfma_f32_16x16x32_bf16 v[48:51], v[172:175], v[188:191], 0
	v_mfma_f32_16x16x32_bf16 v[44:47], v[158:161], v[196:199], 0
	v_mfma_f32_16x16x32_bf16 v[40:43], v[172:175], v[196:199], 0
	v_mfma_f32_16x16x32_bf16 v[36:39], v[158:161], v[204:207], 0
	v_mfma_f32_16x16x32_bf16 v[32:35], v[172:175], v[204:207], 0
	s_setprio 0
	s_setprio 1
	v_mfma_f32_16x16x32_bf16 v[60:63], v[162:165], v[184:187], v[60:63]
	v_mfma_f32_16x16x32_bf16 v[56:59], v[176:179], v[184:187], v[56:59]
	v_mfma_f32_16x16x32_bf16 v[52:55], v[162:165], v[192:195], v[52:55]
	v_mfma_f32_16x16x32_bf16 v[48:51], v[176:179], v[192:195], v[48:51]
	v_mfma_f32_16x16x32_bf16 v[44:47], v[162:165], v[200:203], v[44:47]
	v_mfma_f32_16x16x32_bf16 v[40:43], v[176:179], v[200:203], v[40:43]
	v_mfma_f32_16x16x32_bf16 v[36:39], v[162:165], v[208:211], v[36:39]
	v_mfma_f32_16x16x32_bf16 v[32:35], v[176:179], v[208:211], v[32:35]
	s_setprio 0
	s_barrier
	s_add_i32 s4, s58, s48
	v_lshl_add_u64 v[144:145], s[44:45], 0, v[148:149]
	s_mov_b32 m0, s4
	ds_read_b128 v[180:183], v171 offset:16384
	ds_read_b128 v[184:187], v171 offset:17408
	ds_read_b128 v[188:191], v171 offset:18432
	ds_read_b128 v[192:195], v171 offset:19456
	ds_read_b128 v[196:199], v171 offset:20480
	ds_read_b128 v[200:203], v171 offset:21504
	ds_read_b128 v[204:207], v171 offset:22528
	ds_read_b128 v[208:211], v171 offset:23552
	global_load_lds_dwordx4 v[144:145], off
	s_add_i32 m0, s4, 0x2000
	s_add_u32 s4, s44, 0xb0000
	v_lshl_add_u64 v[166:167], s[44:45], 0, v[152:153]
	s_addc_u32 s5, s45, 0
	s_add_i32 s84, s59, s48
	global_load_lds_dwordx4 v[166:167], off
	v_lshl_add_u64 v[212:213], s[4:5], 0, v[148:149]
	s_mov_b32 m0, s84
	v_lshl_add_u64 v[214:215], s[46:47], 0, v[150:151]
	global_load_lds_dwordx4 v[212:213], off
	v_lshl_add_u64 v[212:213], s[4:5], 0, v[152:153]
	s_add_i32 m0, s84, 0x2000
	s_nop 0
	global_load_lds_dwordx4 v[212:213], off
	v_lshl_add_u64 v[212:213], s[46:47], 0, v[146:147]
	s_mov_b32 m0, s49
	s_nop 0
	global_load_lds_dwordx4 v[212:213], off
	s_mov_b32 m0, s50
	s_nop 0
	global_load_lds_dwordx4 v[214:215], off
	s_cmp_lg_u32 s100, 0
	s_cbranch_scc0 .Lrf_2892_1
	s_waitcnt vmcnt(16)
	s_branch .Lrj_2892_1

; #define G_STAGE(bufoff, gbase, voff) do { _Pragma("unroll") for (int _i = 0; _i < 2; ++_i) \
;         __builtin_amdgcn_global_load_lds((const unsigned*)((const char*)(gbase) + voff[_i]), (LAS unsigned*)(lds + (bufoff) + ldsw + _i * 8192), 16, 0, 0); } while (0)
; #define G_LDA(dst, b, h) do { _Pragma("unroll") for (int m = 0; m < 4; ++m) _Pragma("unroll") for (int k = 0; k < 2; ++k) dst[m][k] = *(const LAS bf16x8*)(lds + G_SA(b, h) + aoff + m * 2048 + k * 1024); } while (0)
; #define G_LDB(dst, b, h) do { _Pragma("unroll") for (int n = 0; n < 2; ++n) _Pragma("unroll") for (int k = 0; k < 2; ++k) dst[n][k] = *(const LAS bf16x8*)(lds + G_SB(b, h) + boff + n * 2048 + k * 1024); } while (0)
; #define G_MMA(ai, bj, At_, Bt_) do { __builtin_amdgcn_s_setprio(1); _Pragma("unroll") for (int m = 0; m < 4; ++m) _Pragma("unroll") for (int n = 0; n < 2; ++n) _Pragma("unroll") for (int k = 0; k < 2; ++k) \
;         acc[ai][bj][m][n] = __builtin_amdgcn_mfma_f32_16x16x32_bf16(Bt_[n][k], At_[m][k], acc[ai][bj][m][n], 0, 0, 0); __builtin_amdgcn_s_setprio(0); } while (0)
; #define WAIT_V(n) asm volatile("s_waitcnt vmcnt(" #n ")" ::: "memory")
; #define WAIT_L(n) asm volatile("s_waitcnt lgkmcnt(" #n ")" ::: "memory")
; #define BAR __builtin_amdgcn_s_barrier()
; #define SCHED __builtin_amdgcn_sched_barrier(0)
; template <class Get, class Epi>
; DI void gemm_loop(int ntiles, int ld, char* shm, const Get& get, const Epi& epi) {
;     ...
;             WAIT_V(8); WAIT_L(0); BAR; G_MMA(1, 0, At, B0); G_MMA(1, 1, At, B1); BAR; SCHED;
;             G_LDB(B0, 1, 0); G_LDB(B1, 1, 1); SCHED; G_LDA(At, 1, 0); G_STAGE(G_SA(0, 1), a2 + hstep, voffA);
;             WAIT_V(8); WAIT_L(0); BAR; G_MMA(0, 0, At, B0); G_MMA(0, 1, At, B1); BAR; SCHED;
.Lrj_2892_1:
	s_waitcnt lgkmcnt(0)
	s_barrier
	s_setprio 1
	s_waitcnt lgkmcnt(0)
	v_mfma_f32_16x16x32_bf16 v[92:95], v[128:131], v[180:183], 0
	v_mfma_f32_16x16x32_bf16 v[88:91], v[136:139], v[180:183], 0
	v_mfma_f32_16x16x32_bf16 v[84:87], v[128:131], v[188:191], 0
	v_mfma_f32_16x16x32_bf16 v[80:83], v[136:139], v[188:191], 0
	v_mfma_f32_16x16x32_bf16 v[76:79], v[128:131], v[196:199], 0
	v_mfma_f32_16x16x32_bf16 v[72:75], v[136:139], v[196:199], 0
	v_mfma_f32_16x16x32_bf16 v[68:71], v[128:131], v[204:207], 0
	v_mfma_f32_16x16x32_bf16 v[64:67], v[136:139], v[204:207], 0
	s_setprio 0
	s_setprio 1
	v_mfma_f32_16x16x32_bf16 v[92:95], v[132:135], v[184:187], v[92:95]
	v_mfma_f32_16x16x32_bf16 v[88:91], v[140:143], v[184:187], v[88:91]
	v_mfma_f32_16x16x32_bf16 v[84:87], v[132:135], v[192:195], v[84:87]
	v_mfma_f32_16x16x32_bf16 v[80:83], v[140:143], v[192:195], v[80:83]
	v_mfma_f32_16x16x32_bf16 v[76:79], v[132:135], v[200:203], v[76:79]
	v_mfma_f32_16x16x32_bf16 v[72:75], v[140:143], v[200:203], v[72:75]
	v_mfma_f32_16x16x32_bf16 v[68:71], v[132:135], v[208:211], v[68:71]
	v_mfma_f32_16x16x32_bf16 v[64:67], v[140:143], v[208:211], v[64:67]
	s_setprio 0
	s_setprio 1
	v_mfma_f32_16x16x32_bf16 v[28:31], v[158:161], v[180:183], 0
	v_mfma_f32_16x16x32_bf16 v[24:27], v[172:175], v[180:183], 0
	v_mfma_f32_16x16x32_bf16 v[20:23], v[158:161], v[188:191], 0
	v_mfma_f32_16x16x32_bf16 v[16:19], v[172:175], v[188:191], 0
	v_mfma_f32_16x16x32_bf16 v[12:15], v[158:161], v[196:199], 0
	v_mfma_f32_16x16x32_bf16 v[8:11], v[172:175], v[196:199], 0
	v_mfma_f32_16x16x32_bf16 v[4:7], v[158:161], v[204:207], 0
	v_mfma_f32_16x16x32_bf16 v[0:3], v[172:175], v[204:207], 0
	s_setprio 0
	s_setprio 1
	v_mfma_f32_16x16x32_bf16 v[28:31], v[162:165], v[184:187], v[28:31]
	v_mfma_f32_16x16x32_bf16 v[24:27], v[176:179], v[184:187], v[24:27]
	v_mfma_f32_16x16x32_bf16 v[20:23], v[162:165], v[192:195], v[20:23]
	v_mfma_f32_16x16x32_bf16 v[16:19], v[176:179], v[192:195], v[16:19]
	v_mfma_f32_16x16x32_bf16 v[12:15], v[162:165], v[200:203], v[12:15]
	v_mfma_f32_16x16x32_bf16 v[8:11], v[176:179], v[200:203], v[8:11]
	v_mfma_f32_16x16x32_bf16 v[4:7], v[162:165], v[208:211], v[4:7]
	v_mfma_f32_16x16x32_bf16 v[0:3], v[176:179], v[208:211], v[0:3]
	s_setprio 0
	s_barrier
	s_add_i32 s84, 0, 0x18000
	s_add_i32 s85, 0, 0x1c000
	v_add_u32_e32 v140, s84, v168
	v_add_u32_e32 v176, s85, v168
	ds_read_b128 v[128:131], v140
	ds_read_b128 v[132:135], v140 offset:1024
	ds_read_b128 v[136:139], v140 offset:2048
	ds_read_b128 v[140:143], v140 offset:3072
	ds_read_b128 v[158:161], v176
	ds_read_b128 v[162:165], v176 offset:1024
	ds_read_b128 v[172:175], v176 offset:2048
	ds_read_b128 v[176:179], v176 offset:3072
	s_add_u32 s4, s46, 0xb0000
	s_addc_u32 s5, s47, 0
	s_mov_b32 m0, s51
	v_lshl_add_u64 v[216:217], s[4:5], 0, v[146:147]
	ds_read_b128 v[180:183], v171 offset:32768
	ds_read_b128 v[184:187], v171 offset:33792
	ds_read_b128 v[188:191], v171 offset:34816
	ds_read_b128 v[192:195], v171 offset:35840
	ds_read_b128 v[196:199], v171 offset:36864
	ds_read_b128 v[200:203], v171 offset:37888
	ds_read_b128 v[204:207], v171 offset:38912
	ds_read_b128 v[208:211], v171 offset:39936
	global_load_lds_dwordx4 v[216:217], off
	v_lshl_add_u64 v[216:217], s[4:5], 0, v[150:151]
	s_mov_b32 m0, s52
	s_nop 0
	global_load_lds_dwordx4 v[216:217], off
	s_waitcnt vmcnt(8)
	s_waitcnt lgkmcnt(0)
	s_barrier
	s_setprio 1
	s_waitcnt lgkmcnt(0)
	v_mfma_f32_16x16x32_bf16 v[124:127], v[128:131], v[180:183], v[124:127]
	v_mfma_f32_16x16x32_bf16 v[120:123], v[136:139], v[180:183], v[120:123]
	v_mfma_f32_16x16x32_bf16 v[116:119], v[128:131], v[188:191], v[116:119]
	v_mfma_f32_16x16x32_bf16 v[112:115], v[136:139], v[188:191], v[112:115]
	v_mfma_f32_16x16x32_bf16 v[108:111], v[128:131], v[196:199], v[108:111]
	v_mfma_f32_16x16x32_bf16 v[104:107], v[136:139], v[196:199], v[104:107]
	v_mfma_f32_16x16x32_bf16 v[100:103], v[128:131], v[204:207], v[100:103]
	v_mfma_f32_16x16x32_bf16 v[96:99], v[136:139], v[204:207], v[96:99]
	s_setprio 0
	s_setprio 1
	v_mfma_f32_16x16x32_bf16 v[124:127], v[132:135], v[184:187], v[124:127]
	v_mfma_f32_16x16x32_bf16 v[120:123], v[140:143], v[184:187], v[120:123]
	v_mfma_f32_16x16x32_bf16 v[116:119], v[132:135], v[192:195], v[116:119]
	v_mfma_f32_16x16x32_bf16 v[112:115], v[140:143], v[192:195], v[112:115]
	v_mfma_f32_16x16x32_bf16 v[108:111], v[132:135], v[200:203], v[108:111]
	v_mfma_f32_16x16x32_bf16 v[104:107], v[140:143], v[200:203], v[104:107]
	v_mfma_f32_16x16x32_bf16 v[100:103], v[132:135], v[208:211], v[100:103]
	v_mfma_f32_16x16x32_bf16 v[96:99], v[140:143], v[208:211], v[96:99]
	s_setprio 0
	s_setprio 1
	v_mfma_f32_16x16x32_bf16 v[60:63], v[158:161], v[180:183], v[60:63]
	v_mfma_f32_16x16x32_bf16 v[56:59], v[172:175], v[180:183], v[56:59]
	v_mfma_f32_16x16x32_bf16 v[52:55], v[158:161], v[188:191], v[52:55]
	v_mfma_f32_16x16x32_bf16 v[48:51], v[172:175], v[188:191], v[48:51]
	v_mfma_f32_16x16x32_bf16 v[44:47], v[158:161], v[196:199], v[44:47]
	v_mfma_f32_16x16x32_bf16 v[40:43], v[172:175], v[196:199], v[40:43]
	v_mfma_f32_16x16x32_bf16 v[36:39], v[158:161], v[204:207], v[36:39]
	v_mfma_f32_16x16x32_bf16 v[32:35], v[172:175], v[204:207], v[32:35]
	s_setprio 0
	s_setprio 1
	v_mfma_f32_16x16x32_bf16 v[60:63], v[162:165], v[184:187], v[60:63]
	v_mfma_f32_16x16x32_bf16 v[56:59], v[176:179], v[184:187], v[56:59]
	v_mfma_f32_16x16x32_bf16 v[52:55], v[162:165], v[192:195], v[52:55]
	v_mfma_f32_16x16x32_bf16 v[48:51], v[176:179], v[192:195], v[48:51]
	v_mfma_f32_16x16x32_bf16 v[44:47], v[162:165], v[200:203], v[44:47]
	v_mfma_f32_16x16x32_bf16 v[40:43], v[176:179], v[200:203], v[40:43]
	v_mfma_f32_16x16x32_bf16 v[36:39], v[162:165], v[208:211], v[36:39]
	v_mfma_f32_16x16x32_bf16 v[32:35], v[176:179], v[208:211], v[32:35]
	s_setprio 0
	s_barrier
; #define G_STAGE(bufoff, gbase, voff) do { _Pragma("unroll") for (int _i = 0; _i < 2; ++_i) \
;         __builtin_amdgcn_global_load_lds((const unsigned*)((const char*)(gbase) + voff[_i]), (LAS unsigned*)(lds + (bufoff) + ldsw + _i * 8192), 16, 0, 0); } while (0)
; #define G_LDA(dst, b, h) do { _Pragma("unroll") for (int m = 0; m < 4; ++m) _Pragma("unroll") for (int k = 0; k < 2; ++k) dst[m][k] = *(const LAS bf16x8*)(lds + G_SA(b, h) + aoff + m * 2048 + k * 1024); } while (0)
; #define G_LDB(dst, b, h) do { _Pragma("unroll") for (int n = 0; n < 2; ++n) _Pragma("unroll") for (int k = 0; k < 2; ++k) dst[n][k] = *(const LAS bf16x8*)(lds + G_SB(b, h) + boff + n * 2048 + k * 1024); } while (0)
; #define G_MMA(ai, bj, At_, Bt_) do { __builtin_amdgcn_s_setprio(1); _Pragma("unroll") for (int m = 0; m < 4; ++m) _Pragma("unroll") for (int n = 0; n < 2; ++n) _Pragma("unroll") for (int k = 0; k < 2; ++k) \
;         acc[ai][bj][m][n] = __builtin_amdgcn_mfma_f32_16x16x32_bf16(Bt_[n][k], At_[m][k], acc[ai][bj][m][n], 0, 0, 0); __builtin_amdgcn_s_setprio(0); } while (0)
; #define WAIT_V(n) asm volatile("s_waitcnt vmcnt(" #n ")" ::: "memory")
; #define WAIT_L(n) asm volatile("s_waitcnt lgkmcnt(" #n ")" ::: "memory")
; #define BAR __builtin_amdgcn_s_barrier()
; #define SCHED __builtin_amdgcn_sched_barrier(0)
; template <class Get, class Epi>
; DI void gemm_loop(int ntiles, int ld, char* shm, const Get& get, const Epi& epi) {
;     ...
;             G_LDB(B0, 0, 0); G_LDB(B1, 0, 1); SCHED; G_LDA(At, 0, 0); G_STAGE(G_SA(1, 1), a1 + hstep, voffA);
;             WAIT_V(8); WAIT_L(0); BAR; G_MMA(0, 0, At, B0); G_MMA(0, 1, At, B1); BAR; SCHED;
;     ...
;             G_LDA(At, 1, 1); G_STAGE(G_SB(1, 0), b3, voffB); G_STAGE(G_SB(1, 1), b3 + hstep, voffB); G_STAGE(G_SA(1, 0), a3, voffA);
;             WAIT_V(8); WAIT_L(0); BAR; G_MMA(1, 0, At, B0); G_MMA(1, 1, At, B1); BAR; SCHED;
	s_add_i32 s4, s84, s48
	v_lshl_add_u64 v[144:145], v[144:145], 0, s[10:11]
	s_mov_b32 m0, s4
	ds_read_b128 v[180:183], v171 offset:49152
	ds_read_b128 v[184:187], v171 offset:50176
	ds_read_b128 v[188:191], v171 offset:51200
	ds_read_b128 v[192:195], v171 offset:52224
	ds_read_b128 v[196:199], v171 offset:53248
	ds_read_b128 v[200:203], v171 offset:54272
	ds_read_b128 v[204:207], v171 offset:55296
	ds_read_b128 v[208:211], v171 offset:56320
	global_load_lds_dwordx4 v[144:145], off
	s_add_i32 m0, s4, 0x2000
	s_add_u32 s4, s44, 0xb0080
	v_lshl_add_u64 v[144:145], v[166:167], 0, s[10:11]
	s_addc_u32 s5, s45, 0
	s_add_i32 s44, s85, s48
	global_load_lds_dwordx4 v[144:145], off
	v_lshl_add_u64 v[144:145], s[4:5], 0, v[148:149]
	s_mov_b32 m0, s44
	s_nop 0
	global_load_lds_dwordx4 v[144:145], off
	v_lshl_add_u64 v[144:145], s[4:5], 0, v[152:153]
	s_add_i32 m0, s44, 0x2000
	s_nop 0
	global_load_lds_dwordx4 v[144:145], off
	v_lshl_add_u64 v[144:145], v[212:213], 0, s[10:11]
	s_mov_b32 m0, s55
	s_nop 0
	global_load_lds_dwordx4 v[144:145], off
	v_lshl_add_u64 v[144:145], v[214:215], 0, s[10:11]
	s_mov_b32 m0, s56
	s_nop 0
	global_load_lds_dwordx4 v[144:145], off
	s_waitcnt vmcnt(8)
	s_waitcnt lgkmcnt(0)
	s_barrier
	s_setprio 1
	s_waitcnt lgkmcnt(0)
	v_mfma_f32_16x16x32_bf16 v[92:95], v[128:131], v[180:183], v[92:95]
	v_mfma_f32_16x16x32_bf16 v[88:91], v[136:139], v[180:183], v[88:91]
	v_mfma_f32_16x16x32_bf16 v[84:87], v[128:131], v[188:191], v[84:87]
	v_mfma_f32_16x16x32_bf16 v[80:83], v[136:139], v[188:191], v[80:83]
	v_mfma_f32_16x16x32_bf16 v[76:79], v[128:131], v[196:199], v[76:79]
	v_mfma_f32_16x16x32_bf16 v[72:75], v[136:139], v[196:199], v[72:75]
	v_mfma_f32_16x16x32_bf16 v[68:71], v[128:131], v[204:207], v[68:71]
	v_mfma_f32_16x16x32_bf16 v[64:67], v[136:139], v[204:207], v[64:67]
	s_setprio 0
	s_setprio 1
	v_mfma_f32_16x16x32_bf16 v[92:95], v[132:135], v[184:187], v[92:95]
	v_mfma_f32_16x16x32_bf16 v[88:91], v[140:143], v[184:187], v[88:91]
	v_mfma_f32_16x16x32_bf16 v[84:87], v[132:135], v[192:195], v[84:87]
	v_mfma_f32_16x16x32_bf16 v[80:83], v[140:143], v[192:195], v[80:83]
	v_mfma_f32_16x16x32_bf16 v[76:79], v[132:135], v[200:203], v[76:79]
	v_mfma_f32_16x16x32_bf16 v[72:75], v[140:143], v[200:203], v[72:75]
	v_mfma_f32_16x16x32_bf16 v[68:71], v[132:135], v[208:211], v[68:71]
	v_mfma_f32_16x16x32_bf16 v[64:67], v[140:143], v[208:211], v[64:67]
	s_setprio 0
	s_setprio 1
	v_mfma_f32_16x16x32_bf16 v[28:31], v[158:161], v[180:183], v[28:31]
	v_mfma_f32_16x16x32_bf16 v[24:27], v[172:175], v[180:183], v[24:27]
	v_mfma_f32_16x16x32_bf16 v[20:23], v[158:161], v[188:191], v[20:23]
	v_mfma_f32_16x16x32_bf16 v[16:19], v[172:175], v[188:191], v[16:19]
	v_mfma_f32_16x16x32_bf16 v[12:15], v[158:161], v[196:199], v[12:15]
	v_mfma_f32_16x16x32_bf16 v[8:11], v[172:175], v[196:199], v[8:11]
	v_mfma_f32_16x16x32_bf16 v[4:7], v[158:161], v[204:207], v[4:7]
	v_mfma_f32_16x16x32_bf16 v[0:3], v[172:175], v[204:207], v[0:3]
	s_setprio 0
	s_setprio 1
	v_mfma_f32_16x16x32_bf16 v[28:31], v[162:165], v[184:187], v[28:31]
	v_mfma_f32_16x16x32_bf16 v[24:27], v[176:179], v[184:187], v[24:27]
	v_mfma_f32_16x16x32_bf16 v[20:23], v[162:165], v[192:195], v[20:23]
	v_mfma_f32_16x16x32_bf16 v[16:19], v[176:179], v[192:195], v[16:19]
	v_mfma_f32_16x16x32_bf16 v[12:15], v[162:165], v[200:203], v[12:15]
	v_mfma_f32_16x16x32_bf16 v[8:11], v[176:179], v[200:203], v[8:11]
	v_mfma_f32_16x16x32_bf16 v[4:7], v[162:165], v[208:211], v[4:7]
	v_mfma_f32_16x16x32_bf16 v[0:3], v[176:179], v[208:211], v[0:3]
	s_setprio 0
	s_barrier
	s_add_u32 s81, s81, 0x100
	s_addc_u32 s82, s82, 0
	s_cmp_ge_u32 s83, s79
	s_mov_b64 s[4:5], s[14:15]
	s_mov_b32 s44, s83
	s_cbranch_scc0 .LBB0_2892
	s_branch .Lpost_2892
.LBB0_2892:
	ds_read_b128 v[128:131], v169
	ds_read_b128 v[132:135], v169 offset:1024
	ds_read_b128 v[136:139], v169 offset:2048
	ds_read_b128 v[140:143], v169 offset:3072
	ds_read_b128 v[158:161], v170
	ds_read_b128 v[162:165], v170 offset:1024
	ds_read_b128 v[172:175], v170 offset:2048
	ds_read_b128 v[176:179], v170 offset:3072
	s_add_i32 s83, s44, 2
	s_add_u32 s14, s4, 0x100
	s_addc_u32 s15, s5, 0
	s_cmp_eq_u32 s80, s44
	s_cselect_b32 s44, s42, s81
	s_cselect_b32 s47, s41, s15
	s_cselect_b32 s46, s40, s14
	s_cselect_b32 s45, s43, s82
	v_lshl_add_u64 v[144:145], s[4:5], 0, v[154:155]
	s_add_i32 m0, s49, 0xc000
	ds_read_b128 v[180:183], v171
	ds_read_b128 v[184:187], v171 offset:1024
	ds_read_b128 v[188:191], v171 offset:2048
	ds_read_b128 v[192:195], v171 offset:3072
	ds_read_b128 v[196:199], v171 offset:4096
	ds_read_b128 v[200:203], v171 offset:5120
	ds_read_b128 v[204:207], v171 offset:6144
	ds_read_b128 v[208:211], v171 offset:7168
	global_load_lds_dwordx4 v[144:145], off
	v_lshl_add_u64 v[144:145], s[4:5], 0, v[156:157]
	s_add_i32 m0, s49, 0xe000
	s_nop 0
	global_load_lds_dwordx4 v[144:145], off
	s_waitcnt vmcnt(8)
	s_waitcnt lgkmcnt(0)
	s_barrier
; #define G_STAGE(bufoff, gbase, voff) do { _Pragma("unroll") for (int _i = 0; _i < 2; ++_i) \
;         __builtin_amdgcn_global_load_lds((const unsigned*)((const char*)(gbase) + voff[_i]), (LAS unsigned*)(lds + (bufoff) + ldsw + _i * 8192), 16, 0, 0); } while (0)
; #define G_LDA(dst, b, h) do { _Pragma("unroll") for (int m = 0; m < 4; ++m) _Pragma("unroll") for (int k = 0; k < 2; ++k) dst[m][k] = *(const LAS bf16x8*)(lds + G_SA(b, h) + aoff + m * 2048 + k * 1024); } while (0)
; #define G_MMA(ai, bj, At_, Bt_) do { __builtin_amdgcn_s_setprio(1); _Pragma("unroll") for (int m = 0; m < 4; ++m) _Pragma("unroll") for (int n = 0; n < 2; ++n) _Pragma("unroll") for (int k = 0; k < 2; ++k) \
;         acc[ai][bj][m][n] = __builtin_amdgcn_mfma_f32_16x16x32_bf16(Bt_[n][k], At_[m][k], acc[ai][bj][m][n], 0, 0, 0); __builtin_amdgcn_s_setprio(0); } while (0)
; #define WAIT_V(n) asm volatile("s_waitcnt vmcnt(" #n ")" ::: "memory")
; #define WAIT_L(n) asm volatile("s_waitcnt lgkmcnt(" #n ")" ::: "memory")
; #define BAR __builtin_amdgcn_s_barrier()
; #define SCHED __builtin_amdgcn_sched_barrier(0)
; template <class Get, class Epi>
; DI void gemm_loop(int ntiles, int ld, char* shm, const Get& get, const Epi& epi) {
;     ...
;             WAIT_V(8); WAIT_L(0); BAR; G_MMA(0, 0, At, B0); G_MMA(0, 1, At, B1); BAR; SCHED;
;             G_LDA(At, 0, 1); G_STAGE(G_SB(0, 0), b2, voffB); G_STAGE(G_SB(0, 1), b2 + hstep, voffB); G_STAGE(G_SA(0, 0), a2, voffA);
;             WAIT_V(8); WAIT_L(0); BAR; G_MMA(1, 0, At, B0); G_MMA(1, 1, At, B1); BAR; SCHED;
	s_setprio 1
	s_waitcnt lgkmcnt(0)
	v_mfma_f32_16x16x32_bf16 v[124:127], v[128:131], v[180:183], v[124:127]
	v_mfma_f32_16x16x32_bf16 v[120:123], v[136:139], v[180:183], v[120:123]
	v_mfma_f32_16x16x32_bf16 v[116:119], v[128:131], v[188:191], v[116:119]
	v_mfma_f32_16x16x32_bf16 v[112:115], v[136:139], v[188:191], v[112:115]
	v_mfma_f32_16x16x32_bf16 v[108:111], v[128:131], v[196:199], v[108:111]
	v_mfma_f32_16x16x32_bf16 v[104:107], v[136:139], v[196:199], v[104:107]
	v_mfma_f32_16x16x32_bf16 v[100:103], v[128:131], v[204:207], v[100:103]
	v_mfma_f32_16x16x32_bf16 v[96:99], v[136:139], v[204:207], v[96:99]
	s_setprio 0
	s_setprio 1
	v_mfma_f32_16x16x32_bf16 v[124:127], v[132:135], v[184:187], v[124:127]
	v_mfma_f32_16x16x32_bf16 v[120:123], v[140:143], v[184:187], v[120:123]
	v_mfma_f32_16x16x32_bf16 v[116:119], v[132:135], v[192:195], v[116:119]
	v_mfma_f32_16x16x32_bf16 v[112:115], v[140:143], v[192:195], v[112:115]
	v_mfma_f32_16x16x32_bf16 v[108:111], v[132:135], v[200:203], v[108:111]
	v_mfma_f32_16x16x32_bf16 v[104:107], v[140:143], v[200:203], v[104:107]
	v_mfma_f32_16x16x32_bf16 v[100:103], v[132:135], v[208:211], v[100:103]
	v_mfma_f32_16x16x32_bf16 v[96:99], v[140:143], v[208:211], v[96:99]
	s_setprio 0
	s_setprio 1
	v_mfma_f32_16x16x32_bf16 v[60:63], v[158:161], v[180:183], v[60:63]
	v_mfma_f32_16x16x32_bf16 v[56:59], v[172:175], v[180:183], v[56:59]
	v_mfma_f32_16x16x32_bf16 v[52:55], v[158:161], v[188:191], v[52:55]
	v_mfma_f32_16x16x32_bf16 v[48:51], v[172:175], v[188:191], v[48:51]
	v_mfma_f32_16x16x32_bf16 v[44:47], v[158:161], v[196:199], v[44:47]
	v_mfma_f32_16x16x32_bf16 v[40:43], v[172:175], v[196:199], v[40:43]
	v_mfma_f32_16x16x32_bf16 v[36:39], v[158:161], v[204:207], v[36:39]
	v_mfma_f32_16x16x32_bf16 v[32:35], v[172:175], v[204:207], v[32:35]
	s_setprio 0
	s_setprio 1
	v_mfma_f32_16x16x32_bf16 v[60:63], v[162:165], v[184:187], v[60:63]
	v_mfma_f32_16x16x32_bf16 v[56:59], v[176:179], v[184:187], v[56:59]
	v_mfma_f32_16x16x32_bf16 v[52:55], v[162:165], v[192:195], v[52:55]
	v_mfma_f32_16x16x32_bf16 v[48:51], v[176:179], v[192:195], v[48:51]
	v_mfma_f32_16x16x32_bf16 v[44:47], v[162:165], v[200:203], v[44:47]
	v_mfma_f32_16x16x32_bf16 v[40:43], v[176:179], v[200:203], v[40:43]
	v_mfma_f32_16x16x32_bf16 v[36:39], v[162:165], v[208:211], v[36:39]
	v_mfma_f32_16x16x32_bf16 v[32:35], v[176:179], v[208:211], v[32:35]
	s_setprio 0
	s_barrier
	s_add_i32 s4, s58, s48
	v_lshl_add_u64 v[144:145], s[44:45], 0, v[148:149]
	s_mov_b32 m0, s4
	ds_read_b128 v[180:183], v171 offset:16384
	ds_read_b128 v[184:187], v171 offset:17408
	ds_read_b128 v[188:191], v171 offset:18432
	ds_read_b128 v[192:195], v171 offset:19456
	ds_read_b128 v[196:199], v171 offset:20480
	ds_read_b128 v[200:203], v171 offset:21504
	ds_read_b128 v[204:207], v171 offset:22528
	ds_read_b128 v[208:211], v171 offset:23552
	global_load_lds_dwordx4 v[144:145], off
	s_add_i32 m0, s4, 0x2000
	s_add_u32 s4, s44, 0xb0000
	v_lshl_add_u64 v[166:167], s[44:45], 0, v[152:153]
	s_addc_u32 s5, s45, 0
	s_add_i32 s84, s59, s48
	global_load_lds_dwordx4 v[166:167], off
	v_lshl_add_u64 v[212:213], s[4:5], 0, v[148:149]
	s_mov_b32 m0, s84
	v_lshl_add_u64 v[214:215], s[46:47], 0, v[150:151]
	global_load_lds_dwordx4 v[212:213], off
	v_lshl_add_u64 v[212:213], s[4:5], 0, v[152:153]
	s_add_i32 m0, s84, 0x2000
	s_nop 0
	global_load_lds_dwordx4 v[212:213], off
	v_lshl_add_u64 v[212:213], s[46:47], 0, v[146:147]
	s_mov_b32 m0, s49
	s_nop 0
	global_load_lds_dwordx4 v[212:213], off
	s_mov_b32 m0, s50
	s_nop 0
	global_load_lds_dwordx4 v[214:215], off
	s_waitcnt vmcnt(8)
	s_waitcnt lgkmcnt(0)
	s_barrier
	s_setprio 1
	s_waitcnt lgkmcnt(0)
	v_mfma_f32_16x16x32_bf16 v[92:95], v[128:131], v[180:183], v[92:95]
	v_mfma_f32_16x16x32_bf16 v[88:91], v[136:139], v[180:183], v[88:91]
	v_mfma_f32_16x16x32_bf16 v[84:87], v[128:131], v[188:191], v[84:87]
	v_mfma_f32_16x16x32_bf16 v[80:83], v[136:139], v[188:191], v[80:83]
	v_mfma_f32_16x16x32_bf16 v[76:79], v[128:131], v[196:199], v[76:79]
	v_mfma_f32_16x16x32_bf16 v[72:75], v[136:139], v[196:199], v[72:75]
	v_mfma_f32_16x16x32_bf16 v[68:71], v[128:131], v[204:207], v[68:71]
	v_mfma_f32_16x16x32_bf16 v[64:67], v[136:139], v[204:207], v[64:67]
	s_setprio 0
	s_setprio 1
	v_mfma_f32_16x16x32_bf16 v[92:95], v[132:135], v[184:187], v[92:95]
	v_mfma_f32_16x16x32_bf16 v[88:91], v[140:143], v[184:187], v[88:91]
	v_mfma_f32_16x16x32_bf16 v[84:87], v[132:135], v[192:195], v[84:87]
	v_mfma_f32_16x16x32_bf16 v[80:83], v[140:143], v[192:195], v[80:83]
	v_mfma_f32_16x16x32_bf16 v[76:79], v[132:135], v[200:203], v[76:79]
	v_mfma_f32_16x16x32_bf16 v[72:75], v[140:143], v[200:203], v[72:75]
	v_mfma_f32_16x16x32_bf16 v[68:71], v[132:135], v[208:211], v[68:71]
	v_mfma_f32_16x16x32_bf16 v[64:67], v[140:143], v[208:211], v[64:67]
	s_setprio 0
	s_setprio 1
	v_mfma_f32_16x16x32_bf16 v[28:31], v[158:161], v[180:183], v[28:31]
	v_mfma_f32_16x16x32_bf16 v[24:27], v[172:175], v[180:183], v[24:27]
	v_mfma_f32_16x16x32_bf16 v[20:23], v[158:161], v[188:191], v[20:23]
	v_mfma_f32_16x16x32_bf16 v[16:19], v[172:175], v[188:191], v[16:19]
	v_mfma_f32_16x16x32_bf16 v[12:15], v[158:161], v[196:199], v[12:15]
	v_mfma_f32_16x16x32_bf16 v[8:11], v[172:175], v[196:199], v[8:11]
	v_mfma_f32_16x16x32_bf16 v[4:7], v[158:161], v[204:207], v[4:7]
	v_mfma_f32_16x16x32_bf16 v[0:3], v[172:175], v[204:207], v[0:3]
	s_setprio 0
	s_setprio 1
	v_mfma_f32_16x16x32_bf16 v[28:31], v[162:165], v[184:187], v[28:31]
	v_mfma_f32_16x16x32_bf16 v[24:27], v[176:179], v[184:187], v[24:27]
	v_mfma_f32_16x16x32_bf16 v[20:23], v[162:165], v[192:195], v[20:23]
	v_mfma_f32_16x16x32_bf16 v[16:19], v[176:179], v[192:195], v[16:19]
	v_mfma_f32_16x16x32_bf16 v[12:15], v[162:165], v[200:203], v[12:15]
	v_mfma_f32_16x16x32_bf16 v[8:11], v[176:179], v[200:203], v[8:11]
	v_mfma_f32_16x16x32_bf16 v[4:7], v[162:165], v[208:211], v[4:7]
	v_mfma_f32_16x16x32_bf16 v[0:3], v[176:179], v[208:211], v[0:3]
	s_setprio 0
	s_barrier
; #define G_STAGE(bufoff, gbase, voff) do { _Pragma("unroll") for (int _i = 0; _i < 2; ++_i) \
;         __builtin_amdgcn_global_load_lds((const unsigned*)((const char*)(gbase) + voff[_i]), (LAS unsigned*)(lds + (bufoff) + ldsw + _i * 8192), 16, 0, 0); } while (0)
; #define G_LDA(dst, b, h) do { _Pragma("unroll") for (int m = 0; m < 4; ++m) _Pragma("unroll") for (int k = 0; k < 2; ++k) dst[m][k] = *(const LAS bf16x8*)(lds + G_SA(b, h) + aoff + m * 2048 + k * 1024); } while (0)
; #define G_LDB(dst, b, h) do { _Pragma("unroll") for (int n = 0; n < 2; ++n) _Pragma("unroll") for (int k = 0; k < 2; ++k) dst[n][k] = *(const LAS bf16x8*)(lds + G_SB(b, h) + boff + n * 2048 + k * 1024); } while (0)
; #define G_MMA(ai, bj, At_, Bt_) do { __builtin_amdgcn_s_setprio(1); _Pragma("unroll") for (int m = 0; m < 4; ++m) _Pragma("unroll") for (int n = 0; n < 2; ++n) _Pragma("unroll") for (int k = 0; k < 2; ++k) \
;         acc[ai][bj][m][n] = __builtin_amdgcn_mfma_f32_16x16x32_bf16(Bt_[n][k], At_[m][k], acc[ai][bj][m][n], 0, 0, 0); __builtin_amdgcn_s_setprio(0); } while (0)
; #define WAIT_V(n) asm volatile("s_waitcnt vmcnt(" #n ")" ::: "memory")
; #define WAIT_L(n) asm volatile("s_waitcnt lgkmcnt(" #n ")" ::: "memory")
; #define BAR __builtin_amdgcn_s_barrier()
; #define SCHED __builtin_amdgcn_sched_barrier(0)
; template <class Get, class Epi>
; DI void gemm_loop(int ntiles, int ld, char* shm, const Get& get, const Epi& epi) {
;     ...
;             G_LDB(B0, 1, 0); G_LDB(B1, 1, 1); SCHED; G_LDA(At, 1, 0); G_STAGE(G_SA(0, 1), a2 + hstep, voffA);
;             WAIT_V(8); WAIT_L(0); BAR; G_MMA(0, 0, At, B0); G_MMA(0, 1, At, B1); BAR; SCHED;
	s_add_i32 s84, 0, 0x18000
	s_add_i32 s85, 0, 0x1c000
	v_add_u32_e32 v140, s84, v168
	v_add_u32_e32 v176, s85, v168
	ds_read_b128 v[128:131], v140
	ds_read_b128 v[132:135], v140 offset:1024
	ds_read_b128 v[136:139], v140 offset:2048
	ds_read_b128 v[140:143], v140 offset:3072
	ds_read_b128 v[158:161], v176
	ds_read_b128 v[162:165], v176 offset:1024
	ds_read_b128 v[172:175], v176 offset:2048
	ds_read_b128 v[176:179], v176 offset:3072
	s_add_u32 s4, s46, 0xb0000
	s_addc_u32 s5, s47, 0
	s_mov_b32 m0, s51
	v_lshl_add_u64 v[216:217], s[4:5], 0, v[146:147]
	ds_read_b128 v[180:183], v171 offset:32768
	ds_read_b128 v[184:187], v171 offset:33792
	ds_read_b128 v[188:191], v171 offset:34816
	ds_read_b128 v[192:195], v171 offset:35840
	ds_read_b128 v[196:199], v171 offset:36864
	ds_read_b128 v[200:203], v171 offset:37888
	ds_read_b128 v[204:207], v171 offset:38912
	ds_read_b128 v[208:211], v171 offset:39936
	global_load_lds_dwordx4 v[216:217], off
	v_lshl_add_u64 v[216:217], s[4:5], 0, v[150:151]
	s_mov_b32 m0, s52
	s_nop 0
	global_load_lds_dwordx4 v[216:217], off
	s_waitcnt vmcnt(8)
	s_waitcnt lgkmcnt(0)
	s_barrier
	s_setprio 1
	s_waitcnt lgkmcnt(0)
	v_mfma_f32_16x16x32_bf16 v[124:127], v[128:131], v[180:183], v[124:127]
	v_mfma_f32_16x16x32_bf16 v[120:123], v[136:139], v[180:183], v[120:123]
	v_mfma_f32_16x16x32_bf16 v[116:119], v[128:131], v[188:191], v[116:119]
	v_mfma_f32_16x16x32_bf16 v[112:115], v[136:139], v[188:191], v[112:115]
	v_mfma_f32_16x16x32_bf16 v[108:111], v[128:131], v[196:199], v[108:111]
	v_mfma_f32_16x16x32_bf16 v[104:107], v[136:139], v[196:199], v[104:107]
	v_mfma_f32_16x16x32_bf16 v[100:103], v[128:131], v[204:207], v[100:103]
	v_mfma_f32_16x16x32_bf16 v[96:99], v[136:139], v[204:207], v[96:99]
	s_setprio 0
	s_setprio 1
	v_mfma_f32_16x16x32_bf16 v[124:127], v[132:135], v[184:187], v[124:127]
	v_mfma_f32_16x16x32_bf16 v[120:123], v[140:143], v[184:187], v[120:123]
	v_mfma_f32_16x16x32_bf16 v[116:119], v[132:135], v[192:195], v[116:119]
	v_mfma_f32_16x16x32_bf16 v[112:115], v[140:143], v[192:195], v[112:115]
	v_mfma_f32_16x16x32_bf16 v[108:111], v[132:135], v[200:203], v[108:111]
	v_mfma_f32_16x16x32_bf16 v[104:107], v[140:143], v[200:203], v[104:107]
	v_mfma_f32_16x16x32_bf16 v[100:103], v[132:135], v[208:211], v[100:103]
	v_mfma_f32_16x16x32_bf16 v[96:99], v[140:143], v[208:211], v[96:99]
	s_setprio 0
	s_setprio 1
	v_mfma_f32_16x16x32_bf16 v[60:63], v[158:161], v[180:183], v[60:63]
	v_mfma_f32_16x16x32_bf16 v[56:59], v[172:175], v[180:183], v[56:59]
	v_mfma_f32_16x16x32_bf16 v[52:55], v[158:161], v[188:191], v[52:55]
	v_mfma_f32_16x16x32_bf16 v[48:51], v[172:175], v[188:191], v[48:51]
	v_mfma_f32_16x16x32_bf16 v[44:47], v[158:161], v[196:199], v[44:47]
	v_mfma_f32_16x16x32_bf16 v[40:43], v[172:175], v[196:199], v[40:43]
	v_mfma_f32_16x16x32_bf16 v[36:39], v[158:161], v[204:207], v[36:39]
	v_mfma_f32_16x16x32_bf16 v[32:35], v[172:175], v[204:207], v[32:35]
	s_setprio 0
	s_setprio 1
	v_mfma_f32_16x16x32_bf16 v[60:63], v[162:165], v[184:187], v[60:63]
	v_mfma_f32_16x16x32_bf16 v[56:59], v[176:179], v[184:187], v[56:59]
	v_mfma_f32_16x16x32_bf16 v[52:55], v[162:165], v[192:195], v[52:55]
	v_mfma_f32_16x16x32_bf16 v[48:51], v[176:179], v[192:195], v[48:51]
	v_mfma_f32_16x16x32_bf16 v[44:47], v[162:165], v[200:203], v[44:47]
	v_mfma_f32_16x16x32_bf16 v[40:43], v[176:179], v[200:203], v[40:43]
	v_mfma_f32_16x16x32_bf16 v[36:39], v[162:165], v[208:211], v[36:39]
	v_mfma_f32_16x16x32_bf16 v[32:35], v[176:179], v[208:211], v[32:35]
	s_setprio 0
	s_barrier
; #define G_STAGE(bufoff, gbase, voff) do { _Pragma("unroll") for (int _i = 0; _i < 2; ++_i) \
;         __builtin_amdgcn_global_load_lds((const unsigned*)((const char*)(gbase) + voff[_i]), (LAS unsigned*)(lds + (bufoff) + ldsw + _i * 8192), 16, 0, 0); } while (0)
; #define G_LDA(dst, b, h) do { _Pragma("unroll") for (int m = 0; m < 4; ++m) _Pragma("unroll") for (int k = 0; k < 2; ++k) dst[m][k] = *(const LAS bf16x8*)(lds + G_SA(b, h) + aoff + m * 2048 + k * 1024); } while (0)
; #define G_MMA(ai, bj, At_, Bt_) do { __builtin_amdgcn_s_setprio(1); _Pragma("unroll") for (int m = 0; m < 4; ++m) _Pragma("unroll") for (int n = 0; n < 2; ++n) _Pragma("unroll") for (int k = 0; k < 2; ++k) \
;         acc[ai][bj][m][n] = __builtin_amdgcn_mfma_f32_16x16x32_bf16(Bt_[n][k], At_[m][k], acc[ai][bj][m][n], 0, 0, 0); __builtin_amdgcn_s_setprio(0); } while (0)
; #define WAIT_V(n) asm volatile("s_waitcnt vmcnt(" #n ")" ::: "memory")
; #define WAIT_L(n) asm volatile("s_waitcnt lgkmcnt(" #n ")" ::: "memory")
; #define BAR __builtin_amdgcn_s_barrier()
; #define SCHED __builtin_amdgcn_sched_barrier(0)
; template <class Get, class Epi>
; DI void gemm_loop(int ntiles, int ld, char* shm, const Get& get, const Epi& epi) {
;     ...
;             G_LDA(At, 1, 1); G_STAGE(G_SB(1, 0), b3, voffB); G_STAGE(G_SB(1, 1), b3 + hstep, voffB); G_STAGE(G_SA(1, 0), a3, voffA);
;             WAIT_V(8); WAIT_L(0); BAR; G_MMA(1, 0, At, B0); G_MMA(1, 1, At, B1); BAR; SCHED;
	s_add_i32 s4, s84, s48
	v_lshl_add_u64 v[144:145], v[144:145], 0, s[10:11]
	s_mov_b32 m0, s4
	ds_read_b128 v[180:183], v171 offset:49152
	ds_read_b128 v[184:187], v171 offset:50176
	ds_read_b128 v[188:191], v171 offset:51200
	ds_read_b128 v[192:195], v171 offset:52224
	ds_read_b128 v[196:199], v171 offset:53248
	ds_read_b128 v[200:203], v171 offset:54272
	ds_read_b128 v[204:207], v171 offset:55296
	ds_read_b128 v[208:211], v171 offset:56320
	global_load_lds_dwordx4 v[144:145], off
	s_add_i32 m0, s4, 0x2000
	s_add_u32 s4, s44, 0xb0080
	v_lshl_add_u64 v[144:145], v[166:167], 0, s[10:11]
	s_addc_u32 s5, s45, 0
	s_add_i32 s44, s85, s48
	global_load_lds_dwordx4 v[144:145], off
	v_lshl_add_u64 v[144:145], s[4:5], 0, v[148:149]
	s_mov_b32 m0, s44
	s_nop 0
	global_load_lds_dwordx4 v[144:145], off
	v_lshl_add_u64 v[144:145], s[4:5], 0, v[152:153]
	s_add_i32 m0, s44, 0x2000
	s_nop 0
	global_load_lds_dwordx4 v[144:145], off
	v_lshl_add_u64 v[144:145], v[212:213], 0, s[10:11]
	s_mov_b32 m0, s55
	s_nop 0
	global_load_lds_dwordx4 v[144:145], off
	v_lshl_add_u64 v[144:145], v[214:215], 0, s[10:11]
	s_mov_b32 m0, s56
	s_nop 0
	global_load_lds_dwordx4 v[144:145], off
	s_waitcnt vmcnt(8)
	s_waitcnt lgkmcnt(0)
	s_barrier
	s_setprio 1
	s_waitcnt lgkmcnt(0)
	v_mfma_f32_16x16x32_bf16 v[92:95], v[128:131], v[180:183], v[92:95]
	v_mfma_f32_16x16x32_bf16 v[88:91], v[136:139], v[180:183], v[88:91]
	v_mfma_f32_16x16x32_bf16 v[84:87], v[128:131], v[188:191], v[84:87]
	v_mfma_f32_16x16x32_bf16 v[80:83], v[136:139], v[188:191], v[80:83]
	v_mfma_f32_16x16x32_bf16 v[76:79], v[128:131], v[196:199], v[76:79]
	v_mfma_f32_16x16x32_bf16 v[72:75], v[136:139], v[196:199], v[72:75]
	v_mfma_f32_16x16x32_bf16 v[68:71], v[128:131], v[204:207], v[68:71]
	v_mfma_f32_16x16x32_bf16 v[64:67], v[136:139], v[204:207], v[64:67]
	s_setprio 0
	s_setprio 1
	v_mfma_f32_16x16x32_bf16 v[92:95], v[132:135], v[184:187], v[92:95]
	v_mfma_f32_16x16x32_bf16 v[88:91], v[140:143], v[184:187], v[88:91]
	v_mfma_f32_16x16x32_bf16 v[84:87], v[132:135], v[192:195], v[84:87]
	v_mfma_f32_16x16x32_bf16 v[80:83], v[140:143], v[192:195], v[80:83]
	v_mfma_f32_16x16x32_bf16 v[76:79], v[132:135], v[200:203], v[76:79]
	v_mfma_f32_16x16x32_bf16 v[72:75], v[140:143], v[200:203], v[72:75]
	v_mfma_f32_16x16x32_bf16 v[68:71], v[132:135], v[208:211], v[68:71]
	v_mfma_f32_16x16x32_bf16 v[64:67], v[140:143], v[208:211], v[64:67]
	s_setprio 0
	s_setprio 1
	v_mfma_f32_16x16x32_bf16 v[28:31], v[158:161], v[180:183], v[28:31]
	v_mfma_f32_16x16x32_bf16 v[24:27], v[172:175], v[180:183], v[24:27]
	v_mfma_f32_16x16x32_bf16 v[20:23], v[158:161], v[188:191], v[20:23]
	v_mfma_f32_16x16x32_bf16 v[16:19], v[172:175], v[188:191], v[16:19]
	v_mfma_f32_16x16x32_bf16 v[12:15], v[158:161], v[196:199], v[12:15]
	v_mfma_f32_16x16x32_bf16 v[8:11], v[172:175], v[196:199], v[8:11]
	v_mfma_f32_16x16x32_bf16 v[4:7], v[158:161], v[204:207], v[4:7]
	v_mfma_f32_16x16x32_bf16 v[0:3], v[172:175], v[204:207], v[0:3]
	s_setprio 0
	s_setprio 1
	v_mfma_f32_16x16x32_bf16 v[28:31], v[162:165], v[184:187], v[28:31]
	v_mfma_f32_16x16x32_bf16 v[24:27], v[176:179], v[184:187], v[24:27]
	v_mfma_f32_16x16x32_bf16 v[20:23], v[162:165], v[192:195], v[20:23]
	v_mfma_f32_16x16x32_bf16 v[16:19], v[176:179], v[192:195], v[16:19]
	v_mfma_f32_16x16x32_bf16 v[12:15], v[162:165], v[200:203], v[12:15]
	v_mfma_f32_16x16x32_bf16 v[8:11], v[176:179], v[200:203], v[8:11]
	v_mfma_f32_16x16x32_bf16 v[4:7], v[162:165], v[208:211], v[4:7]
	v_mfma_f32_16x16x32_bf16 v[0:3], v[176:179], v[208:211], v[0:3]
	s_setprio 0
	s_barrier
	s_add_u32 s81, s81, 0x100
	s_addc_u32 s82, s82, 0
	s_cmp_ge_u32 s83, s79
	s_mov_b64 s[4:5], s[14:15]
	s_mov_b32 s44, s83
	s_cbranch_scc0 .LBB0_2892

; #define G_STAGE(bufoff, gbase, voff) do { _Pragma("unroll") for (int _i = 0; _i < 2; ++_i) \
;         __builtin_amdgcn_global_load_lds((const unsigned*)((const char*)(gbase) + voff[_i]), (LAS unsigned*)(lds + (bufoff) + ldsw + _i * 8192), 16, 0, 0); } while (0)
; #define G_LDA(dst, b, h) do { _Pragma("unroll") for (int m = 0; m < 4; ++m) _Pragma("unroll") for (int k = 0; k < 2; ++k) dst[m][k] = *(const LAS bf16x8*)(lds + G_SA(b, h) + aoff + m * 2048 + k * 1024); } while (0)
; #define G_MMA(ai, bj, At_, Bt_) do { __builtin_amdgcn_s_setprio(1); _Pragma("unroll") for (int m = 0; m < 4; ++m) _Pragma("unroll") for (int n = 0; n < 2; ++n) _Pragma("unroll") for (int k = 0; k < 2; ++k) \
;         acc[ai][bj][m][n] = __builtin_amdgcn_mfma_f32_16x16x32_bf16(Bt_[n][k], At_[m][k], acc[ai][bj][m][n], 0, 0, 0); __builtin_amdgcn_s_setprio(0); } while (0)
; #define WAIT_V(n) asm volatile("s_waitcnt vmcnt(" #n ")" ::: "memory")
; #define WAIT_L(n) asm volatile("s_waitcnt lgkmcnt(" #n ")" ::: "memory")
; #define BAR __builtin_amdgcn_s_barrier()
; #define SCHED __builtin_amdgcn_sched_barrier(0)
; template <class Get, class Epi>
; DI void gemm_loop(int ntiles, int ld, char* shm, const Get& get, const Epi& epi) {
;     ...
;             WAIT_V(8); WAIT_L(0); BAR; G_MMA(0, 0, At, B0); G_MMA(0, 1, At, B1); BAR; SCHED;
;             G_LDA(At, 0, 1); G_STAGE(G_SB(0, 0), b2, voffB); G_STAGE(G_SB(0, 1), b2 + hstep, voffB); G_STAGE(G_SA(0, 0), a2, voffA);
.Lrj_3141_0:
	s_waitcnt lgkmcnt(0)
	s_barrier
	s_setprio 1
	s_waitcnt lgkmcnt(0)
	v_mfma_f32_16x16x32_bf16 v[124:127], v[144:147], v[176:179], 0
	v_mfma_f32_16x16x32_bf16 v[120:123], v[152:155], v[176:179], 0
	v_mfma_f32_16x16x32_bf16 v[116:119], v[144:147], v[184:187], 0
	v_mfma_f32_16x16x32_bf16 v[112:115], v[152:155], v[184:187], 0
	v_mfma_f32_16x16x32_bf16 v[100:103], v[144:147], v[192:195], 0
	v_mfma_f32_16x16x32_bf16 v[96:99], v[152:155], v[192:195], 0
	v_mfma_f32_16x16x32_bf16 v[84:87], v[144:147], v[200:203], 0
	v_mfma_f32_16x16x32_bf16 v[80:83], v[152:155], v[200:203], 0
	s_setprio 0
	s_setprio 1
	v_mfma_f32_16x16x32_bf16 v[124:127], v[148:151], v[180:183], v[124:127]
	v_mfma_f32_16x16x32_bf16 v[120:123], v[156:159], v[180:183], v[120:123]
	v_mfma_f32_16x16x32_bf16 v[116:119], v[148:151], v[188:191], v[116:119]
	v_mfma_f32_16x16x32_bf16 v[112:115], v[156:159], v[188:191], v[112:115]
	v_mfma_f32_16x16x32_bf16 v[100:103], v[148:151], v[196:199], v[100:103]
	v_mfma_f32_16x16x32_bf16 v[96:99], v[156:159], v[196:199], v[96:99]
	v_mfma_f32_16x16x32_bf16 v[84:87], v[148:151], v[204:207], v[84:87]
	v_mfma_f32_16x16x32_bf16 v[80:83], v[156:159], v[204:207], v[80:83]
	s_setprio 0
	s_setprio 1
	v_mfma_f32_16x16x32_bf16 v[108:111], v[160:163], v[176:179], 0
	v_mfma_f32_16x16x32_bf16 v[104:107], v[168:171], v[176:179], 0
	v_mfma_f32_16x16x32_bf16 v[92:95], v[160:163], v[184:187], 0
	v_mfma_f32_16x16x32_bf16 v[88:91], v[168:171], v[184:187], 0
	v_mfma_f32_16x16x32_bf16 v[76:79], v[160:163], v[192:195], 0
	v_mfma_f32_16x16x32_bf16 v[72:75], v[168:171], v[192:195], 0
	v_mfma_f32_16x16x32_bf16 v[68:71], v[160:163], v[200:203], 0
	v_mfma_f32_16x16x32_bf16 v[64:67], v[168:171], v[200:203], 0
	s_setprio 0
	s_setprio 1
	v_mfma_f32_16x16x32_bf16 v[108:111], v[164:167], v[180:183], v[108:111]
	v_mfma_f32_16x16x32_bf16 v[104:107], v[172:175], v[180:183], v[104:107]
	v_mfma_f32_16x16x32_bf16 v[92:95], v[164:167], v[188:191], v[92:95]
	v_mfma_f32_16x16x32_bf16 v[88:91], v[172:175], v[188:191], v[88:91]
	v_mfma_f32_16x16x32_bf16 v[76:79], v[164:167], v[196:199], v[76:79]
	v_mfma_f32_16x16x32_bf16 v[72:75], v[172:175], v[196:199], v[72:75]
	v_mfma_f32_16x16x32_bf16 v[68:71], v[164:167], v[204:207], v[68:71]
	v_mfma_f32_16x16x32_bf16 v[64:67], v[172:175], v[204:207], v[64:67]
	s_setprio 0
	s_barrier
	s_add_i32 s71, s57, s50
	v_lshl_add_u64 v[208:209], s[14:15], 0, v[130:131]
	s_mov_b32 m0, s71
	ds_read_b128 v[176:179], v143 offset:16384
	ds_read_b128 v[180:183], v143 offset:17408
	ds_read_b128 v[184:187], v143 offset:18432
	ds_read_b128 v[188:191], v143 offset:19456
	ds_read_b128 v[192:195], v143 offset:20480
	ds_read_b128 v[196:199], v143 offset:21504
	ds_read_b128 v[200:203], v143 offset:22528
	ds_read_b128 v[204:207], v143 offset:23552
	global_load_lds_dwordx4 v[208:209], off
	s_add_i32 m0, s71, 0x2000
	s_add_u32 s72, s14, 0x40000
	v_lshl_add_u64 v[210:211], s[14:15], 0, v[134:135]
	s_addc_u32 s73, s15, 0
	s_add_i32 s71, s58, s50
	global_load_lds_dwordx4 v[210:211], off
	v_lshl_add_u64 v[212:213], s[72:73], 0, v[130:131]
	s_mov_b32 m0, s71
	v_lshl_add_u64 v[214:215], s[46:47], 0, v[132:133]
	global_load_lds_dwordx4 v[212:213], off
	v_lshl_add_u64 v[212:213], s[72:73], 0, v[134:135]
	s_add_i32 m0, s71, 0x2000
	s_nop 0
	global_load_lds_dwordx4 v[212:213], off
	v_lshl_add_u64 v[212:213], s[46:47], 0, v[128:129]
	s_mov_b32 m0, s35
	s_nop 0
	global_load_lds_dwordx4 v[212:213], off
	s_mov_b32 m0, s51
	s_nop 0
	global_load_lds_dwordx4 v[214:215], off
	s_cmp_lg_u32 s100, 0
	s_cbranch_scc0 .Lrf_3141_1
	s_waitcnt vmcnt(16)
	s_branch .Lrj_3141_1

; #define G_STAGE(bufoff, gbase, voff) do { _Pragma("unroll") for (int _i = 0; _i < 2; ++_i) \
;         __builtin_amdgcn_global_load_lds((const unsigned*)((const char*)(gbase) + voff[_i]), (LAS unsigned*)(lds + (bufoff) + ldsw + _i * 8192), 16, 0, 0); } while (0)
; #define G_LDA(dst, b, h) do { _Pragma("unroll") for (int m = 0; m < 4; ++m) _Pragma("unroll") for (int k = 0; k < 2; ++k) dst[m][k] = *(const LAS bf16x8*)(lds + G_SA(b, h) + aoff + m * 2048 + k * 1024); } while (0)
; #define G_LDB(dst, b, h) do { _Pragma("unroll") for (int n = 0; n < 2; ++n) _Pragma("unroll") for (int k = 0; k < 2; ++k) dst[n][k] = *(const LAS bf16x8*)(lds + G_SB(b, h) + boff + n * 2048 + k * 1024); } while (0)
; #define G_MMA(ai, bj, At_, Bt_) do { __builtin_amdgcn_s_setprio(1); _Pragma("unroll") for (int m = 0; m < 4; ++m) _Pragma("unroll") for (int n = 0; n < 2; ++n) _Pragma("unroll") for (int k = 0; k < 2; ++k) \
;         acc[ai][bj][m][n] = __builtin_amdgcn_mfma_f32_16x16x32_bf16(Bt_[n][k], At_[m][k], acc[ai][bj][m][n], 0, 0, 0); __builtin_amdgcn_s_setprio(0); } while (0)
; #define WAIT_V(n) asm volatile("s_waitcnt vmcnt(" #n ")" ::: "memory")
; #define WAIT_L(n) asm volatile("s_waitcnt lgkmcnt(" #n ")" ::: "memory")
; #define BAR __builtin_amdgcn_s_barrier()
; #define SCHED __builtin_amdgcn_sched_barrier(0)
; template <class Get, class Epi>
; DI void gemm_loop(int ntiles, int ld, char* shm, const Get& get, const Epi& epi) {
;     ...
;             WAIT_V(8); WAIT_L(0); BAR; G_MMA(1, 0, At, B0); G_MMA(1, 1, At, B1); BAR; SCHED;
;             G_LDB(B0, 1, 0); G_LDB(B1, 1, 1); SCHED; G_LDA(At, 1, 0); G_STAGE(G_SA(0, 1), a2 + hstep, voffA);
;             WAIT_V(8); WAIT_L(0); BAR; G_MMA(0, 0, At, B0); G_MMA(0, 1, At, B1); BAR; SCHED;
.Lrj_3141_1:
	s_waitcnt lgkmcnt(0)
	s_barrier
	s_setprio 1
	s_waitcnt lgkmcnt(0)
	v_mfma_f32_16x16x32_bf16 v[60:63], v[144:147], v[176:179], 0
	v_mfma_f32_16x16x32_bf16 v[56:59], v[152:155], v[176:179], 0
	v_mfma_f32_16x16x32_bf16 v[52:55], v[144:147], v[184:187], 0
	v_mfma_f32_16x16x32_bf16 v[48:51], v[152:155], v[184:187], 0
	v_mfma_f32_16x16x32_bf16 v[36:39], v[144:147], v[192:195], 0
	v_mfma_f32_16x16x32_bf16 v[32:35], v[152:155], v[192:195], 0
	v_mfma_f32_16x16x32_bf16 v[20:23], v[144:147], v[200:203], 0
	v_mfma_f32_16x16x32_bf16 v[16:19], v[152:155], v[200:203], 0
	s_setprio 0
	s_setprio 1
	v_mfma_f32_16x16x32_bf16 v[60:63], v[148:151], v[180:183], v[60:63]
	v_mfma_f32_16x16x32_bf16 v[56:59], v[156:159], v[180:183], v[56:59]
	v_mfma_f32_16x16x32_bf16 v[52:55], v[148:151], v[188:191], v[52:55]
	v_mfma_f32_16x16x32_bf16 v[48:51], v[156:159], v[188:191], v[48:51]
	v_mfma_f32_16x16x32_bf16 v[36:39], v[148:151], v[196:199], v[36:39]
	v_mfma_f32_16x16x32_bf16 v[32:35], v[156:159], v[196:199], v[32:35]
	v_mfma_f32_16x16x32_bf16 v[20:23], v[148:151], v[204:207], v[20:23]
	v_mfma_f32_16x16x32_bf16 v[16:19], v[156:159], v[204:207], v[16:19]
	s_setprio 0
	s_setprio 1
	v_mfma_f32_16x16x32_bf16 v[44:47], v[160:163], v[176:179], 0
	v_mfma_f32_16x16x32_bf16 v[40:43], v[168:171], v[176:179], 0
	v_mfma_f32_16x16x32_bf16 v[28:31], v[160:163], v[184:187], 0
	v_mfma_f32_16x16x32_bf16 v[24:27], v[168:171], v[184:187], 0
	v_mfma_f32_16x16x32_bf16 v[12:15], v[160:163], v[192:195], 0
	v_mfma_f32_16x16x32_bf16 v[8:11], v[168:171], v[192:195], 0
	v_mfma_f32_16x16x32_bf16 v[4:7], v[160:163], v[200:203], 0
	v_mfma_f32_16x16x32_bf16 v[0:3], v[168:171], v[200:203], 0
	s_setprio 0
	s_setprio 1
	v_mfma_f32_16x16x32_bf16 v[44:47], v[164:167], v[180:183], v[44:47]
	v_mfma_f32_16x16x32_bf16 v[40:43], v[172:175], v[180:183], v[40:43]
	v_mfma_f32_16x16x32_bf16 v[28:31], v[164:167], v[188:191], v[28:31]
	v_mfma_f32_16x16x32_bf16 v[24:27], v[172:175], v[188:191], v[24:27]
	v_mfma_f32_16x16x32_bf16 v[12:15], v[164:167], v[196:199], v[12:15]
	v_mfma_f32_16x16x32_bf16 v[8:11], v[172:175], v[196:199], v[8:11]
	v_mfma_f32_16x16x32_bf16 v[4:7], v[164:167], v[204:207], v[4:7]
	v_mfma_f32_16x16x32_bf16 v[0:3], v[172:175], v[204:207], v[0:3]
	s_setprio 0
	s_barrier
	s_add_i32 s71, 0, 0x18000
	s_add_i32 s72, 0, 0x1c000
	v_add_u32_e32 v156, s71, v140
	v_add_u32_e32 v172, s72, v140
	ds_read_b128 v[144:147], v156
	ds_read_b128 v[148:151], v156 offset:1024
	ds_read_b128 v[152:155], v156 offset:2048
	ds_read_b128 v[156:159], v156 offset:3072
	ds_read_b128 v[160:163], v172
	ds_read_b128 v[164:167], v172 offset:1024
	ds_read_b128 v[168:171], v172 offset:2048
	ds_read_b128 v[172:175], v172 offset:3072
	s_add_u32 s46, s46, 0x40000
	s_addc_u32 s47, s47, 0
	s_mov_b32 m0, s52
	v_lshl_add_u64 v[216:217], s[46:47], 0, v[128:129]
	ds_read_b128 v[176:179], v143 offset:32768
	ds_read_b128 v[180:183], v143 offset:33792
	ds_read_b128 v[184:187], v143 offset:34816
	ds_read_b128 v[188:191], v143 offset:35840
	ds_read_b128 v[192:195], v143 offset:36864
	ds_read_b128 v[196:199], v143 offset:37888
	ds_read_b128 v[200:203], v143 offset:38912
	ds_read_b128 v[204:207], v143 offset:39936
	global_load_lds_dwordx4 v[216:217], off
	v_lshl_add_u64 v[216:217], s[46:47], 0, v[132:133]
	s_mov_b32 m0, s53
	s_nop 0
	global_load_lds_dwordx4 v[216:217], off
	s_waitcnt vmcnt(8)
	s_waitcnt lgkmcnt(0)
	s_barrier
	s_setprio 1
	s_waitcnt lgkmcnt(0)
	v_mfma_f32_16x16x32_bf16 v[124:127], v[144:147], v[176:179], v[124:127]
	v_mfma_f32_16x16x32_bf16 v[120:123], v[152:155], v[176:179], v[120:123]
	v_mfma_f32_16x16x32_bf16 v[116:119], v[144:147], v[184:187], v[116:119]
	v_mfma_f32_16x16x32_bf16 v[112:115], v[152:155], v[184:187], v[112:115]
	v_mfma_f32_16x16x32_bf16 v[100:103], v[144:147], v[192:195], v[100:103]
	v_mfma_f32_16x16x32_bf16 v[96:99], v[152:155], v[192:195], v[96:99]
	v_mfma_f32_16x16x32_bf16 v[84:87], v[144:147], v[200:203], v[84:87]
	v_mfma_f32_16x16x32_bf16 v[80:83], v[152:155], v[200:203], v[80:83]
	s_setprio 0
	s_setprio 1
	v_mfma_f32_16x16x32_bf16 v[124:127], v[148:151], v[180:183], v[124:127]
	v_mfma_f32_16x16x32_bf16 v[120:123], v[156:159], v[180:183], v[120:123]
	v_mfma_f32_16x16x32_bf16 v[116:119], v[148:151], v[188:191], v[116:119]
	v_mfma_f32_16x16x32_bf16 v[112:115], v[156:159], v[188:191], v[112:115]
	v_mfma_f32_16x16x32_bf16 v[100:103], v[148:151], v[196:199], v[100:103]
	v_mfma_f32_16x16x32_bf16 v[96:99], v[156:159], v[196:199], v[96:99]
	v_mfma_f32_16x16x32_bf16 v[84:87], v[148:151], v[204:207], v[84:87]
	v_mfma_f32_16x16x32_bf16 v[80:83], v[156:159], v[204:207], v[80:83]
	s_setprio 0
	s_setprio 1
	v_mfma_f32_16x16x32_bf16 v[108:111], v[160:163], v[176:179], v[108:111]
	v_mfma_f32_16x16x32_bf16 v[104:107], v[168:171], v[176:179], v[104:107]
	v_mfma_f32_16x16x32_bf16 v[92:95], v[160:163], v[184:187], v[92:95]
	v_mfma_f32_16x16x32_bf16 v[88:91], v[168:171], v[184:187], v[88:91]
	v_mfma_f32_16x16x32_bf16 v[76:79], v[160:163], v[192:195], v[76:79]
	v_mfma_f32_16x16x32_bf16 v[72:75], v[168:171], v[192:195], v[72:75]
	v_mfma_f32_16x16x32_bf16 v[68:71], v[160:163], v[200:203], v[68:71]
	v_mfma_f32_16x16x32_bf16 v[64:67], v[168:171], v[200:203], v[64:67]
	s_setprio 0
	s_setprio 1
	v_mfma_f32_16x16x32_bf16 v[108:111], v[164:167], v[180:183], v[108:111]
	v_mfma_f32_16x16x32_bf16 v[104:107], v[172:175], v[180:183], v[104:107]
	v_mfma_f32_16x16x32_bf16 v[92:95], v[164:167], v[188:191], v[92:95]
	v_mfma_f32_16x16x32_bf16 v[88:91], v[172:175], v[188:191], v[88:91]
	v_mfma_f32_16x16x32_bf16 v[76:79], v[164:167], v[196:199], v[76:79]
	v_mfma_f32_16x16x32_bf16 v[72:75], v[172:175], v[196:199], v[72:75]
	v_mfma_f32_16x16x32_bf16 v[68:71], v[164:167], v[204:207], v[68:71]
	v_mfma_f32_16x16x32_bf16 v[64:67], v[172:175], v[204:207], v[64:67]
	s_setprio 0
	s_barrier
; #define G_STAGE(bufoff, gbase, voff) do { _Pragma("unroll") for (int _i = 0; _i < 2; ++_i) \
;         __builtin_amdgcn_global_load_lds((const unsigned*)((const char*)(gbase) + voff[_i]), (LAS unsigned*)(lds + (bufoff) + ldsw + _i * 8192), 16, 0, 0); } while (0)
; #define G_LDA(dst, b, h) do { _Pragma("unroll") for (int m = 0; m < 4; ++m) _Pragma("unroll") for (int k = 0; k < 2; ++k) dst[m][k] = *(const LAS bf16x8*)(lds + G_SA(b, h) + aoff + m * 2048 + k * 1024); } while (0)
; #define G_LDB(dst, b, h) do { _Pragma("unroll") for (int n = 0; n < 2; ++n) _Pragma("unroll") for (int k = 0; k < 2; ++k) dst[n][k] = *(const LAS bf16x8*)(lds + G_SB(b, h) + boff + n * 2048 + k * 1024); } while (0)
; #define G_MMA(ai, bj, At_, Bt_) do { __builtin_amdgcn_s_setprio(1); _Pragma("unroll") for (int m = 0; m < 4; ++m) _Pragma("unroll") for (int n = 0; n < 2; ++n) _Pragma("unroll") for (int k = 0; k < 2; ++k) \
;         acc[ai][bj][m][n] = __builtin_amdgcn_mfma_f32_16x16x32_bf16(Bt_[n][k], At_[m][k], acc[ai][bj][m][n], 0, 0, 0); __builtin_amdgcn_s_setprio(0); } while (0)
; #define WAIT_V(n) asm volatile("s_waitcnt vmcnt(" #n ")" ::: "memory")
; #define WAIT_L(n) asm volatile("s_waitcnt lgkmcnt(" #n ")" ::: "memory")
; #define BAR __builtin_amdgcn_s_barrier()
; #define SCHED __builtin_amdgcn_sched_barrier(0)
; template <class Get, class Epi>
; DI void gemm_loop(int ntiles, int ld, char* shm, const Get& get, const Epi& epi) {
;     ...
;             G_LDB(B0, 0, 0); G_LDB(B1, 0, 1); SCHED; G_LDA(At, 0, 0); G_STAGE(G_SA(1, 1), a1 + hstep, voffA);
;             WAIT_V(8); WAIT_L(0); BAR; G_MMA(0, 0, At, B0); G_MMA(0, 1, At, B1); BAR; SCHED;
;     ...
;             G_LDA(At, 1, 1); G_STAGE(G_SB(1, 0), b3, voffB); G_STAGE(G_SB(1, 1), b3 + hstep, voffB); G_STAGE(G_SA(1, 0), a3, voffA);
;             WAIT_V(8); WAIT_L(0); BAR; G_MMA(1, 0, At, B0); G_MMA(1, 1, At, B1); BAR; SCHED;
;         }
	s_add_i32 s46, s71, s50
	v_lshl_add_u64 v[208:209], v[208:209], 0, s[8:9]
	s_mov_b32 m0, s46
	ds_read_b128 v[176:179], v143 offset:49152
	ds_read_b128 v[180:183], v143 offset:50176
	ds_read_b128 v[184:187], v143 offset:51200
	ds_read_b128 v[188:191], v143 offset:52224
	ds_read_b128 v[192:195], v143 offset:53248
	ds_read_b128 v[196:199], v143 offset:54272
	ds_read_b128 v[200:203], v143 offset:55296
	ds_read_b128 v[204:207], v143 offset:56320
	global_load_lds_dwordx4 v[208:209], off
	s_add_i32 m0, s46, 0x2000
	s_add_u32 s14, s14, 0x40080
	v_lshl_add_u64 v[208:209], v[210:211], 0, s[8:9]
	s_addc_u32 s15, s15, 0
	s_add_i32 s46, s72, s50
	global_load_lds_dwordx4 v[208:209], off
	v_lshl_add_u64 v[208:209], s[14:15], 0, v[130:131]
	s_mov_b32 m0, s46
	s_nop 0
	global_load_lds_dwordx4 v[208:209], off
	v_lshl_add_u64 v[208:209], s[14:15], 0, v[134:135]
	s_add_i32 m0, s46, 0x2000
	s_nop 0
	global_load_lds_dwordx4 v[208:209], off
	v_lshl_add_u64 v[208:209], v[212:213], 0, s[8:9]
	s_mov_b32 m0, s55
	s_nop 0
	global_load_lds_dwordx4 v[208:209], off
	v_lshl_add_u64 v[208:209], v[214:215], 0, s[8:9]
	s_mov_b32 m0, s56
	s_nop 0
	global_load_lds_dwordx4 v[208:209], off
	s_waitcnt vmcnt(8)
	s_waitcnt lgkmcnt(0)
	s_barrier
	s_setprio 1
	s_waitcnt lgkmcnt(0)
	v_mfma_f32_16x16x32_bf16 v[60:63], v[144:147], v[176:179], v[60:63]
	v_mfma_f32_16x16x32_bf16 v[56:59], v[152:155], v[176:179], v[56:59]
	v_mfma_f32_16x16x32_bf16 v[52:55], v[144:147], v[184:187], v[52:55]
	v_mfma_f32_16x16x32_bf16 v[48:51], v[152:155], v[184:187], v[48:51]
	v_mfma_f32_16x16x32_bf16 v[36:39], v[144:147], v[192:195], v[36:39]
	v_mfma_f32_16x16x32_bf16 v[32:35], v[152:155], v[192:195], v[32:35]
	v_mfma_f32_16x16x32_bf16 v[20:23], v[144:147], v[200:203], v[20:23]
	v_mfma_f32_16x16x32_bf16 v[16:19], v[152:155], v[200:203], v[16:19]
	s_setprio 0
	s_setprio 1
	v_mfma_f32_16x16x32_bf16 v[60:63], v[148:151], v[180:183], v[60:63]
	v_mfma_f32_16x16x32_bf16 v[56:59], v[156:159], v[180:183], v[56:59]
	v_mfma_f32_16x16x32_bf16 v[52:55], v[148:151], v[188:191], v[52:55]
	v_mfma_f32_16x16x32_bf16 v[48:51], v[156:159], v[188:191], v[48:51]
	v_mfma_f32_16x16x32_bf16 v[36:39], v[148:151], v[196:199], v[36:39]
	v_mfma_f32_16x16x32_bf16 v[32:35], v[156:159], v[196:199], v[32:35]
	v_mfma_f32_16x16x32_bf16 v[20:23], v[148:151], v[204:207], v[20:23]
	v_mfma_f32_16x16x32_bf16 v[16:19], v[156:159], v[204:207], v[16:19]
	s_setprio 0
	s_setprio 1
	v_mfma_f32_16x16x32_bf16 v[44:47], v[160:163], v[176:179], v[44:47]
	v_mfma_f32_16x16x32_bf16 v[40:43], v[168:171], v[176:179], v[40:43]
	v_mfma_f32_16x16x32_bf16 v[28:31], v[160:163], v[184:187], v[28:31]
	v_mfma_f32_16x16x32_bf16 v[24:27], v[168:171], v[184:187], v[24:27]
	v_mfma_f32_16x16x32_bf16 v[12:15], v[160:163], v[192:195], v[12:15]
	v_mfma_f32_16x16x32_bf16 v[8:11], v[168:171], v[192:195], v[8:11]
	v_mfma_f32_16x16x32_bf16 v[4:7], v[160:163], v[200:203], v[4:7]
	v_mfma_f32_16x16x32_bf16 v[0:3], v[168:171], v[200:203], v[0:3]
	s_setprio 0
	s_setprio 1
	v_mfma_f32_16x16x32_bf16 v[44:47], v[164:167], v[180:183], v[44:47]
	v_mfma_f32_16x16x32_bf16 v[40:43], v[172:175], v[180:183], v[40:43]
	v_mfma_f32_16x16x32_bf16 v[28:31], v[164:167], v[188:191], v[28:31]
	v_mfma_f32_16x16x32_bf16 v[24:27], v[172:175], v[188:191], v[24:27]
	v_mfma_f32_16x16x32_bf16 v[12:15], v[164:167], v[196:199], v[12:15]
	v_mfma_f32_16x16x32_bf16 v[8:11], v[172:175], v[196:199], v[8:11]
	v_mfma_f32_16x16x32_bf16 v[4:7], v[164:167], v[204:207], v[4:7]
	v_mfma_f32_16x16x32_bf16 v[0:3], v[172:175], v[204:207], v[0:3]
	s_setprio 0
	s_barrier
	s_add_i32 s70, s70, 2
	s_add_u32 s48, s48, 0x100
	s_addc_u32 s49, s49, 0
	s_add_u32 s64, s64, 0x100
	s_addc_u32 s65, s65, 0
	s_cmp_gt_u32 s70, 13
	s_cbranch_scc0 .LBB0_3141
	s_branch .Lpost_3141
.LBB0_3141:
	ds_read_b128 v[144:147], v141
	ds_read_b128 v[148:151], v141 offset:1024
	ds_read_b128 v[152:155], v141 offset:2048
	ds_read_b128 v[156:159], v141 offset:3072
	ds_read_b128 v[160:163], v142
	ds_read_b128 v[164:167], v142 offset:1024
	ds_read_b128 v[168:171], v142 offset:2048
	ds_read_b128 v[172:175], v142 offset:3072
	s_add_u32 s14, s48, 0xfffc0080
	s_addc_u32 s15, s49, -1
	s_cmp_eq_u32 s70, 12
	s_cselect_b32 s47, s11, s15
	s_cselect_b32 s46, s39, s14
	s_cselect_b32 s15, s41, s65
	s_cselect_b32 s14, s63, s64
	v_lshl_add_u64 v[208:209], s[48:49], 0, v[136:137]
	s_add_i32 m0, s35, 0xc000
	ds_read_b128 v[176:179], v143
	ds_read_b128 v[180:183], v143 offset:1024
	ds_read_b128 v[184:187], v143 offset:2048
	ds_read_b128 v[188:191], v143 offset:3072
	ds_read_b128 v[192:195], v143 offset:4096
	ds_read_b128 v[196:199], v143 offset:5120
	ds_read_b128 v[200:203], v143 offset:6144
	ds_read_b128 v[204:207], v143 offset:7168
	global_load_lds_dwordx4 v[208:209], off
	v_lshl_add_u64 v[208:209], s[48:49], 0, v[138:139]
	s_add_i32 m0, s35, 0xe000
	s_nop 0
	global_load_lds_dwordx4 v[208:209], off
	s_waitcnt vmcnt(8)
	s_waitcnt lgkmcnt(0)
	s_barrier
; #define G_STAGE(bufoff, gbase, voff) do { _Pragma("unroll") for (int _i = 0; _i < 2; ++_i) \
;         __builtin_amdgcn_global_load_lds((const unsigned*)((const char*)(gbase) + voff[_i]), (LAS unsigned*)(lds + (bufoff) + ldsw + _i * 8192), 16, 0, 0); } while (0)
; #define G_LDA(dst, b, h) do { _Pragma("unroll") for (int m = 0; m < 4; ++m) _Pragma("unroll") for (int k = 0; k < 2; ++k) dst[m][k] = *(const LAS bf16x8*)(lds + G_SA(b, h) + aoff + m * 2048 + k * 1024); } while (0)
; #define G_MMA(ai, bj, At_, Bt_) do { __builtin_amdgcn_s_setprio(1); _Pragma("unroll") for (int m = 0; m < 4; ++m) _Pragma("unroll") for (int n = 0; n < 2; ++n) _Pragma("unroll") for (int k = 0; k < 2; ++k) \
;         acc[ai][bj][m][n] = __builtin_amdgcn_mfma_f32_16x16x32_bf16(Bt_[n][k], At_[m][k], acc[ai][bj][m][n], 0, 0, 0); __builtin_amdgcn_s_setprio(0); } while (0)
; #define WAIT_V(n) asm volatile("s_waitcnt vmcnt(" #n ")" ::: "memory")
; #define WAIT_L(n) asm volatile("s_waitcnt lgkmcnt(" #n ")" ::: "memory")
; #define BAR __builtin_amdgcn_s_barrier()
; #define SCHED __builtin_amdgcn_sched_barrier(0)
; template <class Get, class Epi>
; DI void gemm_loop(int ntiles, int ld, char* shm, const Get& get, const Epi& epi) {
;     ...
;             WAIT_V(8); WAIT_L(0); BAR; G_MMA(0, 0, At, B0); G_MMA(0, 1, At, B1); BAR; SCHED;
;             G_LDA(At, 0, 1); G_STAGE(G_SB(0, 0), b2, voffB); G_STAGE(G_SB(0, 1), b2 + hstep, voffB); G_STAGE(G_SA(0, 0), a2, voffA);
;             WAIT_V(8); WAIT_L(0); BAR; G_MMA(1, 0, At, B0); G_MMA(1, 1, At, B1); BAR; SCHED;
	s_setprio 1
	s_waitcnt lgkmcnt(0)
	v_mfma_f32_16x16x32_bf16 v[124:127], v[144:147], v[176:179], v[124:127]
	v_mfma_f32_16x16x32_bf16 v[120:123], v[152:155], v[176:179], v[120:123]
	v_mfma_f32_16x16x32_bf16 v[116:119], v[144:147], v[184:187], v[116:119]
	v_mfma_f32_16x16x32_bf16 v[112:115], v[152:155], v[184:187], v[112:115]
	v_mfma_f32_16x16x32_bf16 v[100:103], v[144:147], v[192:195], v[100:103]
	v_mfma_f32_16x16x32_bf16 v[96:99], v[152:155], v[192:195], v[96:99]
	v_mfma_f32_16x16x32_bf16 v[84:87], v[144:147], v[200:203], v[84:87]
	v_mfma_f32_16x16x32_bf16 v[80:83], v[152:155], v[200:203], v[80:83]
	s_setprio 0
	s_setprio 1
	v_mfma_f32_16x16x32_bf16 v[124:127], v[148:151], v[180:183], v[124:127]
	v_mfma_f32_16x16x32_bf16 v[120:123], v[156:159], v[180:183], v[120:123]
	v_mfma_f32_16x16x32_bf16 v[116:119], v[148:151], v[188:191], v[116:119]
	v_mfma_f32_16x16x32_bf16 v[112:115], v[156:159], v[188:191], v[112:115]
	v_mfma_f32_16x16x32_bf16 v[100:103], v[148:151], v[196:199], v[100:103]
	v_mfma_f32_16x16x32_bf16 v[96:99], v[156:159], v[196:199], v[96:99]
	v_mfma_f32_16x16x32_bf16 v[84:87], v[148:151], v[204:207], v[84:87]
	v_mfma_f32_16x16x32_bf16 v[80:83], v[156:159], v[204:207], v[80:83]
	s_setprio 0
	s_setprio 1
	v_mfma_f32_16x16x32_bf16 v[108:111], v[160:163], v[176:179], v[108:111]
	v_mfma_f32_16x16x32_bf16 v[104:107], v[168:171], v[176:179], v[104:107]
	v_mfma_f32_16x16x32_bf16 v[92:95], v[160:163], v[184:187], v[92:95]
	v_mfma_f32_16x16x32_bf16 v[88:91], v[168:171], v[184:187], v[88:91]
	v_mfma_f32_16x16x32_bf16 v[76:79], v[160:163], v[192:195], v[76:79]
	v_mfma_f32_16x16x32_bf16 v[72:75], v[168:171], v[192:195], v[72:75]
	v_mfma_f32_16x16x32_bf16 v[68:71], v[160:163], v[200:203], v[68:71]
	v_mfma_f32_16x16x32_bf16 v[64:67], v[168:171], v[200:203], v[64:67]
	s_setprio 0
	s_setprio 1
	v_mfma_f32_16x16x32_bf16 v[108:111], v[164:167], v[180:183], v[108:111]
	v_mfma_f32_16x16x32_bf16 v[104:107], v[172:175], v[180:183], v[104:107]
	v_mfma_f32_16x16x32_bf16 v[92:95], v[164:167], v[188:191], v[92:95]
	v_mfma_f32_16x16x32_bf16 v[88:91], v[172:175], v[188:191], v[88:91]
	v_mfma_f32_16x16x32_bf16 v[76:79], v[164:167], v[196:199], v[76:79]
	v_mfma_f32_16x16x32_bf16 v[72:75], v[172:175], v[196:199], v[72:75]
	v_mfma_f32_16x16x32_bf16 v[68:71], v[164:167], v[204:207], v[68:71]
	v_mfma_f32_16x16x32_bf16 v[64:67], v[172:175], v[204:207], v[64:67]
	s_setprio 0
	s_barrier
	s_add_i32 s71, s57, s50
	v_lshl_add_u64 v[208:209], s[14:15], 0, v[130:131]
	s_mov_b32 m0, s71
	ds_read_b128 v[176:179], v143 offset:16384
	ds_read_b128 v[180:183], v143 offset:17408
	ds_read_b128 v[184:187], v143 offset:18432
	ds_read_b128 v[188:191], v143 offset:19456
	ds_read_b128 v[192:195], v143 offset:20480
	ds_read_b128 v[196:199], v143 offset:21504
	ds_read_b128 v[200:203], v143 offset:22528
	ds_read_b128 v[204:207], v143 offset:23552
	global_load_lds_dwordx4 v[208:209], off
	s_add_i32 m0, s71, 0x2000
	s_add_u32 s72, s14, 0x40000
	v_lshl_add_u64 v[210:211], s[14:15], 0, v[134:135]
	s_addc_u32 s73, s15, 0
	s_add_i32 s71, s58, s50
	global_load_lds_dwordx4 v[210:211], off
	v_lshl_add_u64 v[212:213], s[72:73], 0, v[130:131]
	s_mov_b32 m0, s71
	v_lshl_add_u64 v[214:215], s[46:47], 0, v[132:133]
	global_load_lds_dwordx4 v[212:213], off
	v_lshl_add_u64 v[212:213], s[72:73], 0, v[134:135]
	s_add_i32 m0, s71, 0x2000
	s_nop 0
	global_load_lds_dwordx4 v[212:213], off
	v_lshl_add_u64 v[212:213], s[46:47], 0, v[128:129]
	s_mov_b32 m0, s35
	s_nop 0
	global_load_lds_dwordx4 v[212:213], off
	s_mov_b32 m0, s51
	s_nop 0
	global_load_lds_dwordx4 v[214:215], off
	s_waitcnt vmcnt(8)
	s_waitcnt lgkmcnt(0)
	s_barrier
	s_setprio 1
	s_waitcnt lgkmcnt(0)
	v_mfma_f32_16x16x32_bf16 v[60:63], v[144:147], v[176:179], v[60:63]
	v_mfma_f32_16x16x32_bf16 v[56:59], v[152:155], v[176:179], v[56:59]
	v_mfma_f32_16x16x32_bf16 v[52:55], v[144:147], v[184:187], v[52:55]
	v_mfma_f32_16x16x32_bf16 v[48:51], v[152:155], v[184:187], v[48:51]
	v_mfma_f32_16x16x32_bf16 v[36:39], v[144:147], v[192:195], v[36:39]
	v_mfma_f32_16x16x32_bf16 v[32:35], v[152:155], v[192:195], v[32:35]
	v_mfma_f32_16x16x32_bf16 v[20:23], v[144:147], v[200:203], v[20:23]
	v_mfma_f32_16x16x32_bf16 v[16:19], v[152:155], v[200:203], v[16:19]
	s_setprio 0
	s_setprio 1
	v_mfma_f32_16x16x32_bf16 v[60:63], v[148:151], v[180:183], v[60:63]
	v_mfma_f32_16x16x32_bf16 v[56:59], v[156:159], v[180:183], v[56:59]
	v_mfma_f32_16x16x32_bf16 v[52:55], v[148:151], v[188:191], v[52:55]
	v_mfma_f32_16x16x32_bf16 v[48:51], v[156:159], v[188:191], v[48:51]
	v_mfma_f32_16x16x32_bf16 v[36:39], v[148:151], v[196:199], v[36:39]
	v_mfma_f32_16x16x32_bf16 v[32:35], v[156:159], v[196:199], v[32:35]
	v_mfma_f32_16x16x32_bf16 v[20:23], v[148:151], v[204:207], v[20:23]
	v_mfma_f32_16x16x32_bf16 v[16:19], v[156:159], v[204:207], v[16:19]
	s_setprio 0
	s_setprio 1
	v_mfma_f32_16x16x32_bf16 v[44:47], v[160:163], v[176:179], v[44:47]
	v_mfma_f32_16x16x32_bf16 v[40:43], v[168:171], v[176:179], v[40:43]
	v_mfma_f32_16x16x32_bf16 v[28:31], v[160:163], v[184:187], v[28:31]
	v_mfma_f32_16x16x32_bf16 v[24:27], v[168:171], v[184:187], v[24:27]
	v_mfma_f32_16x16x32_bf16 v[12:15], v[160:163], v[192:195], v[12:15]
	v_mfma_f32_16x16x32_bf16 v[8:11], v[168:171], v[192:195], v[8:11]
	v_mfma_f32_16x16x32_bf16 v[4:7], v[160:163], v[200:203], v[4:7]
	v_mfma_f32_16x16x32_bf16 v[0:3], v[168:171], v[200:203], v[0:3]
	s_setprio 0
	s_setprio 1
	v_mfma_f32_16x16x32_bf16 v[44:47], v[164:167], v[180:183], v[44:47]
	v_mfma_f32_16x16x32_bf16 v[40:43], v[172:175], v[180:183], v[40:43]
	v_mfma_f32_16x16x32_bf16 v[28:31], v[164:167], v[188:191], v[28:31]
	v_mfma_f32_16x16x32_bf16 v[24:27], v[172:175], v[188:191], v[24:27]
	v_mfma_f32_16x16x32_bf16 v[12:15], v[164:167], v[196:199], v[12:15]
	v_mfma_f32_16x16x32_bf16 v[8:11], v[172:175], v[196:199], v[8:11]
	v_mfma_f32_16x16x32_bf16 v[4:7], v[164:167], v[204:207], v[4:7]
	v_mfma_f32_16x16x32_bf16 v[0:3], v[172:175], v[204:207], v[0:3]
	s_setprio 0
	s_barrier
; #define G_STAGE(bufoff, gbase, voff) do { _Pragma("unroll") for (int _i = 0; _i < 2; ++_i) \
;         __builtin_amdgcn_global_load_lds((const unsigned*)((const char*)(gbase) + voff[_i]), (LAS unsigned*)(lds + (bufoff) + ldsw + _i * 8192), 16, 0, 0); } while (0)
; #define G_LDA(dst, b, h) do { _Pragma("unroll") for (int m = 0; m < 4; ++m) _Pragma("unroll") for (int k = 0; k < 2; ++k) dst[m][k] = *(const LAS bf16x8*)(lds + G_SA(b, h) + aoff + m * 2048 + k * 1024); } while (0)
; #define G_LDB(dst, b, h) do { _Pragma("unroll") for (int n = 0; n < 2; ++n) _Pragma("unroll") for (int k = 0; k < 2; ++k) dst[n][k] = *(const LAS bf16x8*)(lds + G_SB(b, h) + boff + n * 2048 + k * 1024); } while (0)
; #define G_MMA(ai, bj, At_, Bt_) do { __builtin_amdgcn_s_setprio(1); _Pragma("unroll") for (int m = 0; m < 4; ++m) _Pragma("unroll") for (int n = 0; n < 2; ++n) _Pragma("unroll") for (int k = 0; k < 2; ++k) \
;         acc[ai][bj][m][n] = __builtin_amdgcn_mfma_f32_16x16x32_bf16(Bt_[n][k], At_[m][k], acc[ai][bj][m][n], 0, 0, 0); __builtin_amdgcn_s_setprio(0); } while (0)
; #define WAIT_V(n) asm volatile("s_waitcnt vmcnt(" #n ")" ::: "memory")
; #define WAIT_L(n) asm volatile("s_waitcnt lgkmcnt(" #n ")" ::: "memory")
; #define BAR __builtin_amdgcn_s_barrier()
; #define SCHED __builtin_amdgcn_sched_barrier(0)
; template <class Get, class Epi>
; DI void gemm_loop(int ntiles, int ld, char* shm, const Get& get, const Epi& epi) {
;     ...
;             G_LDB(B0, 1, 0); G_LDB(B1, 1, 1); SCHED; G_LDA(At, 1, 0); G_STAGE(G_SA(0, 1), a2 + hstep, voffA);
;             WAIT_V(8); WAIT_L(0); BAR; G_MMA(0, 0, At, B0); G_MMA(0, 1, At, B1); BAR; SCHED;
	s_add_i32 s71, 0, 0x18000
	s_add_i32 s72, 0, 0x1c000
	v_add_u32_e32 v156, s71, v140
	v_add_u32_e32 v172, s72, v140
	ds_read_b128 v[144:147], v156
	ds_read_b128 v[148:151], v156 offset:1024
	ds_read_b128 v[152:155], v156 offset:2048
	ds_read_b128 v[156:159], v156 offset:3072
	ds_read_b128 v[160:163], v172
	ds_read_b128 v[164:167], v172 offset:1024
	ds_read_b128 v[168:171], v172 offset:2048
	ds_read_b128 v[172:175], v172 offset:3072
	s_add_u32 s46, s46, 0x40000
	s_addc_u32 s47, s47, 0
	s_mov_b32 m0, s52
	v_lshl_add_u64 v[216:217], s[46:47], 0, v[128:129]
	ds_read_b128 v[176:179], v143 offset:32768
	ds_read_b128 v[180:183], v143 offset:33792
	ds_read_b128 v[184:187], v143 offset:34816
	ds_read_b128 v[188:191], v143 offset:35840
	ds_read_b128 v[192:195], v143 offset:36864
	ds_read_b128 v[196:199], v143 offset:37888
	ds_read_b128 v[200:203], v143 offset:38912
	ds_read_b128 v[204:207], v143 offset:39936
	global_load_lds_dwordx4 v[216:217], off
	v_lshl_add_u64 v[216:217], s[46:47], 0, v[132:133]
	s_mov_b32 m0, s53
	s_nop 0
	global_load_lds_dwordx4 v[216:217], off
	s_waitcnt vmcnt(8)
	s_waitcnt lgkmcnt(0)
	s_barrier
	s_setprio 1
	s_waitcnt lgkmcnt(0)
	v_mfma_f32_16x16x32_bf16 v[124:127], v[144:147], v[176:179], v[124:127]
	v_mfma_f32_16x16x32_bf16 v[120:123], v[152:155], v[176:179], v[120:123]
	v_mfma_f32_16x16x32_bf16 v[116:119], v[144:147], v[184:187], v[116:119]
	v_mfma_f32_16x16x32_bf16 v[112:115], v[152:155], v[184:187], v[112:115]
	v_mfma_f32_16x16x32_bf16 v[100:103], v[144:147], v[192:195], v[100:103]
	v_mfma_f32_16x16x32_bf16 v[96:99], v[152:155], v[192:195], v[96:99]
	v_mfma_f32_16x16x32_bf16 v[84:87], v[144:147], v[200:203], v[84:87]
	v_mfma_f32_16x16x32_bf16 v[80:83], v[152:155], v[200:203], v[80:83]
	s_setprio 0
	s_setprio 1
	v_mfma_f32_16x16x32_bf16 v[124:127], v[148:151], v[180:183], v[124:127]
	v_mfma_f32_16x16x32_bf16 v[120:123], v[156:159], v[180:183], v[120:123]
	v_mfma_f32_16x16x32_bf16 v[116:119], v[148:151], v[188:191], v[116:119]
	v_mfma_f32_16x16x32_bf16 v[112:115], v[156:159], v[188:191], v[112:115]
	v_mfma_f32_16x16x32_bf16 v[100:103], v[148:151], v[196:199], v[100:103]
	v_mfma_f32_16x16x32_bf16 v[96:99], v[156:159], v[196:199], v[96:99]
	v_mfma_f32_16x16x32_bf16 v[84:87], v[148:151], v[204:207], v[84:87]
	v_mfma_f32_16x16x32_bf16 v[80:83], v[156:159], v[204:207], v[80:83]
	s_setprio 0
	s_setprio 1
	v_mfma_f32_16x16x32_bf16 v[108:111], v[160:163], v[176:179], v[108:111]
	v_mfma_f32_16x16x32_bf16 v[104:107], v[168:171], v[176:179], v[104:107]
	v_mfma_f32_16x16x32_bf16 v[92:95], v[160:163], v[184:187], v[92:95]
	v_mfma_f32_16x16x32_bf16 v[88:91], v[168:171], v[184:187], v[88:91]
	v_mfma_f32_16x16x32_bf16 v[76:79], v[160:163], v[192:195], v[76:79]
	v_mfma_f32_16x16x32_bf16 v[72:75], v[168:171], v[192:195], v[72:75]
	v_mfma_f32_16x16x32_bf16 v[68:71], v[160:163], v[200:203], v[68:71]
	v_mfma_f32_16x16x32_bf16 v[64:67], v[168:171], v[200:203], v[64:67]
	s_setprio 0
	s_setprio 1
	v_mfma_f32_16x16x32_bf16 v[108:111], v[164:167], v[180:183], v[108:111]
	v_mfma_f32_16x16x32_bf16 v[104:107], v[172:175], v[180:183], v[104:107]
	v_mfma_f32_16x16x32_bf16 v[92:95], v[164:167], v[188:191], v[92:95]
	v_mfma_f32_16x16x32_bf16 v[88:91], v[172:175], v[188:191], v[88:91]
	v_mfma_f32_16x16x32_bf16 v[76:79], v[164:167], v[196:199], v[76:79]
	v_mfma_f32_16x16x32_bf16 v[72:75], v[172:175], v[196:199], v[72:75]
	v_mfma_f32_16x16x32_bf16 v[68:71], v[164:167], v[204:207], v[68:71]
	v_mfma_f32_16x16x32_bf16 v[64:67], v[172:175], v[204:207], v[64:67]
	s_setprio 0
	s_barrier
; #define G_STAGE(bufoff, gbase, voff) do { _Pragma("unroll") for (int _i = 0; _i < 2; ++_i) \
;         __builtin_amdgcn_global_load_lds((const unsigned*)((const char*)(gbase) + voff[_i]), (LAS unsigned*)(lds + (bufoff) + ldsw + _i * 8192), 16, 0, 0); } while (0)
; #define G_LDA(dst, b, h) do { _Pragma("unroll") for (int m = 0; m < 4; ++m) _Pragma("unroll") for (int k = 0; k < 2; ++k) dst[m][k] = *(const LAS bf16x8*)(lds + G_SA(b, h) + aoff + m * 2048 + k * 1024); } while (0)
; #define G_MMA(ai, bj, At_, Bt_) do { __builtin_amdgcn_s_setprio(1); _Pragma("unroll") for (int m = 0; m < 4; ++m) _Pragma("unroll") for (int n = 0; n < 2; ++n) _Pragma("unroll") for (int k = 0; k < 2; ++k) \
;         acc[ai][bj][m][n] = __builtin_amdgcn_mfma_f32_16x16x32_bf16(Bt_[n][k], At_[m][k], acc[ai][bj][m][n], 0, 0, 0); __builtin_amdgcn_s_setprio(0); } while (0)
; #define WAIT_V(n) asm volatile("s_waitcnt vmcnt(" #n ")" ::: "memory")
; #define WAIT_L(n) asm volatile("s_waitcnt lgkmcnt(" #n ")" ::: "memory")
; #define BAR __builtin_amdgcn_s_barrier()
; #define SCHED __builtin_amdgcn_sched_barrier(0)
; template <class Get, class Epi>
; DI void gemm_loop(int ntiles, int ld, char* shm, const Get& get, const Epi& epi) {
;     ...
;             G_LDA(At, 1, 1); G_STAGE(G_SB(1, 0), b3, voffB); G_STAGE(G_SB(1, 1), b3 + hstep, voffB); G_STAGE(G_SA(1, 0), a3, voffA);
;             WAIT_V(8); WAIT_L(0); BAR; G_MMA(1, 0, At, B0); G_MMA(1, 1, At, B1); BAR; SCHED;
	s_add_i32 s46, s71, s50
	v_lshl_add_u64 v[208:209], v[208:209], 0, s[8:9]
	s_mov_b32 m0, s46
	ds_read_b128 v[176:179], v143 offset:49152
	ds_read_b128 v[180:183], v143 offset:50176
	ds_read_b128 v[184:187], v143 offset:51200
	ds_read_b128 v[188:191], v143 offset:52224
	ds_read_b128 v[192:195], v143 offset:53248
	ds_read_b128 v[196:199], v143 offset:54272
	ds_read_b128 v[200:203], v143 offset:55296
	ds_read_b128 v[204:207], v143 offset:56320
	global_load_lds_dwordx4 v[208:209], off
	s_add_i32 m0, s46, 0x2000
	s_add_u32 s14, s14, 0x40080
	v_lshl_add_u64 v[208:209], v[210:211], 0, s[8:9]
	s_addc_u32 s15, s15, 0
	s_add_i32 s46, s72, s50
	global_load_lds_dwordx4 v[208:209], off
	v_lshl_add_u64 v[208:209], s[14:15], 0, v[130:131]
	s_mov_b32 m0, s46
	s_nop 0
	global_load_lds_dwordx4 v[208:209], off
	v_lshl_add_u64 v[208:209], s[14:15], 0, v[134:135]
	s_add_i32 m0, s46, 0x2000
	s_nop 0
	global_load_lds_dwordx4 v[208:209], off
	v_lshl_add_u64 v[208:209], v[212:213], 0, s[8:9]
	s_mov_b32 m0, s55
	s_nop 0
	global_load_lds_dwordx4 v[208:209], off
	v_lshl_add_u64 v[208:209], v[214:215], 0, s[8:9]
	s_mov_b32 m0, s56
	s_nop 0
	global_load_lds_dwordx4 v[208:209], off
	s_waitcnt vmcnt(8)
	s_waitcnt lgkmcnt(0)
	s_barrier
	s_setprio 1
	s_waitcnt lgkmcnt(0)
	v_mfma_f32_16x16x32_bf16 v[60:63], v[144:147], v[176:179], v[60:63]
	v_mfma_f32_16x16x32_bf16 v[56:59], v[152:155], v[176:179], v[56:59]
	v_mfma_f32_16x16x32_bf16 v[52:55], v[144:147], v[184:187], v[52:55]
	v_mfma_f32_16x16x32_bf16 v[48:51], v[152:155], v[184:187], v[48:51]
	v_mfma_f32_16x16x32_bf16 v[36:39], v[144:147], v[192:195], v[36:39]
	v_mfma_f32_16x16x32_bf16 v[32:35], v[152:155], v[192:195], v[32:35]
	v_mfma_f32_16x16x32_bf16 v[20:23], v[144:147], v[200:203], v[20:23]
	v_mfma_f32_16x16x32_bf16 v[16:19], v[152:155], v[200:203], v[16:19]
	s_setprio 0
	s_setprio 1
	v_mfma_f32_16x16x32_bf16 v[60:63], v[148:151], v[180:183], v[60:63]
	v_mfma_f32_16x16x32_bf16 v[56:59], v[156:159], v[180:183], v[56:59]
	v_mfma_f32_16x16x32_bf16 v[52:55], v[148:151], v[188:191], v[52:55]
	v_mfma_f32_16x16x32_bf16 v[48:51], v[156:159], v[188:191], v[48:51]
	v_mfma_f32_16x16x32_bf16 v[36:39], v[148:151], v[196:199], v[36:39]
	v_mfma_f32_16x16x32_bf16 v[32:35], v[156:159], v[196:199], v[32:35]
	v_mfma_f32_16x16x32_bf16 v[20:23], v[148:151], v[204:207], v[20:23]
	v_mfma_f32_16x16x32_bf16 v[16:19], v[156:159], v[204:207], v[16:19]
	s_setprio 0
	s_setprio 1
	v_mfma_f32_16x16x32_bf16 v[44:47], v[160:163], v[176:179], v[44:47]
	v_mfma_f32_16x16x32_bf16 v[40:43], v[168:171], v[176:179], v[40:43]
	v_mfma_f32_16x16x32_bf16 v[28:31], v[160:163], v[184:187], v[28:31]
	v_mfma_f32_16x16x32_bf16 v[24:27], v[168:171], v[184:187], v[24:27]
	v_mfma_f32_16x16x32_bf16 v[12:15], v[160:163], v[192:195], v[12:15]
	v_mfma_f32_16x16x32_bf16 v[8:11], v[168:171], v[192:195], v[8:11]
	v_mfma_f32_16x16x32_bf16 v[4:7], v[160:163], v[200:203], v[4:7]
	v_mfma_f32_16x16x32_bf16 v[0:3], v[168:171], v[200:203], v[0:3]
	s_setprio 0
	s_setprio 1
	v_mfma_f32_16x16x32_bf16 v[44:47], v[164:167], v[180:183], v[44:47]
	v_mfma_f32_16x16x32_bf16 v[40:43], v[172:175], v[180:183], v[40:43]
	v_mfma_f32_16x16x32_bf16 v[28:31], v[164:167], v[188:191], v[28:31]
	v_mfma_f32_16x16x32_bf16 v[24:27], v[172:175], v[188:191], v[24:27]
	v_mfma_f32_16x16x32_bf16 v[12:15], v[164:167], v[196:199], v[12:15]
	v_mfma_f32_16x16x32_bf16 v[8:11], v[172:175], v[196:199], v[8:11]
	v_mfma_f32_16x16x32_bf16 v[4:7], v[164:167], v[204:207], v[4:7]
	v_mfma_f32_16x16x32_bf16 v[0:3], v[172:175], v[204:207], v[0:3]
	s_setprio 0
	s_barrier
	s_add_i32 s70, s70, 2
	s_add_u32 s48, s48, 0x100
	s_addc_u32 s49, s49, 0
	s_add_u32 s64, s64, 0x100
	s_addc_u32 s65, s65, 0
	s_cmp_gt_u32 s70, 13
	s_cbranch_scc0 .LBB0_3141

; #define G_STAGE(bufoff, gbase, voff) do { _Pragma("unroll") for (int _i = 0; _i < 2; ++_i) \
;         __builtin_amdgcn_global_load_lds((const unsigned*)((const char*)(gbase) + voff[_i]), (LAS unsigned*)(lds + (bufoff) + ldsw + _i * 8192), 16, 0, 0); } while (0)
; #define G_LDA(dst, b, h) do { _Pragma("unroll") for (int m = 0; m < 4; ++m) _Pragma("unroll") for (int k = 0; k < 2; ++k) dst[m][k] = *(const LAS bf16x8*)(lds + G_SA(b, h) + aoff + m * 2048 + k * 1024); } while (0)
; #define G_MMA(ai, bj, At_, Bt_) do { __builtin_amdgcn_s_setprio(1); _Pragma("unroll") for (int m = 0; m < 4; ++m) _Pragma("unroll") for (int n = 0; n < 2; ++n) _Pragma("unroll") for (int k = 0; k < 2; ++k) \
;         acc[ai][bj][m][n] = __builtin_amdgcn_mfma_f32_16x16x32_bf16(Bt_[n][k], At_[m][k], acc[ai][bj][m][n], 0, 0, 0); __builtin_amdgcn_s_setprio(0); } while (0)
; #define WAIT_V(n) asm volatile("s_waitcnt vmcnt(" #n ")" ::: "memory")
; #define WAIT_L(n) asm volatile("s_waitcnt lgkmcnt(" #n ")" ::: "memory")
; #define BAR __builtin_amdgcn_s_barrier()
; #define SCHED __builtin_amdgcn_sched_barrier(0)
; template <class Get, class Epi>
; DI void gemm_loop(int ntiles, int ld, char* shm, const Get& get, const Epi& epi) {
;     ...
;             WAIT_V(8); WAIT_L(0); BAR; G_MMA(0, 0, At, B0); G_MMA(0, 1, At, B1); BAR; SCHED;
;             G_LDA(At, 0, 1); G_STAGE(G_SB(0, 0), b2, voffB); G_STAGE(G_SB(0, 1), b2 + hstep, voffB); G_STAGE(G_SA(0, 0), a2, voffA);
.Lrj_3466_0:
	s_waitcnt lgkmcnt(0)
	s_barrier
	s_setprio 1
	s_waitcnt lgkmcnt(0)
	v_mfma_f32_16x16x32_bf16 v[124:127], v[128:131], v[180:183], 0
	v_mfma_f32_16x16x32_bf16 v[120:123], v[136:139], v[180:183], 0
	v_mfma_f32_16x16x32_bf16 v[116:119], v[128:131], v[188:191], 0
	v_mfma_f32_16x16x32_bf16 v[112:115], v[136:139], v[188:191], 0
	v_mfma_f32_16x16x32_bf16 v[108:111], v[128:131], v[196:199], 0
	v_mfma_f32_16x16x32_bf16 v[104:107], v[136:139], v[196:199], 0
	v_mfma_f32_16x16x32_bf16 v[100:103], v[128:131], v[204:207], 0
	v_mfma_f32_16x16x32_bf16 v[96:99], v[136:139], v[204:207], 0
	s_setprio 0
	s_setprio 1
	v_mfma_f32_16x16x32_bf16 v[124:127], v[132:135], v[184:187], v[124:127]
	v_mfma_f32_16x16x32_bf16 v[120:123], v[140:143], v[184:187], v[120:123]
	v_mfma_f32_16x16x32_bf16 v[116:119], v[132:135], v[192:195], v[116:119]
	v_mfma_f32_16x16x32_bf16 v[112:115], v[140:143], v[192:195], v[112:115]
	v_mfma_f32_16x16x32_bf16 v[108:111], v[132:135], v[200:203], v[108:111]
	v_mfma_f32_16x16x32_bf16 v[104:107], v[140:143], v[200:203], v[104:107]
	v_mfma_f32_16x16x32_bf16 v[100:103], v[132:135], v[208:211], v[100:103]
	v_mfma_f32_16x16x32_bf16 v[96:99], v[140:143], v[208:211], v[96:99]
	s_setprio 0
	s_setprio 1
	v_mfma_f32_16x16x32_bf16 v[60:63], v[158:161], v[180:183], 0
	v_mfma_f32_16x16x32_bf16 v[56:59], v[172:175], v[180:183], 0
	v_mfma_f32_16x16x32_bf16 v[52:55], v[158:161], v[188:191], 0
	v_mfma_f32_16x16x32_bf16 v[48:51], v[172:175], v[188:191], 0
	v_mfma_f32_16x16x32_bf16 v[44:47], v[158:161], v[196:199], 0
	v_mfma_f32_16x16x32_bf16 v[40:43], v[172:175], v[196:199], 0
	v_mfma_f32_16x16x32_bf16 v[36:39], v[158:161], v[204:207], 0
	v_mfma_f32_16x16x32_bf16 v[32:35], v[172:175], v[204:207], 0
	s_setprio 0
	s_setprio 1
	v_mfma_f32_16x16x32_bf16 v[60:63], v[162:165], v[184:187], v[60:63]
	v_mfma_f32_16x16x32_bf16 v[56:59], v[176:179], v[184:187], v[56:59]
	v_mfma_f32_16x16x32_bf16 v[52:55], v[162:165], v[192:195], v[52:55]
	v_mfma_f32_16x16x32_bf16 v[48:51], v[176:179], v[192:195], v[48:51]
	v_mfma_f32_16x16x32_bf16 v[44:47], v[162:165], v[200:203], v[44:47]
	v_mfma_f32_16x16x32_bf16 v[40:43], v[176:179], v[200:203], v[40:43]
	v_mfma_f32_16x16x32_bf16 v[36:39], v[162:165], v[208:211], v[36:39]
	v_mfma_f32_16x16x32_bf16 v[32:35], v[176:179], v[208:211], v[32:35]
	s_setprio 0
	s_barrier
	s_add_i32 s72, s56, s48
	v_lshl_add_u64 v[144:145], s[14:15], 0, v[148:149]
	s_mov_b32 m0, s72
	ds_read_b128 v[180:183], v171 offset:16384
	ds_read_b128 v[184:187], v171 offset:17408
	ds_read_b128 v[188:191], v171 offset:18432
	ds_read_b128 v[192:195], v171 offset:19456
	ds_read_b128 v[196:199], v171 offset:20480
	ds_read_b128 v[200:203], v171 offset:21504
	ds_read_b128 v[204:207], v171 offset:22528
	ds_read_b128 v[208:211], v171 offset:23552
	global_load_lds_dwordx4 v[144:145], off
	s_add_i32 m0, s72, 0x2000
	s_add_u32 s72, s14, 0x40000
	v_lshl_add_u64 v[166:167], s[14:15], 0, v[152:153]
	s_addc_u32 s73, s15, 0
	s_add_i32 s74, s57, s48
	global_load_lds_dwordx4 v[166:167], off
	v_lshl_add_u64 v[212:213], s[72:73], 0, v[148:149]
	s_mov_b32 m0, s74
	v_lshl_add_u64 v[214:215], s[46:47], 0, v[150:151]
	global_load_lds_dwordx4 v[212:213], off
	v_lshl_add_u64 v[212:213], s[72:73], 0, v[152:153]
	s_add_i32 m0, s74, 0x2000
	s_nop 0
	global_load_lds_dwordx4 v[212:213], off
	v_lshl_add_u64 v[212:213], s[46:47], 0, v[146:147]
	s_mov_b32 m0, s43
	s_nop 0
	global_load_lds_dwordx4 v[212:213], off
	s_mov_b32 m0, s49
	s_nop 0
	global_load_lds_dwordx4 v[214:215], off
	s_cmp_lg_u32 s100, 0
	s_cbranch_scc0 .Lrf_3466_1
	s_waitcnt vmcnt(16)
	s_branch .Lrj_3466_1

; #define G_STAGE(bufoff, gbase, voff) do { _Pragma("unroll") for (int _i = 0; _i < 2; ++_i) \
;         __builtin_amdgcn_global_load_lds((const unsigned*)((const char*)(gbase) + voff[_i]), (LAS unsigned*)(lds + (bufoff) + ldsw + _i * 8192), 16, 0, 0); } while (0)
; #define G_LDA(dst, b, h) do { _Pragma("unroll") for (int m = 0; m < 4; ++m) _Pragma("unroll") for (int k = 0; k < 2; ++k) dst[m][k] = *(const LAS bf16x8*)(lds + G_SA(b, h) + aoff + m * 2048 + k * 1024); } while (0)
; #define G_LDB(dst, b, h) do { _Pragma("unroll") for (int n = 0; n < 2; ++n) _Pragma("unroll") for (int k = 0; k < 2; ++k) dst[n][k] = *(const LAS bf16x8*)(lds + G_SB(b, h) + boff + n * 2048 + k * 1024); } while (0)
; #define G_MMA(ai, bj, At_, Bt_) do { __builtin_amdgcn_s_setprio(1); _Pragma("unroll") for (int m = 0; m < 4; ++m) _Pragma("unroll") for (int n = 0; n < 2; ++n) _Pragma("unroll") for (int k = 0; k < 2; ++k) \
;         acc[ai][bj][m][n] = __builtin_amdgcn_mfma_f32_16x16x32_bf16(Bt_[n][k], At_[m][k], acc[ai][bj][m][n], 0, 0, 0); __builtin_amdgcn_s_setprio(0); } while (0)
; #define WAIT_V(n) asm volatile("s_waitcnt vmcnt(" #n ")" ::: "memory")
; #define WAIT_L(n) asm volatile("s_waitcnt lgkmcnt(" #n ")" ::: "memory")
; #define BAR __builtin_amdgcn_s_barrier()
; #define SCHED __builtin_amdgcn_sched_barrier(0)
; template <class Get, class Epi>
; DI void gemm_loop(int ntiles, int ld, char* shm, const Get& get, const Epi& epi) {
;     ...
;             WAIT_V(8); WAIT_L(0); BAR; G_MMA(1, 0, At, B0); G_MMA(1, 1, At, B1); BAR; SCHED;
;             G_LDB(B0, 1, 0); G_LDB(B1, 1, 1); SCHED; G_LDA(At, 1, 0); G_STAGE(G_SA(0, 1), a2 + hstep, voffA);
;             WAIT_V(8); WAIT_L(0); BAR; G_MMA(0, 0, At, B0); G_MMA(0, 1, At, B1); BAR; SCHED;
.Lrj_3466_1:
	s_waitcnt lgkmcnt(0)
	s_barrier
	s_setprio 1
	s_waitcnt lgkmcnt(0)
	v_mfma_f32_16x16x32_bf16 v[92:95], v[128:131], v[180:183], 0
	v_mfma_f32_16x16x32_bf16 v[88:91], v[136:139], v[180:183], 0
	v_mfma_f32_16x16x32_bf16 v[84:87], v[128:131], v[188:191], 0
	v_mfma_f32_16x16x32_bf16 v[80:83], v[136:139], v[188:191], 0
	v_mfma_f32_16x16x32_bf16 v[76:79], v[128:131], v[196:199], 0
	v_mfma_f32_16x16x32_bf16 v[72:75], v[136:139], v[196:199], 0
	v_mfma_f32_16x16x32_bf16 v[68:71], v[128:131], v[204:207], 0
	v_mfma_f32_16x16x32_bf16 v[64:67], v[136:139], v[204:207], 0
	s_setprio 0
	s_setprio 1
	v_mfma_f32_16x16x32_bf16 v[92:95], v[132:135], v[184:187], v[92:95]
	v_mfma_f32_16x16x32_bf16 v[88:91], v[140:143], v[184:187], v[88:91]
	v_mfma_f32_16x16x32_bf16 v[84:87], v[132:135], v[192:195], v[84:87]
	v_mfma_f32_16x16x32_bf16 v[80:83], v[140:143], v[192:195], v[80:83]
	v_mfma_f32_16x16x32_bf16 v[76:79], v[132:135], v[200:203], v[76:79]
	v_mfma_f32_16x16x32_bf16 v[72:75], v[140:143], v[200:203], v[72:75]
	v_mfma_f32_16x16x32_bf16 v[68:71], v[132:135], v[208:211], v[68:71]
	v_mfma_f32_16x16x32_bf16 v[64:67], v[140:143], v[208:211], v[64:67]
	s_setprio 0
	s_setprio 1
	v_mfma_f32_16x16x32_bf16 v[28:31], v[158:161], v[180:183], 0
	v_mfma_f32_16x16x32_bf16 v[24:27], v[172:175], v[180:183], 0
	v_mfma_f32_16x16x32_bf16 v[20:23], v[158:161], v[188:191], 0
	v_mfma_f32_16x16x32_bf16 v[16:19], v[172:175], v[188:191], 0
	v_mfma_f32_16x16x32_bf16 v[12:15], v[158:161], v[196:199], 0
	v_mfma_f32_16x16x32_bf16 v[8:11], v[172:175], v[196:199], 0
	v_mfma_f32_16x16x32_bf16 v[4:7], v[158:161], v[204:207], 0
	v_mfma_f32_16x16x32_bf16 v[0:3], v[172:175], v[204:207], 0
	s_setprio 0
	s_setprio 1
	v_mfma_f32_16x16x32_bf16 v[28:31], v[162:165], v[184:187], v[28:31]
	v_mfma_f32_16x16x32_bf16 v[24:27], v[176:179], v[184:187], v[24:27]
	v_mfma_f32_16x16x32_bf16 v[20:23], v[162:165], v[192:195], v[20:23]
	v_mfma_f32_16x16x32_bf16 v[16:19], v[176:179], v[192:195], v[16:19]
	v_mfma_f32_16x16x32_bf16 v[12:15], v[162:165], v[200:203], v[12:15]
	v_mfma_f32_16x16x32_bf16 v[8:11], v[176:179], v[200:203], v[8:11]
	v_mfma_f32_16x16x32_bf16 v[4:7], v[162:165], v[208:211], v[4:7]
	v_mfma_f32_16x16x32_bf16 v[0:3], v[176:179], v[208:211], v[0:3]
	s_setprio 0
	s_barrier
	s_add_i32 s72, 0, 0x18000
	s_add_i32 s73, 0, 0x1c000
	v_add_u32_e32 v140, s72, v168
	v_add_u32_e32 v176, s73, v168
	ds_read_b128 v[128:131], v140
	ds_read_b128 v[132:135], v140 offset:1024
	ds_read_b128 v[136:139], v140 offset:2048
	ds_read_b128 v[140:143], v140 offset:3072
	ds_read_b128 v[158:161], v176
	ds_read_b128 v[162:165], v176 offset:1024
	ds_read_b128 v[172:175], v176 offset:2048
	ds_read_b128 v[176:179], v176 offset:3072
	s_add_u32 s46, s46, 0x40000
	s_addc_u32 s47, s47, 0
	s_mov_b32 m0, s50
	v_lshl_add_u64 v[216:217], s[46:47], 0, v[146:147]
	ds_read_b128 v[180:183], v171 offset:32768
	ds_read_b128 v[184:187], v171 offset:33792
	ds_read_b128 v[188:191], v171 offset:34816
	ds_read_b128 v[192:195], v171 offset:35840
	ds_read_b128 v[196:199], v171 offset:36864
	ds_read_b128 v[200:203], v171 offset:37888
	ds_read_b128 v[204:207], v171 offset:38912
	ds_read_b128 v[208:211], v171 offset:39936
	global_load_lds_dwordx4 v[216:217], off
	v_lshl_add_u64 v[216:217], s[46:47], 0, v[150:151]
	s_mov_b32 m0, s51
	s_nop 0
	global_load_lds_dwordx4 v[216:217], off
	s_waitcnt vmcnt(8)
	s_waitcnt lgkmcnt(0)
	s_barrier
	s_setprio 1
	s_waitcnt lgkmcnt(0)
	v_mfma_f32_16x16x32_bf16 v[124:127], v[128:131], v[180:183], v[124:127]
	v_mfma_f32_16x16x32_bf16 v[120:123], v[136:139], v[180:183], v[120:123]
	v_mfma_f32_16x16x32_bf16 v[116:119], v[128:131], v[188:191], v[116:119]
	v_mfma_f32_16x16x32_bf16 v[112:115], v[136:139], v[188:191], v[112:115]
	v_mfma_f32_16x16x32_bf16 v[108:111], v[128:131], v[196:199], v[108:111]
	v_mfma_f32_16x16x32_bf16 v[104:107], v[136:139], v[196:199], v[104:107]
	v_mfma_f32_16x16x32_bf16 v[100:103], v[128:131], v[204:207], v[100:103]
	v_mfma_f32_16x16x32_bf16 v[96:99], v[136:139], v[204:207], v[96:99]
	s_setprio 0
	s_setprio 1
	v_mfma_f32_16x16x32_bf16 v[124:127], v[132:135], v[184:187], v[124:127]
	v_mfma_f32_16x16x32_bf16 v[120:123], v[140:143], v[184:187], v[120:123]
	v_mfma_f32_16x16x32_bf16 v[116:119], v[132:135], v[192:195], v[116:119]
	v_mfma_f32_16x16x32_bf16 v[112:115], v[140:143], v[192:195], v[112:115]
	v_mfma_f32_16x16x32_bf16 v[108:111], v[132:135], v[200:203], v[108:111]
	v_mfma_f32_16x16x32_bf16 v[104:107], v[140:143], v[200:203], v[104:107]
	v_mfma_f32_16x16x32_bf16 v[100:103], v[132:135], v[208:211], v[100:103]
	v_mfma_f32_16x16x32_bf16 v[96:99], v[140:143], v[208:211], v[96:99]
	s_setprio 0
	s_setprio 1
	v_mfma_f32_16x16x32_bf16 v[60:63], v[158:161], v[180:183], v[60:63]
	v_mfma_f32_16x16x32_bf16 v[56:59], v[172:175], v[180:183], v[56:59]
	v_mfma_f32_16x16x32_bf16 v[52:55], v[158:161], v[188:191], v[52:55]
	v_mfma_f32_16x16x32_bf16 v[48:51], v[172:175], v[188:191], v[48:51]
	v_mfma_f32_16x16x32_bf16 v[44:47], v[158:161], v[196:199], v[44:47]
	v_mfma_f32_16x16x32_bf16 v[40:43], v[172:175], v[196:199], v[40:43]
	v_mfma_f32_16x16x32_bf16 v[36:39], v[158:161], v[204:207], v[36:39]
	v_mfma_f32_16x16x32_bf16 v[32:35], v[172:175], v[204:207], v[32:35]
	s_setprio 0
	s_setprio 1
	v_mfma_f32_16x16x32_bf16 v[60:63], v[162:165], v[184:187], v[60:63]
	v_mfma_f32_16x16x32_bf16 v[56:59], v[176:179], v[184:187], v[56:59]
	v_mfma_f32_16x16x32_bf16 v[52:55], v[162:165], v[192:195], v[52:55]
	v_mfma_f32_16x16x32_bf16 v[48:51], v[176:179], v[192:195], v[48:51]
	v_mfma_f32_16x16x32_bf16 v[44:47], v[162:165], v[200:203], v[44:47]
	v_mfma_f32_16x16x32_bf16 v[40:43], v[176:179], v[200:203], v[40:43]
	v_mfma_f32_16x16x32_bf16 v[36:39], v[162:165], v[208:211], v[36:39]
	v_mfma_f32_16x16x32_bf16 v[32:35], v[176:179], v[208:211], v[32:35]
	s_setprio 0
	s_barrier
; #define G_STAGE(bufoff, gbase, voff) do { _Pragma("unroll") for (int _i = 0; _i < 2; ++_i) \
;         __builtin_amdgcn_global_load_lds((const unsigned*)((const char*)(gbase) + voff[_i]), (LAS unsigned*)(lds + (bufoff) + ldsw + _i * 8192), 16, 0, 0); } while (0)
; #define G_LDA(dst, b, h) do { _Pragma("unroll") for (int m = 0; m < 4; ++m) _Pragma("unroll") for (int k = 0; k < 2; ++k) dst[m][k] = *(const LAS bf16x8*)(lds + G_SA(b, h) + aoff + m * 2048 + k * 1024); } while (0)
; #define G_LDB(dst, b, h) do { _Pragma("unroll") for (int n = 0; n < 2; ++n) _Pragma("unroll") for (int k = 0; k < 2; ++k) dst[n][k] = *(const LAS bf16x8*)(lds + G_SB(b, h) + boff + n * 2048 + k * 1024); } while (0)
; #define G_MMA(ai, bj, At_, Bt_) do { __builtin_amdgcn_s_setprio(1); _Pragma("unroll") for (int m = 0; m < 4; ++m) _Pragma("unroll") for (int n = 0; n < 2; ++n) _Pragma("unroll") for (int k = 0; k < 2; ++k) \
;         acc[ai][bj][m][n] = __builtin_amdgcn_mfma_f32_16x16x32_bf16(Bt_[n][k], At_[m][k], acc[ai][bj][m][n], 0, 0, 0); __builtin_amdgcn_s_setprio(0); } while (0)
; #define WAIT_V(n) asm volatile("s_waitcnt vmcnt(" #n ")" ::: "memory")
; #define WAIT_L(n) asm volatile("s_waitcnt lgkmcnt(" #n ")" ::: "memory")
; #define BAR __builtin_amdgcn_s_barrier()
; #define SCHED __builtin_amdgcn_sched_barrier(0)
; template <class Get, class Epi>
; DI void gemm_loop(int ntiles, int ld, char* shm, const Get& get, const Epi& epi) {
;     ...
;             G_LDB(B0, 0, 0); G_LDB(B1, 0, 1); SCHED; G_LDA(At, 0, 0); G_STAGE(G_SA(1, 1), a1 + hstep, voffA);
;             WAIT_V(8); WAIT_L(0); BAR; G_MMA(0, 0, At, B0); G_MMA(0, 1, At, B1); BAR; SCHED;
;     ...
;             G_LDA(At, 1, 1); G_STAGE(G_SB(1, 0), b3, voffB); G_STAGE(G_SB(1, 1), b3 + hstep, voffB); G_STAGE(G_SA(1, 0), a3, voffA);
;             WAIT_V(8); WAIT_L(0); BAR; G_MMA(1, 0, At, B0); G_MMA(1, 1, At, B1); BAR; SCHED;
;         }
	s_add_i32 s46, s72, s48
	v_lshl_add_u64 v[144:145], v[144:145], 0, s[4:5]
	s_mov_b32 m0, s46
	ds_read_b128 v[180:183], v171 offset:49152
	ds_read_b128 v[184:187], v171 offset:50176
	ds_read_b128 v[188:191], v171 offset:51200
	ds_read_b128 v[192:195], v171 offset:52224
	ds_read_b128 v[196:199], v171 offset:53248
	ds_read_b128 v[200:203], v171 offset:54272
	ds_read_b128 v[204:207], v171 offset:55296
	ds_read_b128 v[208:211], v171 offset:56320
	global_load_lds_dwordx4 v[144:145], off
	s_add_i32 m0, s46, 0x2000
	s_add_u32 s14, s14, 0x40080
	v_lshl_add_u64 v[144:145], v[166:167], 0, s[4:5]
	s_addc_u32 s15, s15, 0
	s_add_i32 s46, s73, s48
	global_load_lds_dwordx4 v[144:145], off
	v_lshl_add_u64 v[144:145], s[14:15], 0, v[148:149]
	s_mov_b32 m0, s46
	s_nop 0
	global_load_lds_dwordx4 v[144:145], off
	v_lshl_add_u64 v[144:145], s[14:15], 0, v[152:153]
	s_add_i32 m0, s46, 0x2000
	s_nop 0
	global_load_lds_dwordx4 v[144:145], off
	v_lshl_add_u64 v[144:145], v[212:213], 0, s[4:5]
	s_mov_b32 m0, s54
	s_nop 0
	global_load_lds_dwordx4 v[144:145], off
	v_lshl_add_u64 v[144:145], v[214:215], 0, s[4:5]
	s_mov_b32 m0, s55
	s_nop 0
	global_load_lds_dwordx4 v[144:145], off
	s_waitcnt vmcnt(8)
	s_waitcnt lgkmcnt(0)
	s_barrier
	s_setprio 1
	s_waitcnt lgkmcnt(0)
	v_mfma_f32_16x16x32_bf16 v[92:95], v[128:131], v[180:183], v[92:95]
	v_mfma_f32_16x16x32_bf16 v[88:91], v[136:139], v[180:183], v[88:91]
	v_mfma_f32_16x16x32_bf16 v[84:87], v[128:131], v[188:191], v[84:87]
	v_mfma_f32_16x16x32_bf16 v[80:83], v[136:139], v[188:191], v[80:83]
	v_mfma_f32_16x16x32_bf16 v[76:79], v[128:131], v[196:199], v[76:79]
	v_mfma_f32_16x16x32_bf16 v[72:75], v[136:139], v[196:199], v[72:75]
	v_mfma_f32_16x16x32_bf16 v[68:71], v[128:131], v[204:207], v[68:71]
	v_mfma_f32_16x16x32_bf16 v[64:67], v[136:139], v[204:207], v[64:67]
	s_setprio 0
	s_setprio 1
	v_mfma_f32_16x16x32_bf16 v[92:95], v[132:135], v[184:187], v[92:95]
	v_mfma_f32_16x16x32_bf16 v[88:91], v[140:143], v[184:187], v[88:91]
	v_mfma_f32_16x16x32_bf16 v[84:87], v[132:135], v[192:195], v[84:87]
	v_mfma_f32_16x16x32_bf16 v[80:83], v[140:143], v[192:195], v[80:83]
	v_mfma_f32_16x16x32_bf16 v[76:79], v[132:135], v[200:203], v[76:79]
	v_mfma_f32_16x16x32_bf16 v[72:75], v[140:143], v[200:203], v[72:75]
	v_mfma_f32_16x16x32_bf16 v[68:71], v[132:135], v[208:211], v[68:71]
	v_mfma_f32_16x16x32_bf16 v[64:67], v[140:143], v[208:211], v[64:67]
	s_setprio 0
	s_setprio 1
	v_mfma_f32_16x16x32_bf16 v[28:31], v[158:161], v[180:183], v[28:31]
	v_mfma_f32_16x16x32_bf16 v[24:27], v[172:175], v[180:183], v[24:27]
	v_mfma_f32_16x16x32_bf16 v[20:23], v[158:161], v[188:191], v[20:23]
	v_mfma_f32_16x16x32_bf16 v[16:19], v[172:175], v[188:191], v[16:19]
	v_mfma_f32_16x16x32_bf16 v[12:15], v[158:161], v[196:199], v[12:15]
	v_mfma_f32_16x16x32_bf16 v[8:11], v[172:175], v[196:199], v[8:11]
	v_mfma_f32_16x16x32_bf16 v[4:7], v[158:161], v[204:207], v[4:7]
	v_mfma_f32_16x16x32_bf16 v[0:3], v[172:175], v[204:207], v[0:3]
	s_setprio 0
	s_setprio 1
	v_mfma_f32_16x16x32_bf16 v[28:31], v[162:165], v[184:187], v[28:31]
	v_mfma_f32_16x16x32_bf16 v[24:27], v[176:179], v[184:187], v[24:27]
	v_mfma_f32_16x16x32_bf16 v[20:23], v[162:165], v[192:195], v[20:23]
	v_mfma_f32_16x16x32_bf16 v[16:19], v[176:179], v[192:195], v[16:19]
	v_mfma_f32_16x16x32_bf16 v[12:15], v[162:165], v[200:203], v[12:15]
	v_mfma_f32_16x16x32_bf16 v[8:11], v[176:179], v[200:203], v[8:11]
	v_mfma_f32_16x16x32_bf16 v[4:7], v[162:165], v[208:211], v[4:7]
	v_mfma_f32_16x16x32_bf16 v[0:3], v[176:179], v[208:211], v[0:3]
	s_setprio 0
	s_barrier
	s_add_i32 s71, s71, 2
	s_add_u32 s44, s44, 0x100
	s_addc_u32 s45, s45, 0
	s_add_u32 s65, s65, 0x100
	s_addc_u32 s70, s70, 0
	s_cmp_gt_u32 s71, 13
	s_cbranch_scc0 .LBB0_3466
	s_branch .Lpost_3466
.LBB0_3466:
	ds_read_b128 v[128:131], v169
	ds_read_b128 v[132:135], v169 offset:1024
	ds_read_b128 v[136:139], v169 offset:2048
	ds_read_b128 v[140:143], v169 offset:3072
	ds_read_b128 v[158:161], v170
	ds_read_b128 v[162:165], v170 offset:1024
	ds_read_b128 v[172:175], v170 offset:2048
	ds_read_b128 v[176:179], v170 offset:3072
	s_add_u32 s14, s44, 0xfffc0080
	s_addc_u32 s15, s45, -1
	s_cmp_eq_u32 s71, 12
	s_cselect_b32 s47, s3, s15
	s_cselect_b32 s46, s35, s14
	s_cselect_b32 s15, s37, s70
	s_cselect_b32 s14, s64, s65
	v_lshl_add_u64 v[144:145], s[44:45], 0, v[154:155]
	s_add_i32 m0, s43, 0xc000
	ds_read_b128 v[180:183], v171
	ds_read_b128 v[184:187], v171 offset:1024
	ds_read_b128 v[188:191], v171 offset:2048
	ds_read_b128 v[192:195], v171 offset:3072
	ds_read_b128 v[196:199], v171 offset:4096
	ds_read_b128 v[200:203], v171 offset:5120
	ds_read_b128 v[204:207], v171 offset:6144
	ds_read_b128 v[208:211], v171 offset:7168
	global_load_lds_dwordx4 v[144:145], off
	v_lshl_add_u64 v[144:145], s[44:45], 0, v[156:157]
	s_add_i32 m0, s43, 0xe000
	s_nop 0
	global_load_lds_dwordx4 v[144:145], off
	s_waitcnt vmcnt(8)
	s_waitcnt lgkmcnt(0)
	s_barrier
; #define G_STAGE(bufoff, gbase, voff) do { _Pragma("unroll") for (int _i = 0; _i < 2; ++_i) \
;         __builtin_amdgcn_global_load_lds((const unsigned*)((const char*)(gbase) + voff[_i]), (LAS unsigned*)(lds + (bufoff) + ldsw + _i * 8192), 16, 0, 0); } while (0)
; #define G_LDA(dst, b, h) do { _Pragma("unroll") for (int m = 0; m < 4; ++m) _Pragma("unroll") for (int k = 0; k < 2; ++k) dst[m][k] = *(const LAS bf16x8*)(lds + G_SA(b, h) + aoff + m * 2048 + k * 1024); } while (0)
; #define G_MMA(ai, bj, At_, Bt_) do { __builtin_amdgcn_s_setprio(1); _Pragma("unroll") for (int m = 0; m < 4; ++m) _Pragma("unroll") for (int n = 0; n < 2; ++n) _Pragma("unroll") for (int k = 0; k < 2; ++k) \
;         acc[ai][bj][m][n] = __builtin_amdgcn_mfma_f32_16x16x32_bf16(Bt_[n][k], At_[m][k], acc[ai][bj][m][n], 0, 0, 0); __builtin_amdgcn_s_setprio(0); } while (0)
; #define WAIT_V(n) asm volatile("s_waitcnt vmcnt(" #n ")" ::: "memory")
; #define WAIT_L(n) asm volatile("s_waitcnt lgkmcnt(" #n ")" ::: "memory")
; #define BAR __builtin_amdgcn_s_barrier()
; #define SCHED __builtin_amdgcn_sched_barrier(0)
; template <class Get, class Epi>
; DI void gemm_loop(int ntiles, int ld, char* shm, const Get& get, const Epi& epi) {
;     ...
;             WAIT_V(8); WAIT_L(0); BAR; G_MMA(0, 0, At, B0); G_MMA(0, 1, At, B1); BAR; SCHED;
;             G_LDA(At, 0, 1); G_STAGE(G_SB(0, 0), b2, voffB); G_STAGE(G_SB(0, 1), b2 + hstep, voffB); G_STAGE(G_SA(0, 0), a2, voffA);
;             WAIT_V(8); WAIT_L(0); BAR; G_MMA(1, 0, At, B0); G_MMA(1, 1, At, B1); BAR; SCHED;
	s_setprio 1
	s_waitcnt lgkmcnt(0)
	v_mfma_f32_16x16x32_bf16 v[124:127], v[128:131], v[180:183], v[124:127]
	v_mfma_f32_16x16x32_bf16 v[120:123], v[136:139], v[180:183], v[120:123]
	v_mfma_f32_16x16x32_bf16 v[116:119], v[128:131], v[188:191], v[116:119]
	v_mfma_f32_16x16x32_bf16 v[112:115], v[136:139], v[188:191], v[112:115]
	v_mfma_f32_16x16x32_bf16 v[108:111], v[128:131], v[196:199], v[108:111]
	v_mfma_f32_16x16x32_bf16 v[104:107], v[136:139], v[196:199], v[104:107]
	v_mfma_f32_16x16x32_bf16 v[100:103], v[128:131], v[204:207], v[100:103]
	v_mfma_f32_16x16x32_bf16 v[96:99], v[136:139], v[204:207], v[96:99]
	s_setprio 0
	s_setprio 1
	v_mfma_f32_16x16x32_bf16 v[124:127], v[132:135], v[184:187], v[124:127]
	v_mfma_f32_16x16x32_bf16 v[120:123], v[140:143], v[184:187], v[120:123]
	v_mfma_f32_16x16x32_bf16 v[116:119], v[132:135], v[192:195], v[116:119]
	v_mfma_f32_16x16x32_bf16 v[112:115], v[140:143], v[192:195], v[112:115]
	v_mfma_f32_16x16x32_bf16 v[108:111], v[132:135], v[200:203], v[108:111]
	v_mfma_f32_16x16x32_bf16 v[104:107], v[140:143], v[200:203], v[104:107]
	v_mfma_f32_16x16x32_bf16 v[100:103], v[132:135], v[208:211], v[100:103]
	v_mfma_f32_16x16x32_bf16 v[96:99], v[140:143], v[208:211], v[96:99]
	s_setprio 0
	s_setprio 1
	v_mfma_f32_16x16x32_bf16 v[60:63], v[158:161], v[180:183], v[60:63]
	v_mfma_f32_16x16x32_bf16 v[56:59], v[172:175], v[180:183], v[56:59]
	v_mfma_f32_16x16x32_bf16 v[52:55], v[158:161], v[188:191], v[52:55]
	v_mfma_f32_16x16x32_bf16 v[48:51], v[172:175], v[188:191], v[48:51]
	v_mfma_f32_16x16x32_bf16 v[44:47], v[158:161], v[196:199], v[44:47]
	v_mfma_f32_16x16x32_bf16 v[40:43], v[172:175], v[196:199], v[40:43]
	v_mfma_f32_16x16x32_bf16 v[36:39], v[158:161], v[204:207], v[36:39]
	v_mfma_f32_16x16x32_bf16 v[32:35], v[172:175], v[204:207], v[32:35]
	s_setprio 0
	s_setprio 1
	v_mfma_f32_16x16x32_bf16 v[60:63], v[162:165], v[184:187], v[60:63]
	v_mfma_f32_16x16x32_bf16 v[56:59], v[176:179], v[184:187], v[56:59]
	v_mfma_f32_16x16x32_bf16 v[52:55], v[162:165], v[192:195], v[52:55]
	v_mfma_f32_16x16x32_bf16 v[48:51], v[176:179], v[192:195], v[48:51]
	v_mfma_f32_16x16x32_bf16 v[44:47], v[162:165], v[200:203], v[44:47]
	v_mfma_f32_16x16x32_bf16 v[40:43], v[176:179], v[200:203], v[40:43]
	v_mfma_f32_16x16x32_bf16 v[36:39], v[162:165], v[208:211], v[36:39]
	v_mfma_f32_16x16x32_bf16 v[32:35], v[176:179], v[208:211], v[32:35]
	s_setprio 0
	s_barrier
	s_add_i32 s72, s56, s48
	v_lshl_add_u64 v[144:145], s[14:15], 0, v[148:149]
	s_mov_b32 m0, s72
	ds_read_b128 v[180:183], v171 offset:16384
	ds_read_b128 v[184:187], v171 offset:17408
	ds_read_b128 v[188:191], v171 offset:18432
	ds_read_b128 v[192:195], v171 offset:19456
	ds_read_b128 v[196:199], v171 offset:20480
	ds_read_b128 v[200:203], v171 offset:21504
	ds_read_b128 v[204:207], v171 offset:22528
	ds_read_b128 v[208:211], v171 offset:23552
	global_load_lds_dwordx4 v[144:145], off
	s_add_i32 m0, s72, 0x2000
	s_add_u32 s72, s14, 0x40000
	v_lshl_add_u64 v[166:167], s[14:15], 0, v[152:153]
	s_addc_u32 s73, s15, 0
	s_add_i32 s74, s57, s48
	global_load_lds_dwordx4 v[166:167], off
	v_lshl_add_u64 v[212:213], s[72:73], 0, v[148:149]
	s_mov_b32 m0, s74
	v_lshl_add_u64 v[214:215], s[46:47], 0, v[150:151]
	global_load_lds_dwordx4 v[212:213], off
	v_lshl_add_u64 v[212:213], s[72:73], 0, v[152:153]
	s_add_i32 m0, s74, 0x2000
	s_nop 0
	global_load_lds_dwordx4 v[212:213], off
	v_lshl_add_u64 v[212:213], s[46:47], 0, v[146:147]
	s_mov_b32 m0, s43
	s_nop 0
	global_load_lds_dwordx4 v[212:213], off
	s_mov_b32 m0, s49
	s_nop 0
	global_load_lds_dwordx4 v[214:215], off
	s_waitcnt vmcnt(8)
	s_waitcnt lgkmcnt(0)
	s_barrier
	s_setprio 1
	s_waitcnt lgkmcnt(0)
	v_mfma_f32_16x16x32_bf16 v[92:95], v[128:131], v[180:183], v[92:95]
	v_mfma_f32_16x16x32_bf16 v[88:91], v[136:139], v[180:183], v[88:91]
	v_mfma_f32_16x16x32_bf16 v[84:87], v[128:131], v[188:191], v[84:87]
	v_mfma_f32_16x16x32_bf16 v[80:83], v[136:139], v[188:191], v[80:83]
	v_mfma_f32_16x16x32_bf16 v[76:79], v[128:131], v[196:199], v[76:79]
	v_mfma_f32_16x16x32_bf16 v[72:75], v[136:139], v[196:199], v[72:75]
	v_mfma_f32_16x16x32_bf16 v[68:71], v[128:131], v[204:207], v[68:71]
	v_mfma_f32_16x16x32_bf16 v[64:67], v[136:139], v[204:207], v[64:67]
	s_setprio 0
	s_setprio 1
	v_mfma_f32_16x16x32_bf16 v[92:95], v[132:135], v[184:187], v[92:95]
	v_mfma_f32_16x16x32_bf16 v[88:91], v[140:143], v[184:187], v[88:91]
	v_mfma_f32_16x16x32_bf16 v[84:87], v[132:135], v[192:195], v[84:87]
	v_mfma_f32_16x16x32_bf16 v[80:83], v[140:143], v[192:195], v[80:83]
	v_mfma_f32_16x16x32_bf16 v[76:79], v[132:135], v[200:203], v[76:79]
	v_mfma_f32_16x16x32_bf16 v[72:75], v[140:143], v[200:203], v[72:75]
	v_mfma_f32_16x16x32_bf16 v[68:71], v[132:135], v[208:211], v[68:71]
	v_mfma_f32_16x16x32_bf16 v[64:67], v[140:143], v[208:211], v[64:67]
	s_setprio 0
	s_setprio 1
	v_mfma_f32_16x16x32_bf16 v[28:31], v[158:161], v[180:183], v[28:31]
	v_mfma_f32_16x16x32_bf16 v[24:27], v[172:175], v[180:183], v[24:27]
	v_mfma_f32_16x16x32_bf16 v[20:23], v[158:161], v[188:191], v[20:23]
	v_mfma_f32_16x16x32_bf16 v[16:19], v[172:175], v[188:191], v[16:19]
	v_mfma_f32_16x16x32_bf16 v[12:15], v[158:161], v[196:199], v[12:15]
	v_mfma_f32_16x16x32_bf16 v[8:11], v[172:175], v[196:199], v[8:11]
	v_mfma_f32_16x16x32_bf16 v[4:7], v[158:161], v[204:207], v[4:7]
	v_mfma_f32_16x16x32_bf16 v[0:3], v[172:175], v[204:207], v[0:3]
	s_setprio 0
	s_setprio 1
	v_mfma_f32_16x16x32_bf16 v[28:31], v[162:165], v[184:187], v[28:31]
	v_mfma_f32_16x16x32_bf16 v[24:27], v[176:179], v[184:187], v[24:27]
	v_mfma_f32_16x16x32_bf16 v[20:23], v[162:165], v[192:195], v[20:23]
	v_mfma_f32_16x16x32_bf16 v[16:19], v[176:179], v[192:195], v[16:19]
	v_mfma_f32_16x16x32_bf16 v[12:15], v[162:165], v[200:203], v[12:15]
	v_mfma_f32_16x16x32_bf16 v[8:11], v[176:179], v[200:203], v[8:11]
	v_mfma_f32_16x16x32_bf16 v[4:7], v[162:165], v[208:211], v[4:7]
	v_mfma_f32_16x16x32_bf16 v[0:3], v[176:179], v[208:211], v[0:3]
	s_setprio 0
	s_barrier
; #define G_STAGE(bufoff, gbase, voff) do { _Pragma("unroll") for (int _i = 0; _i < 2; ++_i) \
;         __builtin_amdgcn_global_load_lds((const unsigned*)((const char*)(gbase) + voff[_i]), (LAS unsigned*)(lds + (bufoff) + ldsw + _i * 8192), 16, 0, 0); } while (0)
; #define G_LDA(dst, b, h) do { _Pragma("unroll") for (int m = 0; m < 4; ++m) _Pragma("unroll") for (int k = 0; k < 2; ++k) dst[m][k] = *(const LAS bf16x8*)(lds + G_SA(b, h) + aoff + m * 2048 + k * 1024); } while (0)
; #define G_LDB(dst, b, h) do { _Pragma("unroll") for (int n = 0; n < 2; ++n) _Pragma("unroll") for (int k = 0; k < 2; ++k) dst[n][k] = *(const LAS bf16x8*)(lds + G_SB(b, h) + boff + n * 2048 + k * 1024); } while (0)
; #define G_MMA(ai, bj, At_, Bt_) do { __builtin_amdgcn_s_setprio(1); _Pragma("unroll") for (int m = 0; m < 4; ++m) _Pragma("unroll") for (int n = 0; n < 2; ++n) _Pragma("unroll") for (int k = 0; k < 2; ++k) \
;         acc[ai][bj][m][n] = __builtin_amdgcn_mfma_f32_16x16x32_bf16(Bt_[n][k], At_[m][k], acc[ai][bj][m][n], 0, 0, 0); __builtin_amdgcn_s_setprio(0); } while (0)
; #define WAIT_V(n) asm volatile("s_waitcnt vmcnt(" #n ")" ::: "memory")
; #define WAIT_L(n) asm volatile("s_waitcnt lgkmcnt(" #n ")" ::: "memory")
; #define BAR __builtin_amdgcn_s_barrier()
; #define SCHED __builtin_amdgcn_sched_barrier(0)
; template <class Get, class Epi>
; DI void gemm_loop(int ntiles, int ld, char* shm, const Get& get, const Epi& epi) {
;     ...
;             G_LDB(B0, 1, 0); G_LDB(B1, 1, 1); SCHED; G_LDA(At, 1, 0); G_STAGE(G_SA(0, 1), a2 + hstep, voffA);
;             WAIT_V(8); WAIT_L(0); BAR; G_MMA(0, 0, At, B0); G_MMA(0, 1, At, B1); BAR; SCHED;
	s_add_i32 s72, 0, 0x18000
	s_add_i32 s73, 0, 0x1c000
	v_add_u32_e32 v140, s72, v168
	v_add_u32_e32 v176, s73, v168
	ds_read_b128 v[128:131], v140
	ds_read_b128 v[132:135], v140 offset:1024
	ds_read_b128 v[136:139], v140 offset:2048
	ds_read_b128 v[140:143], v140 offset:3072
	ds_read_b128 v[158:161], v176
	ds_read_b128 v[162:165], v176 offset:1024
	ds_read_b128 v[172:175], v176 offset:2048
	ds_read_b128 v[176:179], v176 offset:3072
	s_add_u32 s46, s46, 0x40000
	s_addc_u32 s47, s47, 0
	s_mov_b32 m0, s50
	v_lshl_add_u64 v[216:217], s[46:47], 0, v[146:147]
	ds_read_b128 v[180:183], v171 offset:32768
	ds_read_b128 v[184:187], v171 offset:33792
	ds_read_b128 v[188:191], v171 offset:34816
	ds_read_b128 v[192:195], v171 offset:35840
	ds_read_b128 v[196:199], v171 offset:36864
	ds_read_b128 v[200:203], v171 offset:37888
	ds_read_b128 v[204:207], v171 offset:38912
	ds_read_b128 v[208:211], v171 offset:39936
	global_load_lds_dwordx4 v[216:217], off
	v_lshl_add_u64 v[216:217], s[46:47], 0, v[150:151]
	s_mov_b32 m0, s51
	s_nop 0
	global_load_lds_dwordx4 v[216:217], off
	s_waitcnt vmcnt(8)
	s_waitcnt lgkmcnt(0)
	s_barrier
	s_setprio 1
	s_waitcnt lgkmcnt(0)
	v_mfma_f32_16x16x32_bf16 v[124:127], v[128:131], v[180:183], v[124:127]
	v_mfma_f32_16x16x32_bf16 v[120:123], v[136:139], v[180:183], v[120:123]
	v_mfma_f32_16x16x32_bf16 v[116:119], v[128:131], v[188:191], v[116:119]
	v_mfma_f32_16x16x32_bf16 v[112:115], v[136:139], v[188:191], v[112:115]
	v_mfma_f32_16x16x32_bf16 v[108:111], v[128:131], v[196:199], v[108:111]
	v_mfma_f32_16x16x32_bf16 v[104:107], v[136:139], v[196:199], v[104:107]
	v_mfma_f32_16x16x32_bf16 v[100:103], v[128:131], v[204:207], v[100:103]
	v_mfma_f32_16x16x32_bf16 v[96:99], v[136:139], v[204:207], v[96:99]
	s_setprio 0
	s_setprio 1
	v_mfma_f32_16x16x32_bf16 v[124:127], v[132:135], v[184:187], v[124:127]
	v_mfma_f32_16x16x32_bf16 v[120:123], v[140:143], v[184:187], v[120:123]
	v_mfma_f32_16x16x32_bf16 v[116:119], v[132:135], v[192:195], v[116:119]
	v_mfma_f32_16x16x32_bf16 v[112:115], v[140:143], v[192:195], v[112:115]
	v_mfma_f32_16x16x32_bf16 v[108:111], v[132:135], v[200:203], v[108:111]
	v_mfma_f32_16x16x32_bf16 v[104:107], v[140:143], v[200:203], v[104:107]
	v_mfma_f32_16x16x32_bf16 v[100:103], v[132:135], v[208:211], v[100:103]
	v_mfma_f32_16x16x32_bf16 v[96:99], v[140:143], v[208:211], v[96:99]
	s_setprio 0
	s_setprio 1
	v_mfma_f32_16x16x32_bf16 v[60:63], v[158:161], v[180:183], v[60:63]
	v_mfma_f32_16x16x32_bf16 v[56:59], v[172:175], v[180:183], v[56:59]
	v_mfma_f32_16x16x32_bf16 v[52:55], v[158:161], v[188:191], v[52:55]
	v_mfma_f32_16x16x32_bf16 v[48:51], v[172:175], v[188:191], v[48:51]
	v_mfma_f32_16x16x32_bf16 v[44:47], v[158:161], v[196:199], v[44:47]
	v_mfma_f32_16x16x32_bf16 v[40:43], v[172:175], v[196:199], v[40:43]
	v_mfma_f32_16x16x32_bf16 v[36:39], v[158:161], v[204:207], v[36:39]
	v_mfma_f32_16x16x32_bf16 v[32:35], v[172:175], v[204:207], v[32:35]
	s_setprio 0
	s_setprio 1
	v_mfma_f32_16x16x32_bf16 v[60:63], v[162:165], v[184:187], v[60:63]
	v_mfma_f32_16x16x32_bf16 v[56:59], v[176:179], v[184:187], v[56:59]
	v_mfma_f32_16x16x32_bf16 v[52:55], v[162:165], v[192:195], v[52:55]
	v_mfma_f32_16x16x32_bf16 v[48:51], v[176:179], v[192:195], v[48:51]
	v_mfma_f32_16x16x32_bf16 v[44:47], v[162:165], v[200:203], v[44:47]
	v_mfma_f32_16x16x32_bf16 v[40:43], v[176:179], v[200:203], v[40:43]
	v_mfma_f32_16x16x32_bf16 v[36:39], v[162:165], v[208:211], v[36:39]
	v_mfma_f32_16x16x32_bf16 v[32:35], v[176:179], v[208:211], v[32:35]
	s_setprio 0
	s_barrier
; #define G_STAGE(bufoff, gbase, voff) do { _Pragma("unroll") for (int _i = 0; _i < 2; ++_i) \
;         __builtin_amdgcn_global_load_lds((const unsigned*)((const char*)(gbase) + voff[_i]), (LAS unsigned*)(lds + (bufoff) + ldsw + _i * 8192), 16, 0, 0); } while (0)
; #define G_LDA(dst, b, h) do { _Pragma("unroll") for (int m = 0; m < 4; ++m) _Pragma("unroll") for (int k = 0; k < 2; ++k) dst[m][k] = *(const LAS bf16x8*)(lds + G_SA(b, h) + aoff + m * 2048 + k * 1024); } while (0)
; #define G_MMA(ai, bj, At_, Bt_) do { __builtin_amdgcn_s_setprio(1); _Pragma("unroll") for (int m = 0; m < 4; ++m) _Pragma("unroll") for (int n = 0; n < 2; ++n) _Pragma("unroll") for (int k = 0; k < 2; ++k) \
;         acc[ai][bj][m][n] = __builtin_amdgcn_mfma_f32_16x16x32_bf16(Bt_[n][k], At_[m][k], acc[ai][bj][m][n], 0, 0, 0); __builtin_amdgcn_s_setprio(0); } while (0)
; #define WAIT_V(n) asm volatile("s_waitcnt vmcnt(" #n ")" ::: "memory")
; #define WAIT_L(n) asm volatile("s_waitcnt lgkmcnt(" #n ")" ::: "memory")
; #define BAR __builtin_amdgcn_s_barrier()
; #define SCHED __builtin_amdgcn_sched_barrier(0)
; template <class Get, class Epi>
; DI void gemm_loop(int ntiles, int ld, char* shm, const Get& get, const Epi& epi) {
;     ...
;             G_LDA(At, 1, 1); G_STAGE(G_SB(1, 0), b3, voffB); G_STAGE(G_SB(1, 1), b3 + hstep, voffB); G_STAGE(G_SA(1, 0), a3, voffA);
;             WAIT_V(8); WAIT_L(0); BAR; G_MMA(1, 0, At, B0); G_MMA(1, 1, At, B1); BAR; SCHED;
	s_add_i32 s46, s72, s48
	v_lshl_add_u64 v[144:145], v[144:145], 0, s[4:5]
	s_mov_b32 m0, s46
	ds_read_b128 v[180:183], v171 offset:49152
	ds_read_b128 v[184:187], v171 offset:50176
	ds_read_b128 v[188:191], v171 offset:51200
	ds_read_b128 v[192:195], v171 offset:52224
	ds_read_b128 v[196:199], v171 offset:53248
	ds_read_b128 v[200:203], v171 offset:54272
	ds_read_b128 v[204:207], v171 offset:55296
	ds_read_b128 v[208:211], v171 offset:56320
	global_load_lds_dwordx4 v[144:145], off
	s_add_i32 m0, s46, 0x2000
	s_add_u32 s14, s14, 0x40080
	v_lshl_add_u64 v[144:145], v[166:167], 0, s[4:5]
	s_addc_u32 s15, s15, 0
	s_add_i32 s46, s73, s48
	global_load_lds_dwordx4 v[144:145], off
	v_lshl_add_u64 v[144:145], s[14:15], 0, v[148:149]
	s_mov_b32 m0, s46
	s_nop 0
	global_load_lds_dwordx4 v[144:145], off
	v_lshl_add_u64 v[144:145], s[14:15], 0, v[152:153]
	s_add_i32 m0, s46, 0x2000
	s_nop 0
	global_load_lds_dwordx4 v[144:145], off
	v_lshl_add_u64 v[144:145], v[212:213], 0, s[4:5]
	s_mov_b32 m0, s54
	s_nop 0
	global_load_lds_dwordx4 v[144:145], off
	v_lshl_add_u64 v[144:145], v[214:215], 0, s[4:5]
	s_mov_b32 m0, s55
	s_nop 0
	global_load_lds_dwordx4 v[144:145], off
	s_waitcnt vmcnt(8)
	s_waitcnt lgkmcnt(0)
	s_barrier
	s_setprio 1
	s_waitcnt lgkmcnt(0)
	v_mfma_f32_16x16x32_bf16 v[92:95], v[128:131], v[180:183], v[92:95]
	v_mfma_f32_16x16x32_bf16 v[88:91], v[136:139], v[180:183], v[88:91]
	v_mfma_f32_16x16x32_bf16 v[84:87], v[128:131], v[188:191], v[84:87]
	v_mfma_f32_16x16x32_bf16 v[80:83], v[136:139], v[188:191], v[80:83]
	v_mfma_f32_16x16x32_bf16 v[76:79], v[128:131], v[196:199], v[76:79]
	v_mfma_f32_16x16x32_bf16 v[72:75], v[136:139], v[196:199], v[72:75]
	v_mfma_f32_16x16x32_bf16 v[68:71], v[128:131], v[204:207], v[68:71]
	v_mfma_f32_16x16x32_bf16 v[64:67], v[136:139], v[204:207], v[64:67]
	s_setprio 0
	s_setprio 1
	v_mfma_f32_16x16x32_bf16 v[92:95], v[132:135], v[184:187], v[92:95]
	v_mfma_f32_16x16x32_bf16 v[88:91], v[140:143], v[184:187], v[88:91]
	v_mfma_f32_16x16x32_bf16 v[84:87], v[132:135], v[192:195], v[84:87]
	v_mfma_f32_16x16x32_bf16 v[80:83], v[140:143], v[192:195], v[80:83]
	v_mfma_f32_16x16x32_bf16 v[76:79], v[132:135], v[200:203], v[76:79]
	v_mfma_f32_16x16x32_bf16 v[72:75], v[140:143], v[200:203], v[72:75]
	v_mfma_f32_16x16x32_bf16 v[68:71], v[132:135], v[208:211], v[68:71]
	v_mfma_f32_16x16x32_bf16 v[64:67], v[140:143], v[208:211], v[64:67]
	s_setprio 0
	s_setprio 1
	v_mfma_f32_16x16x32_bf16 v[28:31], v[158:161], v[180:183], v[28:31]
	v_mfma_f32_16x16x32_bf16 v[24:27], v[172:175], v[180:183], v[24:27]
	v_mfma_f32_16x16x32_bf16 v[20:23], v[158:161], v[188:191], v[20:23]
	v_mfma_f32_16x16x32_bf16 v[16:19], v[172:175], v[188:191], v[16:19]
	v_mfma_f32_16x16x32_bf16 v[12:15], v[158:161], v[196:199], v[12:15]
	v_mfma_f32_16x16x32_bf16 v[8:11], v[172:175], v[196:199], v[8:11]
	v_mfma_f32_16x16x32_bf16 v[4:7], v[158:161], v[204:207], v[4:7]
	v_mfma_f32_16x16x32_bf16 v[0:3], v[172:175], v[204:207], v[0:3]
	s_setprio 0
	s_setprio 1
	v_mfma_f32_16x16x32_bf16 v[28:31], v[162:165], v[184:187], v[28:31]
	v_mfma_f32_16x16x32_bf16 v[24:27], v[176:179], v[184:187], v[24:27]
	v_mfma_f32_16x16x32_bf16 v[20:23], v[162:165], v[192:195], v[20:23]
	v_mfma_f32_16x16x32_bf16 v[16:19], v[176:179], v[192:195], v[16:19]
	v_mfma_f32_16x16x32_bf16 v[12:15], v[162:165], v[200:203], v[12:15]
	v_mfma_f32_16x16x32_bf16 v[8:11], v[176:179], v[200:203], v[8:11]
	v_mfma_f32_16x16x32_bf16 v[4:7], v[162:165], v[208:211], v[4:7]
	v_mfma_f32_16x16x32_bf16 v[0:3], v[176:179], v[208:211], v[0:3]
	s_setprio 0
	s_barrier
	s_add_i32 s71, s71, 2
	s_add_u32 s44, s44, 0x100
	s_addc_u32 s45, s45, 0
	s_add_u32 s65, s65, 0x100
	s_addc_u32 s70, s70, 0
	s_cmp_gt_u32 s71, 13
	s_cbranch_scc0 .LBB0_3466

; #define G_STAGE(bufoff, gbase, voff) do { _Pragma("unroll") for (int _i = 0; _i < 2; ++_i) \
;         __builtin_amdgcn_global_load_lds((const unsigned*)((const char*)(gbase) + voff[_i]), (LAS unsigned*)(lds + (bufoff) + ldsw + _i * 8192), 16, 0, 0); } while (0)
; #define G_LDA(dst, b, h) do { _Pragma("unroll") for (int m = 0; m < 4; ++m) _Pragma("unroll") for (int k = 0; k < 2; ++k) dst[m][k] = *(const LAS bf16x8*)(lds + G_SA(b, h) + aoff + m * 2048 + k * 1024); } while (0)
; #define G_MMA(ai, bj, At_, Bt_) do { __builtin_amdgcn_s_setprio(1); _Pragma("unroll") for (int m = 0; m < 4; ++m) _Pragma("unroll") for (int n = 0; n < 2; ++n) _Pragma("unroll") for (int k = 0; k < 2; ++k) \
;         acc[ai][bj][m][n] = __builtin_amdgcn_mfma_f32_16x16x32_bf16(Bt_[n][k], At_[m][k], acc[ai][bj][m][n], 0, 0, 0); __builtin_amdgcn_s_setprio(0); } while (0)
; #define WAIT_V(n) asm volatile("s_waitcnt vmcnt(" #n ")" ::: "memory")
; #define WAIT_L(n) asm volatile("s_waitcnt lgkmcnt(" #n ")" ::: "memory")
; #define BAR __builtin_amdgcn_s_barrier()
; #define SCHED __builtin_amdgcn_sched_barrier(0)
; template <class Get, class Epi>
; DI void gemm_loop(int ntiles, int ld, char* shm, const Get& get, const Epi& epi) {
;     ...
;             WAIT_V(8); WAIT_L(0); BAR; G_MMA(0, 0, At, B0); G_MMA(0, 1, At, B1); BAR; SCHED;
;             G_LDA(At, 0, 1); G_STAGE(G_SB(0, 0), b2, voffB); G_STAGE(G_SB(0, 1), b2 + hstep, voffB); G_STAGE(G_SA(0, 0), a2, voffA);
.Lrj_3679_0:
	s_waitcnt lgkmcnt(0)
	s_barrier
	s_setprio 1
	s_waitcnt lgkmcnt(0)
	v_mfma_f32_16x16x32_bf16 v[124:127], v[144:147], v[176:179], 0
	v_mfma_f32_16x16x32_bf16 v[120:123], v[152:155], v[176:179], 0
	v_mfma_f32_16x16x32_bf16 v[108:111], v[144:147], v[184:187], 0
	v_mfma_f32_16x16x32_bf16 v[104:107], v[152:155], v[184:187], 0
	v_mfma_f32_16x16x32_bf16 v[92:95], v[144:147], v[192:195], 0
	v_mfma_f32_16x16x32_bf16 v[88:91], v[152:155], v[192:195], 0
	v_mfma_f32_16x16x32_bf16 v[76:79], v[144:147], v[200:203], 0
	v_mfma_f32_16x16x32_bf16 v[72:75], v[152:155], v[200:203], 0
	s_setprio 0
	s_setprio 1
	v_mfma_f32_16x16x32_bf16 v[124:127], v[148:151], v[180:183], v[124:127]
	v_mfma_f32_16x16x32_bf16 v[120:123], v[156:159], v[180:183], v[120:123]
	v_mfma_f32_16x16x32_bf16 v[108:111], v[148:151], v[188:191], v[108:111]
	v_mfma_f32_16x16x32_bf16 v[104:107], v[156:159], v[188:191], v[104:107]
	v_mfma_f32_16x16x32_bf16 v[92:95], v[148:151], v[196:199], v[92:95]
	v_mfma_f32_16x16x32_bf16 v[88:91], v[156:159], v[196:199], v[88:91]
	v_mfma_f32_16x16x32_bf16 v[76:79], v[148:151], v[204:207], v[76:79]
	v_mfma_f32_16x16x32_bf16 v[72:75], v[156:159], v[204:207], v[72:75]
	s_setprio 0
	s_setprio 1
	v_mfma_f32_16x16x32_bf16 v[116:119], v[160:163], v[176:179], 0
	v_mfma_f32_16x16x32_bf16 v[112:115], v[168:171], v[176:179], 0
	v_mfma_f32_16x16x32_bf16 v[100:103], v[160:163], v[184:187], 0
	v_mfma_f32_16x16x32_bf16 v[96:99], v[168:171], v[184:187], 0
	v_mfma_f32_16x16x32_bf16 v[84:87], v[160:163], v[192:195], 0
	v_mfma_f32_16x16x32_bf16 v[80:83], v[168:171], v[192:195], 0
	v_mfma_f32_16x16x32_bf16 v[68:71], v[160:163], v[200:203], 0
	v_mfma_f32_16x16x32_bf16 v[64:67], v[168:171], v[200:203], 0
	s_setprio 0
	s_setprio 1
	v_mfma_f32_16x16x32_bf16 v[116:119], v[164:167], v[180:183], v[116:119]
	v_mfma_f32_16x16x32_bf16 v[112:115], v[172:175], v[180:183], v[112:115]
	v_mfma_f32_16x16x32_bf16 v[100:103], v[164:167], v[188:191], v[100:103]
	v_mfma_f32_16x16x32_bf16 v[96:99], v[172:175], v[188:191], v[96:99]
	v_mfma_f32_16x16x32_bf16 v[84:87], v[164:167], v[196:199], v[84:87]
	v_mfma_f32_16x16x32_bf16 v[80:83], v[172:175], v[196:199], v[80:83]
	v_mfma_f32_16x16x32_bf16 v[68:71], v[164:167], v[204:207], v[68:71]
	v_mfma_f32_16x16x32_bf16 v[64:67], v[172:175], v[204:207], v[64:67]
	s_setprio 0
	s_barrier
	s_add_i32 s54, s44, s38
	v_lshl_add_u64 v[208:209], s[14:15], 0, v[132:133]
	s_mov_b32 m0, s54
	ds_read_b128 v[176:179], v143 offset:16384
	ds_read_b128 v[180:183], v143 offset:17408
	ds_read_b128 v[184:187], v143 offset:18432
	ds_read_b128 v[188:191], v143 offset:19456
	ds_read_b128 v[192:195], v143 offset:20480
	ds_read_b128 v[196:199], v143 offset:21504
	ds_read_b128 v[200:203], v143 offset:22528
	ds_read_b128 v[204:207], v143 offset:23552
	global_load_lds_dwordx4 v[208:209], off
	s_add_i32 m0, s54, 0x2000
	s_add_u32 s54, s14, 0x40000
	v_lshl_add_u64 v[210:211], s[14:15], 0, v[128:129]
	s_addc_u32 s55, s15, 0
	s_add_i32 s56, s45, s38
	global_load_lds_dwordx4 v[210:211], off
	v_lshl_add_u64 v[212:213], s[54:55], 0, v[132:133]
	s_mov_b32 m0, s56
	v_lshl_add_u64 v[214:215], s[36:37], 0, v[130:131]
	global_load_lds_dwordx4 v[212:213], off
	v_lshl_add_u64 v[212:213], s[54:55], 0, v[128:129]
	s_add_i32 m0, s56, 0x2000
	s_nop 0
	global_load_lds_dwordx4 v[212:213], off
	v_lshl_add_u64 v[212:213], s[36:37], 0, v[134:135]
	s_mov_b32 m0, s25
	s_nop 0
	global_load_lds_dwordx4 v[212:213], off
	s_mov_b32 m0, s31
	s_nop 0
	global_load_lds_dwordx4 v[214:215], off
	s_cmp_lg_u32 s100, 0
	s_cbranch_scc0 .Lrf_3679_1
	s_waitcnt vmcnt(16)
	s_branch .Lrj_3679_1

; #define G_STAGE(bufoff, gbase, voff) do { _Pragma("unroll") for (int _i = 0; _i < 2; ++_i) \
;         __builtin_amdgcn_global_load_lds((const unsigned*)((const char*)(gbase) + voff[_i]), (LAS unsigned*)(lds + (bufoff) + ldsw + _i * 8192), 16, 0, 0); } while (0)
; #define G_LDA(dst, b, h) do { _Pragma("unroll") for (int m = 0; m < 4; ++m) _Pragma("unroll") for (int k = 0; k < 2; ++k) dst[m][k] = *(const LAS bf16x8*)(lds + G_SA(b, h) + aoff + m * 2048 + k * 1024); } while (0)
; #define G_LDB(dst, b, h) do { _Pragma("unroll") for (int n = 0; n < 2; ++n) _Pragma("unroll") for (int k = 0; k < 2; ++k) dst[n][k] = *(const LAS bf16x8*)(lds + G_SB(b, h) + boff + n * 2048 + k * 1024); } while (0)
; #define G_MMA(ai, bj, At_, Bt_) do { __builtin_amdgcn_s_setprio(1); _Pragma("unroll") for (int m = 0; m < 4; ++m) _Pragma("unroll") for (int n = 0; n < 2; ++n) _Pragma("unroll") for (int k = 0; k < 2; ++k) \
;         acc[ai][bj][m][n] = __builtin_amdgcn_mfma_f32_16x16x32_bf16(Bt_[n][k], At_[m][k], acc[ai][bj][m][n], 0, 0, 0); __builtin_amdgcn_s_setprio(0); } while (0)
; #define WAIT_V(n) asm volatile("s_waitcnt vmcnt(" #n ")" ::: "memory")
; #define WAIT_L(n) asm volatile("s_waitcnt lgkmcnt(" #n ")" ::: "memory")
; #define BAR __builtin_amdgcn_s_barrier()
; #define SCHED __builtin_amdgcn_sched_barrier(0)
; template <class Get, class Epi>
; DI void gemm_loop(int ntiles, int ld, char* shm, const Get& get, const Epi& epi) {
;     ...
;             WAIT_V(8); WAIT_L(0); BAR; G_MMA(1, 0, At, B0); G_MMA(1, 1, At, B1); BAR; SCHED;
;             G_LDB(B0, 1, 0); G_LDB(B1, 1, 1); SCHED; G_LDA(At, 1, 0); G_STAGE(G_SA(0, 1), a2 + hstep, voffA);
;             WAIT_V(8); WAIT_L(0); BAR; G_MMA(0, 0, At, B0); G_MMA(0, 1, At, B1); BAR; SCHED;
.Lrj_3679_1:
	s_waitcnt lgkmcnt(0)
	s_barrier
	s_setprio 1
	s_waitcnt lgkmcnt(0)
	v_mfma_f32_16x16x32_bf16 v[60:63], v[144:147], v[176:179], 0
	v_mfma_f32_16x16x32_bf16 v[56:59], v[152:155], v[176:179], 0
	v_mfma_f32_16x16x32_bf16 v[44:47], v[144:147], v[184:187], 0
	v_mfma_f32_16x16x32_bf16 v[40:43], v[152:155], v[184:187], 0
	v_mfma_f32_16x16x32_bf16 v[28:31], v[144:147], v[192:195], 0
	v_mfma_f32_16x16x32_bf16 v[24:27], v[152:155], v[192:195], 0
	v_mfma_f32_16x16x32_bf16 v[12:15], v[144:147], v[200:203], 0
	v_mfma_f32_16x16x32_bf16 v[8:11], v[152:155], v[200:203], 0
	s_setprio 0
	s_setprio 1
	v_mfma_f32_16x16x32_bf16 v[60:63], v[148:151], v[180:183], v[60:63]
	v_mfma_f32_16x16x32_bf16 v[56:59], v[156:159], v[180:183], v[56:59]
	v_mfma_f32_16x16x32_bf16 v[44:47], v[148:151], v[188:191], v[44:47]
	v_mfma_f32_16x16x32_bf16 v[40:43], v[156:159], v[188:191], v[40:43]
	v_mfma_f32_16x16x32_bf16 v[28:31], v[148:151], v[196:199], v[28:31]
	v_mfma_f32_16x16x32_bf16 v[24:27], v[156:159], v[196:199], v[24:27]
	v_mfma_f32_16x16x32_bf16 v[12:15], v[148:151], v[204:207], v[12:15]
	v_mfma_f32_16x16x32_bf16 v[8:11], v[156:159], v[204:207], v[8:11]
	s_setprio 0
	s_setprio 1
	v_mfma_f32_16x16x32_bf16 v[52:55], v[160:163], v[176:179], 0
	v_mfma_f32_16x16x32_bf16 v[48:51], v[168:171], v[176:179], 0
	v_mfma_f32_16x16x32_bf16 v[36:39], v[160:163], v[184:187], 0
	v_mfma_f32_16x16x32_bf16 v[32:35], v[168:171], v[184:187], 0
	v_mfma_f32_16x16x32_bf16 v[20:23], v[160:163], v[192:195], 0
	v_mfma_f32_16x16x32_bf16 v[16:19], v[168:171], v[192:195], 0
	v_mfma_f32_16x16x32_bf16 v[4:7], v[160:163], v[200:203], 0
	v_mfma_f32_16x16x32_bf16 v[0:3], v[168:171], v[200:203], 0
	s_setprio 0
	s_setprio 1
	v_mfma_f32_16x16x32_bf16 v[52:55], v[164:167], v[180:183], v[52:55]
	v_mfma_f32_16x16x32_bf16 v[48:51], v[172:175], v[180:183], v[48:51]
	v_mfma_f32_16x16x32_bf16 v[36:39], v[164:167], v[188:191], v[36:39]
	v_mfma_f32_16x16x32_bf16 v[32:35], v[172:175], v[188:191], v[32:35]
	v_mfma_f32_16x16x32_bf16 v[20:23], v[164:167], v[196:199], v[20:23]
	v_mfma_f32_16x16x32_bf16 v[16:19], v[172:175], v[196:199], v[16:19]
	v_mfma_f32_16x16x32_bf16 v[4:7], v[164:167], v[204:207], v[4:7]
	v_mfma_f32_16x16x32_bf16 v[0:3], v[172:175], v[204:207], v[0:3]
	s_setprio 0
	s_barrier
	s_add_i32 s54, 0, 0x18000
	s_add_i32 s55, 0, 0x1c000
	v_add_u32_e32 v156, s54, v140
	v_add_u32_e32 v172, s55, v140
	ds_read_b128 v[144:147], v156
	ds_read_b128 v[148:151], v156 offset:1024
	ds_read_b128 v[152:155], v156 offset:2048
	ds_read_b128 v[156:159], v156 offset:3072
	ds_read_b128 v[160:163], v172
	ds_read_b128 v[164:167], v172 offset:1024
	ds_read_b128 v[168:171], v172 offset:2048
	ds_read_b128 v[172:175], v172 offset:3072
	s_add_u32 s36, s36, 0x40000
	s_addc_u32 s37, s37, 0
	s_mov_b32 m0, s40
	v_lshl_add_u64 v[216:217], s[36:37], 0, v[134:135]
	ds_read_b128 v[176:179], v143 offset:32768
	ds_read_b128 v[180:183], v143 offset:33792
	ds_read_b128 v[184:187], v143 offset:34816
	ds_read_b128 v[188:191], v143 offset:35840
	ds_read_b128 v[192:195], v143 offset:36864
	ds_read_b128 v[196:199], v143 offset:37888
	ds_read_b128 v[200:203], v143 offset:38912
	ds_read_b128 v[204:207], v143 offset:39936
	global_load_lds_dwordx4 v[216:217], off
	v_lshl_add_u64 v[216:217], s[36:37], 0, v[130:131]
	s_mov_b32 m0, s41
	s_nop 0
	global_load_lds_dwordx4 v[216:217], off
	s_waitcnt vmcnt(8)
	s_waitcnt lgkmcnt(0)
	s_barrier
	s_setprio 1
	s_waitcnt lgkmcnt(0)
	v_mfma_f32_16x16x32_bf16 v[124:127], v[144:147], v[176:179], v[124:127]
	v_mfma_f32_16x16x32_bf16 v[120:123], v[152:155], v[176:179], v[120:123]
	v_mfma_f32_16x16x32_bf16 v[108:111], v[144:147], v[184:187], v[108:111]
	v_mfma_f32_16x16x32_bf16 v[104:107], v[152:155], v[184:187], v[104:107]
	v_mfma_f32_16x16x32_bf16 v[92:95], v[144:147], v[192:195], v[92:95]
	v_mfma_f32_16x16x32_bf16 v[88:91], v[152:155], v[192:195], v[88:91]
	v_mfma_f32_16x16x32_bf16 v[76:79], v[144:147], v[200:203], v[76:79]
	v_mfma_f32_16x16x32_bf16 v[72:75], v[152:155], v[200:203], v[72:75]
	s_setprio 0
	s_setprio 1
	v_mfma_f32_16x16x32_bf16 v[124:127], v[148:151], v[180:183], v[124:127]
	v_mfma_f32_16x16x32_bf16 v[120:123], v[156:159], v[180:183], v[120:123]
	v_mfma_f32_16x16x32_bf16 v[108:111], v[148:151], v[188:191], v[108:111]
	v_mfma_f32_16x16x32_bf16 v[104:107], v[156:159], v[188:191], v[104:107]
	v_mfma_f32_16x16x32_bf16 v[92:95], v[148:151], v[196:199], v[92:95]
	v_mfma_f32_16x16x32_bf16 v[88:91], v[156:159], v[196:199], v[88:91]
	v_mfma_f32_16x16x32_bf16 v[76:79], v[148:151], v[204:207], v[76:79]
	v_mfma_f32_16x16x32_bf16 v[72:75], v[156:159], v[204:207], v[72:75]
	s_setprio 0
	s_setprio 1
	v_mfma_f32_16x16x32_bf16 v[116:119], v[160:163], v[176:179], v[116:119]
	v_mfma_f32_16x16x32_bf16 v[112:115], v[168:171], v[176:179], v[112:115]
	v_mfma_f32_16x16x32_bf16 v[100:103], v[160:163], v[184:187], v[100:103]
	v_mfma_f32_16x16x32_bf16 v[96:99], v[168:171], v[184:187], v[96:99]
	v_mfma_f32_16x16x32_bf16 v[84:87], v[160:163], v[192:195], v[84:87]
	v_mfma_f32_16x16x32_bf16 v[80:83], v[168:171], v[192:195], v[80:83]
	v_mfma_f32_16x16x32_bf16 v[68:71], v[160:163], v[200:203], v[68:71]
	v_mfma_f32_16x16x32_bf16 v[64:67], v[168:171], v[200:203], v[64:67]
	s_setprio 0
	s_setprio 1
	v_mfma_f32_16x16x32_bf16 v[116:119], v[164:167], v[180:183], v[116:119]
	v_mfma_f32_16x16x32_bf16 v[112:115], v[172:175], v[180:183], v[112:115]
	v_mfma_f32_16x16x32_bf16 v[100:103], v[164:167], v[188:191], v[100:103]
	v_mfma_f32_16x16x32_bf16 v[96:99], v[172:175], v[188:191], v[96:99]
	v_mfma_f32_16x16x32_bf16 v[84:87], v[164:167], v[196:199], v[84:87]
	v_mfma_f32_16x16x32_bf16 v[80:83], v[172:175], v[196:199], v[80:83]
	v_mfma_f32_16x16x32_bf16 v[68:71], v[164:167], v[204:207], v[68:71]
	v_mfma_f32_16x16x32_bf16 v[64:67], v[172:175], v[204:207], v[64:67]
	s_setprio 0
	s_barrier
; #define G_STAGE(bufoff, gbase, voff) do { _Pragma("unroll") for (int _i = 0; _i < 2; ++_i) \
;         __builtin_amdgcn_global_load_lds((const unsigned*)((const char*)(gbase) + voff[_i]), (LAS unsigned*)(lds + (bufoff) + ldsw + _i * 8192), 16, 0, 0); } while (0)
; #define G_LDA(dst, b, h) do { _Pragma("unroll") for (int m = 0; m < 4; ++m) _Pragma("unroll") for (int k = 0; k < 2; ++k) dst[m][k] = *(const LAS bf16x8*)(lds + G_SA(b, h) + aoff + m * 2048 + k * 1024); } while (0)
; #define G_LDB(dst, b, h) do { _Pragma("unroll") for (int n = 0; n < 2; ++n) _Pragma("unroll") for (int k = 0; k < 2; ++k) dst[n][k] = *(const LAS bf16x8*)(lds + G_SB(b, h) + boff + n * 2048 + k * 1024); } while (0)
; #define G_MMA(ai, bj, At_, Bt_) do { __builtin_amdgcn_s_setprio(1); _Pragma("unroll") for (int m = 0; m < 4; ++m) _Pragma("unroll") for (int n = 0; n < 2; ++n) _Pragma("unroll") for (int k = 0; k < 2; ++k) \
;         acc[ai][bj][m][n] = __builtin_amdgcn_mfma_f32_16x16x32_bf16(Bt_[n][k], At_[m][k], acc[ai][bj][m][n], 0, 0, 0); __builtin_amdgcn_s_setprio(0); } while (0)
; #define WAIT_V(n) asm volatile("s_waitcnt vmcnt(" #n ")" ::: "memory")
; #define WAIT_L(n) asm volatile("s_waitcnt lgkmcnt(" #n ")" ::: "memory")
; #define BAR __builtin_amdgcn_s_barrier()
; #define SCHED __builtin_amdgcn_sched_barrier(0)
; template <class Get, class Epi>
; DI void gemm_loop(int ntiles, int ld, char* shm, const Get& get, const Epi& epi) {
;     ...
;             G_LDB(B0, 0, 0); G_LDB(B1, 0, 1); SCHED; G_LDA(At, 0, 0); G_STAGE(G_SA(1, 1), a1 + hstep, voffA);
;             WAIT_V(8); WAIT_L(0); BAR; G_MMA(0, 0, At, B0); G_MMA(0, 1, At, B1); BAR; SCHED;
;     ...
;             G_LDA(At, 1, 1); G_STAGE(G_SB(1, 0), b3, voffB); G_STAGE(G_SB(1, 1), b3 + hstep, voffB); G_STAGE(G_SA(1, 0), a3, voffA);
;             WAIT_V(8); WAIT_L(0); BAR; G_MMA(1, 0, At, B0); G_MMA(1, 1, At, B1); BAR; SCHED;
;         }
	s_add_i32 s36, s54, s38
	v_lshl_add_u64 v[208:209], v[208:209], 0, s[2:3]
	s_mov_b32 m0, s36
	ds_read_b128 v[176:179], v143 offset:49152
	ds_read_b128 v[180:183], v143 offset:50176
	ds_read_b128 v[184:187], v143 offset:51200
	ds_read_b128 v[188:191], v143 offset:52224
	ds_read_b128 v[192:195], v143 offset:53248
	ds_read_b128 v[196:199], v143 offset:54272
	ds_read_b128 v[200:203], v143 offset:55296
	ds_read_b128 v[204:207], v143 offset:56320
	global_load_lds_dwordx4 v[208:209], off
	s_add_i32 m0, s36, 0x2000
	s_add_u32 s14, s14, 0x40080
	v_lshl_add_u64 v[208:209], v[210:211], 0, s[2:3]
	s_addc_u32 s15, s15, 0
	s_add_i32 s36, s55, s38
	global_load_lds_dwordx4 v[208:209], off
	v_lshl_add_u64 v[208:209], s[14:15], 0, v[132:133]
	s_mov_b32 m0, s36
	s_nop 0
	global_load_lds_dwordx4 v[208:209], off
	v_lshl_add_u64 v[208:209], s[14:15], 0, v[128:129]
	s_add_i32 m0, s36, 0x2000
	s_nop 0
	global_load_lds_dwordx4 v[208:209], off
	v_lshl_add_u64 v[208:209], v[212:213], 0, s[2:3]
	s_mov_b32 m0, s42
	s_nop 0
	global_load_lds_dwordx4 v[208:209], off
	v_lshl_add_u64 v[208:209], v[214:215], 0, s[2:3]
	s_mov_b32 m0, s43
	s_nop 0
	global_load_lds_dwordx4 v[208:209], off
	s_waitcnt vmcnt(8)
	s_waitcnt lgkmcnt(0)
	s_barrier
	s_setprio 1
	s_waitcnt lgkmcnt(0)
	v_mfma_f32_16x16x32_bf16 v[60:63], v[144:147], v[176:179], v[60:63]
	v_mfma_f32_16x16x32_bf16 v[56:59], v[152:155], v[176:179], v[56:59]
	v_mfma_f32_16x16x32_bf16 v[44:47], v[144:147], v[184:187], v[44:47]
	v_mfma_f32_16x16x32_bf16 v[40:43], v[152:155], v[184:187], v[40:43]
	v_mfma_f32_16x16x32_bf16 v[28:31], v[144:147], v[192:195], v[28:31]
	v_mfma_f32_16x16x32_bf16 v[24:27], v[152:155], v[192:195], v[24:27]
	v_mfma_f32_16x16x32_bf16 v[12:15], v[144:147], v[200:203], v[12:15]
	v_mfma_f32_16x16x32_bf16 v[8:11], v[152:155], v[200:203], v[8:11]
	s_setprio 0
	s_setprio 1
	v_mfma_f32_16x16x32_bf16 v[60:63], v[148:151], v[180:183], v[60:63]
	v_mfma_f32_16x16x32_bf16 v[56:59], v[156:159], v[180:183], v[56:59]
	v_mfma_f32_16x16x32_bf16 v[44:47], v[148:151], v[188:191], v[44:47]
	v_mfma_f32_16x16x32_bf16 v[40:43], v[156:159], v[188:191], v[40:43]
	v_mfma_f32_16x16x32_bf16 v[28:31], v[148:151], v[196:199], v[28:31]
	v_mfma_f32_16x16x32_bf16 v[24:27], v[156:159], v[196:199], v[24:27]
	v_mfma_f32_16x16x32_bf16 v[12:15], v[148:151], v[204:207], v[12:15]
	v_mfma_f32_16x16x32_bf16 v[8:11], v[156:159], v[204:207], v[8:11]
	s_setprio 0
	s_setprio 1
	v_mfma_f32_16x16x32_bf16 v[52:55], v[160:163], v[176:179], v[52:55]
	v_mfma_f32_16x16x32_bf16 v[48:51], v[168:171], v[176:179], v[48:51]
	v_mfma_f32_16x16x32_bf16 v[36:39], v[160:163], v[184:187], v[36:39]
	v_mfma_f32_16x16x32_bf16 v[32:35], v[168:171], v[184:187], v[32:35]
	v_mfma_f32_16x16x32_bf16 v[20:23], v[160:163], v[192:195], v[20:23]
	v_mfma_f32_16x16x32_bf16 v[16:19], v[168:171], v[192:195], v[16:19]
	v_mfma_f32_16x16x32_bf16 v[4:7], v[160:163], v[200:203], v[4:7]
	v_mfma_f32_16x16x32_bf16 v[0:3], v[168:171], v[200:203], v[0:3]
	s_setprio 0
	s_setprio 1
	v_mfma_f32_16x16x32_bf16 v[52:55], v[164:167], v[180:183], v[52:55]
	v_mfma_f32_16x16x32_bf16 v[48:51], v[172:175], v[180:183], v[48:51]
	v_mfma_f32_16x16x32_bf16 v[36:39], v[164:167], v[188:191], v[36:39]
	v_mfma_f32_16x16x32_bf16 v[32:35], v[172:175], v[188:191], v[32:35]
	v_mfma_f32_16x16x32_bf16 v[20:23], v[164:167], v[196:199], v[20:23]
	v_mfma_f32_16x16x32_bf16 v[16:19], v[172:175], v[196:199], v[16:19]
	v_mfma_f32_16x16x32_bf16 v[4:7], v[164:167], v[204:207], v[4:7]
	v_mfma_f32_16x16x32_bf16 v[0:3], v[172:175], v[204:207], v[0:3]
	s_setprio 0
	s_barrier
	s_add_i32 s53, s53, 2
	s_add_u32 s34, s34, 0x100
	s_addc_u32 s35, s35, 0
	s_add_u32 s51, s51, 0x100
	s_addc_u32 s52, s52, 0
	s_cmp_gt_u32 s53, 13
	s_cbranch_scc0 .LBB0_3679
	s_branch .Lpost_3679
.LBB0_3679:
	ds_read_b128 v[144:147], v141
	ds_read_b128 v[148:151], v141 offset:1024
	ds_read_b128 v[152:155], v141 offset:2048
	ds_read_b128 v[156:159], v141 offset:3072
	ds_read_b128 v[160:163], v142
	ds_read_b128 v[164:167], v142 offset:1024
	ds_read_b128 v[168:171], v142 offset:2048
	ds_read_b128 v[172:175], v142 offset:3072
	s_add_u32 s14, s34, 0xfffc0080
	s_addc_u32 s15, s35, -1
	s_cmp_eq_u32 s53, 12
	s_cselect_b32 s37, s9, s15
	s_cselect_b32 s36, s49, s14
	s_cselect_b32 s15, s11, s52
	s_cselect_b32 s14, s50, s51
	v_lshl_add_u64 v[208:209], s[34:35], 0, v[136:137]
	s_add_i32 m0, s25, 0xc000
	ds_read_b128 v[176:179], v143
	ds_read_b128 v[180:183], v143 offset:1024
	ds_read_b128 v[184:187], v143 offset:2048
	ds_read_b128 v[188:191], v143 offset:3072
	ds_read_b128 v[192:195], v143 offset:4096
	ds_read_b128 v[196:199], v143 offset:5120
	ds_read_b128 v[200:203], v143 offset:6144
	ds_read_b128 v[204:207], v143 offset:7168
	global_load_lds_dwordx4 v[208:209], off
	v_lshl_add_u64 v[208:209], s[34:35], 0, v[138:139]
	s_add_i32 m0, s25, 0xe000
	s_nop 0
	global_load_lds_dwordx4 v[208:209], off
	s_waitcnt vmcnt(8)
	s_waitcnt lgkmcnt(0)
	s_barrier
; #define G_STAGE(bufoff, gbase, voff) do { _Pragma("unroll") for (int _i = 0; _i < 2; ++_i) \
;         __builtin_amdgcn_global_load_lds((const unsigned*)((const char*)(gbase) + voff[_i]), (LAS unsigned*)(lds + (bufoff) + ldsw + _i * 8192), 16, 0, 0); } while (0)
; #define G_LDA(dst, b, h) do { _Pragma("unroll") for (int m = 0; m < 4; ++m) _Pragma("unroll") for (int k = 0; k < 2; ++k) dst[m][k] = *(const LAS bf16x8*)(lds + G_SA(b, h) + aoff + m * 2048 + k * 1024); } while (0)
; #define G_MMA(ai, bj, At_, Bt_) do { __builtin_amdgcn_s_setprio(1); _Pragma("unroll") for (int m = 0; m < 4; ++m) _Pragma("unroll") for (int n = 0; n < 2; ++n) _Pragma("unroll") for (int k = 0; k < 2; ++k) \
;         acc[ai][bj][m][n] = __builtin_amdgcn_mfma_f32_16x16x32_bf16(Bt_[n][k], At_[m][k], acc[ai][bj][m][n], 0, 0, 0); __builtin_amdgcn_s_setprio(0); } while (0)
; #define WAIT_V(n) asm volatile("s_waitcnt vmcnt(" #n ")" ::: "memory")
; #define WAIT_L(n) asm volatile("s_waitcnt lgkmcnt(" #n ")" ::: "memory")
; #define BAR __builtin_amdgcn_s_barrier()
; #define SCHED __builtin_amdgcn_sched_barrier(0)
; template <class Get, class Epi>
; DI void gemm_loop(int ntiles, int ld, char* shm, const Get& get, const Epi& epi) {
;     ...
;             WAIT_V(8); WAIT_L(0); BAR; G_MMA(0, 0, At, B0); G_MMA(0, 1, At, B1); BAR; SCHED;
;             G_LDA(At, 0, 1); G_STAGE(G_SB(0, 0), b2, voffB); G_STAGE(G_SB(0, 1), b2 + hstep, voffB); G_STAGE(G_SA(0, 0), a2, voffA);
;             WAIT_V(8); WAIT_L(0); BAR; G_MMA(1, 0, At, B0); G_MMA(1, 1, At, B1); BAR; SCHED;
	s_setprio 1
	s_waitcnt lgkmcnt(0)
	v_mfma_f32_16x16x32_bf16 v[124:127], v[144:147], v[176:179], v[124:127]
	v_mfma_f32_16x16x32_bf16 v[120:123], v[152:155], v[176:179], v[120:123]
	v_mfma_f32_16x16x32_bf16 v[108:111], v[144:147], v[184:187], v[108:111]
	v_mfma_f32_16x16x32_bf16 v[104:107], v[152:155], v[184:187], v[104:107]
	v_mfma_f32_16x16x32_bf16 v[92:95], v[144:147], v[192:195], v[92:95]
	v_mfma_f32_16x16x32_bf16 v[88:91], v[152:155], v[192:195], v[88:91]
	v_mfma_f32_16x16x32_bf16 v[76:79], v[144:147], v[200:203], v[76:79]
	v_mfma_f32_16x16x32_bf16 v[72:75], v[152:155], v[200:203], v[72:75]
	s_setprio 0
	s_setprio 1
	v_mfma_f32_16x16x32_bf16 v[124:127], v[148:151], v[180:183], v[124:127]
	v_mfma_f32_16x16x32_bf16 v[120:123], v[156:159], v[180:183], v[120:123]
	v_mfma_f32_16x16x32_bf16 v[108:111], v[148:151], v[188:191], v[108:111]
	v_mfma_f32_16x16x32_bf16 v[104:107], v[156:159], v[188:191], v[104:107]
	v_mfma_f32_16x16x32_bf16 v[92:95], v[148:151], v[196:199], v[92:95]
	v_mfma_f32_16x16x32_bf16 v[88:91], v[156:159], v[196:199], v[88:91]
	v_mfma_f32_16x16x32_bf16 v[76:79], v[148:151], v[204:207], v[76:79]
	v_mfma_f32_16x16x32_bf16 v[72:75], v[156:159], v[204:207], v[72:75]
	s_setprio 0
	s_setprio 1
	v_mfma_f32_16x16x32_bf16 v[116:119], v[160:163], v[176:179], v[116:119]
	v_mfma_f32_16x16x32_bf16 v[112:115], v[168:171], v[176:179], v[112:115]
	v_mfma_f32_16x16x32_bf16 v[100:103], v[160:163], v[184:187], v[100:103]
	v_mfma_f32_16x16x32_bf16 v[96:99], v[168:171], v[184:187], v[96:99]
	v_mfma_f32_16x16x32_bf16 v[84:87], v[160:163], v[192:195], v[84:87]
	v_mfma_f32_16x16x32_bf16 v[80:83], v[168:171], v[192:195], v[80:83]
	v_mfma_f32_16x16x32_bf16 v[68:71], v[160:163], v[200:203], v[68:71]
	v_mfma_f32_16x16x32_bf16 v[64:67], v[168:171], v[200:203], v[64:67]
	s_setprio 0
	s_setprio 1
	v_mfma_f32_16x16x32_bf16 v[116:119], v[164:167], v[180:183], v[116:119]
	v_mfma_f32_16x16x32_bf16 v[112:115], v[172:175], v[180:183], v[112:115]
	v_mfma_f32_16x16x32_bf16 v[100:103], v[164:167], v[188:191], v[100:103]
	v_mfma_f32_16x16x32_bf16 v[96:99], v[172:175], v[188:191], v[96:99]
	v_mfma_f32_16x16x32_bf16 v[84:87], v[164:167], v[196:199], v[84:87]
	v_mfma_f32_16x16x32_bf16 v[80:83], v[172:175], v[196:199], v[80:83]
	v_mfma_f32_16x16x32_bf16 v[68:71], v[164:167], v[204:207], v[68:71]
	v_mfma_f32_16x16x32_bf16 v[64:67], v[172:175], v[204:207], v[64:67]
	s_setprio 0
	s_barrier
	s_add_i32 s54, s44, s38
	v_lshl_add_u64 v[208:209], s[14:15], 0, v[132:133]
	s_mov_b32 m0, s54
	ds_read_b128 v[176:179], v143 offset:16384
	ds_read_b128 v[180:183], v143 offset:17408
	ds_read_b128 v[184:187], v143 offset:18432
	ds_read_b128 v[188:191], v143 offset:19456
	ds_read_b128 v[192:195], v143 offset:20480
	ds_read_b128 v[196:199], v143 offset:21504
	ds_read_b128 v[200:203], v143 offset:22528
	ds_read_b128 v[204:207], v143 offset:23552
	global_load_lds_dwordx4 v[208:209], off
	s_add_i32 m0, s54, 0x2000
	s_add_u32 s54, s14, 0x40000
	v_lshl_add_u64 v[210:211], s[14:15], 0, v[128:129]
	s_addc_u32 s55, s15, 0
	s_add_i32 s56, s45, s38
	global_load_lds_dwordx4 v[210:211], off
	v_lshl_add_u64 v[212:213], s[54:55], 0, v[132:133]
	s_mov_b32 m0, s56
	v_lshl_add_u64 v[214:215], s[36:37], 0, v[130:131]
	global_load_lds_dwordx4 v[212:213], off
	v_lshl_add_u64 v[212:213], s[54:55], 0, v[128:129]
	s_add_i32 m0, s56, 0x2000
	s_nop 0
	global_load_lds_dwordx4 v[212:213], off
	v_lshl_add_u64 v[212:213], s[36:37], 0, v[134:135]
	s_mov_b32 m0, s25
	s_nop 0
	global_load_lds_dwordx4 v[212:213], off
	s_mov_b32 m0, s31
	s_nop 0
	global_load_lds_dwordx4 v[214:215], off
	s_waitcnt vmcnt(8)
	s_waitcnt lgkmcnt(0)
	s_barrier
	s_setprio 1
	s_waitcnt lgkmcnt(0)
	v_mfma_f32_16x16x32_bf16 v[60:63], v[144:147], v[176:179], v[60:63]
	v_mfma_f32_16x16x32_bf16 v[56:59], v[152:155], v[176:179], v[56:59]
	v_mfma_f32_16x16x32_bf16 v[44:47], v[144:147], v[184:187], v[44:47]
	v_mfma_f32_16x16x32_bf16 v[40:43], v[152:155], v[184:187], v[40:43]
	v_mfma_f32_16x16x32_bf16 v[28:31], v[144:147], v[192:195], v[28:31]
	v_mfma_f32_16x16x32_bf16 v[24:27], v[152:155], v[192:195], v[24:27]
	v_mfma_f32_16x16x32_bf16 v[12:15], v[144:147], v[200:203], v[12:15]
	v_mfma_f32_16x16x32_bf16 v[8:11], v[152:155], v[200:203], v[8:11]
	s_setprio 0
	s_setprio 1
	v_mfma_f32_16x16x32_bf16 v[60:63], v[148:151], v[180:183], v[60:63]
	v_mfma_f32_16x16x32_bf16 v[56:59], v[156:159], v[180:183], v[56:59]
	v_mfma_f32_16x16x32_bf16 v[44:47], v[148:151], v[188:191], v[44:47]
	v_mfma_f32_16x16x32_bf16 v[40:43], v[156:159], v[188:191], v[40:43]
	v_mfma_f32_16x16x32_bf16 v[28:31], v[148:151], v[196:199], v[28:31]
	v_mfma_f32_16x16x32_bf16 v[24:27], v[156:159], v[196:199], v[24:27]
	v_mfma_f32_16x16x32_bf16 v[12:15], v[148:151], v[204:207], v[12:15]
	v_mfma_f32_16x16x32_bf16 v[8:11], v[156:159], v[204:207], v[8:11]
	s_setprio 0
	s_setprio 1
	v_mfma_f32_16x16x32_bf16 v[52:55], v[160:163], v[176:179], v[52:55]
	v_mfma_f32_16x16x32_bf16 v[48:51], v[168:171], v[176:179], v[48:51]
	v_mfma_f32_16x16x32_bf16 v[36:39], v[160:163], v[184:187], v[36:39]
	v_mfma_f32_16x16x32_bf16 v[32:35], v[168:171], v[184:187], v[32:35]
	v_mfma_f32_16x16x32_bf16 v[20:23], v[160:163], v[192:195], v[20:23]
	v_mfma_f32_16x16x32_bf16 v[16:19], v[168:171], v[192:195], v[16:19]
	v_mfma_f32_16x16x32_bf16 v[4:7], v[160:163], v[200:203], v[4:7]
	v_mfma_f32_16x16x32_bf16 v[0:3], v[168:171], v[200:203], v[0:3]
	s_setprio 0
	s_setprio 1
	v_mfma_f32_16x16x32_bf16 v[52:55], v[164:167], v[180:183], v[52:55]
	v_mfma_f32_16x16x32_bf16 v[48:51], v[172:175], v[180:183], v[48:51]
	v_mfma_f32_16x16x32_bf16 v[36:39], v[164:167], v[188:191], v[36:39]
	v_mfma_f32_16x16x32_bf16 v[32:35], v[172:175], v[188:191], v[32:35]
	v_mfma_f32_16x16x32_bf16 v[20:23], v[164:167], v[196:199], v[20:23]
	v_mfma_f32_16x16x32_bf16 v[16:19], v[172:175], v[196:199], v[16:19]
	v_mfma_f32_16x16x32_bf16 v[4:7], v[164:167], v[204:207], v[4:7]
	v_mfma_f32_16x16x32_bf16 v[0:3], v[172:175], v[204:207], v[0:3]
	s_setprio 0
	s_barrier
; #define G_STAGE(bufoff, gbase, voff) do { _Pragma("unroll") for (int _i = 0; _i < 2; ++_i) \
;         __builtin_amdgcn_global_load_lds((const unsigned*)((const char*)(gbase) + voff[_i]), (LAS unsigned*)(lds + (bufoff) + ldsw + _i * 8192), 16, 0, 0); } while (0)
; #define G_LDA(dst, b, h) do { _Pragma("unroll") for (int m = 0; m < 4; ++m) _Pragma("unroll") for (int k = 0; k < 2; ++k) dst[m][k] = *(const LAS bf16x8*)(lds + G_SA(b, h) + aoff + m * 2048 + k * 1024); } while (0)
; #define G_LDB(dst, b, h) do { _Pragma("unroll") for (int n = 0; n < 2; ++n) _Pragma("unroll") for (int k = 0; k < 2; ++k) dst[n][k] = *(const LAS bf16x8*)(lds + G_SB(b, h) + boff + n * 2048 + k * 1024); } while (0)
; #define G_MMA(ai, bj, At_, Bt_) do { __builtin_amdgcn_s_setprio(1); _Pragma("unroll") for (int m = 0; m < 4; ++m) _Pragma("unroll") for (int n = 0; n < 2; ++n) _Pragma("unroll") for (int k = 0; k < 2; ++k) \
;         acc[ai][bj][m][n] = __builtin_amdgcn_mfma_f32_16x16x32_bf16(Bt_[n][k], At_[m][k], acc[ai][bj][m][n], 0, 0, 0); __builtin_amdgcn_s_setprio(0); } while (0)
; #define WAIT_V(n) asm volatile("s_waitcnt vmcnt(" #n ")" ::: "memory")
; #define WAIT_L(n) asm volatile("s_waitcnt lgkmcnt(" #n ")" ::: "memory")
; #define BAR __builtin_amdgcn_s_barrier()
; #define SCHED __builtin_amdgcn_sched_barrier(0)
; template <class Get, class Epi>
; DI void gemm_loop(int ntiles, int ld, char* shm, const Get& get, const Epi& epi) {
;     ...
;             G_LDB(B0, 1, 0); G_LDB(B1, 1, 1); SCHED; G_LDA(At, 1, 0); G_STAGE(G_SA(0, 1), a2 + hstep, voffA);
;             WAIT_V(8); WAIT_L(0); BAR; G_MMA(0, 0, At, B0); G_MMA(0, 1, At, B1); BAR; SCHED;
	s_add_i32 s54, 0, 0x18000
	s_add_i32 s55, 0, 0x1c000
	v_add_u32_e32 v156, s54, v140
	v_add_u32_e32 v172, s55, v140
	ds_read_b128 v[144:147], v156
	ds_read_b128 v[148:151], v156 offset:1024
	ds_read_b128 v[152:155], v156 offset:2048
	ds_read_b128 v[156:159], v156 offset:3072
	ds_read_b128 v[160:163], v172
	ds_read_b128 v[164:167], v172 offset:1024
	ds_read_b128 v[168:171], v172 offset:2048
	ds_read_b128 v[172:175], v172 offset:3072
	s_add_u32 s36, s36, 0x40000
	s_addc_u32 s37, s37, 0
	s_mov_b32 m0, s40
	v_lshl_add_u64 v[216:217], s[36:37], 0, v[134:135]
	ds_read_b128 v[176:179], v143 offset:32768
	ds_read_b128 v[180:183], v143 offset:33792
	ds_read_b128 v[184:187], v143 offset:34816
	ds_read_b128 v[188:191], v143 offset:35840
	ds_read_b128 v[192:195], v143 offset:36864
	ds_read_b128 v[196:199], v143 offset:37888
	ds_read_b128 v[200:203], v143 offset:38912
	ds_read_b128 v[204:207], v143 offset:39936
	global_load_lds_dwordx4 v[216:217], off
	v_lshl_add_u64 v[216:217], s[36:37], 0, v[130:131]
	s_mov_b32 m0, s41
	s_nop 0
	global_load_lds_dwordx4 v[216:217], off
	s_waitcnt vmcnt(8)
	s_waitcnt lgkmcnt(0)
	s_barrier
	s_setprio 1
	s_waitcnt lgkmcnt(0)
	v_mfma_f32_16x16x32_bf16 v[124:127], v[144:147], v[176:179], v[124:127]
	v_mfma_f32_16x16x32_bf16 v[120:123], v[152:155], v[176:179], v[120:123]
	v_mfma_f32_16x16x32_bf16 v[108:111], v[144:147], v[184:187], v[108:111]
	v_mfma_f32_16x16x32_bf16 v[104:107], v[152:155], v[184:187], v[104:107]
	v_mfma_f32_16x16x32_bf16 v[92:95], v[144:147], v[192:195], v[92:95]
	v_mfma_f32_16x16x32_bf16 v[88:91], v[152:155], v[192:195], v[88:91]
	v_mfma_f32_16x16x32_bf16 v[76:79], v[144:147], v[200:203], v[76:79]
	v_mfma_f32_16x16x32_bf16 v[72:75], v[152:155], v[200:203], v[72:75]
	s_setprio 0
	s_setprio 1
	v_mfma_f32_16x16x32_bf16 v[124:127], v[148:151], v[180:183], v[124:127]
	v_mfma_f32_16x16x32_bf16 v[120:123], v[156:159], v[180:183], v[120:123]
	v_mfma_f32_16x16x32_bf16 v[108:111], v[148:151], v[188:191], v[108:111]
	v_mfma_f32_16x16x32_bf16 v[104:107], v[156:159], v[188:191], v[104:107]
	v_mfma_f32_16x16x32_bf16 v[92:95], v[148:151], v[196:199], v[92:95]
	v_mfma_f32_16x16x32_bf16 v[88:91], v[156:159], v[196:199], v[88:91]
	v_mfma_f32_16x16x32_bf16 v[76:79], v[148:151], v[204:207], v[76:79]
	v_mfma_f32_16x16x32_bf16 v[72:75], v[156:159], v[204:207], v[72:75]
	s_setprio 0
	s_setprio 1
	v_mfma_f32_16x16x32_bf16 v[116:119], v[160:163], v[176:179], v[116:119]
	v_mfma_f32_16x16x32_bf16 v[112:115], v[168:171], v[176:179], v[112:115]
	v_mfma_f32_16x16x32_bf16 v[100:103], v[160:163], v[184:187], v[100:103]
	v_mfma_f32_16x16x32_bf16 v[96:99], v[168:171], v[184:187], v[96:99]
	v_mfma_f32_16x16x32_bf16 v[84:87], v[160:163], v[192:195], v[84:87]
	v_mfma_f32_16x16x32_bf16 v[80:83], v[168:171], v[192:195], v[80:83]
	v_mfma_f32_16x16x32_bf16 v[68:71], v[160:163], v[200:203], v[68:71]
	v_mfma_f32_16x16x32_bf16 v[64:67], v[168:171], v[200:203], v[64:67]
	s_setprio 0
	s_setprio 1
	v_mfma_f32_16x16x32_bf16 v[116:119], v[164:167], v[180:183], v[116:119]
	v_mfma_f32_16x16x32_bf16 v[112:115], v[172:175], v[180:183], v[112:115]
	v_mfma_f32_16x16x32_bf16 v[100:103], v[164:167], v[188:191], v[100:103]
	v_mfma_f32_16x16x32_bf16 v[96:99], v[172:175], v[188:191], v[96:99]
	v_mfma_f32_16x16x32_bf16 v[84:87], v[164:167], v[196:199], v[84:87]
	v_mfma_f32_16x16x32_bf16 v[80:83], v[172:175], v[196:199], v[80:83]
	v_mfma_f32_16x16x32_bf16 v[68:71], v[164:167], v[204:207], v[68:71]
	v_mfma_f32_16x16x32_bf16 v[64:67], v[172:175], v[204:207], v[64:67]
	s_setprio 0
	s_barrier
; #define G_STAGE(bufoff, gbase, voff) do { _Pragma("unroll") for (int _i = 0; _i < 2; ++_i) \
;         __builtin_amdgcn_global_load_lds((const unsigned*)((const char*)(gbase) + voff[_i]), (LAS unsigned*)(lds + (bufoff) + ldsw + _i * 8192), 16, 0, 0); } while (0)
; #define G_LDA(dst, b, h) do { _Pragma("unroll") for (int m = 0; m < 4; ++m) _Pragma("unroll") for (int k = 0; k < 2; ++k) dst[m][k] = *(const LAS bf16x8*)(lds + G_SA(b, h) + aoff + m * 2048 + k * 1024); } while (0)
; #define G_MMA(ai, bj, At_, Bt_) do { __builtin_amdgcn_s_setprio(1); _Pragma("unroll") for (int m = 0; m < 4; ++m) _Pragma("unroll") for (int n = 0; n < 2; ++n) _Pragma("unroll") for (int k = 0; k < 2; ++k) \
;         acc[ai][bj][m][n] = __builtin_amdgcn_mfma_f32_16x16x32_bf16(Bt_[n][k], At_[m][k], acc[ai][bj][m][n], 0, 0, 0); __builtin_amdgcn_s_setprio(0); } while (0)
; #define WAIT_V(n) asm volatile("s_waitcnt vmcnt(" #n ")" ::: "memory")
; #define WAIT_L(n) asm volatile("s_waitcnt lgkmcnt(" #n ")" ::: "memory")
; #define BAR __builtin_amdgcn_s_barrier()
; #define SCHED __builtin_amdgcn_sched_barrier(0)
; template <class Get, class Epi>
; DI void gemm_loop(int ntiles, int ld, char* shm, const Get& get, const Epi& epi) {
;     ...
;             G_LDA(At, 1, 1); G_STAGE(G_SB(1, 0), b3, voffB); G_STAGE(G_SB(1, 1), b3 + hstep, voffB); G_STAGE(G_SA(1, 0), a3, voffA);
;             WAIT_V(8); WAIT_L(0); BAR; G_MMA(1, 0, At, B0); G_MMA(1, 1, At, B1); BAR; SCHED;
	s_add_i32 s36, s54, s38
	v_lshl_add_u64 v[208:209], v[208:209], 0, s[2:3]
	s_mov_b32 m0, s36
	ds_read_b128 v[176:179], v143 offset:49152
	ds_read_b128 v[180:183], v143 offset:50176
	ds_read_b128 v[184:187], v143 offset:51200
	ds_read_b128 v[188:191], v143 offset:52224
	ds_read_b128 v[192:195], v143 offset:53248
	ds_read_b128 v[196:199], v143 offset:54272
	ds_read_b128 v[200:203], v143 offset:55296
	ds_read_b128 v[204:207], v143 offset:56320
	global_load_lds_dwordx4 v[208:209], off
	s_add_i32 m0, s36, 0x2000
	s_add_u32 s14, s14, 0x40080
	v_lshl_add_u64 v[208:209], v[210:211], 0, s[2:3]
	s_addc_u32 s15, s15, 0
	s_add_i32 s36, s55, s38
	global_load_lds_dwordx4 v[208:209], off
	v_lshl_add_u64 v[208:209], s[14:15], 0, v[132:133]
	s_mov_b32 m0, s36
	s_nop 0
	global_load_lds_dwordx4 v[208:209], off
	v_lshl_add_u64 v[208:209], s[14:15], 0, v[128:129]
	s_add_i32 m0, s36, 0x2000
	s_nop 0
	global_load_lds_dwordx4 v[208:209], off
	v_lshl_add_u64 v[208:209], v[212:213], 0, s[2:3]
	s_mov_b32 m0, s42
	s_nop 0
	global_load_lds_dwordx4 v[208:209], off
	v_lshl_add_u64 v[208:209], v[214:215], 0, s[2:3]
	s_mov_b32 m0, s43
	s_nop 0
	global_load_lds_dwordx4 v[208:209], off
	s_waitcnt vmcnt(8)
	s_waitcnt lgkmcnt(0)
	s_barrier
	s_setprio 1
	s_waitcnt lgkmcnt(0)
	v_mfma_f32_16x16x32_bf16 v[60:63], v[144:147], v[176:179], v[60:63]
	v_mfma_f32_16x16x32_bf16 v[56:59], v[152:155], v[176:179], v[56:59]
	v_mfma_f32_16x16x32_bf16 v[44:47], v[144:147], v[184:187], v[44:47]
	v_mfma_f32_16x16x32_bf16 v[40:43], v[152:155], v[184:187], v[40:43]
	v_mfma_f32_16x16x32_bf16 v[28:31], v[144:147], v[192:195], v[28:31]
	v_mfma_f32_16x16x32_bf16 v[24:27], v[152:155], v[192:195], v[24:27]
	v_mfma_f32_16x16x32_bf16 v[12:15], v[144:147], v[200:203], v[12:15]
	v_mfma_f32_16x16x32_bf16 v[8:11], v[152:155], v[200:203], v[8:11]
	s_setprio 0
	s_setprio 1
	v_mfma_f32_16x16x32_bf16 v[60:63], v[148:151], v[180:183], v[60:63]
	v_mfma_f32_16x16x32_bf16 v[56:59], v[156:159], v[180:183], v[56:59]
	v_mfma_f32_16x16x32_bf16 v[44:47], v[148:151], v[188:191], v[44:47]
	v_mfma_f32_16x16x32_bf16 v[40:43], v[156:159], v[188:191], v[40:43]
	v_mfma_f32_16x16x32_bf16 v[28:31], v[148:151], v[196:199], v[28:31]
	v_mfma_f32_16x16x32_bf16 v[24:27], v[156:159], v[196:199], v[24:27]
	v_mfma_f32_16x16x32_bf16 v[12:15], v[148:151], v[204:207], v[12:15]
	v_mfma_f32_16x16x32_bf16 v[8:11], v[156:159], v[204:207], v[8:11]
	s_setprio 0
	s_setprio 1
	v_mfma_f32_16x16x32_bf16 v[52:55], v[160:163], v[176:179], v[52:55]
	v_mfma_f32_16x16x32_bf16 v[48:51], v[168:171], v[176:179], v[48:51]
	v_mfma_f32_16x16x32_bf16 v[36:39], v[160:163], v[184:187], v[36:39]
	v_mfma_f32_16x16x32_bf16 v[32:35], v[168:171], v[184:187], v[32:35]
	v_mfma_f32_16x16x32_bf16 v[20:23], v[160:163], v[192:195], v[20:23]
	v_mfma_f32_16x16x32_bf16 v[16:19], v[168:171], v[192:195], v[16:19]
	v_mfma_f32_16x16x32_bf16 v[4:7], v[160:163], v[200:203], v[4:7]
	v_mfma_f32_16x16x32_bf16 v[0:3], v[168:171], v[200:203], v[0:3]
	s_setprio 0
	s_setprio 1
	v_mfma_f32_16x16x32_bf16 v[52:55], v[164:167], v[180:183], v[52:55]
	v_mfma_f32_16x16x32_bf16 v[48:51], v[172:175], v[180:183], v[48:51]
	v_mfma_f32_16x16x32_bf16 v[36:39], v[164:167], v[188:191], v[36:39]
	v_mfma_f32_16x16x32_bf16 v[32:35], v[172:175], v[188:191], v[32:35]
	v_mfma_f32_16x16x32_bf16 v[20:23], v[164:167], v[196:199], v[20:23]
	v_mfma_f32_16x16x32_bf16 v[16:19], v[172:175], v[196:199], v[16:19]
	v_mfma_f32_16x16x32_bf16 v[4:7], v[164:167], v[204:207], v[4:7]
	v_mfma_f32_16x16x32_bf16 v[0:3], v[172:175], v[204:207], v[0:3]
	s_setprio 0
	s_barrier
	s_add_i32 s53, s53, 2
	s_add_u32 s34, s34, 0x100
	s_addc_u32 s35, s35, 0
	s_add_u32 s51, s51, 0x100
	s_addc_u32 s52, s52, 0
	s_cmp_gt_u32 s53, 13
	s_cbranch_scc0 .LBB0_3679

; #define G_STAGE(bufoff, gbase, voff) do { _Pragma("unroll") for (int _i = 0; _i < 2; ++_i) \
;         __builtin_amdgcn_global_load_lds((const unsigned*)((const char*)(gbase) + voff[_i]), (LAS unsigned*)(lds + (bufoff) + ldsw + _i * 8192), 16, 0, 0); } while (0)
; #define G_LDA(dst, b, h) do { _Pragma("unroll") for (int m = 0; m < 4; ++m) _Pragma("unroll") for (int k = 0; k < 2; ++k) dst[m][k] = *(const LAS bf16x8*)(lds + G_SA(b, h) + aoff + m * 2048 + k * 1024); } while (0)
; #define G_MMA(ai, bj, At_, Bt_) do { __builtin_amdgcn_s_setprio(1); _Pragma("unroll") for (int m = 0; m < 4; ++m) _Pragma("unroll") for (int n = 0; n < 2; ++n) _Pragma("unroll") for (int k = 0; k < 2; ++k) \
;         acc[ai][bj][m][n] = __builtin_amdgcn_mfma_f32_16x16x32_bf16(Bt_[n][k], At_[m][k], acc[ai][bj][m][n], 0, 0, 0); __builtin_amdgcn_s_setprio(0); } while (0)
; #define WAIT_V(n) asm volatile("s_waitcnt vmcnt(" #n ")" ::: "memory")
; #define WAIT_L(n) asm volatile("s_waitcnt lgkmcnt(" #n ")" ::: "memory")
; #define BAR __builtin_amdgcn_s_barrier()
; #define SCHED __builtin_amdgcn_sched_barrier(0)
; template <class Get, class Epi>
; DI void gemm_loop(int ntiles, int ld, char* shm, const Get& get, const Epi& epi) {
;     ...
;             WAIT_V(8); WAIT_L(0); BAR; G_MMA(0, 0, At, B0); G_MMA(0, 1, At, B1); BAR; SCHED;
;             G_LDA(At, 0, 1); G_STAGE(G_SB(0, 0), b2, voffB); G_STAGE(G_SB(0, 1), b2 + hstep, voffB); G_STAGE(G_SA(0, 0), a2, voffA);
.Lrj_3759_0:
	s_waitcnt lgkmcnt(0)
	s_barrier
	s_setprio 1
	s_waitcnt lgkmcnt(0)
	v_mfma_f32_16x16x32_bf16 v[124:127], v[128:131], v[180:183], 0
	v_mfma_f32_16x16x32_bf16 v[120:123], v[136:139], v[180:183], 0
	v_mfma_f32_16x16x32_bf16 v[116:119], v[128:131], v[188:191], 0
	v_mfma_f32_16x16x32_bf16 v[112:115], v[136:139], v[188:191], 0
	v_mfma_f32_16x16x32_bf16 v[108:111], v[128:131], v[196:199], 0
	v_mfma_f32_16x16x32_bf16 v[104:107], v[136:139], v[196:199], 0
	v_mfma_f32_16x16x32_bf16 v[100:103], v[128:131], v[204:207], 0
	v_mfma_f32_16x16x32_bf16 v[96:99], v[136:139], v[204:207], 0
	s_setprio 0
	s_setprio 1
	v_mfma_f32_16x16x32_bf16 v[124:127], v[132:135], v[184:187], v[124:127]
	v_mfma_f32_16x16x32_bf16 v[120:123], v[140:143], v[184:187], v[120:123]
	v_mfma_f32_16x16x32_bf16 v[116:119], v[132:135], v[192:195], v[116:119]
	v_mfma_f32_16x16x32_bf16 v[112:115], v[140:143], v[192:195], v[112:115]
	v_mfma_f32_16x16x32_bf16 v[108:111], v[132:135], v[200:203], v[108:111]
	v_mfma_f32_16x16x32_bf16 v[104:107], v[140:143], v[200:203], v[104:107]
	v_mfma_f32_16x16x32_bf16 v[100:103], v[132:135], v[208:211], v[100:103]
	v_mfma_f32_16x16x32_bf16 v[96:99], v[140:143], v[208:211], v[96:99]
	s_setprio 0
	s_setprio 1
	v_mfma_f32_16x16x32_bf16 v[60:63], v[158:161], v[180:183], 0
	v_mfma_f32_16x16x32_bf16 v[56:59], v[172:175], v[180:183], 0
	v_mfma_f32_16x16x32_bf16 v[52:55], v[158:161], v[188:191], 0
	v_mfma_f32_16x16x32_bf16 v[48:51], v[172:175], v[188:191], 0
	v_mfma_f32_16x16x32_bf16 v[44:47], v[158:161], v[196:199], 0
	v_mfma_f32_16x16x32_bf16 v[40:43], v[172:175], v[196:199], 0
	v_mfma_f32_16x16x32_bf16 v[36:39], v[158:161], v[204:207], 0
	v_mfma_f32_16x16x32_bf16 v[32:35], v[172:175], v[204:207], 0
	s_setprio 0
	s_setprio 1
	v_mfma_f32_16x16x32_bf16 v[60:63], v[162:165], v[184:187], v[60:63]
	v_mfma_f32_16x16x32_bf16 v[56:59], v[176:179], v[184:187], v[56:59]
	v_mfma_f32_16x16x32_bf16 v[52:55], v[162:165], v[192:195], v[52:55]
	v_mfma_f32_16x16x32_bf16 v[48:51], v[176:179], v[192:195], v[48:51]
	v_mfma_f32_16x16x32_bf16 v[44:47], v[162:165], v[200:203], v[44:47]
	v_mfma_f32_16x16x32_bf16 v[40:43], v[176:179], v[200:203], v[40:43]
	v_mfma_f32_16x16x32_bf16 v[36:39], v[162:165], v[208:211], v[36:39]
	v_mfma_f32_16x16x32_bf16 v[32:35], v[176:179], v[208:211], v[32:35]
	s_setprio 0
	s_barrier
	s_add_i32 s2, s44, s33
	v_lshl_add_u64 v[144:145], s[30:31], 0, v[148:149]
	s_mov_b32 m0, s2
	ds_read_b128 v[180:183], v171 offset:16384
	ds_read_b128 v[184:187], v171 offset:17408
	ds_read_b128 v[188:191], v171 offset:18432
	ds_read_b128 v[192:195], v171 offset:19456
	ds_read_b128 v[196:199], v171 offset:20480
	ds_read_b128 v[200:203], v171 offset:21504
	ds_read_b128 v[204:207], v171 offset:22528
	ds_read_b128 v[208:211], v171 offset:23552
	global_load_lds_dwordx4 v[144:145], off
	s_add_i32 m0, s2, 0x2000
	s_add_u32 s2, s30, 0xb0000
	v_lshl_add_u64 v[166:167], s[30:31], 0, v[152:153]
	s_addc_u32 s3, s31, 0
	s_add_i32 s55, s45, s33
	global_load_lds_dwordx4 v[166:167], off
	v_lshl_add_u64 v[212:213], s[2:3], 0, v[148:149]
	s_mov_b32 m0, s55
	v_lshl_add_u64 v[214:215], s[34:35], 0, v[150:151]
	global_load_lds_dwordx4 v[212:213], off
	v_lshl_add_u64 v[212:213], s[2:3], 0, v[152:153]
	s_add_i32 m0, s55, 0x2000
	s_nop 0
	global_load_lds_dwordx4 v[212:213], off
	v_lshl_add_u64 v[212:213], s[34:35], 0, v[146:147]
	s_mov_b32 m0, s36
	s_nop 0
	global_load_lds_dwordx4 v[212:213], off
	s_mov_b32 m0, s37
	s_nop 0
	global_load_lds_dwordx4 v[214:215], off
	s_cmp_lg_u32 s100, 0
	s_cbranch_scc0 .Lrf_3759_1
	s_waitcnt vmcnt(16)
	s_branch .Lrj_3759_1

; #define G_STAGE(bufoff, gbase, voff) do { _Pragma("unroll") for (int _i = 0; _i < 2; ++_i) \
;         __builtin_amdgcn_global_load_lds((const unsigned*)((const char*)(gbase) + voff[_i]), (LAS unsigned*)(lds + (bufoff) + ldsw + _i * 8192), 16, 0, 0); } while (0)
; #define G_LDA(dst, b, h) do { _Pragma("unroll") for (int m = 0; m < 4; ++m) _Pragma("unroll") for (int k = 0; k < 2; ++k) dst[m][k] = *(const LAS bf16x8*)(lds + G_SA(b, h) + aoff + m * 2048 + k * 1024); } while (0)
; #define G_LDB(dst, b, h) do { _Pragma("unroll") for (int n = 0; n < 2; ++n) _Pragma("unroll") for (int k = 0; k < 2; ++k) dst[n][k] = *(const LAS bf16x8*)(lds + G_SB(b, h) + boff + n * 2048 + k * 1024); } while (0)
; #define G_MMA(ai, bj, At_, Bt_) do { __builtin_amdgcn_s_setprio(1); _Pragma("unroll") for (int m = 0; m < 4; ++m) _Pragma("unroll") for (int n = 0; n < 2; ++n) _Pragma("unroll") for (int k = 0; k < 2; ++k) \
;         acc[ai][bj][m][n] = __builtin_amdgcn_mfma_f32_16x16x32_bf16(Bt_[n][k], At_[m][k], acc[ai][bj][m][n], 0, 0, 0); __builtin_amdgcn_s_setprio(0); } while (0)
; #define WAIT_V(n) asm volatile("s_waitcnt vmcnt(" #n ")" ::: "memory")
; #define WAIT_L(n) asm volatile("s_waitcnt lgkmcnt(" #n ")" ::: "memory")
; #define BAR __builtin_amdgcn_s_barrier()
; #define SCHED __builtin_amdgcn_sched_barrier(0)
; template <class Get, class Epi>
; DI void gemm_loop(int ntiles, int ld, char* shm, const Get& get, const Epi& epi) {
;     ...
;             WAIT_V(8); WAIT_L(0); BAR; G_MMA(1, 0, At, B0); G_MMA(1, 1, At, B1); BAR; SCHED;
;             G_LDB(B0, 1, 0); G_LDB(B1, 1, 1); SCHED; G_LDA(At, 1, 0); G_STAGE(G_SA(0, 1), a2 + hstep, voffA);
;             WAIT_V(8); WAIT_L(0); BAR; G_MMA(0, 0, At, B0); G_MMA(0, 1, At, B1); BAR; SCHED;
.Lrj_3759_1:
	s_waitcnt lgkmcnt(0)
	s_barrier
	s_setprio 1
	s_waitcnt lgkmcnt(0)
	v_mfma_f32_16x16x32_bf16 v[92:95], v[128:131], v[180:183], 0
	v_mfma_f32_16x16x32_bf16 v[88:91], v[136:139], v[180:183], 0
	v_mfma_f32_16x16x32_bf16 v[84:87], v[128:131], v[188:191], 0
	v_mfma_f32_16x16x32_bf16 v[80:83], v[136:139], v[188:191], 0
	v_mfma_f32_16x16x32_bf16 v[76:79], v[128:131], v[196:199], 0
	v_mfma_f32_16x16x32_bf16 v[72:75], v[136:139], v[196:199], 0
	v_mfma_f32_16x16x32_bf16 v[68:71], v[128:131], v[204:207], 0
	v_mfma_f32_16x16x32_bf16 v[64:67], v[136:139], v[204:207], 0
	s_setprio 0
	s_setprio 1
	v_mfma_f32_16x16x32_bf16 v[92:95], v[132:135], v[184:187], v[92:95]
	v_mfma_f32_16x16x32_bf16 v[88:91], v[140:143], v[184:187], v[88:91]
	v_mfma_f32_16x16x32_bf16 v[84:87], v[132:135], v[192:195], v[84:87]
	v_mfma_f32_16x16x32_bf16 v[80:83], v[140:143], v[192:195], v[80:83]
	v_mfma_f32_16x16x32_bf16 v[76:79], v[132:135], v[200:203], v[76:79]
	v_mfma_f32_16x16x32_bf16 v[72:75], v[140:143], v[200:203], v[72:75]
	v_mfma_f32_16x16x32_bf16 v[68:71], v[132:135], v[208:211], v[68:71]
	v_mfma_f32_16x16x32_bf16 v[64:67], v[140:143], v[208:211], v[64:67]
	s_setprio 0
	s_setprio 1
	v_mfma_f32_16x16x32_bf16 v[28:31], v[158:161], v[180:183], 0
	v_mfma_f32_16x16x32_bf16 v[24:27], v[172:175], v[180:183], 0
	v_mfma_f32_16x16x32_bf16 v[20:23], v[158:161], v[188:191], 0
	v_mfma_f32_16x16x32_bf16 v[16:19], v[172:175], v[188:191], 0
	v_mfma_f32_16x16x32_bf16 v[12:15], v[158:161], v[196:199], 0
	v_mfma_f32_16x16x32_bf16 v[8:11], v[172:175], v[196:199], 0
	v_mfma_f32_16x16x32_bf16 v[4:7], v[158:161], v[204:207], 0
	v_mfma_f32_16x16x32_bf16 v[0:3], v[172:175], v[204:207], 0
	s_setprio 0
	s_setprio 1
	v_mfma_f32_16x16x32_bf16 v[28:31], v[162:165], v[184:187], v[28:31]
	v_mfma_f32_16x16x32_bf16 v[24:27], v[176:179], v[184:187], v[24:27]
	v_mfma_f32_16x16x32_bf16 v[20:23], v[162:165], v[192:195], v[20:23]
	v_mfma_f32_16x16x32_bf16 v[16:19], v[176:179], v[192:195], v[16:19]
	v_mfma_f32_16x16x32_bf16 v[12:15], v[162:165], v[200:203], v[12:15]
	v_mfma_f32_16x16x32_bf16 v[8:11], v[176:179], v[200:203], v[8:11]
	v_mfma_f32_16x16x32_bf16 v[4:7], v[162:165], v[208:211], v[4:7]
	v_mfma_f32_16x16x32_bf16 v[0:3], v[176:179], v[208:211], v[0:3]
	s_setprio 0
	s_barrier
	s_add_i32 s55, 0, 0x18000
	s_add_i32 s56, 0, 0x1c000
	v_add_u32_e32 v140, s55, v168
	v_add_u32_e32 v176, s56, v168
	ds_read_b128 v[128:131], v140
	ds_read_b128 v[132:135], v140 offset:1024
	ds_read_b128 v[136:139], v140 offset:2048
	ds_read_b128 v[140:143], v140 offset:3072
	ds_read_b128 v[158:161], v176
	ds_read_b128 v[162:165], v176 offset:1024
	ds_read_b128 v[172:175], v176 offset:2048
	ds_read_b128 v[176:179], v176 offset:3072
	s_add_u32 s2, s34, 0xb0000
	s_addc_u32 s3, s35, 0
	s_mov_b32 m0, s38
	v_lshl_add_u64 v[216:217], s[2:3], 0, v[146:147]
	ds_read_b128 v[180:183], v171 offset:32768
	ds_read_b128 v[184:187], v171 offset:33792
	ds_read_b128 v[188:191], v171 offset:34816
	ds_read_b128 v[192:195], v171 offset:35840
	ds_read_b128 v[196:199], v171 offset:36864
	ds_read_b128 v[200:203], v171 offset:37888
	ds_read_b128 v[204:207], v171 offset:38912
	ds_read_b128 v[208:211], v171 offset:39936
	global_load_lds_dwordx4 v[216:217], off
	v_lshl_add_u64 v[216:217], s[2:3], 0, v[150:151]
	s_mov_b32 m0, s39
	s_nop 0
	global_load_lds_dwordx4 v[216:217], off
	s_waitcnt vmcnt(8)
	s_waitcnt lgkmcnt(0)
	s_barrier
	s_setprio 1
	s_waitcnt lgkmcnt(0)
	v_mfma_f32_16x16x32_bf16 v[124:127], v[128:131], v[180:183], v[124:127]
	v_mfma_f32_16x16x32_bf16 v[120:123], v[136:139], v[180:183], v[120:123]
	v_mfma_f32_16x16x32_bf16 v[116:119], v[128:131], v[188:191], v[116:119]
	v_mfma_f32_16x16x32_bf16 v[112:115], v[136:139], v[188:191], v[112:115]
	v_mfma_f32_16x16x32_bf16 v[108:111], v[128:131], v[196:199], v[108:111]
	v_mfma_f32_16x16x32_bf16 v[104:107], v[136:139], v[196:199], v[104:107]
	v_mfma_f32_16x16x32_bf16 v[100:103], v[128:131], v[204:207], v[100:103]
	v_mfma_f32_16x16x32_bf16 v[96:99], v[136:139], v[204:207], v[96:99]
	s_setprio 0
	s_setprio 1
	v_mfma_f32_16x16x32_bf16 v[124:127], v[132:135], v[184:187], v[124:127]
	v_mfma_f32_16x16x32_bf16 v[120:123], v[140:143], v[184:187], v[120:123]
	v_mfma_f32_16x16x32_bf16 v[116:119], v[132:135], v[192:195], v[116:119]
	v_mfma_f32_16x16x32_bf16 v[112:115], v[140:143], v[192:195], v[112:115]
	v_mfma_f32_16x16x32_bf16 v[108:111], v[132:135], v[200:203], v[108:111]
	v_mfma_f32_16x16x32_bf16 v[104:107], v[140:143], v[200:203], v[104:107]
	v_mfma_f32_16x16x32_bf16 v[100:103], v[132:135], v[208:211], v[100:103]
	v_mfma_f32_16x16x32_bf16 v[96:99], v[140:143], v[208:211], v[96:99]
	s_setprio 0
	s_setprio 1
	v_mfma_f32_16x16x32_bf16 v[60:63], v[158:161], v[180:183], v[60:63]
	v_mfma_f32_16x16x32_bf16 v[56:59], v[172:175], v[180:183], v[56:59]
	v_mfma_f32_16x16x32_bf16 v[52:55], v[158:161], v[188:191], v[52:55]
	v_mfma_f32_16x16x32_bf16 v[48:51], v[172:175], v[188:191], v[48:51]
	v_mfma_f32_16x16x32_bf16 v[44:47], v[158:161], v[196:199], v[44:47]
	v_mfma_f32_16x16x32_bf16 v[40:43], v[172:175], v[196:199], v[40:43]
	v_mfma_f32_16x16x32_bf16 v[36:39], v[158:161], v[204:207], v[36:39]
	v_mfma_f32_16x16x32_bf16 v[32:35], v[172:175], v[204:207], v[32:35]
	s_setprio 0
	s_setprio 1
	v_mfma_f32_16x16x32_bf16 v[60:63], v[162:165], v[184:187], v[60:63]
	v_mfma_f32_16x16x32_bf16 v[56:59], v[176:179], v[184:187], v[56:59]
	v_mfma_f32_16x16x32_bf16 v[52:55], v[162:165], v[192:195], v[52:55]
	v_mfma_f32_16x16x32_bf16 v[48:51], v[176:179], v[192:195], v[48:51]
	v_mfma_f32_16x16x32_bf16 v[44:47], v[162:165], v[200:203], v[44:47]
	v_mfma_f32_16x16x32_bf16 v[40:43], v[176:179], v[200:203], v[40:43]
	v_mfma_f32_16x16x32_bf16 v[36:39], v[162:165], v[208:211], v[36:39]
	v_mfma_f32_16x16x32_bf16 v[32:35], v[176:179], v[208:211], v[32:35]
	s_setprio 0
	s_barrier
; #define G_STAGE(bufoff, gbase, voff) do { _Pragma("unroll") for (int _i = 0; _i < 2; ++_i) \
;         __builtin_amdgcn_global_load_lds((const unsigned*)((const char*)(gbase) + voff[_i]), (LAS unsigned*)(lds + (bufoff) + ldsw + _i * 8192), 16, 0, 0); } while (0)
; #define G_LDA(dst, b, h) do { _Pragma("unroll") for (int m = 0; m < 4; ++m) _Pragma("unroll") for (int k = 0; k < 2; ++k) dst[m][k] = *(const LAS bf16x8*)(lds + G_SA(b, h) + aoff + m * 2048 + k * 1024); } while (0)
; #define G_LDB(dst, b, h) do { _Pragma("unroll") for (int n = 0; n < 2; ++n) _Pragma("unroll") for (int k = 0; k < 2; ++k) dst[n][k] = *(const LAS bf16x8*)(lds + G_SB(b, h) + boff + n * 2048 + k * 1024); } while (0)
; #define G_MMA(ai, bj, At_, Bt_) do { __builtin_amdgcn_s_setprio(1); _Pragma("unroll") for (int m = 0; m < 4; ++m) _Pragma("unroll") for (int n = 0; n < 2; ++n) _Pragma("unroll") for (int k = 0; k < 2; ++k) \
;         acc[ai][bj][m][n] = __builtin_amdgcn_mfma_f32_16x16x32_bf16(Bt_[n][k], At_[m][k], acc[ai][bj][m][n], 0, 0, 0); __builtin_amdgcn_s_setprio(0); } while (0)
; #define WAIT_V(n) asm volatile("s_waitcnt vmcnt(" #n ")" ::: "memory")
; #define WAIT_L(n) asm volatile("s_waitcnt lgkmcnt(" #n ")" ::: "memory")
; #define BAR __builtin_amdgcn_s_barrier()
; #define SCHED __builtin_amdgcn_sched_barrier(0)
; template <class Get, class Epi>
; DI void gemm_loop(int ntiles, int ld, char* shm, const Get& get, const Epi& epi) {
;     ...
;             G_LDB(B0, 0, 0); G_LDB(B1, 0, 1); SCHED; G_LDA(At, 0, 0); G_STAGE(G_SA(1, 1), a1 + hstep, voffA);
;             WAIT_V(8); WAIT_L(0); BAR; G_MMA(0, 0, At, B0); G_MMA(0, 1, At, B1); BAR; SCHED;
;     ...
;             G_LDA(At, 1, 1); G_STAGE(G_SB(1, 0), b3, voffB); G_STAGE(G_SB(1, 1), b3 + hstep, voffB); G_STAGE(G_SA(1, 0), a3, voffA);
;             WAIT_V(8); WAIT_L(0); BAR; G_MMA(1, 0, At, B0); G_MMA(1, 1, At, B1); BAR; SCHED;
;         }
	s_add_i32 s2, s55, s33
	v_lshl_add_u64 v[144:145], v[144:145], 0, s[6:7]
	s_mov_b32 m0, s2
	ds_read_b128 v[180:183], v171 offset:49152
	ds_read_b128 v[184:187], v171 offset:50176
	ds_read_b128 v[188:191], v171 offset:51200
	ds_read_b128 v[192:195], v171 offset:52224
	ds_read_b128 v[196:199], v171 offset:53248
	ds_read_b128 v[200:203], v171 offset:54272
	ds_read_b128 v[204:207], v171 offset:55296
	ds_read_b128 v[208:211], v171 offset:56320
	global_load_lds_dwordx4 v[144:145], off
	s_add_i32 m0, s2, 0x2000
	s_add_u32 s2, s30, 0xb0080
	v_lshl_add_u64 v[144:145], v[166:167], 0, s[6:7]
	s_addc_u32 s3, s31, 0
	s_add_i32 s30, s56, s33
	global_load_lds_dwordx4 v[144:145], off
	v_lshl_add_u64 v[144:145], s[2:3], 0, v[148:149]
	s_mov_b32 m0, s30
	s_nop 0
	global_load_lds_dwordx4 v[144:145], off
	v_lshl_add_u64 v[144:145], s[2:3], 0, v[152:153]
	s_add_i32 m0, s30, 0x2000
	s_nop 0
	global_load_lds_dwordx4 v[144:145], off
	v_lshl_add_u64 v[144:145], v[212:213], 0, s[6:7]
	s_mov_b32 m0, s42
	s_nop 0
	global_load_lds_dwordx4 v[144:145], off
	v_lshl_add_u64 v[144:145], v[214:215], 0, s[6:7]
	s_mov_b32 m0, s43
	s_nop 0
	global_load_lds_dwordx4 v[144:145], off
	s_waitcnt vmcnt(8)
	s_waitcnt lgkmcnt(0)
	s_barrier
	s_setprio 1
	s_waitcnt lgkmcnt(0)
	v_mfma_f32_16x16x32_bf16 v[92:95], v[128:131], v[180:183], v[92:95]
	v_mfma_f32_16x16x32_bf16 v[88:91], v[136:139], v[180:183], v[88:91]
	v_mfma_f32_16x16x32_bf16 v[84:87], v[128:131], v[188:191], v[84:87]
	v_mfma_f32_16x16x32_bf16 v[80:83], v[136:139], v[188:191], v[80:83]
	v_mfma_f32_16x16x32_bf16 v[76:79], v[128:131], v[196:199], v[76:79]
	v_mfma_f32_16x16x32_bf16 v[72:75], v[136:139], v[196:199], v[72:75]
	v_mfma_f32_16x16x32_bf16 v[68:71], v[128:131], v[204:207], v[68:71]
	v_mfma_f32_16x16x32_bf16 v[64:67], v[136:139], v[204:207], v[64:67]
	s_setprio 0
	s_setprio 1
	v_mfma_f32_16x16x32_bf16 v[92:95], v[132:135], v[184:187], v[92:95]
	v_mfma_f32_16x16x32_bf16 v[88:91], v[140:143], v[184:187], v[88:91]
	v_mfma_f32_16x16x32_bf16 v[84:87], v[132:135], v[192:195], v[84:87]
	v_mfma_f32_16x16x32_bf16 v[80:83], v[140:143], v[192:195], v[80:83]
	v_mfma_f32_16x16x32_bf16 v[76:79], v[132:135], v[200:203], v[76:79]
	v_mfma_f32_16x16x32_bf16 v[72:75], v[140:143], v[200:203], v[72:75]
	v_mfma_f32_16x16x32_bf16 v[68:71], v[132:135], v[208:211], v[68:71]
	v_mfma_f32_16x16x32_bf16 v[64:67], v[140:143], v[208:211], v[64:67]
	s_setprio 0
	s_setprio 1
	v_mfma_f32_16x16x32_bf16 v[28:31], v[158:161], v[180:183], v[28:31]
	v_mfma_f32_16x16x32_bf16 v[24:27], v[172:175], v[180:183], v[24:27]
	v_mfma_f32_16x16x32_bf16 v[20:23], v[158:161], v[188:191], v[20:23]
	v_mfma_f32_16x16x32_bf16 v[16:19], v[172:175], v[188:191], v[16:19]
	v_mfma_f32_16x16x32_bf16 v[12:15], v[158:161], v[196:199], v[12:15]
	v_mfma_f32_16x16x32_bf16 v[8:11], v[172:175], v[196:199], v[8:11]
	v_mfma_f32_16x16x32_bf16 v[4:7], v[158:161], v[204:207], v[4:7]
	v_mfma_f32_16x16x32_bf16 v[0:3], v[172:175], v[204:207], v[0:3]
	s_setprio 0
	s_setprio 1
	v_mfma_f32_16x16x32_bf16 v[28:31], v[162:165], v[184:187], v[28:31]
	v_mfma_f32_16x16x32_bf16 v[24:27], v[176:179], v[184:187], v[24:27]
	v_mfma_f32_16x16x32_bf16 v[20:23], v[162:165], v[192:195], v[20:23]
	v_mfma_f32_16x16x32_bf16 v[16:19], v[176:179], v[192:195], v[16:19]
	v_mfma_f32_16x16x32_bf16 v[12:15], v[162:165], v[200:203], v[12:15]
	v_mfma_f32_16x16x32_bf16 v[8:11], v[176:179], v[200:203], v[8:11]
	v_mfma_f32_16x16x32_bf16 v[4:7], v[162:165], v[208:211], v[4:7]
	v_mfma_f32_16x16x32_bf16 v[0:3], v[176:179], v[208:211], v[0:3]
	s_setprio 0
	s_barrier
	s_add_i32 s54, s54, 2
	s_add_u32 s52, s52, 0x100
	s_addc_u32 s53, s53, 0
	s_cmp_gt_u32 s54, 41
	s_mov_b64 s[2:3], s[24:25]
	s_cbranch_scc0 .LBB0_3759
	s_branch .Lpost_3759
.LBB0_3759:
	ds_read_b128 v[128:131], v169
	ds_read_b128 v[132:135], v169 offset:1024
	ds_read_b128 v[136:139], v169 offset:2048
	ds_read_b128 v[140:143], v169 offset:3072
	ds_read_b128 v[158:161], v170
	ds_read_b128 v[162:165], v170 offset:1024
	ds_read_b128 v[172:175], v170 offset:2048
	ds_read_b128 v[176:179], v170 offset:3072
	s_add_u32 s24, s2, 0x100
	s_addc_u32 s25, s3, 0
	s_cmp_eq_u32 s54, 40
	s_cselect_b32 s35, s21, s25
	s_cselect_b32 s34, s20, s24
	s_cselect_b32 s31, s23, s53
	s_cselect_b32 s30, s22, s52
	v_lshl_add_u64 v[144:145], s[2:3], 0, v[154:155]
	s_add_i32 m0, s36, 0xc000
	ds_read_b128 v[180:183], v171
	ds_read_b128 v[184:187], v171 offset:1024
	ds_read_b128 v[188:191], v171 offset:2048
	ds_read_b128 v[192:195], v171 offset:3072
	ds_read_b128 v[196:199], v171 offset:4096
	ds_read_b128 v[200:203], v171 offset:5120
	ds_read_b128 v[204:207], v171 offset:6144
	ds_read_b128 v[208:211], v171 offset:7168
	global_load_lds_dwordx4 v[144:145], off
	v_lshl_add_u64 v[144:145], s[2:3], 0, v[156:157]
	s_add_i32 m0, s36, 0xe000
	s_nop 0
	global_load_lds_dwordx4 v[144:145], off
	s_waitcnt vmcnt(8)
	s_waitcnt lgkmcnt(0)
	s_barrier
; #define G_STAGE(bufoff, gbase, voff) do { _Pragma("unroll") for (int _i = 0; _i < 2; ++_i) \
;         __builtin_amdgcn_global_load_lds((const unsigned*)((const char*)(gbase) + voff[_i]), (LAS unsigned*)(lds + (bufoff) + ldsw + _i * 8192), 16, 0, 0); } while (0)
; #define G_LDA(dst, b, h) do { _Pragma("unroll") for (int m = 0; m < 4; ++m) _Pragma("unroll") for (int k = 0; k < 2; ++k) dst[m][k] = *(const LAS bf16x8*)(lds + G_SA(b, h) + aoff + m * 2048 + k * 1024); } while (0)
; #define G_MMA(ai, bj, At_, Bt_) do { __builtin_amdgcn_s_setprio(1); _Pragma("unroll") for (int m = 0; m < 4; ++m) _Pragma("unroll") for (int n = 0; n < 2; ++n) _Pragma("unroll") for (int k = 0; k < 2; ++k) \
;         acc[ai][bj][m][n] = __builtin_amdgcn_mfma_f32_16x16x32_bf16(Bt_[n][k], At_[m][k], acc[ai][bj][m][n], 0, 0, 0); __builtin_amdgcn_s_setprio(0); } while (0)
; #define WAIT_V(n) asm volatile("s_waitcnt vmcnt(" #n ")" ::: "memory")
; #define WAIT_L(n) asm volatile("s_waitcnt lgkmcnt(" #n ")" ::: "memory")
; #define BAR __builtin_amdgcn_s_barrier()
; #define SCHED __builtin_amdgcn_sched_barrier(0)
; template <class Get, class Epi>
; DI void gemm_loop(int ntiles, int ld, char* shm, const Get& get, const Epi& epi) {
;     ...
;             WAIT_V(8); WAIT_L(0); BAR; G_MMA(0, 0, At, B0); G_MMA(0, 1, At, B1); BAR; SCHED;
;             G_LDA(At, 0, 1); G_STAGE(G_SB(0, 0), b2, voffB); G_STAGE(G_SB(0, 1), b2 + hstep, voffB); G_STAGE(G_SA(0, 0), a2, voffA);
;             WAIT_V(8); WAIT_L(0); BAR; G_MMA(1, 0, At, B0); G_MMA(1, 1, At, B1); BAR; SCHED;
	s_setprio 1
	s_waitcnt lgkmcnt(0)
	v_mfma_f32_16x16x32_bf16 v[124:127], v[128:131], v[180:183], v[124:127]
	v_mfma_f32_16x16x32_bf16 v[120:123], v[136:139], v[180:183], v[120:123]
	v_mfma_f32_16x16x32_bf16 v[116:119], v[128:131], v[188:191], v[116:119]
	v_mfma_f32_16x16x32_bf16 v[112:115], v[136:139], v[188:191], v[112:115]
	v_mfma_f32_16x16x32_bf16 v[108:111], v[128:131], v[196:199], v[108:111]
	v_mfma_f32_16x16x32_bf16 v[104:107], v[136:139], v[196:199], v[104:107]
	v_mfma_f32_16x16x32_bf16 v[100:103], v[128:131], v[204:207], v[100:103]
	v_mfma_f32_16x16x32_bf16 v[96:99], v[136:139], v[204:207], v[96:99]
	s_setprio 0
	s_setprio 1
	v_mfma_f32_16x16x32_bf16 v[124:127], v[132:135], v[184:187], v[124:127]
	v_mfma_f32_16x16x32_bf16 v[120:123], v[140:143], v[184:187], v[120:123]
	v_mfma_f32_16x16x32_bf16 v[116:119], v[132:135], v[192:195], v[116:119]
	v_mfma_f32_16x16x32_bf16 v[112:115], v[140:143], v[192:195], v[112:115]
	v_mfma_f32_16x16x32_bf16 v[108:111], v[132:135], v[200:203], v[108:111]
	v_mfma_f32_16x16x32_bf16 v[104:107], v[140:143], v[200:203], v[104:107]
	v_mfma_f32_16x16x32_bf16 v[100:103], v[132:135], v[208:211], v[100:103]
	v_mfma_f32_16x16x32_bf16 v[96:99], v[140:143], v[208:211], v[96:99]
	s_setprio 0
	s_setprio 1
	v_mfma_f32_16x16x32_bf16 v[60:63], v[158:161], v[180:183], v[60:63]
	v_mfma_f32_16x16x32_bf16 v[56:59], v[172:175], v[180:183], v[56:59]
	v_mfma_f32_16x16x32_bf16 v[52:55], v[158:161], v[188:191], v[52:55]
	v_mfma_f32_16x16x32_bf16 v[48:51], v[172:175], v[188:191], v[48:51]
	v_mfma_f32_16x16x32_bf16 v[44:47], v[158:161], v[196:199], v[44:47]
	v_mfma_f32_16x16x32_bf16 v[40:43], v[172:175], v[196:199], v[40:43]
	v_mfma_f32_16x16x32_bf16 v[36:39], v[158:161], v[204:207], v[36:39]
	v_mfma_f32_16x16x32_bf16 v[32:35], v[172:175], v[204:207], v[32:35]
	s_setprio 0
	s_setprio 1
	v_mfma_f32_16x16x32_bf16 v[60:63], v[162:165], v[184:187], v[60:63]
	v_mfma_f32_16x16x32_bf16 v[56:59], v[176:179], v[184:187], v[56:59]
	v_mfma_f32_16x16x32_bf16 v[52:55], v[162:165], v[192:195], v[52:55]
	v_mfma_f32_16x16x32_bf16 v[48:51], v[176:179], v[192:195], v[48:51]
	v_mfma_f32_16x16x32_bf16 v[44:47], v[162:165], v[200:203], v[44:47]
	v_mfma_f32_16x16x32_bf16 v[40:43], v[176:179], v[200:203], v[40:43]
	v_mfma_f32_16x16x32_bf16 v[36:39], v[162:165], v[208:211], v[36:39]
	v_mfma_f32_16x16x32_bf16 v[32:35], v[176:179], v[208:211], v[32:35]
	s_setprio 0
	s_barrier
	s_add_i32 s2, s44, s33
	v_lshl_add_u64 v[144:145], s[30:31], 0, v[148:149]
	s_mov_b32 m0, s2
	ds_read_b128 v[180:183], v171 offset:16384
	ds_read_b128 v[184:187], v171 offset:17408
	ds_read_b128 v[188:191], v171 offset:18432
	ds_read_b128 v[192:195], v171 offset:19456
	ds_read_b128 v[196:199], v171 offset:20480
	ds_read_b128 v[200:203], v171 offset:21504
	ds_read_b128 v[204:207], v171 offset:22528
	ds_read_b128 v[208:211], v171 offset:23552
	global_load_lds_dwordx4 v[144:145], off
	s_add_i32 m0, s2, 0x2000
	s_add_u32 s2, s30, 0xb0000
	v_lshl_add_u64 v[166:167], s[30:31], 0, v[152:153]
	s_addc_u32 s3, s31, 0
	s_add_i32 s55, s45, s33
	global_load_lds_dwordx4 v[166:167], off
	v_lshl_add_u64 v[212:213], s[2:3], 0, v[148:149]
	s_mov_b32 m0, s55
	v_lshl_add_u64 v[214:215], s[34:35], 0, v[150:151]
	global_load_lds_dwordx4 v[212:213], off
	v_lshl_add_u64 v[212:213], s[2:3], 0, v[152:153]
	s_add_i32 m0, s55, 0x2000
	s_nop 0
	global_load_lds_dwordx4 v[212:213], off
	v_lshl_add_u64 v[212:213], s[34:35], 0, v[146:147]
	s_mov_b32 m0, s36
	s_nop 0
	global_load_lds_dwordx4 v[212:213], off
	s_mov_b32 m0, s37
	s_nop 0
	global_load_lds_dwordx4 v[214:215], off
	s_waitcnt vmcnt(8)
	s_waitcnt lgkmcnt(0)
	s_barrier
	s_setprio 1
	s_waitcnt lgkmcnt(0)
	v_mfma_f32_16x16x32_bf16 v[92:95], v[128:131], v[180:183], v[92:95]
	v_mfma_f32_16x16x32_bf16 v[88:91], v[136:139], v[180:183], v[88:91]
	v_mfma_f32_16x16x32_bf16 v[84:87], v[128:131], v[188:191], v[84:87]
	v_mfma_f32_16x16x32_bf16 v[80:83], v[136:139], v[188:191], v[80:83]
	v_mfma_f32_16x16x32_bf16 v[76:79], v[128:131], v[196:199], v[76:79]
	v_mfma_f32_16x16x32_bf16 v[72:75], v[136:139], v[196:199], v[72:75]
	v_mfma_f32_16x16x32_bf16 v[68:71], v[128:131], v[204:207], v[68:71]
	v_mfma_f32_16x16x32_bf16 v[64:67], v[136:139], v[204:207], v[64:67]
	s_setprio 0
	s_setprio 1
	v_mfma_f32_16x16x32_bf16 v[92:95], v[132:135], v[184:187], v[92:95]
	v_mfma_f32_16x16x32_bf16 v[88:91], v[140:143], v[184:187], v[88:91]
	v_mfma_f32_16x16x32_bf16 v[84:87], v[132:135], v[192:195], v[84:87]
	v_mfma_f32_16x16x32_bf16 v[80:83], v[140:143], v[192:195], v[80:83]
	v_mfma_f32_16x16x32_bf16 v[76:79], v[132:135], v[200:203], v[76:79]
	v_mfma_f32_16x16x32_bf16 v[72:75], v[140:143], v[200:203], v[72:75]
	v_mfma_f32_16x16x32_bf16 v[68:71], v[132:135], v[208:211], v[68:71]
	v_mfma_f32_16x16x32_bf16 v[64:67], v[140:143], v[208:211], v[64:67]
	s_setprio 0
	s_setprio 1
	v_mfma_f32_16x16x32_bf16 v[28:31], v[158:161], v[180:183], v[28:31]
	v_mfma_f32_16x16x32_bf16 v[24:27], v[172:175], v[180:183], v[24:27]
	v_mfma_f32_16x16x32_bf16 v[20:23], v[158:161], v[188:191], v[20:23]
	v_mfma_f32_16x16x32_bf16 v[16:19], v[172:175], v[188:191], v[16:19]
	v_mfma_f32_16x16x32_bf16 v[12:15], v[158:161], v[196:199], v[12:15]
	v_mfma_f32_16x16x32_bf16 v[8:11], v[172:175], v[196:199], v[8:11]
	v_mfma_f32_16x16x32_bf16 v[4:7], v[158:161], v[204:207], v[4:7]
	v_mfma_f32_16x16x32_bf16 v[0:3], v[172:175], v[204:207], v[0:3]
	s_setprio 0
	s_setprio 1
	v_mfma_f32_16x16x32_bf16 v[28:31], v[162:165], v[184:187], v[28:31]
	v_mfma_f32_16x16x32_bf16 v[24:27], v[176:179], v[184:187], v[24:27]
	v_mfma_f32_16x16x32_bf16 v[20:23], v[162:165], v[192:195], v[20:23]
	v_mfma_f32_16x16x32_bf16 v[16:19], v[176:179], v[192:195], v[16:19]
	v_mfma_f32_16x16x32_bf16 v[12:15], v[162:165], v[200:203], v[12:15]
	v_mfma_f32_16x16x32_bf16 v[8:11], v[176:179], v[200:203], v[8:11]
	v_mfma_f32_16x16x32_bf16 v[4:7], v[162:165], v[208:211], v[4:7]
	v_mfma_f32_16x16x32_bf16 v[0:3], v[176:179], v[208:211], v[0:3]
	s_setprio 0
	s_barrier
; #define G_STAGE(bufoff, gbase, voff) do { _Pragma("unroll") for (int _i = 0; _i < 2; ++_i) \
;         __builtin_amdgcn_global_load_lds((const unsigned*)((const char*)(gbase) + voff[_i]), (LAS unsigned*)(lds + (bufoff) + ldsw + _i * 8192), 16, 0, 0); } while (0)
; #define G_LDA(dst, b, h) do { _Pragma("unroll") for (int m = 0; m < 4; ++m) _Pragma("unroll") for (int k = 0; k < 2; ++k) dst[m][k] = *(const LAS bf16x8*)(lds + G_SA(b, h) + aoff + m * 2048 + k * 1024); } while (0)
; #define G_LDB(dst, b, h) do { _Pragma("unroll") for (int n = 0; n < 2; ++n) _Pragma("unroll") for (int k = 0; k < 2; ++k) dst[n][k] = *(const LAS bf16x8*)(lds + G_SB(b, h) + boff + n * 2048 + k * 1024); } while (0)
; #define G_MMA(ai, bj, At_, Bt_) do { __builtin_amdgcn_s_setprio(1); _Pragma("unroll") for (int m = 0; m < 4; ++m) _Pragma("unroll") for (int n = 0; n < 2; ++n) _Pragma("unroll") for (int k = 0; k < 2; ++k) \
;         acc[ai][bj][m][n] = __builtin_amdgcn_mfma_f32_16x16x32_bf16(Bt_[n][k], At_[m][k], acc[ai][bj][m][n], 0, 0, 0); __builtin_amdgcn_s_setprio(0); } while (0)
; #define WAIT_V(n) asm volatile("s_waitcnt vmcnt(" #n ")" ::: "memory")
; #define WAIT_L(n) asm volatile("s_waitcnt lgkmcnt(" #n ")" ::: "memory")
; #define BAR __builtin_amdgcn_s_barrier()
; #define SCHED __builtin_amdgcn_sched_barrier(0)
; template <class Get, class Epi>
; DI void gemm_loop(int ntiles, int ld, char* shm, const Get& get, const Epi& epi) {
;     ...
;             G_LDB(B0, 1, 0); G_LDB(B1, 1, 1); SCHED; G_LDA(At, 1, 0); G_STAGE(G_SA(0, 1), a2 + hstep, voffA);
;             WAIT_V(8); WAIT_L(0); BAR; G_MMA(0, 0, At, B0); G_MMA(0, 1, At, B1); BAR; SCHED;
	s_add_i32 s55, 0, 0x18000
	s_add_i32 s56, 0, 0x1c000
	v_add_u32_e32 v140, s55, v168
	v_add_u32_e32 v176, s56, v168
	ds_read_b128 v[128:131], v140
	ds_read_b128 v[132:135], v140 offset:1024
	ds_read_b128 v[136:139], v140 offset:2048
	ds_read_b128 v[140:143], v140 offset:3072
	ds_read_b128 v[158:161], v176
	ds_read_b128 v[162:165], v176 offset:1024
	ds_read_b128 v[172:175], v176 offset:2048
	ds_read_b128 v[176:179], v176 offset:3072
	s_add_u32 s2, s34, 0xb0000
	s_addc_u32 s3, s35, 0
	s_mov_b32 m0, s38
	v_lshl_add_u64 v[216:217], s[2:3], 0, v[146:147]
	ds_read_b128 v[180:183], v171 offset:32768
	ds_read_b128 v[184:187], v171 offset:33792
	ds_read_b128 v[188:191], v171 offset:34816
	ds_read_b128 v[192:195], v171 offset:35840
	ds_read_b128 v[196:199], v171 offset:36864
	ds_read_b128 v[200:203], v171 offset:37888
	ds_read_b128 v[204:207], v171 offset:38912
	ds_read_b128 v[208:211], v171 offset:39936
	global_load_lds_dwordx4 v[216:217], off
	v_lshl_add_u64 v[216:217], s[2:3], 0, v[150:151]
	s_mov_b32 m0, s39
	s_nop 0
	global_load_lds_dwordx4 v[216:217], off
	s_waitcnt vmcnt(8)
	s_waitcnt lgkmcnt(0)
	s_barrier
	s_setprio 1
	s_waitcnt lgkmcnt(0)
	v_mfma_f32_16x16x32_bf16 v[124:127], v[128:131], v[180:183], v[124:127]
	v_mfma_f32_16x16x32_bf16 v[120:123], v[136:139], v[180:183], v[120:123]
	v_mfma_f32_16x16x32_bf16 v[116:119], v[128:131], v[188:191], v[116:119]
	v_mfma_f32_16x16x32_bf16 v[112:115], v[136:139], v[188:191], v[112:115]
	v_mfma_f32_16x16x32_bf16 v[108:111], v[128:131], v[196:199], v[108:111]
	v_mfma_f32_16x16x32_bf16 v[104:107], v[136:139], v[196:199], v[104:107]
	v_mfma_f32_16x16x32_bf16 v[100:103], v[128:131], v[204:207], v[100:103]
	v_mfma_f32_16x16x32_bf16 v[96:99], v[136:139], v[204:207], v[96:99]
	s_setprio 0
	s_setprio 1
	v_mfma_f32_16x16x32_bf16 v[124:127], v[132:135], v[184:187], v[124:127]
	v_mfma_f32_16x16x32_bf16 v[120:123], v[140:143], v[184:187], v[120:123]
	v_mfma_f32_16x16x32_bf16 v[116:119], v[132:135], v[192:195], v[116:119]
	v_mfma_f32_16x16x32_bf16 v[112:115], v[140:143], v[192:195], v[112:115]
	v_mfma_f32_16x16x32_bf16 v[108:111], v[132:135], v[200:203], v[108:111]
	v_mfma_f32_16x16x32_bf16 v[104:107], v[140:143], v[200:203], v[104:107]
	v_mfma_f32_16x16x32_bf16 v[100:103], v[132:135], v[208:211], v[100:103]
	v_mfma_f32_16x16x32_bf16 v[96:99], v[140:143], v[208:211], v[96:99]
	s_setprio 0
	s_setprio 1
	v_mfma_f32_16x16x32_bf16 v[60:63], v[158:161], v[180:183], v[60:63]
	v_mfma_f32_16x16x32_bf16 v[56:59], v[172:175], v[180:183], v[56:59]
	v_mfma_f32_16x16x32_bf16 v[52:55], v[158:161], v[188:191], v[52:55]
	v_mfma_f32_16x16x32_bf16 v[48:51], v[172:175], v[188:191], v[48:51]
	v_mfma_f32_16x16x32_bf16 v[44:47], v[158:161], v[196:199], v[44:47]
	v_mfma_f32_16x16x32_bf16 v[40:43], v[172:175], v[196:199], v[40:43]
	v_mfma_f32_16x16x32_bf16 v[36:39], v[158:161], v[204:207], v[36:39]
	v_mfma_f32_16x16x32_bf16 v[32:35], v[172:175], v[204:207], v[32:35]
	s_setprio 0
	s_setprio 1
	v_mfma_f32_16x16x32_bf16 v[60:63], v[162:165], v[184:187], v[60:63]
	v_mfma_f32_16x16x32_bf16 v[56:59], v[176:179], v[184:187], v[56:59]
	v_mfma_f32_16x16x32_bf16 v[52:55], v[162:165], v[192:195], v[52:55]
	v_mfma_f32_16x16x32_bf16 v[48:51], v[176:179], v[192:195], v[48:51]
	v_mfma_f32_16x16x32_bf16 v[44:47], v[162:165], v[200:203], v[44:47]
	v_mfma_f32_16x16x32_bf16 v[40:43], v[176:179], v[200:203], v[40:43]
	v_mfma_f32_16x16x32_bf16 v[36:39], v[162:165], v[208:211], v[36:39]
	v_mfma_f32_16x16x32_bf16 v[32:35], v[176:179], v[208:211], v[32:35]
	s_setprio 0
	s_barrier
; #define G_STAGE(bufoff, gbase, voff) do { _Pragma("unroll") for (int _i = 0; _i < 2; ++_i) \
;         __builtin_amdgcn_global_load_lds((const unsigned*)((const char*)(gbase) + voff[_i]), (LAS unsigned*)(lds + (bufoff) + ldsw + _i * 8192), 16, 0, 0); } while (0)
; #define G_LDA(dst, b, h) do { _Pragma("unroll") for (int m = 0; m < 4; ++m) _Pragma("unroll") for (int k = 0; k < 2; ++k) dst[m][k] = *(const LAS bf16x8*)(lds + G_SA(b, h) + aoff + m * 2048 + k * 1024); } while (0)
; #define G_MMA(ai, bj, At_, Bt_) do { __builtin_amdgcn_s_setprio(1); _Pragma("unroll") for (int m = 0; m < 4; ++m) _Pragma("unroll") for (int n = 0; n < 2; ++n) _Pragma("unroll") for (int k = 0; k < 2; ++k) \
;         acc[ai][bj][m][n] = __builtin_amdgcn_mfma_f32_16x16x32_bf16(Bt_[n][k], At_[m][k], acc[ai][bj][m][n], 0, 0, 0); __builtin_amdgcn_s_setprio(0); } while (0)
; #define WAIT_V(n) asm volatile("s_waitcnt vmcnt(" #n ")" ::: "memory")
; #define WAIT_L(n) asm volatile("s_waitcnt lgkmcnt(" #n ")" ::: "memory")
; #define BAR __builtin_amdgcn_s_barrier()
; #define SCHED __builtin_amdgcn_sched_barrier(0)
; template <class Get, class Epi>
; DI void gemm_loop(int ntiles, int ld, char* shm, const Get& get, const Epi& epi) {
;     ...
;             G_LDA(At, 1, 1); G_STAGE(G_SB(1, 0), b3, voffB); G_STAGE(G_SB(1, 1), b3 + hstep, voffB); G_STAGE(G_SA(1, 0), a3, voffA);
;             WAIT_V(8); WAIT_L(0); BAR; G_MMA(1, 0, At, B0); G_MMA(1, 1, At, B1); BAR; SCHED;
	s_add_i32 s2, s55, s33
	v_lshl_add_u64 v[144:145], v[144:145], 0, s[6:7]
	s_mov_b32 m0, s2
	ds_read_b128 v[180:183], v171 offset:49152
	ds_read_b128 v[184:187], v171 offset:50176
	ds_read_b128 v[188:191], v171 offset:51200
	ds_read_b128 v[192:195], v171 offset:52224
	ds_read_b128 v[196:199], v171 offset:53248
	ds_read_b128 v[200:203], v171 offset:54272
	ds_read_b128 v[204:207], v171 offset:55296
	ds_read_b128 v[208:211], v171 offset:56320
	global_load_lds_dwordx4 v[144:145], off
	s_add_i32 m0, s2, 0x2000
	s_add_u32 s2, s30, 0xb0080
	v_lshl_add_u64 v[144:145], v[166:167], 0, s[6:7]
	s_addc_u32 s3, s31, 0
	s_add_i32 s30, s56, s33
	global_load_lds_dwordx4 v[144:145], off
	v_lshl_add_u64 v[144:145], s[2:3], 0, v[148:149]
	s_mov_b32 m0, s30
	s_nop 0
	global_load_lds_dwordx4 v[144:145], off
	v_lshl_add_u64 v[144:145], s[2:3], 0, v[152:153]
	s_add_i32 m0, s30, 0x2000
	s_nop 0
	global_load_lds_dwordx4 v[144:145], off
	v_lshl_add_u64 v[144:145], v[212:213], 0, s[6:7]
	s_mov_b32 m0, s42
	s_nop 0
	global_load_lds_dwordx4 v[144:145], off
	v_lshl_add_u64 v[144:145], v[214:215], 0, s[6:7]
	s_mov_b32 m0, s43
	s_nop 0
	global_load_lds_dwordx4 v[144:145], off
	s_waitcnt vmcnt(8)
	s_waitcnt lgkmcnt(0)
	s_barrier
	s_setprio 1
	s_waitcnt lgkmcnt(0)
	v_mfma_f32_16x16x32_bf16 v[92:95], v[128:131], v[180:183], v[92:95]
	v_mfma_f32_16x16x32_bf16 v[88:91], v[136:139], v[180:183], v[88:91]
	v_mfma_f32_16x16x32_bf16 v[84:87], v[128:131], v[188:191], v[84:87]
	v_mfma_f32_16x16x32_bf16 v[80:83], v[136:139], v[188:191], v[80:83]
	v_mfma_f32_16x16x32_bf16 v[76:79], v[128:131], v[196:199], v[76:79]
	v_mfma_f32_16x16x32_bf16 v[72:75], v[136:139], v[196:199], v[72:75]
	v_mfma_f32_16x16x32_bf16 v[68:71], v[128:131], v[204:207], v[68:71]
	v_mfma_f32_16x16x32_bf16 v[64:67], v[136:139], v[204:207], v[64:67]
	s_setprio 0
	s_setprio 1
	v_mfma_f32_16x16x32_bf16 v[92:95], v[132:135], v[184:187], v[92:95]
	v_mfma_f32_16x16x32_bf16 v[88:91], v[140:143], v[184:187], v[88:91]
	v_mfma_f32_16x16x32_bf16 v[84:87], v[132:135], v[192:195], v[84:87]
	v_mfma_f32_16x16x32_bf16 v[80:83], v[140:143], v[192:195], v[80:83]
	v_mfma_f32_16x16x32_bf16 v[76:79], v[132:135], v[200:203], v[76:79]
	v_mfma_f32_16x16x32_bf16 v[72:75], v[140:143], v[200:203], v[72:75]
	v_mfma_f32_16x16x32_bf16 v[68:71], v[132:135], v[208:211], v[68:71]
	v_mfma_f32_16x16x32_bf16 v[64:67], v[140:143], v[208:211], v[64:67]
	s_setprio 0
	s_setprio 1
	v_mfma_f32_16x16x32_bf16 v[28:31], v[158:161], v[180:183], v[28:31]
	v_mfma_f32_16x16x32_bf16 v[24:27], v[172:175], v[180:183], v[24:27]
	v_mfma_f32_16x16x32_bf16 v[20:23], v[158:161], v[188:191], v[20:23]
	v_mfma_f32_16x16x32_bf16 v[16:19], v[172:175], v[188:191], v[16:19]
	v_mfma_f32_16x16x32_bf16 v[12:15], v[158:161], v[196:199], v[12:15]
	v_mfma_f32_16x16x32_bf16 v[8:11], v[172:175], v[196:199], v[8:11]
	v_mfma_f32_16x16x32_bf16 v[4:7], v[158:161], v[204:207], v[4:7]
	v_mfma_f32_16x16x32_bf16 v[0:3], v[172:175], v[204:207], v[0:3]
	s_setprio 0
	s_setprio 1
	v_mfma_f32_16x16x32_bf16 v[28:31], v[162:165], v[184:187], v[28:31]
	v_mfma_f32_16x16x32_bf16 v[24:27], v[176:179], v[184:187], v[24:27]
	v_mfma_f32_16x16x32_bf16 v[20:23], v[162:165], v[192:195], v[20:23]
	v_mfma_f32_16x16x32_bf16 v[16:19], v[176:179], v[192:195], v[16:19]
	v_mfma_f32_16x16x32_bf16 v[12:15], v[162:165], v[200:203], v[12:15]
	v_mfma_f32_16x16x32_bf16 v[8:11], v[176:179], v[200:203], v[8:11]
	v_mfma_f32_16x16x32_bf16 v[4:7], v[162:165], v[208:211], v[4:7]
	v_mfma_f32_16x16x32_bf16 v[0:3], v[176:179], v[208:211], v[0:3]
	s_setprio 0
	s_barrier
	s_add_i32 s54, s54, 2
	s_add_u32 s52, s52, 0x100
	s_addc_u32 s53, s53, 0
	s_cmp_gt_u32 s54, 41
	s_mov_b64 s[2:3], s[24:25]
	s_cbranch_scc0 .LBB0_3759
